# write-through (sc0 sc1) on all dwordx4 global stores so the grid-barrier release fence has less dirty L2 to flush
# speedup vs baseline: 1.0098x; 1.0098x over previous
; #define LAS __attribute__((address_space(3)))
; __device__ __forceinline__ unsigned cvtpk(float lo, float hi) { f32x2 v = {lo, hi}; bf16x2_t b = __builtin_convertvector(v, bf16x2_t); return __builtin_bit_cast(unsigned, b); }
; __device__ __forceinline__ void witem_store(const WItem& w, int K, bf16_t* WT, int kvperm, LAS float* scr, int item, int nblk, int lane) {
;     const int kb = item / nblk, nb = item % nblk, k0 = 64 * kb, n0 = 32 * nb;
;     const int col = 4 * (lane & 7), rr = lane >> 3;
; #pragma unroll
;     for (int i = 0; i < 8; ++i) { LAS float* d = scr + (8 * i + rr) * 33 + col; const float g = w.g[i]; d[0] = w.v[i].x * g; d[1] = w.v[i].y * g; d[2] = w.v[i].z * g; d[3] = w.v[i].w * g; }
;     asm volatile("s_waitcnt lgkmcnt(0)" ::: "memory");
;     const int c = lane & 7;
; #pragma unroll
;     for (int j = 0; j < 4; ++j) { const int n = (lane >> 3) + 8 * j; const LAS float* s = scr + (8 * c) * 33 + n;
;         u32x4 o; o.x = cvtpk(s[0 * 33], s[1 * 33]); o.y = cvtpk(s[2 * 33], s[3 * 33]); o.z = cvtpk(s[4 * 33], s[5 * 33]); o.w = cvtpk(s[6 * 33], s[7 * 33]);
;         int nr = n0 + n; if (kvperm == 1) { const int hh = nr >> 8, ww = nr & 255; nr = (ww < 128) ? hh * 128 + ww : 2048 + hh * 128 + (ww - 128); }
;         else if (kvperm == 2) { const int isv = nr >= 5632, f = isv ? nr - 5632 : nr; nr = (f >> 7) * 256 + isv * 128 + (f & 127); }
;         *(u32x4*)(WT + (size_t)nr * K + k0 + 8 * c) = o; }
;     asm volatile("s_waitcnt lgkmcnt(0)" ::: "memory");
; }
;     ...
;     while (it < i1) {
;         cur = nxt;
;         const int nit = it + NGW;
;         if (nit < i1) witem_load(nxt, W, N, gk, nit, nblk, lane);
;         witem_store(cur, K, WT, kvperm, scr, it, nblk, lane);
;         it = nit;
;     }
.LBB0_51:
	v_pk_mul_f32 v[2:3], v[2:3], v[72:73] op_sel_hi:[1,0]
	ds_write2_b32 v79, v2, v3 offset1:1
	v_pk_mul_f32 v[2:3], v[4:5], v[72:73] op_sel_hi:[1,0]
	ds_write2_b32 v79, v2, v3 offset0:2 offset1:3
	v_pk_mul_f32 v[2:3], v[6:7], v[74:75] op_sel_hi:[1,0]
	v_add_u32_e32 v4, 0x420, v79
	ds_write2_b32 v4, v2, v3 offset1:1
	v_pk_mul_f32 v[2:3], v[8:9], v[74:75] op_sel_hi:[1,0]
	v_add_u32_e32 v4, 0x428, v79
	ds_write2_b32 v4, v2, v3 offset1:1
	v_pk_mul_f32 v[2:3], v[10:11], v[76:77] op_sel_hi:[1,0]
	v_add_u32_e32 v4, 0x840, v79
	ds_write2_b32 v4, v2, v3 offset1:1
	v_pk_mul_f32 v[2:3], v[12:13], v[76:77] op_sel_hi:[1,0]
	v_add_u32_e32 v4, 0x848, v79
	ds_write2_b32 v4, v2, v3 offset1:1
	v_pk_mul_f32 v[2:3], v[14:15], v[78:79] op_sel_hi:[1,0]
	v_add_u32_e32 v4, 0xc60, v79
	ds_write2_b32 v4, v2, v3 offset1:1
	v_pk_mul_f32 v[2:3], v[16:17], v[78:79] op_sel_hi:[1,0]
	v_add_u32_e32 v4, 0xc68, v79
	ds_write2_b32 v4, v2, v3 offset1:1
	v_pk_mul_f32 v[2:3], v[18:19], v[80:81] op_sel_hi:[1,0]
	v_add_u32_e32 v4, 0x1080, v79
	ds_write2_b32 v4, v2, v3 offset1:1
	v_pk_mul_f32 v[2:3], v[20:21], v[80:81] op_sel_hi:[1,0]
	v_add_u32_e32 v4, 0x1088, v79
	ds_write2_b32 v4, v2, v3 offset1:1
	s_waitcnt vmcnt(0)
	v_pk_mul_f32 v[2:3], v[22:23], v[84:85] op_sel_hi:[1,0]
	v_add_u32_e32 v4, 0x14a0, v79
	ds_write2_b32 v4, v2, v3 offset1:1
	v_pk_mul_f32 v[2:3], v[24:25], v[84:85] op_sel_hi:[1,0]
	v_add_u32_e32 v4, 0x14a8, v79
	ds_write2_b32 v4, v2, v3 offset1:1
	v_pk_mul_f32 v[2:3], v[26:27], v[88:89] op_sel_hi:[1,0]
	v_add_u32_e32 v4, 0x18c0, v79
	s_mul_hi_i32 s4, s20, 0x66666667
	ds_write2_b32 v4, v2, v3 offset1:1
	v_pk_mul_f32 v[2:3], v[28:29], v[88:89] op_sel_hi:[1,0]
	v_add_u32_e32 v4, 0x18c8, v79
	s_lshr_b32 s5, s4, 31
	s_ashr_i32 s4, s4, 4
	ds_write2_b32 v4, v2, v3 offset1:1
	v_pk_mul_f32 v[2:3], v[34:35], v[90:91] op_sel_hi:[1,0]
	v_add_u32_e32 v4, 0x1ce0, v79
	s_add_i32 s6, s4, s5
	ds_write2_b32 v4, v2, v3 offset1:1
	v_pk_mul_f32 v[2:3], v[36:37], v[90:91] op_sel_hi:[1,0]
	v_add_u32_e32 v4, 0x1ce8, v79
	s_lshl_b32 s4, s6, 6
	ds_write2_b32 v4, v2, v3 offset1:1
	s_waitcnt lgkmcnt(0)
	s_ashr_i32 s5, s4, 31
	ds_read2_b32 v[6:7], v77 offset0:33 offset1:41
	ds_read2_b32 v[8:9], v77 offset1:8
	ds_read2_b32 v[10:11], v77 offset0:66 offset1:74
	ds_read2_b32 v[12:13], v77 offset0:99 offset1:107
	ds_read2_b32 v[14:15], v77 offset0:132 offset1:140
	ds_read2_b32 v[16:17], v77 offset0:165 offset1:173
	ds_read2_b32 v[18:19], v77 offset0:198 offset1:206
	ds_read2_b32 v[20:21], v77 offset0:231 offset1:239
	v_lshl_add_u64 v[22:23], s[4:5], 1, v[86:87]
	s_mul_i32 s4, s6, 0xfffffb00
	s_add_i32 s4, s4, s21
	v_add_u32_e32 v24, s4, v81
	v_ashrrev_i32_e32 v25, 31, v24
	v_lshlrev_b64 v[26:27], 12, v[24:25]
	s_waitcnt lgkmcnt(6)
	v_cvt_pk_bf16_f32 v2, v8, v6
	s_waitcnt lgkmcnt(4)
	v_cvt_pk_bf16_f32 v3, v10, v12
	s_waitcnt lgkmcnt(2)
	v_cvt_pk_bf16_f32 v4, v14, v16
	s_waitcnt lgkmcnt(0)
	v_cvt_pk_bf16_f32 v5, v18, v20
	v_lshl_add_u64 v[26:27], v[22:23], 0, v[26:27]
	v_add_u32_e32 v6, 8, v24
	global_store_dwordx4 v[26:27], v[2:5], off sc0 sc1
	v_mov_b64_e32 v[34:35], v[66:67]
	v_add_u32_e32 v81, s25, v81
	v_cvt_pk_bf16_f32 v2, v9, v7
	v_ashrrev_i32_e32 v7, 31, v6
	v_cvt_pk_bf16_f32 v3, v11, v13
	v_cvt_pk_bf16_f32 v4, v15, v17
	v_cvt_pk_bf16_f32 v5, v19, v21
	v_lshlrev_b64 v[6:7], 12, v[6:7]
	ds_read2_b32 v[8:9], v77 offset0:49 offset1:57
	ds_read2_b32 v[10:11], v77 offset0:16 offset1:24
	ds_read2_b32 v[12:13], v77 offset0:82 offset1:90
	ds_read2_b32 v[14:15], v77 offset0:115 offset1:123
	ds_read2_b32 v[16:17], v77 offset0:148 offset1:156
	ds_read2_b32 v[18:19], v77 offset0:181 offset1:189
	ds_read2_b32 v[20:21], v77 offset0:214 offset1:222
	ds_read2_b32 v[26:27], v77 offset0:247 offset1:255
	v_lshl_add_u64 v[6:7], v[22:23], 0, v[6:7]
	global_store_dwordx4 v[6:7], v[2:5], off sc0 sc1
	v_add_u32_e32 v6, 16, v24
	v_ashrrev_i32_e32 v7, 31, v6
	v_lshlrev_b64 v[6:7], 12, v[6:7]
	s_waitcnt lgkmcnt(6)
	v_cvt_pk_bf16_f32 v2, v10, v8
	s_waitcnt lgkmcnt(4)
	v_cvt_pk_bf16_f32 v3, v12, v14
	s_waitcnt lgkmcnt(2)
	v_cvt_pk_bf16_f32 v4, v16, v18
	s_waitcnt lgkmcnt(0)
	v_cvt_pk_bf16_f32 v5, v20, v26
	v_lshl_add_u64 v[6:7], v[22:23], 0, v[6:7]
	global_store_dwordx4 v[6:7], v[2:5], off sc0 sc1
	v_add_u32_e32 v6, 24, v24
	v_ashrrev_i32_e32 v7, 31, v6
	v_lshlrev_b64 v[6:7], 12, v[6:7]
	v_cvt_pk_bf16_f32 v2, v11, v9
	v_cvt_pk_bf16_f32 v3, v13, v15
	v_cvt_pk_bf16_f32 v4, v17, v19
	v_cvt_pk_bf16_f32 v5, v21, v27
	v_lshl_add_u64 v[6:7], v[22:23], 0, v[6:7]
	global_store_dwordx4 v[6:7], v[2:5], off sc0 sc1
	s_waitcnt lgkmcnt(0)
	v_mov_b64_e32 v[6:7], v[42:43]
	v_mov_b64_e32 v[10:11], v[46:47]
	v_mov_b64_e32 v[2:3], v[38:39]
	v_mov_b64_e32 v[14:15], v[50:51]
	v_mov_b64_e32 v[18:19], v[54:55]
	v_mov_b64_e32 v[22:23], v[58:59]
	v_mov_b64_e32 v[26:27], v[62:63]
	s_add_i32 s29, s29, s25
	v_add_u32_e32 v73, s25, v73
	s_andn2_b64 vcc, exec, s[16:17]
	s_mov_b32 s20, s30
	v_mov_b64_e32 v[4:5], v[40:41]
	v_mov_b64_e32 v[8:9], v[44:45]
	v_mov_b64_e32 v[12:13], v[48:49]
	v_mov_b64_e32 v[16:17], v[52:53]
	v_mov_b64_e32 v[20:21], v[56:57]
	v_mov_b64_e32 v[24:25], v[60:61]
	v_mov_b64_e32 v[28:29], v[64:65]
	v_mov_b64_e32 v[36:37], v[68:69]
	v_mov_b32_e32 v72, v85
	v_mov_b32_e32 v74, v91
	v_mov_b32_e32 v76, v96
	v_mov_b32_e32 v78, v97
	v_mov_b32_e32 v80, v98
	v_mov_b32_e32 v84, v99
	v_mov_b32_e32 v88, v100
	v_mov_b32_e32 v90, v31
	s_cbranch_vccz .LBB0_91

; #define LAS __attribute__((address_space(3)))
; __device__ __forceinline__ unsigned cvtpk(float lo, float hi) { f32x2 v = {lo, hi}; bf16x2_t b = __builtin_convertvector(v, bf16x2_t); return __builtin_bit_cast(unsigned, b); }
; __device__ __forceinline__ void witem_store(const WItem& w, int K, bf16_t* WT, int kvperm, LAS float* scr, int item, int nblk, int lane) {
;     const int kb = item / nblk, nb = item % nblk, k0 = 64 * kb, n0 = 32 * nb;
;     const int col = 4 * (lane & 7), rr = lane >> 3;
; #pragma unroll
;     for (int i = 0; i < 8; ++i) { LAS float* d = scr + (8 * i + rr) * 33 + col; const float g = w.g[i]; d[0] = w.v[i].x * g; d[1] = w.v[i].y * g; d[2] = w.v[i].z * g; d[3] = w.v[i].w * g; }
;     asm volatile("s_waitcnt lgkmcnt(0)" ::: "memory");
;     const int c = lane & 7;
; #pragma unroll
;     for (int j = 0; j < 4; ++j) { const int n = (lane >> 3) + 8 * j; const LAS float* s = scr + (8 * c) * 33 + n;
;         u32x4 o; o.x = cvtpk(s[0 * 33], s[1 * 33]); o.y = cvtpk(s[2 * 33], s[3 * 33]); o.z = cvtpk(s[4 * 33], s[5 * 33]); o.w = cvtpk(s[6 * 33], s[7 * 33]);
;         int nr = n0 + n; if (kvperm == 1) { const int hh = nr >> 8, ww = nr & 255; nr = (ww < 128) ? hh * 128 + ww : 2048 + hh * 128 + (ww - 128); }
;         else if (kvperm == 2) { const int isv = nr >= 5632, f = isv ? nr - 5632 : nr; nr = (f >> 7) * 256 + isv * 128 + (f & 127); }
;         *(u32x4*)(WT + (size_t)nr * K + k0 + 8 * c) = o; }
;     asm volatile("s_waitcnt lgkmcnt(0)" ::: "memory");
; }
;     ...
;     while (it < i1) {
;         cur = nxt;
;         const int nit = it + NGW;
;         if (nit < i1) witem_load(nxt, W, N, gk, nit, nblk, lane);
;         witem_store(cur, K, WT, kvperm, scr, it, nblk, lane);
;         it = nit;
;     }
.LBB0_136:
	v_pk_mul_f32 v[2:3], v[2:3], v[72:73] op_sel_hi:[1,0]
	ds_write2_b32 v79, v2, v3 offset1:1
	v_pk_mul_f32 v[2:3], v[4:5], v[72:73] op_sel_hi:[1,0]
	ds_write2_b32 v79, v2, v3 offset0:2 offset1:3
	v_pk_mul_f32 v[2:3], v[6:7], v[74:75] op_sel_hi:[1,0]
	v_add_u32_e32 v4, 0x420, v79
	ds_write2_b32 v4, v2, v3 offset1:1
	v_pk_mul_f32 v[2:3], v[8:9], v[74:75] op_sel_hi:[1,0]
	v_add_u32_e32 v4, 0x428, v79
	ds_write2_b32 v4, v2, v3 offset1:1
	v_pk_mul_f32 v[2:3], v[10:11], v[76:77] op_sel_hi:[1,0]
	v_add_u32_e32 v4, 0x840, v79
	ds_write2_b32 v4, v2, v3 offset1:1
	v_pk_mul_f32 v[2:3], v[12:13], v[76:77] op_sel_hi:[1,0]
	v_add_u32_e32 v4, 0x848, v79
	ds_write2_b32 v4, v2, v3 offset1:1
	v_pk_mul_f32 v[2:3], v[14:15], v[78:79] op_sel_hi:[1,0]
	v_add_u32_e32 v4, 0xc60, v79
	ds_write2_b32 v4, v2, v3 offset1:1
	v_pk_mul_f32 v[2:3], v[16:17], v[78:79] op_sel_hi:[1,0]
	v_add_u32_e32 v4, 0xc68, v79
	ds_write2_b32 v4, v2, v3 offset1:1
	v_pk_mul_f32 v[2:3], v[18:19], v[80:81] op_sel_hi:[1,0]
	v_add_u32_e32 v4, 0x1080, v79
	ds_write2_b32 v4, v2, v3 offset1:1
	v_pk_mul_f32 v[2:3], v[20:21], v[80:81] op_sel_hi:[1,0]
	v_add_u32_e32 v4, 0x1088, v79
	ds_write2_b32 v4, v2, v3 offset1:1
	s_waitcnt vmcnt(0)
	v_pk_mul_f32 v[2:3], v[22:23], v[84:85] op_sel_hi:[1,0]
	v_add_u32_e32 v4, 0x14a0, v79
	ds_write2_b32 v4, v2, v3 offset1:1
	v_pk_mul_f32 v[2:3], v[24:25], v[84:85] op_sel_hi:[1,0]
	v_add_u32_e32 v4, 0x14a8, v79
	ds_write2_b32 v4, v2, v3 offset1:1
	v_pk_mul_f32 v[2:3], v[26:27], v[88:89] op_sel_hi:[1,0]
	v_add_u32_e32 v4, 0x18c0, v79
	s_mul_hi_i32 s4, s26, 0x2aaaaaab
	ds_write2_b32 v4, v2, v3 offset1:1
	v_pk_mul_f32 v[2:3], v[28:29], v[88:89] op_sel_hi:[1,0]
	v_add_u32_e32 v4, 0x18c8, v79
	s_lshr_b32 s5, s4, 31
	s_ashr_i32 s4, s4, 4
	ds_write2_b32 v4, v2, v3 offset1:1
	v_pk_mul_f32 v[2:3], v[34:35], v[90:91] op_sel_hi:[1,0]
	v_add_u32_e32 v4, 0x1ce0, v79
	s_add_i32 s6, s4, s5
	ds_write2_b32 v4, v2, v3 offset1:1
	v_pk_mul_f32 v[2:3], v[36:37], v[90:91] op_sel_hi:[1,0]
	v_add_u32_e32 v4, 0x1ce8, v79
	s_lshl_b32 s4, s6, 6
	ds_write2_b32 v4, v2, v3 offset1:1
	s_waitcnt lgkmcnt(0)
	s_ashr_i32 s5, s4, 31
	ds_read2_b32 v[6:7], v77 offset0:33 offset1:41
	ds_read2_b32 v[8:9], v77 offset1:8
	ds_read2_b32 v[10:11], v77 offset0:66 offset1:74
	ds_read2_b32 v[12:13], v77 offset0:99 offset1:107
	ds_read2_b32 v[14:15], v77 offset0:132 offset1:140
	ds_read2_b32 v[16:17], v77 offset0:165 offset1:173
	ds_read2_b32 v[18:19], v77 offset0:198 offset1:206
	ds_read2_b32 v[20:21], v77 offset0:231 offset1:239
	v_lshl_add_u64 v[22:23], s[4:5], 1, v[86:87]
	s_mul_i32 s4, s6, 0xfffff400
	s_add_i32 s4, s4, s28
	v_add_u32_e32 v24, s4, v81
	v_ashrrev_i32_e32 v25, 31, v24
	v_lshlrev_b64 v[26:27], 10, v[24:25]
	s_waitcnt lgkmcnt(6)
	v_cvt_pk_bf16_f32 v2, v8, v6
	s_waitcnt lgkmcnt(4)
	v_cvt_pk_bf16_f32 v3, v10, v12
	s_waitcnt lgkmcnt(2)
	v_cvt_pk_bf16_f32 v4, v14, v16
	s_waitcnt lgkmcnt(0)
	v_cvt_pk_bf16_f32 v5, v18, v20
	v_lshl_add_u64 v[26:27], v[22:23], 0, v[26:27]
	v_add_u32_e32 v6, 8, v24
	global_store_dwordx4 v[26:27], v[2:5], off sc0 sc1
	v_mov_b64_e32 v[34:35], v[66:67]
	v_add_u32_e32 v81, s29, v81
	v_cvt_pk_bf16_f32 v2, v9, v7
	v_ashrrev_i32_e32 v7, 31, v6
	v_cvt_pk_bf16_f32 v3, v11, v13
	v_cvt_pk_bf16_f32 v4, v15, v17
	v_cvt_pk_bf16_f32 v5, v19, v21
	v_lshlrev_b64 v[6:7], 10, v[6:7]
	ds_read2_b32 v[8:9], v77 offset0:49 offset1:57
	ds_read2_b32 v[10:11], v77 offset0:16 offset1:24
	ds_read2_b32 v[12:13], v77 offset0:82 offset1:90
	ds_read2_b32 v[14:15], v77 offset0:115 offset1:123
	ds_read2_b32 v[16:17], v77 offset0:148 offset1:156
	ds_read2_b32 v[18:19], v77 offset0:181 offset1:189
	ds_read2_b32 v[20:21], v77 offset0:214 offset1:222
	ds_read2_b32 v[26:27], v77 offset0:247 offset1:255
	v_lshl_add_u64 v[6:7], v[22:23], 0, v[6:7]
	global_store_dwordx4 v[6:7], v[2:5], off sc0 sc1
	v_add_u32_e32 v6, 16, v24
	v_ashrrev_i32_e32 v7, 31, v6
	v_lshlrev_b64 v[6:7], 10, v[6:7]
	s_waitcnt lgkmcnt(6)
	v_cvt_pk_bf16_f32 v2, v10, v8
	s_waitcnt lgkmcnt(4)
	v_cvt_pk_bf16_f32 v3, v12, v14
	s_waitcnt lgkmcnt(2)
	v_cvt_pk_bf16_f32 v4, v16, v18
	s_waitcnt lgkmcnt(0)
	v_cvt_pk_bf16_f32 v5, v20, v26
	v_lshl_add_u64 v[6:7], v[22:23], 0, v[6:7]
	global_store_dwordx4 v[6:7], v[2:5], off sc0 sc1
	v_add_u32_e32 v6, 24, v24
	v_ashrrev_i32_e32 v7, 31, v6
	v_lshlrev_b64 v[6:7], 10, v[6:7]
	v_cvt_pk_bf16_f32 v2, v11, v9
	v_cvt_pk_bf16_f32 v3, v13, v15
	v_cvt_pk_bf16_f32 v4, v17, v19
	v_cvt_pk_bf16_f32 v5, v21, v27
	v_lshl_add_u64 v[6:7], v[22:23], 0, v[6:7]
	global_store_dwordx4 v[6:7], v[2:5], off sc0 sc1
	s_waitcnt lgkmcnt(0)
	v_mov_b64_e32 v[6:7], v[42:43]
	v_mov_b64_e32 v[10:11], v[46:47]
	v_mov_b64_e32 v[2:3], v[38:39]
	v_mov_b64_e32 v[14:15], v[50:51]
	v_mov_b64_e32 v[18:19], v[54:55]
	v_mov_b64_e32 v[22:23], v[58:59]
	v_mov_b64_e32 v[26:27], v[62:63]
	s_add_i32 s34, s34, s29
	v_add_u32_e32 v73, s29, v73
	s_andn2_b64 vcc, exec, s[18:19]
	s_mov_b32 s26, s35
	v_mov_b64_e32 v[4:5], v[40:41]
	v_mov_b64_e32 v[8:9], v[44:45]
	v_mov_b64_e32 v[12:13], v[48:49]
	v_mov_b64_e32 v[16:17], v[52:53]
	v_mov_b64_e32 v[20:21], v[56:57]
	v_mov_b64_e32 v[24:25], v[60:61]
	v_mov_b64_e32 v[28:29], v[64:65]
	v_mov_b64_e32 v[36:37], v[68:69]
	v_mov_b32_e32 v72, v85
	v_mov_b32_e32 v74, v91
	v_mov_b32_e32 v76, v96
	v_mov_b32_e32 v78, v97
	v_mov_b32_e32 v80, v98
	v_mov_b32_e32 v84, v99
	v_mov_b32_e32 v88, v100
	v_mov_b32_e32 v90, v31
	s_cbranch_vccz .LBB0_176

; #define LAS __attribute__((address_space(3)))
; __device__ __forceinline__ unsigned cvtpk(float lo, float hi) { f32x2 v = {lo, hi}; bf16x2_t b = __builtin_convertvector(v, bf16x2_t); return __builtin_bit_cast(unsigned, b); }
; __device__ __forceinline__ void witem_store(const WItem& w, int K, bf16_t* WT, int kvperm, LAS float* scr, int item, int nblk, int lane) {
;     const int kb = item / nblk, nb = item % nblk, k0 = 64 * kb, n0 = 32 * nb;
;     const int col = 4 * (lane & 7), rr = lane >> 3;
; #pragma unroll
;     for (int i = 0; i < 8; ++i) { LAS float* d = scr + (8 * i + rr) * 33 + col; const float g = w.g[i]; d[0] = w.v[i].x * g; d[1] = w.v[i].y * g; d[2] = w.v[i].z * g; d[3] = w.v[i].w * g; }
;     asm volatile("s_waitcnt lgkmcnt(0)" ::: "memory");
;     const int c = lane & 7;
; #pragma unroll
;     for (int j = 0; j < 4; ++j) { const int n = (lane >> 3) + 8 * j; const LAS float* s = scr + (8 * c) * 33 + n;
;         u32x4 o; o.x = cvtpk(s[0 * 33], s[1 * 33]); o.y = cvtpk(s[2 * 33], s[3 * 33]); o.z = cvtpk(s[4 * 33], s[5 * 33]); o.w = cvtpk(s[6 * 33], s[7 * 33]);
;         int nr = n0 + n; if (kvperm == 1) { const int hh = nr >> 8, ww = nr & 255; nr = (ww < 128) ? hh * 128 + ww : 2048 + hh * 128 + (ww - 128); }
;         else if (kvperm == 2) { const int isv = nr >= 5632, f = isv ? nr - 5632 : nr; nr = (f >> 7) * 256 + isv * 128 + (f & 127); }
;         *(u32x4*)(WT + (size_t)nr * K + k0 + 8 * c) = o; }
;     asm volatile("s_waitcnt lgkmcnt(0)" ::: "memory");
; }
;     ...
;     while (it < i1) {
;         cur = nxt;
;         const int nit = it + NGW;
;         if (nit < i1) witem_load(nxt, W, N, gk, nit, nblk, lane);
;         witem_store(cur, K, WT, kvperm, scr, it, nblk, lane);
;         it = nit;
;     }
.LBB0_221:
	v_pk_mul_f32 v[2:3], v[2:3], v[72:73] op_sel_hi:[1,0]
	ds_write2_b32 v91, v2, v3 offset1:1
	v_pk_mul_f32 v[2:3], v[4:5], v[72:73] op_sel_hi:[1,0]
	ds_write2_b32 v91, v2, v3 offset0:2 offset1:3
	v_pk_mul_f32 v[2:3], v[6:7], v[74:75] op_sel_hi:[1,0]
	v_add_u32_e32 v4, 0x420, v91
	ds_write2_b32 v4, v2, v3 offset1:1
	v_pk_mul_f32 v[2:3], v[8:9], v[74:75] op_sel_hi:[1,0]
	v_add_u32_e32 v4, 0x428, v91
	ds_write2_b32 v4, v2, v3 offset1:1
	v_pk_mul_f32 v[2:3], v[10:11], v[76:77] op_sel_hi:[1,0]
	v_add_u32_e32 v4, 0x840, v91
	ds_write2_b32 v4, v2, v3 offset1:1
	v_pk_mul_f32 v[2:3], v[12:13], v[76:77] op_sel_hi:[1,0]
	v_add_u32_e32 v4, 0x848, v91
	ds_write2_b32 v4, v2, v3 offset1:1
	v_pk_mul_f32 v[2:3], v[14:15], v[78:79] op_sel_hi:[1,0]
	v_add_u32_e32 v4, 0xc60, v91
	ds_write2_b32 v4, v2, v3 offset1:1
	v_pk_mul_f32 v[2:3], v[16:17], v[78:79] op_sel_hi:[1,0]
	v_add_u32_e32 v4, 0xc68, v91
	ds_write2_b32 v4, v2, v3 offset1:1
	v_pk_mul_f32 v[2:3], v[18:19], v[80:81] op_sel_hi:[1,0]
	v_add_u32_e32 v4, 0x1080, v91
	s_ashr_i32 s4, s26, 31
	ds_write2_b32 v4, v2, v3 offset1:1
	v_pk_mul_f32 v[2:3], v[20:21], v[80:81] op_sel_hi:[1,0]
	v_add_u32_e32 v4, 0x1088, v91
	s_lshr_b32 s4, s4, 25
	ds_write2_b32 v4, v2, v3 offset1:1
	v_pk_mul_f32 v[2:3], v[22:23], v[86:87] op_sel_hi:[1,0]
	v_add_u32_e32 v4, 0x14a0, v91
	s_add_i32 s4, s26, s4
	ds_write2_b32 v4, v2, v3 offset1:1
	v_pk_mul_f32 v[2:3], v[24:25], v[86:87] op_sel_hi:[1,0]
	v_add_u32_e32 v4, 0x14a8, v91
	s_ashr_i32 s6, s4, 7
	ds_write2_b32 v4, v2, v3 offset1:1
	v_pk_mul_f32 v[2:3], v[30:31], v[88:89] op_sel_hi:[1,0]
	v_add_u32_e32 v4, 0x18c0, v91
	s_lshl_b32 s4, s6, 6
	ds_write2_b32 v4, v2, v3 offset1:1
	v_pk_mul_f32 v[2:3], v[32:33], v[88:89] op_sel_hi:[1,0]
	v_add_u32_e32 v4, 0x18c8, v91
	ds_write2_b32 v4, v2, v3 offset1:1
	v_pk_mul_f32 v[2:3], v[34:35], v[90:91] op_sel_hi:[1,0]
	v_add_u32_e32 v4, 0x1ce0, v91
	s_ashr_i32 s5, s4, 31
	ds_write2_b32 v4, v2, v3 offset1:1
	v_pk_mul_f32 v[2:3], v[36:37], v[90:91] op_sel_hi:[1,0]
	v_add_u32_e32 v4, 0x1ce8, v91
	v_lshl_add_u64 v[6:7], s[4:5], 1, v[84:85]
	s_lshl_b32 s4, s6, 11
	ds_write2_b32 v4, v2, v3 offset1:1
	s_sub_i32 s4, s29, s4
	s_waitcnt lgkmcnt(0)
	s_and_b32 s4, s4, 0xffffff80
	ds_read2_b32 v[8:9], v81 offset0:33 offset1:41
	ds_read2_b32 v[10:11], v81 offset1:8
	ds_read2_b32 v[12:13], v81 offset0:66 offset1:74
	ds_read2_b32 v[14:15], v81 offset0:99 offset1:107
	ds_read2_b32 v[16:17], v81 offset0:132 offset1:140
	ds_read2_b32 v[18:19], v81 offset0:165 offset1:173
	ds_read2_b32 v[20:21], v81 offset0:198 offset1:206
	ds_read2_b32 v[22:23], v81 offset0:231 offset1:239
	s_add_i32 s5, s4, 0x780
	s_and_b32 s6, s35, 0xe0
	s_waitcnt lgkmcnt(6)
	v_cvt_pk_bf16_f32 v2, v10, v8
	v_or_b32_e32 v8, s6, v73
	s_cmpk_lt_u32 s6, 0x80
	v_or_b32_e32 v10, s4, v8
	v_add_u32_e32 v8, s5, v8
	s_cselect_b64 vcc, -1, 0
	v_cndmask_b32_e32 v24, v8, v10, vcc
	v_ashrrev_i32_e32 v25, 31, v24
	v_lshlrev_b64 v[24:25], 10, v[24:25]
	s_waitcnt lgkmcnt(4)
	v_cvt_pk_bf16_f32 v3, v12, v14
	s_waitcnt lgkmcnt(2)
	v_cvt_pk_bf16_f32 v4, v16, v18
	s_waitcnt lgkmcnt(0)
	v_cvt_pk_bf16_f32 v5, v20, v22
	v_lshl_add_u64 v[24:25], v[6:7], 0, v[24:25]
	v_or_b32_e32 v8, s6, v75
	global_store_dwordx4 v[24:25], v[2:5], off sc0 sc1
	s_waitcnt vmcnt(1)
	v_mov_b64_e32 v[30:31], v[62:63]
	v_mov_b64_e32 v[34:35], v[66:67]
	v_cvt_pk_bf16_f32 v2, v11, v9
	v_or_b32_e32 v9, s4, v8
	v_add_u32_e32 v8, s5, v8
	v_cndmask_b32_e32 v8, v8, v9, vcc
	v_ashrrev_i32_e32 v9, 31, v8
	v_lshlrev_b64 v[8:9], 10, v[8:9]
	v_cvt_pk_bf16_f32 v3, v13, v15
	v_cvt_pk_bf16_f32 v4, v17, v19
	v_cvt_pk_bf16_f32 v5, v21, v23
	v_lshl_add_u64 v[8:9], v[6:7], 0, v[8:9]
	ds_read2_b32 v[10:11], v81 offset0:49 offset1:57
	ds_read2_b32 v[12:13], v81 offset0:16 offset1:24
	ds_read2_b32 v[14:15], v81 offset0:82 offset1:90
	ds_read2_b32 v[16:17], v81 offset0:115 offset1:123
	ds_read2_b32 v[18:19], v81 offset0:148 offset1:156
	ds_read2_b32 v[20:21], v81 offset0:181 offset1:189
	ds_read2_b32 v[22:23], v81 offset0:214 offset1:222
	ds_read2_b32 v[24:25], v81 offset0:247 offset1:255
	global_store_dwordx4 v[8:9], v[2:5], off sc0 sc1
	v_or_b32_e32 v8, s6, v77
	v_or_b32_e32 v9, s4, v8
	v_add_u32_e32 v8, s5, v8
	v_cndmask_b32_e32 v8, v8, v9, vcc
	v_ashrrev_i32_e32 v9, 31, v8
	v_lshlrev_b64 v[8:9], 10, v[8:9]
	s_waitcnt lgkmcnt(6)
	v_cvt_pk_bf16_f32 v2, v12, v10
	s_waitcnt lgkmcnt(4)
	v_cvt_pk_bf16_f32 v3, v14, v16
	s_waitcnt lgkmcnt(2)
	v_cvt_pk_bf16_f32 v4, v18, v20
	s_waitcnt lgkmcnt(0)
	v_cvt_pk_bf16_f32 v5, v22, v24
	v_lshl_add_u64 v[8:9], v[6:7], 0, v[8:9]
	global_store_dwordx4 v[8:9], v[2:5], off sc0 sc1
	s_add_i32 s29, s29, s30
	s_mov_b32 s35, s34
	v_or_b32_e32 v2, s6, v79
	v_or_b32_e32 v3, s4, v2
	v_add_u32_e32 v2, s5, v2
	v_cndmask_b32_e32 v8, v2, v3, vcc
	v_ashrrev_i32_e32 v9, 31, v8
	v_lshlrev_b64 v[8:9], 10, v[8:9]
	v_cvt_pk_bf16_f32 v2, v13, v11
	v_cvt_pk_bf16_f32 v3, v15, v17
	v_cvt_pk_bf16_f32 v4, v19, v21
	v_cvt_pk_bf16_f32 v5, v23, v25
	v_lshl_add_u64 v[6:7], v[6:7], 0, v[8:9]
	global_store_dwordx4 v[6:7], v[2:5], off sc0 sc1
	s_waitcnt lgkmcnt(0)
	v_mov_b64_e32 v[6:7], v[42:43]
	v_mov_b64_e32 v[10:11], v[46:47]
	v_mov_b64_e32 v[2:3], v[38:39]
	v_mov_b64_e32 v[14:15], v[50:51]
	v_mov_b64_e32 v[18:19], v[54:55]
	v_mov_b64_e32 v[22:23], v[58:59]
	s_andn2_b64 vcc, exec, s[18:19]
	s_mov_b32 s26, s33
	v_mov_b64_e32 v[4:5], v[40:41]
	v_mov_b64_e32 v[8:9], v[44:45]
	v_mov_b64_e32 v[12:13], v[48:49]
	v_mov_b64_e32 v[16:17], v[52:53]
	v_mov_b64_e32 v[20:21], v[56:57]
	v_mov_b64_e32 v[24:25], v[60:61]
	v_mov_b64_e32 v[32:33], v[64:65]
	v_mov_b64_e32 v[36:37], v[68:69]
	v_mov_b32_e32 v72, v96
	v_mov_b32_e32 v74, v97
	v_mov_b32_e32 v76, v98
	v_mov_b32_e32 v78, v99
	v_mov_b32_e32 v80, v100
	v_mov_b32_e32 v86, v101
	v_mov_b32_e32 v88, v102
	v_mov_b32_e32 v90, v27
	s_cbranch_vccz .LBB0_263

; #define LAS __attribute__((address_space(3)))
; __device__ __forceinline__ unsigned cvtpk(float lo, float hi) { f32x2 v = {lo, hi}; bf16x2_t b = __builtin_convertvector(v, bf16x2_t); return __builtin_bit_cast(unsigned, b); }
; __device__ __forceinline__ void witem_store(const WItem& w, int K, bf16_t* WT, int kvperm, LAS float* scr, int item, int nblk, int lane) {
;     const int kb = item / nblk, nb = item % nblk, k0 = 64 * kb, n0 = 32 * nb;
;     const int col = 4 * (lane & 7), rr = lane >> 3;
; #pragma unroll
;     for (int i = 0; i < 8; ++i) { LAS float* d = scr + (8 * i + rr) * 33 + col; const float g = w.g[i]; d[0] = w.v[i].x * g; d[1] = w.v[i].y * g; d[2] = w.v[i].z * g; d[3] = w.v[i].w * g; }
;     asm volatile("s_waitcnt lgkmcnt(0)" ::: "memory");
;     const int c = lane & 7;
; #pragma unroll
;     for (int j = 0; j < 4; ++j) { const int n = (lane >> 3) + 8 * j; const LAS float* s = scr + (8 * c) * 33 + n;
;         u32x4 o; o.x = cvtpk(s[0 * 33], s[1 * 33]); o.y = cvtpk(s[2 * 33], s[3 * 33]); o.z = cvtpk(s[4 * 33], s[5 * 33]); o.w = cvtpk(s[6 * 33], s[7 * 33]);
;         int nr = n0 + n; if (kvperm == 1) { const int hh = nr >> 8, ww = nr & 255; nr = (ww < 128) ? hh * 128 + ww : 2048 + hh * 128 + (ww - 128); }
;         else if (kvperm == 2) { const int isv = nr >= 5632, f = isv ? nr - 5632 : nr; nr = (f >> 7) * 256 + isv * 128 + (f & 127); }
;         *(u32x4*)(WT + (size_t)nr * K + k0 + 8 * c) = o; }
;     asm volatile("s_waitcnt lgkmcnt(0)" ::: "memory");
; }
;     ...
;     while (it < i1) {
;         cur = nxt;
;         const int nit = it + NGW;
;         if (nit < i1) witem_load(nxt, W, N, gk, nit, nblk, lane);
;         witem_store(cur, K, WT, kvperm, scr, it, nblk, lane);
;         it = nit;
;     }
.LBB0_282:
	ds_write2_b32 v83, v6, v7 offset1:1
	ds_write2_b32 v83, v8, v9 offset0:2 offset1:3
	v_add_u32_e32 v6, 0x420, v83
	ds_write2_b32 v6, v2, v3 offset1:1
	v_add_u32_e32 v2, 0x428, v83
	ds_write2_b32 v2, v4, v5 offset1:1
	v_add_u32_e32 v2, 0x840, v83
	ds_write2_b32 v2, v14, v15 offset1:1
	v_add_u32_e32 v2, 0x848, v83
	ds_write2_b32 v2, v16, v17 offset1:1
	v_add_u32_e32 v2, 0xc60, v83
	ds_write2_b32 v2, v10, v11 offset1:1
	v_add_u32_e32 v2, 0xc68, v83
	ds_write2_b32 v2, v12, v13 offset1:1
	v_add_u32_e32 v2, 0x1080, v83
	ds_write2_b32 v2, v26, v27 offset1:1
	v_add_u32_e32 v2, 0x1088, v83
	ds_write2_b32 v2, v28, v29 offset1:1
	v_add_u32_e32 v2, 0x14a0, v83
	ds_write2_b32 v2, v22, v23 offset1:1
	v_add_u32_e32 v2, 0x14a8, v83
	ds_write2_b32 v2, v24, v25 offset1:1
	v_add_u32_e32 v2, 0x18c0, v83
	s_ashr_i32 s6, s16, 31
	ds_write2_b32 v2, v38, v39 offset1:1
	v_add_u32_e32 v2, 0x18c8, v83
	s_lshr_b32 s6, s6, 26
	ds_write2_b32 v2, v40, v41 offset1:1
	v_add_u32_e32 v2, 0x1ce0, v83
	s_add_i32 s16, s16, s6
	ds_write2_b32 v2, v42, v43 offset1:1
	v_add_u32_e32 v2, 0x1ce8, v83
	s_and_b32 s6, s16, 0xffffffc0
	ds_write2_b32 v2, v44, v45 offset1:1
	s_waitcnt lgkmcnt(0)
	s_ashr_i32 s7, s6, 31
	ds_read2_b32 v[6:7], v82 offset0:33 offset1:41
	ds_read2_b32 v[8:9], v82 offset1:8
	ds_read2_b32 v[10:11], v82 offset0:66 offset1:74
	ds_read2_b32 v[12:13], v82 offset0:99 offset1:107
	ds_read2_b32 v[14:15], v82 offset0:132 offset1:140
	ds_read2_b32 v[16:17], v82 offset0:165 offset1:173
	ds_read2_b32 v[20:21], v82 offset0:198 offset1:206
	ds_read2_b32 v[22:23], v82 offset0:231 offset1:239
	v_lshl_add_u64 v[24:25], s[6:7], 1, v[74:75]
	s_lshl_b32 s6, s16, 5
	s_waitcnt lgkmcnt(6)
	v_cvt_pk_bf16_f32 v2, v8, v6
	v_add_u32_e32 v6, s17, v84
	s_and_b32 s6, s6, 0xfffff800
	v_subrev_u32_e32 v26, s6, v6
	v_ashrrev_i32_e32 v27, 31, v26
	v_lshlrev_b64 v[28:29], 12, v[26:27]
	s_waitcnt lgkmcnt(4)
	v_cvt_pk_bf16_f32 v3, v10, v12
	s_waitcnt lgkmcnt(2)
	v_cvt_pk_bf16_f32 v4, v14, v16
	s_waitcnt lgkmcnt(0)
	v_cvt_pk_bf16_f32 v5, v20, v22
	v_lshl_add_u64 v[28:29], v[24:25], 0, v[28:29]
	v_add_u32_e32 v6, 8, v26
	global_store_dwordx4 v[28:29], v[2:5], off sc0 sc1
	s_waitcnt vmcnt(1)
	v_mov_b64_e32 v[38:39], v[62:63]
	v_add_u32_e32 v84, s18, v84
	v_cvt_pk_bf16_f32 v2, v9, v7
	v_ashrrev_i32_e32 v7, 31, v6
	v_cvt_pk_bf16_f32 v3, v11, v13
	v_cvt_pk_bf16_f32 v4, v15, v17
	v_cvt_pk_bf16_f32 v5, v21, v23
	v_lshlrev_b64 v[6:7], 12, v[6:7]
	ds_read2_b32 v[8:9], v82 offset0:49 offset1:57
	ds_read2_b32 v[10:11], v82 offset0:16 offset1:24
	ds_read2_b32 v[12:13], v82 offset0:82 offset1:90
	ds_read2_b32 v[14:15], v82 offset0:115 offset1:123
	ds_read2_b32 v[16:17], v82 offset0:148 offset1:156
	ds_read2_b32 v[20:21], v82 offset0:181 offset1:189
	ds_read2_b32 v[22:23], v82 offset0:214 offset1:222
	ds_read2_b32 v[28:29], v82 offset0:247 offset1:255
	v_lshl_add_u64 v[6:7], v[24:25], 0, v[6:7]
	global_store_dwordx4 v[6:7], v[2:5], off sc0 sc1
	v_add_u32_e32 v6, 16, v26
	v_ashrrev_i32_e32 v7, 31, v6
	v_lshlrev_b64 v[6:7], 12, v[6:7]
	s_waitcnt lgkmcnt(6)
	v_cvt_pk_bf16_f32 v2, v10, v8
	s_waitcnt lgkmcnt(4)
	v_cvt_pk_bf16_f32 v3, v12, v14
	s_waitcnt lgkmcnt(2)
	v_cvt_pk_bf16_f32 v4, v16, v20
	s_waitcnt lgkmcnt(0)
	v_cvt_pk_bf16_f32 v5, v22, v28
	v_lshl_add_u64 v[6:7], v[24:25], 0, v[6:7]
	global_store_dwordx4 v[6:7], v[2:5], off sc0 sc1
	v_add_u32_e32 v6, 24, v26
	v_ashrrev_i32_e32 v7, 31, v6
	v_lshlrev_b64 v[6:7], 12, v[6:7]
	v_cvt_pk_bf16_f32 v2, v11, v9
	v_cvt_pk_bf16_f32 v3, v13, v15
	v_cvt_pk_bf16_f32 v4, v17, v21
	v_cvt_pk_bf16_f32 v5, v23, v29
	v_lshl_add_u64 v[6:7], v[24:25], 0, v[6:7]
	global_store_dwordx4 v[6:7], v[2:5], off sc0 sc1
	s_waitcnt lgkmcnt(0)
	v_mov_b64_e32 v[6:7], v[34:35]
	v_mov_b64_e32 v[14:15], v[46:47]
	v_mov_b64_e32 v[2:3], v[30:31]
	v_mov_b64_e32 v[10:11], v[50:51]
	v_mov_b64_e32 v[26:27], v[54:55]
	v_mov_b64_e32 v[22:23], v[58:59]
	s_add_i32 s21, s21, s18
	v_add_u32_e32 v80, s18, v80
	s_andn2_b64 vcc, exec, s[4:5]
	s_mov_b32 s16, s25
	v_mov_b64_e32 v[8:9], v[36:37]
	v_mov_b64_e32 v[4:5], v[32:33]
	v_mov_b64_e32 v[16:17], v[48:49]
	v_mov_b64_e32 v[12:13], v[52:53]
	v_mov_b64_e32 v[28:29], v[56:57]
	v_mov_b64_e32 v[24:25], v[60:61]
	v_mov_b64_e32 v[40:41], v[64:65]
	v_mov_b32_e32 v42, v66
	v_mov_b32_e32 v43, v67
	v_mov_b32_e32 v44, v68
	v_mov_b32_e32 v45, v69
	s_cbranch_vccz .LBB0_300

; #define LAS __attribute__((address_space(3)))
; __device__ __forceinline__ unsigned cvtpk(float lo, float hi) { f32x2 v = {lo, hi}; bf16x2_t b = __builtin_convertvector(v, bf16x2_t); return __builtin_bit_cast(unsigned, b); }
; __device__ __forceinline__ void witem_store(const WItem& w, int K, bf16_t* WT, int kvperm, LAS float* scr, int item, int nblk, int lane) {
;     const int kb = item / nblk, nb = item % nblk, k0 = 64 * kb, n0 = 32 * nb;
;     const int col = 4 * (lane & 7), rr = lane >> 3;
; #pragma unroll
;     for (int i = 0; i < 8; ++i) { LAS float* d = scr + (8 * i + rr) * 33 + col; const float g = w.g[i]; d[0] = w.v[i].x * g; d[1] = w.v[i].y * g; d[2] = w.v[i].z * g; d[3] = w.v[i].w * g; }
;     asm volatile("s_waitcnt lgkmcnt(0)" ::: "memory");
;     const int c = lane & 7;
; #pragma unroll
;     for (int j = 0; j < 4; ++j) { const int n = (lane >> 3) + 8 * j; const LAS float* s = scr + (8 * c) * 33 + n;
;         u32x4 o; o.x = cvtpk(s[0 * 33], s[1 * 33]); o.y = cvtpk(s[2 * 33], s[3 * 33]); o.z = cvtpk(s[4 * 33], s[5 * 33]); o.w = cvtpk(s[6 * 33], s[7 * 33]);
;         int nr = n0 + n; if (kvperm == 1) { const int hh = nr >> 8, ww = nr & 255; nr = (ww < 128) ? hh * 128 + ww : 2048 + hh * 128 + (ww - 128); }
;         else if (kvperm == 2) { const int isv = nr >= 5632, f = isv ? nr - 5632 : nr; nr = (f >> 7) * 256 + isv * 128 + (f & 127); }
;         *(u32x4*)(WT + (size_t)nr * K + k0 + 8 * c) = o; }
;     asm volatile("s_waitcnt lgkmcnt(0)" ::: "memory");
; }
;     ...
;     while (it < i1) {
;         cur = nxt;
;         const int nit = it + NGW;
;         if (nit < i1) witem_load(nxt, W, N, gk, nit, nblk, lane);
;         witem_store(cur, K, WT, kvperm, scr, it, nblk, lane);
;         it = nit;
;     }
.LBB0_319:
	v_pk_mul_f32 v[4:5], v[10:11], v[76:77] op_sel_hi:[1,0]
	ds_write2_b32 v83, v4, v5 offset1:1
	v_pk_mul_f32 v[4:5], v[12:13], v[76:77] op_sel_hi:[1,0]
	ds_write2_b32 v83, v4, v5 offset0:2 offset1:3
	v_pk_mul_f32 v[4:5], v[6:7], v[78:79] op_sel_hi:[1,0]
	v_add_u32_e32 v6, 0x420, v83
	ds_write2_b32 v6, v4, v5 offset1:1
	v_pk_mul_f32 v[4:5], v[8:9], v[78:79] op_sel_hi:[1,0]
	v_add_u32_e32 v6, 0x428, v83
	ds_write2_b32 v6, v4, v5 offset1:1
	v_pk_mul_f32 v[4:5], v[22:23], v[80:81] op_sel_hi:[1,0]
	v_add_u32_e32 v6, 0x840, v83
	ds_write2_b32 v6, v4, v5 offset1:1
	v_pk_mul_f32 v[4:5], v[24:25], v[80:81] op_sel_hi:[1,0]
	v_add_u32_e32 v6, 0x848, v83
	ds_write2_b32 v6, v4, v5 offset1:1
	v_pk_mul_f32 v[4:5], v[14:15], v[82:83] op_sel_hi:[1,0]
	v_add_u32_e32 v6, 0xc60, v83
	ds_write2_b32 v6, v4, v5 offset1:1
	v_pk_mul_f32 v[4:5], v[16:17], v[82:83] op_sel_hi:[1,0]
	v_add_u32_e32 v6, 0xc68, v83
	ds_write2_b32 v6, v4, v5 offset1:1
	v_pk_mul_f32 v[4:5], v[34:35], v[84:85] op_sel_hi:[1,0]
	v_add_u32_e32 v6, 0x1080, v83
	ds_write2_b32 v6, v4, v5 offset1:1
	v_pk_mul_f32 v[4:5], v[36:37], v[84:85] op_sel_hi:[1,0]
	v_add_u32_e32 v6, 0x1088, v83
	ds_write2_b32 v6, v4, v5 offset1:1
	s_waitcnt vmcnt(7)
	v_pk_mul_f32 v[4:5], v[30:31], v[86:87] op_sel_hi:[1,0]
	v_add_u32_e32 v6, 0x14a0, v83
	ds_write2_b32 v6, v4, v5 offset1:1
	v_pk_mul_f32 v[4:5], v[32:33], v[86:87] op_sel_hi:[1,0]
	v_add_u32_e32 v6, 0x14a8, v83
	ds_write2_b32 v6, v4, v5 offset1:1
	v_pk_mul_f32 v[4:5], v[46:47], v[88:89] op_sel_hi:[1,0]
	v_add_u32_e32 v6, 0x18c0, v83
	s_mul_hi_i32 s12, s16, 0x51eb851f
	ds_write2_b32 v6, v4, v5 offset1:1
	v_pk_mul_f32 v[4:5], v[48:49], v[88:89] op_sel_hi:[1,0]
	v_add_u32_e32 v6, 0x18c8, v83
	s_lshr_b32 s13, s12, 31
	s_ashr_i32 s12, s12, 6
	ds_write2_b32 v6, v4, v5 offset1:1
	s_waitcnt vmcnt(6)
	v_pk_mul_f32 v[4:5], v[38:39], v[90:91] op_sel_hi:[1,0]
	v_add_u32_e32 v6, 0x1ce0, v83
	s_add_i32 s16, s12, s13
	ds_write2_b32 v6, v4, v5 offset1:1
	v_pk_mul_f32 v[4:5], v[40:41], v[90:91] op_sel_hi:[1,0]
	v_add_u32_e32 v6, 0x1ce8, v83
	s_lshl_b32 s12, s16, 6
	ds_write2_b32 v6, v4, v5 offset1:1
	s_waitcnt lgkmcnt(0)
	s_ashr_i32 s13, s12, 31
	ds_read2_b32 v[8:9], v81 offset0:33 offset1:41
	ds_read2_b32 v[10:11], v81 offset1:8
	ds_read2_b32 v[12:13], v81 offset0:66 offset1:74
	ds_read2_b32 v[14:15], v81 offset0:99 offset1:107
	ds_read2_b32 v[16:17], v81 offset0:132 offset1:140
	ds_read2_b32 v[22:23], v81 offset0:165 offset1:173
	ds_read2_b32 v[24:25], v81 offset0:198 offset1:206
	ds_read2_b32 v[30:31], v81 offset0:231 offset1:239
	v_lshl_add_u64 v[32:33], s[12:13], 1, v[74:75]
	s_mul_i32 s12, s16, 0xffffe700
	s_add_i32 s12, s12, s17
	v_add_u32_e32 v34, s12, v85
	v_ashrrev_i32_e32 v35, 31, v34
	v_lshlrev_b64 v[36:37], 12, v[34:35]
	s_waitcnt lgkmcnt(6)
	v_cvt_pk_bf16_f32 v4, v10, v8
	s_waitcnt lgkmcnt(4)
	v_cvt_pk_bf16_f32 v5, v12, v14
	s_waitcnt lgkmcnt(2)
	v_cvt_pk_bf16_f32 v6, v16, v22
	s_waitcnt lgkmcnt(0)
	v_cvt_pk_bf16_f32 v7, v24, v30
	v_lshl_add_u64 v[36:37], v[32:33], 0, v[36:37]
	v_add_u32_e32 v8, 8, v34
	global_store_dwordx4 v[36:37], v[4:7], off sc0 sc1
	s_waitcnt vmcnt(3)
	v_mov_b64_e32 v[46:47], v[62:63]
	s_waitcnt vmcnt(2)
	v_mov_b64_e32 v[38:39], v[66:67]
	v_cvt_pk_bf16_f32 v4, v11, v9
	v_ashrrev_i32_e32 v9, 31, v8
	v_cvt_pk_bf16_f32 v5, v13, v15
	v_cvt_pk_bf16_f32 v6, v17, v23
	v_cvt_pk_bf16_f32 v7, v25, v31
	v_lshlrev_b64 v[8:9], 12, v[8:9]
	ds_read2_b32 v[10:11], v81 offset0:49 offset1:57
	ds_read2_b32 v[12:13], v81 offset0:16 offset1:24
	ds_read2_b32 v[14:15], v81 offset0:82 offset1:90
	ds_read2_b32 v[16:17], v81 offset0:115 offset1:123
	ds_read2_b32 v[22:23], v81 offset0:148 offset1:156
	ds_read2_b32 v[24:25], v81 offset0:181 offset1:189
	ds_read2_b32 v[30:31], v81 offset0:214 offset1:222
	ds_read2_b32 v[36:37], v81 offset0:247 offset1:255
	v_lshl_add_u64 v[8:9], v[32:33], 0, v[8:9]
	global_store_dwordx4 v[8:9], v[4:7], off sc0 sc1
	v_add_u32_e32 v8, 16, v34
	v_ashrrev_i32_e32 v9, 31, v8
	v_lshlrev_b64 v[8:9], 12, v[8:9]
	s_waitcnt lgkmcnt(6)
	v_cvt_pk_bf16_f32 v4, v12, v10
	s_waitcnt lgkmcnt(4)
	v_cvt_pk_bf16_f32 v5, v14, v16
	s_waitcnt lgkmcnt(2)
	v_cvt_pk_bf16_f32 v6, v22, v24
	s_waitcnt lgkmcnt(0)
	v_cvt_pk_bf16_f32 v7, v30, v36
	v_lshl_add_u64 v[8:9], v[32:33], 0, v[8:9]
	global_store_dwordx4 v[8:9], v[4:7], off sc0 sc1
	v_add_u32_e32 v8, 24, v34
	v_ashrrev_i32_e32 v9, 31, v8
	v_lshlrev_b64 v[8:9], 12, v[8:9]
	v_cvt_pk_bf16_f32 v4, v13, v11
	v_cvt_pk_bf16_f32 v5, v15, v17
	v_cvt_pk_bf16_f32 v6, v23, v25
	v_cvt_pk_bf16_f32 v7, v31, v37
	v_lshl_add_u64 v[8:9], v[32:33], 0, v[8:9]
	global_store_dwordx4 v[8:9], v[4:7], off sc0 sc1
	s_waitcnt lgkmcnt(0)
	v_mov_b64_e32 v[10:11], v[26:27]
	v_mov_b64_e32 v[22:23], v[42:43]
	v_mov_b64_e32 v[6:7], v[18:19]
	v_mov_b64_e32 v[14:15], v[50:51]
	v_mov_b64_e32 v[34:35], v[54:55]
	v_mov_b64_e32 v[30:31], v[58:59]
	v_add_u32_e32 v85, s18, v85
	s_add_i32 s25, s25, s18
	v_add_u32_e32 v77, s18, v77
	s_andn2_b64 vcc, exec, s[6:7]
	s_mov_b32 s16, s26
	v_mov_b64_e32 v[12:13], v[28:29]
	v_mov_b64_e32 v[8:9], v[20:21]
	v_mov_b64_e32 v[24:25], v[44:45]
	v_mov_b64_e32 v[16:17], v[52:53]
	v_mov_b64_e32 v[36:37], v[56:57]
	v_mov_b64_e32 v[32:33], v[60:61]
	v_mov_b64_e32 v[48:49], v[64:65]
	v_mov_b64_e32 v[40:41], v[68:69]
	v_mov_b32_e32 v76, v87
	v_mov_b32_e32 v78, v91
	v_mov_b32_e32 v80, v93
	v_mov_b32_e32 v82, v98
	v_mov_b32_e32 v84, v99
	v_mov_b32_e32 v86, v100
	v_mov_b32_e32 v88, v101
	s_waitcnt vmcnt(4)
	v_mov_b32_e32 v90, v3
	s_cbranch_vccz .LBB0_337

; #define LAS __attribute__((address_space(3)))
; __device__ __forceinline__ unsigned cvtpk(float lo, float hi) { f32x2 v = {lo, hi}; bf16x2_t b = __builtin_convertvector(v, bf16x2_t); return __builtin_bit_cast(unsigned, b); }
; __device__ __forceinline__ void witem_store(const WItem& w, int K, bf16_t* WT, int kvperm, LAS float* scr, int item, int nblk, int lane) {
;     const int kb = item / nblk, nb = item % nblk, k0 = 64 * kb, n0 = 32 * nb;
;     const int col = 4 * (lane & 7), rr = lane >> 3;
; #pragma unroll
;     for (int i = 0; i < 8; ++i) { LAS float* d = scr + (8 * i + rr) * 33 + col; const float g = w.g[i]; d[0] = w.v[i].x * g; d[1] = w.v[i].y * g; d[2] = w.v[i].z * g; d[3] = w.v[i].w * g; }
;     asm volatile("s_waitcnt lgkmcnt(0)" ::: "memory");
;     const int c = lane & 7;
; #pragma unroll
;     for (int j = 0; j < 4; ++j) { const int n = (lane >> 3) + 8 * j; const LAS float* s = scr + (8 * c) * 33 + n;
;         u32x4 o; o.x = cvtpk(s[0 * 33], s[1 * 33]); o.y = cvtpk(s[2 * 33], s[3 * 33]); o.z = cvtpk(s[4 * 33], s[5 * 33]); o.w = cvtpk(s[6 * 33], s[7 * 33]);
;         int nr = n0 + n; if (kvperm == 1) { const int hh = nr >> 8, ww = nr & 255; nr = (ww < 128) ? hh * 128 + ww : 2048 + hh * 128 + (ww - 128); }
;         else if (kvperm == 2) { const int isv = nr >= 5632, f = isv ? nr - 5632 : nr; nr = (f >> 7) * 256 + isv * 128 + (f & 127); }
;         *(u32x4*)(WT + (size_t)nr * K + k0 + 8 * c) = o; }
;     asm volatile("s_waitcnt lgkmcnt(0)" ::: "memory");
; }
;     ...
;     while (it < i1) {
;         cur = nxt;
;         const int nit = it + NGW;
;         if (nit < i1) witem_load(nxt, W, N, gk, nit, nblk, lane);
;         witem_store(cur, K, WT, kvperm, scr, it, nblk, lane);
;         it = nit;
;     }
.LBB0_382:
	v_pk_mul_f32 v[2:3], v[2:3], v[72:73] op_sel_hi:[1,0]
	ds_write2_b32 v79, v2, v3 offset1:1
	v_pk_mul_f32 v[2:3], v[4:5], v[72:73] op_sel_hi:[1,0]
	ds_write2_b32 v79, v2, v3 offset0:2 offset1:3
	v_pk_mul_f32 v[2:3], v[6:7], v[74:75] op_sel_hi:[1,0]
	v_add_u32_e32 v4, 0x420, v79
	ds_write2_b32 v4, v2, v3 offset1:1
	v_pk_mul_f32 v[2:3], v[8:9], v[74:75] op_sel_hi:[1,0]
	v_add_u32_e32 v4, 0x428, v79
	ds_write2_b32 v4, v2, v3 offset1:1
	v_pk_mul_f32 v[2:3], v[10:11], v[76:77] op_sel_hi:[1,0]
	v_add_u32_e32 v4, 0x840, v79
	ds_write2_b32 v4, v2, v3 offset1:1
	v_pk_mul_f32 v[2:3], v[12:13], v[76:77] op_sel_hi:[1,0]
	v_add_u32_e32 v4, 0x848, v79
	ds_write2_b32 v4, v2, v3 offset1:1
	v_pk_mul_f32 v[2:3], v[14:15], v[78:79] op_sel_hi:[1,0]
	v_add_u32_e32 v4, 0xc60, v79
	ds_write2_b32 v4, v2, v3 offset1:1
	v_pk_mul_f32 v[2:3], v[16:17], v[78:79] op_sel_hi:[1,0]
	v_add_u32_e32 v4, 0xc68, v79
	ds_write2_b32 v4, v2, v3 offset1:1
	v_pk_mul_f32 v[2:3], v[18:19], v[84:85] op_sel_hi:[1,0]
	v_add_u32_e32 v4, 0x1080, v79
	ds_write2_b32 v4, v2, v3 offset1:1
	v_pk_mul_f32 v[2:3], v[20:21], v[84:85] op_sel_hi:[1,0]
	v_add_u32_e32 v4, 0x1088, v79
	ds_write2_b32 v4, v2, v3 offset1:1
	v_pk_mul_f32 v[2:3], v[26:27], v[86:87] op_sel_hi:[1,0]
	v_add_u32_e32 v4, 0x14a0, v79
	s_mul_hi_i32 s4, s26, 0x2e8ba2e9
	ds_write2_b32 v4, v2, v3 offset1:1
	v_pk_mul_f32 v[2:3], v[28:29], v[86:87] op_sel_hi:[1,0]
	v_add_u32_e32 v4, 0x14a8, v79
	s_lshr_b32 s5, s4, 31
	s_ashr_i32 s4, s4, 6
	ds_write2_b32 v4, v2, v3 offset1:1
	v_pk_mul_f32 v[2:3], v[30:31], v[88:89] op_sel_hi:[1,0]
	v_add_u32_e32 v4, 0x18c0, v79
	s_add_i32 s6, s4, s5
	ds_write2_b32 v4, v2, v3 offset1:1
	v_pk_mul_f32 v[2:3], v[32:33], v[88:89] op_sel_hi:[1,0]
	v_add_u32_e32 v4, 0x18c8, v79
	s_lshl_b32 s4, s6, 6
	ds_write2_b32 v4, v2, v3 offset1:1
	s_waitcnt vmcnt(0)
	v_pk_mul_f32 v[2:3], v[38:39], v[90:91] op_sel_hi:[1,0]
	v_add_u32_e32 v4, 0x1ce0, v79
	ds_write2_b32 v4, v2, v3 offset1:1
	v_pk_mul_f32 v[2:3], v[40:41], v[90:91] op_sel_hi:[1,0]
	v_add_u32_e32 v4, 0x1ce8, v79
	s_ashr_i32 s5, s4, 31
	ds_write2_b32 v4, v2, v3 offset1:1
	v_lshl_add_u64 v[24:25], s[4:5], 1, v[82:83]
	s_mul_i32 s4, s6, 0xffffd400
	s_waitcnt lgkmcnt(0)
	s_add_i32 s4, s4, s28
	ds_read2_b32 v[6:7], v77 offset0:33 offset1:41
	ds_read2_b32 v[8:9], v77 offset1:8
	ds_read2_b32 v[10:11], v77 offset0:66 offset1:74
	ds_read2_b32 v[12:13], v77 offset0:99 offset1:107
	ds_read2_b32 v[14:15], v77 offset0:132 offset1:140
	ds_read2_b32 v[16:17], v77 offset0:165 offset1:173
	ds_read2_b32 v[18:19], v77 offset0:198 offset1:206
	ds_read2_b32 v[20:21], v77 offset0:231 offset1:239
	v_add_u32_e32 v28, s4, v87
	s_waitcnt lgkmcnt(6)
	v_cvt_pk_bf16_f32 v2, v8, v6
	v_add_u32_e32 v6, 0xffffea00, v28
	v_cmp_lt_i32_e32 vcc, s34, v28
	s_waitcnt lgkmcnt(4)
	v_cvt_pk_bf16_f32 v3, v10, v12
	s_waitcnt lgkmcnt(2)
	v_cvt_pk_bf16_f32 v4, v14, v16
	v_cndmask_b32_e32 v6, v28, v6, vcc
	v_lshlrev_b32_e32 v8, 1, v6
	v_and_b32_e32 v8, 0xffffff00, v8
	v_cndmask_b32_e32 v10, 0, v85, vcc
	v_and_b32_e32 v6, 0x67, v6
	v_or3_b32 v26, v6, v10, v8
	v_ashrrev_i32_e32 v27, 31, v26
	v_lshlrev_b64 v[26:27], 12, v[26:27]
	s_waitcnt lgkmcnt(0)
	v_cvt_pk_bf16_f32 v5, v18, v20
	v_lshl_add_u64 v[26:27], v[24:25], 0, v[26:27]
	v_add_u32_e32 v6, 8, v28
	global_store_dwordx4 v[26:27], v[2:5], off sc0 sc1
	v_cmp_lt_i32_e32 vcc, s34, v6
	v_mov_b64_e32 v[30:31], v[62:63]
	v_cvt_pk_bf16_f32 v2, v9, v7
	v_add_u32_e32 v7, 0xffffea08, v28
	v_cndmask_b32_e32 v6, v6, v7, vcc
	v_lshlrev_b32_e32 v7, 1, v6
	v_and_b32_e32 v7, 0xffffff00, v7
	v_cndmask_b32_e32 v8, 0, v85, vcc
	v_and_b32_e32 v6, 0x6f, v6
	v_or3_b32 v6, v6, v8, v7
	v_ashrrev_i32_e32 v7, 31, v6
	v_lshlrev_b64 v[6:7], 12, v[6:7]
	v_cvt_pk_bf16_f32 v3, v11, v13
	v_cvt_pk_bf16_f32 v4, v15, v17
	v_cvt_pk_bf16_f32 v5, v19, v21
	v_lshl_add_u64 v[6:7], v[24:25], 0, v[6:7]
	ds_read2_b32 v[8:9], v77 offset0:16 offset1:24
	ds_read2_b32 v[10:11], v77 offset0:49 offset1:57
	ds_read2_b32 v[12:13], v77 offset0:82 offset1:90
	ds_read2_b32 v[14:15], v77 offset0:115 offset1:123
	ds_read2_b32 v[16:17], v77 offset0:148 offset1:156
	ds_read2_b32 v[18:19], v77 offset0:181 offset1:189
	ds_read2_b32 v[20:21], v77 offset0:214 offset1:222
	ds_read2_b32 v[26:27], v77 offset0:247 offset1:255
	global_store_dwordx4 v[6:7], v[2:5], off sc0 sc1
	v_add_u32_e32 v6, 16, v28
	v_add_u32_e32 v7, 0xffffea10, v28
	v_cmp_lt_i32_e32 vcc, s34, v6
	s_waitcnt lgkmcnt(6)
	v_cvt_pk_bf16_f32 v2, v8, v10
	s_waitcnt lgkmcnt(4)
	v_cvt_pk_bf16_f32 v3, v12, v14
	v_cndmask_b32_e32 v6, v6, v7, vcc
	v_lshlrev_b32_e32 v7, 1, v6
	v_and_b32_e32 v7, 0xffffff00, v7
	v_cndmask_b32_e32 v8, 0, v85, vcc
	v_and_b32_e32 v6, 0x77, v6
	v_or3_b32 v6, v6, v8, v7
	v_ashrrev_i32_e32 v7, 31, v6
	v_lshlrev_b64 v[6:7], 12, v[6:7]
	s_waitcnt lgkmcnt(2)
	v_cvt_pk_bf16_f32 v4, v16, v18
	s_waitcnt lgkmcnt(0)
	v_cvt_pk_bf16_f32 v5, v20, v26
	v_lshl_add_u64 v[6:7], v[24:25], 0, v[6:7]
	global_store_dwordx4 v[6:7], v[2:5], off sc0 sc1
	v_mov_b64_e32 v[38:39], v[66:67]
	v_add_u32_e32 v87, s29, v87
	v_add_u32_e32 v2, 24, v28
	v_add_u32_e32 v3, 0xffffea18, v28
	v_cmp_lt_i32_e32 vcc, s34, v2
	v_cvt_pk_bf16_f32 v5, v21, v27
	v_mov_b64_e32 v[26:27], v[58:59]
	v_cndmask_b32_e32 v2, v2, v3, vcc
	v_lshlrev_b32_e32 v3, 1, v2
	v_and_b32_e32 v3, 0xffffff00, v3
	v_cndmask_b32_e32 v4, 0, v85, vcc
	v_and_b32_e32 v2, 0x7f, v2
	v_or3_b32 v6, v2, v4, v3
	v_ashrrev_i32_e32 v7, 31, v6
	v_lshlrev_b64 v[6:7], 12, v[6:7]
	v_cvt_pk_bf16_f32 v2, v9, v11
	v_cvt_pk_bf16_f32 v3, v13, v15
	v_cvt_pk_bf16_f32 v4, v17, v19
	v_lshl_add_u64 v[6:7], v[24:25], 0, v[6:7]
	global_store_dwordx4 v[6:7], v[2:5], off sc0 sc1
	s_waitcnt lgkmcnt(0)
	v_mov_b64_e32 v[6:7], v[42:43]
	v_mov_b64_e32 v[10:11], v[46:47]
	v_mov_b64_e32 v[2:3], v[34:35]
	v_mov_b64_e32 v[14:15], v[50:51]
	v_mov_b64_e32 v[18:19], v[54:55]
	s_add_i32 s35, s35, s29
	v_add_u32_e32 v73, s29, v73
	s_andn2_b64 vcc, exec, s[18:19]
	s_mov_b32 s26, s36
	v_mov_b64_e32 v[4:5], v[36:37]
	v_mov_b64_e32 v[8:9], v[44:45]
	v_mov_b64_e32 v[12:13], v[48:49]
	v_mov_b64_e32 v[16:17], v[52:53]
	v_mov_b64_e32 v[20:21], v[56:57]
	v_mov_b64_e32 v[28:29], v[60:61]
	v_mov_b64_e32 v[32:33], v[64:65]
	v_mov_b64_e32 v[40:41], v[68:69]
	v_mov_b32_e32 v72, v91
	v_mov_b32_e32 v74, v96
	v_mov_b32_e32 v76, v97
	v_mov_b32_e32 v78, v98
	v_mov_b32_e32 v84, v99
	v_mov_b32_e32 v86, v100
	v_mov_b32_e32 v88, v101
	v_mov_b32_e32 v90, v23
	s_cbranch_vccz .LBB0_422

; #define LAS __attribute__((address_space(3)))
; __device__ __forceinline__ unsigned cvtpk(float lo, float hi) { f32x2 v = {lo, hi}; bf16x2_t b = __builtin_convertvector(v, bf16x2_t); return __builtin_bit_cast(unsigned, b); }
; __device__ __forceinline__ void witem_store(const WItem& w, int K, bf16_t* WT, int kvperm, LAS float* scr, int item, int nblk, int lane) {
;     const int kb = item / nblk, nb = item % nblk, k0 = 64 * kb, n0 = 32 * nb;
;     const int col = 4 * (lane & 7), rr = lane >> 3;
; #pragma unroll
;     for (int i = 0; i < 8; ++i) { LAS float* d = scr + (8 * i + rr) * 33 + col; const float g = w.g[i]; d[0] = w.v[i].x * g; d[1] = w.v[i].y * g; d[2] = w.v[i].z * g; d[3] = w.v[i].w * g; }
;     asm volatile("s_waitcnt lgkmcnt(0)" ::: "memory");
;     const int c = lane & 7;
; #pragma unroll
;     for (int j = 0; j < 4; ++j) { const int n = (lane >> 3) + 8 * j; const LAS float* s = scr + (8 * c) * 33 + n;
;         u32x4 o; o.x = cvtpk(s[0 * 33], s[1 * 33]); o.y = cvtpk(s[2 * 33], s[3 * 33]); o.z = cvtpk(s[4 * 33], s[5 * 33]); o.w = cvtpk(s[6 * 33], s[7 * 33]);
;         int nr = n0 + n; if (kvperm == 1) { const int hh = nr >> 8, ww = nr & 255; nr = (ww < 128) ? hh * 128 + ww : 2048 + hh * 128 + (ww - 128); }
;         else if (kvperm == 2) { const int isv = nr >= 5632, f = isv ? nr - 5632 : nr; nr = (f >> 7) * 256 + isv * 128 + (f & 127); }
;         *(u32x4*)(WT + (size_t)nr * K + k0 + 8 * c) = o; }
;     asm volatile("s_waitcnt lgkmcnt(0)" ::: "memory");
; }
;     ...
;     while (it < i1) {
;         cur = nxt;
;         const int nit = it + NGW;
;         if (nit < i1) witem_load(nxt, W, N, gk, nit, nblk, lane);
;         witem_store(cur, K, WT, kvperm, scr, it, nblk, lane);
;         it = nit;
;     }
.LBB0_441:
	ds_write2_b32 v84, v6, v7 offset1:1
	ds_write2_b32 v84, v8, v9 offset0:2 offset1:3
	v_add_u32_e32 v6, 0x420, v84
	ds_write2_b32 v6, v2, v3 offset1:1
	v_add_u32_e32 v2, 0x428, v84
	ds_write2_b32 v2, v4, v5 offset1:1
	v_add_u32_e32 v2, 0x840, v84
	ds_write2_b32 v2, v14, v15 offset1:1
	v_add_u32_e32 v2, 0x848, v84
	ds_write2_b32 v2, v16, v17 offset1:1
	v_add_u32_e32 v2, 0xc60, v84
	ds_write2_b32 v2, v10, v11 offset1:1
	v_add_u32_e32 v2, 0xc68, v84
	ds_write2_b32 v2, v12, v13 offset1:1
	v_add_u32_e32 v2, 0x1080, v84
	ds_write2_b32 v2, v26, v27 offset1:1
	v_add_u32_e32 v2, 0x1088, v84
	ds_write2_b32 v2, v28, v29 offset1:1
	v_add_u32_e32 v2, 0x14a0, v84
	ds_write2_b32 v2, v18, v19 offset1:1
	v_add_u32_e32 v2, 0x14a8, v84
	ds_write2_b32 v2, v20, v21 offset1:1
	v_add_u32_e32 v2, 0x18c0, v84
	ds_write2_b32 v2, v38, v39 offset1:1
	v_add_u32_e32 v2, 0x18c8, v84
	ds_write2_b32 v2, v40, v41 offset1:1
	v_add_u32_e32 v2, 0x1ce0, v84
	ds_write2_b32 v2, v42, v43 offset1:1
	v_add_u32_e32 v2, 0x1ce8, v84
	s_ashr_i32 s16, s21, 31
	ds_write2_b32 v2, v44, v45 offset1:1
	s_lshr_b32 s16, s16, 26
	s_waitcnt lgkmcnt(0)
	s_add_i32 s16, s21, s16
	ds_read2_b32 v[6:7], v82 offset0:33 offset1:41
	ds_read2_b32 v[8:9], v82 offset1:8
	ds_read2_b32 v[10:11], v82 offset0:66 offset1:74
	ds_read2_b32 v[12:13], v82 offset0:99 offset1:107
	ds_read2_b32 v[14:15], v82 offset0:132 offset1:140
	ds_read2_b32 v[16:17], v82 offset0:165 offset1:173
	ds_read2_b32 v[18:19], v82 offset0:198 offset1:206
	ds_read2_b32 v[20:21], v82 offset0:231 offset1:239
	s_lshr_b32 s21, s16, 6
	s_andn2_b32 s16, s16, 63
	s_mul_i32 s21, s21, 0xff500000
	s_ashr_i32 s17, s16, 31
	v_add_u32_e32 v26, s21, v83
	v_lshl_add_u64 v[24:25], s[16:17], 1, v[74:75]
	v_ashrrev_i32_e32 v27, 31, v26
	s_waitcnt lgkmcnt(6)
	v_cvt_pk_bf16_f32 v2, v8, v6
	s_waitcnt lgkmcnt(4)
	v_cvt_pk_bf16_f32 v3, v10, v12
	s_waitcnt lgkmcnt(2)
	v_cvt_pk_bf16_f32 v4, v14, v16
	s_waitcnt lgkmcnt(0)
	v_cvt_pk_bf16_f32 v5, v18, v20
	v_lshl_add_u64 v[28:29], v[26:27], 1, v[24:25]
	global_store_dwordx4 v[28:29], v[2:5], off sc0 sc1
	v_add_u32_e32 v6, 0xb000, v26
	s_waitcnt vmcnt(1)
	v_mov_b64_e32 v[38:39], v[62:63]
	v_cvt_pk_bf16_f32 v2, v9, v7
	v_cvt_pk_bf16_f32 v3, v11, v13
	v_cvt_pk_bf16_f32 v4, v15, v17
	v_cvt_pk_bf16_f32 v5, v19, v21
	ds_read2_b32 v[8:9], v82 offset0:49 offset1:57
	ds_read2_b32 v[10:11], v82 offset0:16 offset1:24
	ds_read2_b32 v[12:13], v82 offset0:82 offset1:90
	ds_read2_b32 v[14:15], v82 offset0:115 offset1:123
	ds_read2_b32 v[16:17], v82 offset0:148 offset1:156
	ds_read2_b32 v[18:19], v82 offset0:181 offset1:189
	ds_read2_b32 v[20:21], v82 offset0:214 offset1:222
	ds_read2_b32 v[28:29], v82 offset0:247 offset1:255
	v_ashrrev_i32_e32 v7, 31, v6
	v_lshl_add_u64 v[6:7], v[6:7], 1, v[24:25]
	global_store_dwordx4 v[6:7], v[2:5], off sc0 sc1
	v_add_u32_e32 v6, 0x16000, v26
	v_ashrrev_i32_e32 v7, 31, v6
	s_waitcnt lgkmcnt(6)
	v_cvt_pk_bf16_f32 v2, v10, v8
	s_waitcnt lgkmcnt(4)
	v_cvt_pk_bf16_f32 v3, v12, v14
	s_waitcnt lgkmcnt(2)
	v_cvt_pk_bf16_f32 v4, v16, v18
	s_waitcnt lgkmcnt(0)
	v_cvt_pk_bf16_f32 v5, v20, v28
	v_lshl_add_u64 v[6:7], v[6:7], 1, v[24:25]
	global_store_dwordx4 v[6:7], v[2:5], off sc0 sc1
	v_add_u32_e32 v6, 0x21000, v26
	v_ashrrev_i32_e32 v7, 31, v6
	v_cvt_pk_bf16_f32 v2, v11, v9
	v_cvt_pk_bf16_f32 v3, v13, v15
	v_cvt_pk_bf16_f32 v4, v17, v19
	v_cvt_pk_bf16_f32 v5, v21, v29
	v_lshl_add_u64 v[6:7], v[6:7], 1, v[24:25]
	global_store_dwordx4 v[6:7], v[2:5], off sc0 sc1
	s_waitcnt lgkmcnt(0)
	v_mov_b64_e32 v[6:7], v[34:35]
	v_mov_b64_e32 v[14:15], v[46:47]
	v_mov_b64_e32 v[2:3], v[30:31]
	v_mov_b64_e32 v[10:11], v[50:51]
	v_mov_b64_e32 v[26:27], v[54:55]
	v_mov_b64_e32 v[18:19], v[58:59]
	v_add_u32_e32 v83, s2, v83
	s_add_i32 s25, s25, s26
	s_andn2_b64 vcc, exec, s[6:7]
	s_mov_b32 s21, s28
	v_mov_b64_e32 v[8:9], v[36:37]
	v_mov_b64_e32 v[4:5], v[32:33]
	v_mov_b64_e32 v[16:17], v[48:49]
	v_mov_b64_e32 v[12:13], v[52:53]
	v_mov_b64_e32 v[28:29], v[56:57]
	v_mov_b64_e32 v[20:21], v[60:61]
	v_mov_b64_e32 v[40:41], v[64:65]
	v_mov_b32_e32 v42, v66
	v_mov_b32_e32 v43, v67
	v_mov_b32_e32 v44, v68
	v_mov_b32_e32 v45, v69
	s_cbranch_vccz .LBB0_459

; #define LAS __attribute__((address_space(3)))
; __device__ __forceinline__ unsigned cvtpk(float lo, float hi) { f32x2 v = {lo, hi}; bf16x2_t b = __builtin_convertvector(v, bf16x2_t); return __builtin_bit_cast(unsigned, b); }
; __device__ __forceinline__ void witem_store(const WItem& w, int K, bf16_t* WT, int kvperm, LAS float* scr, int item, int nblk, int lane) {
;     const int kb = item / nblk, nb = item % nblk, k0 = 64 * kb, n0 = 32 * nb;
;     const int col = 4 * (lane & 7), rr = lane >> 3;
; #pragma unroll
;     for (int i = 0; i < 8; ++i) { LAS float* d = scr + (8 * i + rr) * 33 + col; const float g = w.g[i]; d[0] = w.v[i].x * g; d[1] = w.v[i].y * g; d[2] = w.v[i].z * g; d[3] = w.v[i].w * g; }
;     asm volatile("s_waitcnt lgkmcnt(0)" ::: "memory");
;     const int c = lane & 7;
; #pragma unroll
;     for (int j = 0; j < 4; ++j) { const int n = (lane >> 3) + 8 * j; const LAS float* s = scr + (8 * c) * 33 + n;
;         u32x4 o; o.x = cvtpk(s[0 * 33], s[1 * 33]); o.y = cvtpk(s[2 * 33], s[3 * 33]); o.z = cvtpk(s[4 * 33], s[5 * 33]); o.w = cvtpk(s[6 * 33], s[7 * 33]);
;         int nr = n0 + n; if (kvperm == 1) { const int hh = nr >> 8, ww = nr & 255; nr = (ww < 128) ? hh * 128 + ww : 2048 + hh * 128 + (ww - 128); }
;         else if (kvperm == 2) { const int isv = nr >= 5632, f = isv ? nr - 5632 : nr; nr = (f >> 7) * 256 + isv * 128 + (f & 127); }
;         *(u32x4*)(WT + (size_t)nr * K + k0 + 8 * c) = o; }
;     asm volatile("s_waitcnt lgkmcnt(0)" ::: "memory");
; }
;     ...
;     while (it < i1) {
;         cur = nxt;
;         const int nit = it + NGW;
;         if (nit < i1) witem_load(nxt, W, N, gk, nit, nblk, lane);
;         witem_store(cur, K, WT, kvperm, scr, it, nblk, lane);
;         it = nit;
;     }
.LBB0_478:
	ds_write2_b32 v84, v6, v7 offset1:1
	ds_write2_b32 v84, v8, v9 offset0:2 offset1:3
	v_add_u32_e32 v6, 0x420, v84
	ds_write2_b32 v6, v2, v3 offset1:1
	v_add_u32_e32 v2, 0x428, v84
	ds_write2_b32 v2, v4, v5 offset1:1
	v_add_u32_e32 v2, 0x840, v84
	ds_write2_b32 v2, v14, v15 offset1:1
	v_add_u32_e32 v2, 0x848, v84
	ds_write2_b32 v2, v16, v17 offset1:1
	v_add_u32_e32 v2, 0xc60, v84
	ds_write2_b32 v2, v10, v11 offset1:1
	v_add_u32_e32 v2, 0xc68, v84
	ds_write2_b32 v2, v12, v13 offset1:1
	v_add_u32_e32 v2, 0x1080, v84
	ds_write2_b32 v2, v26, v27 offset1:1
	v_add_u32_e32 v2, 0x1088, v84
	ds_write2_b32 v2, v28, v29 offset1:1
	v_add_u32_e32 v2, 0x14a0, v84
	ds_write2_b32 v2, v18, v19 offset1:1
	v_add_u32_e32 v2, 0x14a8, v84
	ds_write2_b32 v2, v20, v21 offset1:1
	v_add_u32_e32 v2, 0x18c0, v84
	ds_write2_b32 v2, v38, v39 offset1:1
	v_add_u32_e32 v2, 0x18c8, v84
	ds_write2_b32 v2, v40, v41 offset1:1
	v_add_u32_e32 v2, 0x1ce0, v84
	ds_write2_b32 v2, v42, v43 offset1:1
	v_add_u32_e32 v2, 0x1ce8, v84
	s_ashr_i32 s6, s19, 31
	ds_write2_b32 v2, v44, v45 offset1:1
	s_lshr_b32 s6, s6, 26
	s_waitcnt lgkmcnt(0)
	s_add_i32 s6, s19, s6
	ds_read2_b32 v[6:7], v82 offset0:33 offset1:41
	ds_read2_b32 v[8:9], v82 offset1:8
	ds_read2_b32 v[10:11], v82 offset0:66 offset1:74
	ds_read2_b32 v[12:13], v82 offset0:99 offset1:107
	ds_read2_b32 v[14:15], v82 offset0:132 offset1:140
	ds_read2_b32 v[16:17], v82 offset0:165 offset1:173
	ds_read2_b32 v[18:19], v82 offset0:198 offset1:206
	ds_read2_b32 v[20:21], v82 offset0:231 offset1:239
	s_lshr_b32 s19, s6, 6
	s_andn2_b32 s6, s6, 63
	s_mul_i32 s19, s19, 0xff500000
	s_ashr_i32 s7, s6, 31
	v_add_u32_e32 v26, s19, v83
	v_lshl_add_u64 v[24:25], s[6:7], 1, v[74:75]
	v_ashrrev_i32_e32 v27, 31, v26
	s_waitcnt lgkmcnt(6)
	v_cvt_pk_bf16_f32 v2, v8, v6
	s_waitcnt lgkmcnt(4)
	v_cvt_pk_bf16_f32 v3, v10, v12
	s_waitcnt lgkmcnt(2)
	v_cvt_pk_bf16_f32 v4, v14, v16
	s_waitcnt lgkmcnt(0)
	v_cvt_pk_bf16_f32 v5, v18, v20
	v_lshl_add_u64 v[28:29], v[26:27], 1, v[24:25]
	global_store_dwordx4 v[28:29], v[2:5], off sc0 sc1
	v_add_u32_e32 v6, 0xb000, v26
	s_waitcnt vmcnt(1)
	v_mov_b64_e32 v[38:39], v[62:63]
	v_cvt_pk_bf16_f32 v2, v9, v7
	v_cvt_pk_bf16_f32 v3, v11, v13
	v_cvt_pk_bf16_f32 v4, v15, v17
	v_cvt_pk_bf16_f32 v5, v19, v21
	ds_read2_b32 v[8:9], v82 offset0:49 offset1:57
	ds_read2_b32 v[10:11], v82 offset0:16 offset1:24
	ds_read2_b32 v[12:13], v82 offset0:82 offset1:90
	ds_read2_b32 v[14:15], v82 offset0:115 offset1:123
	ds_read2_b32 v[16:17], v82 offset0:148 offset1:156
	ds_read2_b32 v[18:19], v82 offset0:181 offset1:189
	ds_read2_b32 v[20:21], v82 offset0:214 offset1:222
	ds_read2_b32 v[28:29], v82 offset0:247 offset1:255
	v_ashrrev_i32_e32 v7, 31, v6
	v_lshl_add_u64 v[6:7], v[6:7], 1, v[24:25]
	global_store_dwordx4 v[6:7], v[2:5], off sc0 sc1
	v_add_u32_e32 v6, 0x16000, v26
	v_ashrrev_i32_e32 v7, 31, v6
	s_waitcnt lgkmcnt(6)
	v_cvt_pk_bf16_f32 v2, v10, v8
	s_waitcnt lgkmcnt(4)
	v_cvt_pk_bf16_f32 v3, v12, v14
	s_waitcnt lgkmcnt(2)
	v_cvt_pk_bf16_f32 v4, v16, v18
	s_waitcnt lgkmcnt(0)
	v_cvt_pk_bf16_f32 v5, v20, v28
	v_lshl_add_u64 v[6:7], v[6:7], 1, v[24:25]
	global_store_dwordx4 v[6:7], v[2:5], off sc0 sc1
	v_add_u32_e32 v6, 0x21000, v26
	v_ashrrev_i32_e32 v7, 31, v6
	v_cvt_pk_bf16_f32 v2, v11, v9
	v_cvt_pk_bf16_f32 v3, v13, v15
	v_cvt_pk_bf16_f32 v4, v17, v19
	v_cvt_pk_bf16_f32 v5, v21, v29
	v_lshl_add_u64 v[6:7], v[6:7], 1, v[24:25]
	global_store_dwordx4 v[6:7], v[2:5], off sc0 sc1
	s_waitcnt lgkmcnt(0)
	v_mov_b64_e32 v[6:7], v[34:35]
	v_mov_b64_e32 v[14:15], v[46:47]
	v_mov_b64_e32 v[2:3], v[30:31]
	v_mov_b64_e32 v[10:11], v[50:51]
	v_mov_b64_e32 v[26:27], v[54:55]
	v_mov_b64_e32 v[18:19], v[58:59]
	v_add_u32_e32 v83, s2, v83
	s_add_i32 s20, s20, s21
	s_andn2_b64 vcc, exec, s[4:5]
	s_mov_b32 s19, s25
	v_mov_b64_e32 v[8:9], v[36:37]
	v_mov_b64_e32 v[4:5], v[32:33]
	v_mov_b64_e32 v[16:17], v[48:49]
	v_mov_b64_e32 v[12:13], v[52:53]
	v_mov_b64_e32 v[28:29], v[56:57]
	v_mov_b64_e32 v[20:21], v[60:61]
	v_mov_b64_e32 v[40:41], v[64:65]
	v_mov_b32_e32 v42, v66
	v_mov_b32_e32 v43, v67
	v_mov_b32_e32 v44, v68
	v_mov_b32_e32 v45, v69
	s_cbranch_vccz .LBB0_496

; #define LAS __attribute__((address_space(3)))
; __device__ __forceinline__ unsigned cvtpk(float lo, float hi) { f32x2 v = {lo, hi}; bf16x2_t b = __builtin_convertvector(v, bf16x2_t); return __builtin_bit_cast(unsigned, b); }
; __device__ __forceinline__ void witem_store(const WItem& w, int K, bf16_t* WT, int kvperm, LAS float* scr, int item, int nblk, int lane) {
;     const int kb = item / nblk, nb = item % nblk, k0 = 64 * kb, n0 = 32 * nb;
;     const int col = 4 * (lane & 7), rr = lane >> 3;
; #pragma unroll
;     for (int i = 0; i < 8; ++i) { LAS float* d = scr + (8 * i + rr) * 33 + col; const float g = w.g[i]; d[0] = w.v[i].x * g; d[1] = w.v[i].y * g; d[2] = w.v[i].z * g; d[3] = w.v[i].w * g; }
;     asm volatile("s_waitcnt lgkmcnt(0)" ::: "memory");
;     const int c = lane & 7;
; #pragma unroll
;     for (int j = 0; j < 4; ++j) { const int n = (lane >> 3) + 8 * j; const LAS float* s = scr + (8 * c) * 33 + n;
;         u32x4 o; o.x = cvtpk(s[0 * 33], s[1 * 33]); o.y = cvtpk(s[2 * 33], s[3 * 33]); o.z = cvtpk(s[4 * 33], s[5 * 33]); o.w = cvtpk(s[6 * 33], s[7 * 33]);
;         int nr = n0 + n; if (kvperm == 1) { const int hh = nr >> 8, ww = nr & 255; nr = (ww < 128) ? hh * 128 + ww : 2048 + hh * 128 + (ww - 128); }
;         else if (kvperm == 2) { const int isv = nr >= 5632, f = isv ? nr - 5632 : nr; nr = (f >> 7) * 256 + isv * 128 + (f & 127); }
;         *(u32x4*)(WT + (size_t)nr * K + k0 + 8 * c) = o; }
;     asm volatile("s_waitcnt lgkmcnt(0)" ::: "memory");
; }
;     ...
;     while (it < i1) {
;         cur = nxt;
;         const int nit = it + NGW;
;         if (nit < i1) witem_load(nxt, W, N, gk, nit, nblk, lane);
;         witem_store(cur, K, WT, kvperm, scr, it, nblk, lane);
;         it = nit;
;     }
.LBB0_515:
	v_pk_mul_f32 v[4:5], v[18:19], v[76:77] op_sel_hi:[1,0]
	ds_write2_b32 v81, v4, v5 offset1:1
	v_pk_mul_f32 v[4:5], v[20:21], v[76:77] op_sel_hi:[1,0]
	ds_write2_b32 v81, v4, v5 offset0:2 offset1:3
	v_pk_mul_f32 v[4:5], v[6:7], v[78:79] op_sel_hi:[1,0]
	v_add_u32_e32 v6, 0x420, v81
	ds_write2_b32 v6, v4, v5 offset1:1
	v_pk_mul_f32 v[4:5], v[8:9], v[78:79] op_sel_hi:[1,0]
	v_add_u32_e32 v6, 0x428, v81
	ds_write2_b32 v6, v4, v5 offset1:1
	v_pk_mul_f32 v[4:5], v[26:27], v[80:81] op_sel_hi:[1,0]
	v_add_u32_e32 v6, 0x840, v81
	ds_write2_b32 v6, v4, v5 offset1:1
	v_pk_mul_f32 v[4:5], v[28:29], v[80:81] op_sel_hi:[1,0]
	v_add_u32_e32 v6, 0x848, v81
	ds_write2_b32 v6, v4, v5 offset1:1
	v_pk_mul_f32 v[4:5], v[22:23], v[82:83] op_sel_hi:[1,0]
	v_add_u32_e32 v6, 0xc60, v81
	ds_write2_b32 v6, v4, v5 offset1:1
	v_pk_mul_f32 v[4:5], v[24:25], v[82:83] op_sel_hi:[1,0]
	v_add_u32_e32 v6, 0xc68, v81
	ds_write2_b32 v6, v4, v5 offset1:1
	v_pk_mul_f32 v[4:5], v[42:43], v[84:85] op_sel_hi:[1,0]
	v_add_u32_e32 v6, 0x1080, v81
	ds_write2_b32 v6, v4, v5 offset1:1
	v_pk_mul_f32 v[4:5], v[44:45], v[84:85] op_sel_hi:[1,0]
	v_add_u32_e32 v6, 0x1088, v81
	ds_write2_b32 v6, v4, v5 offset1:1
	s_waitcnt vmcnt(7)
	v_pk_mul_f32 v[4:5], v[34:35], v[86:87] op_sel_hi:[1,0]
	v_add_u32_e32 v6, 0x14a0, v81
	s_mul_hi_i32 s12, s19, 0x2e8ba2e9
	ds_write2_b32 v6, v4, v5 offset1:1
	v_pk_mul_f32 v[4:5], v[36:37], v[86:87] op_sel_hi:[1,0]
	v_add_u32_e32 v6, 0x14a8, v81
	s_lshr_b32 s13, s12, 31
	s_ashr_i32 s12, s12, 6
	ds_write2_b32 v6, v4, v5 offset1:1
	s_waitcnt vmcnt(6)
	v_pk_mul_f32 v[4:5], v[54:55], v[88:89] op_sel_hi:[1,0]
	v_add_u32_e32 v6, 0x18c0, v81
	s_add_i32 s19, s12, s13
	ds_write2_b32 v6, v4, v5 offset1:1
	v_pk_mul_f32 v[4:5], v[56:57], v[88:89] op_sel_hi:[1,0]
	v_add_u32_e32 v6, 0x18c8, v81
	s_lshl_b32 s12, s19, 6
	ds_write2_b32 v6, v4, v5 offset1:1
	s_waitcnt vmcnt(5)
	v_pk_mul_f32 v[4:5], v[46:47], v[90:91] op_sel_hi:[1,0]
	v_add_u32_e32 v6, 0x1ce0, v81
	ds_write2_b32 v6, v4, v5 offset1:1
	v_pk_mul_f32 v[4:5], v[48:49], v[90:91] op_sel_hi:[1,0]
	v_add_u32_e32 v6, 0x1ce8, v81
	s_ashr_i32 s13, s12, 31
	ds_write2_b32 v6, v4, v5 offset1:1
	v_lshl_add_u64 v[36:37], s[12:13], 1, v[74:75]
	s_mul_i32 s12, s19, 0xffffd400
	s_waitcnt lgkmcnt(0)
	s_add_i32 s12, s12, s2
	ds_read2_b32 v[8:9], v79 offset0:33 offset1:41
	ds_read2_b32 v[18:19], v79 offset1:8
	ds_read2_b32 v[20:21], v79 offset0:66 offset1:74
	ds_read2_b32 v[22:23], v79 offset0:99 offset1:107
	ds_read2_b32 v[24:25], v79 offset0:132 offset1:140
	ds_read2_b32 v[26:27], v79 offset0:165 offset1:173
	ds_read2_b32 v[28:29], v79 offset0:198 offset1:206
	ds_read2_b32 v[34:35], v79 offset0:231 offset1:239
	v_add_u32_e32 v44, s12, v85
	s_waitcnt lgkmcnt(6)
	v_cvt_pk_bf16_f32 v4, v18, v8
	v_add_u32_e32 v8, 0xffffea00, v44
	v_cmp_lt_i32_e32 vcc, s18, v44
	s_waitcnt lgkmcnt(4)
	v_cvt_pk_bf16_f32 v5, v20, v22
	s_waitcnt lgkmcnt(2)
	v_cvt_pk_bf16_f32 v6, v24, v26
	v_cndmask_b32_e32 v8, v44, v8, vcc
	v_lshlrev_b32_e32 v18, 1, v8
	v_and_b32_e32 v18, 0xffffff00, v18
	v_cndmask_b32_e32 v20, 0, v83, vcc
	v_and_b32_e32 v8, 0x67, v8
	v_or3_b32 v42, v8, v20, v18
	v_ashrrev_i32_e32 v43, 31, v42
	v_lshlrev_b64 v[42:43], 12, v[42:43]
	s_waitcnt lgkmcnt(0)
	v_cvt_pk_bf16_f32 v7, v28, v34
	v_lshl_add_u64 v[42:43], v[36:37], 0, v[42:43]
	v_add_u32_e32 v8, 8, v44
	global_store_dwordx4 v[42:43], v[4:7], off sc0 sc1
	v_cmp_lt_i32_e32 vcc, s18, v8
	s_waitcnt vmcnt(3)
	v_mov_b64_e32 v[54:55], v[62:63]
	v_cvt_pk_bf16_f32 v4, v19, v9
	v_add_u32_e32 v9, 0xffffea08, v44
	v_cndmask_b32_e32 v8, v8, v9, vcc
	v_lshlrev_b32_e32 v9, 1, v8
	v_and_b32_e32 v9, 0xffffff00, v9
	v_cndmask_b32_e32 v18, 0, v83, vcc
	v_and_b32_e32 v8, 0x6f, v8
	v_or3_b32 v8, v8, v18, v9
	v_ashrrev_i32_e32 v9, 31, v8
	v_lshlrev_b64 v[8:9], 12, v[8:9]
	v_cvt_pk_bf16_f32 v5, v21, v23
	v_cvt_pk_bf16_f32 v6, v25, v27
	v_cvt_pk_bf16_f32 v7, v29, v35
	v_lshl_add_u64 v[8:9], v[36:37], 0, v[8:9]
	ds_read2_b32 v[18:19], v79 offset0:16 offset1:24
	ds_read2_b32 v[20:21], v79 offset0:49 offset1:57
	ds_read2_b32 v[22:23], v79 offset0:82 offset1:90
	ds_read2_b32 v[24:25], v79 offset0:115 offset1:123
	ds_read2_b32 v[26:27], v79 offset0:148 offset1:156
	ds_read2_b32 v[28:29], v79 offset0:181 offset1:189
	ds_read2_b32 v[34:35], v79 offset0:214 offset1:222
	ds_read2_b32 v[42:43], v79 offset0:247 offset1:255
	global_store_dwordx4 v[8:9], v[4:7], off sc0 sc1
	v_add_u32_e32 v8, 16, v44
	v_add_u32_e32 v9, 0xffffea10, v44
	v_cmp_lt_i32_e32 vcc, s18, v8
	s_waitcnt lgkmcnt(6)
	v_cvt_pk_bf16_f32 v4, v18, v20
	s_waitcnt lgkmcnt(4)
	v_cvt_pk_bf16_f32 v5, v22, v24
	v_cndmask_b32_e32 v8, v8, v9, vcc
	v_lshlrev_b32_e32 v9, 1, v8
	v_and_b32_e32 v9, 0xffffff00, v9
	v_cndmask_b32_e32 v18, 0, v83, vcc
	v_and_b32_e32 v8, 0x77, v8
	v_or3_b32 v8, v8, v18, v9
	v_ashrrev_i32_e32 v9, 31, v8
	v_lshlrev_b64 v[8:9], 12, v[8:9]
	s_waitcnt lgkmcnt(2)
	v_cvt_pk_bf16_f32 v6, v26, v28
	s_waitcnt lgkmcnt(0)
	v_cvt_pk_bf16_f32 v7, v34, v42
	v_lshl_add_u64 v[8:9], v[36:37], 0, v[8:9]
	global_store_dwordx4 v[8:9], v[4:7], off sc0 sc1
	s_waitcnt vmcnt(4)
	v_mov_b64_e32 v[46:47], v[66:67]
	v_add_u32_e32 v85, s14, v85
	v_add_u32_e32 v4, 24, v44
	v_add_u32_e32 v5, 0xffffea18, v44
	v_cmp_lt_i32_e32 vcc, s18, v4
	v_cvt_pk_bf16_f32 v7, v35, v43
	v_mov_b64_e32 v[42:43], v[50:51]
	v_cndmask_b32_e32 v4, v4, v5, vcc
	v_lshlrev_b32_e32 v5, 1, v4
	v_and_b32_e32 v5, 0xffffff00, v5
	v_cndmask_b32_e32 v6, 0, v83, vcc
	v_and_b32_e32 v4, 0x7f, v4
	v_or3_b32 v8, v4, v6, v5
	v_ashrrev_i32_e32 v9, 31, v8
	v_lshlrev_b64 v[8:9], 12, v[8:9]
	v_cvt_pk_bf16_f32 v4, v19, v21
	v_cvt_pk_bf16_f32 v5, v23, v25
	v_cvt_pk_bf16_f32 v6, v27, v29
	v_lshl_add_u64 v[8:9], v[36:37], 0, v[8:9]
	global_store_dwordx4 v[8:9], v[4:7], off sc0 sc1
	s_waitcnt lgkmcnt(0)
	v_mov_b64_e32 v[20:21], v[16:17]
	v_mov_b64_e32 v[26:27], v[30:31]
	v_mov_b64_e32 v[6:7], v[10:11]
	v_mov_b64_e32 v[22:23], v[38:39]
	v_mov_b64_e32 v[34:35], v[58:59]
	s_add_i32 s20, s20, s14
	v_add_u32_e32 v77, s14, v77
	s_andn2_b64 vcc, exec, s[6:7]
	s_mov_b32 s19, s21
	v_mov_b64_e32 v[18:19], v[14:15]
	v_mov_b64_e32 v[8:9], v[12:13]
	v_mov_b64_e32 v[28:29], v[32:33]
	v_mov_b64_e32 v[24:25], v[40:41]
	v_mov_b64_e32 v[44:45], v[52:53]
	v_mov_b64_e32 v[36:37], v[60:61]
	v_mov_b64_e32 v[56:57], v[64:65]
	v_mov_b64_e32 v[48:49], v[68:69]
	v_mov_b32_e32 v76, v87
	v_mov_b32_e32 v78, v89
	v_mov_b32_e32 v80, v91
	v_mov_b32_e32 v82, v93
	v_mov_b32_e32 v84, v98
	v_mov_b32_e32 v86, v99
	v_mov_b32_e32 v88, v100
	s_waitcnt vmcnt(4)
	v_mov_b32_e32 v90, v3
	s_cbranch_vccz .LBB0_533

; #define LAS __attribute__((address_space(3)))
; __device__ __forceinline__ unsigned cvtpk(float lo, float hi) { f32x2 v = {lo, hi}; bf16x2_t b = __builtin_convertvector(v, bf16x2_t); return __builtin_bit_cast(unsigned, b); }
; __device__ __forceinline__ void witem_store(const WItem& w, int K, bf16_t* WT, int kvperm, LAS float* scr, int item, int nblk, int lane) {
;     const int kb = item / nblk, nb = item % nblk, k0 = 64 * kb, n0 = 32 * nb;
;     const int col = 4 * (lane & 7), rr = lane >> 3;
; #pragma unroll
;     for (int i = 0; i < 8; ++i) { LAS float* d = scr + (8 * i + rr) * 33 + col; const float g = w.g[i]; d[0] = w.v[i].x * g; d[1] = w.v[i].y * g; d[2] = w.v[i].z * g; d[3] = w.v[i].w * g; }
;     asm volatile("s_waitcnt lgkmcnt(0)" ::: "memory");
;     const int c = lane & 7;
; #pragma unroll
;     for (int j = 0; j < 4; ++j) { const int n = (lane >> 3) + 8 * j; const LAS float* s = scr + (8 * c) * 33 + n;
;         u32x4 o; o.x = cvtpk(s[0 * 33], s[1 * 33]); o.y = cvtpk(s[2 * 33], s[3 * 33]); o.z = cvtpk(s[4 * 33], s[5 * 33]); o.w = cvtpk(s[6 * 33], s[7 * 33]);
;         int nr = n0 + n; if (kvperm == 1) { const int hh = nr >> 8, ww = nr & 255; nr = (ww < 128) ? hh * 128 + ww : 2048 + hh * 128 + (ww - 128); }
;         else if (kvperm == 2) { const int isv = nr >= 5632, f = isv ? nr - 5632 : nr; nr = (f >> 7) * 256 + isv * 128 + (f & 127); }
;         *(u32x4*)(WT + (size_t)nr * K + k0 + 8 * c) = o; }
;     asm volatile("s_waitcnt lgkmcnt(0)" ::: "memory");
; }
;     ...
;     while (it < i1) {
;         cur = nxt;
;         const int nit = it + NGW;
;         if (nit < i1) witem_load(nxt, W, N, gk, nit, nblk, lane);
;         witem_store(cur, K, WT, kvperm, scr, it, nblk, lane);
;         it = nit;
;     }
.LBB0_663:
	v_pk_mul_f32 v[2:3], v[8:9], v[72:73] op_sel_hi:[1,0]
	ds_write2_b32 v87, v2, v3 offset1:1
	v_pk_mul_f32 v[2:3], v[10:11], v[72:73] op_sel_hi:[1,0]
	ds_write2_b32 v87, v2, v3 offset0:2 offset1:3
	v_pk_mul_f32 v[2:3], v[4:5], v[74:75] op_sel_hi:[1,0]
	v_add_u32_e32 v4, 0x420, v87
	ds_write2_b32 v4, v2, v3 offset1:1
	v_pk_mul_f32 v[2:3], v[6:7], v[74:75] op_sel_hi:[1,0]
	v_add_u32_e32 v4, 0x428, v87
	ds_write2_b32 v4, v2, v3 offset1:1
	v_pk_mul_f32 v[2:3], v[20:21], v[76:77] op_sel_hi:[1,0]
	v_add_u32_e32 v4, 0x840, v87
	ds_write2_b32 v4, v2, v3 offset1:1
	v_pk_mul_f32 v[2:3], v[22:23], v[76:77] op_sel_hi:[1,0]
	v_add_u32_e32 v4, 0x848, v87
	ds_write2_b32 v4, v2, v3 offset1:1
	v_pk_mul_f32 v[2:3], v[12:13], v[78:79] op_sel_hi:[1,0]
	v_add_u32_e32 v4, 0xc60, v87
	ds_write2_b32 v4, v2, v3 offset1:1
	v_pk_mul_f32 v[2:3], v[14:15], v[78:79] op_sel_hi:[1,0]
	v_add_u32_e32 v4, 0xc68, v87
	ds_write2_b32 v4, v2, v3 offset1:1
	v_pk_mul_f32 v[2:3], v[32:33], v[80:81] op_sel_hi:[1,0]
	v_add_u32_e32 v4, 0x1080, v87
	ds_write2_b32 v4, v2, v3 offset1:1
	v_pk_mul_f32 v[2:3], v[34:35], v[80:81] op_sel_hi:[1,0]
	v_add_u32_e32 v4, 0x1088, v87
	ds_write2_b32 v4, v2, v3 offset1:1
	v_pk_mul_f32 v[2:3], v[28:29], v[82:83] op_sel_hi:[1,0]
	v_add_u32_e32 v4, 0x14a0, v87
	ds_write2_b32 v4, v2, v3 offset1:1
	v_pk_mul_f32 v[2:3], v[30:31], v[82:83] op_sel_hi:[1,0]
	v_add_u32_e32 v4, 0x14a8, v87
	ds_write2_b32 v4, v2, v3 offset1:1
	v_pk_mul_f32 v[2:3], v[44:45], v[84:85] op_sel_hi:[1,0]
	v_add_u32_e32 v4, 0x18c0, v87
	s_mul_hi_i32 s10, s17, 0x66666667
	ds_write2_b32 v4, v2, v3 offset1:1
	v_pk_mul_f32 v[2:3], v[46:47], v[84:85] op_sel_hi:[1,0]
	v_add_u32_e32 v4, 0x18c8, v87
	s_lshr_b32 s11, s10, 31
	s_ashr_i32 s10, s10, 5
	ds_write2_b32 v4, v2, v3 offset1:1
	v_pk_mul_f32 v[2:3], v[36:37], v[86:87] op_sel_hi:[1,0]
	v_add_u32_e32 v4, 0x1ce0, v87
	s_add_i32 s17, s10, s11
	ds_write2_b32 v4, v2, v3 offset1:1
	v_pk_mul_f32 v[2:3], v[38:39], v[86:87] op_sel_hi:[1,0]
	v_add_u32_e32 v4, 0x1ce8, v87
	s_lshl_b32 s10, s17, 6
	ds_write2_b32 v4, v2, v3 offset1:1
	s_waitcnt lgkmcnt(0)
	s_ashr_i32 s11, s10, 31
	ds_read2_b32 v[6:7], v85 offset0:33 offset1:41
	ds_read2_b32 v[8:9], v85 offset1:8
	ds_read2_b32 v[10:11], v85 offset0:66 offset1:74
	ds_read2_b32 v[12:13], v85 offset0:99 offset1:107
	ds_read2_b32 v[14:15], v85 offset0:132 offset1:140
	ds_read2_b32 v[20:21], v85 offset0:165 offset1:173
	ds_read2_b32 v[22:23], v85 offset0:198 offset1:206
	ds_read2_b32 v[28:29], v85 offset0:231 offset1:239
	v_lshl_add_u64 v[30:31], s[10:11], 1, v[70:71]
	s_mul_i32 s10, s17, 0xfffff600
	s_add_i32 s10, s10, s18
	v_add_u32_e32 v32, s10, v94
	v_ashrrev_i32_e32 v33, 31, v32
	v_lshlrev_b64 v[34:35], 12, v[32:33]
	s_waitcnt lgkmcnt(6)
	v_cvt_pk_bf16_f32 v2, v8, v6
	s_waitcnt lgkmcnt(4)
	v_cvt_pk_bf16_f32 v3, v10, v12
	s_waitcnt lgkmcnt(2)
	v_cvt_pk_bf16_f32 v4, v14, v20
	s_waitcnt lgkmcnt(0)
	v_cvt_pk_bf16_f32 v5, v22, v28
	v_lshl_add_u64 v[34:35], v[30:31], 0, v[34:35]
	v_add_u32_e32 v6, 8, v32
	global_store_dwordx4 v[34:35], v[2:5], off sc0 sc1
	s_waitcnt vmcnt(3)
	v_mov_b64_e32 v[44:45], v[60:61]
	s_waitcnt vmcnt(2)
	v_mov_b64_e32 v[36:37], v[64:65]
	v_cvt_pk_bf16_f32 v2, v9, v7
	v_ashrrev_i32_e32 v7, 31, v6
	v_cvt_pk_bf16_f32 v3, v11, v13
	v_cvt_pk_bf16_f32 v4, v15, v21
	v_cvt_pk_bf16_f32 v5, v23, v29
	v_lshlrev_b64 v[6:7], 12, v[6:7]
	ds_read2_b32 v[8:9], v85 offset0:49 offset1:57
	ds_read2_b32 v[10:11], v85 offset0:16 offset1:24
	ds_read2_b32 v[12:13], v85 offset0:82 offset1:90
	ds_read2_b32 v[14:15], v85 offset0:115 offset1:123
	ds_read2_b32 v[20:21], v85 offset0:148 offset1:156
	ds_read2_b32 v[22:23], v85 offset0:181 offset1:189
	ds_read2_b32 v[28:29], v85 offset0:214 offset1:222
	ds_read2_b32 v[34:35], v85 offset0:247 offset1:255
	v_lshl_add_u64 v[6:7], v[30:31], 0, v[6:7]
	global_store_dwordx4 v[6:7], v[2:5], off sc0 sc1
	v_add_u32_e32 v6, 16, v32
	v_ashrrev_i32_e32 v7, 31, v6
	v_lshlrev_b64 v[6:7], 12, v[6:7]
	s_waitcnt lgkmcnt(6)
	v_cvt_pk_bf16_f32 v2, v10, v8
	s_waitcnt lgkmcnt(4)
	v_cvt_pk_bf16_f32 v3, v12, v14
	s_waitcnt lgkmcnt(2)
	v_cvt_pk_bf16_f32 v4, v20, v22
	s_waitcnt lgkmcnt(0)
	v_cvt_pk_bf16_f32 v5, v28, v34
	v_lshl_add_u64 v[6:7], v[30:31], 0, v[6:7]
	global_store_dwordx4 v[6:7], v[2:5], off sc0 sc1
	v_add_u32_e32 v6, 24, v32
	v_ashrrev_i32_e32 v7, 31, v6
	v_lshlrev_b64 v[6:7], 12, v[6:7]
	v_cvt_pk_bf16_f32 v2, v11, v9
	v_cvt_pk_bf16_f32 v3, v13, v15
	v_cvt_pk_bf16_f32 v4, v21, v23
	v_cvt_pk_bf16_f32 v5, v29, v35
	v_lshl_add_u64 v[6:7], v[30:31], 0, v[6:7]
	global_store_dwordx4 v[6:7], v[2:5], off sc0 sc1
	s_waitcnt lgkmcnt(0)
	v_mov_b64_e32 v[8:9], v[24:25]
	v_mov_b64_e32 v[20:21], v[40:41]
	v_mov_b64_e32 v[4:5], v[16:17]
	v_mov_b64_e32 v[12:13], v[48:49]
	v_mov_b64_e32 v[32:33], v[52:53]
	v_mov_b64_e32 v[28:29], v[56:57]
	v_add_u32_e32 v94, s19, v94
	s_add_i32 s23, s23, s19
	v_add_u32_e32 v75, s19, v75
	s_andn2_b64 vcc, exec, s[8:9]
	s_mov_b32 s17, s24
	v_mov_b64_e32 v[10:11], v[26:27]
	v_mov_b64_e32 v[6:7], v[18:19]
	v_mov_b64_e32 v[22:23], v[42:43]
	v_mov_b64_e32 v[14:15], v[50:51]
	v_mov_b64_e32 v[34:35], v[54:55]
	v_mov_b64_e32 v[30:31], v[58:59]
	v_mov_b64_e32 v[46:47], v[62:63]
	v_mov_b64_e32 v[38:39], v[66:67]
	v_mov_b32_e32 v72, v89
	v_mov_b32_e32 v74, v95
	v_mov_b32_e32 v76, v96
	v_mov_b32_e32 v78, v97
	v_mov_b32_e32 v80, v98
	v_mov_b32_e32 v82, v99
	v_mov_b32_e32 v84, v100
	s_waitcnt vmcnt(4)
	v_mov_b32_e32 v86, v1
	s_cbranch_vccz .LBB0_681

; #define LAS __attribute__((address_space(3)))
; __device__ __forceinline__ unsigned cvtpk(float lo, float hi) { f32x2 v = {lo, hi}; bf16x2_t b = __builtin_convertvector(v, bf16x2_t); return __builtin_bit_cast(unsigned, b); }
; __device__ __forceinline__ void witem_store(const WItem& w, int K, bf16_t* WT, int kvperm, LAS float* scr, int item, int nblk, int lane) {
;     const int kb = item / nblk, nb = item % nblk, k0 = 64 * kb, n0 = 32 * nb;
;     const int col = 4 * (lane & 7), rr = lane >> 3;
; #pragma unroll
;     for (int i = 0; i < 8; ++i) { LAS float* d = scr + (8 * i + rr) * 33 + col; const float g = w.g[i]; d[0] = w.v[i].x * g; d[1] = w.v[i].y * g; d[2] = w.v[i].z * g; d[3] = w.v[i].w * g; }
;     asm volatile("s_waitcnt lgkmcnt(0)" ::: "memory");
;     const int c = lane & 7;
; #pragma unroll
;     for (int j = 0; j < 4; ++j) { const int n = (lane >> 3) + 8 * j; const LAS float* s = scr + (8 * c) * 33 + n;
;         u32x4 o; o.x = cvtpk(s[0 * 33], s[1 * 33]); o.y = cvtpk(s[2 * 33], s[3 * 33]); o.z = cvtpk(s[4 * 33], s[5 * 33]); o.w = cvtpk(s[6 * 33], s[7 * 33]);
;         int nr = n0 + n; if (kvperm == 1) { const int hh = nr >> 8, ww = nr & 255; nr = (ww < 128) ? hh * 128 + ww : 2048 + hh * 128 + (ww - 128); }
;         else if (kvperm == 2) { const int isv = nr >= 5632, f = isv ? nr - 5632 : nr; nr = (f >> 7) * 256 + isv * 128 + (f & 127); }
;         *(u32x4*)(WT + (size_t)nr * K + k0 + 8 * c) = o; }
;     asm volatile("s_waitcnt lgkmcnt(0)" ::: "memory");
; }
;     ...
;     while (it < i1) {
;         cur = nxt;
;         const int nit = it + NGW;
;         if (nit < i1) witem_load(nxt, W, N, gk, nit, nblk, lane);
;         witem_store(cur, K, WT, kvperm, scr, it, nblk, lane);
;         it = nit;
;     }
.LBB0_700:
	ds_write2_b32 v82, v4, v5 offset1:1
	ds_write2_b32 v82, v6, v7 offset0:2 offset1:3
	v_add_u32_e32 v4, 0x420, v82
	ds_write2_b32 v4, v0, v1 offset1:1
	v_add_u32_e32 v0, 0x428, v82
	ds_write2_b32 v0, v2, v3 offset1:1
	v_add_u32_e32 v0, 0x840, v82
	ds_write2_b32 v0, v12, v13 offset1:1
	v_add_u32_e32 v0, 0x848, v82
	ds_write2_b32 v0, v14, v15 offset1:1
	v_add_u32_e32 v0, 0xc60, v82
	ds_write2_b32 v0, v8, v9 offset1:1
	v_add_u32_e32 v0, 0xc68, v82
	ds_write2_b32 v0, v10, v11 offset1:1
	v_add_u32_e32 v0, 0x1080, v82
	ds_write2_b32 v0, v24, v25 offset1:1
	v_add_u32_e32 v0, 0x1088, v82
	ds_write2_b32 v0, v26, v27 offset1:1
	v_add_u32_e32 v0, 0x14a0, v82
	ds_write2_b32 v0, v20, v21 offset1:1
	v_add_u32_e32 v0, 0x14a8, v82
	ds_write2_b32 v0, v22, v23 offset1:1
	v_add_u32_e32 v0, 0x18c0, v82
	s_ashr_i32 s8, s16, 31
	ds_write2_b32 v0, v36, v37 offset1:1
	v_add_u32_e32 v0, 0x18c8, v82
	s_lshr_b32 s8, s8, 26
	ds_write2_b32 v0, v38, v39 offset1:1
	v_add_u32_e32 v0, 0x1ce0, v82
	s_add_i32 s16, s16, s8
	ds_write2_b32 v0, v40, v41 offset1:1
	v_add_u32_e32 v0, 0x1ce8, v82
	s_and_b32 s8, s16, 0xffffffc0
	ds_write2_b32 v0, v42, v43 offset1:1
	s_waitcnt lgkmcnt(0)
	s_ashr_i32 s9, s8, 31
	ds_read2_b32 v[4:5], v80 offset0:33 offset1:41
	ds_read2_b32 v[6:7], v80 offset1:8
	ds_read2_b32 v[8:9], v80 offset0:66 offset1:74
	ds_read2_b32 v[10:11], v80 offset0:99 offset1:107
	ds_read2_b32 v[12:13], v80 offset0:132 offset1:140
	ds_read2_b32 v[14:15], v80 offset0:165 offset1:173
	ds_read2_b32 v[18:19], v80 offset0:198 offset1:206
	ds_read2_b32 v[20:21], v80 offset0:231 offset1:239
	v_lshl_add_u64 v[22:23], s[8:9], 1, v[70:71]
	s_lshl_b32 s8, s16, 5
	s_waitcnt lgkmcnt(6)
	v_cvt_pk_bf16_f32 v0, v6, v4
	v_add_u32_e32 v4, s17, v83
	s_and_b32 s8, s8, 0xfffff800
	v_subrev_u32_e32 v24, s8, v4
	v_ashrrev_i32_e32 v25, 31, v24
	v_lshlrev_b64 v[26:27], 12, v[24:25]
	s_waitcnt lgkmcnt(4)
	v_cvt_pk_bf16_f32 v1, v8, v10
	s_waitcnt lgkmcnt(2)
	v_cvt_pk_bf16_f32 v2, v12, v14
	s_waitcnt lgkmcnt(0)
	v_cvt_pk_bf16_f32 v3, v18, v20
	v_lshl_add_u64 v[26:27], v[22:23], 0, v[26:27]
	v_add_u32_e32 v4, 8, v24
	global_store_dwordx4 v[26:27], v[0:3], off sc0 sc1
	s_waitcnt vmcnt(1)
	v_mov_b64_e32 v[36:37], v[60:61]
	v_add_u32_e32 v83, s18, v83
	v_cvt_pk_bf16_f32 v0, v7, v5
	v_ashrrev_i32_e32 v5, 31, v4
	v_cvt_pk_bf16_f32 v1, v9, v11
	v_cvt_pk_bf16_f32 v2, v13, v15
	v_cvt_pk_bf16_f32 v3, v19, v21
	v_lshlrev_b64 v[4:5], 12, v[4:5]
	ds_read2_b32 v[6:7], v80 offset0:49 offset1:57
	ds_read2_b32 v[8:9], v80 offset0:16 offset1:24
	ds_read2_b32 v[10:11], v80 offset0:82 offset1:90
	ds_read2_b32 v[12:13], v80 offset0:115 offset1:123
	ds_read2_b32 v[14:15], v80 offset0:148 offset1:156
	ds_read2_b32 v[18:19], v80 offset0:181 offset1:189
	ds_read2_b32 v[20:21], v80 offset0:214 offset1:222
	ds_read2_b32 v[26:27], v80 offset0:247 offset1:255
	v_lshl_add_u64 v[4:5], v[22:23], 0, v[4:5]
	global_store_dwordx4 v[4:5], v[0:3], off sc0 sc1
	v_add_u32_e32 v4, 16, v24
	v_ashrrev_i32_e32 v5, 31, v4
	v_lshlrev_b64 v[4:5], 12, v[4:5]
	s_waitcnt lgkmcnt(6)
	v_cvt_pk_bf16_f32 v0, v8, v6
	s_waitcnt lgkmcnt(4)
	v_cvt_pk_bf16_f32 v1, v10, v12
	s_waitcnt lgkmcnt(2)
	v_cvt_pk_bf16_f32 v2, v14, v18
	s_waitcnt lgkmcnt(0)
	v_cvt_pk_bf16_f32 v3, v20, v26
	v_lshl_add_u64 v[4:5], v[22:23], 0, v[4:5]
	global_store_dwordx4 v[4:5], v[0:3], off sc0 sc1
	v_add_u32_e32 v4, 24, v24
	v_ashrrev_i32_e32 v5, 31, v4
	v_lshlrev_b64 v[4:5], 12, v[4:5]
	v_cvt_pk_bf16_f32 v0, v9, v7
	v_cvt_pk_bf16_f32 v1, v11, v13
	v_cvt_pk_bf16_f32 v2, v15, v19
	v_cvt_pk_bf16_f32 v3, v21, v27
	v_lshl_add_u64 v[4:5], v[22:23], 0, v[4:5]
	global_store_dwordx4 v[4:5], v[0:3], off sc0 sc1
	s_waitcnt lgkmcnt(0)
	v_mov_b64_e32 v[4:5], v[32:33]
	v_mov_b64_e32 v[12:13], v[44:45]
	v_mov_b64_e32 v[0:1], v[28:29]
	v_mov_b64_e32 v[8:9], v[48:49]
	v_mov_b64_e32 v[24:25], v[52:53]
	v_mov_b64_e32 v[20:21], v[56:57]
	s_add_i32 s21, s21, s18
	v_add_u32_e32 v76, s18, v76
	s_andn2_b64 vcc, exec, s[6:7]
	s_mov_b32 s16, s22
	v_mov_b64_e32 v[6:7], v[34:35]
	v_mov_b64_e32 v[2:3], v[30:31]
	v_mov_b64_e32 v[14:15], v[46:47]
	v_mov_b64_e32 v[10:11], v[50:51]
	v_mov_b64_e32 v[26:27], v[54:55]
	v_mov_b64_e32 v[22:23], v[58:59]
	v_mov_b64_e32 v[38:39], v[62:63]
	v_mov_b32_e32 v40, v64
	v_mov_b32_e32 v41, v65
	v_mov_b32_e32 v42, v66
	v_mov_b32_e32 v43, v67
	s_cbranch_vccz .LBB0_718

; #define LAS __attribute__((address_space(3)))
; __device__ __forceinline__ unsigned cvtpk(float lo, float hi) { f32x2 v = {lo, hi}; bf16x2_t b = __builtin_convertvector(v, bf16x2_t); return __builtin_bit_cast(unsigned, b); }
; __device__ __forceinline__ void witem_store(const WItem& w, int K, bf16_t* WT, int kvperm, LAS float* scr, int item, int nblk, int lane) {
;     const int kb = item / nblk, nb = item % nblk, k0 = 64 * kb, n0 = 32 * nb;
;     const int col = 4 * (lane & 7), rr = lane >> 3;
; #pragma unroll
;     for (int i = 0; i < 8; ++i) { LAS float* d = scr + (8 * i + rr) * 33 + col; const float g = w.g[i]; d[0] = w.v[i].x * g; d[1] = w.v[i].y * g; d[2] = w.v[i].z * g; d[3] = w.v[i].w * g; }
;     asm volatile("s_waitcnt lgkmcnt(0)" ::: "memory");
;     const int c = lane & 7;
; #pragma unroll
;     for (int j = 0; j < 4; ++j) { const int n = (lane >> 3) + 8 * j; const LAS float* s = scr + (8 * c) * 33 + n;
;         u32x4 o; o.x = cvtpk(s[0 * 33], s[1 * 33]); o.y = cvtpk(s[2 * 33], s[3 * 33]); o.z = cvtpk(s[4 * 33], s[5 * 33]); o.w = cvtpk(s[6 * 33], s[7 * 33]);
;         int nr = n0 + n; if (kvperm == 1) { const int hh = nr >> 8, ww = nr & 255; nr = (ww < 128) ? hh * 128 + ww : 2048 + hh * 128 + (ww - 128); }
;         else if (kvperm == 2) { const int isv = nr >= 5632, f = isv ? nr - 5632 : nr; nr = (f >> 7) * 256 + isv * 128 + (f & 127); }
;         *(u32x4*)(WT + (size_t)nr * K + k0 + 8 * c) = o; }
;     asm volatile("s_waitcnt lgkmcnt(0)" ::: "memory");
; }
;     ...
;     while (it < i1) {
;         cur = nxt;
;         const int nit = it + NGW;
;         if (nit < i1) witem_load(nxt, W, N, gk, nit, nblk, lane);
;         witem_store(cur, K, WT, kvperm, scr, it, nblk, lane);
;         it = nit;
;     }
.LBB0_737:
	v_pk_mul_f32 v[2:3], v[16:17], v[72:73] op_sel_hi:[1,0]
	ds_write2_b32 v79, v2, v3 offset1:1
	v_pk_mul_f32 v[2:3], v[18:19], v[72:73] op_sel_hi:[1,0]
	ds_write2_b32 v79, v2, v3 offset0:2 offset1:3
	v_pk_mul_f32 v[2:3], v[4:5], v[74:75] op_sel_hi:[1,0]
	v_add_u32_e32 v4, 0x420, v79
	ds_write2_b32 v4, v2, v3 offset1:1
	v_pk_mul_f32 v[2:3], v[6:7], v[74:75] op_sel_hi:[1,0]
	v_add_u32_e32 v4, 0x428, v79
	ds_write2_b32 v4, v2, v3 offset1:1
	v_pk_mul_f32 v[2:3], v[24:25], v[76:77] op_sel_hi:[1,0]
	v_add_u32_e32 v4, 0x840, v79
	ds_write2_b32 v4, v2, v3 offset1:1
	v_pk_mul_f32 v[2:3], v[26:27], v[76:77] op_sel_hi:[1,0]
	v_add_u32_e32 v4, 0x848, v79
	ds_write2_b32 v4, v2, v3 offset1:1
	v_pk_mul_f32 v[2:3], v[20:21], v[78:79] op_sel_hi:[1,0]
	v_add_u32_e32 v4, 0xc60, v79
	ds_write2_b32 v4, v2, v3 offset1:1
	v_pk_mul_f32 v[2:3], v[22:23], v[78:79] op_sel_hi:[1,0]
	v_add_u32_e32 v4, 0xc68, v79
	ds_write2_b32 v4, v2, v3 offset1:1
	v_pk_mul_f32 v[2:3], v[36:37], v[80:81] op_sel_hi:[1,0]
	v_add_u32_e32 v4, 0x1080, v79
	ds_write2_b32 v4, v2, v3 offset1:1
	v_pk_mul_f32 v[2:3], v[38:39], v[80:81] op_sel_hi:[1,0]
	v_add_u32_e32 v4, 0x1088, v79
	ds_write2_b32 v4, v2, v3 offset1:1
	v_pk_mul_f32 v[2:3], v[32:33], v[82:83] op_sel_hi:[1,0]
	v_add_u32_e32 v4, 0x14a0, v79
	s_mul_hi_i32 s6, s11, 0x2e8ba2e9
	ds_write2_b32 v4, v2, v3 offset1:1
	v_pk_mul_f32 v[2:3], v[34:35], v[82:83] op_sel_hi:[1,0]
	v_add_u32_e32 v4, 0x14a8, v79
	s_lshr_b32 s7, s6, 31
	s_ashr_i32 s6, s6, 6
	ds_write2_b32 v4, v2, v3 offset1:1
	s_waitcnt vmcnt(7)
	v_pk_mul_f32 v[2:3], v[52:53], v[84:85] op_sel_hi:[1,0]
	v_add_u32_e32 v4, 0x18c0, v79
	s_add_i32 s11, s6, s7
	ds_write2_b32 v4, v2, v3 offset1:1
	v_pk_mul_f32 v[2:3], v[54:55], v[84:85] op_sel_hi:[1,0]
	v_add_u32_e32 v4, 0x18c8, v79
	s_lshl_b32 s6, s11, 6
	ds_write2_b32 v4, v2, v3 offset1:1
	s_waitcnt vmcnt(6)
	v_pk_mul_f32 v[2:3], v[44:45], v[86:87] op_sel_hi:[1,0]
	v_add_u32_e32 v4, 0x1ce0, v79
	ds_write2_b32 v4, v2, v3 offset1:1
	v_pk_mul_f32 v[2:3], v[46:47], v[86:87] op_sel_hi:[1,0]
	v_add_u32_e32 v4, 0x1ce8, v79
	s_ashr_i32 s7, s6, 31
	ds_write2_b32 v4, v2, v3 offset1:1
	v_lshl_add_u64 v[34:35], s[6:7], 1, v[70:71]
	s_mul_i32 s6, s11, 0xffffd400
	s_waitcnt lgkmcnt(0)
	s_add_i32 s6, s6, s8
	ds_read2_b32 v[6:7], v75 offset0:33 offset1:41
	ds_read2_b32 v[16:17], v75 offset1:8
	ds_read2_b32 v[18:19], v75 offset0:66 offset1:74
	ds_read2_b32 v[20:21], v75 offset0:99 offset1:107
	ds_read2_b32 v[22:23], v75 offset0:132 offset1:140
	ds_read2_b32 v[24:25], v75 offset0:165 offset1:173
	ds_read2_b32 v[26:27], v75 offset0:198 offset1:206
	ds_read2_b32 v[32:33], v75 offset0:231 offset1:239
	v_add_u32_e32 v38, s6, v83
	s_waitcnt lgkmcnt(6)
	v_cvt_pk_bf16_f32 v2, v16, v6
	v_add_u32_e32 v6, 0xffffea00, v38
	v_cmp_lt_i32_e32 vcc, s14, v38
	s_waitcnt lgkmcnt(4)
	v_cvt_pk_bf16_f32 v3, v18, v20
	s_waitcnt lgkmcnt(2)
	v_cvt_pk_bf16_f32 v4, v22, v24
	v_cndmask_b32_e32 v6, v38, v6, vcc
	v_lshlrev_b32_e32 v16, 1, v6
	v_and_b32_e32 v16, 0xffffff00, v16
	v_cndmask_b32_e32 v18, 0, v81, vcc
	v_and_b32_e32 v6, 0x67, v6
	v_or3_b32 v36, v6, v18, v16
	v_ashrrev_i32_e32 v37, 31, v36
	v_lshlrev_b64 v[36:37], 12, v[36:37]
	s_waitcnt lgkmcnt(0)
	v_cvt_pk_bf16_f32 v5, v26, v32
	v_lshl_add_u64 v[36:37], v[34:35], 0, v[36:37]
	v_add_u32_e32 v6, 8, v38
	global_store_dwordx4 v[36:37], v[2:5], off sc0 sc1
	v_cmp_lt_i32_e32 vcc, s14, v6
	s_waitcnt vmcnt(3)
	v_mov_b64_e32 v[52:53], v[60:61]
	v_cvt_pk_bf16_f32 v2, v17, v7
	v_add_u32_e32 v7, 0xffffea08, v38
	v_cndmask_b32_e32 v6, v6, v7, vcc
	v_lshlrev_b32_e32 v7, 1, v6
	v_and_b32_e32 v7, 0xffffff00, v7
	v_cndmask_b32_e32 v16, 0, v81, vcc
	v_and_b32_e32 v6, 0x6f, v6
	v_or3_b32 v6, v6, v16, v7
	v_ashrrev_i32_e32 v7, 31, v6
	v_lshlrev_b64 v[6:7], 12, v[6:7]
	v_cvt_pk_bf16_f32 v3, v19, v21
	v_cvt_pk_bf16_f32 v4, v23, v25
	v_cvt_pk_bf16_f32 v5, v27, v33
	v_lshl_add_u64 v[6:7], v[34:35], 0, v[6:7]
	ds_read2_b32 v[16:17], v75 offset0:16 offset1:24
	ds_read2_b32 v[18:19], v75 offset0:49 offset1:57
	ds_read2_b32 v[20:21], v75 offset0:82 offset1:90
	ds_read2_b32 v[22:23], v75 offset0:115 offset1:123
	ds_read2_b32 v[24:25], v75 offset0:148 offset1:156
	ds_read2_b32 v[26:27], v75 offset0:181 offset1:189
	ds_read2_b32 v[32:33], v75 offset0:214 offset1:222
	ds_read2_b32 v[36:37], v75 offset0:247 offset1:255
	global_store_dwordx4 v[6:7], v[2:5], off sc0 sc1
	v_add_u32_e32 v6, 16, v38
	v_add_u32_e32 v7, 0xffffea10, v38
	v_cmp_lt_i32_e32 vcc, s14, v6
	s_waitcnt lgkmcnt(6)
	v_cvt_pk_bf16_f32 v2, v16, v18
	s_waitcnt lgkmcnt(4)
	v_cvt_pk_bf16_f32 v3, v20, v22
	v_cndmask_b32_e32 v6, v6, v7, vcc
	v_lshlrev_b32_e32 v7, 1, v6
	v_and_b32_e32 v7, 0xffffff00, v7
	v_cndmask_b32_e32 v16, 0, v81, vcc
	v_and_b32_e32 v6, 0x77, v6
	v_or3_b32 v6, v6, v16, v7
	v_ashrrev_i32_e32 v7, 31, v6
	v_lshlrev_b64 v[6:7], 12, v[6:7]
	s_waitcnt lgkmcnt(2)
	v_cvt_pk_bf16_f32 v4, v24, v26
	s_waitcnt lgkmcnt(0)
	v_cvt_pk_bf16_f32 v5, v32, v36
	v_lshl_add_u64 v[6:7], v[34:35], 0, v[6:7]
	global_store_dwordx4 v[6:7], v[2:5], off sc0 sc1
	s_waitcnt vmcnt(4)
	v_mov_b64_e32 v[44:45], v[64:65]
	v_add_u32_e32 v83, s9, v83
	v_add_u32_e32 v2, 24, v38
	v_add_u32_e32 v3, 0xffffea18, v38
	v_cmp_lt_i32_e32 vcc, s14, v2
	v_cvt_pk_bf16_f32 v5, v33, v37
	v_mov_b64_e32 v[36:37], v[48:49]
	v_cndmask_b32_e32 v2, v2, v3, vcc
	v_lshlrev_b32_e32 v3, 1, v2
	v_and_b32_e32 v3, 0xffffff00, v3
	v_cndmask_b32_e32 v4, 0, v81, vcc
	v_and_b32_e32 v2, 0x7f, v2
	v_or3_b32 v6, v2, v4, v3
	v_ashrrev_i32_e32 v7, 31, v6
	v_lshlrev_b64 v[6:7], 12, v[6:7]
	v_cvt_pk_bf16_f32 v2, v17, v19
	v_cvt_pk_bf16_f32 v3, v21, v23
	v_cvt_pk_bf16_f32 v4, v25, v27
	v_lshl_add_u64 v[6:7], v[34:35], 0, v[6:7]
	global_store_dwordx4 v[6:7], v[2:5], off sc0 sc1
	s_waitcnt lgkmcnt(0)
	v_mov_b64_e32 v[18:19], v[14:15]
	v_mov_b64_e32 v[24:25], v[28:29]
	v_mov_b64_e32 v[4:5], v[8:9]
	v_mov_b64_e32 v[20:21], v[40:41]
	v_mov_b64_e32 v[32:33], v[56:57]
	s_add_i32 s15, s15, s9
	v_add_u32_e32 v73, s9, v73
	s_andn2_b64 vcc, exec, s[0:1]
	s_mov_b32 s11, s16
	v_mov_b64_e32 v[16:17], v[12:13]
	v_mov_b64_e32 v[6:7], v[10:11]
	v_mov_b64_e32 v[26:27], v[30:31]
	v_mov_b64_e32 v[22:23], v[42:43]
	v_mov_b64_e32 v[38:39], v[50:51]
	v_mov_b64_e32 v[34:35], v[58:59]
	v_mov_b64_e32 v[54:55], v[62:63]
	v_mov_b64_e32 v[46:47], v[66:67]
	v_mov_b32_e32 v72, v85
	v_mov_b32_e32 v74, v87
	v_mov_b32_e32 v76, v89
	v_mov_b32_e32 v78, v94
	v_mov_b32_e32 v80, v95
	v_mov_b32_e32 v82, v96
	v_mov_b32_e32 v84, v97
	s_waitcnt vmcnt(4)
	v_mov_b32_e32 v86, v1
	s_cbranch_vccz .LBB0_755

; __device__ __forceinline__ unsigned cvt_pk_bf16(float lo, float hi) { unsigned r; asm volatile("v_cvt_pk_bf16_f32 %0, %1, %2" : "=v"(r) : "v"(lo), "v"(hi)); return r; }
; __device__ __forceinline__ float row_ss(const float* part, int row, int fq, int nf4) {
;     const f32x4* p = (const f32x4*)(part + (size_t)row * 32);
;     float s = 0.f;
; #pragma unroll
;     for (int j = 0; j < 2; ++j) { const int idx = fq + 4 * j; if (idx < nf4) { const f32x4 v = p[idx]; s += (v[0] + v[1]) + (v[2] + v[3]); } }
;     s += __shfl_xor(s, 16); s += __shfl_xor(s, 32);
;     return s;
; }
;     __device__ __forceinline__ void operator()(const f32x4 (&acc)[2][2][4][2], const Unit& u, int wr, int wc, int fr, int fq) const {
;         const int row0 = u.pm * BM + wr * 64 + fr; int colt = u.pn * BM; bf16_t* base = O;
;         float sc = 1.f; if (split_cols) { const int t = colt / split_cols; base += (size_t)t * split_stride; colt -= t * split_cols; if (t == 0) sc = scale0; } else sc = scale0;
;         const int col0 = colt + wc * 32 + 8 * fq, bcol0 = u.pn * BM + wc * 32 + 8 * fq;
;         f32x4 bv[2][2];
; #pragma unroll
;         for (int bj = 0; bj < 2; ++bj)
; #pragma unroll
;             for (int n = 0; n < 2; ++n) bv[bj][n] = bias ? *(const f32x4*)(bias + bcol0 + bj * HALF + 4 * n) : (f32x4){0.f, 0.f, 0.f, 0.f};
; #pragma unroll
;         for (int ai = 0; ai < 2; ++ai)
; #pragma unroll
;             for (int m = 0; m < 4; ++m) { const int row = row0 + ai * HALF + m * 16; bf16_t* rowp = base + (size_t)row * ldc + col0;
;                 const float rs = rss ? __builtin_amdgcn_rsqf(row_ss(rss, row, fq, nf4) * rinv + 1e-6f) : 1.f;
; #pragma unroll
;                 for (int bj = 0; bj < 2; ++bj) { f32x4 v0 = acc[ai][bj][m][0] * rs + bv[bj][0], v1 = acc[ai][bj][m][1] * rs + bv[bj][1];
;                     v0 = v0 * sc; v1 = v1 * sc; u32x4 w; w.x = cvt_pk_bf16(v0[0], v0[1]); w.y = cvt_pk_bf16(v0[2], v0[3]); w.z = cvt_pk_bf16(v1[0], v1[1]); w.w = cvt_pk_bf16(v1[2], v1[3]);
;                     *(u32x4*)(rowp + bj * HALF) = w; } }
.LBB0_823:
	s_or_b64 exec, exec, s[26:27]
	v_and_b32_e32 v149, 64, v156
	v_xor_b32_e32 v147, 16, v156
	v_add_u32_e32 v149, 64, v149
	v_cmp_lt_i32_e32 vcc, v147, v149
	v_xor_b32_e32 v160, 32, v156
	s_nop 0
	v_cndmask_b32_e32 v147, v156, v147, vcc
	v_lshlrev_b32_e32 v147, 2, v147
	ds_bpermute_b32 v158, v147, v148
	v_cmp_lt_i32_e32 vcc, v160, v149
	s_waitcnt lgkmcnt(0)
	v_add_f32_e32 v161, v148, v158
	v_cndmask_b32_e32 v148, v156, v160, vcc
	v_lshlrev_b32_e32 v158, 2, v148
	ds_bpermute_b32 v160, v158, v161
	v_lshl_or_b32 v148, s24, 8, v152
	v_ashrrev_i32_e32 v149, 31, v148
	v_lshl_add_u64 v[148:149], v[148:149], 1, s[8:9]
	v_mad_i64_i32 v[162:163], s[24:25], v146, s50, v[148:149]
	s_waitcnt lgkmcnt(0)
	v_add_f32_e32 v160, v161, v160
	v_fmamk_f32 v160, v160, 0x3b000000, v157
	v_rsq_f32_e32 v160, v160
	s_nop 0
	v_pk_fma_f32 v[124:125], v[124:125], v[160:161], 0 op_sel_hi:[1,0,0]
	v_pk_fma_f32 v[126:127], v[126:127], v[160:161], 0 op_sel_hi:[1,0,0]
	v_pk_fma_f32 v[120:121], v[120:121], v[160:161], 0 op_sel_hi:[1,0,0]
	v_pk_fma_f32 v[122:123], v[122:123], v[160:161], 0 op_sel_hi:[1,0,0]
	v_pk_mul_f32 v[126:127], v[126:127], s[14:15] op_sel_hi:[1,0]
	v_pk_mul_f32 v[124:125], v[124:125], s[14:15] op_sel_hi:[1,0]
	v_pk_mul_f32 v[164:165], v[122:123], s[14:15] op_sel_hi:[1,0]
	v_pk_mul_f32 v[122:123], v[120:121], s[14:15] op_sel_hi:[1,0]
	v_cvt_pk_bf16_f32 v120, v124, v125
	v_cvt_pk_bf16_f32 v121, v126, v127
	v_pk_fma_f32 v[116:117], v[116:117], v[160:161], 0 op_sel_hi:[1,0,0]
	v_pk_fma_f32 v[112:113], v[112:113], v[160:161], 0 op_sel_hi:[1,0,0]
	v_pk_fma_f32 v[114:115], v[114:115], v[160:161], 0 op_sel_hi:[1,0,0]
	v_cvt_pk_bf16_f32 v122, v122, v123
	v_cvt_pk_bf16_f32 v123, v164, v165
	global_store_dwordx4 v[162:163], v[120:123], off sc0 sc1
	v_pk_fma_f32 v[118:119], v[118:119], v[160:161], 0 op_sel_hi:[1,0,0]
	v_pk_mul_f32 v[116:117], v[116:117], s[14:15] op_sel_hi:[1,0]
	v_pk_mul_f32 v[120:121], v[114:115], s[14:15] op_sel_hi:[1,0]
	v_pk_mul_f32 v[114:115], v[112:113], s[14:15] op_sel_hi:[1,0]
	v_cvt_pk_bf16_f32 v112, v116, v117
	v_pk_mul_f32 v[118:119], v[118:119], s[14:15] op_sel_hi:[1,0]
	s_nop 0
	v_cvt_pk_bf16_f32 v113, v118, v119
	v_cvt_pk_bf16_f32 v114, v114, v115
	v_cvt_pk_bf16_f32 v115, v120, v121
	global_store_dwordx4 v[162:163], v[112:115], off offset:256 sc0 sc1
	s_nop 1
	v_or_b32_e32 v112, 16, v146
	v_ashrrev_i32_e32 v113, 31, v112
	s_and_saveexec_b64 s[24:25], s[4:5]
	s_cbranch_execz .LBB0_825
	v_lshlrev_b64 v[114:115], 7, v[112:113]
	v_lshl_add_u64 v[114:115], v[136:137], 0, v[114:115]
	global_load_dwordx4 v[114:117], v[114:115], off
	s_waitcnt vmcnt(0)
	v_mov_b32_e32 v118, v115
	v_mov_b32_e32 v119, v116
	v_mov_b32_e32 v115, v117
	v_pk_add_f32 v[114:115], v[118:119], v[114:115]
	s_nop 0
	v_add_f32_e32 v113, v114, v115
	v_add_f32_e32 v159, 0, v113
.LBB0_825:
	s_or_b64 exec, exec, s[24:25]
	ds_bpermute_b32 v113, v147, v159
	s_waitcnt lgkmcnt(0)
	v_add_f32_e32 v113, v159, v113
	ds_bpermute_b32 v114, v158, v113
	s_waitcnt lgkmcnt(0)
	v_add_f32_e32 v113, v113, v114
	v_fmamk_f32 v113, v113, 0x3b000000, v157
	v_rsq_f32_e32 v114, v113
	v_mad_i64_i32 v[112:113], s[24:25], v112, s50, v[148:149]
	v_pk_fma_f32 v[108:109], v[108:109], v[114:115], 0 op_sel_hi:[1,0,0]
	v_pk_fma_f32 v[110:111], v[110:111], v[114:115], 0 op_sel_hi:[1,0,0]
	v_pk_fma_f32 v[104:105], v[104:105], v[114:115], 0 op_sel_hi:[1,0,0]
	v_pk_fma_f32 v[106:107], v[106:107], v[114:115], 0 op_sel_hi:[1,0,0]
	v_pk_mul_f32 v[110:111], v[110:111], s[14:15] op_sel_hi:[1,0]
	v_pk_mul_f32 v[108:109], v[108:109], s[14:15] op_sel_hi:[1,0]
	v_pk_mul_f32 v[116:117], v[106:107], s[14:15] op_sel_hi:[1,0]
	v_pk_mul_f32 v[106:107], v[104:105], s[14:15] op_sel_hi:[1,0]
	v_cvt_pk_bf16_f32 v104, v108, v109
	v_cvt_pk_bf16_f32 v105, v110, v111
	v_pk_fma_f32 v[100:101], v[100:101], v[114:115], 0 op_sel_hi:[1,0,0]
	v_pk_fma_f32 v[96:97], v[96:97], v[114:115], 0 op_sel_hi:[1,0,0]
	v_pk_fma_f32 v[98:99], v[98:99], v[114:115], 0 op_sel_hi:[1,0,0]
	v_cvt_pk_bf16_f32 v106, v106, v107
	v_cvt_pk_bf16_f32 v107, v116, v117
	global_store_dwordx4 v[112:113], v[104:107], off sc0 sc1
	v_pk_fma_f32 v[102:103], v[102:103], v[114:115], 0 op_sel_hi:[1,0,0]
	v_pk_mul_f32 v[100:101], v[100:101], s[14:15] op_sel_hi:[1,0]
	v_pk_mul_f32 v[104:105], v[98:99], s[14:15] op_sel_hi:[1,0]
	v_pk_mul_f32 v[98:99], v[96:97], s[14:15] op_sel_hi:[1,0]
	v_cvt_pk_bf16_f32 v96, v100, v101
	v_pk_mul_f32 v[102:103], v[102:103], s[14:15] op_sel_hi:[1,0]
	s_nop 0
	v_cvt_pk_bf16_f32 v97, v102, v103
	v_cvt_pk_bf16_f32 v98, v98, v99
	v_cvt_pk_bf16_f32 v99, v104, v105
	global_store_dwordx4 v[112:113], v[96:99], off offset:256 sc0 sc1
	s_nop 1
	v_or_b32_e32 v96, 32, v146
	v_ashrrev_i32_e32 v97, 31, v96
	v_mov_b32_e32 v98, 0
	v_mov_b32_e32 v99, 0
	s_and_saveexec_b64 s[24:25], s[4:5]
	s_cbranch_execz .LBB0_827
	v_lshlrev_b64 v[100:101], 7, v[96:97]
	v_lshl_add_u64 v[100:101], v[136:137], 0, v[100:101]
	global_load_dwordx4 v[100:103], v[100:101], off
	s_waitcnt vmcnt(0)
	v_mov_b32_e32 v104, v101
	v_mov_b32_e32 v105, v102
	v_mov_b32_e32 v101, v103
	v_pk_add_f32 v[100:101], v[104:105], v[100:101]
	s_nop 0
	v_add_f32_e32 v97, v100, v101
	v_add_f32_e32 v99, 0, v97
; __device__ __forceinline__ unsigned cvt_pk_bf16(float lo, float hi) { unsigned r; asm volatile("v_cvt_pk_bf16_f32 %0, %1, %2" : "=v"(r) : "v"(lo), "v"(hi)); return r; }
; __device__ __forceinline__ float row_ss(const float* part, int row, int fq, int nf4) {
;     const f32x4* p = (const f32x4*)(part + (size_t)row * 32);
;     float s = 0.f;
; #pragma unroll
;     for (int j = 0; j < 2; ++j) { const int idx = fq + 4 * j; if (idx < nf4) { const f32x4 v = p[idx]; s += (v[0] + v[1]) + (v[2] + v[3]); } }
;     s += __shfl_xor(s, 16); s += __shfl_xor(s, 32);
;     return s;
; }
;     __device__ __forceinline__ void operator()(const f32x4 (&acc)[2][2][4][2], const Unit& u, int wr, int wc, int fr, int fq) const {
;         const int row0 = u.pm * BM + wr * 64 + fr; int colt = u.pn * BM; bf16_t* base = O;
;         float sc = 1.f; if (split_cols) { const int t = colt / split_cols; base += (size_t)t * split_stride; colt -= t * split_cols; if (t == 0) sc = scale0; } else sc = scale0;
;         const int col0 = colt + wc * 32 + 8 * fq, bcol0 = u.pn * BM + wc * 32 + 8 * fq;
;         f32x4 bv[2][2];
; #pragma unroll
;         for (int bj = 0; bj < 2; ++bj)
; #pragma unroll
;             for (int n = 0; n < 2; ++n) bv[bj][n] = bias ? *(const f32x4*)(bias + bcol0 + bj * HALF + 4 * n) : (f32x4){0.f, 0.f, 0.f, 0.f};
; #pragma unroll
;         for (int ai = 0; ai < 2; ++ai)
; #pragma unroll
;             for (int m = 0; m < 4; ++m) { const int row = row0 + ai * HALF + m * 16; bf16_t* rowp = base + (size_t)row * ldc + col0;
;                 const float rs = rss ? __builtin_amdgcn_rsqf(row_ss(rss, row, fq, nf4) * rinv + 1e-6f) : 1.f;
; #pragma unroll
;                 for (int bj = 0; bj < 2; ++bj) { f32x4 v0 = acc[ai][bj][m][0] * rs + bv[bj][0], v1 = acc[ai][bj][m][1] * rs + bv[bj][1];
;                     v0 = v0 * sc; v1 = v1 * sc; u32x4 w; w.x = cvt_pk_bf16(v0[0], v0[1]); w.y = cvt_pk_bf16(v0[2], v0[3]); w.z = cvt_pk_bf16(v1[0], v1[1]); w.w = cvt_pk_bf16(v1[2], v1[3]);
;                     *(u32x4*)(rowp + bj * HALF) = w; } }
.LBB0_827:
	s_or_b64 exec, exec, s[24:25]
	ds_bpermute_b32 v97, v147, v99
	s_waitcnt lgkmcnt(0)
	v_add_f32_e32 v97, v99, v97
	ds_bpermute_b32 v99, v158, v97
	s_waitcnt lgkmcnt(0)
	v_add_f32_e32 v97, v97, v99
	v_fmamk_f32 v97, v97, 0x3b000000, v157
	v_rsq_f32_e32 v100, v97
	v_mad_i64_i32 v[96:97], s[24:25], v96, s50, v[148:149]
	v_pk_fma_f32 v[92:93], v[92:93], v[100:101], 0 op_sel_hi:[1,0,0]
	v_pk_fma_f32 v[94:95], v[94:95], v[100:101], 0 op_sel_hi:[1,0,0]
	v_pk_fma_f32 v[88:89], v[88:89], v[100:101], 0 op_sel_hi:[1,0,0]
	v_pk_fma_f32 v[90:91], v[90:91], v[100:101], 0 op_sel_hi:[1,0,0]
	v_pk_mul_f32 v[94:95], v[94:95], s[14:15] op_sel_hi:[1,0]
	v_pk_mul_f32 v[92:93], v[92:93], s[14:15] op_sel_hi:[1,0]
	v_pk_mul_f32 v[102:103], v[90:91], s[14:15] op_sel_hi:[1,0]
	v_pk_mul_f32 v[90:91], v[88:89], s[14:15] op_sel_hi:[1,0]
	v_cvt_pk_bf16_f32 v88, v92, v93
	v_cvt_pk_bf16_f32 v89, v94, v95
	v_pk_fma_f32 v[84:85], v[84:85], v[100:101], 0 op_sel_hi:[1,0,0]
	v_pk_fma_f32 v[80:81], v[80:81], v[100:101], 0 op_sel_hi:[1,0,0]
	v_pk_fma_f32 v[82:83], v[82:83], v[100:101], 0 op_sel_hi:[1,0,0]
	v_cvt_pk_bf16_f32 v90, v90, v91
	v_cvt_pk_bf16_f32 v91, v102, v103
	global_store_dwordx4 v[96:97], v[88:91], off sc0 sc1
	v_pk_fma_f32 v[86:87], v[86:87], v[100:101], 0 op_sel_hi:[1,0,0]
	v_pk_mul_f32 v[84:85], v[84:85], s[14:15] op_sel_hi:[1,0]
	v_pk_mul_f32 v[88:89], v[82:83], s[14:15] op_sel_hi:[1,0]
	v_pk_mul_f32 v[82:83], v[80:81], s[14:15] op_sel_hi:[1,0]
	v_cvt_pk_bf16_f32 v80, v84, v85
	v_pk_mul_f32 v[86:87], v[86:87], s[14:15] op_sel_hi:[1,0]
	s_nop 0
	v_cvt_pk_bf16_f32 v81, v86, v87
	v_cvt_pk_bf16_f32 v82, v82, v83
	v_cvt_pk_bf16_f32 v83, v88, v89
	global_store_dwordx4 v[96:97], v[80:83], off offset:256 sc0 sc1
	s_nop 1
	v_or_b32_e32 v80, 48, v146
	v_ashrrev_i32_e32 v81, 31, v80
	s_and_saveexec_b64 s[24:25], s[4:5]
	s_cbranch_execz .LBB0_829
	v_lshlrev_b64 v[82:83], 7, v[80:81]
	v_lshl_add_u64 v[82:83], v[136:137], 0, v[82:83]
	global_load_dwordx4 v[82:85], v[82:83], off
	s_waitcnt vmcnt(0)
	v_mov_b32_e32 v86, v83
	v_mov_b32_e32 v87, v84
	v_mov_b32_e32 v83, v85
	v_pk_add_f32 v[82:83], v[86:87], v[82:83]
	s_nop 0
	v_add_f32_e32 v81, v82, v83
	v_add_f32_e32 v98, 0, v81
.LBB0_829:
	s_or_b64 exec, exec, s[24:25]
	ds_bpermute_b32 v81, v147, v98
	s_waitcnt lgkmcnt(0)
	v_add_f32_e32 v81, v98, v81
	ds_bpermute_b32 v82, v158, v81
	s_waitcnt lgkmcnt(0)
	v_add_f32_e32 v81, v81, v82
	v_fmamk_f32 v81, v81, 0x3b000000, v157
	v_rsq_f32_e32 v82, v81
	v_mad_i64_i32 v[80:81], s[24:25], v80, s50, v[148:149]
	v_pk_fma_f32 v[76:77], v[76:77], v[82:83], 0 op_sel_hi:[1,0,0]
	v_pk_fma_f32 v[78:79], v[78:79], v[82:83], 0 op_sel_hi:[1,0,0]
	v_pk_fma_f32 v[72:73], v[72:73], v[82:83], 0 op_sel_hi:[1,0,0]
	v_pk_fma_f32 v[74:75], v[74:75], v[82:83], 0 op_sel_hi:[1,0,0]
	v_pk_mul_f32 v[78:79], v[78:79], s[14:15] op_sel_hi:[1,0]
	v_pk_mul_f32 v[76:77], v[76:77], s[14:15] op_sel_hi:[1,0]
	v_pk_mul_f32 v[84:85], v[74:75], s[14:15] op_sel_hi:[1,0]
	v_pk_mul_f32 v[74:75], v[72:73], s[14:15] op_sel_hi:[1,0]
	v_cvt_pk_bf16_f32 v72, v76, v77
	v_cvt_pk_bf16_f32 v73, v78, v79
	v_pk_fma_f32 v[68:69], v[68:69], v[82:83], 0 op_sel_hi:[1,0,0]
	v_pk_fma_f32 v[64:65], v[64:65], v[82:83], 0 op_sel_hi:[1,0,0]
	v_pk_fma_f32 v[66:67], v[66:67], v[82:83], 0 op_sel_hi:[1,0,0]
	v_cvt_pk_bf16_f32 v74, v74, v75
	v_cvt_pk_bf16_f32 v75, v84, v85
	global_store_dwordx4 v[80:81], v[72:75], off sc0 sc1
	v_pk_fma_f32 v[70:71], v[70:71], v[82:83], 0 op_sel_hi:[1,0,0]
	v_pk_mul_f32 v[68:69], v[68:69], s[14:15] op_sel_hi:[1,0]
	v_pk_mul_f32 v[72:73], v[66:67], s[14:15] op_sel_hi:[1,0]
	v_pk_mul_f32 v[66:67], v[64:65], s[14:15] op_sel_hi:[1,0]
	v_cvt_pk_bf16_f32 v64, v68, v69
	v_pk_mul_f32 v[70:71], v[70:71], s[14:15] op_sel_hi:[1,0]
	s_nop 0
	v_cvt_pk_bf16_f32 v65, v70, v71
	v_cvt_pk_bf16_f32 v66, v66, v67
	v_cvt_pk_bf16_f32 v67, v72, v73
	global_store_dwordx4 v[80:81], v[64:67], off offset:256 sc0 sc1
	s_nop 1
	v_add_u32_e32 v64, 0x80, v146
	v_ashrrev_i32_e32 v65, 31, v64
	v_mov_b32_e32 v66, 0
	v_mov_b32_e32 v67, 0
	s_and_saveexec_b64 s[24:25], s[4:5]
	s_cbranch_execz .LBB0_831
	v_lshlrev_b64 v[68:69], 7, v[64:65]
	v_lshl_add_u64 v[68:69], v[136:137], 0, v[68:69]
	global_load_dwordx4 v[68:71], v[68:69], off
	s_waitcnt vmcnt(0)
	v_mov_b32_e32 v72, v69
	v_mov_b32_e32 v73, v70
	v_mov_b32_e32 v69, v71
	v_pk_add_f32 v[68:69], v[72:73], v[68:69]
	s_nop 0
	v_add_f32_e32 v65, v68, v69
	v_add_f32_e32 v67, 0, v65
.LBB0_831:
	s_or_b64 exec, exec, s[24:25]
	ds_bpermute_b32 v65, v147, v67
	s_waitcnt lgkmcnt(0)
	v_add_f32_e32 v65, v67, v65
	ds_bpermute_b32 v67, v158, v65
	s_waitcnt lgkmcnt(0)
	v_add_f32_e32 v65, v65, v67
	v_fmamk_f32 v65, v65, 0x3b000000, v157
	v_rsq_f32_e32 v68, v65
	v_mad_i64_i32 v[64:65], s[24:25], v64, s50, v[148:149]
	v_pk_fma_f32 v[60:61], v[60:61], v[68:69], 0 op_sel_hi:[1,0,0]
	v_pk_fma_f32 v[62:63], v[62:63], v[68:69], 0 op_sel_hi:[1,0,0]
	v_pk_fma_f32 v[56:57], v[56:57], v[68:69], 0 op_sel_hi:[1,0,0]
	v_pk_fma_f32 v[58:59], v[58:59], v[68:69], 0 op_sel_hi:[1,0,0]
	v_pk_mul_f32 v[62:63], v[62:63], s[14:15] op_sel_hi:[1,0]
	v_pk_mul_f32 v[60:61], v[60:61], s[14:15] op_sel_hi:[1,0]
	v_pk_mul_f32 v[70:71], v[58:59], s[14:15] op_sel_hi:[1,0]
	v_pk_mul_f32 v[58:59], v[56:57], s[14:15] op_sel_hi:[1,0]
	v_cvt_pk_bf16_f32 v56, v60, v61
	v_cvt_pk_bf16_f32 v57, v62, v63
	v_pk_fma_f32 v[52:53], v[52:53], v[68:69], 0 op_sel_hi:[1,0,0]
	v_pk_fma_f32 v[48:49], v[48:49], v[68:69], 0 op_sel_hi:[1,0,0]
	v_pk_fma_f32 v[50:51], v[50:51], v[68:69], 0 op_sel_hi:[1,0,0]
	v_cvt_pk_bf16_f32 v58, v58, v59
	v_cvt_pk_bf16_f32 v59, v70, v71
	global_store_dwordx4 v[64:65], v[56:59], off sc0 sc1
	v_pk_fma_f32 v[54:55], v[54:55], v[68:69], 0 op_sel_hi:[1,0,0]
	v_pk_mul_f32 v[52:53], v[52:53], s[14:15] op_sel_hi:[1,0]
	v_pk_mul_f32 v[56:57], v[50:51], s[14:15] op_sel_hi:[1,0]
	v_pk_mul_f32 v[50:51], v[48:49], s[14:15] op_sel_hi:[1,0]
	v_cvt_pk_bf16_f32 v48, v52, v53
	v_pk_mul_f32 v[54:55], v[54:55], s[14:15] op_sel_hi:[1,0]
	s_nop 0
	v_cvt_pk_bf16_f32 v49, v54, v55
	v_cvt_pk_bf16_f32 v50, v50, v51
	v_cvt_pk_bf16_f32 v51, v56, v57
	global_store_dwordx4 v[64:65], v[48:51], off offset:256 sc0 sc1
	s_nop 1
	v_add_u32_e32 v48, 0x90, v146
	v_ashrrev_i32_e32 v49, 31, v48
	s_and_saveexec_b64 s[24:25], s[4:5]
	s_cbranch_execz .LBB0_833
	v_lshlrev_b64 v[50:51], 7, v[48:49]
	v_lshl_add_u64 v[50:51], v[136:137], 0, v[50:51]
	global_load_dwordx4 v[50:53], v[50:51], off
	s_waitcnt vmcnt(0)
	v_mov_b32_e32 v54, v51
	v_mov_b32_e32 v55, v52
	v_mov_b32_e32 v51, v53
	v_pk_add_f32 v[50:51], v[54:55], v[50:51]
	s_nop 0
	v_add_f32_e32 v49, v50, v51
	v_add_f32_e32 v66, 0, v49
; __device__ __forceinline__ unsigned cvt_pk_bf16(float lo, float hi) { unsigned r; asm volatile("v_cvt_pk_bf16_f32 %0, %1, %2" : "=v"(r) : "v"(lo), "v"(hi)); return r; }
; __device__ __forceinline__ float row_ss(const float* part, int row, int fq, int nf4) {
;     const f32x4* p = (const f32x4*)(part + (size_t)row * 32);
;     float s = 0.f;
; #pragma unroll
;     for (int j = 0; j < 2; ++j) { const int idx = fq + 4 * j; if (idx < nf4) { const f32x4 v = p[idx]; s += (v[0] + v[1]) + (v[2] + v[3]); } }
;     s += __shfl_xor(s, 16); s += __shfl_xor(s, 32);
;     return s;
; }
;     __device__ __forceinline__ void operator()(const f32x4 (&acc)[2][2][4][2], const Unit& u, int wr, int wc, int fr, int fq) const {
;         const int row0 = u.pm * BM + wr * 64 + fr; int colt = u.pn * BM; bf16_t* base = O;
;         float sc = 1.f; if (split_cols) { const int t = colt / split_cols; base += (size_t)t * split_stride; colt -= t * split_cols; if (t == 0) sc = scale0; } else sc = scale0;
;         const int col0 = colt + wc * 32 + 8 * fq, bcol0 = u.pn * BM + wc * 32 + 8 * fq;
;         f32x4 bv[2][2];
; #pragma unroll
;         for (int bj = 0; bj < 2; ++bj)
; #pragma unroll
;             for (int n = 0; n < 2; ++n) bv[bj][n] = bias ? *(const f32x4*)(bias + bcol0 + bj * HALF + 4 * n) : (f32x4){0.f, 0.f, 0.f, 0.f};
; #pragma unroll
;         for (int ai = 0; ai < 2; ++ai)
; #pragma unroll
;             for (int m = 0; m < 4; ++m) { const int row = row0 + ai * HALF + m * 16; bf16_t* rowp = base + (size_t)row * ldc + col0;
;                 const float rs = rss ? __builtin_amdgcn_rsqf(row_ss(rss, row, fq, nf4) * rinv + 1e-6f) : 1.f;
; #pragma unroll
;                 for (int bj = 0; bj < 2; ++bj) { f32x4 v0 = acc[ai][bj][m][0] * rs + bv[bj][0], v1 = acc[ai][bj][m][1] * rs + bv[bj][1];
;                     v0 = v0 * sc; v1 = v1 * sc; u32x4 w; w.x = cvt_pk_bf16(v0[0], v0[1]); w.y = cvt_pk_bf16(v0[2], v0[3]); w.z = cvt_pk_bf16(v1[0], v1[1]); w.w = cvt_pk_bf16(v1[2], v1[3]);
;                     *(u32x4*)(rowp + bj * HALF) = w; } }
.LBB0_833:
	s_or_b64 exec, exec, s[24:25]
	ds_bpermute_b32 v49, v147, v66
	s_waitcnt lgkmcnt(0)
	v_add_f32_e32 v49, v66, v49
	ds_bpermute_b32 v50, v158, v49
	s_waitcnt lgkmcnt(0)
	v_add_f32_e32 v49, v49, v50
	v_fmamk_f32 v49, v49, 0x3b000000, v157
	v_rsq_f32_e32 v50, v49
	v_mad_i64_i32 v[48:49], s[24:25], v48, s50, v[148:149]
	v_pk_fma_f32 v[44:45], v[44:45], v[50:51], 0 op_sel_hi:[1,0,0]
	v_pk_fma_f32 v[46:47], v[46:47], v[50:51], 0 op_sel_hi:[1,0,0]
	v_pk_fma_f32 v[40:41], v[40:41], v[50:51], 0 op_sel_hi:[1,0,0]
	v_pk_fma_f32 v[42:43], v[42:43], v[50:51], 0 op_sel_hi:[1,0,0]
	v_pk_mul_f32 v[46:47], v[46:47], s[14:15] op_sel_hi:[1,0]
	v_pk_mul_f32 v[44:45], v[44:45], s[14:15] op_sel_hi:[1,0]
	v_pk_mul_f32 v[52:53], v[42:43], s[14:15] op_sel_hi:[1,0]
	v_pk_mul_f32 v[42:43], v[40:41], s[14:15] op_sel_hi:[1,0]
	v_cvt_pk_bf16_f32 v40, v44, v45
	v_cvt_pk_bf16_f32 v41, v46, v47
	v_pk_fma_f32 v[36:37], v[36:37], v[50:51], 0 op_sel_hi:[1,0,0]
	v_pk_fma_f32 v[32:33], v[32:33], v[50:51], 0 op_sel_hi:[1,0,0]
	v_pk_fma_f32 v[34:35], v[34:35], v[50:51], 0 op_sel_hi:[1,0,0]
	v_cvt_pk_bf16_f32 v42, v42, v43
	v_cvt_pk_bf16_f32 v43, v52, v53
	global_store_dwordx4 v[48:49], v[40:43], off sc0 sc1
	v_pk_fma_f32 v[38:39], v[38:39], v[50:51], 0 op_sel_hi:[1,0,0]
	v_pk_mul_f32 v[36:37], v[36:37], s[14:15] op_sel_hi:[1,0]
	v_pk_mul_f32 v[40:41], v[34:35], s[14:15] op_sel_hi:[1,0]
	v_pk_mul_f32 v[34:35], v[32:33], s[14:15] op_sel_hi:[1,0]
	v_cvt_pk_bf16_f32 v32, v36, v37
	v_pk_mul_f32 v[38:39], v[38:39], s[14:15] op_sel_hi:[1,0]
	s_nop 0
	v_cvt_pk_bf16_f32 v33, v38, v39
	v_cvt_pk_bf16_f32 v34, v34, v35
	v_cvt_pk_bf16_f32 v35, v40, v41
	global_store_dwordx4 v[48:49], v[32:35], off offset:256 sc0 sc1
	s_nop 1
	v_add_u32_e32 v32, 0xa0, v146
	v_ashrrev_i32_e32 v33, 31, v32
	v_mov_b32_e32 v34, 0
	v_mov_b32_e32 v35, 0
	s_and_saveexec_b64 s[24:25], s[4:5]
	s_cbranch_execz .LBB0_835
	v_lshlrev_b64 v[36:37], 7, v[32:33]
	v_lshl_add_u64 v[36:37], v[136:137], 0, v[36:37]
	global_load_dwordx4 v[36:39], v[36:37], off
	s_waitcnt vmcnt(0)
	v_mov_b32_e32 v40, v37
	v_mov_b32_e32 v41, v38
	v_mov_b32_e32 v37, v39
	v_pk_add_f32 v[36:37], v[40:41], v[36:37]
	s_nop 0
	v_add_f32_e32 v33, v36, v37
	v_add_f32_e32 v35, 0, v33
.LBB0_835:
	s_or_b64 exec, exec, s[24:25]
	ds_bpermute_b32 v33, v147, v35
	s_waitcnt lgkmcnt(0)
	v_add_f32_e32 v33, v35, v33
	ds_bpermute_b32 v35, v158, v33
	s_waitcnt lgkmcnt(0)
	v_add_f32_e32 v33, v33, v35
	v_fmamk_f32 v33, v33, 0x3b000000, v157
	v_rsq_f32_e32 v36, v33
	v_mad_i64_i32 v[32:33], s[24:25], v32, s50, v[148:149]
	v_pk_fma_f32 v[28:29], v[28:29], v[36:37], 0 op_sel_hi:[1,0,0]
	v_pk_fma_f32 v[30:31], v[30:31], v[36:37], 0 op_sel_hi:[1,0,0]
	v_pk_fma_f32 v[24:25], v[24:25], v[36:37], 0 op_sel_hi:[1,0,0]
	v_pk_fma_f32 v[26:27], v[26:27], v[36:37], 0 op_sel_hi:[1,0,0]
	v_pk_mul_f32 v[30:31], v[30:31], s[14:15] op_sel_hi:[1,0]
	v_pk_mul_f32 v[28:29], v[28:29], s[14:15] op_sel_hi:[1,0]
	v_pk_mul_f32 v[38:39], v[26:27], s[14:15] op_sel_hi:[1,0]
	v_pk_mul_f32 v[26:27], v[24:25], s[14:15] op_sel_hi:[1,0]
	v_cvt_pk_bf16_f32 v24, v28, v29
	v_cvt_pk_bf16_f32 v25, v30, v31
	v_pk_fma_f32 v[20:21], v[20:21], v[36:37], 0 op_sel_hi:[1,0,0]
	v_pk_fma_f32 v[16:17], v[16:17], v[36:37], 0 op_sel_hi:[1,0,0]
	v_pk_fma_f32 v[18:19], v[18:19], v[36:37], 0 op_sel_hi:[1,0,0]
	v_cvt_pk_bf16_f32 v26, v26, v27
	v_cvt_pk_bf16_f32 v27, v38, v39
	global_store_dwordx4 v[32:33], v[24:27], off sc0 sc1
	v_pk_fma_f32 v[22:23], v[22:23], v[36:37], 0 op_sel_hi:[1,0,0]
	v_pk_mul_f32 v[20:21], v[20:21], s[14:15] op_sel_hi:[1,0]
	v_pk_mul_f32 v[24:25], v[18:19], s[14:15] op_sel_hi:[1,0]
	v_pk_mul_f32 v[18:19], v[16:17], s[14:15] op_sel_hi:[1,0]
	v_cvt_pk_bf16_f32 v16, v20, v21
	v_pk_mul_f32 v[22:23], v[22:23], s[14:15] op_sel_hi:[1,0]
	s_nop 0
	v_cvt_pk_bf16_f32 v17, v22, v23
	v_cvt_pk_bf16_f32 v18, v18, v19
	v_cvt_pk_bf16_f32 v19, v24, v25
	global_store_dwordx4 v[32:33], v[16:19], off offset:256 sc0 sc1
	s_nop 1
	v_add_u32_e32 v16, 0xb0, v146
	v_ashrrev_i32_e32 v17, 31, v16
	s_and_saveexec_b64 s[24:25], s[4:5]
	s_cbranch_execz .LBB0_837
	v_lshlrev_b64 v[18:19], 7, v[16:17]
	v_lshl_add_u64 v[18:19], v[136:137], 0, v[18:19]
	global_load_dwordx4 v[18:21], v[18:19], off
	s_waitcnt vmcnt(0)
	v_mov_b32_e32 v22, v19
	v_mov_b32_e32 v23, v20
	v_mov_b32_e32 v19, v21
	v_pk_add_f32 v[18:19], v[22:23], v[18:19]
	s_nop 0
	v_add_f32_e32 v17, v18, v19
	v_add_f32_e32 v34, 0, v17
.LBB0_837:
	s_or_b64 exec, exec, s[24:25]
	ds_bpermute_b32 v17, v147, v34
	s_andn2_b64 vcc, exec, s[6:7]
	s_mov_b64 s[6:7], -1
	s_waitcnt lgkmcnt(0)
	v_add_f32_e32 v17, v34, v17
	ds_bpermute_b32 v18, v158, v17
	s_waitcnt lgkmcnt(0)
	v_add_f32_e32 v17, v17, v18
	v_fmamk_f32 v17, v17, 0x3b000000, v157
	v_rsq_f32_e32 v18, v17
	v_mad_i64_i32 v[16:17], s[24:25], v16, s50, v[148:149]
	v_pk_fma_f32 v[12:13], v[12:13], v[18:19], 0 op_sel_hi:[1,0,0]
	v_pk_fma_f32 v[14:15], v[14:15], v[18:19], 0 op_sel_hi:[1,0,0]
	v_pk_fma_f32 v[8:9], v[8:9], v[18:19], 0 op_sel_hi:[1,0,0]
	v_pk_fma_f32 v[10:11], v[10:11], v[18:19], 0 op_sel_hi:[1,0,0]
	v_pk_mul_f32 v[14:15], v[14:15], s[14:15] op_sel_hi:[1,0]
	v_pk_mul_f32 v[12:13], v[12:13], s[14:15] op_sel_hi:[1,0]
	v_pk_mul_f32 v[20:21], v[10:11], s[14:15] op_sel_hi:[1,0]
	v_pk_mul_f32 v[10:11], v[8:9], s[14:15] op_sel_hi:[1,0]
	v_cvt_pk_bf16_f32 v8, v12, v13
	v_cvt_pk_bf16_f32 v9, v14, v15
	v_pk_fma_f32 v[0:1], v[0:1], v[18:19], 0 op_sel_hi:[1,0,0]
	v_pk_fma_f32 v[2:3], v[2:3], v[18:19], 0 op_sel_hi:[1,0,0]
	v_cvt_pk_bf16_f32 v10, v10, v11
	v_cvt_pk_bf16_f32 v11, v20, v21
	global_store_dwordx4 v[16:17], v[8:11], off sc0 sc1
	v_pk_fma_f32 v[4:5], v[4:5], v[18:19], 0 op_sel_hi:[1,0,0]
	v_pk_fma_f32 v[6:7], v[6:7], v[18:19], 0 op_sel_hi:[1,0,0]
	v_pk_mul_f32 v[8:9], v[2:3], s[14:15] op_sel_hi:[1,0]
	v_pk_mul_f32 v[2:3], v[0:1], s[14:15] op_sel_hi:[1,0]
	v_pk_mul_f32 v[6:7], v[6:7], s[14:15] op_sel_hi:[1,0]
	v_pk_mul_f32 v[4:5], v[4:5], s[14:15] op_sel_hi:[1,0]
	s_nop 0
	v_cvt_pk_bf16_f32 v0, v4, v5
	v_cvt_pk_bf16_f32 v1, v6, v7
	v_cvt_pk_bf16_f32 v2, v2, v3
	v_cvt_pk_bf16_f32 v3, v8, v9
	global_store_dwordx4 v[16:17], v[0:3], off offset:256 sc0 sc1
	s_cbranch_vccnz .LBB0_814
	s_andn2_b64 vcc, exec, s[0:1]
	s_cbranch_vccnz .LBB0_813
	s_barrier
	s_branch .LBB0_813

; __device__ __forceinline__ unsigned cvt_pk_bf16(float lo, float hi) { unsigned r; asm volatile("v_cvt_pk_bf16_f32 %0, %1, %2" : "=v"(r) : "v"(lo), "v"(hi)); return r; }
; __device__ __forceinline__ float row_ss(const float* part, int row, int fq, int nf4) {
;     const f32x4* p = (const f32x4*)(part + (size_t)row * 32);
;     float s = 0.f;
; #pragma unroll
;     for (int j = 0; j < 2; ++j) { const int idx = fq + 4 * j; if (idx < nf4) { const f32x4 v = p[idx]; s += (v[0] + v[1]) + (v[2] + v[3]); } }
;     s += __shfl_xor(s, 16); s += __shfl_xor(s, 32);
;     return s;
; }
;     __device__ __forceinline__ void operator()(const f32x4 (&acc)[2][2][4][2], const Unit& u, int wr, int wc, int fr, int fq) const {
;         const int row0 = u.pm * BM + wr * 64 + fr; int colt = u.pn * BM; bf16_t* base = O;
;         float sc = 1.f; if (split_cols) { const int t = colt / split_cols; base += (size_t)t * split_stride; colt -= t * split_cols; if (t == 0) sc = scale0; } else sc = scale0;
;         const int col0 = colt + wc * 32 + 8 * fq, bcol0 = u.pn * BM + wc * 32 + 8 * fq;
;         f32x4 bv[2][2];
; #pragma unroll
;         for (int bj = 0; bj < 2; ++bj)
; #pragma unroll
;             for (int n = 0; n < 2; ++n) bv[bj][n] = bias ? *(const f32x4*)(bias + bcol0 + bj * HALF + 4 * n) : (f32x4){0.f, 0.f, 0.f, 0.f};
; #pragma unroll
;         for (int ai = 0; ai < 2; ++ai)
; #pragma unroll
;             for (int m = 0; m < 4; ++m) { const int row = row0 + ai * HALF + m * 16; bf16_t* rowp = base + (size_t)row * ldc + col0;
;                 const float rs = rss ? __builtin_amdgcn_rsqf(row_ss(rss, row, fq, nf4) * rinv + 1e-6f) : 1.f;
; #pragma unroll
;                 for (int bj = 0; bj < 2; ++bj) { f32x4 v0 = acc[ai][bj][m][0] * rs + bv[bj][0], v1 = acc[ai][bj][m][1] * rs + bv[bj][1];
;                     v0 = v0 * sc; v1 = v1 * sc; u32x4 w; w.x = cvt_pk_bf16(v0[0], v0[1]); w.y = cvt_pk_bf16(v0[2], v0[3]); w.z = cvt_pk_bf16(v1[0], v1[1]); w.w = cvt_pk_bf16(v1[2], v1[3]);
;                     *(u32x4*)(rowp + bj * HALF) = w; } }
.LBB0_865:
	s_or_b64 exec, exec, s[24:25]
	v_and_b32_e32 v158, 64, v156
	v_xor_b32_e32 v149, 16, v156
	v_add_u32_e32 v159, 64, v158
	v_cmp_lt_i32_e32 vcc, v149, v159
	s_ashr_i32 s6, s22, 31
	s_lshr_b32 s6, s6, 29
	v_cndmask_b32_e32 v149, v156, v149, vcc
	v_lshlrev_b32_e32 v158, 2, v149
	ds_bpermute_b32 v149, v158, v148
	s_add_i32 s6, s22, s6
	s_ashr_i32 s17, s6, 3
	s_lshl_b32 s15, s22, 8
	s_mul_i32 s6, s17, 0x3000000
	s_waitcnt lgkmcnt(0)
	v_add_f32_e32 v161, v148, v149
	v_xor_b32_e32 v148, 32, v156
	v_cmp_lt_i32_e32 vcc, v148, v159
	s_mul_hi_i32 s7, s17, 0x3000000
	s_add_u32 s6, s42, s6
	v_cndmask_b32_e32 v148, v156, v148, vcc
	v_lshlrev_b32_e32 v159, 2, v148
	ds_bpermute_b32 v162, v159, v161
	s_addc_u32 s7, s43, s7
	s_lshl_b32 s17, s17, 11
	s_sub_i32 s15, s15, s17
	v_or_b32_e32 v148, s15, v152
	s_waitcnt lgkmcnt(0)
	v_add_f32_e32 v161, v161, v162
	v_fmamk_f32 v161, v161, 0x3b000000, v157
	v_rsq_f32_e32 v162, v161
	v_ashrrev_i32_e32 v149, 31, v148
	v_lshl_add_u64 v[148:149], v[148:149], 1, s[6:7]
	v_lshlrev_b64 v[164:165], 12, v[146:147]
	v_lshl_add_u64 v[164:165], v[148:149], 0, v[164:165]
	v_pk_fma_f32 v[126:127], v[126:127], v[162:163], 0 op_sel_hi:[1,0,0]
	v_pk_fma_f32 v[124:125], v[124:125], v[162:163], 0 op_sel_hi:[1,0,0]
	v_pk_fma_f32 v[166:167], v[122:123], v[162:163], 0 op_sel_hi:[1,0,0]
	v_pk_fma_f32 v[122:123], v[120:121], v[162:163], 0 op_sel_hi:[1,0,0]
	v_cvt_pk_bf16_f32 v120, v124, v125
	v_cvt_pk_bf16_f32 v121, v126, v127
	v_pk_fma_f32 v[116:117], v[116:117], v[162:163], 0 op_sel_hi:[1,0,0]
	v_cvt_pk_bf16_f32 v122, v122, v123
	v_cvt_pk_bf16_f32 v123, v166, v167
	global_store_dwordx4 v[164:165], v[120:123], off sc0 sc1
	v_pk_fma_f32 v[118:119], v[118:119], v[162:163], 0 op_sel_hi:[1,0,0]
	s_nop 0
	v_pk_fma_f32 v[120:121], v[114:115], v[162:163], 0 op_sel_hi:[1,0,0]
	v_pk_fma_f32 v[114:115], v[112:113], v[162:163], 0 op_sel_hi:[1,0,0]
	v_cvt_pk_bf16_f32 v112, v116, v117
	v_cvt_pk_bf16_f32 v113, v118, v119
	s_nop 0
	v_cvt_pk_bf16_f32 v114, v114, v115
	v_cvt_pk_bf16_f32 v115, v120, v121
	global_store_dwordx4 v[164:165], v[112:115], off offset:256 sc0 sc1
	s_nop 1
	v_or_b32_e32 v112, 16, v146
	v_ashrrev_i32_e32 v113, 31, v112
	s_and_saveexec_b64 s[22:23], s[4:5]
	s_cbranch_execz .LBB0_867
	v_lshlrev_b64 v[114:115], 7, v[112:113]
	v_lshl_add_u64 v[114:115], v[136:137], 0, v[114:115]
	global_load_dwordx4 v[114:117], v[114:115], off
	s_waitcnt vmcnt(0)
	v_mov_b32_e32 v118, v115
	v_mov_b32_e32 v119, v116
	v_mov_b32_e32 v115, v117
	v_pk_add_f32 v[114:115], v[118:119], v[114:115]
	s_nop 0
	v_add_f32_e32 v114, v114, v115
	v_add_f32_e32 v160, 0, v114
.LBB0_867:
	s_or_b64 exec, exec, s[22:23]
	ds_bpermute_b32 v114, v158, v160
	v_lshlrev_b64 v[112:113], 12, v[112:113]
	v_lshl_add_u64 v[112:113], v[148:149], 0, v[112:113]
	s_waitcnt lgkmcnt(0)
	v_add_f32_e32 v114, v160, v114
	ds_bpermute_b32 v115, v159, v114
	s_waitcnt lgkmcnt(0)
	v_add_f32_e32 v114, v114, v115
	v_fmamk_f32 v114, v114, 0x3b000000, v157
	v_rsq_f32_e32 v114, v114
	s_nop 0
	v_pk_fma_f32 v[110:111], v[110:111], v[114:115], 0 op_sel_hi:[1,0,0]
	v_pk_fma_f32 v[108:109], v[108:109], v[114:115], 0 op_sel_hi:[1,0,0]
	v_pk_fma_f32 v[118:119], v[98:99], v[114:115], 0 op_sel_hi:[1,0,0]
	v_cvt_pk_bf16_f32 v98, v108, v109
	v_cvt_pk_bf16_f32 v99, v110, v111
	v_pk_fma_f32 v[106:107], v[106:107], v[114:115], 0 op_sel_hi:[1,0,0]
	v_pk_fma_f32 v[104:105], v[104:105], v[114:115], 0 op_sel_hi:[1,0,0]
	v_pk_fma_f32 v[116:117], v[100:101], v[114:115], 0 op_sel_hi:[1,0,0]
	v_cvt_pk_bf16_f32 v100, v104, v105
	v_cvt_pk_bf16_f32 v101, v106, v107
	global_store_dwordx4 v[112:113], v[98:101], off sc0 sc1
	v_pk_fma_f32 v[102:103], v[102:103], v[114:115], 0 op_sel_hi:[1,0,0]
	s_nop 0
	v_pk_fma_f32 v[98:99], v[96:97], v[114:115], 0 op_sel_hi:[1,0,0]
	v_cvt_pk_bf16_f32 v96, v116, v117
	v_cvt_pk_bf16_f32 v97, v102, v103
	s_nop 0
	v_cvt_pk_bf16_f32 v98, v98, v99
	v_cvt_pk_bf16_f32 v99, v118, v119
	global_store_dwordx4 v[112:113], v[96:99], off offset:256 sc0 sc1
	s_nop 1
	v_or_b32_e32 v96, 32, v146
	v_ashrrev_i32_e32 v97, 31, v96
	v_mov_b32_e32 v98, 0
	v_mov_b32_e32 v99, 0
	s_and_saveexec_b64 s[22:23], s[4:5]
	s_cbranch_execz .LBB0_869
	v_lshlrev_b64 v[100:101], 7, v[96:97]
	v_lshl_add_u64 v[100:101], v[136:137], 0, v[100:101]
	global_load_dwordx4 v[100:103], v[100:101], off
	s_waitcnt vmcnt(0)
	v_mov_b32_e32 v104, v101
	v_mov_b32_e32 v105, v102
	v_mov_b32_e32 v101, v103
	v_pk_add_f32 v[100:101], v[104:105], v[100:101]
	s_nop 0
	v_add_f32_e32 v99, v100, v101
	v_add_f32_e32 v99, 0, v99
.LBB0_869:
	s_or_b64 exec, exec, s[22:23]
	ds_bpermute_b32 v100, v158, v99
	v_lshlrev_b64 v[96:97], 12, v[96:97]
	v_lshl_add_u64 v[96:97], v[148:149], 0, v[96:97]
	s_waitcnt lgkmcnt(0)
	v_add_f32_e32 v99, v99, v100
	ds_bpermute_b32 v100, v159, v99
	s_waitcnt lgkmcnt(0)
	v_add_f32_e32 v99, v99, v100
	v_fmamk_f32 v99, v99, 0x3b000000, v157
	v_rsq_f32_e32 v100, v99
	s_nop 0
	v_pk_fma_f32 v[94:95], v[94:95], v[100:101], 0 op_sel_hi:[1,0,0]
	v_pk_fma_f32 v[92:93], v[92:93], v[100:101], 0 op_sel_hi:[1,0,0]
	v_pk_fma_f32 v[104:105], v[82:83], v[100:101], 0 op_sel_hi:[1,0,0]
	v_cvt_pk_bf16_f32 v82, v92, v93
	v_cvt_pk_bf16_f32 v83, v94, v95
	v_pk_fma_f32 v[90:91], v[90:91], v[100:101], 0 op_sel_hi:[1,0,0]
	v_pk_fma_f32 v[88:89], v[88:89], v[100:101], 0 op_sel_hi:[1,0,0]
	v_pk_fma_f32 v[102:103], v[84:85], v[100:101], 0 op_sel_hi:[1,0,0]
	v_cvt_pk_bf16_f32 v84, v88, v89
	v_cvt_pk_bf16_f32 v85, v90, v91
	global_store_dwordx4 v[96:97], v[82:85], off sc0 sc1
	v_pk_fma_f32 v[86:87], v[86:87], v[100:101], 0 op_sel_hi:[1,0,0]
	s_nop 0
	v_pk_fma_f32 v[82:83], v[80:81], v[100:101], 0 op_sel_hi:[1,0,0]
	v_cvt_pk_bf16_f32 v80, v102, v103
	v_cvt_pk_bf16_f32 v81, v86, v87
	s_nop 0
	v_cvt_pk_bf16_f32 v82, v82, v83
	v_cvt_pk_bf16_f32 v83, v104, v105
	global_store_dwordx4 v[96:97], v[80:83], off offset:256 sc0 sc1
	s_nop 1
	v_or_b32_e32 v80, 48, v146
	v_ashrrev_i32_e32 v81, 31, v80
	s_and_saveexec_b64 s[22:23], s[4:5]
	s_cbranch_execz .LBB0_871
	v_lshlrev_b64 v[82:83], 7, v[80:81]
	v_lshl_add_u64 v[82:83], v[136:137], 0, v[82:83]
	global_load_dwordx4 v[82:85], v[82:83], off
	s_waitcnt vmcnt(0)
	v_mov_b32_e32 v86, v83
	v_mov_b32_e32 v87, v84
	v_mov_b32_e32 v83, v85
	v_pk_add_f32 v[82:83], v[86:87], v[82:83]
	s_nop 0
	v_add_f32_e32 v82, v82, v83
	v_add_f32_e32 v98, 0, v82
; __device__ __forceinline__ unsigned cvt_pk_bf16(float lo, float hi) { unsigned r; asm volatile("v_cvt_pk_bf16_f32 %0, %1, %2" : "=v"(r) : "v"(lo), "v"(hi)); return r; }
; __device__ __forceinline__ float row_ss(const float* part, int row, int fq, int nf4) {
;     const f32x4* p = (const f32x4*)(part + (size_t)row * 32);
;     float s = 0.f;
; #pragma unroll
;     for (int j = 0; j < 2; ++j) { const int idx = fq + 4 * j; if (idx < nf4) { const f32x4 v = p[idx]; s += (v[0] + v[1]) + (v[2] + v[3]); } }
;     s += __shfl_xor(s, 16); s += __shfl_xor(s, 32);
;     return s;
; }
;     __device__ __forceinline__ void operator()(const f32x4 (&acc)[2][2][4][2], const Unit& u, int wr, int wc, int fr, int fq) const {
;         const int row0 = u.pm * BM + wr * 64 + fr; int colt = u.pn * BM; bf16_t* base = O;
;         float sc = 1.f; if (split_cols) { const int t = colt / split_cols; base += (size_t)t * split_stride; colt -= t * split_cols; if (t == 0) sc = scale0; } else sc = scale0;
;         const int col0 = colt + wc * 32 + 8 * fq, bcol0 = u.pn * BM + wc * 32 + 8 * fq;
;         f32x4 bv[2][2];
; #pragma unroll
;         for (int bj = 0; bj < 2; ++bj)
; #pragma unroll
;             for (int n = 0; n < 2; ++n) bv[bj][n] = bias ? *(const f32x4*)(bias + bcol0 + bj * HALF + 4 * n) : (f32x4){0.f, 0.f, 0.f, 0.f};
; #pragma unroll
;         for (int ai = 0; ai < 2; ++ai)
; #pragma unroll
;             for (int m = 0; m < 4; ++m) { const int row = row0 + ai * HALF + m * 16; bf16_t* rowp = base + (size_t)row * ldc + col0;
;                 const float rs = rss ? __builtin_amdgcn_rsqf(row_ss(rss, row, fq, nf4) * rinv + 1e-6f) : 1.f;
; #pragma unroll
;                 for (int bj = 0; bj < 2; ++bj) { f32x4 v0 = acc[ai][bj][m][0] * rs + bv[bj][0], v1 = acc[ai][bj][m][1] * rs + bv[bj][1];
;                     v0 = v0 * sc; v1 = v1 * sc; u32x4 w; w.x = cvt_pk_bf16(v0[0], v0[1]); w.y = cvt_pk_bf16(v0[2], v0[3]); w.z = cvt_pk_bf16(v1[0], v1[1]); w.w = cvt_pk_bf16(v1[2], v1[3]);
;                     *(u32x4*)(rowp + bj * HALF) = w; } }
.LBB0_871:
	s_or_b64 exec, exec, s[22:23]
	ds_bpermute_b32 v82, v158, v98
	v_lshlrev_b64 v[80:81], 12, v[80:81]
	v_lshl_add_u64 v[80:81], v[148:149], 0, v[80:81]
	s_waitcnt lgkmcnt(0)
	v_add_f32_e32 v82, v98, v82
	ds_bpermute_b32 v83, v159, v82
	s_waitcnt lgkmcnt(0)
	v_add_f32_e32 v82, v82, v83
	v_fmamk_f32 v82, v82, 0x3b000000, v157
	v_rsq_f32_e32 v82, v82
	s_nop 0
	v_pk_fma_f32 v[78:79], v[78:79], v[82:83], 0 op_sel_hi:[1,0,0]
	v_pk_fma_f32 v[76:77], v[76:77], v[82:83], 0 op_sel_hi:[1,0,0]
	v_pk_fma_f32 v[86:87], v[66:67], v[82:83], 0 op_sel_hi:[1,0,0]
	v_cvt_pk_bf16_f32 v66, v76, v77
	v_cvt_pk_bf16_f32 v67, v78, v79
	v_pk_fma_f32 v[74:75], v[74:75], v[82:83], 0 op_sel_hi:[1,0,0]
	v_pk_fma_f32 v[72:73], v[72:73], v[82:83], 0 op_sel_hi:[1,0,0]
	v_pk_fma_f32 v[84:85], v[68:69], v[82:83], 0 op_sel_hi:[1,0,0]
	v_cvt_pk_bf16_f32 v68, v72, v73
	v_cvt_pk_bf16_f32 v69, v74, v75
	global_store_dwordx4 v[80:81], v[66:69], off sc0 sc1
	v_pk_fma_f32 v[70:71], v[70:71], v[82:83], 0 op_sel_hi:[1,0,0]
	s_nop 0
	v_pk_fma_f32 v[66:67], v[64:65], v[82:83], 0 op_sel_hi:[1,0,0]
	v_cvt_pk_bf16_f32 v64, v84, v85
	v_cvt_pk_bf16_f32 v65, v70, v71
	s_nop 0
	v_cvt_pk_bf16_f32 v66, v66, v67
	v_cvt_pk_bf16_f32 v67, v86, v87
	global_store_dwordx4 v[80:81], v[64:67], off offset:256 sc0 sc1
	s_nop 1
	v_add_u32_e32 v64, 0x80, v146
	v_ashrrev_i32_e32 v65, 31, v64
	v_mov_b32_e32 v66, 0
	v_mov_b32_e32 v67, 0
	s_and_saveexec_b64 s[22:23], s[4:5]
	s_cbranch_execz .LBB0_873
	v_lshlrev_b64 v[68:69], 7, v[64:65]
	v_lshl_add_u64 v[68:69], v[136:137], 0, v[68:69]
	global_load_dwordx4 v[68:71], v[68:69], off
	s_waitcnt vmcnt(0)
	v_mov_b32_e32 v72, v69
	v_mov_b32_e32 v73, v70
	v_mov_b32_e32 v69, v71
	v_pk_add_f32 v[68:69], v[72:73], v[68:69]
	s_nop 0
	v_add_f32_e32 v67, v68, v69
	v_add_f32_e32 v67, 0, v67
.LBB0_873:
	s_or_b64 exec, exec, s[22:23]
	ds_bpermute_b32 v68, v158, v67
	v_lshlrev_b64 v[64:65], 12, v[64:65]
	v_lshl_add_u64 v[64:65], v[148:149], 0, v[64:65]
	s_waitcnt lgkmcnt(0)
	v_add_f32_e32 v67, v67, v68
	ds_bpermute_b32 v68, v159, v67
	s_waitcnt lgkmcnt(0)
	v_add_f32_e32 v67, v67, v68
	v_fmamk_f32 v67, v67, 0x3b000000, v157
	v_rsq_f32_e32 v68, v67
	s_nop 0
	v_pk_fma_f32 v[62:63], v[62:63], v[68:69], 0 op_sel_hi:[1,0,0]
	v_pk_fma_f32 v[60:61], v[60:61], v[68:69], 0 op_sel_hi:[1,0,0]
	v_pk_fma_f32 v[72:73], v[50:51], v[68:69], 0 op_sel_hi:[1,0,0]
	v_cvt_pk_bf16_f32 v50, v60, v61
	v_cvt_pk_bf16_f32 v51, v62, v63
	v_pk_fma_f32 v[58:59], v[58:59], v[68:69], 0 op_sel_hi:[1,0,0]
	v_pk_fma_f32 v[56:57], v[56:57], v[68:69], 0 op_sel_hi:[1,0,0]
	v_pk_fma_f32 v[70:71], v[52:53], v[68:69], 0 op_sel_hi:[1,0,0]
	v_cvt_pk_bf16_f32 v52, v56, v57
	v_cvt_pk_bf16_f32 v53, v58, v59
	global_store_dwordx4 v[64:65], v[50:53], off sc0 sc1
	v_pk_fma_f32 v[54:55], v[54:55], v[68:69], 0 op_sel_hi:[1,0,0]
	s_nop 0
	v_pk_fma_f32 v[50:51], v[48:49], v[68:69], 0 op_sel_hi:[1,0,0]
	v_cvt_pk_bf16_f32 v48, v70, v71
	v_cvt_pk_bf16_f32 v49, v54, v55
	s_nop 0
	v_cvt_pk_bf16_f32 v50, v50, v51
	v_cvt_pk_bf16_f32 v51, v72, v73
	global_store_dwordx4 v[64:65], v[48:51], off offset:256 sc0 sc1
	s_nop 1
	v_add_u32_e32 v48, 0x90, v146
	v_ashrrev_i32_e32 v49, 31, v48
	s_and_saveexec_b64 s[22:23], s[4:5]
	s_cbranch_execz .LBB0_875
	v_lshlrev_b64 v[50:51], 7, v[48:49]
	v_lshl_add_u64 v[50:51], v[136:137], 0, v[50:51]
	global_load_dwordx4 v[50:53], v[50:51], off
	s_waitcnt vmcnt(0)
	v_mov_b32_e32 v54, v51
	v_mov_b32_e32 v55, v52
	v_mov_b32_e32 v51, v53
	v_pk_add_f32 v[50:51], v[54:55], v[50:51]
	s_nop 0
	v_add_f32_e32 v50, v50, v51
	v_add_f32_e32 v66, 0, v50
; __device__ __forceinline__ unsigned cvt_pk_bf16(float lo, float hi) { unsigned r; asm volatile("v_cvt_pk_bf16_f32 %0, %1, %2" : "=v"(r) : "v"(lo), "v"(hi)); return r; }
; __device__ __forceinline__ float row_ss(const float* part, int row, int fq, int nf4) {
;     const f32x4* p = (const f32x4*)(part + (size_t)row * 32);
;     float s = 0.f;
; #pragma unroll
;     for (int j = 0; j < 2; ++j) { const int idx = fq + 4 * j; if (idx < nf4) { const f32x4 v = p[idx]; s += (v[0] + v[1]) + (v[2] + v[3]); } }
;     s += __shfl_xor(s, 16); s += __shfl_xor(s, 32);
;     return s;
; }
;     __device__ __forceinline__ void operator()(const f32x4 (&acc)[2][2][4][2], const Unit& u, int wr, int wc, int fr, int fq) const {
;         const int row0 = u.pm * BM + wr * 64 + fr; int colt = u.pn * BM; bf16_t* base = O;
;         float sc = 1.f; if (split_cols) { const int t = colt / split_cols; base += (size_t)t * split_stride; colt -= t * split_cols; if (t == 0) sc = scale0; } else sc = scale0;
;         const int col0 = colt + wc * 32 + 8 * fq, bcol0 = u.pn * BM + wc * 32 + 8 * fq;
;         f32x4 bv[2][2];
; #pragma unroll
;         for (int bj = 0; bj < 2; ++bj)
; #pragma unroll
;             for (int n = 0; n < 2; ++n) bv[bj][n] = bias ? *(const f32x4*)(bias + bcol0 + bj * HALF + 4 * n) : (f32x4){0.f, 0.f, 0.f, 0.f};
; #pragma unroll
;         for (int ai = 0; ai < 2; ++ai)
; #pragma unroll
;             for (int m = 0; m < 4; ++m) { const int row = row0 + ai * HALF + m * 16; bf16_t* rowp = base + (size_t)row * ldc + col0;
;                 const float rs = rss ? __builtin_amdgcn_rsqf(row_ss(rss, row, fq, nf4) * rinv + 1e-6f) : 1.f;
; #pragma unroll
;                 for (int bj = 0; bj < 2; ++bj) { f32x4 v0 = acc[ai][bj][m][0] * rs + bv[bj][0], v1 = acc[ai][bj][m][1] * rs + bv[bj][1];
;                     v0 = v0 * sc; v1 = v1 * sc; u32x4 w; w.x = cvt_pk_bf16(v0[0], v0[1]); w.y = cvt_pk_bf16(v0[2], v0[3]); w.z = cvt_pk_bf16(v1[0], v1[1]); w.w = cvt_pk_bf16(v1[2], v1[3]);
;                     *(u32x4*)(rowp + bj * HALF) = w; } }
.LBB0_875:
	s_or_b64 exec, exec, s[22:23]
	ds_bpermute_b32 v50, v158, v66
	v_lshlrev_b64 v[48:49], 12, v[48:49]
	v_lshl_add_u64 v[48:49], v[148:149], 0, v[48:49]
	s_waitcnt lgkmcnt(0)
	v_add_f32_e32 v50, v66, v50
	ds_bpermute_b32 v51, v159, v50
	s_waitcnt lgkmcnt(0)
	v_add_f32_e32 v50, v50, v51
	v_fmamk_f32 v50, v50, 0x3b000000, v157
	v_rsq_f32_e32 v50, v50
	s_nop 0
	v_pk_fma_f32 v[46:47], v[46:47], v[50:51], 0 op_sel_hi:[1,0,0]
	v_pk_fma_f32 v[44:45], v[44:45], v[50:51], 0 op_sel_hi:[1,0,0]
	v_pk_fma_f32 v[54:55], v[34:35], v[50:51], 0 op_sel_hi:[1,0,0]
	v_cvt_pk_bf16_f32 v34, v44, v45
	v_cvt_pk_bf16_f32 v35, v46, v47
	v_pk_fma_f32 v[42:43], v[42:43], v[50:51], 0 op_sel_hi:[1,0,0]
	v_pk_fma_f32 v[40:41], v[40:41], v[50:51], 0 op_sel_hi:[1,0,0]
	v_pk_fma_f32 v[52:53], v[36:37], v[50:51], 0 op_sel_hi:[1,0,0]
	v_cvt_pk_bf16_f32 v36, v40, v41
	v_cvt_pk_bf16_f32 v37, v42, v43
	global_store_dwordx4 v[48:49], v[34:37], off sc0 sc1
	v_pk_fma_f32 v[38:39], v[38:39], v[50:51], 0 op_sel_hi:[1,0,0]
	s_nop 0
	v_pk_fma_f32 v[34:35], v[32:33], v[50:51], 0 op_sel_hi:[1,0,0]
	v_cvt_pk_bf16_f32 v32, v52, v53
	v_cvt_pk_bf16_f32 v33, v38, v39
	s_nop 0
	v_cvt_pk_bf16_f32 v34, v34, v35
	v_cvt_pk_bf16_f32 v35, v54, v55
	global_store_dwordx4 v[48:49], v[32:35], off offset:256 sc0 sc1
	s_nop 1
	v_add_u32_e32 v32, 0xa0, v146
	v_ashrrev_i32_e32 v33, 31, v32
	v_mov_b32_e32 v34, 0
	v_mov_b32_e32 v35, 0
	s_and_saveexec_b64 s[22:23], s[4:5]
	s_cbranch_execz .LBB0_877
	v_lshlrev_b64 v[36:37], 7, v[32:33]
	v_lshl_add_u64 v[36:37], v[136:137], 0, v[36:37]
	global_load_dwordx4 v[36:39], v[36:37], off
	s_waitcnt vmcnt(0)
	v_mov_b32_e32 v40, v37
	v_mov_b32_e32 v41, v38
	v_mov_b32_e32 v37, v39
	v_pk_add_f32 v[36:37], v[40:41], v[36:37]
	s_nop 0
	v_add_f32_e32 v35, v36, v37
	v_add_f32_e32 v35, 0, v35
.LBB0_877:
	s_or_b64 exec, exec, s[22:23]
	ds_bpermute_b32 v36, v158, v35
	v_lshlrev_b64 v[32:33], 12, v[32:33]
	v_lshl_add_u64 v[32:33], v[148:149], 0, v[32:33]
	s_waitcnt lgkmcnt(0)
	v_add_f32_e32 v35, v35, v36
	ds_bpermute_b32 v36, v159, v35
	s_waitcnt lgkmcnt(0)
	v_add_f32_e32 v35, v35, v36
	v_fmamk_f32 v35, v35, 0x3b000000, v157
	v_rsq_f32_e32 v36, v35
	s_nop 0
	v_pk_fma_f32 v[30:31], v[30:31], v[36:37], 0 op_sel_hi:[1,0,0]
	v_pk_fma_f32 v[28:29], v[28:29], v[36:37], 0 op_sel_hi:[1,0,0]
	v_pk_fma_f32 v[40:41], v[18:19], v[36:37], 0 op_sel_hi:[1,0,0]
	v_cvt_pk_bf16_f32 v18, v28, v29
	v_cvt_pk_bf16_f32 v19, v30, v31
	v_pk_fma_f32 v[26:27], v[26:27], v[36:37], 0 op_sel_hi:[1,0,0]
	v_pk_fma_f32 v[24:25], v[24:25], v[36:37], 0 op_sel_hi:[1,0,0]
	v_pk_fma_f32 v[38:39], v[20:21], v[36:37], 0 op_sel_hi:[1,0,0]
	v_cvt_pk_bf16_f32 v20, v24, v25
	v_cvt_pk_bf16_f32 v21, v26, v27
	global_store_dwordx4 v[32:33], v[18:21], off sc0 sc1
	v_pk_fma_f32 v[22:23], v[22:23], v[36:37], 0 op_sel_hi:[1,0,0]
	s_nop 0
	v_pk_fma_f32 v[18:19], v[16:17], v[36:37], 0 op_sel_hi:[1,0,0]
	v_cvt_pk_bf16_f32 v16, v38, v39
	v_cvt_pk_bf16_f32 v17, v22, v23
	s_nop 0
	v_cvt_pk_bf16_f32 v18, v18, v19
	v_cvt_pk_bf16_f32 v19, v40, v41
	global_store_dwordx4 v[32:33], v[16:19], off offset:256 sc0 sc1
	s_nop 1
	v_add_u32_e32 v16, 0xb0, v146
	v_ashrrev_i32_e32 v17, 31, v16
	s_and_saveexec_b64 s[22:23], s[4:5]
	s_cbranch_execz .LBB0_879
	v_lshlrev_b64 v[18:19], 7, v[16:17]
	v_lshl_add_u64 v[18:19], v[136:137], 0, v[18:19]
	global_load_dwordx4 v[18:21], v[18:19], off
	s_waitcnt vmcnt(0)
	v_mov_b32_e32 v22, v19
	v_mov_b32_e32 v23, v20
	v_mov_b32_e32 v19, v21
	v_pk_add_f32 v[18:19], v[22:23], v[18:19]
	s_nop 0
	v_add_f32_e32 v18, v18, v19
	v_add_f32_e32 v34, 0, v18
.LBB0_879:
	s_or_b64 exec, exec, s[22:23]
	ds_bpermute_b32 v18, v158, v34
	v_lshlrev_b64 v[16:17], 12, v[16:17]
	v_lshl_add_u64 v[16:17], v[148:149], 0, v[16:17]
	s_andn2_b64 vcc, exec, s[8:9]
	s_mov_b64 s[8:9], -1
	s_waitcnt lgkmcnt(0)
	v_add_f32_e32 v18, v34, v18
	ds_bpermute_b32 v19, v159, v18
	s_waitcnt lgkmcnt(0)
	v_add_f32_e32 v18, v18, v19
	v_fmamk_f32 v18, v18, 0x3b000000, v157
	v_rsq_f32_e32 v18, v18
	s_nop 0
	v_pk_fma_f32 v[14:15], v[14:15], v[18:19], 0 op_sel_hi:[1,0,0]
	v_pk_fma_f32 v[12:13], v[12:13], v[18:19], 0 op_sel_hi:[1,0,0]
	v_pk_fma_f32 v[22:23], v[2:3], v[18:19], 0 op_sel_hi:[1,0,0]
	v_cvt_pk_bf16_f32 v2, v12, v13
	v_cvt_pk_bf16_f32 v3, v14, v15
	v_pk_fma_f32 v[10:11], v[10:11], v[18:19], 0 op_sel_hi:[1,0,0]
	v_pk_fma_f32 v[8:9], v[8:9], v[18:19], 0 op_sel_hi:[1,0,0]
	v_pk_fma_f32 v[20:21], v[4:5], v[18:19], 0 op_sel_hi:[1,0,0]
	v_cvt_pk_bf16_f32 v4, v8, v9
	v_cvt_pk_bf16_f32 v5, v10, v11
	global_store_dwordx4 v[16:17], v[2:5], off sc0 sc1
	v_pk_fma_f32 v[6:7], v[6:7], v[18:19], 0 op_sel_hi:[1,0,0]
	s_nop 0
	v_pk_fma_f32 v[2:3], v[0:1], v[18:19], 0 op_sel_hi:[1,0,0]
	v_cvt_pk_bf16_f32 v0, v20, v21
	v_cvt_pk_bf16_f32 v1, v6, v7
	s_nop 0
	v_cvt_pk_bf16_f32 v2, v2, v3
	v_cvt_pk_bf16_f32 v3, v22, v23
	global_store_dwordx4 v[16:17], v[0:3], off offset:256 sc0 sc1
	s_cbranch_vccnz .LBB0_852
	s_andn2_b64 vcc, exec, s[0:1]
	s_cbranch_vccnz .LBB0_851
	s_barrier
	s_branch .LBB0_851

; #define LAS __attribute__((address_space(3)))
; __device__ __forceinline__ unsigned cvtpk(float lo, float hi) { f32x2 v = {lo, hi}; bf16x2_t b = __builtin_convertvector(v, bf16x2_t); return __builtin_bit_cast(unsigned, b); }
; __device__ __forceinline__ void witem_store(const WItem& w, int K, bf16_t* WT, int kvperm, LAS float* scr, int item, int nblk, int lane) {
;     const int kb = item / nblk, nb = item % nblk, k0 = 64 * kb, n0 = 32 * nb;
;     const int col = 4 * (lane & 7), rr = lane >> 3;
; #pragma unroll
;     for (int i = 0; i < 8; ++i) { LAS float* d = scr + (8 * i + rr) * 33 + col; const float g = w.g[i]; d[0] = w.v[i].x * g; d[1] = w.v[i].y * g; d[2] = w.v[i].z * g; d[3] = w.v[i].w * g; }
;     asm volatile("s_waitcnt lgkmcnt(0)" ::: "memory");
;     const int c = lane & 7;
; #pragma unroll
;     for (int j = 0; j < 4; ++j) { const int n = (lane >> 3) + 8 * j; const LAS float* s = scr + (8 * c) * 33 + n;
;         u32x4 o; o.x = cvtpk(s[0 * 33], s[1 * 33]); o.y = cvtpk(s[2 * 33], s[3 * 33]); o.z = cvtpk(s[4 * 33], s[5 * 33]); o.w = cvtpk(s[6 * 33], s[7 * 33]);
;         int nr = n0 + n; if (kvperm == 1) { const int hh = nr >> 8, ww = nr & 255; nr = (ww < 128) ? hh * 128 + ww : 2048 + hh * 128 + (ww - 128); }
;         else if (kvperm == 2) { const int isv = nr >= 5632, f = isv ? nr - 5632 : nr; nr = (f >> 7) * 256 + isv * 128 + (f & 127); }
;         *(u32x4*)(WT + (size_t)nr * K + k0 + 8 * c) = o; }
;     asm volatile("s_waitcnt lgkmcnt(0)" ::: "memory");
; }
;     ...
;     while (it < i1) {
;         cur = nxt;
;         const int nit = it + NGW;
;         if (nit < i1) witem_load(nxt, W, N, gk, nit, nblk, lane);
;         witem_store(cur, K, WT, kvperm, scr, it, nblk, lane);
;         it = nit;
;     }
.LBB0_906:
	ds_write2_b32 v79, v4, v5 offset1:1
	ds_write2_b32 v79, v6, v7 offset0:2 offset1:3
	v_add_u32_e32 v4, 0x420, v79
	ds_write2_b32 v4, v0, v1 offset1:1
	v_add_u32_e32 v0, 0x428, v79
	ds_write2_b32 v0, v2, v3 offset1:1
	v_add_u32_e32 v0, 0x840, v79
	ds_write2_b32 v0, v12, v13 offset1:1
	v_add_u32_e32 v0, 0x848, v79
	ds_write2_b32 v0, v14, v15 offset1:1
	v_add_u32_e32 v0, 0xc60, v79
	ds_write2_b32 v0, v8, v9 offset1:1
	v_add_u32_e32 v0, 0xc68, v79
	ds_write2_b32 v0, v10, v11 offset1:1
	v_add_u32_e32 v0, 0x1080, v79
	ds_write2_b32 v0, v24, v25 offset1:1
	v_add_u32_e32 v0, 0x1088, v79
	ds_write2_b32 v0, v26, v27 offset1:1
	v_add_u32_e32 v0, 0x14a0, v79
	ds_write2_b32 v0, v20, v21 offset1:1
	v_add_u32_e32 v0, 0x14a8, v79
	ds_write2_b32 v0, v22, v23 offset1:1
	v_add_u32_e32 v0, 0x18c0, v79
	s_ashr_i32 s4, s6, 31
	ds_write2_b32 v0, v36, v37 offset1:1
	v_add_u32_e32 v0, 0x18c8, v79
	s_lshr_b32 s4, s4, 26
	ds_write2_b32 v0, v38, v39 offset1:1
	v_add_u32_e32 v0, 0x1ce0, v79
	s_add_i32 s6, s6, s4
	ds_write2_b32 v0, v40, v41 offset1:1
	v_add_u32_e32 v0, 0x1ce8, v79
	s_and_b32 s4, s6, 0xffffffc0
	ds_write2_b32 v0, v42, v43 offset1:1
	s_waitcnt lgkmcnt(0)
	s_ashr_i32 s5, s4, 31
	ds_read2_b32 v[4:5], v78 offset0:33 offset1:41
	ds_read2_b32 v[6:7], v78 offset1:8
	ds_read2_b32 v[8:9], v78 offset0:66 offset1:74
	ds_read2_b32 v[10:11], v78 offset0:99 offset1:107
	ds_read2_b32 v[12:13], v78 offset0:132 offset1:140
	ds_read2_b32 v[14:15], v78 offset0:165 offset1:173
	ds_read2_b32 v[18:19], v78 offset0:198 offset1:206
	ds_read2_b32 v[20:21], v78 offset0:231 offset1:239
	v_lshl_add_u64 v[22:23], s[4:5], 1, v[70:71]
	s_lshl_b32 s4, s6, 5
	s_waitcnt lgkmcnt(6)
	v_cvt_pk_bf16_f32 v0, v6, v4
	v_add_u32_e32 v4, s7, v80
	s_and_b32 s4, s4, 0xfffff800
	v_subrev_u32_e32 v24, s4, v4
	v_ashrrev_i32_e32 v25, 31, v24
	v_lshlrev_b64 v[26:27], 12, v[24:25]
	s_waitcnt lgkmcnt(4)
	v_cvt_pk_bf16_f32 v1, v8, v10
	s_waitcnt lgkmcnt(2)
	v_cvt_pk_bf16_f32 v2, v12, v14
	s_waitcnt lgkmcnt(0)
	v_cvt_pk_bf16_f32 v3, v18, v20
	v_lshl_add_u64 v[26:27], v[22:23], 0, v[26:27]
	v_add_u32_e32 v4, 8, v24
	global_store_dwordx4 v[26:27], v[0:3], off sc0 sc1
	s_waitcnt vmcnt(1)
	v_mov_b64_e32 v[36:37], v[60:61]
	v_add_u32_e32 v80, s8, v80
	v_cvt_pk_bf16_f32 v0, v7, v5
	v_ashrrev_i32_e32 v5, 31, v4
	v_cvt_pk_bf16_f32 v1, v9, v11
	v_cvt_pk_bf16_f32 v2, v13, v15
	v_cvt_pk_bf16_f32 v3, v19, v21
	v_lshlrev_b64 v[4:5], 12, v[4:5]
	ds_read2_b32 v[6:7], v78 offset0:49 offset1:57
	ds_read2_b32 v[8:9], v78 offset0:16 offset1:24
	ds_read2_b32 v[10:11], v78 offset0:82 offset1:90
	ds_read2_b32 v[12:13], v78 offset0:115 offset1:123
	ds_read2_b32 v[14:15], v78 offset0:148 offset1:156
	ds_read2_b32 v[18:19], v78 offset0:181 offset1:189
	ds_read2_b32 v[20:21], v78 offset0:214 offset1:222
	ds_read2_b32 v[26:27], v78 offset0:247 offset1:255
	v_lshl_add_u64 v[4:5], v[22:23], 0, v[4:5]
	global_store_dwordx4 v[4:5], v[0:3], off sc0 sc1
	v_add_u32_e32 v4, 16, v24
	v_ashrrev_i32_e32 v5, 31, v4
	v_lshlrev_b64 v[4:5], 12, v[4:5]
	s_waitcnt lgkmcnt(6)
	v_cvt_pk_bf16_f32 v0, v8, v6
	s_waitcnt lgkmcnt(4)
	v_cvt_pk_bf16_f32 v1, v10, v12
	s_waitcnt lgkmcnt(2)
	v_cvt_pk_bf16_f32 v2, v14, v18
	s_waitcnt lgkmcnt(0)
	v_cvt_pk_bf16_f32 v3, v20, v26
	v_lshl_add_u64 v[4:5], v[22:23], 0, v[4:5]
	global_store_dwordx4 v[4:5], v[0:3], off sc0 sc1
	v_add_u32_e32 v4, 24, v24
	v_ashrrev_i32_e32 v5, 31, v4
	v_lshlrev_b64 v[4:5], 12, v[4:5]
	v_cvt_pk_bf16_f32 v0, v9, v7
	v_cvt_pk_bf16_f32 v1, v11, v13
	v_cvt_pk_bf16_f32 v2, v15, v19
	v_cvt_pk_bf16_f32 v3, v21, v27
	v_lshl_add_u64 v[4:5], v[22:23], 0, v[4:5]
	global_store_dwordx4 v[4:5], v[0:3], off sc0 sc1
	s_waitcnt lgkmcnt(0)
	v_mov_b64_e32 v[4:5], v[32:33]
	v_mov_b64_e32 v[12:13], v[44:45]
	v_mov_b64_e32 v[0:1], v[28:29]
	v_mov_b64_e32 v[8:9], v[48:49]
	v_mov_b64_e32 v[24:25], v[52:53]
	v_mov_b64_e32 v[20:21], v[56:57]
	s_add_i32 s11, s11, s8
	v_add_u32_e32 v76, s8, v76
	s_andn2_b64 vcc, exec, s[0:1]
	s_mov_b32 s6, s12
	v_mov_b64_e32 v[6:7], v[34:35]
	v_mov_b64_e32 v[2:3], v[30:31]
	v_mov_b64_e32 v[14:15], v[46:47]
	v_mov_b64_e32 v[10:11], v[50:51]
	v_mov_b64_e32 v[26:27], v[54:55]
	v_mov_b64_e32 v[22:23], v[58:59]
	v_mov_b64_e32 v[38:39], v[62:63]
	v_mov_b32_e32 v40, v64
	v_mov_b32_e32 v41, v65
	v_mov_b32_e32 v42, v66
	v_mov_b32_e32 v43, v67
	s_cbranch_vccz .LBB0_924

; __device__ __forceinline__ unsigned cvt_pk_bf16(float lo, float hi) { unsigned r; asm volatile("v_cvt_pk_bf16_f32 %0, %1, %2" : "=v"(r) : "v"(lo), "v"(hi)); return r; }
;     __device__ __forceinline__ void operator()(const f32x4 (&acc)[2][2][4][2], const Unit& u, int wr, int wc, int fr, int fq) const {
;         const int row0 = u.pm * BM + wr * 64 + fr, col0 = u.pn * BM + wc * 32 + 8 * fq;
;         f32x4 bv[2][2];
; #pragma unroll
;         for (int bj = 0; bj < 2; ++bj)
; #pragma unroll
;             for (int n = 0; n < 2; ++n) bv[bj][n] = bias ? *(const f32x4*)(bias + col0 + bj * HALF + 4 * n) : (f32x4){0.f, 0.f, 0.f, 0.f};
;         float* ssp = ssout + (size_t)(u.pn * 4 + wc);
; #pragma unroll
;         for (int ai = 0; ai < 2; ++ai) {
;             u32x4 old[4][2];
; #pragma unroll
;             for (int m = 0; m < 4; ++m)
; #pragma unroll
;                 for (int bj = 0; bj < 2; ++bj) old[m][bj] = *(const u32x4*)(HB + (size_t)(row0 + ai * HALF + m * 16) * ldc + col0 + bj * HALF);
; #pragma unroll
;             for (int m = 0; m < 4; ++m) { const int row = row0 + ai * HALF + m * 16; float ss = 0.f;
; #pragma unroll
;                 for (int bj = 0; bj < 2; ++bj) { const u32x4 ow = old[m][bj];
;                     f32x4 v0 = (acc[ai][bj][m][0] + bv[bj][0]) * accs, v1 = (acc[ai][bj][m][1] + bv[bj][1]) * accs;
;                     v0[0] += __uint_as_float(ow.x << 16); v0[1] += __uint_as_float(ow.x & 0xffff0000u); v0[2] += __uint_as_float(ow.y << 16); v0[3] += __uint_as_float(ow.y & 0xffff0000u);
;                     v1[0] += __uint_as_float(ow.z << 16); v1[1] += __uint_as_float(ow.z & 0xffff0000u); v1[2] += __uint_as_float(ow.w << 16); v1[3] += __uint_as_float(ow.w & 0xffff0000u);
;                     ss += (v0[0] * v0[0] + v0[1] * v0[1]) + (v0[2] * v0[2] + v0[3] * v0[3]) + (v1[0] * v1[0] + v1[1] * v1[1]) + (v1[2] * v1[2] + v1[3] * v1[3]);
;                     u32x4 w; w.x = cvt_pk_bf16(v0[0], v0[1]); w.y = cvt_pk_bf16(v0[2], v0[3]); w.z = cvt_pk_bf16(v1[0], v1[1]); w.w = cvt_pk_bf16(v1[2], v1[3]);
;                     *(u32x4*)(HB + (size_t)row * ldc + col0 + bj * HALF) = w; }
;                 ss += __shfl_xor(ss, 16); ss += __shfl_xor(ss, 32);
;                 if (fq == 0) ssp[(size_t)row * 32] = ss; }
.LBB0_1069:
	v_lshl_or_b32 v152, s24, 8, v166
	v_ashrrev_i32_e32 v153, 31, v152
	v_lshl_add_u32 v154, s26, 8, v164
	v_lshlrev_b64 v[180:181], 1, v[152:153]
	v_ashrrev_i32_e32 v155, 31, v154
	v_lshl_add_u64 v[156:157], s[4:5], 0, v[180:181]
	v_lshlrev_b64 v[182:183], 12, v[154:155]
	v_lshl_add_u64 v[128:129], v[156:157], 0, v[182:183]
	global_load_dwordx4 v[172:175], v[128:129], off
	global_load_dwordx4 v[176:179], v[128:129], off offset:256
	v_or_b32_e32 v162, 16, v154
	v_or_b32_e32 v160, 32, v154
	v_or_b32_e32 v158, 48, v154
	v_ashrrev_i32_e32 v163, 31, v162
	v_ashrrev_i32_e32 v161, 31, v160
	v_pk_add_f32 v[196:197], v[114:115], 0 op_sel_hi:[1,0]
	v_pk_add_f32 v[198:199], v[112:113], 0 op_sel_hi:[1,0]
	v_ashrrev_i32_e32 v159, 31, v158
	v_lshlrev_b64 v[112:113], 12, v[162:163]
	v_lshlrev_b64 v[114:115], 12, v[160:161]
	v_pk_add_f32 v[194:195], v[116:117], 0 op_sel_hi:[1,0]
	v_lshlrev_b64 v[116:117], 12, v[158:159]
	v_lshl_add_u64 v[112:113], v[156:157], 0, v[112:113]
	v_lshl_add_u64 v[114:115], v[156:157], 0, v[114:115]
	v_pk_add_f32 v[184:185], v[126:127], 0 op_sel_hi:[1,0]
	v_pk_add_f32 v[186:187], v[124:125], 0 op_sel_hi:[1,0]
	v_pk_add_f32 v[188:189], v[122:123], 0 op_sel_hi:[1,0]
	v_pk_add_f32 v[190:191], v[120:121], 0 op_sel_hi:[1,0]
	v_pk_add_f32 v[192:193], v[118:119], 0 op_sel_hi:[1,0]
	v_lshl_add_u64 v[200:201], v[156:157], 0, v[116:117]
	global_load_dwordx4 v[132:135], v[112:113], off
	global_load_dwordx4 v[128:131], v[112:113], off offset:256
	global_load_dwordx4 v[124:127], v[114:115], off
	global_load_dwordx4 v[120:123], v[114:115], off offset:256
	global_load_dwordx4 v[116:119], v[200:201], off
	s_nop 0
	global_load_dwordx4 v[112:115], v[200:201], off offset:256
	s_lshl_b32 s6, s24, 2
	s_or_b32 s6, s6, s46
	s_ashr_i32 s7, s6, 31
	s_lshl_b64 s[6:7], s[6:7], 2
	s_add_u32 s24, s44, s6
	s_addc_u32 s25, s45, s7
	s_waitcnt vmcnt(0)
	v_lshlrev_b32_e32 v171, 16, v172
	v_and_b32_e32 v172, 0xffff0000, v172
	v_lshlrev_b32_e32 v200, 16, v173
	v_and_b32_e32 v173, 0xffff0000, v173
	v_lshlrev_b32_e32 v201, 16, v174
	v_lshlrev_b32_e32 v202, 16, v175
	v_lshlrev_b32_e32 v203, 16, v176
	v_and_b32_e32 v176, 0xffff0000, v176
	v_lshlrev_b32_e32 v206, 16, v177
	v_and_b32_e32 v177, 0xffff0000, v177
	v_add_f32_e32 v172, v187, v172
	v_add_f32_e32 v173, v185, v173
	v_and_b32_e32 v175, 0xffff0000, v175
	v_lshlrev_b32_e32 v207, 16, v178
	v_and_b32_e32 v178, 0xffff0000, v178
	v_lshlrev_b32_e32 v208, 16, v179
	v_add_f32_e32 v171, v186, v171
	v_add_f32_e32 v184, v184, v200
	v_add_f32_e32 v185, v190, v201
	v_add_f32_e32 v186, v188, v202
	v_add_f32_e32 v188, v195, v176
	v_add_f32_e32 v190, v193, v177
	v_mul_f32_e32 v176, v172, v172
	v_mul_f32_e32 v177, v173, v173
	v_and_b32_e32 v174, 0xffff0000, v174
	v_add_f32_e32 v175, v189, v175
	v_add_f32_e32 v187, v194, v203
	v_add_f32_e32 v189, v192, v206
	v_add_f32_e32 v178, v199, v178
	v_add_f32_e32 v192, v196, v208
	v_mul_f32_e32 v195, v188, v188
	v_mul_f32_e32 v196, v190, v190
	v_fmac_f32_e32 v176, v171, v171
	v_fmac_f32_e32 v177, v184, v184
	v_and_b32_e32 v179, 0xffff0000, v179
	v_add_f32_e32 v174, v191, v174
	v_add_f32_e32 v191, v198, v207
	v_cvt_pk_bf16_f32 v172, v171, v172
	v_fmac_f32_e32 v195, v187, v187
	v_add_f32_e32 v171, v176, v177
	v_fmac_f32_e32 v196, v189, v189
	v_mul_f32_e32 v177, v178, v178
	v_add_f32_e32 v179, v197, v179
	v_mul_f32_e32 v193, v174, v174
	v_add_f32_e32 v176, v195, v196
	v_fmac_f32_e32 v177, v191, v191
	v_mul_f32_e32 v194, v175, v175
	v_fmac_f32_e32 v193, v185, v185
	v_add_f32_e32 v176, v177, v176
	v_mul_f32_e32 v177, v179, v179
	v_fmac_f32_e32 v194, v186, v186
	v_add_f32_e32 v171, v193, v171
	v_fmac_f32_e32 v177, v192, v192
	v_add_f32_e32 v171, v194, v171
	v_add_f32_e32 v176, v177, v176
	v_cvt_pk_bf16_f32 v173, v184, v173
	v_add_f32_e32 v184, v171, v176
	v_and_b32_e32 v176, 64, v170
	v_cvt_pk_bf16_f32 v174, v185, v174
	v_xor_b32_e32 v171, 16, v170
	v_add_u32_e32 v185, 64, v176
	v_cmp_lt_i32_e32 vcc, v171, v185
	v_cvt_pk_bf16_f32 v175, v186, v175
	v_lshl_add_u64 v[176:177], s[4:5], 0, v[182:183]
	v_lshl_add_u64 v[180:181], v[176:177], 0, v[180:181]
	v_cndmask_b32_e32 v171, v170, v171, vcc
	v_lshlrev_b32_e32 v171, 2, v171
	ds_bpermute_b32 v186, v171, v184
	global_store_dwordx4 v[180:181], v[172:175], off sc0 sc1
	v_cvt_pk_bf16_f32 v176, v187, v188
	v_cvt_pk_bf16_f32 v177, v189, v190
	v_cvt_pk_bf16_f32 v178, v191, v178
	v_cvt_pk_bf16_f32 v179, v192, v179
	global_store_dwordx4 v[180:181], v[176:179], off offset:256 sc0 sc1
	s_nop 0
	v_xor_b32_e32 v172, 32, v170
	v_cmp_lt_i32_e32 vcc, v172, v185
	s_waitcnt lgkmcnt(0)
	v_add_f32_e32 v173, v184, v186
	v_cndmask_b32_e32 v172, v170, v172, vcc
	v_lshlrev_b32_e32 v172, 2, v172
	ds_bpermute_b32 v174, v172, v173
	s_and_saveexec_b64 s[26:27], s[8:9]
	s_cbranch_execz .LBB0_1071
	v_lshlrev_b64 v[176:177], 7, v[154:155]
	v_lshl_add_u64 v[176:177], s[24:25], 0, v[176:177]
	s_waitcnt lgkmcnt(0)
	v_add_f32_e32 v155, v173, v174
	global_store_dword v[176:177], v155, off
; __device__ __forceinline__ unsigned cvt_pk_bf16(float lo, float hi) { unsigned r; asm volatile("v_cvt_pk_bf16_f32 %0, %1, %2" : "=v"(r) : "v"(lo), "v"(hi)); return r; }
;     __device__ __forceinline__ void operator()(const f32x4 (&acc)[2][2][4][2], const Unit& u, int wr, int wc, int fr, int fq) const {
;         const int row0 = u.pm * BM + wr * 64 + fr, col0 = u.pn * BM + wc * 32 + 8 * fq;
;         f32x4 bv[2][2];
; #pragma unroll
;         for (int bj = 0; bj < 2; ++bj)
; #pragma unroll
;             for (int n = 0; n < 2; ++n) bv[bj][n] = bias ? *(const f32x4*)(bias + col0 + bj * HALF + 4 * n) : (f32x4){0.f, 0.f, 0.f, 0.f};
;         float* ssp = ssout + (size_t)(u.pn * 4 + wc);
; #pragma unroll
;         for (int ai = 0; ai < 2; ++ai) {
;             u32x4 old[4][2];
; #pragma unroll
;             for (int m = 0; m < 4; ++m)
; #pragma unroll
;                 for (int bj = 0; bj < 2; ++bj) old[m][bj] = *(const u32x4*)(HB + (size_t)(row0 + ai * HALF + m * 16) * ldc + col0 + bj * HALF);
; #pragma unroll
;             for (int m = 0; m < 4; ++m) { const int row = row0 + ai * HALF + m * 16; float ss = 0.f;
; #pragma unroll
;                 for (int bj = 0; bj < 2; ++bj) { const u32x4 ow = old[m][bj];
;                     f32x4 v0 = (acc[ai][bj][m][0] + bv[bj][0]) * accs, v1 = (acc[ai][bj][m][1] + bv[bj][1]) * accs;
;                     v0[0] += __uint_as_float(ow.x << 16); v0[1] += __uint_as_float(ow.x & 0xffff0000u); v0[2] += __uint_as_float(ow.y << 16); v0[3] += __uint_as_float(ow.y & 0xffff0000u);
;                     v1[0] += __uint_as_float(ow.z << 16); v1[1] += __uint_as_float(ow.z & 0xffff0000u); v1[2] += __uint_as_float(ow.w << 16); v1[3] += __uint_as_float(ow.w & 0xffff0000u);
;                     ss += (v0[0] * v0[0] + v0[1] * v0[1]) + (v0[2] * v0[2] + v0[3] * v0[3]) + (v1[0] * v1[0] + v1[1] * v1[1]) + (v1[2] * v1[2] + v1[3] * v1[3]);
;                     u32x4 w; w.x = cvt_pk_bf16(v0[0], v0[1]); w.y = cvt_pk_bf16(v0[2], v0[3]); w.z = cvt_pk_bf16(v1[0], v1[1]); w.w = cvt_pk_bf16(v1[2], v1[3]);
;                     *(u32x4*)(HB + (size_t)row * ldc + col0 + bj * HALF) = w; }
;                 ss += __shfl_xor(ss, 16); ss += __shfl_xor(ss, 32);
;                 if (fq == 0) ssp[(size_t)row * 32] = ss; }
.LBB0_1071:
	s_or_b64 exec, exec, s[26:27]
	v_pk_add_f32 v[108:109], v[108:109], 0 op_sel_hi:[1,0]
	v_lshlrev_b32_e32 v155, 16, v132
	v_and_b32_e32 v132, 0xffff0000, v132
	v_pk_add_f32 v[110:111], v[110:111], 0 op_sel_hi:[1,0]
	v_add_f32_e32 v109, v109, v132
	v_lshlrev_b32_e32 v132, 16, v133
	v_add_f32_e32 v110, v110, v132
	v_and_b32_e32 v132, 0xffff0000, v133
	v_pk_add_f32 v[104:105], v[104:105], 0 op_sel_hi:[1,0]
	v_add_f32_e32 v111, v111, v132
	v_lshlrev_b32_e32 v132, 16, v134
	v_add_f32_e32 v132, v104, v132
	v_and_b32_e32 v104, 0xffff0000, v134
	v_pk_add_f32 v[106:107], v[106:107], 0 op_sel_hi:[1,0]
	v_add_f32_e32 v133, v105, v104
	v_lshlrev_b32_e32 v104, 16, v135
	v_add_f32_e32 v134, v106, v104
	v_and_b32_e32 v104, 0xffff0000, v135
	v_add_f32_e32 v108, v108, v155
	v_add_f32_e32 v107, v107, v104
	v_mul_f32_e32 v104, v109, v109
	v_mul_f32_e32 v105, v111, v111
	v_fmac_f32_e32 v104, v108, v108
	v_fmac_f32_e32 v105, v110, v110
	v_add_f32_e32 v104, v104, v105
	v_mul_f32_e32 v105, v133, v133
	v_fmac_f32_e32 v105, v132, v132
	v_add_f32_e32 v104, v105, v104
	v_mul_f32_e32 v105, v107, v107
	v_fmac_f32_e32 v105, v134, v134
	v_add_f32_e32 v135, v105, v104
	v_cvt_pk_bf16_f32 v104, v108, v109
	v_pk_add_f32 v[100:101], v[100:101], 0 op_sel_hi:[1,0]
	v_lshlrev_b32_e32 v108, 16, v128
	v_add_f32_e32 v100, v100, v108
	v_and_b32_e32 v108, 0xffff0000, v128
	v_pk_add_f32 v[102:103], v[102:103], 0 op_sel_hi:[1,0]
	v_add_f32_e32 v101, v101, v108
	v_lshlrev_b32_e32 v108, 16, v129
	v_add_f32_e32 v108, v102, v108
	v_and_b32_e32 v102, 0xffff0000, v129
	v_pk_add_f32 v[96:97], v[96:97], 0 op_sel_hi:[1,0]
	v_add_f32_e32 v109, v103, v102
	v_lshlrev_b32_e32 v102, 16, v130
	v_cvt_pk_bf16_f32 v105, v110, v111
	v_add_f32_e32 v110, v96, v102
	v_and_b32_e32 v96, 0xffff0000, v130
	v_pk_add_f32 v[98:99], v[98:99], 0 op_sel_hi:[1,0]
	v_add_f32_e32 v111, v97, v96
	v_lshlrev_b32_e32 v96, 16, v131
	v_add_f32_e32 v128, v98, v96
	v_and_b32_e32 v96, 0xffff0000, v131
	v_add_f32_e32 v129, v99, v96
	v_mul_f32_e32 v96, v101, v101
	v_mul_f32_e32 v97, v109, v109
	v_fmac_f32_e32 v96, v100, v100
	v_fmac_f32_e32 v97, v108, v108
	v_add_f32_e32 v96, v96, v97
	v_mul_f32_e32 v97, v111, v111
	v_fmac_f32_e32 v97, v110, v110
	v_add_f32_e32 v96, v97, v96
	v_mul_f32_e32 v97, v129, v129
	v_fmac_f32_e32 v97, v128, v128
	v_add_f32_e32 v96, v97, v96
	v_add_f32_e32 v99, v135, v96
	ds_bpermute_b32 v130, v171, v99
	s_waitcnt lgkmcnt(1)
	v_lshlrev_b64 v[174:175], 11, v[162:163]
	v_lshl_add_u64 v[96:97], v[174:175], 1, s[4:5]
	v_lshl_add_u64 v[102:103], v[152:153], 1, v[96:97]
	v_cvt_pk_bf16_f32 v106, v132, v133
	s_waitcnt lgkmcnt(0)
	v_add_f32_e32 v96, v99, v130
	ds_bpermute_b32 v97, v172, v96
	v_cvt_pk_bf16_f32 v107, v134, v107
	global_store_dwordx4 v[102:103], v[104:107], off sc0 sc1
	v_cvt_pk_bf16_f32 v98, v100, v101
	v_cvt_pk_bf16_f32 v99, v108, v109
	v_cvt_pk_bf16_f32 v100, v110, v111
	v_cvt_pk_bf16_f32 v101, v128, v129
	global_store_dwordx4 v[102:103], v[98:101], off offset:256 sc0 sc1
	s_and_saveexec_b64 s[26:27], s[8:9]
	s_cbranch_execz .LBB0_1073
	v_lshlrev_b64 v[98:99], 7, v[162:163]
	v_lshl_add_u64 v[98:99], s[24:25], 0, v[98:99]
	s_waitcnt lgkmcnt(0)
	v_add_f32_e32 v96, v96, v97
	global_store_dword v[98:99], v96, off
.LBB0_1073:
	s_or_b64 exec, exec, s[26:27]
	v_pk_add_f32 v[92:93], v[92:93], 0 op_sel_hi:[1,0]
	v_lshlrev_b32_e32 v98, 16, v124
	v_add_f32_e32 v92, v92, v98
	v_and_b32_e32 v98, 0xffff0000, v124
	v_pk_add_f32 v[94:95], v[94:95], 0 op_sel_hi:[1,0]
	v_add_f32_e32 v93, v93, v98
	v_lshlrev_b32_e32 v98, 16, v125
	v_add_f32_e32 v94, v94, v98
	v_and_b32_e32 v98, 0xffff0000, v125
	v_pk_add_f32 v[88:89], v[88:89], 0 op_sel_hi:[1,0]
	v_add_f32_e32 v95, v95, v98
	v_lshlrev_b32_e32 v98, 16, v126
	v_add_f32_e32 v98, v88, v98
	v_and_b32_e32 v88, 0xffff0000, v126
	v_pk_add_f32 v[90:91], v[90:91], 0 op_sel_hi:[1,0]
	v_add_f32_e32 v99, v89, v88
	v_lshlrev_b32_e32 v88, 16, v127
	v_add_f32_e32 v100, v90, v88
	v_and_b32_e32 v88, 0xffff0000, v127
	v_add_f32_e32 v91, v91, v88
	v_mul_f32_e32 v88, v93, v93
	v_mul_f32_e32 v89, v95, v95
	v_fmac_f32_e32 v88, v92, v92
	v_fmac_f32_e32 v89, v94, v94
	v_add_f32_e32 v88, v88, v89
	v_mul_f32_e32 v89, v99, v99
	v_fmac_f32_e32 v89, v98, v98
	v_add_f32_e32 v88, v89, v88
	v_mul_f32_e32 v89, v91, v91
	v_fmac_f32_e32 v89, v100, v100
	v_add_f32_e32 v101, v89, v88
	v_cvt_pk_bf16_f32 v88, v92, v93
	v_pk_add_f32 v[84:85], v[84:85], 0 op_sel_hi:[1,0]
	v_lshlrev_b32_e32 v92, 16, v120
	v_add_f32_e32 v84, v84, v92
	v_and_b32_e32 v92, 0xffff0000, v120
	v_pk_add_f32 v[86:87], v[86:87], 0 op_sel_hi:[1,0]
	v_add_f32_e32 v85, v85, v92
	v_lshlrev_b32_e32 v92, 16, v121
	v_add_f32_e32 v92, v86, v92
	v_and_b32_e32 v86, 0xffff0000, v121
	v_pk_add_f32 v[80:81], v[80:81], 0 op_sel_hi:[1,0]
	v_add_f32_e32 v93, v87, v86
	v_lshlrev_b32_e32 v86, 16, v122
	v_cvt_pk_bf16_f32 v89, v94, v95
	v_add_f32_e32 v94, v80, v86
	v_and_b32_e32 v80, 0xffff0000, v122
	v_pk_add_f32 v[82:83], v[82:83], 0 op_sel_hi:[1,0]
	v_add_f32_e32 v95, v81, v80
	v_lshlrev_b32_e32 v80, 16, v123
	v_cvt_pk_bf16_f32 v90, v98, v99
	v_add_f32_e32 v98, v82, v80
	v_and_b32_e32 v80, 0xffff0000, v123
	v_add_f32_e32 v99, v83, v80
	v_mul_f32_e32 v80, v85, v85
	v_mul_f32_e32 v81, v93, v93
	v_fmac_f32_e32 v80, v84, v84
	v_fmac_f32_e32 v81, v92, v92
	v_add_f32_e32 v80, v80, v81
	v_mul_f32_e32 v81, v95, v95
	v_fmac_f32_e32 v81, v94, v94
	v_add_f32_e32 v80, v81, v80
	v_mul_f32_e32 v81, v99, v99
	v_fmac_f32_e32 v81, v98, v98
	v_add_f32_e32 v80, v81, v80
	v_add_f32_e32 v83, v101, v80
	v_cvt_pk_bf16_f32 v91, v100, v91
	ds_bpermute_b32 v100, v171, v83
	s_waitcnt lgkmcnt(1)
	v_lshlrev_b64 v[96:97], 11, v[160:161]
	v_lshl_add_u64 v[80:81], v[96:97], 1, s[4:5]
	v_lshl_add_u64 v[86:87], v[152:153], 1, v[80:81]
	global_store_dwordx4 v[86:87], v[88:91], off sc0 sc1
	s_waitcnt lgkmcnt(0)
	v_add_f32_e32 v80, v83, v100
	ds_bpermute_b32 v81, v172, v80
	v_cvt_pk_bf16_f32 v82, v84, v85
	v_cvt_pk_bf16_f32 v83, v92, v93
	v_cvt_pk_bf16_f32 v84, v94, v95
	v_cvt_pk_bf16_f32 v85, v98, v99
	global_store_dwordx4 v[86:87], v[82:85], off offset:256 sc0 sc1
	s_and_saveexec_b64 s[26:27], s[8:9]
	s_cbranch_execz .LBB0_1075
	v_lshlrev_b64 v[82:83], 7, v[160:161]
	v_lshl_add_u64 v[82:83], s[24:25], 0, v[82:83]
	s_waitcnt lgkmcnt(0)
	v_add_f32_e32 v80, v80, v81
	global_store_dword v[82:83], v80, off
; __device__ __forceinline__ unsigned cvt_pk_bf16(float lo, float hi) { unsigned r; asm volatile("v_cvt_pk_bf16_f32 %0, %1, %2" : "=v"(r) : "v"(lo), "v"(hi)); return r; }
;     __device__ __forceinline__ void operator()(const f32x4 (&acc)[2][2][4][2], const Unit& u, int wr, int wc, int fr, int fq) const {
;         const int row0 = u.pm * BM + wr * 64 + fr, col0 = u.pn * BM + wc * 32 + 8 * fq;
;         f32x4 bv[2][2];
; #pragma unroll
;         for (int bj = 0; bj < 2; ++bj)
; #pragma unroll
;             for (int n = 0; n < 2; ++n) bv[bj][n] = bias ? *(const f32x4*)(bias + col0 + bj * HALF + 4 * n) : (f32x4){0.f, 0.f, 0.f, 0.f};
;         float* ssp = ssout + (size_t)(u.pn * 4 + wc);
; #pragma unroll
;         for (int ai = 0; ai < 2; ++ai) {
;             u32x4 old[4][2];
; #pragma unroll
;             for (int m = 0; m < 4; ++m)
; #pragma unroll
;                 for (int bj = 0; bj < 2; ++bj) old[m][bj] = *(const u32x4*)(HB + (size_t)(row0 + ai * HALF + m * 16) * ldc + col0 + bj * HALF);
; #pragma unroll
;             for (int m = 0; m < 4; ++m) { const int row = row0 + ai * HALF + m * 16; float ss = 0.f;
; #pragma unroll
;                 for (int bj = 0; bj < 2; ++bj) { const u32x4 ow = old[m][bj];
;                     f32x4 v0 = (acc[ai][bj][m][0] + bv[bj][0]) * accs, v1 = (acc[ai][bj][m][1] + bv[bj][1]) * accs;
;                     v0[0] += __uint_as_float(ow.x << 16); v0[1] += __uint_as_float(ow.x & 0xffff0000u); v0[2] += __uint_as_float(ow.y << 16); v0[3] += __uint_as_float(ow.y & 0xffff0000u);
;                     v1[0] += __uint_as_float(ow.z << 16); v1[1] += __uint_as_float(ow.z & 0xffff0000u); v1[2] += __uint_as_float(ow.w << 16); v1[3] += __uint_as_float(ow.w & 0xffff0000u);
;                     ss += (v0[0] * v0[0] + v0[1] * v0[1]) + (v0[2] * v0[2] + v0[3] * v0[3]) + (v1[0] * v1[0] + v1[1] * v1[1]) + (v1[2] * v1[2] + v1[3] * v1[3]);
;                     u32x4 w; w.x = cvt_pk_bf16(v0[0], v0[1]); w.y = cvt_pk_bf16(v0[2], v0[3]); w.z = cvt_pk_bf16(v1[0], v1[1]); w.w = cvt_pk_bf16(v1[2], v1[3]);
;                     *(u32x4*)(HB + (size_t)row * ldc + col0 + bj * HALF) = w; }
;                 ss += __shfl_xor(ss, 16); ss += __shfl_xor(ss, 32);
;                 if (fq == 0) ssp[(size_t)row * 32] = ss; }
.LBB0_1075:
	s_or_b64 exec, exec, s[26:27]
	v_pk_add_f32 v[76:77], v[76:77], 0 op_sel_hi:[1,0]
	v_lshlrev_b32_e32 v82, 16, v116
	v_add_f32_e32 v76, v76, v82
	v_and_b32_e32 v82, 0xffff0000, v116
	v_pk_add_f32 v[78:79], v[78:79], 0 op_sel_hi:[1,0]
	v_add_f32_e32 v77, v77, v82
	v_lshlrev_b32_e32 v82, 16, v117
	v_add_f32_e32 v78, v78, v82
	v_and_b32_e32 v82, 0xffff0000, v117
	v_pk_add_f32 v[72:73], v[72:73], 0 op_sel_hi:[1,0]
	v_add_f32_e32 v79, v79, v82
	v_lshlrev_b32_e32 v82, 16, v118
	v_add_f32_e32 v82, v72, v82
	v_and_b32_e32 v72, 0xffff0000, v118
	v_pk_add_f32 v[74:75], v[74:75], 0 op_sel_hi:[1,0]
	v_add_f32_e32 v83, v73, v72
	v_lshlrev_b32_e32 v72, 16, v119
	v_add_f32_e32 v84, v74, v72
	v_and_b32_e32 v72, 0xffff0000, v119
	v_add_f32_e32 v75, v75, v72
	v_mul_f32_e32 v72, v77, v77
	v_mul_f32_e32 v73, v79, v79
	v_fmac_f32_e32 v72, v76, v76
	v_fmac_f32_e32 v73, v78, v78
	v_add_f32_e32 v72, v72, v73
	v_mul_f32_e32 v73, v83, v83
	v_fmac_f32_e32 v73, v82, v82
	v_add_f32_e32 v72, v73, v72
	v_mul_f32_e32 v73, v75, v75
	v_fmac_f32_e32 v73, v84, v84
	v_add_f32_e32 v85, v73, v72
	v_cvt_pk_bf16_f32 v72, v76, v77
	v_pk_add_f32 v[68:69], v[68:69], 0 op_sel_hi:[1,0]
	v_lshlrev_b32_e32 v76, 16, v112
	v_add_f32_e32 v68, v68, v76
	v_and_b32_e32 v76, 0xffff0000, v112
	v_pk_add_f32 v[70:71], v[70:71], 0 op_sel_hi:[1,0]
	v_add_f32_e32 v69, v69, v76
	v_lshlrev_b32_e32 v76, 16, v113
	v_add_f32_e32 v76, v70, v76
	v_and_b32_e32 v70, 0xffff0000, v113
	v_pk_add_f32 v[64:65], v[64:65], 0 op_sel_hi:[1,0]
	v_add_f32_e32 v77, v71, v70
	v_lshlrev_b32_e32 v70, 16, v114
	v_cvt_pk_bf16_f32 v73, v78, v79
	v_add_f32_e32 v78, v64, v70
	v_and_b32_e32 v64, 0xffff0000, v114
	v_pk_add_f32 v[66:67], v[66:67], 0 op_sel_hi:[1,0]
	v_add_f32_e32 v79, v65, v64
	v_lshlrev_b32_e32 v64, 16, v115
	v_cvt_pk_bf16_f32 v74, v82, v83
	v_add_f32_e32 v82, v66, v64
	v_and_b32_e32 v64, 0xffff0000, v115
	v_add_f32_e32 v83, v67, v64
	v_mul_f32_e32 v64, v69, v69
	v_mul_f32_e32 v65, v77, v77
	v_fmac_f32_e32 v64, v68, v68
	v_fmac_f32_e32 v65, v76, v76
	v_add_f32_e32 v64, v64, v65
	v_mul_f32_e32 v65, v79, v79
	v_fmac_f32_e32 v65, v78, v78
	v_add_f32_e32 v64, v65, v64
	v_mul_f32_e32 v65, v83, v83
	v_fmac_f32_e32 v65, v82, v82
	v_add_f32_e32 v64, v65, v64
	v_add_f32_e32 v67, v85, v64
	v_cvt_pk_bf16_f32 v75, v84, v75
	ds_bpermute_b32 v84, v171, v67
	s_waitcnt lgkmcnt(1)
	v_lshlrev_b64 v[80:81], 11, v[158:159]
	v_lshl_add_u64 v[64:65], v[80:81], 1, s[4:5]
	v_lshl_add_u64 v[70:71], v[152:153], 1, v[64:65]
	global_store_dwordx4 v[70:71], v[72:75], off sc0 sc1
	s_waitcnt lgkmcnt(0)
	v_add_f32_e32 v64, v67, v84
	ds_bpermute_b32 v65, v172, v64
	v_cvt_pk_bf16_f32 v66, v68, v69
	v_cvt_pk_bf16_f32 v67, v76, v77
	v_cvt_pk_bf16_f32 v68, v78, v79
	v_cvt_pk_bf16_f32 v69, v82, v83
	global_store_dwordx4 v[70:71], v[66:69], off offset:256 sc0 sc1
	s_and_saveexec_b64 s[26:27], s[8:9]
	s_cbranch_execz .LBB0_1077
	v_lshlrev_b64 v[66:67], 7, v[158:159]
	v_lshl_add_u64 v[66:67], s[24:25], 0, v[66:67]
	s_waitcnt lgkmcnt(0)
	v_add_f32_e32 v64, v64, v65
	global_store_dword v[66:67], v64, off
.LBB0_1077:
	s_or_b64 exec, exec, s[26:27]
	v_add_u32_e32 v94, 0x80, v154
	v_ashrrev_i32_e32 v95, 31, v94
	v_lshlrev_b64 v[104:105], 12, v[94:95]
	s_waitcnt lgkmcnt(0)
	v_lshl_add_u64 v[64:65], v[156:157], 0, v[104:105]
	global_load_dwordx4 v[96:99], v[64:65], off
	global_load_dwordx4 v[100:103], v[64:65], off offset:256
	v_add_u32_e32 v92, 0x90, v154
	v_add_u32_e32 v90, 0xa0, v154
	v_add_u32_e32 v88, 0xb0, v154
	v_ashrrev_i32_e32 v93, 31, v92
	v_ashrrev_i32_e32 v91, 31, v90
	v_ashrrev_i32_e32 v89, 31, v88
	v_lshlrev_b64 v[64:65], 12, v[92:93]
	v_lshlrev_b64 v[66:67], 12, v[90:91]
	v_lshlrev_b64 v[68:69], 12, v[88:89]
	v_lshl_add_u64 v[64:65], v[156:157], 0, v[64:65]
	v_lshl_add_u64 v[66:67], v[156:157], 0, v[66:67]
	v_lshl_add_u64 v[106:107], v[156:157], 0, v[68:69]
	global_load_dwordx4 v[84:87], v[64:65], off
	global_load_dwordx4 v[80:83], v[64:65], off offset:256
	global_load_dwordx4 v[76:79], v[66:67], off
	global_load_dwordx4 v[72:75], v[66:67], off offset:256
	global_load_dwordx4 v[68:71], v[106:107], off
	s_nop 0
	global_load_dwordx4 v[64:67], v[106:107], off offset:256
	v_pk_add_f32 v[62:63], v[62:63], 0 op_sel_hi:[1,0]
	v_pk_add_f32 v[60:61], v[60:61], 0 op_sel_hi:[1,0]
	v_pk_add_f32 v[58:59], v[58:59], 0 op_sel_hi:[1,0]
	v_pk_add_f32 v[56:57], v[56:57], 0 op_sel_hi:[1,0]
	v_pk_add_f32 v[54:55], v[54:55], 0 op_sel_hi:[1,0]
	v_pk_add_f32 v[52:53], v[52:53], 0 op_sel_hi:[1,0]
	v_pk_add_f32 v[50:51], v[50:51], 0 op_sel_hi:[1,0]
	v_pk_add_f32 v[48:49], v[48:49], 0 op_sel_hi:[1,0]
	s_waitcnt vmcnt(7)
	v_lshlrev_b32_e32 v106, 16, v96
	v_and_b32_e32 v96, 0xffff0000, v96
	v_lshlrev_b32_e32 v107, 16, v97
	v_and_b32_e32 v97, 0xffff0000, v97
	v_lshlrev_b32_e32 v108, 16, v98
	v_and_b32_e32 v98, 0xffff0000, v98
	v_lshlrev_b32_e32 v109, 16, v99
	v_and_b32_e32 v99, 0xffff0000, v99
	s_waitcnt vmcnt(6)
	v_lshlrev_b32_e32 v110, 16, v100
	v_and_b32_e32 v100, 0xffff0000, v100
	v_lshlrev_b32_e32 v111, 16, v101
	v_and_b32_e32 v101, 0xffff0000, v101
	v_lshlrev_b32_e32 v112, 16, v102
	v_and_b32_e32 v102, 0xffff0000, v102
	v_lshlrev_b32_e32 v113, 16, v103
	v_and_b32_e32 v103, 0xffff0000, v103
	v_add_f32_e32 v61, v61, v96
	v_add_f32_e32 v63, v63, v97
	v_add_f32_e32 v57, v57, v98
	v_add_f32_e32 v59, v59, v99
	v_add_f32_e32 v97, v53, v100
	v_add_f32_e32 v99, v55, v101
	v_add_f32_e32 v60, v60, v106
	v_add_f32_e32 v62, v62, v107
	v_add_f32_e32 v56, v56, v108
	v_add_f32_e32 v58, v58, v109
	v_add_f32_e32 v96, v52, v110
	v_add_f32_e32 v98, v54, v111
	v_add_f32_e32 v100, v48, v112
	v_add_f32_e32 v101, v49, v102
	v_add_f32_e32 v102, v50, v113
	v_add_f32_e32 v103, v51, v103
	v_mul_f32_e32 v52, v61, v61
	v_mul_f32_e32 v53, v63, v63
	v_mul_f32_e32 v54, v57, v57
	v_mul_f32_e32 v55, v59, v59
	v_cvt_pk_bf16_f32 v48, v60, v61
	v_cvt_pk_bf16_f32 v49, v62, v63
	v_cvt_pk_bf16_f32 v50, v56, v57
	v_cvt_pk_bf16_f32 v51, v58, v59
	v_mul_f32_e32 v57, v97, v97
	v_mul_f32_e32 v59, v99, v99
	v_mul_f32_e32 v61, v101, v101
	v_fmac_f32_e32 v52, v60, v60
	v_fmac_f32_e32 v53, v62, v62
	v_fmac_f32_e32 v57, v96, v96
	v_fmac_f32_e32 v59, v98, v98
	v_mul_f32_e32 v63, v103, v103
	v_fmac_f32_e32 v54, v56, v56
	v_fmac_f32_e32 v61, v100, v100
	v_add_f32_e32 v52, v52, v53
	v_add_f32_e32 v53, v57, v59
	v_fmac_f32_e32 v55, v58, v58
	v_fmac_f32_e32 v63, v102, v102
	v_add_f32_e32 v52, v54, v52
	v_add_f32_e32 v53, v61, v53
	v_add_f32_e32 v52, v55, v52
	v_add_f32_e32 v53, v63, v53
	v_add_f32_e32 v56, v52, v53
	ds_bpermute_b32 v57, v171, v56
	v_lshl_add_u64 v[52:53], s[4:5], 0, v[104:105]
	v_lshl_add_u64 v[54:55], v[152:153], 1, v[52:53]
	global_store_dwordx4 v[54:55], v[48:51], off sc0 sc1
	s_waitcnt lgkmcnt(0)
	s_nop 0
	v_add_f32_e32 v48, v56, v57
	ds_bpermute_b32 v49, v172, v48
	v_cvt_pk_bf16_f32 v50, v96, v97
	v_cvt_pk_bf16_f32 v51, v98, v99
	v_cvt_pk_bf16_f32 v52, v100, v101
	v_cvt_pk_bf16_f32 v53, v102, v103
	global_store_dwordx4 v[54:55], v[50:53], off offset:256 sc0 sc1
	s_and_saveexec_b64 s[26:27], s[8:9]
	s_cbranch_execz .LBB0_1079
; __device__ __forceinline__ unsigned cvt_pk_bf16(float lo, float hi) { unsigned r; asm volatile("v_cvt_pk_bf16_f32 %0, %1, %2" : "=v"(r) : "v"(lo), "v"(hi)); return r; }
;     __device__ __forceinline__ void operator()(const f32x4 (&acc)[2][2][4][2], const Unit& u, int wr, int wc, int fr, int fq) const {
;     ...
;             for (int m = 0; m < 4; ++m) { const int row = row0 + ai * HALF + m * 16; float ss = 0.f;
; #pragma unroll
;                 for (int bj = 0; bj < 2; ++bj) { const u32x4 ow = old[m][bj];
;                     f32x4 v0 = (acc[ai][bj][m][0] + bv[bj][0]) * accs, v1 = (acc[ai][bj][m][1] + bv[bj][1]) * accs;
;                     v0[0] += __uint_as_float(ow.x << 16); v0[1] += __uint_as_float(ow.x & 0xffff0000u); v0[2] += __uint_as_float(ow.y << 16); v0[3] += __uint_as_float(ow.y & 0xffff0000u);
;                     v1[0] += __uint_as_float(ow.z << 16); v1[1] += __uint_as_float(ow.z & 0xffff0000u); v1[2] += __uint_as_float(ow.w << 16); v1[3] += __uint_as_float(ow.w & 0xffff0000u);
;                     ss += (v0[0] * v0[0] + v0[1] * v0[1]) + (v0[2] * v0[2] + v0[3] * v0[3]) + (v1[0] * v1[0] + v1[1] * v1[1]) + (v1[2] * v1[2] + v1[3] * v1[3]);
;                     u32x4 w; w.x = cvt_pk_bf16(v0[0], v0[1]); w.y = cvt_pk_bf16(v0[2], v0[3]); w.z = cvt_pk_bf16(v1[0], v1[1]); w.w = cvt_pk_bf16(v1[2], v1[3]);
;                     *(u32x4*)(HB + (size_t)row * ldc + col0 + bj * HALF) = w; }
;                 ss += __shfl_xor(ss, 16); ss += __shfl_xor(ss, 32);
;                 if (fq == 0) ssp[(size_t)row * 32] = ss; }
	v_lshlrev_b64 v[50:51], 7, v[94:95]
	v_lshl_add_u64 v[50:51], s[24:25], 0, v[50:51]
	s_waitcnt lgkmcnt(0)
	v_add_f32_e32 v48, v48, v49
	global_store_dword v[50:51], v48, off
.LBB0_1079:
	s_or_b64 exec, exec, s[26:27]
	v_pk_add_f32 v[44:45], v[44:45], 0 op_sel_hi:[1,0]
	s_waitcnt vmcnt(7)
	v_lshlrev_b32_e32 v50, 16, v84
	v_add_f32_e32 v44, v44, v50
	v_and_b32_e32 v50, 0xffff0000, v84
	v_pk_add_f32 v[46:47], v[46:47], 0 op_sel_hi:[1,0]
	v_add_f32_e32 v45, v45, v50
	v_lshlrev_b32_e32 v50, 16, v85
	v_add_f32_e32 v46, v46, v50
	v_and_b32_e32 v50, 0xffff0000, v85
	v_pk_add_f32 v[40:41], v[40:41], 0 op_sel_hi:[1,0]
	v_add_f32_e32 v47, v47, v50
	v_lshlrev_b32_e32 v50, 16, v86
	v_add_f32_e32 v50, v40, v50
	v_and_b32_e32 v40, 0xffff0000, v86
	v_pk_add_f32 v[42:43], v[42:43], 0 op_sel_hi:[1,0]
	v_add_f32_e32 v51, v41, v40
	v_lshlrev_b32_e32 v40, 16, v87
	v_add_f32_e32 v52, v42, v40
	v_and_b32_e32 v40, 0xffff0000, v87
	v_add_f32_e32 v43, v43, v40
	v_mul_f32_e32 v40, v45, v45
	v_mul_f32_e32 v41, v47, v47
	v_fmac_f32_e32 v40, v44, v44
	v_fmac_f32_e32 v41, v46, v46
	v_add_f32_e32 v40, v40, v41
	v_mul_f32_e32 v41, v51, v51
	v_fmac_f32_e32 v41, v50, v50
	v_add_f32_e32 v40, v41, v40
	v_mul_f32_e32 v41, v43, v43
	v_fmac_f32_e32 v41, v52, v52
	v_add_f32_e32 v53, v41, v40
	v_cvt_pk_bf16_f32 v40, v44, v45
	v_pk_add_f32 v[36:37], v[36:37], 0 op_sel_hi:[1,0]
	s_waitcnt vmcnt(6)
	v_lshlrev_b32_e32 v44, 16, v80
	v_add_f32_e32 v36, v36, v44
	v_and_b32_e32 v44, 0xffff0000, v80
	v_pk_add_f32 v[38:39], v[38:39], 0 op_sel_hi:[1,0]
	v_add_f32_e32 v37, v37, v44
	v_lshlrev_b32_e32 v44, 16, v81
	v_add_f32_e32 v44, v38, v44
	v_and_b32_e32 v38, 0xffff0000, v81
	v_pk_add_f32 v[32:33], v[32:33], 0 op_sel_hi:[1,0]
	v_add_f32_e32 v45, v39, v38
	v_lshlrev_b32_e32 v38, 16, v82
	v_cvt_pk_bf16_f32 v41, v46, v47
	v_add_f32_e32 v46, v32, v38
	v_and_b32_e32 v32, 0xffff0000, v82
	v_pk_add_f32 v[34:35], v[34:35], 0 op_sel_hi:[1,0]
	v_add_f32_e32 v47, v33, v32
	v_lshlrev_b32_e32 v32, 16, v83
	v_cvt_pk_bf16_f32 v42, v50, v51
	v_add_f32_e32 v50, v34, v32
	v_and_b32_e32 v32, 0xffff0000, v83
	v_add_f32_e32 v51, v35, v32
	v_mul_f32_e32 v32, v37, v37
	v_mul_f32_e32 v33, v45, v45
	v_fmac_f32_e32 v32, v36, v36
	v_fmac_f32_e32 v33, v44, v44
	v_add_f32_e32 v32, v32, v33
	v_mul_f32_e32 v33, v47, v47
	v_fmac_f32_e32 v33, v46, v46
	v_add_f32_e32 v32, v33, v32
	v_mul_f32_e32 v33, v51, v51
	v_fmac_f32_e32 v33, v50, v50
	v_add_f32_e32 v32, v33, v32
	v_add_f32_e32 v35, v53, v32
	v_cvt_pk_bf16_f32 v43, v52, v43
	ds_bpermute_b32 v52, v171, v35
	s_waitcnt lgkmcnt(1)
	v_lshlrev_b64 v[48:49], 11, v[92:93]
	v_lshl_add_u64 v[32:33], v[48:49], 1, s[4:5]
	v_lshl_add_u64 v[38:39], v[152:153], 1, v[32:33]
	global_store_dwordx4 v[38:39], v[40:43], off sc0 sc1
	s_waitcnt lgkmcnt(0)
	v_add_f32_e32 v32, v35, v52
	ds_bpermute_b32 v33, v172, v32
	v_cvt_pk_bf16_f32 v34, v36, v37
	v_cvt_pk_bf16_f32 v35, v44, v45
	v_cvt_pk_bf16_f32 v36, v46, v47
	v_cvt_pk_bf16_f32 v37, v50, v51
	global_store_dwordx4 v[38:39], v[34:37], off offset:256 sc0 sc1
	s_and_saveexec_b64 s[26:27], s[8:9]
	s_cbranch_execz .LBB0_1081
	v_lshlrev_b64 v[34:35], 7, v[92:93]
	v_lshl_add_u64 v[34:35], s[24:25], 0, v[34:35]
	s_waitcnt lgkmcnt(0)
	v_add_f32_e32 v32, v32, v33
	global_store_dword v[34:35], v32, off
; __device__ __forceinline__ unsigned cvt_pk_bf16(float lo, float hi) { unsigned r; asm volatile("v_cvt_pk_bf16_f32 %0, %1, %2" : "=v"(r) : "v"(lo), "v"(hi)); return r; }
;     __device__ __forceinline__ void operator()(const f32x4 (&acc)[2][2][4][2], const Unit& u, int wr, int wc, int fr, int fq) const {
;     ...
;             for (int m = 0; m < 4; ++m) { const int row = row0 + ai * HALF + m * 16; float ss = 0.f;
; #pragma unroll
;                 for (int bj = 0; bj < 2; ++bj) { const u32x4 ow = old[m][bj];
;                     f32x4 v0 = (acc[ai][bj][m][0] + bv[bj][0]) * accs, v1 = (acc[ai][bj][m][1] + bv[bj][1]) * accs;
;                     v0[0] += __uint_as_float(ow.x << 16); v0[1] += __uint_as_float(ow.x & 0xffff0000u); v0[2] += __uint_as_float(ow.y << 16); v0[3] += __uint_as_float(ow.y & 0xffff0000u);
;                     v1[0] += __uint_as_float(ow.z << 16); v1[1] += __uint_as_float(ow.z & 0xffff0000u); v1[2] += __uint_as_float(ow.w << 16); v1[3] += __uint_as_float(ow.w & 0xffff0000u);
;                     ss += (v0[0] * v0[0] + v0[1] * v0[1]) + (v0[2] * v0[2] + v0[3] * v0[3]) + (v1[0] * v1[0] + v1[1] * v1[1]) + (v1[2] * v1[2] + v1[3] * v1[3]);
;                     u32x4 w; w.x = cvt_pk_bf16(v0[0], v0[1]); w.y = cvt_pk_bf16(v0[2], v0[3]); w.z = cvt_pk_bf16(v1[0], v1[1]); w.w = cvt_pk_bf16(v1[2], v1[3]);
;                     *(u32x4*)(HB + (size_t)row * ldc + col0 + bj * HALF) = w; }
;                 ss += __shfl_xor(ss, 16); ss += __shfl_xor(ss, 32);
;                 if (fq == 0) ssp[(size_t)row * 32] = ss; }
.LBB0_1081:
	s_or_b64 exec, exec, s[26:27]
	v_pk_add_f32 v[28:29], v[28:29], 0 op_sel_hi:[1,0]
	s_waitcnt vmcnt(7)
	v_lshlrev_b32_e32 v34, 16, v76
	v_add_f32_e32 v28, v28, v34
	v_and_b32_e32 v34, 0xffff0000, v76
	v_pk_add_f32 v[30:31], v[30:31], 0 op_sel_hi:[1,0]
	v_add_f32_e32 v29, v29, v34
	v_lshlrev_b32_e32 v34, 16, v77
	v_add_f32_e32 v30, v30, v34
	v_and_b32_e32 v34, 0xffff0000, v77
	v_pk_add_f32 v[24:25], v[24:25], 0 op_sel_hi:[1,0]
	v_add_f32_e32 v31, v31, v34
	v_lshlrev_b32_e32 v34, 16, v78
	v_add_f32_e32 v34, v24, v34
	v_and_b32_e32 v24, 0xffff0000, v78
	v_pk_add_f32 v[26:27], v[26:27], 0 op_sel_hi:[1,0]
	v_add_f32_e32 v35, v25, v24
	v_lshlrev_b32_e32 v24, 16, v79
	v_add_f32_e32 v36, v26, v24
	v_and_b32_e32 v24, 0xffff0000, v79
	v_add_f32_e32 v27, v27, v24
	v_mul_f32_e32 v24, v29, v29
	v_mul_f32_e32 v25, v31, v31
	v_fmac_f32_e32 v24, v28, v28
	v_fmac_f32_e32 v25, v30, v30
	v_add_f32_e32 v24, v24, v25
	v_mul_f32_e32 v25, v35, v35
	v_fmac_f32_e32 v25, v34, v34
	v_add_f32_e32 v24, v25, v24
	v_mul_f32_e32 v25, v27, v27
	v_fmac_f32_e32 v25, v36, v36
	v_add_f32_e32 v37, v25, v24
	v_cvt_pk_bf16_f32 v24, v28, v29
	v_pk_add_f32 v[20:21], v[20:21], 0 op_sel_hi:[1,0]
	s_waitcnt vmcnt(6)
	v_lshlrev_b32_e32 v28, 16, v72
	v_add_f32_e32 v20, v20, v28
	v_and_b32_e32 v28, 0xffff0000, v72
	v_pk_add_f32 v[22:23], v[22:23], 0 op_sel_hi:[1,0]
	v_add_f32_e32 v21, v21, v28
	v_lshlrev_b32_e32 v28, 16, v73
	v_add_f32_e32 v28, v22, v28
	v_and_b32_e32 v22, 0xffff0000, v73
	v_pk_add_f32 v[16:17], v[16:17], 0 op_sel_hi:[1,0]
	v_add_f32_e32 v29, v23, v22
	v_lshlrev_b32_e32 v22, 16, v74
	v_cvt_pk_bf16_f32 v25, v30, v31
	v_add_f32_e32 v30, v16, v22
	v_and_b32_e32 v16, 0xffff0000, v74
	v_pk_add_f32 v[18:19], v[18:19], 0 op_sel_hi:[1,0]
	v_add_f32_e32 v31, v17, v16
	v_lshlrev_b32_e32 v16, 16, v75
	v_cvt_pk_bf16_f32 v26, v34, v35
	v_add_f32_e32 v34, v18, v16
	v_and_b32_e32 v16, 0xffff0000, v75
	v_add_f32_e32 v35, v19, v16
	v_mul_f32_e32 v16, v21, v21
	v_mul_f32_e32 v17, v29, v29
	v_fmac_f32_e32 v16, v20, v20
	v_fmac_f32_e32 v17, v28, v28
	v_add_f32_e32 v16, v16, v17
	v_mul_f32_e32 v17, v31, v31
	v_fmac_f32_e32 v17, v30, v30
	v_add_f32_e32 v16, v17, v16
	v_mul_f32_e32 v17, v35, v35
	v_fmac_f32_e32 v17, v34, v34
	v_add_f32_e32 v16, v17, v16
	v_add_f32_e32 v19, v37, v16
	v_cvt_pk_bf16_f32 v27, v36, v27
	ds_bpermute_b32 v36, v171, v19
	s_waitcnt lgkmcnt(1)
	v_lshlrev_b64 v[32:33], 11, v[90:91]
	v_lshl_add_u64 v[16:17], v[32:33], 1, s[4:5]
	v_lshl_add_u64 v[22:23], v[152:153], 1, v[16:17]
	global_store_dwordx4 v[22:23], v[24:27], off sc0 sc1
	s_waitcnt lgkmcnt(0)
	v_add_f32_e32 v16, v19, v36
	ds_bpermute_b32 v17, v172, v16
	v_cvt_pk_bf16_f32 v18, v20, v21
	v_cvt_pk_bf16_f32 v19, v28, v29
	v_cvt_pk_bf16_f32 v20, v30, v31
	v_cvt_pk_bf16_f32 v21, v34, v35
	global_store_dwordx4 v[22:23], v[18:21], off offset:256 sc0 sc1
	s_and_saveexec_b64 s[26:27], s[8:9]
	s_cbranch_execz .LBB0_1083
	v_lshlrev_b64 v[18:19], 7, v[90:91]
	v_lshl_add_u64 v[18:19], s[24:25], 0, v[18:19]
	s_waitcnt lgkmcnt(0)
	v_add_f32_e32 v16, v16, v17
	global_store_dword v[18:19], v16, off
.LBB0_1083:
	s_or_b64 exec, exec, s[26:27]
	v_pk_add_f32 v[12:13], v[12:13], 0 op_sel_hi:[1,0]
	s_waitcnt vmcnt(7)
	v_lshlrev_b32_e32 v18, 16, v68
	v_add_f32_e32 v12, v12, v18
	v_and_b32_e32 v18, 0xffff0000, v68
	v_pk_add_f32 v[14:15], v[14:15], 0 op_sel_hi:[1,0]
	v_add_f32_e32 v13, v13, v18
	v_lshlrev_b32_e32 v18, 16, v69
	v_add_f32_e32 v14, v14, v18
	v_and_b32_e32 v18, 0xffff0000, v69
	v_pk_add_f32 v[8:9], v[8:9], 0 op_sel_hi:[1,0]
	v_add_f32_e32 v15, v15, v18
	v_lshlrev_b32_e32 v18, 16, v70
	v_add_f32_e32 v18, v8, v18
	v_and_b32_e32 v8, 0xffff0000, v70
	v_pk_add_f32 v[10:11], v[10:11], 0 op_sel_hi:[1,0]
	v_add_f32_e32 v19, v9, v8
	v_lshlrev_b32_e32 v8, 16, v71
	v_add_f32_e32 v20, v10, v8
	v_and_b32_e32 v8, 0xffff0000, v71
	v_add_f32_e32 v11, v11, v8
	v_mul_f32_e32 v8, v13, v13
	v_mul_f32_e32 v9, v15, v15
	v_fmac_f32_e32 v8, v12, v12
	v_fmac_f32_e32 v9, v14, v14
	v_add_f32_e32 v8, v8, v9
	v_mul_f32_e32 v9, v19, v19
	v_fmac_f32_e32 v9, v18, v18
	v_add_f32_e32 v8, v9, v8
	v_mul_f32_e32 v9, v11, v11
	v_fmac_f32_e32 v9, v20, v20
	v_add_f32_e32 v21, v9, v8
	v_cvt_pk_bf16_f32 v8, v12, v13
	v_pk_add_f32 v[4:5], v[4:5], 0 op_sel_hi:[1,0]
	s_waitcnt vmcnt(6)
	v_lshlrev_b32_e32 v12, 16, v64
	v_add_f32_e32 v4, v4, v12
	v_and_b32_e32 v12, 0xffff0000, v64
	v_pk_add_f32 v[6:7], v[6:7], 0 op_sel_hi:[1,0]
	v_add_f32_e32 v5, v5, v12
	v_lshlrev_b32_e32 v12, 16, v65
	v_add_f32_e32 v12, v6, v12
	v_and_b32_e32 v6, 0xffff0000, v65
	v_pk_add_f32 v[0:1], v[0:1], 0 op_sel_hi:[1,0]
	v_add_f32_e32 v13, v7, v6
	v_lshlrev_b32_e32 v6, 16, v66
	v_cvt_pk_bf16_f32 v9, v14, v15
	v_add_f32_e32 v14, v0, v6
	v_and_b32_e32 v0, 0xffff0000, v66
	v_pk_add_f32 v[2:3], v[2:3], 0 op_sel_hi:[1,0]
	v_add_f32_e32 v15, v1, v0
	v_lshlrev_b32_e32 v0, 16, v67
	v_cvt_pk_bf16_f32 v10, v18, v19
	v_add_f32_e32 v18, v2, v0
	v_and_b32_e32 v0, 0xffff0000, v67
	v_add_f32_e32 v19, v3, v0
	v_mul_f32_e32 v0, v5, v5
	v_mul_f32_e32 v1, v13, v13
	v_fmac_f32_e32 v0, v4, v4
	v_fmac_f32_e32 v1, v12, v12
	v_add_f32_e32 v0, v0, v1
	v_mul_f32_e32 v1, v15, v15
	v_fmac_f32_e32 v1, v14, v14
	v_add_f32_e32 v0, v1, v0
	v_mul_f32_e32 v1, v19, v19
	v_fmac_f32_e32 v1, v18, v18
	v_add_f32_e32 v0, v1, v0
	v_add_f32_e32 v3, v21, v0
	v_cvt_pk_bf16_f32 v11, v20, v11
	ds_bpermute_b32 v20, v171, v3
	s_waitcnt lgkmcnt(1)
	v_lshlrev_b64 v[16:17], 11, v[88:89]
	v_lshl_add_u64 v[0:1], v[16:17], 1, s[4:5]
	v_lshl_add_u64 v[6:7], v[152:153], 1, v[0:1]
	global_store_dwordx4 v[6:7], v[8:11], off sc0 sc1
	s_waitcnt lgkmcnt(0)
	v_add_f32_e32 v0, v3, v20
	ds_bpermute_b32 v1, v172, v0
	v_cvt_pk_bf16_f32 v2, v4, v5
	v_cvt_pk_bf16_f32 v3, v12, v13
	v_cvt_pk_bf16_f32 v4, v14, v15
	v_cvt_pk_bf16_f32 v5, v18, v19
	global_store_dwordx4 v[6:7], v[2:5], off offset:256 sc0 sc1
	s_and_saveexec_b64 s[26:27], s[8:9]
	s_cbranch_execz .LBB0_1085
	v_lshlrev_b64 v[2:3], 7, v[88:89]
	v_lshl_add_u64 v[2:3], s[24:25], 0, v[2:3]
	s_waitcnt lgkmcnt(0)
	v_add_f32_e32 v0, v0, v1
	global_store_dword v[2:3], v0, off

; __device__ __forceinline__ unsigned cvt_pk_bf16(float lo, float hi) { unsigned r; asm volatile("v_cvt_pk_bf16_f32 %0, %1, %2" : "=v"(r) : "v"(lo), "v"(hi)); return r; }
; __device__ __forceinline__ float dpp_up1(float x) { return __builtin_bit_cast(float, __builtin_amdgcn_update_dpp(0, __builtin_bit_cast(int, x), 0x111, 0xf, 0xf, true)); }
;     __device__ __forceinline__ void operator()(const f32x4 (&acc)[2][2][4][2], const Unit& u, int wr, int wc, int fr, int fq) const {
;     ...
;                 f32x4 pg2, pg3, pv2, pv3;
; #pragma unroll
;                 for (int e = 0; e < 4; ++e) { pg2[e] = dpp_up1(xg[2][e]); pg3[e] = dpp_up1(xg[3][e]); pv2[e] = dpp_up1(xv[2][e]); pv3[e] = dpp_up1(xv[3][e]); }
; #pragma unroll
;                 for (int m = 0; m < 4; ++m) {
;                     u32x2_t w; float o[4];
; #pragma unroll
;                     for (int e = 0; e < 4; ++e) {
;                         const float g1 = m >= 1 ? xg[m - (m >= 1 ? 1 : 0)][e] : pg3[e], g2 = m >= 2 ? xg[m - (m >= 2 ? 2 : 0)][e] : (m == 1 ? pg3[e] : pg2[e]);
;                         const float v1 = m >= 1 ? xv[m - (m >= 1 ? 1 : 0)][e] : pv3[e], v2 = m >= 2 ? xv[m - (m >= 2 ? 2 : 0)][e] : (m == 1 ? pv3[e] : pv2[e]);
;                         const float cg_ = bg[e] + w0g[e] * g2 + w1g[e] * g1 + w2g[e] * xg[m][e];
;                         const float cv_ = bv[e] + w0v[e] * v2 + w1v[e] * v1 + w2v[e] * xv[m][e];
;                         o[e] = cg_ * __builtin_amdgcn_rcpf(1.0f + __expf(-cg_)) * cv_;
;                     }
;                     w.x = cvt_pk_bf16(o[0], o[1]); w.y = cvt_pk_bf16(o[2], o[3]);
;                     const int g = g0 + m;
;                     if (n == 0) stash[ai][m] = w;
;                     else if ((fr > 0 || m >= 2) && g < TT) { u32x4 ww; ww.x = stash[ai][m].x; ww.y = stash[ai][m].y; ww.z = w.x; ww.w = w.y; *(u32x4*)(G + (size_t)g * DFF_ + f0 - 4) = ww; }
.LBB0_1163:
	v_mov_b32_dpp v46, v58 row_shr:1 row_mask:0xf bank_mask:0xf bound_ctrl:1
	v_mov_b32_dpp v113, v44 row_shr:1 row_mask:0xf bank_mask:0xf bound_ctrl:1
	s_waitcnt vmcnt(4)
	v_fma_f32 v123, v94, v46, v70
	v_fmac_f32_e32 v123, v102, v113
	v_fmac_f32_e32 v123, v98, v76
	v_mul_f32_e32 v46, 0xbfb8aa3b, v123
	v_exp_f32_e32 v124, v46
	v_mov_b32_dpp v115, v59 row_shr:1 row_mask:0xf bank_mask:0xf bound_ctrl:1
	v_mov_b32_dpp v111, v45 row_shr:1 row_mask:0xf bank_mask:0xf bound_ctrl:1
	v_fma_f32 v115, v95, v115, v71
	v_fmac_f32_e32 v115, v103, v111
	v_add_f32_e32 v124, 1.0, v124
	v_fmac_f32_e32 v115, v99, v77
	v_rcp_f32_e32 v124, v124
	v_mul_f32_e32 v125, 0xbfb8aa3b, v115
	v_mov_b32_dpp v114, v52 row_shr:1 row_mask:0xf bank_mask:0xf bound_ctrl:1
	v_exp_f32_e32 v125, v125
	v_mov_b32_dpp v112, v38 row_shr:1 row_mask:0xf bank_mask:0xf bound_ctrl:1
	s_waitcnt vmcnt(0)
	v_fma_f32 v114, v78, v114, v90
	v_fmac_f32_e32 v114, v82, v112
	v_fmac_f32_e32 v114, v86, v68
	v_mul_f32_e32 v123, v123, v124
	v_mul_f32_e32 v114, v114, v123
	v_add_f32_e32 v123, 1.0, v125
	v_mov_b32_dpp v117, v42 row_shr:1 row_mask:0xf bank_mask:0xf bound_ctrl:1
	v_rcp_f32_e32 v123, v123
	v_mov_b32_dpp v55, v32 row_shr:1 row_mask:0xf bank_mask:0xf bound_ctrl:1
	v_fma_f32 v117, v96, v117, v72
	v_fmac_f32_e32 v117, v104, v55
	v_fmac_f32_e32 v117, v100, v62
	v_mul_f32_e32 v115, v115, v123
	v_mul_f32_e32 v123, 0xbfb8aa3b, v117
	v_mov_b32_dpp v116, v53 row_shr:1 row_mask:0xf bank_mask:0xf bound_ctrl:1
	v_exp_f32_e32 v123, v123
	v_mov_b32_dpp v110, v39 row_shr:1 row_mask:0xf bank_mask:0xf bound_ctrl:1
	v_mov_b32_dpp v121, v43 row_shr:1 row_mask:0xf bank_mask:0xf bound_ctrl:1
	v_fma_f32 v116, v79, v116, v91
	v_mov_b32_dpp v47, v33 row_shr:1 row_mask:0xf bank_mask:0xf bound_ctrl:1
	v_fmac_f32_e32 v116, v83, v110
	v_fma_f32 v121, v97, v121, v73
	v_mov_b32_dpp v120, v36 row_shr:1 row_mask:0xf bank_mask:0xf bound_ctrl:1
	v_fmac_f32_e32 v116, v87, v69
	v_fmac_f32_e32 v121, v105, v47
	v_mul_f32_e32 v115, v116, v115
	v_fma_f32 v116, v80, v120, v92
	v_add_f32_e32 v120, 1.0, v123
	v_fmac_f32_e32 v121, v101, v63
	v_rcp_f32_e32 v120, v120
	v_mul_f32_e32 v123, 0xbfb8aa3b, v121
	v_exp_f32_e32 v123, v123
	v_mov_b32_dpp v54, v34 row_shr:1 row_mask:0xf bank_mask:0xf bound_ctrl:1
	v_fmac_f32_e32 v116, v84, v54
	v_fmac_f32_e32 v116, v88, v60
	v_mul_f32_e32 v117, v117, v120
	v_mul_f32_e32 v116, v116, v117
	v_add_f32_e32 v117, 1.0, v123
	v_rcp_f32_e32 v117, v117
	v_mov_b32_dpp v122, v37 row_shr:1 row_mask:0xf bank_mask:0xf bound_ctrl:1
	v_mov_b32_dpp v46, v35 row_shr:1 row_mask:0xf bank_mask:0xf bound_ctrl:1
	v_fma_f32 v120, v81, v122, v93
	v_fmac_f32_e32 v120, v85, v46
	v_cmp_gt_i32_e32 vcc, s64, v218
	v_fmac_f32_e32 v120, v89, v61
	v_mul_f32_e32 v117, v121, v117
	s_and_b64 s[6:7], s[10:11], vcc
	v_mul_f32_e32 v117, v120, v117
	v_cvt_pk_bf16_f32 v144, v114, v115
	v_cvt_pk_bf16_f32 v145, v116, v117
	s_and_saveexec_b64 s[16:17], s[6:7]
	s_cbranch_execz .LBB0_1165
	v_mov_b64_e32 v[114:115], s[4:5]
	v_mad_i64_i32 v[114:115], s[6:7], v218, s80, v[114:115]
	v_lshl_add_u64 v[114:115], v[182:183], 1, v[114:115]
	global_store_dwordx4 v[114:115], v[142:145], off sc0 sc1
.LBB0_1165:
	s_or_b64 exec, exec, s[16:17]
	v_fma_f32 v113, v94, v113, v70
	v_fmac_f32_e32 v113, v102, v76
	v_fmac_f32_e32 v113, v98, v56
	v_mul_f32_e32 v114, 0xbfb8aa3b, v113
	v_exp_f32_e32 v114, v114
	v_fma_f32 v111, v95, v111, v71
	v_fmac_f32_e32 v111, v103, v77
	v_fmac_f32_e32 v111, v99, v57
	v_add_f32_e32 v114, 1.0, v114
	v_rcp_f32_e32 v114, v114
	v_mul_f32_e32 v115, 0xbfb8aa3b, v111
	v_exp_f32_e32 v115, v115
	v_fma_f32 v112, v78, v112, v90
	v_fmac_f32_e32 v112, v82, v68
	v_fmac_f32_e32 v112, v86, v50
	v_mul_f32_e32 v113, v113, v114
	v_mul_f32_e32 v112, v112, v113
	v_add_f32_e32 v113, 1.0, v115
	v_rcp_f32_e32 v113, v113
	v_fma_f32 v55, v96, v55, v72
	v_fmac_f32_e32 v55, v104, v62
	v_fmac_f32_e32 v55, v100, v48
	v_mul_f32_e32 v111, v111, v113
	v_mul_f32_e32 v113, 0xbfb8aa3b, v55
	v_exp_f32_e32 v113, v113
	v_fma_f32 v110, v79, v110, v91
	v_fmac_f32_e32 v110, v83, v69
	v_fma_f32 v47, v97, v47, v73
	v_fmac_f32_e32 v110, v87, v51
	v_fmac_f32_e32 v47, v105, v63
	v_mul_f32_e32 v110, v110, v111
	v_add_f32_e32 v111, 1.0, v113
	v_fmac_f32_e32 v47, v101, v49
	v_rcp_f32_e32 v111, v111
	v_mul_f32_e32 v113, 0xbfb8aa3b, v47
	v_exp_f32_e32 v113, v113
	v_fma_f32 v54, v80, v54, v92
	v_fmac_f32_e32 v54, v84, v60
	v_fmac_f32_e32 v54, v88, v40
	v_mul_f32_e32 v55, v55, v111
	v_mul_f32_e32 v54, v54, v55
	v_add_f32_e32 v55, 1.0, v113
	v_rcp_f32_e32 v55, v55
	v_fma_f32 v46, v81, v46, v93
	v_fmac_f32_e32 v46, v85, v61
	v_cmp_gt_i32_e32 vcc, s64, v221
	v_fmac_f32_e32 v46, v89, v41
	v_mul_f32_e32 v47, v47, v55
	s_and_b64 s[6:7], s[10:11], vcc
	v_mul_f32_e32 v46, v46, v47
	v_cvt_pk_bf16_f32 v142, v112, v110
	v_cvt_pk_bf16_f32 v143, v54, v46
	s_and_saveexec_b64 s[16:17], s[6:7]
	s_cbranch_execz .LBB0_1167
	v_mov_b64_e32 v[46:47], s[4:5]
	v_mad_i64_i32 v[46:47], s[6:7], v221, s80, v[46:47]
	v_lshl_add_u64 v[46:47], v[182:183], 1, v[46:47]
	global_store_dwordx4 v[46:47], v[140:143], off sc0 sc1
; __device__ __forceinline__ unsigned cvt_pk_bf16(float lo, float hi) { unsigned r; asm volatile("v_cvt_pk_bf16_f32 %0, %1, %2" : "=v"(r) : "v"(lo), "v"(hi)); return r; }
;     __device__ __forceinline__ void operator()(const f32x4 (&acc)[2][2][4][2], const Unit& u, int wr, int wc, int fr, int fq) const {
;     ...
;                 for (int m = 0; m < 4; ++m) {
;                     u32x2_t w; float o[4];
; #pragma unroll
;                     for (int e = 0; e < 4; ++e) {
;                         const float g1 = m >= 1 ? xg[m - (m >= 1 ? 1 : 0)][e] : pg3[e], g2 = m >= 2 ? xg[m - (m >= 2 ? 2 : 0)][e] : (m == 1 ? pg3[e] : pg2[e]);
;                         const float v1 = m >= 1 ? xv[m - (m >= 1 ? 1 : 0)][e] : pv3[e], v2 = m >= 2 ? xv[m - (m >= 2 ? 2 : 0)][e] : (m == 1 ? pv3[e] : pv2[e]);
;                         const float cg_ = bg[e] + w0g[e] * g2 + w1g[e] * g1 + w2g[e] * xg[m][e];
;                         const float cv_ = bv[e] + w0v[e] * v2 + w1v[e] * v1 + w2v[e] * xv[m][e];
;                         o[e] = cg_ * __builtin_amdgcn_rcpf(1.0f + __expf(-cg_)) * cv_;
;                     }
;                     w.x = cvt_pk_bf16(o[0], o[1]); w.y = cvt_pk_bf16(o[2], o[3]);
;                     const int g = g0 + m;
;                     if (n == 0) stash[ai][m] = w;
;                     else if ((fr > 0 || m >= 2) && g < TT) { u32x4 ww; ww.x = stash[ai][m].x; ww.y = stash[ai][m].y; ww.z = w.x; ww.w = w.y; *(u32x4*)(G + (size_t)g * DFF_ + f0 - 4) = ww; }
.LBB0_1167:
	s_or_b64 exec, exec, s[16:17]
	v_fma_f32 v46, v94, v76, v70
	v_fmac_f32_e32 v46, v102, v56
	v_fmac_f32_e32 v46, v98, v58
	v_mul_f32_e32 v47, 0xbfb8aa3b, v46
	v_exp_f32_e32 v47, v47
	v_fma_f32 v55, v95, v77, v71
	v_fmac_f32_e32 v55, v103, v57
	v_fmac_f32_e32 v55, v99, v59
	v_fma_f32 v54, v78, v68, v90
	v_add_f32_e32 v47, 1.0, v47
	v_mul_f32_e32 v68, 0xbfb8aa3b, v55
	v_rcp_f32_e32 v47, v47
	v_exp_f32_e32 v68, v68
	v_fmac_f32_e32 v54, v82, v50
	v_fmac_f32_e32 v54, v86, v52
	v_mul_f32_e32 v46, v46, v47
	v_add_f32_e32 v47, 1.0, v68
	v_rcp_f32_e32 v47, v47
	v_mul_f32_e32 v46, v54, v46
	v_fma_f32 v54, v79, v69, v91
	v_fmac_f32_e32 v54, v83, v51
	v_mul_f32_e32 v47, v55, v47
	v_fma_f32 v55, v96, v62, v72
	v_fmac_f32_e32 v55, v104, v48
	v_fmac_f32_e32 v55, v100, v42
	v_mul_f32_e32 v62, 0xbfb8aa3b, v55
	v_exp_f32_e32 v62, v62
	v_fmac_f32_e32 v54, v87, v53
	v_mul_f32_e32 v47, v54, v47
	v_fma_f32 v54, v80, v60, v92
	v_add_f32_e32 v60, 1.0, v62
	v_fma_f32 v62, v97, v63, v73
	v_fmac_f32_e32 v62, v105, v49
	v_fmac_f32_e32 v62, v101, v43
	v_rcp_f32_e32 v60, v60
	v_mul_f32_e32 v63, 0xbfb8aa3b, v62
	v_exp_f32_e32 v63, v63
	v_fmac_f32_e32 v54, v84, v40
	v_fmac_f32_e32 v54, v88, v36
	v_mul_f32_e32 v55, v55, v60
	v_mul_f32_e32 v54, v54, v55
	v_add_f32_e32 v55, 1.0, v63
	v_rcp_f32_e32 v55, v55
	v_fma_f32 v60, v81, v61, v93
	v_fmac_f32_e32 v60, v85, v41
	v_fmac_f32_e32 v60, v89, v37
	v_mul_f32_e32 v55, v62, v55
	v_cmp_gt_i32_e32 vcc, s81, v218
	v_mul_f32_e32 v55, v60, v55
	v_cvt_pk_bf16_f32 v120, v46, v47
	v_cvt_pk_bf16_f32 v121, v54, v55
	s_and_saveexec_b64 s[16:17], vcc
	s_cbranch_execz .LBB0_1169
	v_mov_b64_e32 v[46:47], s[4:5]
	v_mad_i64_i32 v[46:47], s[6:7], v220, s80, v[46:47]
	v_lshl_add_u64 v[46:47], v[182:183], 1, v[46:47]
	global_store_dwordx4 v[46:47], v[118:121], off sc0 sc1
.LBB0_1169:
	s_or_b64 exec, exec, s[16:17]
	v_fma_f32 v46, v94, v56, v70
	v_fmac_f32_e32 v46, v102, v58
	v_fmac_f32_e32 v46, v98, v44
	v_mul_f32_e32 v44, 0xbfb8aa3b, v46
	v_exp_f32_e32 v44, v44
	v_fma_f32 v47, v78, v50, v90
	v_fma_f32 v50, v95, v57, v71
	v_fmac_f32_e32 v50, v103, v59
	v_fmac_f32_e32 v50, v99, v45
	v_add_f32_e32 v44, 1.0, v44
	v_mul_f32_e32 v45, 0xbfb8aa3b, v50
	v_rcp_f32_e32 v44, v44
	v_exp_f32_e32 v45, v45
	v_fmac_f32_e32 v47, v82, v52
	v_fmac_f32_e32 v47, v86, v38
	v_mul_f32_e32 v38, v46, v44
	v_add_f32_e32 v44, 1.0, v45
	v_rcp_f32_e32 v44, v44
	v_fma_f32 v45, v79, v51, v91
	v_fmac_f32_e32 v45, v83, v53
	v_fma_f32 v40, v80, v40, v92
	v_fmac_f32_e32 v45, v87, v39
	v_mul_f32_e32 v39, v50, v44
	v_fma_f32 v44, v96, v48, v72
	v_fmac_f32_e32 v40, v84, v36
	v_fma_f32 v36, v97, v49, v73
	v_fmac_f32_e32 v44, v104, v42
	v_fmac_f32_e32 v36, v105, v43
	v_fmac_f32_e32 v44, v100, v32
	v_fmac_f32_e32 v36, v101, v33
	v_mul_f32_e32 v32, 0xbfb8aa3b, v44
	v_mul_f32_e32 v33, 0xbfb8aa3b, v36
	v_exp_f32_e32 v32, v32
	v_exp_f32_e32 v33, v33
	v_fmac_f32_e32 v40, v88, v34
	v_fma_f32 v34, v81, v41, v93
	v_add_f32_e32 v32, 1.0, v32
	v_add_f32_e32 v33, 1.0, v33
	v_rcp_f32_e32 v32, v32
	v_rcp_f32_e32 v33, v33
	v_fmac_f32_e32 v34, v85, v37
	v_fmac_f32_e32 v34, v89, v35
	v_mul_f32_e32 v32, v44, v32
	v_mul_f32_e32 v33, v36, v33
	v_cmp_gt_i32_e32 vcc, s82, v218
	v_mul_f32_e32 v38, v47, v38
	v_mul_f32_e32 v39, v45, v39
	v_mul_f32_e32 v32, v40, v32
	v_mul_f32_e32 v33, v34, v33
	v_cvt_pk_bf16_f32 v110, v38, v39
	v_cvt_pk_bf16_f32 v111, v32, v33
	s_and_saveexec_b64 s[16:17], vcc
	s_cbranch_execz .LBB0_1171
	v_mov_b64_e32 v[32:33], s[4:5]
	v_mad_i64_i32 v[32:33], s[6:7], v219, s80, v[32:33]
	v_lshl_add_u64 v[32:33], v[182:183], 1, v[32:33]
	global_store_dwordx4 v[32:33], v[108:111], off sc0 sc1

; __device__ __forceinline__ unsigned cvt_pk_bf16(float lo, float hi) { unsigned r; asm volatile("v_cvt_pk_bf16_f32 %0, %1, %2" : "=v"(r) : "v"(lo), "v"(hi)); return r; }
; __device__ __forceinline__ float dpp_up1(float x) { return __builtin_bit_cast(float, __builtin_amdgcn_update_dpp(0, __builtin_bit_cast(int, x), 0x111, 0xf, 0xf, true)); }
;     __device__ __forceinline__ void operator()(const f32x4 (&acc)[2][2][4][2], const Unit& u, int wr, int wc, int fr, int fq) const {
;     ...
;                 f32x4 pg2, pg3, pv2, pv3;
; #pragma unroll
;                 for (int e = 0; e < 4; ++e) { pg2[e] = dpp_up1(xg[2][e]); pg3[e] = dpp_up1(xg[3][e]); pv2[e] = dpp_up1(xv[2][e]); pv3[e] = dpp_up1(xv[3][e]); }
; #pragma unroll
;                 for (int m = 0; m < 4; ++m) {
;                     u32x2_t w; float o[4];
; #pragma unroll
;                     for (int e = 0; e < 4; ++e) {
;                         const float g1 = m >= 1 ? xg[m - (m >= 1 ? 1 : 0)][e] : pg3[e], g2 = m >= 2 ? xg[m - (m >= 2 ? 2 : 0)][e] : (m == 1 ? pg3[e] : pg2[e]);
;                         const float v1 = m >= 1 ? xv[m - (m >= 1 ? 1 : 0)][e] : pv3[e], v2 = m >= 2 ? xv[m - (m >= 2 ? 2 : 0)][e] : (m == 1 ? pv3[e] : pv2[e]);
;                         const float cg_ = bg[e] + w0g[e] * g2 + w1g[e] * g1 + w2g[e] * xg[m][e];
;                         const float cv_ = bv[e] + w0v[e] * v2 + w1v[e] * v1 + w2v[e] * xv[m][e];
;                         o[e] = cg_ * __builtin_amdgcn_rcpf(1.0f + __expf(-cg_)) * cv_;
;                     }
;                     w.x = cvt_pk_bf16(o[0], o[1]); w.y = cvt_pk_bf16(o[2], o[3]);
;                     const int g = g0 + m;
;                     if (n == 0) stash[ai][m] = w;
;                     else if ((fr > 0 || m >= 2) && g < TT) { u32x4 ww; ww.x = stash[ai][m].x; ww.y = stash[ai][m].y; ww.z = w.x; ww.w = w.y; *(u32x4*)(G + (size_t)g * DFF_ + f0 - 4) = ww; }
.LBB0_1173:
	v_mov_b32_dpp v14, v26 row_shr:1 row_mask:0xf bank_mask:0xf bound_ctrl:1
	v_mov_b32_dpp v39, v12 row_shr:1 row_mask:0xf bank_mask:0xf bound_ctrl:1
	v_fma_f32 v47, v94, v14, v70
	v_fmac_f32_e32 v47, v102, v39
	v_fmac_f32_e32 v47, v98, v34
	v_mul_f32_e32 v14, 0xbfb8aa3b, v47
	v_exp_f32_e32 v48, v14
	v_mov_b32_dpp v41, v27 row_shr:1 row_mask:0xf bank_mask:0xf bound_ctrl:1
	v_mov_b32_dpp v37, v13 row_shr:1 row_mask:0xf bank_mask:0xf bound_ctrl:1
	v_fma_f32 v41, v95, v41, v71
	v_fmac_f32_e32 v41, v103, v37
	v_add_f32_e32 v48, 1.0, v48
	v_fmac_f32_e32 v41, v99, v35
	v_rcp_f32_e32 v48, v48
	v_mul_f32_e32 v49, 0xbfb8aa3b, v41
	v_mov_b32_dpp v40, v20 row_shr:1 row_mask:0xf bank_mask:0xf bound_ctrl:1
	v_exp_f32_e32 v49, v49
	v_mov_b32_dpp v38, v6 row_shr:1 row_mask:0xf bank_mask:0xf bound_ctrl:1
	v_fma_f32 v40, v78, v40, v90
	v_fmac_f32_e32 v40, v82, v38
	v_fmac_f32_e32 v40, v86, v32
	v_mul_f32_e32 v47, v47, v48
	v_mul_f32_e32 v40, v40, v47
	v_add_f32_e32 v47, 1.0, v49
	v_mov_b32_dpp v43, v10 row_shr:1 row_mask:0xf bank_mask:0xf bound_ctrl:1
	v_rcp_f32_e32 v47, v47
	v_mov_b32_dpp v23, v0 row_shr:1 row_mask:0xf bank_mask:0xf bound_ctrl:1
	v_fma_f32 v43, v96, v43, v72
	v_fmac_f32_e32 v43, v104, v23
	v_fmac_f32_e32 v43, v100, v30
	v_mul_f32_e32 v41, v41, v47
	v_mul_f32_e32 v47, 0xbfb8aa3b, v43
	v_mov_b32_dpp v42, v21 row_shr:1 row_mask:0xf bank_mask:0xf bound_ctrl:1
	v_exp_f32_e32 v47, v47
	v_mov_b32_dpp v36, v7 row_shr:1 row_mask:0xf bank_mask:0xf bound_ctrl:1
	v_mov_b32_dpp v45, v11 row_shr:1 row_mask:0xf bank_mask:0xf bound_ctrl:1
	v_fma_f32 v42, v79, v42, v91
	v_mov_b32_dpp v15, v1 row_shr:1 row_mask:0xf bank_mask:0xf bound_ctrl:1
	v_fmac_f32_e32 v42, v83, v36
	v_fma_f32 v45, v97, v45, v73
	v_mov_b32_dpp v44, v4 row_shr:1 row_mask:0xf bank_mask:0xf bound_ctrl:1
	v_fmac_f32_e32 v42, v87, v33
	v_fmac_f32_e32 v45, v105, v15
	v_mul_f32_e32 v41, v42, v41
	v_fma_f32 v42, v80, v44, v92
	v_add_f32_e32 v44, 1.0, v47
	v_fmac_f32_e32 v45, v101, v31
	v_rcp_f32_e32 v44, v44
	v_mul_f32_e32 v47, 0xbfb8aa3b, v45
	v_exp_f32_e32 v47, v47
	v_mov_b32_dpp v22, v2 row_shr:1 row_mask:0xf bank_mask:0xf bound_ctrl:1
	v_fmac_f32_e32 v42, v84, v22
	v_fmac_f32_e32 v42, v88, v28
	v_mul_f32_e32 v43, v43, v44
	v_mul_f32_e32 v42, v42, v43
	v_add_f32_e32 v43, 1.0, v47
	v_rcp_f32_e32 v43, v43
	v_mov_b32_dpp v46, v5 row_shr:1 row_mask:0xf bank_mask:0xf bound_ctrl:1
	v_mov_b32_dpp v14, v3 row_shr:1 row_mask:0xf bank_mask:0xf bound_ctrl:1
	v_fma_f32 v44, v81, v46, v93
	v_fmac_f32_e32 v44, v85, v14
	v_cmp_gt_i32_e32 vcc, s64, v214
	v_fmac_f32_e32 v44, v89, v29
	v_mul_f32_e32 v43, v45, v43
	s_and_b64 s[6:7], s[10:11], vcc
	v_mul_f32_e32 v43, v44, v43
	v_cvt_pk_bf16_f32 v108, v40, v41
	v_cvt_pk_bf16_f32 v109, v42, v43
	s_and_saveexec_b64 s[14:15], s[6:7]
	s_cbranch_execz .LBB0_1175
	v_mov_b64_e32 v[40:41], s[4:5]
	v_mad_i64_i32 v[40:41], s[6:7], v214, s80, v[40:41]
	v_lshl_add_u64 v[40:41], v[182:183], 1, v[40:41]
	global_store_dwordx4 v[40:41], v[106:109], off sc0 sc1
.LBB0_1175:
	s_or_b64 exec, exec, s[14:15]
	v_fma_f32 v39, v94, v39, v70
	v_fmac_f32_e32 v39, v102, v34
	v_fmac_f32_e32 v39, v98, v24
	v_mul_f32_e32 v40, 0xbfb8aa3b, v39
	v_exp_f32_e32 v40, v40
	v_fma_f32 v37, v95, v37, v71
	v_fmac_f32_e32 v37, v103, v35
	v_fmac_f32_e32 v37, v99, v25
	v_add_f32_e32 v40, 1.0, v40
	v_rcp_f32_e32 v40, v40
	v_mul_f32_e32 v41, 0xbfb8aa3b, v37
	v_exp_f32_e32 v41, v41
	v_fma_f32 v38, v78, v38, v90
	v_fmac_f32_e32 v38, v82, v32
	v_fmac_f32_e32 v38, v86, v18
	v_mul_f32_e32 v39, v39, v40
	v_mul_f32_e32 v38, v38, v39
	v_add_f32_e32 v39, 1.0, v41
	v_rcp_f32_e32 v39, v39
	v_fma_f32 v23, v96, v23, v72
	v_fmac_f32_e32 v23, v104, v30
	v_fmac_f32_e32 v23, v100, v16
	v_mul_f32_e32 v37, v37, v39
	v_mul_f32_e32 v39, 0xbfb8aa3b, v23
	v_exp_f32_e32 v39, v39
	v_fma_f32 v36, v79, v36, v91
	v_fmac_f32_e32 v36, v83, v33
	v_fma_f32 v15, v97, v15, v73
	v_fmac_f32_e32 v36, v87, v19
	v_fmac_f32_e32 v15, v105, v31
	v_mul_f32_e32 v36, v36, v37
	v_add_f32_e32 v37, 1.0, v39
	v_fmac_f32_e32 v15, v101, v17
	v_rcp_f32_e32 v37, v37
	v_mul_f32_e32 v39, 0xbfb8aa3b, v15
	v_exp_f32_e32 v39, v39
	v_fma_f32 v22, v80, v22, v92
	v_fmac_f32_e32 v22, v84, v28
	v_fmac_f32_e32 v22, v88, v8
	v_mul_f32_e32 v23, v23, v37
	v_mul_f32_e32 v22, v22, v23
	v_add_f32_e32 v23, 1.0, v39
	v_rcp_f32_e32 v23, v23
	v_fma_f32 v14, v81, v14, v93
	v_fmac_f32_e32 v14, v85, v29
	v_cmp_gt_i32_e32 vcc, s64, v217
	v_fmac_f32_e32 v14, v89, v9
	v_mul_f32_e32 v15, v15, v23
	s_and_b64 s[6:7], s[10:11], vcc
	v_mul_f32_e32 v14, v14, v15
	v_cvt_pk_bf16_f32 v76, v38, v36
	v_cvt_pk_bf16_f32 v77, v22, v14
	s_and_saveexec_b64 s[14:15], s[6:7]
	s_cbranch_execz .LBB0_1177
	v_mov_b64_e32 v[14:15], s[4:5]
	v_mad_i64_i32 v[14:15], s[6:7], v217, s80, v[14:15]
	v_lshl_add_u64 v[14:15], v[182:183], 1, v[14:15]
	global_store_dwordx4 v[14:15], v[74:77], off sc0 sc1
; __device__ __forceinline__ unsigned cvt_pk_bf16(float lo, float hi) { unsigned r; asm volatile("v_cvt_pk_bf16_f32 %0, %1, %2" : "=v"(r) : "v"(lo), "v"(hi)); return r; }
;     __device__ __forceinline__ void operator()(const f32x4 (&acc)[2][2][4][2], const Unit& u, int wr, int wc, int fr, int fq) const {
;     ...
;                 for (int m = 0; m < 4; ++m) {
;                     u32x2_t w; float o[4];
; #pragma unroll
;                     for (int e = 0; e < 4; ++e) {
;                         const float g1 = m >= 1 ? xg[m - (m >= 1 ? 1 : 0)][e] : pg3[e], g2 = m >= 2 ? xg[m - (m >= 2 ? 2 : 0)][e] : (m == 1 ? pg3[e] : pg2[e]);
;                         const float v1 = m >= 1 ? xv[m - (m >= 1 ? 1 : 0)][e] : pv3[e], v2 = m >= 2 ? xv[m - (m >= 2 ? 2 : 0)][e] : (m == 1 ? pv3[e] : pv2[e]);
;                         const float cg_ = bg[e] + w0g[e] * g2 + w1g[e] * g1 + w2g[e] * xg[m][e];
;                         const float cv_ = bv[e] + w0v[e] * v2 + w1v[e] * v1 + w2v[e] * xv[m][e];
;                         o[e] = cg_ * __builtin_amdgcn_rcpf(1.0f + __expf(-cg_)) * cv_;
;                     }
;                     w.x = cvt_pk_bf16(o[0], o[1]); w.y = cvt_pk_bf16(o[2], o[3]);
;                     const int g = g0 + m;
;                     if (n == 0) stash[ai][m] = w;
;                     else if ((fr > 0 || m >= 2) && g < TT) { u32x4 ww; ww.x = stash[ai][m].x; ww.y = stash[ai][m].y; ww.z = w.x; ww.w = w.y; *(u32x4*)(G + (size_t)g * DFF_ + f0 - 4) = ww; }
.LBB0_1177:
	s_or_b64 exec, exec, s[14:15]
	v_fma_f32 v14, v94, v34, v70
	v_fmac_f32_e32 v14, v102, v24
	v_fmac_f32_e32 v14, v98, v26
	v_mul_f32_e32 v15, 0xbfb8aa3b, v14
	v_exp_f32_e32 v15, v15
	v_fma_f32 v23, v95, v35, v71
	v_fmac_f32_e32 v23, v103, v25
	v_fmac_f32_e32 v23, v99, v27
	v_fma_f32 v22, v78, v32, v90
	v_add_f32_e32 v15, 1.0, v15
	v_mul_f32_e32 v32, 0xbfb8aa3b, v23
	v_rcp_f32_e32 v15, v15
	v_exp_f32_e32 v32, v32
	v_fmac_f32_e32 v22, v82, v18
	v_fmac_f32_e32 v22, v86, v20
	v_mul_f32_e32 v14, v14, v15
	v_add_f32_e32 v15, 1.0, v32
	v_rcp_f32_e32 v15, v15
	v_mul_f32_e32 v14, v22, v14
	v_fma_f32 v22, v79, v33, v91
	v_fmac_f32_e32 v22, v83, v19
	v_mul_f32_e32 v15, v23, v15
	v_fma_f32 v23, v96, v30, v72
	v_fmac_f32_e32 v23, v104, v16
	v_fmac_f32_e32 v23, v100, v10
	v_mul_f32_e32 v30, 0xbfb8aa3b, v23
	v_exp_f32_e32 v30, v30
	v_fmac_f32_e32 v22, v87, v21
	v_mul_f32_e32 v15, v22, v15
	v_fma_f32 v22, v80, v28, v92
	v_add_f32_e32 v28, 1.0, v30
	v_fma_f32 v30, v97, v31, v73
	v_fmac_f32_e32 v30, v105, v17
	v_fmac_f32_e32 v30, v101, v11
	v_rcp_f32_e32 v28, v28
	v_mul_f32_e32 v31, 0xbfb8aa3b, v30
	v_exp_f32_e32 v31, v31
	v_fmac_f32_e32 v22, v84, v8
	v_fmac_f32_e32 v22, v88, v4
	v_mul_f32_e32 v23, v23, v28
	v_mul_f32_e32 v22, v22, v23
	v_add_f32_e32 v23, 1.0, v31
	v_rcp_f32_e32 v23, v23
	v_fma_f32 v28, v81, v29, v93
	v_fmac_f32_e32 v28, v85, v9
	v_fmac_f32_e32 v28, v89, v5
	v_mul_f32_e32 v23, v30, v23
	v_cmp_gt_i32_e32 vcc, s81, v214
	v_mul_f32_e32 v23, v28, v23
	v_cvt_pk_bf16_f32 v68, v14, v15
	v_cvt_pk_bf16_f32 v69, v22, v23
	s_and_saveexec_b64 s[14:15], vcc
	s_cbranch_execz .LBB0_1179
	v_mov_b64_e32 v[14:15], s[4:5]
	v_mad_i64_i32 v[14:15], s[6:7], v216, s80, v[14:15]
	v_lshl_add_u64 v[14:15], v[182:183], 1, v[14:15]
	global_store_dwordx4 v[14:15], v[66:69], off sc0 sc1
.LBB0_1179:
	s_or_b64 exec, exec, s[14:15]
	v_fma_f32 v14, v94, v24, v70
	v_fmac_f32_e32 v14, v102, v26
	v_fmac_f32_e32 v14, v98, v12
	v_mul_f32_e32 v12, 0xbfb8aa3b, v14
	v_exp_f32_e32 v12, v12
	v_fma_f32 v15, v78, v18, v90
	v_fma_f32 v18, v95, v25, v71
	v_fmac_f32_e32 v18, v103, v27
	v_fmac_f32_e32 v18, v99, v13
	v_add_f32_e32 v12, 1.0, v12
	v_mul_f32_e32 v13, 0xbfb8aa3b, v18
	v_rcp_f32_e32 v12, v12
	v_exp_f32_e32 v13, v13
	v_fmac_f32_e32 v15, v82, v20
	v_fmac_f32_e32 v15, v86, v6
	v_mul_f32_e32 v6, v14, v12
	v_add_f32_e32 v12, 1.0, v13
	v_rcp_f32_e32 v12, v12
	v_fma_f32 v13, v79, v19, v91
	v_fmac_f32_e32 v13, v83, v21
	v_fmac_f32_e32 v13, v87, v7
	v_mul_f32_e32 v7, v18, v12
	v_fma_f32 v12, v96, v16, v72
	v_fmac_f32_e32 v73, v97, v17
	v_fmac_f32_e32 v12, v104, v10
	v_fmac_f32_e32 v73, v105, v11
	v_fmac_f32_e32 v12, v100, v0
	v_fmac_f32_e32 v73, v101, v1
	v_mul_f32_e32 v0, 0xbfb8aa3b, v12
	v_mul_f32_e32 v1, 0xbfb8aa3b, v73
	v_exp_f32_e32 v0, v0
	v_exp_f32_e32 v1, v1
	v_fma_f32 v8, v80, v8, v92
	v_fmac_f32_e32 v93, v81, v9
	v_add_f32_e32 v0, 1.0, v0
	v_add_f32_e32 v1, 1.0, v1
	v_rcp_f32_e32 v0, v0
	v_rcp_f32_e32 v1, v1
	v_fmac_f32_e32 v8, v84, v4
	v_fmac_f32_e32 v93, v85, v5
	v_fmac_f32_e32 v8, v88, v2
	v_mul_f32_e32 v0, v12, v0
	v_fmac_f32_e32 v93, v89, v3
	v_mul_f32_e32 v1, v73, v1
	v_cmp_gt_i32_e32 vcc, s82, v214
	v_mul_f32_e32 v6, v15, v6
	v_mul_f32_e32 v7, v13, v7
	v_mul_f32_e32 v0, v8, v0
	v_mul_f32_e32 v1, v93, v1
	v_cvt_pk_bf16_f32 v66, v6, v7
	v_cvt_pk_bf16_f32 v67, v0, v1
	s_and_saveexec_b64 s[14:15], vcc
	s_cbranch_execz .LBB0_1181
	v_mov_b64_e32 v[0:1], s[4:5]
	v_mad_i64_i32 v[0:1], s[6:7], v215, s80, v[0:1]
	v_lshl_add_u64 v[0:1], v[182:183], 1, v[0:1]
	global_store_dwordx4 v[0:1], v[64:67], off sc0 sc1

; #define LAS __attribute__((address_space(3)))
; __device__ __forceinline__ unsigned cvtpk(float lo, float hi) { f32x2 v = {lo, hi}; bf16x2_t b = __builtin_convertvector(v, bf16x2_t); return __builtin_bit_cast(unsigned, b); }
; __device__ __forceinline__ void witem_store(const WItem& w, int K, bf16_t* WT, int kvperm, LAS float* scr, int item, int nblk, int lane) {
;     ...
;     for (int i = 0; i < 8; ++i) { LAS float* d = scr + (8 * i + rr) * 33 + col; const float g = w.g[i]; d[0] = w.v[i].x * g; d[1] = w.v[i].y * g; d[2] = w.v[i].z * g; d[3] = w.v[i].w * g; }
;     asm volatile("s_waitcnt lgkmcnt(0)" ::: "memory");
;     const int c = lane & 7;
; #pragma unroll
;     for (int j = 0; j < 4; ++j) { const int n = (lane >> 3) + 8 * j; const LAS float* s = scr + (8 * c) * 33 + n;
;         u32x4 o; o.x = cvtpk(s[0 * 33], s[1 * 33]); o.y = cvtpk(s[2 * 33], s[3 * 33]); o.z = cvtpk(s[4 * 33], s[5 * 33]); o.w = cvtpk(s[6 * 33], s[7 * 33]);
;         int nr = n0 + n; if (kvperm == 1) { const int hh = nr >> 8, ww = nr & 255; nr = (ww < 128) ? hh * 128 + ww : 2048 + hh * 128 + (ww - 128); }
;         else if (kvperm == 2) { const int isv = nr >= 5632, f = isv ? nr - 5632 : nr; nr = (f >> 7) * 256 + isv * 128 + (f & 127); }
;         *(u32x4*)(WT + (size_t)nr * K + k0 + 8 * c) = o; }
.LBB0_1205:
	v_pk_mul_f32 v[2:3], v[12:13], v[72:73] op_sel_hi:[1,0]
	ds_write2_b32 v79, v2, v3 offset1:1
	v_pk_mul_f32 v[2:3], v[14:15], v[72:73] op_sel_hi:[1,0]
	ds_write2_b32 v79, v2, v3 offset0:2 offset1:3
	v_pk_mul_f32 v[2:3], v[4:5], v[74:75] op_sel_hi:[1,0]
	v_add_u32_e32 v4, 0x420, v79
	ds_write2_b32 v4, v2, v3 offset1:1
	v_pk_mul_f32 v[2:3], v[6:7], v[74:75] op_sel_hi:[1,0]
	v_add_u32_e32 v4, 0x428, v79
	ds_write2_b32 v4, v2, v3 offset1:1
	v_pk_mul_f32 v[2:3], v[24:25], v[76:77] op_sel_hi:[1,0]
	v_add_u32_e32 v4, 0x840, v79
	ds_write2_b32 v4, v2, v3 offset1:1
	v_pk_mul_f32 v[2:3], v[26:27], v[76:77] op_sel_hi:[1,0]
	v_add_u32_e32 v4, 0x848, v79
	ds_write2_b32 v4, v2, v3 offset1:1
	v_pk_mul_f32 v[2:3], v[20:21], v[78:79] op_sel_hi:[1,0]
	v_add_u32_e32 v4, 0xc60, v79
	ds_write2_b32 v4, v2, v3 offset1:1
	v_pk_mul_f32 v[2:3], v[22:23], v[78:79] op_sel_hi:[1,0]
	v_add_u32_e32 v4, 0xc68, v79
	ds_write2_b32 v4, v2, v3 offset1:1
	v_pk_mul_f32 v[2:3], v[36:37], v[80:81] op_sel_hi:[1,0]
	v_add_u32_e32 v4, 0x1080, v79
	ds_write2_b32 v4, v2, v3 offset1:1
	v_pk_mul_f32 v[2:3], v[38:39], v[80:81] op_sel_hi:[1,0]
	v_add_u32_e32 v4, 0x1088, v79
	ds_write2_b32 v4, v2, v3 offset1:1
	v_pk_mul_f32 v[2:3], v[28:29], v[82:83] op_sel_hi:[1,0]
	v_add_u32_e32 v4, 0x14a0, v79
	ds_write2_b32 v4, v2, v3 offset1:1
	v_pk_mul_f32 v[2:3], v[30:31], v[82:83] op_sel_hi:[1,0]
	v_add_u32_e32 v4, 0x14a8, v79
	ds_write2_b32 v4, v2, v3 offset1:1
	s_waitcnt vmcnt(7)
	v_pk_mul_f32 v[2:3], v[48:49], v[84:85] op_sel_hi:[1,0]
	v_add_u32_e32 v4, 0x18c0, v79
	s_mul_hi_i32 s6, s6, 0x2e8ba2e9
	ds_write2_b32 v4, v2, v3 offset1:1
	v_pk_mul_f32 v[2:3], v[50:51], v[84:85] op_sel_hi:[1,0]
	v_add_u32_e32 v4, 0x18c8, v79
	s_lshr_b32 s10, s6, 31
	s_ashr_i32 s6, s6, 6
	ds_write2_b32 v4, v2, v3 offset1:1
	s_waitcnt vmcnt(6)
	v_pk_mul_f32 v[2:3], v[44:45], v[86:87] op_sel_hi:[1,0]
	v_add_u32_e32 v4, 0x1ce0, v79
	s_add_i32 s6, s6, s10
	ds_write2_b32 v4, v2, v3 offset1:1
	v_pk_mul_f32 v[2:3], v[46:47], v[86:87] op_sel_hi:[1,0]
	v_add_u32_e32 v4, 0x1ce8, v79
	s_lshl_b32 s10, s6, 6
	ds_write2_b32 v4, v2, v3 offset1:1
	s_mulk_i32 s6, 0xd400
	s_waitcnt lgkmcnt(0)
	s_add_i32 s6, s6, s7
	ds_read2_b32 v[6:7], v77 offset0:33 offset1:41
	ds_read2_b32 v[12:13], v77 offset1:8
	ds_read2_b32 v[14:15], v77 offset0:66 offset1:74
	ds_read2_b32 v[20:21], v77 offset0:99 offset1:107
	ds_read2_b32 v[22:23], v77 offset0:132 offset1:140
	ds_read2_b32 v[24:25], v77 offset0:165 offset1:173
	ds_read2_b32 v[26:27], v77 offset0:198 offset1:206
	ds_read2_b32 v[28:29], v77 offset0:231 offset1:239
	v_add_u32_e32 v38, s6, v83
	s_waitcnt lgkmcnt(6)
	v_cvt_pk_bf16_f32 v2, v12, v6
	v_add_u32_e32 v6, 0xffffea00, v38
	v_cmp_lt_i32_e32 vcc, s16, v38
	s_waitcnt lgkmcnt(4)
	v_cvt_pk_bf16_f32 v3, v14, v20
	s_ashr_i32 s11, s10, 31
	v_cndmask_b32_e32 v6, v38, v6, vcc
	v_lshlrev_b32_e32 v12, 1, v6
	v_and_b32_e32 v12, 0xffffff00, v12
	v_cndmask_b32_e32 v14, 0, v81, vcc
	v_and_b32_e32 v6, 0x67, v6
	v_or3_b32 v36, v6, v14, v12
	v_ashrrev_i32_e32 v37, 31, v36
	v_lshl_add_u64 v[30:31], s[10:11], 1, v[70:71]
	v_lshlrev_b64 v[36:37], 12, v[36:37]
	s_waitcnt lgkmcnt(2)
	v_cvt_pk_bf16_f32 v4, v22, v24
	s_waitcnt lgkmcnt(0)
	v_cvt_pk_bf16_f32 v5, v26, v28
	v_lshl_add_u64 v[36:37], v[30:31], 0, v[36:37]
	v_add_u32_e32 v6, 8, v38
	global_store_dwordx4 v[36:37], v[2:5], off sc0 sc1
	v_cmp_lt_i32_e32 vcc, s16, v6
	s_waitcnt vmcnt(3)
	v_mov_b64_e32 v[48:49], v[60:61]
	v_cvt_pk_bf16_f32 v2, v13, v7
	v_add_u32_e32 v7, 0xffffea08, v38
	v_cndmask_b32_e32 v6, v6, v7, vcc
	v_lshlrev_b32_e32 v7, 1, v6
	v_and_b32_e32 v7, 0xffffff00, v7
	v_cndmask_b32_e32 v12, 0, v81, vcc
	v_and_b32_e32 v6, 0x6f, v6
	v_or3_b32 v6, v6, v12, v7
	v_ashrrev_i32_e32 v7, 31, v6
	v_lshlrev_b64 v[6:7], 12, v[6:7]
	v_cvt_pk_bf16_f32 v3, v15, v21
	v_cvt_pk_bf16_f32 v4, v23, v25
	v_cvt_pk_bf16_f32 v5, v27, v29
	v_lshl_add_u64 v[6:7], v[30:31], 0, v[6:7]
	ds_read2_b32 v[12:13], v77 offset0:16 offset1:24
	ds_read2_b32 v[14:15], v77 offset0:49 offset1:57
	ds_read2_b32 v[20:21], v77 offset0:82 offset1:90
	ds_read2_b32 v[22:23], v77 offset0:115 offset1:123
	ds_read2_b32 v[24:25], v77 offset0:148 offset1:156
	ds_read2_b32 v[26:27], v77 offset0:181 offset1:189
	ds_read2_b32 v[28:29], v77 offset0:214 offset1:222
	ds_read2_b32 v[36:37], v77 offset0:247 offset1:255
	global_store_dwordx4 v[6:7], v[2:5], off sc0 sc1
	v_add_u32_e32 v6, 16, v38
	v_add_u32_e32 v7, 0xffffea10, v38
	v_cmp_lt_i32_e32 vcc, s16, v6
	s_waitcnt lgkmcnt(6)
	v_cvt_pk_bf16_f32 v2, v12, v14
	s_waitcnt lgkmcnt(4)
	v_cvt_pk_bf16_f32 v3, v20, v22
	v_cndmask_b32_e32 v6, v6, v7, vcc
	v_lshlrev_b32_e32 v7, 1, v6
	v_and_b32_e32 v7, 0xffffff00, v7
	v_cndmask_b32_e32 v12, 0, v81, vcc
	v_and_b32_e32 v6, 0x77, v6
	v_or3_b32 v6, v6, v12, v7
	v_ashrrev_i32_e32 v7, 31, v6
	v_lshlrev_b64 v[6:7], 12, v[6:7]
	s_waitcnt lgkmcnt(2)
	v_cvt_pk_bf16_f32 v4, v24, v26
	s_waitcnt lgkmcnt(0)
	v_cvt_pk_bf16_f32 v5, v28, v36
	v_lshl_add_u64 v[6:7], v[30:31], 0, v[6:7]
	global_store_dwordx4 v[6:7], v[2:5], off sc0 sc1
	s_waitcnt vmcnt(4)
	v_mov_b64_e32 v[44:45], v[64:65]
	v_add_u32_e32 v83, s12, v83
	v_add_u32_e32 v2, 24, v38
	v_add_u32_e32 v3, 0xffffea18, v38
	v_cmp_lt_i32_e32 vcc, s16, v2
	v_cvt_pk_bf16_f32 v5, v29, v37
	v_mov_b64_e32 v[36:37], v[52:53]
	v_cndmask_b32_e32 v2, v2, v3, vcc
	v_lshlrev_b32_e32 v3, 1, v2
	v_and_b32_e32 v3, 0xffffff00, v3
	v_cndmask_b32_e32 v4, 0, v81, vcc
	v_and_b32_e32 v2, 0x7f, v2
	v_or3_b32 v6, v2, v4, v3
	v_ashrrev_i32_e32 v7, 31, v6
	v_lshlrev_b64 v[6:7], 12, v[6:7]
	v_cvt_pk_bf16_f32 v2, v13, v15
	v_cvt_pk_bf16_f32 v3, v21, v23
	v_cvt_pk_bf16_f32 v4, v25, v27
	v_lshl_add_u64 v[6:7], v[30:31], 0, v[6:7]
	global_store_dwordx4 v[6:7], v[2:5], off sc0 sc1
	s_waitcnt lgkmcnt(0)
	v_mov_b64_e32 v[12:13], v[16:17]
	v_mov_b64_e32 v[24:25], v[32:33]
	v_mov_b64_e32 v[4:5], v[8:9]
	v_mov_b64_e32 v[20:21], v[40:41]
	v_mov_b64_e32 v[28:29], v[56:57]
	s_add_i32 s17, s17, s12
	v_add_u32_e32 v73, s12, v73
	s_andn2_b64 vcc, exec, s[8:9]
	s_mov_b32 s6, s18
	v_mov_b64_e32 v[14:15], v[18:19]
	v_mov_b64_e32 v[6:7], v[10:11]
	v_mov_b64_e32 v[26:27], v[34:35]
	v_mov_b64_e32 v[22:23], v[42:43]
	v_mov_b64_e32 v[38:39], v[54:55]
	v_mov_b64_e32 v[30:31], v[58:59]
	v_mov_b64_e32 v[50:51], v[62:63]
	v_mov_b64_e32 v[46:47], v[66:67]
	v_mov_b32_e32 v72, v85
	v_mov_b32_e32 v74, v87
	v_mov_b32_e32 v76, v89
	v_mov_b32_e32 v78, v94
	v_mov_b32_e32 v80, v95
	v_mov_b32_e32 v82, v96
	v_mov_b32_e32 v84, v97
	s_waitcnt vmcnt(4)
	v_mov_b32_e32 v86, v1
	s_cbranch_vccz .LBB0_1223

; __device__ __forceinline__ unsigned cvt_pk_bf16(float lo, float hi) { unsigned r; asm volatile("v_cvt_pk_bf16_f32 %0, %1, %2" : "=v"(r) : "v"(lo), "v"(hi)); return r; }
;     __device__ __forceinline__ void operator()(const f32x4 (&acc)[2][2][4][2], const Unit& u, int wr, int wc, int fr, int fq) const {
;     ...
;         for (int ai = 0; ai < 2; ++ai) {
;             u32x4 old[4][2];
; #pragma unroll
;             for (int m = 0; m < 4; ++m)
; #pragma unroll
;                 for (int bj = 0; bj < 2; ++bj) old[m][bj] = *(const u32x4*)(HB + (size_t)(row0 + ai * HALF + m * 16) * ldc + col0 + bj * HALF);
; #pragma unroll
;             for (int m = 0; m < 4; ++m) { const int row = row0 + ai * HALF + m * 16; float ss = 0.f;
; #pragma unroll
;                 for (int bj = 0; bj < 2; ++bj) { const u32x4 ow = old[m][bj];
;                     f32x4 v0 = (acc[ai][bj][m][0] + bv[bj][0]) * accs, v1 = (acc[ai][bj][m][1] + bv[bj][1]) * accs;
;                     v0[0] += __uint_as_float(ow.x << 16); v0[1] += __uint_as_float(ow.x & 0xffff0000u); v0[2] += __uint_as_float(ow.y << 16); v0[3] += __uint_as_float(ow.y & 0xffff0000u);
;                     v1[0] += __uint_as_float(ow.z << 16); v1[1] += __uint_as_float(ow.z & 0xffff0000u); v1[2] += __uint_as_float(ow.w << 16); v1[3] += __uint_as_float(ow.w & 0xffff0000u);
;                     ss += (v0[0] * v0[0] + v0[1] * v0[1]) + (v0[2] * v0[2] + v0[3] * v0[3]) + (v1[0] * v1[0] + v1[1] * v1[1]) + (v1[2] * v1[2] + v1[3] * v1[3]);
;                     u32x4 w; w.x = cvt_pk_bf16(v0[0], v0[1]); w.y = cvt_pk_bf16(v0[2], v0[3]); w.z = cvt_pk_bf16(v1[0], v1[1]); w.w = cvt_pk_bf16(v1[2], v1[3]);
;                     *(u32x4*)(HB + (size_t)row * ldc + col0 + bj * HALF) = w; }
;                 ss += __shfl_xor(ss, 16); ss += __shfl_xor(ss, 32);
;                 if (fq == 0) ssp[(size_t)row * 32] = ss; }
.LBB0_1301:
	v_lshl_or_b32 v152, s6, 8, v166
	v_ashrrev_i32_e32 v153, 31, v152
	v_lshl_add_u32 v154, s7, 8, v164
	v_lshlrev_b64 v[180:181], 1, v[152:153]
	v_ashrrev_i32_e32 v155, 31, v154
	v_lshl_add_u64 v[156:157], s[8:9], 0, v[180:181]
	v_lshlrev_b64 v[182:183], 12, v[154:155]
	v_lshl_add_u64 v[128:129], v[156:157], 0, v[182:183]
	global_load_dwordx4 v[172:175], v[128:129], off
	global_load_dwordx4 v[176:179], v[128:129], off offset:256
	v_or_b32_e32 v162, 16, v154
	v_or_b32_e32 v160, 32, v154
	v_or_b32_e32 v158, 48, v154
	v_ashrrev_i32_e32 v163, 31, v162
	v_ashrrev_i32_e32 v161, 31, v160
	v_pk_add_f32 v[196:197], v[114:115], 0 op_sel_hi:[1,0]
	v_pk_add_f32 v[198:199], v[112:113], 0 op_sel_hi:[1,0]
	v_ashrrev_i32_e32 v159, 31, v158
	v_lshlrev_b64 v[112:113], 12, v[162:163]
	v_lshlrev_b64 v[114:115], 12, v[160:161]
	v_pk_add_f32 v[194:195], v[116:117], 0 op_sel_hi:[1,0]
	v_lshlrev_b64 v[116:117], 12, v[158:159]
	v_lshl_add_u64 v[112:113], v[156:157], 0, v[112:113]
	v_lshl_add_u64 v[114:115], v[156:157], 0, v[114:115]
	v_pk_add_f32 v[184:185], v[126:127], 0 op_sel_hi:[1,0]
	v_pk_add_f32 v[186:187], v[124:125], 0 op_sel_hi:[1,0]
	v_pk_add_f32 v[188:189], v[122:123], 0 op_sel_hi:[1,0]
	v_pk_add_f32 v[190:191], v[120:121], 0 op_sel_hi:[1,0]
	v_pk_add_f32 v[192:193], v[118:119], 0 op_sel_hi:[1,0]
	v_lshl_add_u64 v[200:201], v[156:157], 0, v[116:117]
	global_load_dwordx4 v[132:135], v[112:113], off
	global_load_dwordx4 v[128:131], v[112:113], off offset:256
	global_load_dwordx4 v[124:127], v[114:115], off
	global_load_dwordx4 v[120:123], v[114:115], off offset:256
	global_load_dwordx4 v[116:119], v[200:201], off
	s_nop 0
	global_load_dwordx4 v[112:115], v[200:201], off offset:256
	s_lshl_b32 s6, s6, 2
	s_or_b32 s6, s6, s42
	s_ashr_i32 s7, s6, 31
	s_lshl_b64 s[6:7], s[6:7], 2
	s_add_u32 s22, s40, s6
	s_addc_u32 s23, s41, s7
	s_waitcnt vmcnt(0)
	v_lshlrev_b32_e32 v171, 16, v172
	v_and_b32_e32 v172, 0xffff0000, v172
	v_lshlrev_b32_e32 v200, 16, v173
	v_and_b32_e32 v173, 0xffff0000, v173
	v_lshlrev_b32_e32 v201, 16, v174
	v_lshlrev_b32_e32 v202, 16, v175
	v_lshlrev_b32_e32 v203, 16, v176
	v_and_b32_e32 v176, 0xffff0000, v176
	v_lshlrev_b32_e32 v206, 16, v177
	v_and_b32_e32 v177, 0xffff0000, v177
	v_add_f32_e32 v172, v187, v172
	v_add_f32_e32 v173, v185, v173
	v_and_b32_e32 v175, 0xffff0000, v175
	v_lshlrev_b32_e32 v207, 16, v178
	v_and_b32_e32 v178, 0xffff0000, v178
	v_lshlrev_b32_e32 v208, 16, v179
	v_add_f32_e32 v171, v186, v171
	v_add_f32_e32 v184, v184, v200
	v_add_f32_e32 v185, v190, v201
	v_add_f32_e32 v186, v188, v202
	v_add_f32_e32 v188, v195, v176
	v_add_f32_e32 v190, v193, v177
	v_mul_f32_e32 v176, v172, v172
	v_mul_f32_e32 v177, v173, v173
	v_and_b32_e32 v174, 0xffff0000, v174
	v_add_f32_e32 v175, v189, v175
	v_add_f32_e32 v187, v194, v203
	v_add_f32_e32 v189, v192, v206
	v_add_f32_e32 v178, v199, v178
	v_add_f32_e32 v192, v196, v208
	v_mul_f32_e32 v195, v188, v188
	v_mul_f32_e32 v196, v190, v190
	v_fmac_f32_e32 v176, v171, v171
	v_fmac_f32_e32 v177, v184, v184
	v_and_b32_e32 v179, 0xffff0000, v179
	v_add_f32_e32 v174, v191, v174
	v_add_f32_e32 v191, v198, v207
	v_cvt_pk_bf16_f32 v172, v171, v172
	v_fmac_f32_e32 v195, v187, v187
	v_add_f32_e32 v171, v176, v177
	v_fmac_f32_e32 v196, v189, v189
	v_mul_f32_e32 v177, v178, v178
	v_add_f32_e32 v179, v197, v179
	v_mul_f32_e32 v193, v174, v174
	v_add_f32_e32 v176, v195, v196
	v_fmac_f32_e32 v177, v191, v191
	v_mul_f32_e32 v194, v175, v175
	v_fmac_f32_e32 v193, v185, v185
	v_add_f32_e32 v176, v177, v176
	v_mul_f32_e32 v177, v179, v179
	v_fmac_f32_e32 v194, v186, v186
	v_add_f32_e32 v171, v193, v171
	v_fmac_f32_e32 v177, v192, v192
	v_add_f32_e32 v171, v194, v171
	v_add_f32_e32 v176, v177, v176
	v_cvt_pk_bf16_f32 v173, v184, v173
	v_add_f32_e32 v184, v171, v176
	v_and_b32_e32 v176, 64, v170
	v_cvt_pk_bf16_f32 v174, v185, v174
	v_xor_b32_e32 v171, 16, v170
	v_add_u32_e32 v185, 64, v176
	v_cmp_lt_i32_e32 vcc, v171, v185
	v_cvt_pk_bf16_f32 v175, v186, v175
	v_lshl_add_u64 v[176:177], s[8:9], 0, v[182:183]
	v_lshl_add_u64 v[180:181], v[176:177], 0, v[180:181]
	v_cndmask_b32_e32 v171, v170, v171, vcc
	v_lshlrev_b32_e32 v171, 2, v171
	ds_bpermute_b32 v186, v171, v184
	global_store_dwordx4 v[180:181], v[172:175], off sc0 sc1
	v_cvt_pk_bf16_f32 v176, v187, v188
	v_cvt_pk_bf16_f32 v177, v189, v190
	v_cvt_pk_bf16_f32 v178, v191, v178
	v_cvt_pk_bf16_f32 v179, v192, v179
	global_store_dwordx4 v[180:181], v[176:179], off offset:256 sc0 sc1
	s_nop 0
	v_xor_b32_e32 v172, 32, v170
	v_cmp_lt_i32_e32 vcc, v172, v185
	s_waitcnt lgkmcnt(0)
	v_add_f32_e32 v173, v184, v186
	v_cndmask_b32_e32 v172, v170, v172, vcc
	v_lshlrev_b32_e32 v172, 2, v172
	ds_bpermute_b32 v174, v172, v173
	s_and_saveexec_b64 s[24:25], s[10:11]
	s_cbranch_execz .LBB0_1303
	v_lshlrev_b64 v[176:177], 7, v[154:155]
	v_lshl_add_u64 v[176:177], s[22:23], 0, v[176:177]
	s_waitcnt lgkmcnt(0)
	v_add_f32_e32 v155, v173, v174
	global_store_dword v[176:177], v155, off
; __device__ __forceinline__ unsigned cvt_pk_bf16(float lo, float hi) { unsigned r; asm volatile("v_cvt_pk_bf16_f32 %0, %1, %2" : "=v"(r) : "v"(lo), "v"(hi)); return r; }
;     __device__ __forceinline__ void operator()(const f32x4 (&acc)[2][2][4][2], const Unit& u, int wr, int wc, int fr, int fq) const {
;     ...
;             for (int m = 0; m < 4; ++m) { const int row = row0 + ai * HALF + m * 16; float ss = 0.f;
; #pragma unroll
;                 for (int bj = 0; bj < 2; ++bj) { const u32x4 ow = old[m][bj];
;                     f32x4 v0 = (acc[ai][bj][m][0] + bv[bj][0]) * accs, v1 = (acc[ai][bj][m][1] + bv[bj][1]) * accs;
;                     v0[0] += __uint_as_float(ow.x << 16); v0[1] += __uint_as_float(ow.x & 0xffff0000u); v0[2] += __uint_as_float(ow.y << 16); v0[3] += __uint_as_float(ow.y & 0xffff0000u);
;                     v1[0] += __uint_as_float(ow.z << 16); v1[1] += __uint_as_float(ow.z & 0xffff0000u); v1[2] += __uint_as_float(ow.w << 16); v1[3] += __uint_as_float(ow.w & 0xffff0000u);
;                     ss += (v0[0] * v0[0] + v0[1] * v0[1]) + (v0[2] * v0[2] + v0[3] * v0[3]) + (v1[0] * v1[0] + v1[1] * v1[1]) + (v1[2] * v1[2] + v1[3] * v1[3]);
;                     u32x4 w; w.x = cvt_pk_bf16(v0[0], v0[1]); w.y = cvt_pk_bf16(v0[2], v0[3]); w.z = cvt_pk_bf16(v1[0], v1[1]); w.w = cvt_pk_bf16(v1[2], v1[3]);
;                     *(u32x4*)(HB + (size_t)row * ldc + col0 + bj * HALF) = w; }
;                 ss += __shfl_xor(ss, 16); ss += __shfl_xor(ss, 32);
;                 if (fq == 0) ssp[(size_t)row * 32] = ss; }
.LBB0_1303:
	s_or_b64 exec, exec, s[24:25]
	v_pk_add_f32 v[108:109], v[108:109], 0 op_sel_hi:[1,0]
	v_lshlrev_b32_e32 v155, 16, v132
	v_and_b32_e32 v132, 0xffff0000, v132
	v_pk_add_f32 v[110:111], v[110:111], 0 op_sel_hi:[1,0]
	v_add_f32_e32 v109, v109, v132
	v_lshlrev_b32_e32 v132, 16, v133
	v_add_f32_e32 v110, v110, v132
	v_and_b32_e32 v132, 0xffff0000, v133
	v_pk_add_f32 v[104:105], v[104:105], 0 op_sel_hi:[1,0]
	v_add_f32_e32 v111, v111, v132
	v_lshlrev_b32_e32 v132, 16, v134
	v_add_f32_e32 v132, v104, v132
	v_and_b32_e32 v104, 0xffff0000, v134
	v_pk_add_f32 v[106:107], v[106:107], 0 op_sel_hi:[1,0]
	v_add_f32_e32 v133, v105, v104
	v_lshlrev_b32_e32 v104, 16, v135
	v_add_f32_e32 v134, v106, v104
	v_and_b32_e32 v104, 0xffff0000, v135
	v_add_f32_e32 v108, v108, v155
	v_add_f32_e32 v107, v107, v104
	v_mul_f32_e32 v104, v109, v109
	v_mul_f32_e32 v105, v111, v111
	v_fmac_f32_e32 v104, v108, v108
	v_fmac_f32_e32 v105, v110, v110
	v_add_f32_e32 v104, v104, v105
	v_mul_f32_e32 v105, v133, v133
	v_fmac_f32_e32 v105, v132, v132
	v_add_f32_e32 v104, v105, v104
	v_mul_f32_e32 v105, v107, v107
	v_fmac_f32_e32 v105, v134, v134
	v_add_f32_e32 v135, v105, v104
	v_cvt_pk_bf16_f32 v104, v108, v109
	v_pk_add_f32 v[100:101], v[100:101], 0 op_sel_hi:[1,0]
	v_lshlrev_b32_e32 v108, 16, v128
	v_add_f32_e32 v100, v100, v108
	v_and_b32_e32 v108, 0xffff0000, v128
	v_pk_add_f32 v[102:103], v[102:103], 0 op_sel_hi:[1,0]
	v_add_f32_e32 v101, v101, v108
	v_lshlrev_b32_e32 v108, 16, v129
	v_add_f32_e32 v108, v102, v108
	v_and_b32_e32 v102, 0xffff0000, v129
	v_pk_add_f32 v[96:97], v[96:97], 0 op_sel_hi:[1,0]
	v_add_f32_e32 v109, v103, v102
	v_lshlrev_b32_e32 v102, 16, v130
	v_cvt_pk_bf16_f32 v105, v110, v111
	v_add_f32_e32 v110, v96, v102
	v_and_b32_e32 v96, 0xffff0000, v130
	v_pk_add_f32 v[98:99], v[98:99], 0 op_sel_hi:[1,0]
	v_add_f32_e32 v111, v97, v96
	v_lshlrev_b32_e32 v96, 16, v131
	v_add_f32_e32 v128, v98, v96
	v_and_b32_e32 v96, 0xffff0000, v131
	v_add_f32_e32 v129, v99, v96
	v_mul_f32_e32 v96, v101, v101
	v_mul_f32_e32 v97, v109, v109
	v_fmac_f32_e32 v96, v100, v100
	v_fmac_f32_e32 v97, v108, v108
	v_add_f32_e32 v96, v96, v97
	v_mul_f32_e32 v97, v111, v111
	v_fmac_f32_e32 v97, v110, v110
	v_add_f32_e32 v96, v97, v96
	v_mul_f32_e32 v97, v129, v129
	v_fmac_f32_e32 v97, v128, v128
	v_add_f32_e32 v96, v97, v96
	v_add_f32_e32 v99, v135, v96
	ds_bpermute_b32 v130, v171, v99
	s_waitcnt lgkmcnt(1)
	v_lshlrev_b64 v[174:175], 11, v[162:163]
	v_lshl_add_u64 v[96:97], v[174:175], 1, s[8:9]
	v_lshl_add_u64 v[102:103], v[152:153], 1, v[96:97]
	v_cvt_pk_bf16_f32 v106, v132, v133
	s_waitcnt lgkmcnt(0)
	v_add_f32_e32 v96, v99, v130
	ds_bpermute_b32 v97, v172, v96
	v_cvt_pk_bf16_f32 v107, v134, v107
	global_store_dwordx4 v[102:103], v[104:107], off sc0 sc1
	v_cvt_pk_bf16_f32 v98, v100, v101
	v_cvt_pk_bf16_f32 v99, v108, v109
	v_cvt_pk_bf16_f32 v100, v110, v111
	v_cvt_pk_bf16_f32 v101, v128, v129
	global_store_dwordx4 v[102:103], v[98:101], off offset:256 sc0 sc1
	s_and_saveexec_b64 s[24:25], s[10:11]
	s_cbranch_execz .LBB0_1305
	v_lshlrev_b64 v[98:99], 7, v[162:163]
	v_lshl_add_u64 v[98:99], s[22:23], 0, v[98:99]
	s_waitcnt lgkmcnt(0)
	v_add_f32_e32 v96, v96, v97
	global_store_dword v[98:99], v96, off
.LBB0_1305:
	s_or_b64 exec, exec, s[24:25]
	v_pk_add_f32 v[92:93], v[92:93], 0 op_sel_hi:[1,0]
	v_lshlrev_b32_e32 v98, 16, v124
	v_add_f32_e32 v92, v92, v98
	v_and_b32_e32 v98, 0xffff0000, v124
	v_pk_add_f32 v[94:95], v[94:95], 0 op_sel_hi:[1,0]
	v_add_f32_e32 v93, v93, v98
	v_lshlrev_b32_e32 v98, 16, v125
	v_add_f32_e32 v94, v94, v98
	v_and_b32_e32 v98, 0xffff0000, v125
	v_pk_add_f32 v[88:89], v[88:89], 0 op_sel_hi:[1,0]
	v_add_f32_e32 v95, v95, v98
	v_lshlrev_b32_e32 v98, 16, v126
	v_add_f32_e32 v98, v88, v98
	v_and_b32_e32 v88, 0xffff0000, v126
	v_pk_add_f32 v[90:91], v[90:91], 0 op_sel_hi:[1,0]
	v_add_f32_e32 v99, v89, v88
	v_lshlrev_b32_e32 v88, 16, v127
	v_add_f32_e32 v100, v90, v88
	v_and_b32_e32 v88, 0xffff0000, v127
	v_add_f32_e32 v91, v91, v88
	v_mul_f32_e32 v88, v93, v93
	v_mul_f32_e32 v89, v95, v95
	v_fmac_f32_e32 v88, v92, v92
	v_fmac_f32_e32 v89, v94, v94
	v_add_f32_e32 v88, v88, v89
	v_mul_f32_e32 v89, v99, v99
	v_fmac_f32_e32 v89, v98, v98
	v_add_f32_e32 v88, v89, v88
	v_mul_f32_e32 v89, v91, v91
	v_fmac_f32_e32 v89, v100, v100
	v_add_f32_e32 v101, v89, v88
	v_cvt_pk_bf16_f32 v88, v92, v93
	v_pk_add_f32 v[84:85], v[84:85], 0 op_sel_hi:[1,0]
	v_lshlrev_b32_e32 v92, 16, v120
	v_add_f32_e32 v84, v84, v92
	v_and_b32_e32 v92, 0xffff0000, v120
	v_pk_add_f32 v[86:87], v[86:87], 0 op_sel_hi:[1,0]
	v_add_f32_e32 v85, v85, v92
	v_lshlrev_b32_e32 v92, 16, v121
	v_add_f32_e32 v92, v86, v92
	v_and_b32_e32 v86, 0xffff0000, v121
	v_pk_add_f32 v[80:81], v[80:81], 0 op_sel_hi:[1,0]
	v_add_f32_e32 v93, v87, v86
	v_lshlrev_b32_e32 v86, 16, v122
	v_cvt_pk_bf16_f32 v89, v94, v95
	v_add_f32_e32 v94, v80, v86
	v_and_b32_e32 v80, 0xffff0000, v122
	v_pk_add_f32 v[82:83], v[82:83], 0 op_sel_hi:[1,0]
	v_add_f32_e32 v95, v81, v80
	v_lshlrev_b32_e32 v80, 16, v123
	v_cvt_pk_bf16_f32 v90, v98, v99
	v_add_f32_e32 v98, v82, v80
	v_and_b32_e32 v80, 0xffff0000, v123
	v_add_f32_e32 v99, v83, v80
	v_mul_f32_e32 v80, v85, v85
	v_mul_f32_e32 v81, v93, v93
	v_fmac_f32_e32 v80, v84, v84
	v_fmac_f32_e32 v81, v92, v92
	v_add_f32_e32 v80, v80, v81
	v_mul_f32_e32 v81, v95, v95
	v_fmac_f32_e32 v81, v94, v94
	v_add_f32_e32 v80, v81, v80
	v_mul_f32_e32 v81, v99, v99
	v_fmac_f32_e32 v81, v98, v98
	v_add_f32_e32 v80, v81, v80
	v_add_f32_e32 v83, v101, v80
	v_cvt_pk_bf16_f32 v91, v100, v91
	ds_bpermute_b32 v100, v171, v83
	s_waitcnt lgkmcnt(1)
	v_lshlrev_b64 v[96:97], 11, v[160:161]
	v_lshl_add_u64 v[80:81], v[96:97], 1, s[8:9]
	v_lshl_add_u64 v[86:87], v[152:153], 1, v[80:81]
	global_store_dwordx4 v[86:87], v[88:91], off sc0 sc1
	s_waitcnt lgkmcnt(0)
	v_add_f32_e32 v80, v83, v100
	ds_bpermute_b32 v81, v172, v80
	v_cvt_pk_bf16_f32 v82, v84, v85
	v_cvt_pk_bf16_f32 v83, v92, v93
	v_cvt_pk_bf16_f32 v84, v94, v95
	v_cvt_pk_bf16_f32 v85, v98, v99
	global_store_dwordx4 v[86:87], v[82:85], off offset:256 sc0 sc1
	s_and_saveexec_b64 s[24:25], s[10:11]
	s_cbranch_execz .LBB0_1307
	v_lshlrev_b64 v[82:83], 7, v[160:161]
	v_lshl_add_u64 v[82:83], s[22:23], 0, v[82:83]
	s_waitcnt lgkmcnt(0)
	v_add_f32_e32 v80, v80, v81
	global_store_dword v[82:83], v80, off
; __device__ __forceinline__ unsigned cvt_pk_bf16(float lo, float hi) { unsigned r; asm volatile("v_cvt_pk_bf16_f32 %0, %1, %2" : "=v"(r) : "v"(lo), "v"(hi)); return r; }
;     __device__ __forceinline__ void operator()(const f32x4 (&acc)[2][2][4][2], const Unit& u, int wr, int wc, int fr, int fq) const {
;     ...
;             u32x4 old[4][2];
; #pragma unroll
;             for (int m = 0; m < 4; ++m)
; #pragma unroll
;                 for (int bj = 0; bj < 2; ++bj) old[m][bj] = *(const u32x4*)(HB + (size_t)(row0 + ai * HALF + m * 16) * ldc + col0 + bj * HALF);
; #pragma unroll
;             for (int m = 0; m < 4; ++m) { const int row = row0 + ai * HALF + m * 16; float ss = 0.f;
; #pragma unroll
;                 for (int bj = 0; bj < 2; ++bj) { const u32x4 ow = old[m][bj];
;                     f32x4 v0 = (acc[ai][bj][m][0] + bv[bj][0]) * accs, v1 = (acc[ai][bj][m][1] + bv[bj][1]) * accs;
;                     v0[0] += __uint_as_float(ow.x << 16); v0[1] += __uint_as_float(ow.x & 0xffff0000u); v0[2] += __uint_as_float(ow.y << 16); v0[3] += __uint_as_float(ow.y & 0xffff0000u);
;                     v1[0] += __uint_as_float(ow.z << 16); v1[1] += __uint_as_float(ow.z & 0xffff0000u); v1[2] += __uint_as_float(ow.w << 16); v1[3] += __uint_as_float(ow.w & 0xffff0000u);
;                     ss += (v0[0] * v0[0] + v0[1] * v0[1]) + (v0[2] * v0[2] + v0[3] * v0[3]) + (v1[0] * v1[0] + v1[1] * v1[1]) + (v1[2] * v1[2] + v1[3] * v1[3]);
;                     u32x4 w; w.x = cvt_pk_bf16(v0[0], v0[1]); w.y = cvt_pk_bf16(v0[2], v0[3]); w.z = cvt_pk_bf16(v1[0], v1[1]); w.w = cvt_pk_bf16(v1[2], v1[3]);
;                     *(u32x4*)(HB + (size_t)row * ldc + col0 + bj * HALF) = w; }
;                 ss += __shfl_xor(ss, 16); ss += __shfl_xor(ss, 32);
;                 if (fq == 0) ssp[(size_t)row * 32] = ss; }
.LBB0_1307:
	s_or_b64 exec, exec, s[24:25]
	v_pk_add_f32 v[76:77], v[76:77], 0 op_sel_hi:[1,0]
	v_lshlrev_b32_e32 v82, 16, v116
	v_add_f32_e32 v76, v76, v82
	v_and_b32_e32 v82, 0xffff0000, v116
	v_pk_add_f32 v[78:79], v[78:79], 0 op_sel_hi:[1,0]
	v_add_f32_e32 v77, v77, v82
	v_lshlrev_b32_e32 v82, 16, v117
	v_add_f32_e32 v78, v78, v82
	v_and_b32_e32 v82, 0xffff0000, v117
	v_pk_add_f32 v[72:73], v[72:73], 0 op_sel_hi:[1,0]
	v_add_f32_e32 v79, v79, v82
	v_lshlrev_b32_e32 v82, 16, v118
	v_add_f32_e32 v82, v72, v82
	v_and_b32_e32 v72, 0xffff0000, v118
	v_pk_add_f32 v[74:75], v[74:75], 0 op_sel_hi:[1,0]
	v_add_f32_e32 v83, v73, v72
	v_lshlrev_b32_e32 v72, 16, v119
	v_add_f32_e32 v84, v74, v72
	v_and_b32_e32 v72, 0xffff0000, v119
	v_add_f32_e32 v75, v75, v72
	v_mul_f32_e32 v72, v77, v77
	v_mul_f32_e32 v73, v79, v79
	v_fmac_f32_e32 v72, v76, v76
	v_fmac_f32_e32 v73, v78, v78
	v_add_f32_e32 v72, v72, v73
	v_mul_f32_e32 v73, v83, v83
	v_fmac_f32_e32 v73, v82, v82
	v_add_f32_e32 v72, v73, v72
	v_mul_f32_e32 v73, v75, v75
	v_fmac_f32_e32 v73, v84, v84
	v_add_f32_e32 v85, v73, v72
	v_cvt_pk_bf16_f32 v72, v76, v77
	v_pk_add_f32 v[68:69], v[68:69], 0 op_sel_hi:[1,0]
	v_lshlrev_b32_e32 v76, 16, v112
	v_add_f32_e32 v68, v68, v76
	v_and_b32_e32 v76, 0xffff0000, v112
	v_pk_add_f32 v[70:71], v[70:71], 0 op_sel_hi:[1,0]
	v_add_f32_e32 v69, v69, v76
	v_lshlrev_b32_e32 v76, 16, v113
	v_add_f32_e32 v76, v70, v76
	v_and_b32_e32 v70, 0xffff0000, v113
	v_pk_add_f32 v[64:65], v[64:65], 0 op_sel_hi:[1,0]
	v_add_f32_e32 v77, v71, v70
	v_lshlrev_b32_e32 v70, 16, v114
	v_cvt_pk_bf16_f32 v73, v78, v79
	v_add_f32_e32 v78, v64, v70
	v_and_b32_e32 v64, 0xffff0000, v114
	v_pk_add_f32 v[66:67], v[66:67], 0 op_sel_hi:[1,0]
	v_add_f32_e32 v79, v65, v64
	v_lshlrev_b32_e32 v64, 16, v115
	v_cvt_pk_bf16_f32 v74, v82, v83
	v_add_f32_e32 v82, v66, v64
	v_and_b32_e32 v64, 0xffff0000, v115
	v_add_f32_e32 v83, v67, v64
	v_mul_f32_e32 v64, v69, v69
	v_mul_f32_e32 v65, v77, v77
	v_fmac_f32_e32 v64, v68, v68
	v_fmac_f32_e32 v65, v76, v76
	v_add_f32_e32 v64, v64, v65
	v_mul_f32_e32 v65, v79, v79
	v_fmac_f32_e32 v65, v78, v78
	v_add_f32_e32 v64, v65, v64
	v_mul_f32_e32 v65, v83, v83
	v_fmac_f32_e32 v65, v82, v82
	v_add_f32_e32 v64, v65, v64
	v_add_f32_e32 v67, v85, v64
	v_cvt_pk_bf16_f32 v75, v84, v75
	ds_bpermute_b32 v84, v171, v67
	s_waitcnt lgkmcnt(1)
	v_lshlrev_b64 v[80:81], 11, v[158:159]
	v_lshl_add_u64 v[64:65], v[80:81], 1, s[8:9]
	v_lshl_add_u64 v[70:71], v[152:153], 1, v[64:65]
	global_store_dwordx4 v[70:71], v[72:75], off sc0 sc1
	s_waitcnt lgkmcnt(0)
	v_add_f32_e32 v64, v67, v84
	ds_bpermute_b32 v65, v172, v64
	v_cvt_pk_bf16_f32 v66, v68, v69
	v_cvt_pk_bf16_f32 v67, v76, v77
	v_cvt_pk_bf16_f32 v68, v78, v79
	v_cvt_pk_bf16_f32 v69, v82, v83
	global_store_dwordx4 v[70:71], v[66:69], off offset:256 sc0 sc1
	s_and_saveexec_b64 s[24:25], s[10:11]
	s_cbranch_execz .LBB0_1309
	v_lshlrev_b64 v[66:67], 7, v[158:159]
	v_lshl_add_u64 v[66:67], s[22:23], 0, v[66:67]
	s_waitcnt lgkmcnt(0)
	v_add_f32_e32 v64, v64, v65
	global_store_dword v[66:67], v64, off
.LBB0_1309:
	s_or_b64 exec, exec, s[24:25]
	v_add_u32_e32 v94, 0x80, v154
	v_ashrrev_i32_e32 v95, 31, v94
	v_lshlrev_b64 v[104:105], 12, v[94:95]
	s_waitcnt lgkmcnt(0)
	v_lshl_add_u64 v[64:65], v[156:157], 0, v[104:105]
	global_load_dwordx4 v[96:99], v[64:65], off
	global_load_dwordx4 v[100:103], v[64:65], off offset:256
	v_add_u32_e32 v92, 0x90, v154
	v_add_u32_e32 v90, 0xa0, v154
	v_add_u32_e32 v88, 0xb0, v154
	v_ashrrev_i32_e32 v93, 31, v92
	v_ashrrev_i32_e32 v91, 31, v90
	v_ashrrev_i32_e32 v89, 31, v88
	v_lshlrev_b64 v[64:65], 12, v[92:93]
	v_lshlrev_b64 v[66:67], 12, v[90:91]
	v_lshlrev_b64 v[68:69], 12, v[88:89]
	v_lshl_add_u64 v[64:65], v[156:157], 0, v[64:65]
	v_lshl_add_u64 v[66:67], v[156:157], 0, v[66:67]
	v_lshl_add_u64 v[106:107], v[156:157], 0, v[68:69]
	global_load_dwordx4 v[84:87], v[64:65], off
	global_load_dwordx4 v[80:83], v[64:65], off offset:256
	global_load_dwordx4 v[76:79], v[66:67], off
	global_load_dwordx4 v[72:75], v[66:67], off offset:256
	global_load_dwordx4 v[68:71], v[106:107], off
	s_nop 0
	global_load_dwordx4 v[64:67], v[106:107], off offset:256
	v_pk_add_f32 v[62:63], v[62:63], 0 op_sel_hi:[1,0]
	v_pk_add_f32 v[60:61], v[60:61], 0 op_sel_hi:[1,0]
	v_pk_add_f32 v[58:59], v[58:59], 0 op_sel_hi:[1,0]
	v_pk_add_f32 v[56:57], v[56:57], 0 op_sel_hi:[1,0]
	v_pk_add_f32 v[54:55], v[54:55], 0 op_sel_hi:[1,0]
	v_pk_add_f32 v[52:53], v[52:53], 0 op_sel_hi:[1,0]
	v_pk_add_f32 v[50:51], v[50:51], 0 op_sel_hi:[1,0]
	v_pk_add_f32 v[48:49], v[48:49], 0 op_sel_hi:[1,0]
	s_waitcnt vmcnt(7)
	v_lshlrev_b32_e32 v106, 16, v96
	v_and_b32_e32 v96, 0xffff0000, v96
	v_lshlrev_b32_e32 v107, 16, v97
	v_and_b32_e32 v97, 0xffff0000, v97
	v_lshlrev_b32_e32 v108, 16, v98
	v_and_b32_e32 v98, 0xffff0000, v98
	v_lshlrev_b32_e32 v109, 16, v99
	v_and_b32_e32 v99, 0xffff0000, v99
	s_waitcnt vmcnt(6)
	v_lshlrev_b32_e32 v110, 16, v100
	v_and_b32_e32 v100, 0xffff0000, v100
	v_lshlrev_b32_e32 v111, 16, v101
	v_and_b32_e32 v101, 0xffff0000, v101
	v_lshlrev_b32_e32 v112, 16, v102
	v_and_b32_e32 v102, 0xffff0000, v102
	v_lshlrev_b32_e32 v113, 16, v103
	v_and_b32_e32 v103, 0xffff0000, v103
	v_add_f32_e32 v61, v61, v96
	v_add_f32_e32 v63, v63, v97
	v_add_f32_e32 v57, v57, v98
	v_add_f32_e32 v59, v59, v99
	v_add_f32_e32 v97, v53, v100
	v_add_f32_e32 v99, v55, v101
	v_add_f32_e32 v60, v60, v106
	v_add_f32_e32 v62, v62, v107
	v_add_f32_e32 v56, v56, v108
	v_add_f32_e32 v58, v58, v109
	v_add_f32_e32 v96, v52, v110
	v_add_f32_e32 v98, v54, v111
	v_add_f32_e32 v100, v48, v112
	v_add_f32_e32 v101, v49, v102
	v_add_f32_e32 v102, v50, v113
	v_add_f32_e32 v103, v51, v103
	v_mul_f32_e32 v52, v61, v61
	v_mul_f32_e32 v53, v63, v63
	v_mul_f32_e32 v54, v57, v57
	v_mul_f32_e32 v55, v59, v59
	v_cvt_pk_bf16_f32 v48, v60, v61
	v_cvt_pk_bf16_f32 v49, v62, v63
	v_cvt_pk_bf16_f32 v50, v56, v57
	v_cvt_pk_bf16_f32 v51, v58, v59
	v_mul_f32_e32 v57, v97, v97
	v_mul_f32_e32 v59, v99, v99
	v_mul_f32_e32 v61, v101, v101
	v_fmac_f32_e32 v52, v60, v60
	v_fmac_f32_e32 v53, v62, v62
	v_fmac_f32_e32 v57, v96, v96
	v_fmac_f32_e32 v59, v98, v98
	v_mul_f32_e32 v63, v103, v103
	v_fmac_f32_e32 v54, v56, v56
	v_fmac_f32_e32 v61, v100, v100
	v_add_f32_e32 v52, v52, v53
	v_add_f32_e32 v53, v57, v59
	v_fmac_f32_e32 v55, v58, v58
	v_fmac_f32_e32 v63, v102, v102
	v_add_f32_e32 v52, v54, v52
	v_add_f32_e32 v53, v61, v53
	v_add_f32_e32 v52, v55, v52
	v_add_f32_e32 v53, v63, v53
	v_add_f32_e32 v56, v52, v53
	ds_bpermute_b32 v57, v171, v56
	v_lshl_add_u64 v[52:53], s[8:9], 0, v[104:105]
	v_lshl_add_u64 v[54:55], v[152:153], 1, v[52:53]
	global_store_dwordx4 v[54:55], v[48:51], off sc0 sc1
	s_waitcnt lgkmcnt(0)
	s_nop 0
	v_add_f32_e32 v48, v56, v57
	ds_bpermute_b32 v49, v172, v48
	v_cvt_pk_bf16_f32 v50, v96, v97
	v_cvt_pk_bf16_f32 v51, v98, v99
	v_cvt_pk_bf16_f32 v52, v100, v101
	v_cvt_pk_bf16_f32 v53, v102, v103
	global_store_dwordx4 v[54:55], v[50:53], off offset:256 sc0 sc1
	s_and_saveexec_b64 s[24:25], s[10:11]
	s_cbranch_execz .LBB0_1311
; __device__ __forceinline__ unsigned cvt_pk_bf16(float lo, float hi) { unsigned r; asm volatile("v_cvt_pk_bf16_f32 %0, %1, %2" : "=v"(r) : "v"(lo), "v"(hi)); return r; }
;     __device__ __forceinline__ void operator()(const f32x4 (&acc)[2][2][4][2], const Unit& u, int wr, int wc, int fr, int fq) const {
;     ...
;             for (int m = 0; m < 4; ++m) { const int row = row0 + ai * HALF + m * 16; float ss = 0.f;
; #pragma unroll
;                 for (int bj = 0; bj < 2; ++bj) { const u32x4 ow = old[m][bj];
;                     f32x4 v0 = (acc[ai][bj][m][0] + bv[bj][0]) * accs, v1 = (acc[ai][bj][m][1] + bv[bj][1]) * accs;
;                     v0[0] += __uint_as_float(ow.x << 16); v0[1] += __uint_as_float(ow.x & 0xffff0000u); v0[2] += __uint_as_float(ow.y << 16); v0[3] += __uint_as_float(ow.y & 0xffff0000u);
;                     v1[0] += __uint_as_float(ow.z << 16); v1[1] += __uint_as_float(ow.z & 0xffff0000u); v1[2] += __uint_as_float(ow.w << 16); v1[3] += __uint_as_float(ow.w & 0xffff0000u);
;                     ss += (v0[0] * v0[0] + v0[1] * v0[1]) + (v0[2] * v0[2] + v0[3] * v0[3]) + (v1[0] * v1[0] + v1[1] * v1[1]) + (v1[2] * v1[2] + v1[3] * v1[3]);
;                     u32x4 w; w.x = cvt_pk_bf16(v0[0], v0[1]); w.y = cvt_pk_bf16(v0[2], v0[3]); w.z = cvt_pk_bf16(v1[0], v1[1]); w.w = cvt_pk_bf16(v1[2], v1[3]);
;                     *(u32x4*)(HB + (size_t)row * ldc + col0 + bj * HALF) = w; }
;                 ss += __shfl_xor(ss, 16); ss += __shfl_xor(ss, 32);
;                 if (fq == 0) ssp[(size_t)row * 32] = ss; }
	v_lshlrev_b64 v[50:51], 7, v[94:95]
	v_lshl_add_u64 v[50:51], s[22:23], 0, v[50:51]
	s_waitcnt lgkmcnt(0)
	v_add_f32_e32 v48, v48, v49
	global_store_dword v[50:51], v48, off
.LBB0_1311:
	s_or_b64 exec, exec, s[24:25]
	v_pk_add_f32 v[44:45], v[44:45], 0 op_sel_hi:[1,0]
	s_waitcnt vmcnt(7)
	v_lshlrev_b32_e32 v50, 16, v84
	v_add_f32_e32 v44, v44, v50
	v_and_b32_e32 v50, 0xffff0000, v84
	v_pk_add_f32 v[46:47], v[46:47], 0 op_sel_hi:[1,0]
	v_add_f32_e32 v45, v45, v50
	v_lshlrev_b32_e32 v50, 16, v85
	v_add_f32_e32 v46, v46, v50
	v_and_b32_e32 v50, 0xffff0000, v85
	v_pk_add_f32 v[40:41], v[40:41], 0 op_sel_hi:[1,0]
	v_add_f32_e32 v47, v47, v50
	v_lshlrev_b32_e32 v50, 16, v86
	v_add_f32_e32 v50, v40, v50
	v_and_b32_e32 v40, 0xffff0000, v86
	v_pk_add_f32 v[42:43], v[42:43], 0 op_sel_hi:[1,0]
	v_add_f32_e32 v51, v41, v40
	v_lshlrev_b32_e32 v40, 16, v87
	v_add_f32_e32 v52, v42, v40
	v_and_b32_e32 v40, 0xffff0000, v87
	v_add_f32_e32 v43, v43, v40
	v_mul_f32_e32 v40, v45, v45
	v_mul_f32_e32 v41, v47, v47
	v_fmac_f32_e32 v40, v44, v44
	v_fmac_f32_e32 v41, v46, v46
	v_add_f32_e32 v40, v40, v41
	v_mul_f32_e32 v41, v51, v51
	v_fmac_f32_e32 v41, v50, v50
	v_add_f32_e32 v40, v41, v40
	v_mul_f32_e32 v41, v43, v43
	v_fmac_f32_e32 v41, v52, v52
	v_add_f32_e32 v53, v41, v40
	v_cvt_pk_bf16_f32 v40, v44, v45
	v_pk_add_f32 v[36:37], v[36:37], 0 op_sel_hi:[1,0]
	s_waitcnt vmcnt(6)
	v_lshlrev_b32_e32 v44, 16, v80
	v_add_f32_e32 v36, v36, v44
	v_and_b32_e32 v44, 0xffff0000, v80
	v_pk_add_f32 v[38:39], v[38:39], 0 op_sel_hi:[1,0]
	v_add_f32_e32 v37, v37, v44
	v_lshlrev_b32_e32 v44, 16, v81
	v_add_f32_e32 v44, v38, v44
	v_and_b32_e32 v38, 0xffff0000, v81
	v_pk_add_f32 v[32:33], v[32:33], 0 op_sel_hi:[1,0]
	v_add_f32_e32 v45, v39, v38
	v_lshlrev_b32_e32 v38, 16, v82
	v_cvt_pk_bf16_f32 v41, v46, v47
	v_add_f32_e32 v46, v32, v38
	v_and_b32_e32 v32, 0xffff0000, v82
	v_pk_add_f32 v[34:35], v[34:35], 0 op_sel_hi:[1,0]
	v_add_f32_e32 v47, v33, v32
	v_lshlrev_b32_e32 v32, 16, v83
	v_cvt_pk_bf16_f32 v42, v50, v51
	v_add_f32_e32 v50, v34, v32
	v_and_b32_e32 v32, 0xffff0000, v83
	v_add_f32_e32 v51, v35, v32
	v_mul_f32_e32 v32, v37, v37
	v_mul_f32_e32 v33, v45, v45
	v_fmac_f32_e32 v32, v36, v36
	v_fmac_f32_e32 v33, v44, v44
	v_add_f32_e32 v32, v32, v33
	v_mul_f32_e32 v33, v47, v47
	v_fmac_f32_e32 v33, v46, v46
	v_add_f32_e32 v32, v33, v32
	v_mul_f32_e32 v33, v51, v51
	v_fmac_f32_e32 v33, v50, v50
	v_add_f32_e32 v32, v33, v32
	v_add_f32_e32 v35, v53, v32
	v_cvt_pk_bf16_f32 v43, v52, v43
	ds_bpermute_b32 v52, v171, v35
	s_waitcnt lgkmcnt(1)
	v_lshlrev_b64 v[48:49], 11, v[92:93]
	v_lshl_add_u64 v[32:33], v[48:49], 1, s[8:9]
	v_lshl_add_u64 v[38:39], v[152:153], 1, v[32:33]
	global_store_dwordx4 v[38:39], v[40:43], off sc0 sc1
	s_waitcnt lgkmcnt(0)
	v_add_f32_e32 v32, v35, v52
	ds_bpermute_b32 v33, v172, v32
	v_cvt_pk_bf16_f32 v34, v36, v37
	v_cvt_pk_bf16_f32 v35, v44, v45
	v_cvt_pk_bf16_f32 v36, v46, v47
	v_cvt_pk_bf16_f32 v37, v50, v51
	global_store_dwordx4 v[38:39], v[34:37], off offset:256 sc0 sc1
	s_and_saveexec_b64 s[24:25], s[10:11]
	s_cbranch_execz .LBB0_1313
	v_lshlrev_b64 v[34:35], 7, v[92:93]
	v_lshl_add_u64 v[34:35], s[22:23], 0, v[34:35]
	s_waitcnt lgkmcnt(0)
	v_add_f32_e32 v32, v32, v33
	global_store_dword v[34:35], v32, off
; __device__ __forceinline__ unsigned cvt_pk_bf16(float lo, float hi) { unsigned r; asm volatile("v_cvt_pk_bf16_f32 %0, %1, %2" : "=v"(r) : "v"(lo), "v"(hi)); return r; }
;     __device__ __forceinline__ void operator()(const f32x4 (&acc)[2][2][4][2], const Unit& u, int wr, int wc, int fr, int fq) const {
;     ...
;             for (int m = 0; m < 4; ++m) { const int row = row0 + ai * HALF + m * 16; float ss = 0.f;
; #pragma unroll
;                 for (int bj = 0; bj < 2; ++bj) { const u32x4 ow = old[m][bj];
;                     f32x4 v0 = (acc[ai][bj][m][0] + bv[bj][0]) * accs, v1 = (acc[ai][bj][m][1] + bv[bj][1]) * accs;
;                     v0[0] += __uint_as_float(ow.x << 16); v0[1] += __uint_as_float(ow.x & 0xffff0000u); v0[2] += __uint_as_float(ow.y << 16); v0[3] += __uint_as_float(ow.y & 0xffff0000u);
;                     v1[0] += __uint_as_float(ow.z << 16); v1[1] += __uint_as_float(ow.z & 0xffff0000u); v1[2] += __uint_as_float(ow.w << 16); v1[3] += __uint_as_float(ow.w & 0xffff0000u);
;                     ss += (v0[0] * v0[0] + v0[1] * v0[1]) + (v0[2] * v0[2] + v0[3] * v0[3]) + (v1[0] * v1[0] + v1[1] * v1[1]) + (v1[2] * v1[2] + v1[3] * v1[3]);
;                     u32x4 w; w.x = cvt_pk_bf16(v0[0], v0[1]); w.y = cvt_pk_bf16(v0[2], v0[3]); w.z = cvt_pk_bf16(v1[0], v1[1]); w.w = cvt_pk_bf16(v1[2], v1[3]);
;                     *(u32x4*)(HB + (size_t)row * ldc + col0 + bj * HALF) = w; }
;                 ss += __shfl_xor(ss, 16); ss += __shfl_xor(ss, 32);
;                 if (fq == 0) ssp[(size_t)row * 32] = ss; }
.LBB0_1313:
	s_or_b64 exec, exec, s[24:25]
	v_pk_add_f32 v[28:29], v[28:29], 0 op_sel_hi:[1,0]
	s_waitcnt vmcnt(7)
	v_lshlrev_b32_e32 v34, 16, v76
	v_add_f32_e32 v28, v28, v34
	v_and_b32_e32 v34, 0xffff0000, v76
	v_pk_add_f32 v[30:31], v[30:31], 0 op_sel_hi:[1,0]
	v_add_f32_e32 v29, v29, v34
	v_lshlrev_b32_e32 v34, 16, v77
	v_add_f32_e32 v30, v30, v34
	v_and_b32_e32 v34, 0xffff0000, v77
	v_pk_add_f32 v[24:25], v[24:25], 0 op_sel_hi:[1,0]
	v_add_f32_e32 v31, v31, v34
	v_lshlrev_b32_e32 v34, 16, v78
	v_add_f32_e32 v34, v24, v34
	v_and_b32_e32 v24, 0xffff0000, v78
	v_pk_add_f32 v[26:27], v[26:27], 0 op_sel_hi:[1,0]
	v_add_f32_e32 v35, v25, v24
	v_lshlrev_b32_e32 v24, 16, v79
	v_add_f32_e32 v36, v26, v24
	v_and_b32_e32 v24, 0xffff0000, v79
	v_add_f32_e32 v27, v27, v24
	v_mul_f32_e32 v24, v29, v29
	v_mul_f32_e32 v25, v31, v31
	v_fmac_f32_e32 v24, v28, v28
	v_fmac_f32_e32 v25, v30, v30
	v_add_f32_e32 v24, v24, v25
	v_mul_f32_e32 v25, v35, v35
	v_fmac_f32_e32 v25, v34, v34
	v_add_f32_e32 v24, v25, v24
	v_mul_f32_e32 v25, v27, v27
	v_fmac_f32_e32 v25, v36, v36
	v_add_f32_e32 v37, v25, v24
	v_cvt_pk_bf16_f32 v24, v28, v29
	v_pk_add_f32 v[20:21], v[20:21], 0 op_sel_hi:[1,0]
	s_waitcnt vmcnt(6)
	v_lshlrev_b32_e32 v28, 16, v72
	v_add_f32_e32 v20, v20, v28
	v_and_b32_e32 v28, 0xffff0000, v72
	v_pk_add_f32 v[22:23], v[22:23], 0 op_sel_hi:[1,0]
	v_add_f32_e32 v21, v21, v28
	v_lshlrev_b32_e32 v28, 16, v73
	v_add_f32_e32 v28, v22, v28
	v_and_b32_e32 v22, 0xffff0000, v73
	v_pk_add_f32 v[16:17], v[16:17], 0 op_sel_hi:[1,0]
	v_add_f32_e32 v29, v23, v22
	v_lshlrev_b32_e32 v22, 16, v74
	v_cvt_pk_bf16_f32 v25, v30, v31
	v_add_f32_e32 v30, v16, v22
	v_and_b32_e32 v16, 0xffff0000, v74
	v_pk_add_f32 v[18:19], v[18:19], 0 op_sel_hi:[1,0]
	v_add_f32_e32 v31, v17, v16
	v_lshlrev_b32_e32 v16, 16, v75
	v_cvt_pk_bf16_f32 v26, v34, v35
	v_add_f32_e32 v34, v18, v16
	v_and_b32_e32 v16, 0xffff0000, v75
	v_add_f32_e32 v35, v19, v16
	v_mul_f32_e32 v16, v21, v21
	v_mul_f32_e32 v17, v29, v29
	v_fmac_f32_e32 v16, v20, v20
	v_fmac_f32_e32 v17, v28, v28
	v_add_f32_e32 v16, v16, v17
	v_mul_f32_e32 v17, v31, v31
	v_fmac_f32_e32 v17, v30, v30
	v_add_f32_e32 v16, v17, v16
	v_mul_f32_e32 v17, v35, v35
	v_fmac_f32_e32 v17, v34, v34
	v_add_f32_e32 v16, v17, v16
	v_add_f32_e32 v19, v37, v16
	v_cvt_pk_bf16_f32 v27, v36, v27
	ds_bpermute_b32 v36, v171, v19
	s_waitcnt lgkmcnt(1)
	v_lshlrev_b64 v[32:33], 11, v[90:91]
	v_lshl_add_u64 v[16:17], v[32:33], 1, s[8:9]
	v_lshl_add_u64 v[22:23], v[152:153], 1, v[16:17]
	global_store_dwordx4 v[22:23], v[24:27], off sc0 sc1
	s_waitcnt lgkmcnt(0)
	v_add_f32_e32 v16, v19, v36
	ds_bpermute_b32 v17, v172, v16
	v_cvt_pk_bf16_f32 v18, v20, v21
	v_cvt_pk_bf16_f32 v19, v28, v29
	v_cvt_pk_bf16_f32 v20, v30, v31
	v_cvt_pk_bf16_f32 v21, v34, v35
	global_store_dwordx4 v[22:23], v[18:21], off offset:256 sc0 sc1
	s_and_saveexec_b64 s[24:25], s[10:11]
	s_cbranch_execz .LBB0_1315
	v_lshlrev_b64 v[18:19], 7, v[90:91]
	v_lshl_add_u64 v[18:19], s[22:23], 0, v[18:19]
	s_waitcnt lgkmcnt(0)
	v_add_f32_e32 v16, v16, v17
	global_store_dword v[18:19], v16, off
.LBB0_1315:
	s_or_b64 exec, exec, s[24:25]
	v_pk_add_f32 v[12:13], v[12:13], 0 op_sel_hi:[1,0]
	s_waitcnt vmcnt(7)
	v_lshlrev_b32_e32 v18, 16, v68
	v_add_f32_e32 v12, v12, v18
	v_and_b32_e32 v18, 0xffff0000, v68
	v_pk_add_f32 v[14:15], v[14:15], 0 op_sel_hi:[1,0]
	v_add_f32_e32 v13, v13, v18
	v_lshlrev_b32_e32 v18, 16, v69
	v_add_f32_e32 v14, v14, v18
	v_and_b32_e32 v18, 0xffff0000, v69
	v_pk_add_f32 v[8:9], v[8:9], 0 op_sel_hi:[1,0]
	v_add_f32_e32 v15, v15, v18
	v_lshlrev_b32_e32 v18, 16, v70
	v_add_f32_e32 v18, v8, v18
	v_and_b32_e32 v8, 0xffff0000, v70
	v_pk_add_f32 v[10:11], v[10:11], 0 op_sel_hi:[1,0]
	v_add_f32_e32 v19, v9, v8
	v_lshlrev_b32_e32 v8, 16, v71
	v_add_f32_e32 v20, v10, v8
	v_and_b32_e32 v8, 0xffff0000, v71
	v_add_f32_e32 v11, v11, v8
	v_mul_f32_e32 v8, v13, v13
	v_mul_f32_e32 v9, v15, v15
	v_fmac_f32_e32 v8, v12, v12
	v_fmac_f32_e32 v9, v14, v14
	v_add_f32_e32 v8, v8, v9
	v_mul_f32_e32 v9, v19, v19
	v_fmac_f32_e32 v9, v18, v18
	v_add_f32_e32 v8, v9, v8
	v_mul_f32_e32 v9, v11, v11
	v_fmac_f32_e32 v9, v20, v20
	v_add_f32_e32 v21, v9, v8
	v_cvt_pk_bf16_f32 v8, v12, v13
	v_pk_add_f32 v[4:5], v[4:5], 0 op_sel_hi:[1,0]
	s_waitcnt vmcnt(6)
	v_lshlrev_b32_e32 v12, 16, v64
	v_add_f32_e32 v4, v4, v12
	v_and_b32_e32 v12, 0xffff0000, v64
	v_pk_add_f32 v[6:7], v[6:7], 0 op_sel_hi:[1,0]
	v_add_f32_e32 v5, v5, v12
	v_lshlrev_b32_e32 v12, 16, v65
	v_add_f32_e32 v12, v6, v12
	v_and_b32_e32 v6, 0xffff0000, v65
	v_pk_add_f32 v[0:1], v[0:1], 0 op_sel_hi:[1,0]
	v_add_f32_e32 v13, v7, v6
	v_lshlrev_b32_e32 v6, 16, v66
	v_cvt_pk_bf16_f32 v9, v14, v15
	v_add_f32_e32 v14, v0, v6
	v_and_b32_e32 v0, 0xffff0000, v66
	v_pk_add_f32 v[2:3], v[2:3], 0 op_sel_hi:[1,0]
	v_add_f32_e32 v15, v1, v0
	v_lshlrev_b32_e32 v0, 16, v67
	v_cvt_pk_bf16_f32 v10, v18, v19
	v_add_f32_e32 v18, v2, v0
	v_and_b32_e32 v0, 0xffff0000, v67
	v_add_f32_e32 v19, v3, v0
	v_mul_f32_e32 v0, v5, v5
	v_mul_f32_e32 v1, v13, v13
	v_fmac_f32_e32 v0, v4, v4
	v_fmac_f32_e32 v1, v12, v12
	v_add_f32_e32 v0, v0, v1
	v_mul_f32_e32 v1, v15, v15
	v_fmac_f32_e32 v1, v14, v14
	v_add_f32_e32 v0, v1, v0
	v_mul_f32_e32 v1, v19, v19
	v_fmac_f32_e32 v1, v18, v18
	v_add_f32_e32 v0, v1, v0
	v_add_f32_e32 v3, v21, v0
	v_cvt_pk_bf16_f32 v11, v20, v11
	ds_bpermute_b32 v20, v171, v3
	s_waitcnt lgkmcnt(1)
	v_lshlrev_b64 v[16:17], 11, v[88:89]
	v_lshl_add_u64 v[0:1], v[16:17], 1, s[8:9]
	v_lshl_add_u64 v[6:7], v[152:153], 1, v[0:1]
	global_store_dwordx4 v[6:7], v[8:11], off sc0 sc1
	s_waitcnt lgkmcnt(0)
	v_add_f32_e32 v0, v3, v20
	ds_bpermute_b32 v1, v172, v0
	v_cvt_pk_bf16_f32 v2, v4, v5
	v_cvt_pk_bf16_f32 v3, v12, v13
	v_cvt_pk_bf16_f32 v4, v14, v15
	v_cvt_pk_bf16_f32 v5, v18, v19
	global_store_dwordx4 v[6:7], v[2:5], off offset:256 sc0 sc1
	s_and_saveexec_b64 s[24:25], s[10:11]
	s_cbranch_execz .LBB0_1317
	v_lshlrev_b64 v[2:3], 7, v[88:89]
	v_lshl_add_u64 v[2:3], s[22:23], 0, v[2:3]
	s_waitcnt lgkmcnt(0)
	v_add_f32_e32 v0, v0, v1
	global_store_dword v[2:3], v0, off

; __device__ __forceinline__ unsigned cvt_pk_bf16(float lo, float hi) { unsigned r; asm volatile("v_cvt_pk_bf16_f32 %0, %1, %2" : "=v"(r) : "v"(lo), "v"(hi)); return r; }
; __device__ __forceinline__ float row_ss(const float* part, int row, int fq, int nf4) {
;     const f32x4* p = (const f32x4*)(part + (size_t)row * 32);
;     float s = 0.f;
; #pragma unroll
;     for (int j = 0; j < 2; ++j) { const int idx = fq + 4 * j; if (idx < nf4) { const f32x4 v = p[idx]; s += (v[0] + v[1]) + (v[2] + v[3]); } }
;     s += __shfl_xor(s, 16); s += __shfl_xor(s, 32);
;     return s;
;     __device__ __forceinline__ void operator()(const f32x4 (&acc)[2][2][4][2], const Unit& u, int wr, int wc, int fr, int fq) const {
;     ...
;         for (int ai = 0; ai < 2; ++ai)
; #pragma unroll
;             for (int m = 0; m < 4; ++m) { const int row = row0 + ai * HALF + m * 16; bf16_t* rowp = base + (size_t)row * ldc + col0;
;                 const float rs = rss ? __builtin_amdgcn_rsqf(row_ss(rss, row, fq, nf4) * rinv + 1e-6f) : 1.f;
; #pragma unroll
;                 for (int bj = 0; bj < 2; ++bj) { f32x4 v0 = acc[ai][bj][m][0] * rs + bv[bj][0], v1 = acc[ai][bj][m][1] * rs + bv[bj][1];
;                     v0 = v0 * sc; v1 = v1 * sc; u32x4 w; w.x = cvt_pk_bf16(v0[0], v0[1]); w.y = cvt_pk_bf16(v0[2], v0[3]); w.z = cvt_pk_bf16(v1[0], v1[1]); w.w = cvt_pk_bf16(v1[2], v1[3]);
;                     *(u32x4*)(rowp + bj * HALF) = w; } }
.LBB0_1393:
	v_lshl_add_u32 v162, s28, 8, v165
	v_ashrrev_i32_e32 v163, 31, v162
	v_lshlrev_b64 v[166:167], 7, v[162:163]
	v_lshl_add_u64 v[166:167], v[152:153], 0, v[166:167]
	global_load_dwordx4 v[178:181], v[166:167], off
	global_load_dwordx4 v[182:185], v[166:167], off offset:64
	v_and_b32_e32 v166, 64, v173
	v_xor_b32_e32 v164, 16, v173
	v_add_u32_e32 v166, 64, v166
	v_xor_b32_e32 v167, 32, v173
	v_or_b32_e32 v186, 16, v162
	v_cmp_lt_i32_e32 vcc, v164, v166
	v_lshlrev_b64 v[188:189], 12, v[162:163]
	v_ashrrev_i32_e32 v187, 31, v186
	v_cndmask_b32_e32 v163, v173, v164, vcc
	v_cmp_lt_i32_e32 vcc, v167, v166
	v_lshlrev_b32_e32 v176, 2, v163
	s_ashr_i32 s12, s6, 31
	v_cndmask_b32_e32 v164, v173, v167, vcc
	v_lshlrev_b64 v[166:167], 7, v[186:187]
	v_lshl_add_u64 v[190:191], v[152:153], 0, v[166:167]
	v_lshlrev_b32_e32 v163, 2, v164
	s_lshr_b32 s12, s12, 29
	s_add_i32 s12, s6, s12
	s_ashr_i32 s21, s12, 3
	s_mul_i32 s12, s21, 0x3000000
	s_mul_hi_i32 s13, s21, 0x3000000
	s_add_u32 s12, s44, s12
	s_addc_u32 s13, s45, s13
	s_lshl_b32 s21, s21, 11
	s_add_i32 s6, s6, 7
	s_sub_i32 s7, s7, s21
	s_cmp_lt_u32 s6, 15
	s_cselect_b64 vcc, -1, 0
	s_waitcnt vmcnt(0)
	v_mov_b32_e32 v166, v178
	v_mov_b32_e32 v167, v182
	v_mov_b32_e32 v182, v179
	v_mov_b32_e32 v178, v180
	v_mov_b32_e32 v179, v184
	v_mov_b32_e32 v184, v181
	v_pk_add_f32 v[166:167], v[166:167], v[182:183]
	v_pk_add_f32 v[178:179], v[178:179], v[184:185]
	s_nop 0
	v_pk_add_f32 v[166:167], v[166:167], v[178:179]
	s_nop 0
	v_add_f32_e32 v164, 0, v166
	v_add_f32_e32 v164, v164, v167
	ds_bpermute_b32 v166, v176, v164
	s_waitcnt lgkmcnt(0)
	v_add_f32_e32 v167, v164, v166
	ds_bpermute_b32 v177, v163, v167
	v_or_b32_e32 v166, s7, v169
	v_cndmask_b32_e32 v164, 1.0, v175, vcc
	s_andn2_b64 vcc, exec, s[10:11]
	s_mov_b64 s[10:11], -1
	s_waitcnt lgkmcnt(0)
	v_add_f32_e32 v167, v167, v177
	v_fmamk_f32 v167, v167, 0x3a000000, v174
	v_rsq_f32_e32 v178, v167
	v_ashrrev_i32_e32 v167, 31, v166
	v_lshl_add_u64 v[166:167], v[166:167], 1, s[12:13]
	v_lshl_add_u64 v[180:181], v[166:167], 0, v[188:189]
	v_pk_fma_f32 v[140:141], v[140:141], v[178:179], v[108:109] op_sel_hi:[1,0,1]
	v_pk_fma_f32 v[142:143], v[142:143], v[178:179], v[110:111] op_sel_hi:[1,0,1]
	v_pk_fma_f32 v[136:137], v[136:137], v[178:179], v[104:105] op_sel_hi:[1,0,1]
	v_pk_fma_f32 v[138:139], v[138:139], v[178:179], v[106:107] op_sel_hi:[1,0,1]
	v_pk_fma_f32 v[128:129], v[128:129], v[178:179], v[120:121] op_sel_hi:[1,0,1]
	v_pk_fma_f32 v[130:131], v[130:131], v[178:179], v[122:123] op_sel_hi:[1,0,1]
	v_pk_fma_f32 v[132:133], v[132:133], v[178:179], v[124:125] op_sel_hi:[1,0,1]
	v_pk_fma_f32 v[134:135], v[134:135], v[178:179], v[126:127] op_sel_hi:[1,0,1]
	v_pk_mul_f32 v[142:143], v[164:165], v[142:143] op_sel_hi:[0,1]
	v_pk_mul_f32 v[140:141], v[164:165], v[140:141] op_sel_hi:[0,1]
	v_pk_mul_f32 v[138:139], v[164:165], v[138:139] op_sel_hi:[0,1]
	v_pk_mul_f32 v[136:137], v[164:165], v[136:137] op_sel_hi:[0,1]
	v_pk_mul_f32 v[178:179], v[164:165], v[130:131] op_sel_hi:[0,1]
	v_pk_mul_f32 v[182:183], v[164:165], v[128:129] op_sel_hi:[0,1]
	v_cvt_pk_bf16_f32 v128, v140, v141
	v_cvt_pk_bf16_f32 v129, v142, v143
	v_cvt_pk_bf16_f32 v130, v136, v137
	v_cvt_pk_bf16_f32 v131, v138, v139
	v_pk_mul_f32 v[134:135], v[164:165], v[134:135] op_sel_hi:[0,1]
	v_pk_mul_f32 v[132:133], v[164:165], v[132:133] op_sel_hi:[0,1]
	global_store_dwordx4 v[180:181], v[128:131], off sc0 sc1
	s_nop 1
	v_cvt_pk_bf16_f32 v128, v132, v133
	v_cvt_pk_bf16_f32 v129, v134, v135
	v_cvt_pk_bf16_f32 v130, v182, v183
	v_cvt_pk_bf16_f32 v131, v178, v179
	global_store_dwordx4 v[180:181], v[128:131], off offset:256 sc0 sc1
	global_load_dwordx4 v[128:131], v[190:191], off
	s_nop 0
	global_load_dwordx4 v[132:135], v[190:191], off offset:64
	s_waitcnt vmcnt(1)
	v_mov_b32_e32 v136, v128
	s_waitcnt vmcnt(0)
	v_mov_b32_e32 v137, v132
	v_mov_b32_e32 v132, v129
	v_mov_b32_e32 v128, v130
	v_mov_b32_e32 v129, v134
	v_mov_b32_e32 v134, v131
	v_pk_add_f32 v[130:131], v[136:137], v[132:133]
	v_pk_add_f32 v[128:129], v[128:129], v[134:135]
	s_nop 0
	v_pk_add_f32 v[128:129], v[130:131], v[128:129]
	v_lshlrev_b64 v[130:131], 12, v[186:187]
	v_add_f32_e32 v128, 0, v128
	v_add_f32_e32 v128, v128, v129
	ds_bpermute_b32 v129, v176, v128
	v_lshl_add_u64 v[130:131], v[166:167], 0, v[130:131]
	s_waitcnt lgkmcnt(0)
	v_add_f32_e32 v132, v128, v129
	ds_bpermute_b32 v133, v163, v132
	v_or_b32_e32 v128, 32, v162
	v_ashrrev_i32_e32 v129, 31, v128
	v_lshlrev_b64 v[134:135], 7, v[128:129]
	v_lshl_add_u64 v[134:135], v[152:153], 0, v[134:135]
	s_waitcnt lgkmcnt(0)
	v_add_f32_e32 v132, v132, v133
	v_fmamk_f32 v132, v132, 0x3a000000, v174
	v_rsq_f32_e32 v132, v132
	s_nop 0
	v_pk_fma_f32 v[116:117], v[116:117], v[132:133], v[108:109] op_sel_hi:[1,0,1]
	v_pk_fma_f32 v[118:119], v[118:119], v[132:133], v[110:111] op_sel_hi:[1,0,1]
	v_pk_fma_f32 v[112:113], v[112:113], v[132:133], v[104:105] op_sel_hi:[1,0,1]
	v_pk_fma_f32 v[114:115], v[114:115], v[132:133], v[106:107] op_sel_hi:[1,0,1]
	v_pk_fma_f32 v[96:97], v[96:97], v[132:133], v[120:121] op_sel_hi:[1,0,1]
	v_pk_fma_f32 v[98:99], v[98:99], v[132:133], v[122:123] op_sel_hi:[1,0,1]
	v_pk_fma_f32 v[100:101], v[100:101], v[132:133], v[124:125] op_sel_hi:[1,0,1]
	v_pk_fma_f32 v[102:103], v[102:103], v[132:133], v[126:127] op_sel_hi:[1,0,1]
	v_pk_mul_f32 v[118:119], v[164:165], v[118:119] op_sel_hi:[0,1]
	v_pk_mul_f32 v[116:117], v[164:165], v[116:117] op_sel_hi:[0,1]
	v_pk_mul_f32 v[114:115], v[164:165], v[114:115] op_sel_hi:[0,1]
	v_pk_mul_f32 v[112:113], v[164:165], v[112:113] op_sel_hi:[0,1]
	v_pk_mul_f32 v[132:133], v[164:165], v[98:99] op_sel_hi:[0,1]
	v_pk_mul_f32 v[136:137], v[164:165], v[96:97] op_sel_hi:[0,1]
	v_cvt_pk_bf16_f32 v96, v116, v117
	v_cvt_pk_bf16_f32 v97, v118, v119
	v_cvt_pk_bf16_f32 v98, v112, v113
	v_cvt_pk_bf16_f32 v99, v114, v115
	v_pk_mul_f32 v[102:103], v[164:165], v[102:103] op_sel_hi:[0,1]
	v_pk_mul_f32 v[100:101], v[164:165], v[100:101] op_sel_hi:[0,1]
	global_store_dwordx4 v[130:131], v[96:99], off sc0 sc1
	s_nop 1
	v_cvt_pk_bf16_f32 v96, v100, v101
	v_cvt_pk_bf16_f32 v97, v102, v103
	v_cvt_pk_bf16_f32 v98, v136, v137
	v_cvt_pk_bf16_f32 v99, v132, v133
	global_store_dwordx4 v[130:131], v[96:99], off offset:256 sc0 sc1
	global_load_dwordx4 v[96:99], v[134:135], off
	s_nop 0
	global_load_dwordx4 v[100:103], v[134:135], off offset:64
	s_waitcnt vmcnt(1)
; __device__ __forceinline__ unsigned cvt_pk_bf16(float lo, float hi) { unsigned r; asm volatile("v_cvt_pk_bf16_f32 %0, %1, %2" : "=v"(r) : "v"(lo), "v"(hi)); return r; }
; __device__ __forceinline__ float row_ss(const float* part, int row, int fq, int nf4) {
;     const f32x4* p = (const f32x4*)(part + (size_t)row * 32);
;     float s = 0.f;
; #pragma unroll
;     for (int j = 0; j < 2; ++j) { const int idx = fq + 4 * j; if (idx < nf4) { const f32x4 v = p[idx]; s += (v[0] + v[1]) + (v[2] + v[3]); } }
;     s += __shfl_xor(s, 16); s += __shfl_xor(s, 32);
;     return s;
;     __device__ __forceinline__ void operator()(const f32x4 (&acc)[2][2][4][2], const Unit& u, int wr, int wc, int fr, int fq) const {
;     ...
;         for (int ai = 0; ai < 2; ++ai)
; #pragma unroll
;             for (int m = 0; m < 4; ++m) { const int row = row0 + ai * HALF + m * 16; bf16_t* rowp = base + (size_t)row * ldc + col0;
;                 const float rs = rss ? __builtin_amdgcn_rsqf(row_ss(rss, row, fq, nf4) * rinv + 1e-6f) : 1.f;
; #pragma unroll
;                 for (int bj = 0; bj < 2; ++bj) { f32x4 v0 = acc[ai][bj][m][0] * rs + bv[bj][0], v1 = acc[ai][bj][m][1] * rs + bv[bj][1];
;                     v0 = v0 * sc; v1 = v1 * sc; u32x4 w; w.x = cvt_pk_bf16(v0[0], v0[1]); w.y = cvt_pk_bf16(v0[2], v0[3]); w.z = cvt_pk_bf16(v1[0], v1[1]); w.w = cvt_pk_bf16(v1[2], v1[3]);
;                     *(u32x4*)(rowp + bj * HALF) = w; } }
	v_mov_b32_e32 v112, v96
	s_waitcnt vmcnt(0)
	v_mov_b32_e32 v113, v100
	v_mov_b32_e32 v100, v97
	v_mov_b32_e32 v96, v98
	v_mov_b32_e32 v97, v102
	v_mov_b32_e32 v102, v99
	v_pk_add_f32 v[98:99], v[112:113], v[100:101]
	v_pk_add_f32 v[96:97], v[96:97], v[102:103]
	s_nop 0
	v_pk_add_f32 v[96:97], v[98:99], v[96:97]
	v_lshlrev_b64 v[98:99], 12, v[128:129]
	v_add_f32_e32 v96, 0, v96
	v_add_f32_e32 v96, v96, v97
	ds_bpermute_b32 v97, v176, v96
	v_lshl_add_u64 v[98:99], v[166:167], 0, v[98:99]
	s_waitcnt lgkmcnt(0)
	v_add_f32_e32 v100, v96, v97
	ds_bpermute_b32 v101, v163, v100
	v_or_b32_e32 v96, 48, v162
	v_ashrrev_i32_e32 v97, 31, v96
	v_lshlrev_b64 v[102:103], 7, v[96:97]
	v_lshl_add_u64 v[102:103], v[152:153], 0, v[102:103]
	s_waitcnt lgkmcnt(0)
	v_add_f32_e32 v100, v100, v101
	v_fmamk_f32 v100, v100, 0x3a000000, v174
	v_rsq_f32_e32 v100, v100
	s_nop 0
	v_pk_fma_f32 v[92:93], v[92:93], v[100:101], v[108:109] op_sel_hi:[1,0,1]
	v_pk_fma_f32 v[94:95], v[94:95], v[100:101], v[110:111] op_sel_hi:[1,0,1]
	v_pk_fma_f32 v[88:89], v[88:89], v[100:101], v[104:105] op_sel_hi:[1,0,1]
	v_pk_fma_f32 v[90:91], v[90:91], v[100:101], v[106:107] op_sel_hi:[1,0,1]
	v_pk_fma_f32 v[80:81], v[80:81], v[100:101], v[120:121] op_sel_hi:[1,0,1]
	v_pk_fma_f32 v[82:83], v[82:83], v[100:101], v[122:123] op_sel_hi:[1,0,1]
	v_pk_fma_f32 v[84:85], v[84:85], v[100:101], v[124:125] op_sel_hi:[1,0,1]
	v_pk_fma_f32 v[86:87], v[86:87], v[100:101], v[126:127] op_sel_hi:[1,0,1]
	v_pk_mul_f32 v[94:95], v[164:165], v[94:95] op_sel_hi:[0,1]
	v_pk_mul_f32 v[92:93], v[164:165], v[92:93] op_sel_hi:[0,1]
	v_pk_mul_f32 v[90:91], v[164:165], v[90:91] op_sel_hi:[0,1]
	v_pk_mul_f32 v[88:89], v[164:165], v[88:89] op_sel_hi:[0,1]
	v_pk_mul_f32 v[100:101], v[164:165], v[82:83] op_sel_hi:[0,1]
	v_pk_mul_f32 v[112:113], v[164:165], v[80:81] op_sel_hi:[0,1]
	v_cvt_pk_bf16_f32 v80, v92, v93
	v_cvt_pk_bf16_f32 v81, v94, v95
	v_cvt_pk_bf16_f32 v82, v88, v89
	v_cvt_pk_bf16_f32 v83, v90, v91
	v_pk_mul_f32 v[86:87], v[164:165], v[86:87] op_sel_hi:[0,1]
	v_pk_mul_f32 v[84:85], v[164:165], v[84:85] op_sel_hi:[0,1]
	global_store_dwordx4 v[98:99], v[80:83], off sc0 sc1
	s_nop 1
	v_cvt_pk_bf16_f32 v80, v84, v85
	v_cvt_pk_bf16_f32 v81, v86, v87
	v_cvt_pk_bf16_f32 v82, v112, v113
	v_cvt_pk_bf16_f32 v83, v100, v101
	global_store_dwordx4 v[98:99], v[80:83], off offset:256 sc0 sc1
	global_load_dwordx4 v[80:83], v[102:103], off
	s_nop 0
	global_load_dwordx4 v[84:87], v[102:103], off offset:64
	s_waitcnt vmcnt(1)
	v_mov_b32_e32 v88, v80
	s_waitcnt vmcnt(0)
	v_mov_b32_e32 v89, v84
	v_mov_b32_e32 v84, v81
	v_mov_b32_e32 v80, v82
	v_mov_b32_e32 v81, v86
	v_mov_b32_e32 v86, v83
	v_pk_add_f32 v[82:83], v[88:89], v[84:85]
	v_pk_add_f32 v[80:81], v[80:81], v[86:87]
	s_nop 0
	v_pk_add_f32 v[80:81], v[82:83], v[80:81]
	v_lshlrev_b64 v[82:83], 12, v[96:97]
	v_add_f32_e32 v80, 0, v80
	v_add_f32_e32 v80, v80, v81
	ds_bpermute_b32 v81, v176, v80
	v_lshl_add_u64 v[82:83], v[166:167], 0, v[82:83]
	s_waitcnt lgkmcnt(0)
	v_add_f32_e32 v84, v80, v81
	ds_bpermute_b32 v85, v163, v84
	v_add_u32_e32 v80, 0x80, v162
	v_ashrrev_i32_e32 v81, 31, v80
	v_lshlrev_b64 v[86:87], 7, v[80:81]
	v_lshl_add_u64 v[86:87], v[152:153], 0, v[86:87]
	s_waitcnt lgkmcnt(0)
	v_add_f32_e32 v84, v84, v85
	v_fmamk_f32 v84, v84, 0x3a000000, v174
	v_rsq_f32_e32 v84, v84
	s_nop 0
	v_pk_fma_f32 v[76:77], v[76:77], v[84:85], v[108:109] op_sel_hi:[1,0,1]
	v_pk_fma_f32 v[78:79], v[78:79], v[84:85], v[110:111] op_sel_hi:[1,0,1]
	v_pk_fma_f32 v[72:73], v[72:73], v[84:85], v[104:105] op_sel_hi:[1,0,1]
	v_pk_fma_f32 v[74:75], v[74:75], v[84:85], v[106:107] op_sel_hi:[1,0,1]
	v_pk_fma_f32 v[64:65], v[64:65], v[84:85], v[120:121] op_sel_hi:[1,0,1]
	v_pk_fma_f32 v[66:67], v[66:67], v[84:85], v[122:123] op_sel_hi:[1,0,1]
	v_pk_fma_f32 v[68:69], v[68:69], v[84:85], v[124:125] op_sel_hi:[1,0,1]
	v_pk_fma_f32 v[70:71], v[70:71], v[84:85], v[126:127] op_sel_hi:[1,0,1]
	v_pk_mul_f32 v[78:79], v[164:165], v[78:79] op_sel_hi:[0,1]
	v_pk_mul_f32 v[76:77], v[164:165], v[76:77] op_sel_hi:[0,1]
	v_pk_mul_f32 v[74:75], v[164:165], v[74:75] op_sel_hi:[0,1]
	v_pk_mul_f32 v[72:73], v[164:165], v[72:73] op_sel_hi:[0,1]
	v_pk_mul_f32 v[84:85], v[164:165], v[66:67] op_sel_hi:[0,1]
	v_pk_mul_f32 v[88:89], v[164:165], v[64:65] op_sel_hi:[0,1]
	v_cvt_pk_bf16_f32 v64, v76, v77
	v_cvt_pk_bf16_f32 v65, v78, v79
	v_cvt_pk_bf16_f32 v66, v72, v73
	v_cvt_pk_bf16_f32 v67, v74, v75
	v_pk_mul_f32 v[70:71], v[164:165], v[70:71] op_sel_hi:[0,1]
	v_pk_mul_f32 v[68:69], v[164:165], v[68:69] op_sel_hi:[0,1]
	global_store_dwordx4 v[82:83], v[64:67], off sc0 sc1
	s_nop 1
	v_cvt_pk_bf16_f32 v64, v68, v69
	v_cvt_pk_bf16_f32 v65, v70, v71
	v_cvt_pk_bf16_f32 v66, v88, v89
	v_cvt_pk_bf16_f32 v67, v84, v85
	global_store_dwordx4 v[82:83], v[64:67], off offset:256 sc0 sc1
	global_load_dwordx4 v[64:67], v[86:87], off
	s_nop 0
	global_load_dwordx4 v[68:71], v[86:87], off offset:64
	s_waitcnt vmcnt(1)
	v_mov_b32_e32 v72, v64
	s_waitcnt vmcnt(0)
	v_mov_b32_e32 v73, v68
	v_mov_b32_e32 v68, v65
	v_mov_b32_e32 v64, v66
	v_mov_b32_e32 v65, v70
	v_mov_b32_e32 v70, v67
	v_pk_add_f32 v[66:67], v[72:73], v[68:69]
	v_pk_add_f32 v[64:65], v[64:65], v[70:71]
	s_nop 0
	v_pk_add_f32 v[64:65], v[66:67], v[64:65]
	v_lshlrev_b64 v[66:67], 12, v[80:81]
	v_add_f32_e32 v64, 0, v64
	v_add_f32_e32 v64, v64, v65
	ds_bpermute_b32 v65, v176, v64
	v_lshl_add_u64 v[66:67], v[166:167], 0, v[66:67]
	s_waitcnt lgkmcnt(0)
	v_add_f32_e32 v68, v64, v65
	ds_bpermute_b32 v69, v163, v68
	v_add_u32_e32 v64, 0x90, v162
	v_ashrrev_i32_e32 v65, 31, v64
	v_lshlrev_b64 v[70:71], 7, v[64:65]
	v_lshl_add_u64 v[70:71], v[152:153], 0, v[70:71]
	s_waitcnt lgkmcnt(0)
; __device__ __forceinline__ unsigned cvt_pk_bf16(float lo, float hi) { unsigned r; asm volatile("v_cvt_pk_bf16_f32 %0, %1, %2" : "=v"(r) : "v"(lo), "v"(hi)); return r; }
; __device__ __forceinline__ float row_ss(const float* part, int row, int fq, int nf4) {
;     const f32x4* p = (const f32x4*)(part + (size_t)row * 32);
;     float s = 0.f;
; #pragma unroll
;     for (int j = 0; j < 2; ++j) { const int idx = fq + 4 * j; if (idx < nf4) { const f32x4 v = p[idx]; s += (v[0] + v[1]) + (v[2] + v[3]); } }
;     s += __shfl_xor(s, 16); s += __shfl_xor(s, 32);
;     return s;
;     __device__ __forceinline__ void operator()(const f32x4 (&acc)[2][2][4][2], const Unit& u, int wr, int wc, int fr, int fq) const {
;     ...
;         for (int ai = 0; ai < 2; ++ai)
; #pragma unroll
;             for (int m = 0; m < 4; ++m) { const int row = row0 + ai * HALF + m * 16; bf16_t* rowp = base + (size_t)row * ldc + col0;
;                 const float rs = rss ? __builtin_amdgcn_rsqf(row_ss(rss, row, fq, nf4) * rinv + 1e-6f) : 1.f;
; #pragma unroll
;                 for (int bj = 0; bj < 2; ++bj) { f32x4 v0 = acc[ai][bj][m][0] * rs + bv[bj][0], v1 = acc[ai][bj][m][1] * rs + bv[bj][1];
;                     v0 = v0 * sc; v1 = v1 * sc; u32x4 w; w.x = cvt_pk_bf16(v0[0], v0[1]); w.y = cvt_pk_bf16(v0[2], v0[3]); w.z = cvt_pk_bf16(v1[0], v1[1]); w.w = cvt_pk_bf16(v1[2], v1[3]);
;                     *(u32x4*)(rowp + bj * HALF) = w; } }
	v_add_f32_e32 v68, v68, v69
	v_fmamk_f32 v68, v68, 0x3a000000, v174
	v_rsq_f32_e32 v68, v68
	s_nop 0
	v_pk_fma_f32 v[60:61], v[60:61], v[68:69], v[108:109] op_sel_hi:[1,0,1]
	v_pk_fma_f32 v[62:63], v[62:63], v[68:69], v[110:111] op_sel_hi:[1,0,1]
	v_pk_fma_f32 v[56:57], v[56:57], v[68:69], v[104:105] op_sel_hi:[1,0,1]
	v_pk_fma_f32 v[58:59], v[58:59], v[68:69], v[106:107] op_sel_hi:[1,0,1]
	v_pk_fma_f32 v[48:49], v[48:49], v[68:69], v[120:121] op_sel_hi:[1,0,1]
	v_pk_fma_f32 v[50:51], v[50:51], v[68:69], v[122:123] op_sel_hi:[1,0,1]
	v_pk_fma_f32 v[52:53], v[52:53], v[68:69], v[124:125] op_sel_hi:[1,0,1]
	v_pk_fma_f32 v[54:55], v[54:55], v[68:69], v[126:127] op_sel_hi:[1,0,1]
	v_pk_mul_f32 v[62:63], v[164:165], v[62:63] op_sel_hi:[0,1]
	v_pk_mul_f32 v[60:61], v[164:165], v[60:61] op_sel_hi:[0,1]
	v_pk_mul_f32 v[58:59], v[164:165], v[58:59] op_sel_hi:[0,1]
	v_pk_mul_f32 v[56:57], v[164:165], v[56:57] op_sel_hi:[0,1]
	v_pk_mul_f32 v[68:69], v[164:165], v[50:51] op_sel_hi:[0,1]
	v_pk_mul_f32 v[72:73], v[164:165], v[48:49] op_sel_hi:[0,1]
	v_cvt_pk_bf16_f32 v48, v60, v61
	v_cvt_pk_bf16_f32 v49, v62, v63
	v_cvt_pk_bf16_f32 v50, v56, v57
	v_cvt_pk_bf16_f32 v51, v58, v59
	v_pk_mul_f32 v[54:55], v[164:165], v[54:55] op_sel_hi:[0,1]
	v_pk_mul_f32 v[52:53], v[164:165], v[52:53] op_sel_hi:[0,1]
	global_store_dwordx4 v[66:67], v[48:51], off sc0 sc1
	s_nop 1
	v_cvt_pk_bf16_f32 v48, v52, v53
	v_cvt_pk_bf16_f32 v49, v54, v55
	v_cvt_pk_bf16_f32 v50, v72, v73
	v_cvt_pk_bf16_f32 v51, v68, v69
	global_store_dwordx4 v[66:67], v[48:51], off offset:256 sc0 sc1
	global_load_dwordx4 v[48:51], v[70:71], off
	s_nop 0
	global_load_dwordx4 v[52:55], v[70:71], off offset:64
	s_waitcnt vmcnt(1)
	v_mov_b32_e32 v56, v48
	s_waitcnt vmcnt(0)
	v_mov_b32_e32 v57, v52
	v_mov_b32_e32 v52, v49
	v_mov_b32_e32 v48, v50
	v_mov_b32_e32 v49, v54
	v_mov_b32_e32 v54, v51
	v_pk_add_f32 v[50:51], v[56:57], v[52:53]
	v_pk_add_f32 v[48:49], v[48:49], v[54:55]
	s_nop 0
	v_pk_add_f32 v[48:49], v[50:51], v[48:49]
	v_lshlrev_b64 v[50:51], 12, v[64:65]
	v_add_f32_e32 v48, 0, v48
	v_add_f32_e32 v48, v48, v49
	ds_bpermute_b32 v49, v176, v48
	v_lshl_add_u64 v[50:51], v[166:167], 0, v[50:51]
	s_waitcnt lgkmcnt(0)
	v_add_f32_e32 v52, v48, v49
	ds_bpermute_b32 v53, v163, v52
	v_add_u32_e32 v48, 0xa0, v162
	v_ashrrev_i32_e32 v49, 31, v48
	v_lshlrev_b64 v[54:55], 7, v[48:49]
	v_lshl_add_u64 v[54:55], v[152:153], 0, v[54:55]
	s_waitcnt lgkmcnt(0)
	v_add_f32_e32 v52, v52, v53
	v_fmamk_f32 v52, v52, 0x3a000000, v174
	v_rsq_f32_e32 v52, v52
	s_nop 0
	v_pk_fma_f32 v[44:45], v[44:45], v[52:53], v[108:109] op_sel_hi:[1,0,1]
	v_pk_fma_f32 v[46:47], v[46:47], v[52:53], v[110:111] op_sel_hi:[1,0,1]
	v_pk_fma_f32 v[40:41], v[40:41], v[52:53], v[104:105] op_sel_hi:[1,0,1]
	v_pk_fma_f32 v[42:43], v[42:43], v[52:53], v[106:107] op_sel_hi:[1,0,1]
	v_pk_fma_f32 v[32:33], v[32:33], v[52:53], v[120:121] op_sel_hi:[1,0,1]
	v_pk_fma_f32 v[34:35], v[34:35], v[52:53], v[122:123] op_sel_hi:[1,0,1]
	v_pk_fma_f32 v[36:37], v[36:37], v[52:53], v[124:125] op_sel_hi:[1,0,1]
	v_pk_fma_f32 v[38:39], v[38:39], v[52:53], v[126:127] op_sel_hi:[1,0,1]
	v_pk_mul_f32 v[46:47], v[164:165], v[46:47] op_sel_hi:[0,1]
	v_pk_mul_f32 v[44:45], v[164:165], v[44:45] op_sel_hi:[0,1]
	v_pk_mul_f32 v[42:43], v[164:165], v[42:43] op_sel_hi:[0,1]
	v_pk_mul_f32 v[40:41], v[164:165], v[40:41] op_sel_hi:[0,1]
	v_pk_mul_f32 v[52:53], v[164:165], v[34:35] op_sel_hi:[0,1]
	v_pk_mul_f32 v[56:57], v[164:165], v[32:33] op_sel_hi:[0,1]
	v_cvt_pk_bf16_f32 v32, v44, v45
	v_cvt_pk_bf16_f32 v33, v46, v47
	v_cvt_pk_bf16_f32 v34, v40, v41
	v_cvt_pk_bf16_f32 v35, v42, v43
	v_pk_mul_f32 v[38:39], v[164:165], v[38:39] op_sel_hi:[0,1]
	v_pk_mul_f32 v[36:37], v[164:165], v[36:37] op_sel_hi:[0,1]
	global_store_dwordx4 v[50:51], v[32:35], off sc0 sc1
	s_nop 1
	v_cvt_pk_bf16_f32 v32, v36, v37
	v_cvt_pk_bf16_f32 v33, v38, v39
	v_cvt_pk_bf16_f32 v34, v56, v57
	v_cvt_pk_bf16_f32 v35, v52, v53
	global_store_dwordx4 v[50:51], v[32:35], off offset:256 sc0 sc1
	global_load_dwordx4 v[32:35], v[54:55], off
	s_nop 0
	global_load_dwordx4 v[36:39], v[54:55], off offset:64
	s_waitcnt vmcnt(1)
	v_mov_b32_e32 v40, v32
	s_waitcnt vmcnt(0)
; __device__ __forceinline__ unsigned cvt_pk_bf16(float lo, float hi) { unsigned r; asm volatile("v_cvt_pk_bf16_f32 %0, %1, %2" : "=v"(r) : "v"(lo), "v"(hi)); return r; }
; __device__ __forceinline__ float row_ss(const float* part, int row, int fq, int nf4) {
;     const f32x4* p = (const f32x4*)(part + (size_t)row * 32);
;     float s = 0.f;
; #pragma unroll
;     for (int j = 0; j < 2; ++j) { const int idx = fq + 4 * j; if (idx < nf4) { const f32x4 v = p[idx]; s += (v[0] + v[1]) + (v[2] + v[3]); } }
;     s += __shfl_xor(s, 16); s += __shfl_xor(s, 32);
;     return s;
;     __device__ __forceinline__ void operator()(const f32x4 (&acc)[2][2][4][2], const Unit& u, int wr, int wc, int fr, int fq) const {
;     ...
;         for (int ai = 0; ai < 2; ++ai)
; #pragma unroll
;             for (int m = 0; m < 4; ++m) { const int row = row0 + ai * HALF + m * 16; bf16_t* rowp = base + (size_t)row * ldc + col0;
;                 const float rs = rss ? __builtin_amdgcn_rsqf(row_ss(rss, row, fq, nf4) * rinv + 1e-6f) : 1.f;
; #pragma unroll
;                 for (int bj = 0; bj < 2; ++bj) { f32x4 v0 = acc[ai][bj][m][0] * rs + bv[bj][0], v1 = acc[ai][bj][m][1] * rs + bv[bj][1];
;                     v0 = v0 * sc; v1 = v1 * sc; u32x4 w; w.x = cvt_pk_bf16(v0[0], v0[1]); w.y = cvt_pk_bf16(v0[2], v0[3]); w.z = cvt_pk_bf16(v1[0], v1[1]); w.w = cvt_pk_bf16(v1[2], v1[3]);
;                     *(u32x4*)(rowp + bj * HALF) = w; } }
	v_mov_b32_e32 v41, v36
	v_mov_b32_e32 v36, v33
	v_mov_b32_e32 v32, v34
	v_mov_b32_e32 v33, v38
	v_mov_b32_e32 v38, v35
	v_pk_add_f32 v[34:35], v[40:41], v[36:37]
	v_pk_add_f32 v[32:33], v[32:33], v[38:39]
	s_nop 0
	v_pk_add_f32 v[32:33], v[34:35], v[32:33]
	v_lshlrev_b64 v[34:35], 12, v[48:49]
	v_add_f32_e32 v32, 0, v32
	v_add_f32_e32 v32, v32, v33
	ds_bpermute_b32 v33, v176, v32
	v_lshl_add_u64 v[34:35], v[166:167], 0, v[34:35]
	s_waitcnt lgkmcnt(0)
	v_add_f32_e32 v36, v32, v33
	ds_bpermute_b32 v37, v163, v36
	v_add_u32_e32 v32, 0xb0, v162
	v_ashrrev_i32_e32 v33, 31, v32
	v_lshlrev_b64 v[38:39], 7, v[32:33]
	v_lshl_add_u64 v[38:39], v[152:153], 0, v[38:39]
	s_waitcnt lgkmcnt(0)
	v_add_f32_e32 v36, v36, v37
	v_fmamk_f32 v36, v36, 0x3a000000, v174
	v_rsq_f32_e32 v36, v36
	s_nop 0
	v_pk_fma_f32 v[28:29], v[28:29], v[36:37], v[108:109] op_sel_hi:[1,0,1]
	v_pk_fma_f32 v[30:31], v[30:31], v[36:37], v[110:111] op_sel_hi:[1,0,1]
	v_pk_fma_f32 v[24:25], v[24:25], v[36:37], v[104:105] op_sel_hi:[1,0,1]
	v_pk_fma_f32 v[26:27], v[26:27], v[36:37], v[106:107] op_sel_hi:[1,0,1]
	v_pk_fma_f32 v[16:17], v[16:17], v[36:37], v[120:121] op_sel_hi:[1,0,1]
	v_pk_fma_f32 v[18:19], v[18:19], v[36:37], v[122:123] op_sel_hi:[1,0,1]
	v_pk_fma_f32 v[20:21], v[20:21], v[36:37], v[124:125] op_sel_hi:[1,0,1]
	v_pk_fma_f32 v[22:23], v[22:23], v[36:37], v[126:127] op_sel_hi:[1,0,1]
	v_pk_mul_f32 v[30:31], v[164:165], v[30:31] op_sel_hi:[0,1]
	v_pk_mul_f32 v[28:29], v[164:165], v[28:29] op_sel_hi:[0,1]
	v_pk_mul_f32 v[26:27], v[164:165], v[26:27] op_sel_hi:[0,1]
	v_pk_mul_f32 v[24:25], v[164:165], v[24:25] op_sel_hi:[0,1]
	v_pk_mul_f32 v[36:37], v[164:165], v[18:19] op_sel_hi:[0,1]
	v_pk_mul_f32 v[40:41], v[164:165], v[16:17] op_sel_hi:[0,1]
	v_cvt_pk_bf16_f32 v16, v28, v29
	v_cvt_pk_bf16_f32 v17, v30, v31
	v_cvt_pk_bf16_f32 v18, v24, v25
	v_cvt_pk_bf16_f32 v19, v26, v27
	v_pk_mul_f32 v[22:23], v[164:165], v[22:23] op_sel_hi:[0,1]
	v_pk_mul_f32 v[20:21], v[164:165], v[20:21] op_sel_hi:[0,1]
	global_store_dwordx4 v[34:35], v[16:19], off sc0 sc1
	s_nop 1
	v_cvt_pk_bf16_f32 v16, v20, v21
	v_cvt_pk_bf16_f32 v17, v22, v23
	v_cvt_pk_bf16_f32 v18, v40, v41
	v_cvt_pk_bf16_f32 v19, v36, v37
	global_store_dwordx4 v[34:35], v[16:19], off offset:256 sc0 sc1
	global_load_dwordx4 v[16:19], v[38:39], off
	s_nop 0
	global_load_dwordx4 v[20:23], v[38:39], off offset:64
	s_waitcnt vmcnt(1)
	v_mov_b32_e32 v24, v16
	s_waitcnt vmcnt(0)
	v_mov_b32_e32 v25, v20
	v_mov_b32_e32 v20, v17
	v_mov_b32_e32 v16, v18
	v_mov_b32_e32 v17, v22
	v_mov_b32_e32 v22, v19
	v_pk_add_f32 v[18:19], v[24:25], v[20:21]
	v_pk_add_f32 v[16:17], v[16:17], v[22:23]
	s_nop 0
	v_pk_add_f32 v[16:17], v[18:19], v[16:17]
	v_lshlrev_b64 v[18:19], 12, v[32:33]
	v_add_f32_e32 v16, 0, v16
	v_add_f32_e32 v16, v16, v17
	ds_bpermute_b32 v17, v176, v16
	v_lshl_add_u64 v[18:19], v[166:167], 0, v[18:19]
	s_waitcnt lgkmcnt(0)
	v_add_f32_e32 v16, v16, v17
	ds_bpermute_b32 v17, v163, v16
	s_waitcnt lgkmcnt(0)
	v_add_f32_e32 v16, v16, v17
	v_fmamk_f32 v16, v16, 0x3a000000, v174
	v_rsq_f32_e32 v16, v16
	s_nop 0
	v_pk_fma_f32 v[12:13], v[12:13], v[16:17], v[108:109] op_sel_hi:[1,0,1]
	v_pk_fma_f32 v[14:15], v[14:15], v[16:17], v[110:111] op_sel_hi:[1,0,1]
	v_pk_fma_f32 v[8:9], v[8:9], v[16:17], v[104:105] op_sel_hi:[1,0,1]
	v_pk_fma_f32 v[10:11], v[10:11], v[16:17], v[106:107] op_sel_hi:[1,0,1]
	v_pk_fma_f32 v[0:1], v[0:1], v[16:17], v[120:121] op_sel_hi:[1,0,1]
	v_pk_fma_f32 v[2:3], v[2:3], v[16:17], v[122:123] op_sel_hi:[1,0,1]
	v_pk_fma_f32 v[4:5], v[4:5], v[16:17], v[124:125] op_sel_hi:[1,0,1]
	v_pk_fma_f32 v[6:7], v[6:7], v[16:17], v[126:127] op_sel_hi:[1,0,1]
	v_pk_mul_f32 v[14:15], v[164:165], v[14:15] op_sel_hi:[0,1]
	v_pk_mul_f32 v[12:13], v[164:165], v[12:13] op_sel_hi:[0,1]
	v_pk_mul_f32 v[10:11], v[164:165], v[10:11] op_sel_hi:[0,1]
	v_pk_mul_f32 v[8:9], v[164:165], v[8:9] op_sel_hi:[0,1]
	v_pk_mul_f32 v[16:17], v[164:165], v[2:3] op_sel_hi:[0,1]
	v_pk_mul_f32 v[20:21], v[164:165], v[0:1] op_sel_hi:[0,1]
	v_cvt_pk_bf16_f32 v0, v12, v13
	v_cvt_pk_bf16_f32 v1, v14, v15
	v_cvt_pk_bf16_f32 v2, v8, v9
	v_cvt_pk_bf16_f32 v3, v10, v11
	v_pk_mul_f32 v[6:7], v[164:165], v[6:7] op_sel_hi:[0,1]
	v_pk_mul_f32 v[4:5], v[164:165], v[4:5] op_sel_hi:[0,1]
	global_store_dwordx4 v[18:19], v[0:3], off sc0 sc1
	s_nop 1
	v_cvt_pk_bf16_f32 v0, v4, v5
	v_cvt_pk_bf16_f32 v1, v6, v7
	v_cvt_pk_bf16_f32 v2, v20, v21
	v_cvt_pk_bf16_f32 v3, v16, v17
	global_store_dwordx4 v[18:19], v[0:3], off offset:256 sc0 sc1
	s_cbranch_vccnz .LBB0_1378
	s_andn2_b64 vcc, exec, s[8:9]
	s_cbranch_vccnz .LBB0_1377
	s_barrier
	s_branch .LBB0_1377

; #define LAS __attribute__((address_space(3)))
; __device__ __forceinline__ unsigned cvtpk(float lo, float hi) { f32x2 v = {lo, hi}; bf16x2_t b = __builtin_convertvector(v, bf16x2_t); return __builtin_bit_cast(unsigned, b); }
; __device__ __forceinline__ void witem_store(const WItem& w, int K, bf16_t* WT, int kvperm, LAS float* scr, int item, int nblk, int lane) {
;     ...
;     for (int i = 0; i < 8; ++i) { LAS float* d = scr + (8 * i + rr) * 33 + col; const float g = w.g[i]; d[0] = w.v[i].x * g; d[1] = w.v[i].y * g; d[2] = w.v[i].z * g; d[3] = w.v[i].w * g; }
;     asm volatile("s_waitcnt lgkmcnt(0)" ::: "memory");
;     const int c = lane & 7;
; #pragma unroll
;     for (int j = 0; j < 4; ++j) { const int n = (lane >> 3) + 8 * j; const LAS float* s = scr + (8 * c) * 33 + n;
;         u32x4 o; o.x = cvtpk(s[0 * 33], s[1 * 33]); o.y = cvtpk(s[2 * 33], s[3 * 33]); o.z = cvtpk(s[4 * 33], s[5 * 33]); o.w = cvtpk(s[6 * 33], s[7 * 33]);
;         int nr = n0 + n; if (kvperm == 1) { const int hh = nr >> 8, ww = nr & 255; nr = (ww < 128) ? hh * 128 + ww : 2048 + hh * 128 + (ww - 128); }
;         else if (kvperm == 2) { const int isv = nr >= 5632, f = isv ? nr - 5632 : nr; nr = (f >> 7) * 256 + isv * 128 + (f & 127); }
;         *(u32x4*)(WT + (size_t)nr * K + k0 + 8 * c) = o; }
.LBB0_1417:
	ds_write2_b32 v84, v4, v5 offset1:1
	ds_write2_b32 v84, v6, v7 offset0:2 offset1:3
	v_add_u32_e32 v4, 0x420, v84
	ds_write2_b32 v4, v0, v1 offset1:1
	v_add_u32_e32 v0, 0x428, v84
	ds_write2_b32 v0, v2, v3 offset1:1
	v_add_u32_e32 v0, 0x840, v84
	ds_write2_b32 v0, v12, v13 offset1:1
	v_add_u32_e32 v0, 0x848, v84
	ds_write2_b32 v0, v14, v15 offset1:1
	v_add_u32_e32 v0, 0xc60, v84
	ds_write2_b32 v0, v8, v9 offset1:1
	v_add_u32_e32 v0, 0xc68, v84
	ds_write2_b32 v0, v10, v11 offset1:1
	v_add_u32_e32 v0, 0x1080, v84
	ds_write2_b32 v0, v24, v25 offset1:1
	v_add_u32_e32 v0, 0x1088, v84
	ds_write2_b32 v0, v26, v27 offset1:1
	v_add_u32_e32 v0, 0x14a0, v84
	ds_write2_b32 v0, v16, v17 offset1:1
	v_add_u32_e32 v0, 0x14a8, v84
	ds_write2_b32 v0, v18, v19 offset1:1
	v_add_u32_e32 v0, 0x18c0, v84
	ds_write2_b32 v0, v36, v37 offset1:1
	v_add_u32_e32 v0, 0x18c8, v84
	ds_write2_b32 v0, v38, v39 offset1:1
	v_add_u32_e32 v0, 0x1ce0, v84
	ds_write2_b32 v0, v40, v41 offset1:1
	v_add_u32_e32 v0, 0x1ce8, v84
	s_ashr_i32 s12, s14, 31
	ds_write2_b32 v0, v42, v43 offset1:1
	s_lshr_b32 s12, s12, 26
	s_waitcnt lgkmcnt(0)
	s_add_i32 s12, s14, s12
	ds_read2_b32 v[4:5], v80 offset0:33 offset1:41
	ds_read2_b32 v[6:7], v80 offset1:8
	ds_read2_b32 v[8:9], v80 offset0:66 offset1:74
	ds_read2_b32 v[10:11], v80 offset0:99 offset1:107
	ds_read2_b32 v[12:13], v80 offset0:132 offset1:140
	ds_read2_b32 v[14:15], v80 offset0:165 offset1:173
	ds_read2_b32 v[16:17], v80 offset0:198 offset1:206
	ds_read2_b32 v[18:19], v80 offset0:231 offset1:239
	s_lshr_b32 s14, s12, 6
	s_andn2_b32 s12, s12, 63
	s_mul_i32 s14, s14, 0xff500000
	s_ashr_i32 s13, s12, 31
	v_add_u32_e32 v24, s14, v82
	v_lshl_add_u64 v[22:23], s[12:13], 1, v[70:71]
	v_ashrrev_i32_e32 v25, 31, v24
	s_waitcnt lgkmcnt(6)
	v_cvt_pk_bf16_f32 v0, v6, v4
	s_waitcnt lgkmcnt(4)
	v_cvt_pk_bf16_f32 v1, v8, v10
	s_waitcnt lgkmcnt(2)
	v_cvt_pk_bf16_f32 v2, v12, v14
	s_waitcnt lgkmcnt(0)
	v_cvt_pk_bf16_f32 v3, v16, v18
	v_lshl_add_u64 v[26:27], v[24:25], 1, v[22:23]
	global_store_dwordx4 v[26:27], v[0:3], off sc0 sc1
	v_add_u32_e32 v4, 0xb000, v24
	s_waitcnt vmcnt(1)
	v_mov_b64_e32 v[36:37], v[60:61]
	v_cvt_pk_bf16_f32 v0, v7, v5
	v_cvt_pk_bf16_f32 v1, v9, v11
	v_cvt_pk_bf16_f32 v2, v13, v15
	v_cvt_pk_bf16_f32 v3, v17, v19
	ds_read2_b32 v[6:7], v80 offset0:49 offset1:57
	ds_read2_b32 v[8:9], v80 offset0:16 offset1:24
	ds_read2_b32 v[10:11], v80 offset0:82 offset1:90
	ds_read2_b32 v[12:13], v80 offset0:115 offset1:123
	ds_read2_b32 v[14:15], v80 offset0:148 offset1:156
	ds_read2_b32 v[16:17], v80 offset0:181 offset1:189
	ds_read2_b32 v[18:19], v80 offset0:214 offset1:222
	ds_read2_b32 v[26:27], v80 offset0:247 offset1:255
	v_ashrrev_i32_e32 v5, 31, v4
	v_lshl_add_u64 v[4:5], v[4:5], 1, v[22:23]
	global_store_dwordx4 v[4:5], v[0:3], off sc0 sc1
	v_add_u32_e32 v4, 0x16000, v24
	v_ashrrev_i32_e32 v5, 31, v4
	s_waitcnt lgkmcnt(6)
	v_cvt_pk_bf16_f32 v0, v8, v6
	s_waitcnt lgkmcnt(4)
	v_cvt_pk_bf16_f32 v1, v10, v12
	s_waitcnt lgkmcnt(2)
	v_cvt_pk_bf16_f32 v2, v14, v16
	s_waitcnt lgkmcnt(0)
	v_cvt_pk_bf16_f32 v3, v18, v26
	v_lshl_add_u64 v[4:5], v[4:5], 1, v[22:23]
	global_store_dwordx4 v[4:5], v[0:3], off sc0 sc1
	v_add_u32_e32 v4, 0x21000, v24
	v_ashrrev_i32_e32 v5, 31, v4
	v_cvt_pk_bf16_f32 v0, v9, v7
	v_cvt_pk_bf16_f32 v1, v11, v13
	v_cvt_pk_bf16_f32 v2, v15, v17
	v_cvt_pk_bf16_f32 v3, v19, v27
	v_lshl_add_u64 v[4:5], v[4:5], 1, v[22:23]
	global_store_dwordx4 v[4:5], v[0:3], off sc0 sc1
	s_waitcnt lgkmcnt(0)
	v_mov_b64_e32 v[4:5], v[32:33]
	v_mov_b64_e32 v[12:13], v[44:45]
	v_mov_b64_e32 v[0:1], v[28:29]
	v_mov_b64_e32 v[8:9], v[48:49]
	v_mov_b64_e32 v[24:25], v[52:53]
	v_mov_b64_e32 v[16:17], v[56:57]
	v_add_u32_e32 v82, s15, v82
	s_add_i32 s16, s16, s17
	s_andn2_b64 vcc, exec, s[10:11]
	s_mov_b32 s14, s22
	v_mov_b64_e32 v[6:7], v[34:35]
	v_mov_b64_e32 v[2:3], v[30:31]
	v_mov_b64_e32 v[14:15], v[46:47]
	v_mov_b64_e32 v[10:11], v[50:51]
	v_mov_b64_e32 v[26:27], v[54:55]
	v_mov_b64_e32 v[18:19], v[58:59]
	v_mov_b64_e32 v[38:39], v[62:63]
	v_mov_b32_e32 v40, v64
	v_mov_b32_e32 v41, v65
	v_mov_b32_e32 v42, v66
	v_mov_b32_e32 v43, v67
	s_cbranch_vccz .LBB0_1435

; #define LAS __attribute__((address_space(3)))
; __device__ __forceinline__ unsigned cvtpk(float lo, float hi) { f32x2 v = {lo, hi}; bf16x2_t b = __builtin_convertvector(v, bf16x2_t); return __builtin_bit_cast(unsigned, b); }
; __device__ __forceinline__ void witem_store(const WItem& w, int K, bf16_t* WT, int kvperm, LAS float* scr, int item, int nblk, int lane) {
;     ...
;     for (int i = 0; i < 8; ++i) { LAS float* d = scr + (8 * i + rr) * 33 + col; const float g = w.g[i]; d[0] = w.v[i].x * g; d[1] = w.v[i].y * g; d[2] = w.v[i].z * g; d[3] = w.v[i].w * g; }
;     asm volatile("s_waitcnt lgkmcnt(0)" ::: "memory");
;     const int c = lane & 7;
; #pragma unroll
;     for (int j = 0; j < 4; ++j) { const int n = (lane >> 3) + 8 * j; const LAS float* s = scr + (8 * c) * 33 + n;
;         u32x4 o; o.x = cvtpk(s[0 * 33], s[1 * 33]); o.y = cvtpk(s[2 * 33], s[3 * 33]); o.z = cvtpk(s[4 * 33], s[5 * 33]); o.w = cvtpk(s[6 * 33], s[7 * 33]);
;         int nr = n0 + n; if (kvperm == 1) { const int hh = nr >> 8, ww = nr & 255; nr = (ww < 128) ? hh * 128 + ww : 2048 + hh * 128 + (ww - 128); }
;         else if (kvperm == 2) { const int isv = nr >= 5632, f = isv ? nr - 5632 : nr; nr = (f >> 7) * 256 + isv * 128 + (f & 127); }
;         *(u32x4*)(WT + (size_t)nr * K + k0 + 8 * c) = o; }
.LBB0_1454:
	v_pk_mul_f32 v[2:3], v[8:9], v[72:73] op_sel_hi:[1,0]
	ds_write2_b32 v87, v2, v3 offset1:1
	v_pk_mul_f32 v[2:3], v[10:11], v[72:73] op_sel_hi:[1,0]
	ds_write2_b32 v87, v2, v3 offset0:2 offset1:3
	v_pk_mul_f32 v[2:3], v[4:5], v[74:75] op_sel_hi:[1,0]
	v_add_u32_e32 v4, 0x420, v87
	ds_write2_b32 v4, v2, v3 offset1:1
	v_pk_mul_f32 v[2:3], v[6:7], v[74:75] op_sel_hi:[1,0]
	v_add_u32_e32 v4, 0x428, v87
	ds_write2_b32 v4, v2, v3 offset1:1
	v_pk_mul_f32 v[2:3], v[20:21], v[76:77] op_sel_hi:[1,0]
	v_add_u32_e32 v4, 0x840, v87
	ds_write2_b32 v4, v2, v3 offset1:1
	v_pk_mul_f32 v[2:3], v[22:23], v[76:77] op_sel_hi:[1,0]
	v_add_u32_e32 v4, 0x848, v87
	ds_write2_b32 v4, v2, v3 offset1:1
	v_pk_mul_f32 v[2:3], v[12:13], v[78:79] op_sel_hi:[1,0]
	v_add_u32_e32 v4, 0xc60, v87
	ds_write2_b32 v4, v2, v3 offset1:1
	v_pk_mul_f32 v[2:3], v[14:15], v[78:79] op_sel_hi:[1,0]
	v_add_u32_e32 v4, 0xc68, v87
	ds_write2_b32 v4, v2, v3 offset1:1
	v_pk_mul_f32 v[2:3], v[32:33], v[80:81] op_sel_hi:[1,0]
	v_add_u32_e32 v4, 0x1080, v87
	ds_write2_b32 v4, v2, v3 offset1:1
	v_pk_mul_f32 v[2:3], v[34:35], v[80:81] op_sel_hi:[1,0]
	v_add_u32_e32 v4, 0x1088, v87
	ds_write2_b32 v4, v2, v3 offset1:1
	v_pk_mul_f32 v[2:3], v[28:29], v[82:83] op_sel_hi:[1,0]
	v_add_u32_e32 v4, 0x14a0, v87
	ds_write2_b32 v4, v2, v3 offset1:1
	v_pk_mul_f32 v[2:3], v[30:31], v[82:83] op_sel_hi:[1,0]
	v_add_u32_e32 v4, 0x14a8, v87
	ds_write2_b32 v4, v2, v3 offset1:1
	v_pk_mul_f32 v[2:3], v[44:45], v[84:85] op_sel_hi:[1,0]
	v_add_u32_e32 v4, 0x18c0, v87
	s_mul_hi_i32 s14, s21, 0x2aaaaaab
	ds_write2_b32 v4, v2, v3 offset1:1
	v_pk_mul_f32 v[2:3], v[46:47], v[84:85] op_sel_hi:[1,0]
	v_add_u32_e32 v4, 0x18c8, v87
	s_lshr_b32 s15, s14, 31
	s_ashr_i32 s14, s14, 5
	ds_write2_b32 v4, v2, v3 offset1:1
	v_pk_mul_f32 v[2:3], v[36:37], v[86:87] op_sel_hi:[1,0]
	v_add_u32_e32 v4, 0x1ce0, v87
	s_add_i32 s21, s14, s15
	ds_write2_b32 v4, v2, v3 offset1:1
	v_pk_mul_f32 v[2:3], v[38:39], v[86:87] op_sel_hi:[1,0]
	v_add_u32_e32 v4, 0x1ce8, v87
	s_lshl_b32 s14, s21, 6
	ds_write2_b32 v4, v2, v3 offset1:1
	s_waitcnt lgkmcnt(0)
	s_ashr_i32 s15, s14, 31
	ds_read2_b32 v[6:7], v85 offset0:33 offset1:41
	ds_read2_b32 v[8:9], v85 offset1:8
	ds_read2_b32 v[10:11], v85 offset0:66 offset1:74
	ds_read2_b32 v[12:13], v85 offset0:99 offset1:107
	ds_read2_b32 v[14:15], v85 offset0:132 offset1:140
	ds_read2_b32 v[20:21], v85 offset0:165 offset1:173
	ds_read2_b32 v[22:23], v85 offset0:198 offset1:206
	ds_read2_b32 v[28:29], v85 offset0:231 offset1:239
	v_lshl_add_u64 v[30:31], s[14:15], 1, v[70:71]
	s_mul_i32 s14, s21, 0xffffe800
	s_add_i32 s14, s14, s22
	v_add_u32_e32 v32, s14, v94
	v_ashrrev_i32_e32 v33, 31, v32
	v_lshlrev_b64 v[34:35], 12, v[32:33]
	s_waitcnt lgkmcnt(6)
	v_cvt_pk_bf16_f32 v2, v8, v6
	s_waitcnt lgkmcnt(4)
	v_cvt_pk_bf16_f32 v3, v10, v12
	s_waitcnt lgkmcnt(2)
	v_cvt_pk_bf16_f32 v4, v14, v20
	s_waitcnt lgkmcnt(0)
	v_cvt_pk_bf16_f32 v5, v22, v28
	v_lshl_add_u64 v[34:35], v[30:31], 0, v[34:35]
	v_add_u32_e32 v6, 8, v32
	global_store_dwordx4 v[34:35], v[2:5], off sc0 sc1
	s_waitcnt vmcnt(3)
	v_mov_b64_e32 v[44:45], v[60:61]
	s_waitcnt vmcnt(2)
	v_mov_b64_e32 v[36:37], v[64:65]
	v_cvt_pk_bf16_f32 v2, v9, v7
	v_ashrrev_i32_e32 v7, 31, v6
	v_cvt_pk_bf16_f32 v3, v11, v13
	v_cvt_pk_bf16_f32 v4, v15, v21
	v_cvt_pk_bf16_f32 v5, v23, v29
	v_lshlrev_b64 v[6:7], 12, v[6:7]
	ds_read2_b32 v[8:9], v85 offset0:49 offset1:57
	ds_read2_b32 v[10:11], v85 offset0:16 offset1:24
	ds_read2_b32 v[12:13], v85 offset0:82 offset1:90
	ds_read2_b32 v[14:15], v85 offset0:115 offset1:123
	ds_read2_b32 v[20:21], v85 offset0:148 offset1:156
	ds_read2_b32 v[22:23], v85 offset0:181 offset1:189
	ds_read2_b32 v[28:29], v85 offset0:214 offset1:222
	ds_read2_b32 v[34:35], v85 offset0:247 offset1:255
	v_lshl_add_u64 v[6:7], v[30:31], 0, v[6:7]
	global_store_dwordx4 v[6:7], v[2:5], off sc0 sc1
	v_add_u32_e32 v6, 16, v32
	v_ashrrev_i32_e32 v7, 31, v6
	v_lshlrev_b64 v[6:7], 12, v[6:7]
	s_waitcnt lgkmcnt(6)
	v_cvt_pk_bf16_f32 v2, v10, v8
	s_waitcnt lgkmcnt(4)
	v_cvt_pk_bf16_f32 v3, v12, v14
	s_waitcnt lgkmcnt(2)
	v_cvt_pk_bf16_f32 v4, v20, v22
	s_waitcnt lgkmcnt(0)
	v_cvt_pk_bf16_f32 v5, v28, v34
	v_lshl_add_u64 v[6:7], v[30:31], 0, v[6:7]
	global_store_dwordx4 v[6:7], v[2:5], off sc0 sc1
	v_add_u32_e32 v6, 24, v32
	v_ashrrev_i32_e32 v7, 31, v6
	v_lshlrev_b64 v[6:7], 12, v[6:7]
	v_cvt_pk_bf16_f32 v2, v11, v9
	v_cvt_pk_bf16_f32 v3, v13, v15
	v_cvt_pk_bf16_f32 v4, v21, v23
	v_cvt_pk_bf16_f32 v5, v29, v35
	v_lshl_add_u64 v[6:7], v[30:31], 0, v[6:7]
	global_store_dwordx4 v[6:7], v[2:5], off sc0 sc1
	s_waitcnt lgkmcnt(0)
	v_mov_b64_e32 v[8:9], v[24:25]
	v_mov_b64_e32 v[20:21], v[40:41]
	v_mov_b64_e32 v[4:5], v[16:17]
	v_mov_b64_e32 v[12:13], v[48:49]
	v_mov_b64_e32 v[32:33], v[52:53]
	v_mov_b64_e32 v[28:29], v[56:57]
	v_add_u32_e32 v94, s23, v94
	s_add_i32 s27, s27, s23
	v_add_u32_e32 v73, s23, v73
	s_andn2_b64 vcc, exec, s[12:13]
	s_mov_b32 s21, s28
	v_mov_b64_e32 v[10:11], v[26:27]
	v_mov_b64_e32 v[6:7], v[18:19]
	v_mov_b64_e32 v[22:23], v[42:43]
	v_mov_b64_e32 v[14:15], v[50:51]
	v_mov_b64_e32 v[34:35], v[54:55]
	v_mov_b64_e32 v[30:31], v[58:59]
	v_mov_b64_e32 v[46:47], v[62:63]
	v_mov_b64_e32 v[38:39], v[66:67]
	v_mov_b32_e32 v72, v89
	v_mov_b32_e32 v74, v95
	v_mov_b32_e32 v76, v96
	v_mov_b32_e32 v78, v97
	v_mov_b32_e32 v80, v98
	v_mov_b32_e32 v82, v99
	v_mov_b32_e32 v84, v100
	s_waitcnt vmcnt(4)
	v_mov_b32_e32 v86, v1
	s_cbranch_vccz .LBB0_1472

; #define LAS __attribute__((address_space(3)))
; __device__ __forceinline__ unsigned cvtpk(float lo, float hi) { f32x2 v = {lo, hi}; bf16x2_t b = __builtin_convertvector(v, bf16x2_t); return __builtin_bit_cast(unsigned, b); }
; __device__ __forceinline__ void witem_store(const WItem& w, int K, bf16_t* WT, int kvperm, LAS float* scr, int item, int nblk, int lane) {
;     ...
;     for (int i = 0; i < 8; ++i) { LAS float* d = scr + (8 * i + rr) * 33 + col; const float g = w.g[i]; d[0] = w.v[i].x * g; d[1] = w.v[i].y * g; d[2] = w.v[i].z * g; d[3] = w.v[i].w * g; }
;     asm volatile("s_waitcnt lgkmcnt(0)" ::: "memory");
;     const int c = lane & 7;
; #pragma unroll
;     for (int j = 0; j < 4; ++j) { const int n = (lane >> 3) + 8 * j; const LAS float* s = scr + (8 * c) * 33 + n;
;         u32x4 o; o.x = cvtpk(s[0 * 33], s[1 * 33]); o.y = cvtpk(s[2 * 33], s[3 * 33]); o.z = cvtpk(s[4 * 33], s[5 * 33]); o.w = cvtpk(s[6 * 33], s[7 * 33]);
;         int nr = n0 + n; if (kvperm == 1) { const int hh = nr >> 8, ww = nr & 255; nr = (ww < 128) ? hh * 128 + ww : 2048 + hh * 128 + (ww - 128); }
;         else if (kvperm == 2) { const int isv = nr >= 5632, f = isv ? nr - 5632 : nr; nr = (f >> 7) * 256 + isv * 128 + (f & 127); }
;         *(u32x4*)(WT + (size_t)nr * K + k0 + 8 * c) = o; }
.LBB0_1491:
	v_pk_mul_f32 v[2:3], v[16:17], v[72:73] op_sel_hi:[1,0]
	ds_write2_b32 v85, v2, v3 offset1:1
	v_pk_mul_f32 v[2:3], v[18:19], v[72:73] op_sel_hi:[1,0]
	ds_write2_b32 v85, v2, v3 offset0:2 offset1:3
	v_pk_mul_f32 v[2:3], v[4:5], v[74:75] op_sel_hi:[1,0]
	v_add_u32_e32 v4, 0x420, v85
	ds_write2_b32 v4, v2, v3 offset1:1
	v_pk_mul_f32 v[2:3], v[6:7], v[74:75] op_sel_hi:[1,0]
	v_add_u32_e32 v4, 0x428, v85
	ds_write2_b32 v4, v2, v3 offset1:1
	v_pk_mul_f32 v[2:3], v[24:25], v[76:77] op_sel_hi:[1,0]
	v_add_u32_e32 v4, 0x840, v85
	ds_write2_b32 v4, v2, v3 offset1:1
	v_pk_mul_f32 v[2:3], v[26:27], v[76:77] op_sel_hi:[1,0]
	v_add_u32_e32 v4, 0x848, v85
	ds_write2_b32 v4, v2, v3 offset1:1
	v_pk_mul_f32 v[2:3], v[20:21], v[78:79] op_sel_hi:[1,0]
	v_add_u32_e32 v4, 0xc60, v85
	ds_write2_b32 v4, v2, v3 offset1:1
	v_pk_mul_f32 v[2:3], v[22:23], v[78:79] op_sel_hi:[1,0]
	v_add_u32_e32 v4, 0xc68, v85
	ds_write2_b32 v4, v2, v3 offset1:1
	v_pk_mul_f32 v[2:3], v[36:37], v[80:81] op_sel_hi:[1,0]
	v_add_u32_e32 v4, 0x1080, v85
	ds_write2_b32 v4, v2, v3 offset1:1
	v_pk_mul_f32 v[2:3], v[38:39], v[80:81] op_sel_hi:[1,0]
	v_add_u32_e32 v4, 0x1088, v85
	ds_write2_b32 v4, v2, v3 offset1:1
	v_pk_mul_f32 v[2:3], v[32:33], v[82:83] op_sel_hi:[1,0]
	v_add_u32_e32 v4, 0x14a0, v85
	s_mul_hi_i32 s16, s27, 0x2e8ba2e9
	ds_write2_b32 v4, v2, v3 offset1:1
	v_pk_mul_f32 v[2:3], v[34:35], v[82:83] op_sel_hi:[1,0]
	v_add_u32_e32 v4, 0x14a8, v85
	s_lshr_b32 s17, s16, 31
	s_ashr_i32 s16, s16, 6
	ds_write2_b32 v4, v2, v3 offset1:1
	v_pk_mul_f32 v[2:3], v[52:53], v[84:85] op_sel_hi:[1,0]
	v_add_u32_e32 v4, 0x18c0, v85
	s_add_i32 s27, s16, s17
	ds_write2_b32 v4, v2, v3 offset1:1
	v_pk_mul_f32 v[2:3], v[54:55], v[84:85] op_sel_hi:[1,0]
	v_add_u32_e32 v4, 0x18c8, v85
	s_lshl_b32 s16, s27, 6
	ds_write2_b32 v4, v2, v3 offset1:1
	v_pk_mul_f32 v[2:3], v[44:45], v[86:87] op_sel_hi:[1,0]
	v_add_u32_e32 v4, 0x1ce0, v85
	ds_write2_b32 v4, v2, v3 offset1:1
	v_pk_mul_f32 v[2:3], v[46:47], v[86:87] op_sel_hi:[1,0]
	v_add_u32_e32 v4, 0x1ce8, v85
	s_ashr_i32 s17, s16, 31
	ds_write2_b32 v4, v2, v3 offset1:1
	v_lshl_add_u64 v[34:35], s[16:17], 1, v[70:71]
	s_mul_i32 s16, s27, 0xffffd400
	s_waitcnt lgkmcnt(0)
	s_add_i32 s16, s16, s22
	ds_read2_b32 v[6:7], v83 offset0:33 offset1:41
	ds_read2_b32 v[16:17], v83 offset1:8
	ds_read2_b32 v[18:19], v83 offset0:66 offset1:74
	ds_read2_b32 v[20:21], v83 offset0:99 offset1:107
	ds_read2_b32 v[22:23], v83 offset0:132 offset1:140
	ds_read2_b32 v[24:25], v83 offset0:165 offset1:173
	ds_read2_b32 v[26:27], v83 offset0:198 offset1:206
	ds_read2_b32 v[32:33], v83 offset0:231 offset1:239
	v_add_u32_e32 v38, s16, v94
	s_waitcnt lgkmcnt(6)
	v_cvt_pk_bf16_f32 v2, v16, v6
	v_add_u32_e32 v6, 0xffffea00, v38
	v_cmp_lt_i32_e32 vcc, s28, v38
	s_waitcnt lgkmcnt(4)
	v_cvt_pk_bf16_f32 v3, v18, v20
	s_waitcnt lgkmcnt(2)
	v_cvt_pk_bf16_f32 v4, v22, v24
	v_cndmask_b32_e32 v6, v38, v6, vcc
	v_lshlrev_b32_e32 v16, 1, v6
	v_and_b32_e32 v16, 0xffffff00, v16
	v_cndmask_b32_e32 v18, 0, v87, vcc
	v_and_b32_e32 v6, 0x67, v6
	v_or3_b32 v36, v6, v18, v16
	v_ashrrev_i32_e32 v37, 31, v36
	v_lshlrev_b64 v[36:37], 12, v[36:37]
	s_waitcnt lgkmcnt(0)
	v_cvt_pk_bf16_f32 v5, v26, v32
	v_lshl_add_u64 v[36:37], v[34:35], 0, v[36:37]
	v_add_u32_e32 v6, 8, v38
	global_store_dwordx4 v[36:37], v[2:5], off sc0 sc1
	v_cmp_lt_i32_e32 vcc, s28, v6
	s_waitcnt vmcnt(3)
	v_mov_b64_e32 v[52:53], v[60:61]
	v_cvt_pk_bf16_f32 v2, v17, v7
	v_add_u32_e32 v7, 0xffffea08, v38
	v_cndmask_b32_e32 v6, v6, v7, vcc
	v_lshlrev_b32_e32 v7, 1, v6
	v_and_b32_e32 v7, 0xffffff00, v7
	v_cndmask_b32_e32 v16, 0, v87, vcc
	v_and_b32_e32 v6, 0x6f, v6
	v_or3_b32 v6, v6, v16, v7
	v_ashrrev_i32_e32 v7, 31, v6
	v_lshlrev_b64 v[6:7], 12, v[6:7]
	v_cvt_pk_bf16_f32 v3, v19, v21
	v_cvt_pk_bf16_f32 v4, v23, v25
	v_cvt_pk_bf16_f32 v5, v27, v33
	v_lshl_add_u64 v[6:7], v[34:35], 0, v[6:7]
	ds_read2_b32 v[16:17], v83 offset0:16 offset1:24
	ds_read2_b32 v[18:19], v83 offset0:49 offset1:57
	ds_read2_b32 v[20:21], v83 offset0:82 offset1:90
	ds_read2_b32 v[22:23], v83 offset0:115 offset1:123
	ds_read2_b32 v[24:25], v83 offset0:148 offset1:156
	ds_read2_b32 v[26:27], v83 offset0:181 offset1:189
	ds_read2_b32 v[32:33], v83 offset0:214 offset1:222
	ds_read2_b32 v[36:37], v83 offset0:247 offset1:255
	global_store_dwordx4 v[6:7], v[2:5], off sc0 sc1
	v_add_u32_e32 v6, 16, v38
	v_add_u32_e32 v7, 0xffffea10, v38
	v_cmp_lt_i32_e32 vcc, s28, v6
	s_waitcnt lgkmcnt(6)
	v_cvt_pk_bf16_f32 v2, v16, v18
	s_waitcnt lgkmcnt(4)
	v_cvt_pk_bf16_f32 v3, v20, v22
	v_cndmask_b32_e32 v6, v6, v7, vcc
	v_lshlrev_b32_e32 v7, 1, v6
	v_and_b32_e32 v7, 0xffffff00, v7
	v_cndmask_b32_e32 v16, 0, v87, vcc
	v_and_b32_e32 v6, 0x77, v6
	v_or3_b32 v6, v6, v16, v7
	v_ashrrev_i32_e32 v7, 31, v6
	v_lshlrev_b64 v[6:7], 12, v[6:7]
	s_waitcnt lgkmcnt(2)
	v_cvt_pk_bf16_f32 v4, v24, v26
	s_waitcnt lgkmcnt(0)
	v_cvt_pk_bf16_f32 v5, v32, v36
	v_lshl_add_u64 v[6:7], v[34:35], 0, v[6:7]
	global_store_dwordx4 v[6:7], v[2:5], off sc0 sc1
	s_waitcnt vmcnt(4)
	v_mov_b64_e32 v[44:45], v[64:65]
	v_add_u32_e32 v94, s23, v94
	v_add_u32_e32 v2, 24, v38
	v_add_u32_e32 v3, 0xffffea18, v38
	v_cmp_lt_i32_e32 vcc, s28, v2
	v_cvt_pk_bf16_f32 v5, v33, v37
	v_mov_b64_e32 v[36:37], v[48:49]
	v_cndmask_b32_e32 v2, v2, v3, vcc
	v_lshlrev_b32_e32 v3, 1, v2
	v_and_b32_e32 v3, 0xffffff00, v3
	v_cndmask_b32_e32 v4, 0, v87, vcc
	v_and_b32_e32 v2, 0x7f, v2
	v_or3_b32 v6, v2, v4, v3
	v_ashrrev_i32_e32 v7, 31, v6
	v_lshlrev_b64 v[6:7], 12, v[6:7]
	v_cvt_pk_bf16_f32 v2, v17, v19
	v_cvt_pk_bf16_f32 v3, v21, v23
	v_cvt_pk_bf16_f32 v4, v25, v27
	v_lshl_add_u64 v[6:7], v[34:35], 0, v[6:7]
	global_store_dwordx4 v[6:7], v[2:5], off sc0 sc1
	s_waitcnt lgkmcnt(0)
	v_mov_b64_e32 v[18:19], v[14:15]
	v_mov_b64_e32 v[24:25], v[28:29]
	v_mov_b64_e32 v[4:5], v[8:9]
	v_mov_b64_e32 v[20:21], v[40:41]
	v_mov_b64_e32 v[32:33], v[56:57]
	s_add_i32 s29, s29, s23
	v_add_u32_e32 v73, s23, v73
	s_andn2_b64 vcc, exec, s[14:15]
	s_mov_b32 s27, s30
	v_mov_b64_e32 v[16:17], v[12:13]
	v_mov_b64_e32 v[6:7], v[10:11]
	v_mov_b64_e32 v[26:27], v[30:31]
	v_mov_b64_e32 v[22:23], v[42:43]
	v_mov_b64_e32 v[38:39], v[50:51]
	v_mov_b64_e32 v[34:35], v[58:59]
	v_mov_b64_e32 v[54:55], v[62:63]
	v_mov_b64_e32 v[46:47], v[66:67]
	v_mov_b32_e32 v72, v89
	v_mov_b32_e32 v74, v95
	v_mov_b32_e32 v76, v96
	v_mov_b32_e32 v78, v97
	v_mov_b32_e32 v80, v98
	v_mov_b32_e32 v82, v99
	v_mov_b32_e32 v84, v100
	s_waitcnt vmcnt(4)
	v_mov_b32_e32 v86, v1
	s_cbranch_vccz .LBB0_1509

; #define LAS __attribute__((address_space(3)))
; __device__ __forceinline__ unsigned cvtpk(float lo, float hi) { f32x2 v = {lo, hi}; bf16x2_t b = __builtin_convertvector(v, bf16x2_t); return __builtin_bit_cast(unsigned, b); }
; __device__ __forceinline__ void witem_store(const WItem& w, int K, bf16_t* WT, int kvperm, LAS float* scr, int item, int nblk, int lane) {
;     ...
;     for (int i = 0; i < 8; ++i) { LAS float* d = scr + (8 * i + rr) * 33 + col; const float g = w.g[i]; d[0] = w.v[i].x * g; d[1] = w.v[i].y * g; d[2] = w.v[i].z * g; d[3] = w.v[i].w * g; }
;     asm volatile("s_waitcnt lgkmcnt(0)" ::: "memory");
;     const int c = lane & 7;
; #pragma unroll
;     for (int j = 0; j < 4; ++j) { const int n = (lane >> 3) + 8 * j; const LAS float* s = scr + (8 * c) * 33 + n;
;         u32x4 o; o.x = cvtpk(s[0 * 33], s[1 * 33]); o.y = cvtpk(s[2 * 33], s[3 * 33]); o.z = cvtpk(s[4 * 33], s[5 * 33]); o.w = cvtpk(s[6 * 33], s[7 * 33]);
;         int nr = n0 + n; if (kvperm == 1) { const int hh = nr >> 8, ww = nr & 255; nr = (ww < 128) ? hh * 128 + ww : 2048 + hh * 128 + (ww - 128); }
;         else if (kvperm == 2) { const int isv = nr >= 5632, f = isv ? nr - 5632 : nr; nr = (f >> 7) * 256 + isv * 128 + (f & 127); }
;         *(u32x4*)(WT + (size_t)nr * K + k0 + 8 * c) = o; }
.LBB0_1528:
	v_pk_mul_f32 v[2:3], v[16:17], v[72:73] op_sel_hi:[1,0]
	ds_write2_b32 v79, v2, v3 offset1:1
	v_pk_mul_f32 v[2:3], v[18:19], v[72:73] op_sel_hi:[1,0]
	ds_write2_b32 v79, v2, v3 offset0:2 offset1:3
	v_pk_mul_f32 v[2:3], v[4:5], v[74:75] op_sel_hi:[1,0]
	v_add_u32_e32 v4, 0x420, v79
	ds_write2_b32 v4, v2, v3 offset1:1
	v_pk_mul_f32 v[2:3], v[6:7], v[74:75] op_sel_hi:[1,0]
	v_add_u32_e32 v4, 0x428, v79
	ds_write2_b32 v4, v2, v3 offset1:1
	v_pk_mul_f32 v[2:3], v[24:25], v[76:77] op_sel_hi:[1,0]
	v_add_u32_e32 v4, 0x840, v79
	ds_write2_b32 v4, v2, v3 offset1:1
	v_pk_mul_f32 v[2:3], v[26:27], v[76:77] op_sel_hi:[1,0]
	v_add_u32_e32 v4, 0x848, v79
	ds_write2_b32 v4, v2, v3 offset1:1
	v_pk_mul_f32 v[2:3], v[20:21], v[78:79] op_sel_hi:[1,0]
	v_add_u32_e32 v4, 0xc60, v79
	ds_write2_b32 v4, v2, v3 offset1:1
	v_pk_mul_f32 v[2:3], v[22:23], v[78:79] op_sel_hi:[1,0]
	v_add_u32_e32 v4, 0xc68, v79
	ds_write2_b32 v4, v2, v3 offset1:1
	v_pk_mul_f32 v[2:3], v[36:37], v[80:81] op_sel_hi:[1,0]
	v_add_u32_e32 v4, 0x1080, v79
	ds_write2_b32 v4, v2, v3 offset1:1
	v_pk_mul_f32 v[2:3], v[38:39], v[80:81] op_sel_hi:[1,0]
	v_add_u32_e32 v4, 0x1088, v79
	ds_write2_b32 v4, v2, v3 offset1:1
	v_pk_mul_f32 v[2:3], v[32:33], v[82:83] op_sel_hi:[1,0]
	v_add_u32_e32 v4, 0x14a0, v79
	s_mul_hi_i32 s10, s15, 0x2e8ba2e9
	ds_write2_b32 v4, v2, v3 offset1:1
	v_pk_mul_f32 v[2:3], v[34:35], v[82:83] op_sel_hi:[1,0]
	v_add_u32_e32 v4, 0x14a8, v79
	s_lshr_b32 s11, s10, 31
	s_ashr_i32 s10, s10, 6
	ds_write2_b32 v4, v2, v3 offset1:1
	s_waitcnt vmcnt(7)
	v_pk_mul_f32 v[2:3], v[52:53], v[84:85] op_sel_hi:[1,0]
	v_add_u32_e32 v4, 0x18c0, v79
	s_add_i32 s15, s10, s11
	ds_write2_b32 v4, v2, v3 offset1:1
	v_pk_mul_f32 v[2:3], v[54:55], v[84:85] op_sel_hi:[1,0]
	v_add_u32_e32 v4, 0x18c8, v79
	s_lshl_b32 s10, s15, 6
	ds_write2_b32 v4, v2, v3 offset1:1
	s_waitcnt vmcnt(6)
	v_pk_mul_f32 v[2:3], v[44:45], v[86:87] op_sel_hi:[1,0]
	v_add_u32_e32 v4, 0x1ce0, v79
	ds_write2_b32 v4, v2, v3 offset1:1
	v_pk_mul_f32 v[2:3], v[46:47], v[86:87] op_sel_hi:[1,0]
	v_add_u32_e32 v4, 0x1ce8, v79
	s_ashr_i32 s11, s10, 31
	ds_write2_b32 v4, v2, v3 offset1:1
	v_lshl_add_u64 v[34:35], s[10:11], 1, v[70:71]
	s_mul_i32 s10, s15, 0xffffd400
	s_waitcnt lgkmcnt(0)
	s_add_i32 s10, s10, s2
	ds_read2_b32 v[6:7], v75 offset0:33 offset1:41
	ds_read2_b32 v[16:17], v75 offset1:8
	ds_read2_b32 v[18:19], v75 offset0:66 offset1:74
	ds_read2_b32 v[20:21], v75 offset0:99 offset1:107
	ds_read2_b32 v[22:23], v75 offset0:132 offset1:140
	ds_read2_b32 v[24:25], v75 offset0:165 offset1:173
	ds_read2_b32 v[26:27], v75 offset0:198 offset1:206
	ds_read2_b32 v[32:33], v75 offset0:231 offset1:239
	v_add_u32_e32 v38, s10, v83
	s_waitcnt lgkmcnt(6)
	v_cvt_pk_bf16_f32 v2, v16, v6
	v_add_u32_e32 v6, 0xffffea00, v38
	v_cmp_lt_i32_e32 vcc, s14, v38
	s_waitcnt lgkmcnt(4)
	v_cvt_pk_bf16_f32 v3, v18, v20
	s_waitcnt lgkmcnt(2)
	v_cvt_pk_bf16_f32 v4, v22, v24
	v_cndmask_b32_e32 v6, v38, v6, vcc
	v_lshlrev_b32_e32 v16, 1, v6
	v_and_b32_e32 v16, 0xffffff00, v16
	v_cndmask_b32_e32 v18, 0, v81, vcc
	v_and_b32_e32 v6, 0x67, v6
	v_or3_b32 v36, v6, v18, v16
	v_ashrrev_i32_e32 v37, 31, v36
	v_lshlrev_b64 v[36:37], 12, v[36:37]
	s_waitcnt lgkmcnt(0)
	v_cvt_pk_bf16_f32 v5, v26, v32
	v_lshl_add_u64 v[36:37], v[34:35], 0, v[36:37]
	v_add_u32_e32 v6, 8, v38
	global_store_dwordx4 v[36:37], v[2:5], off sc0 sc1
	v_cmp_lt_i32_e32 vcc, s14, v6
	s_waitcnt vmcnt(3)
	v_mov_b64_e32 v[52:53], v[60:61]
	v_cvt_pk_bf16_f32 v2, v17, v7
	v_add_u32_e32 v7, 0xffffea08, v38
	v_cndmask_b32_e32 v6, v6, v7, vcc
	v_lshlrev_b32_e32 v7, 1, v6
	v_and_b32_e32 v7, 0xffffff00, v7
	v_cndmask_b32_e32 v16, 0, v81, vcc
	v_and_b32_e32 v6, 0x6f, v6
	v_or3_b32 v6, v6, v16, v7
	v_ashrrev_i32_e32 v7, 31, v6
	v_lshlrev_b64 v[6:7], 12, v[6:7]
	v_cvt_pk_bf16_f32 v3, v19, v21
	v_cvt_pk_bf16_f32 v4, v23, v25
	v_cvt_pk_bf16_f32 v5, v27, v33
	v_lshl_add_u64 v[6:7], v[34:35], 0, v[6:7]
	ds_read2_b32 v[16:17], v75 offset0:16 offset1:24
	ds_read2_b32 v[18:19], v75 offset0:49 offset1:57
	ds_read2_b32 v[20:21], v75 offset0:82 offset1:90
	ds_read2_b32 v[22:23], v75 offset0:115 offset1:123
	ds_read2_b32 v[24:25], v75 offset0:148 offset1:156
	ds_read2_b32 v[26:27], v75 offset0:181 offset1:189
	ds_read2_b32 v[32:33], v75 offset0:214 offset1:222
	ds_read2_b32 v[36:37], v75 offset0:247 offset1:255
	global_store_dwordx4 v[6:7], v[2:5], off sc0 sc1
	v_add_u32_e32 v6, 16, v38
	v_add_u32_e32 v7, 0xffffea10, v38
	v_cmp_lt_i32_e32 vcc, s14, v6
	s_waitcnt lgkmcnt(6)
	v_cvt_pk_bf16_f32 v2, v16, v18
	s_waitcnt lgkmcnt(4)
	v_cvt_pk_bf16_f32 v3, v20, v22
	v_cndmask_b32_e32 v6, v6, v7, vcc
	v_lshlrev_b32_e32 v7, 1, v6
	v_and_b32_e32 v7, 0xffffff00, v7
	v_cndmask_b32_e32 v16, 0, v81, vcc
	v_and_b32_e32 v6, 0x77, v6
	v_or3_b32 v6, v6, v16, v7
	v_ashrrev_i32_e32 v7, 31, v6
	v_lshlrev_b64 v[6:7], 12, v[6:7]
	s_waitcnt lgkmcnt(2)
	v_cvt_pk_bf16_f32 v4, v24, v26
	s_waitcnt lgkmcnt(0)
	v_cvt_pk_bf16_f32 v5, v32, v36
	v_lshl_add_u64 v[6:7], v[34:35], 0, v[6:7]
	global_store_dwordx4 v[6:7], v[2:5], off sc0 sc1
	s_waitcnt vmcnt(4)
	v_mov_b64_e32 v[44:45], v[64:65]
	v_add_u32_e32 v83, s6, v83
	v_add_u32_e32 v2, 24, v38
	v_add_u32_e32 v3, 0xffffea18, v38
	v_cmp_lt_i32_e32 vcc, s14, v2
	v_cvt_pk_bf16_f32 v5, v33, v37
	v_mov_b64_e32 v[36:37], v[48:49]
	v_cndmask_b32_e32 v2, v2, v3, vcc
	v_lshlrev_b32_e32 v3, 1, v2
	v_and_b32_e32 v3, 0xffffff00, v3
	v_cndmask_b32_e32 v4, 0, v81, vcc
	v_and_b32_e32 v2, 0x7f, v2
	v_or3_b32 v6, v2, v4, v3
	v_ashrrev_i32_e32 v7, 31, v6
	v_lshlrev_b64 v[6:7], 12, v[6:7]
	v_cvt_pk_bf16_f32 v2, v17, v19
	v_cvt_pk_bf16_f32 v3, v21, v23
	v_cvt_pk_bf16_f32 v4, v25, v27
	v_lshl_add_u64 v[6:7], v[34:35], 0, v[6:7]
	global_store_dwordx4 v[6:7], v[2:5], off sc0 sc1
	s_waitcnt lgkmcnt(0)
	v_mov_b64_e32 v[18:19], v[14:15]
	v_mov_b64_e32 v[24:25], v[28:29]
	v_mov_b64_e32 v[4:5], v[8:9]
	v_mov_b64_e32 v[20:21], v[40:41]
	v_mov_b64_e32 v[32:33], v[56:57]
	s_add_i32 s16, s16, s6
	v_add_u32_e32 v73, s6, v73
	s_andn2_b64 vcc, exec, s[0:1]
	s_mov_b32 s15, s17
	v_mov_b64_e32 v[16:17], v[12:13]
	v_mov_b64_e32 v[6:7], v[10:11]
	v_mov_b64_e32 v[26:27], v[30:31]
	v_mov_b64_e32 v[22:23], v[42:43]
	v_mov_b64_e32 v[38:39], v[50:51]
	v_mov_b64_e32 v[34:35], v[58:59]
	v_mov_b64_e32 v[54:55], v[62:63]
	v_mov_b64_e32 v[46:47], v[66:67]
	v_mov_b32_e32 v72, v85
	v_mov_b32_e32 v74, v87
	v_mov_b32_e32 v76, v89
	v_mov_b32_e32 v78, v94
	v_mov_b32_e32 v80, v95
	v_mov_b32_e32 v82, v96
	v_mov_b32_e32 v84, v97
	s_waitcnt vmcnt(4)
	v_mov_b32_e32 v86, v1
	s_cbranch_vccz .LBB0_1546

; __device__ __forceinline__ unsigned cvt_pk_bf16(float lo, float hi) { unsigned r; asm volatile("v_cvt_pk_bf16_f32 %0, %1, %2" : "=v"(r) : "v"(lo), "v"(hi)); return r; }
;     __device__ __forceinline__ void operator()(const f32x4 (&acc)[2][2][4][2], const Unit& u, int wr, int wc, int fr, int fq) const {
;         const int row0 = u.pm * BM + wr * 64 + fr, col0 = u.pn * BM + wc * 32 + 8 * fq;
;         f32x4 bv[2][2];
; #pragma unroll
;         for (int bj = 0; bj < 2; ++bj)
; #pragma unroll
;             for (int n = 0; n < 2; ++n) bv[bj][n] = bias ? *(const f32x4*)(bias + col0 + bj * HALF + 4 * n) : (f32x4){0.f, 0.f, 0.f, 0.f};
;         float* ssp = ssout + (size_t)(u.pn * 4 + wc);
; #pragma unroll
;         for (int ai = 0; ai < 2; ++ai) {
;             u32x4 old[4][2];
; #pragma unroll
;             for (int m = 0; m < 4; ++m)
; #pragma unroll
;                 for (int bj = 0; bj < 2; ++bj) old[m][bj] = *(const u32x4*)(HB + (size_t)(row0 + ai * HALF + m * 16) * ldc + col0 + bj * HALF);
; #pragma unroll
;             for (int m = 0; m < 4; ++m) { const int row = row0 + ai * HALF + m * 16; float ss = 0.f;
; #pragma unroll
;                 for (int bj = 0; bj < 2; ++bj) { const u32x4 ow = old[m][bj];
;                     f32x4 v0 = (acc[ai][bj][m][0] + bv[bj][0]) * accs, v1 = (acc[ai][bj][m][1] + bv[bj][1]) * accs;
;                     v0[0] += __uint_as_float(ow.x << 16); v0[1] += __uint_as_float(ow.x & 0xffff0000u); v0[2] += __uint_as_float(ow.y << 16); v0[3] += __uint_as_float(ow.y & 0xffff0000u);
;                     v1[0] += __uint_as_float(ow.z << 16); v1[1] += __uint_as_float(ow.z & 0xffff0000u); v1[2] += __uint_as_float(ow.w << 16); v1[3] += __uint_as_float(ow.w & 0xffff0000u);
;                     ss += (v0[0] * v0[0] + v0[1] * v0[1]) + (v0[2] * v0[2] + v0[3] * v0[3]) + (v1[0] * v1[0] + v1[1] * v1[1]) + (v1[2] * v1[2] + v1[3] * v1[3]);
;                     u32x4 w; w.x = cvt_pk_bf16(v0[0], v0[1]); w.y = cvt_pk_bf16(v0[2], v0[3]); w.z = cvt_pk_bf16(v1[0], v1[1]); w.w = cvt_pk_bf16(v1[2], v1[3]);
;                     *(u32x4*)(HB + (size_t)row * ldc + col0 + bj * HALF) = w; }
;                 ss += __shfl_xor(ss, 16); ss += __shfl_xor(ss, 32);
;                 if (fq == 0) ssp[(size_t)row * 32] = ss; }
.LBB0_1708:
	v_lshl_add_u32 v170, s38, 8, v180
	v_lshlrev_b64 v[196:197], 1, v[168:169]
	v_ashrrev_i32_e32 v171, 31, v170
	v_lshl_add_u64 v[172:173], s[18:19], 0, v[196:197]
	v_lshlrev_b64 v[198:199], 12, v[170:171]
	v_lshl_add_u64 v[144:145], v[172:173], 0, v[198:199]
	global_load_dwordx4 v[188:191], v[144:145], off
	global_load_dwordx4 v[192:195], v[144:145], off offset:256
	v_or_b32_e32 v178, 16, v170
	v_or_b32_e32 v176, 32, v170
	v_or_b32_e32 v174, 48, v170
	v_ashrrev_i32_e32 v179, 31, v178
	v_ashrrev_i32_e32 v177, 31, v176
	s_waitcnt vmcnt(0)
	v_pk_add_f32 v[214:215], v[130:131], v[94:95]
	v_pk_add_f32 v[216:217], v[128:129], v[92:93]
	v_ashrrev_i32_e32 v175, 31, v174
	v_lshlrev_b64 v[128:129], 12, v[178:179]
	v_lshlrev_b64 v[130:131], 12, v[176:177]
	v_pk_add_f32 v[212:213], v[132:133], v[100:101]
	v_lshlrev_b64 v[132:133], 12, v[174:175]
	v_lshl_add_u64 v[128:129], v[172:173], 0, v[128:129]
	v_lshl_add_u64 v[130:131], v[172:173], 0, v[130:131]
	v_pk_add_f32 v[200:201], v[142:143], v[110:111]
	v_pk_add_f32 v[202:203], v[140:141], v[108:109]
	v_pk_add_f32 v[206:207], v[138:139], v[98:99]
	v_pk_add_f32 v[208:209], v[136:137], v[96:97]
	v_pk_add_f32 v[210:211], v[134:135], v[102:103]
	v_lshl_add_u64 v[218:219], v[172:173], 0, v[132:133]
	global_load_dwordx4 v[148:151], v[128:129], off
	global_load_dwordx4 v[144:147], v[128:129], off offset:256
	global_load_dwordx4 v[140:143], v[130:131], off
	global_load_dwordx4 v[136:139], v[130:131], off offset:256
	global_load_dwordx4 v[132:135], v[218:219], off
	s_nop 0
	global_load_dwordx4 v[128:131], v[218:219], off offset:256
	s_lshl_b32 s6, s36, 2
	s_or_b32 s6, s6, s53
	s_ashr_i32 s7, s6, 31
	s_lshl_b64 s[6:7], s[6:7], 2
	s_add_u32 s14, s51, s6
	s_addc_u32 s15, s52, s7
	v_lshlrev_b32_e32 v187, 16, v188
	v_and_b32_e32 v188, 0xffff0000, v188
	v_lshlrev_b32_e32 v218, 16, v189
	v_and_b32_e32 v189, 0xffff0000, v189
	v_lshlrev_b32_e32 v219, 16, v190
	v_lshlrev_b32_e32 v220, 16, v191
	v_lshlrev_b32_e32 v221, 16, v192
	v_and_b32_e32 v192, 0xffff0000, v192
	v_lshlrev_b32_e32 v222, 16, v193
	v_and_b32_e32 v193, 0xffff0000, v193
	v_add_f32_e32 v188, v203, v188
	v_add_f32_e32 v189, v201, v189
	v_and_b32_e32 v191, 0xffff0000, v191
	v_lshlrev_b32_e32 v223, 16, v194
	v_and_b32_e32 v194, 0xffff0000, v194
	v_lshlrev_b32_e32 v224, 16, v195
	v_add_f32_e32 v187, v202, v187
	v_add_f32_e32 v200, v200, v218
	v_add_f32_e32 v201, v208, v219
	v_add_f32_e32 v202, v206, v220
	v_add_f32_e32 v206, v213, v192
	v_add_f32_e32 v208, v211, v193
	v_mul_f32_e32 v192, v188, v188
	v_mul_f32_e32 v193, v189, v189
	v_and_b32_e32 v190, 0xffff0000, v190
	v_add_f32_e32 v191, v207, v191
	v_add_f32_e32 v203, v212, v221
	v_add_f32_e32 v207, v210, v222
	v_add_f32_e32 v194, v217, v194
	v_add_f32_e32 v210, v214, v224
	v_mul_f32_e32 v213, v206, v206
	v_mul_f32_e32 v214, v208, v208
	v_fmac_f32_e32 v192, v187, v187
	v_fmac_f32_e32 v193, v200, v200
	v_and_b32_e32 v195, 0xffff0000, v195
	v_add_f32_e32 v190, v209, v190
	v_add_f32_e32 v209, v216, v223
	v_cvt_pk_bf16_f32 v188, v187, v188
	v_fmac_f32_e32 v213, v203, v203
	v_fmac_f32_e32 v214, v207, v207
	v_add_f32_e32 v187, v192, v193
	v_mul_f32_e32 v193, v194, v194
	v_add_f32_e32 v195, v215, v195
	v_mul_f32_e32 v211, v190, v190
	v_add_f32_e32 v192, v213, v214
	v_fmac_f32_e32 v193, v209, v209
	v_mul_f32_e32 v212, v191, v191
	v_fmac_f32_e32 v211, v201, v201
	v_add_f32_e32 v192, v193, v192
	v_mul_f32_e32 v193, v195, v195
	v_fmac_f32_e32 v212, v202, v202
	v_add_f32_e32 v187, v211, v187
	v_fmac_f32_e32 v193, v210, v210
	v_add_f32_e32 v187, v212, v187
	v_add_f32_e32 v192, v193, v192
	v_cvt_pk_bf16_f32 v189, v200, v189
	v_add_f32_e32 v200, v187, v192
	v_and_b32_e32 v192, 64, v186
	v_cvt_pk_bf16_f32 v190, v201, v190
	v_xor_b32_e32 v187, 16, v186
	v_add_u32_e32 v201, 64, v192
	v_cmp_lt_i32_e32 vcc, v187, v201
	v_cvt_pk_bf16_f32 v191, v202, v191
	v_lshl_add_u64 v[192:193], s[18:19], 0, v[198:199]
	v_lshl_add_u64 v[196:197], v[192:193], 0, v[196:197]
	v_cndmask_b32_e32 v187, v186, v187, vcc
	v_lshlrev_b32_e32 v187, 2, v187
	ds_bpermute_b32 v202, v187, v200
	global_store_dwordx4 v[196:197], v[188:191], off sc0 sc1
	v_cvt_pk_bf16_f32 v192, v203, v206
	v_cvt_pk_bf16_f32 v193, v207, v208
	v_cvt_pk_bf16_f32 v194, v209, v194
	v_cvt_pk_bf16_f32 v195, v210, v195
	global_store_dwordx4 v[196:197], v[192:195], off offset:256 sc0 sc1
	s_nop 0
	v_xor_b32_e32 v188, 32, v186
	v_cmp_lt_i32_e32 vcc, v188, v201
	s_waitcnt lgkmcnt(0)
	v_add_f32_e32 v189, v200, v202
	v_cndmask_b32_e32 v188, v186, v188, vcc
	v_lshlrev_b32_e32 v188, 2, v188
	ds_bpermute_b32 v190, v188, v189
	s_and_saveexec_b64 s[36:37], s[10:11]
	s_cbranch_execz .LBB0_1710
	v_lshlrev_b64 v[192:193], 7, v[170:171]
	v_lshl_add_u64 v[192:193], s[14:15], 0, v[192:193]
	s_waitcnt lgkmcnt(0)
	v_add_f32_e32 v171, v189, v190
	global_store_dword v[192:193], v171, off
; __device__ __forceinline__ unsigned cvt_pk_bf16(float lo, float hi) { unsigned r; asm volatile("v_cvt_pk_bf16_f32 %0, %1, %2" : "=v"(r) : "v"(lo), "v"(hi)); return r; }
;     __device__ __forceinline__ void operator()(const f32x4 (&acc)[2][2][4][2], const Unit& u, int wr, int wc, int fr, int fq) const {
;     ...
;             for (int m = 0; m < 4; ++m) { const int row = row0 + ai * HALF + m * 16; float ss = 0.f;
; #pragma unroll
;                 for (int bj = 0; bj < 2; ++bj) { const u32x4 ow = old[m][bj];
;                     f32x4 v0 = (acc[ai][bj][m][0] + bv[bj][0]) * accs, v1 = (acc[ai][bj][m][1] + bv[bj][1]) * accs;
;                     v0[0] += __uint_as_float(ow.x << 16); v0[1] += __uint_as_float(ow.x & 0xffff0000u); v0[2] += __uint_as_float(ow.y << 16); v0[3] += __uint_as_float(ow.y & 0xffff0000u);
;                     v1[0] += __uint_as_float(ow.z << 16); v1[1] += __uint_as_float(ow.z & 0xffff0000u); v1[2] += __uint_as_float(ow.w << 16); v1[3] += __uint_as_float(ow.w & 0xffff0000u);
;                     ss += (v0[0] * v0[0] + v0[1] * v0[1]) + (v0[2] * v0[2] + v0[3] * v0[3]) + (v1[0] * v1[0] + v1[1] * v1[1]) + (v1[2] * v1[2] + v1[3] * v1[3]);
;                     u32x4 w; w.x = cvt_pk_bf16(v0[0], v0[1]); w.y = cvt_pk_bf16(v0[2], v0[3]); w.z = cvt_pk_bf16(v1[0], v1[1]); w.w = cvt_pk_bf16(v1[2], v1[3]);
;                     *(u32x4*)(HB + (size_t)row * ldc + col0 + bj * HALF) = w; }
;                 ss += __shfl_xor(ss, 16); ss += __shfl_xor(ss, 32);
;                 if (fq == 0) ssp[(size_t)row * 32] = ss; }
.LBB0_1710:
	s_or_b64 exec, exec, s[36:37]
	v_pk_add_f32 v[124:125], v[124:125], v[108:109]
	s_waitcnt vmcnt(7)
	v_lshlrev_b32_e32 v171, 16, v148
	v_and_b32_e32 v148, 0xffff0000, v148
	v_pk_add_f32 v[126:127], v[126:127], v[110:111]
	v_add_f32_e32 v125, v125, v148
	v_lshlrev_b32_e32 v148, 16, v149
	v_add_f32_e32 v126, v126, v148
	v_and_b32_e32 v148, 0xffff0000, v149
	v_pk_add_f32 v[120:121], v[120:121], v[96:97]
	v_add_f32_e32 v127, v127, v148
	v_lshlrev_b32_e32 v148, 16, v150
	v_add_f32_e32 v148, v120, v148
	v_and_b32_e32 v120, 0xffff0000, v150
	v_pk_add_f32 v[122:123], v[122:123], v[98:99]
	v_add_f32_e32 v149, v121, v120
	v_lshlrev_b32_e32 v120, 16, v151
	v_add_f32_e32 v150, v122, v120
	v_and_b32_e32 v120, 0xffff0000, v151
	v_add_f32_e32 v124, v124, v171
	v_add_f32_e32 v123, v123, v120
	v_mul_f32_e32 v120, v125, v125
	v_mul_f32_e32 v121, v127, v127
	v_fmac_f32_e32 v120, v124, v124
	v_fmac_f32_e32 v121, v126, v126
	v_add_f32_e32 v120, v120, v121
	v_mul_f32_e32 v121, v149, v149
	v_fmac_f32_e32 v121, v148, v148
	v_add_f32_e32 v120, v121, v120
	v_mul_f32_e32 v121, v123, v123
	v_fmac_f32_e32 v121, v150, v150
	v_add_f32_e32 v151, v121, v120
	v_cvt_pk_bf16_f32 v120, v124, v125
	v_pk_add_f32 v[116:117], v[116:117], v[100:101]
	s_waitcnt vmcnt(6)
	v_lshlrev_b32_e32 v124, 16, v144
	v_add_f32_e32 v116, v116, v124
	v_and_b32_e32 v124, 0xffff0000, v144
	v_pk_add_f32 v[118:119], v[118:119], v[102:103]
	v_add_f32_e32 v117, v117, v124
	v_lshlrev_b32_e32 v124, 16, v145
	v_add_f32_e32 v124, v118, v124
	v_and_b32_e32 v118, 0xffff0000, v145
	v_pk_add_f32 v[112:113], v[112:113], v[92:93]
	v_add_f32_e32 v125, v119, v118
	v_lshlrev_b32_e32 v118, 16, v146
	v_cvt_pk_bf16_f32 v121, v126, v127
	v_add_f32_e32 v126, v112, v118
	v_and_b32_e32 v112, 0xffff0000, v146
	v_pk_add_f32 v[114:115], v[114:115], v[94:95]
	v_add_f32_e32 v127, v113, v112
	v_lshlrev_b32_e32 v112, 16, v147
	v_add_f32_e32 v144, v114, v112
	v_and_b32_e32 v112, 0xffff0000, v147
	v_add_f32_e32 v145, v115, v112
	v_mul_f32_e32 v112, v117, v117
	v_mul_f32_e32 v113, v125, v125
	v_fmac_f32_e32 v112, v116, v116
	v_fmac_f32_e32 v113, v124, v124
	v_add_f32_e32 v112, v112, v113
	v_mul_f32_e32 v113, v127, v127
	v_fmac_f32_e32 v113, v126, v126
	v_add_f32_e32 v112, v113, v112
	v_mul_f32_e32 v113, v145, v145
	v_fmac_f32_e32 v113, v144, v144
	v_add_f32_e32 v112, v113, v112
	v_add_f32_e32 v115, v151, v112
	ds_bpermute_b32 v146, v187, v115
	s_waitcnt lgkmcnt(1)
	v_lshlrev_b64 v[190:191], 11, v[178:179]
	v_lshl_add_u64 v[112:113], v[190:191], 1, s[18:19]
	v_lshl_add_u64 v[118:119], v[168:169], 1, v[112:113]
	v_cvt_pk_bf16_f32 v122, v148, v149
	s_waitcnt lgkmcnt(0)
	v_add_f32_e32 v112, v115, v146
	ds_bpermute_b32 v113, v188, v112
	v_cvt_pk_bf16_f32 v123, v150, v123
	global_store_dwordx4 v[118:119], v[120:123], off sc0 sc1
	v_cvt_pk_bf16_f32 v114, v116, v117
	v_cvt_pk_bf16_f32 v115, v124, v125
	v_cvt_pk_bf16_f32 v116, v126, v127
	v_cvt_pk_bf16_f32 v117, v144, v145
	global_store_dwordx4 v[118:119], v[114:117], off offset:256 sc0 sc1
	s_and_saveexec_b64 s[36:37], s[10:11]
	s_cbranch_execz .LBB0_1712
	v_lshlrev_b64 v[114:115], 7, v[178:179]
	v_lshl_add_u64 v[114:115], s[14:15], 0, v[114:115]
	s_waitcnt lgkmcnt(0)
	v_add_f32_e32 v112, v112, v113
	global_store_dword v[114:115], v112, off
.LBB0_1712:
	s_or_b64 exec, exec, s[36:37]
	v_pk_add_f32 v[104:105], v[104:105], v[108:109]
	s_waitcnt vmcnt(7)
	v_lshlrev_b32_e32 v114, 16, v140
	v_add_f32_e32 v104, v104, v114
	v_and_b32_e32 v114, 0xffff0000, v140
	v_pk_add_f32 v[106:107], v[106:107], v[110:111]
	v_add_f32_e32 v105, v105, v114
	v_lshlrev_b32_e32 v114, 16, v141
	v_add_f32_e32 v106, v106, v114
	v_and_b32_e32 v114, 0xffff0000, v141
	v_pk_add_f32 v[88:89], v[88:89], v[96:97]
	v_add_f32_e32 v107, v107, v114
	v_lshlrev_b32_e32 v114, 16, v142
	v_add_f32_e32 v114, v88, v114
	v_and_b32_e32 v88, 0xffff0000, v142
	v_pk_add_f32 v[90:91], v[90:91], v[98:99]
	v_add_f32_e32 v115, v89, v88
	v_lshlrev_b32_e32 v88, 16, v143
	v_add_f32_e32 v116, v90, v88
	v_and_b32_e32 v88, 0xffff0000, v143
	v_add_f32_e32 v91, v91, v88
	v_mul_f32_e32 v88, v105, v105
	v_mul_f32_e32 v89, v107, v107
	v_fmac_f32_e32 v88, v104, v104
	v_fmac_f32_e32 v89, v106, v106
	v_add_f32_e32 v88, v88, v89
	v_mul_f32_e32 v89, v115, v115
	v_fmac_f32_e32 v89, v114, v114
	v_add_f32_e32 v88, v89, v88
	v_mul_f32_e32 v89, v91, v91
	v_fmac_f32_e32 v89, v116, v116
	v_add_f32_e32 v117, v89, v88
	v_cvt_pk_bf16_f32 v88, v104, v105
	v_pk_add_f32 v[84:85], v[84:85], v[100:101]
	s_waitcnt vmcnt(6)
	v_lshlrev_b32_e32 v104, 16, v136
	v_add_f32_e32 v84, v84, v104
	v_and_b32_e32 v104, 0xffff0000, v136
	v_pk_add_f32 v[86:87], v[86:87], v[102:103]
	v_add_f32_e32 v85, v85, v104
	v_lshlrev_b32_e32 v104, 16, v137
	v_add_f32_e32 v104, v86, v104
	v_and_b32_e32 v86, 0xffff0000, v137
	v_pk_add_f32 v[80:81], v[80:81], v[92:93]
	v_add_f32_e32 v105, v87, v86
	v_lshlrev_b32_e32 v86, 16, v138
	v_cvt_pk_bf16_f32 v89, v106, v107
	v_add_f32_e32 v106, v80, v86
	v_and_b32_e32 v80, 0xffff0000, v138
	v_pk_add_f32 v[82:83], v[82:83], v[94:95]
	v_add_f32_e32 v107, v81, v80
	v_lshlrev_b32_e32 v80, 16, v139
	v_cvt_pk_bf16_f32 v90, v114, v115
	v_add_f32_e32 v114, v82, v80
	v_and_b32_e32 v80, 0xffff0000, v139
	v_add_f32_e32 v115, v83, v80
	v_mul_f32_e32 v80, v85, v85
	v_mul_f32_e32 v81, v105, v105
	v_fmac_f32_e32 v80, v84, v84
	v_fmac_f32_e32 v81, v104, v104
	v_add_f32_e32 v80, v80, v81
	v_mul_f32_e32 v81, v107, v107
	v_fmac_f32_e32 v81, v106, v106
	v_add_f32_e32 v80, v81, v80
	v_mul_f32_e32 v81, v115, v115
	v_fmac_f32_e32 v81, v114, v114
	v_add_f32_e32 v80, v81, v80
	v_add_f32_e32 v83, v117, v80
	v_cvt_pk_bf16_f32 v91, v116, v91
	ds_bpermute_b32 v116, v187, v83
	s_waitcnt lgkmcnt(1)
	v_lshlrev_b64 v[112:113], 11, v[176:177]
	v_lshl_add_u64 v[80:81], v[112:113], 1, s[18:19]
	v_lshl_add_u64 v[86:87], v[168:169], 1, v[80:81]
	global_store_dwordx4 v[86:87], v[88:91], off sc0 sc1
	s_waitcnt lgkmcnt(0)
	v_add_f32_e32 v80, v83, v116
	ds_bpermute_b32 v81, v188, v80
	v_cvt_pk_bf16_f32 v82, v84, v85
	v_cvt_pk_bf16_f32 v83, v104, v105
	v_cvt_pk_bf16_f32 v84, v106, v107
	v_cvt_pk_bf16_f32 v85, v114, v115
	global_store_dwordx4 v[86:87], v[82:85], off offset:256 sc0 sc1
	s_and_saveexec_b64 s[36:37], s[10:11]
	s_cbranch_execz .LBB0_1714
	v_lshlrev_b64 v[82:83], 7, v[176:177]
	v_lshl_add_u64 v[82:83], s[14:15], 0, v[82:83]
	s_waitcnt lgkmcnt(0)
	v_add_f32_e32 v80, v80, v81
	global_store_dword v[82:83], v80, off
; __device__ __forceinline__ unsigned cvt_pk_bf16(float lo, float hi) { unsigned r; asm volatile("v_cvt_pk_bf16_f32 %0, %1, %2" : "=v"(r) : "v"(lo), "v"(hi)); return r; }
;     __device__ __forceinline__ void operator()(const f32x4 (&acc)[2][2][4][2], const Unit& u, int wr, int wc, int fr, int fq) const {
;     ...
;         for (int ai = 0; ai < 2; ++ai) {
;             u32x4 old[4][2];
; #pragma unroll
;             for (int m = 0; m < 4; ++m)
; #pragma unroll
;                 for (int bj = 0; bj < 2; ++bj) old[m][bj] = *(const u32x4*)(HB + (size_t)(row0 + ai * HALF + m * 16) * ldc + col0 + bj * HALF);
; #pragma unroll
;             for (int m = 0; m < 4; ++m) { const int row = row0 + ai * HALF + m * 16; float ss = 0.f;
; #pragma unroll
;                 for (int bj = 0; bj < 2; ++bj) { const u32x4 ow = old[m][bj];
;                     f32x4 v0 = (acc[ai][bj][m][0] + bv[bj][0]) * accs, v1 = (acc[ai][bj][m][1] + bv[bj][1]) * accs;
;                     v0[0] += __uint_as_float(ow.x << 16); v0[1] += __uint_as_float(ow.x & 0xffff0000u); v0[2] += __uint_as_float(ow.y << 16); v0[3] += __uint_as_float(ow.y & 0xffff0000u);
;                     v1[0] += __uint_as_float(ow.z << 16); v1[1] += __uint_as_float(ow.z & 0xffff0000u); v1[2] += __uint_as_float(ow.w << 16); v1[3] += __uint_as_float(ow.w & 0xffff0000u);
;                     ss += (v0[0] * v0[0] + v0[1] * v0[1]) + (v0[2] * v0[2] + v0[3] * v0[3]) + (v1[0] * v1[0] + v1[1] * v1[1]) + (v1[2] * v1[2] + v1[3] * v1[3]);
;                     u32x4 w; w.x = cvt_pk_bf16(v0[0], v0[1]); w.y = cvt_pk_bf16(v0[2], v0[3]); w.z = cvt_pk_bf16(v1[0], v1[1]); w.w = cvt_pk_bf16(v1[2], v1[3]);
;                     *(u32x4*)(HB + (size_t)row * ldc + col0 + bj * HALF) = w; }
;                 ss += __shfl_xor(ss, 16); ss += __shfl_xor(ss, 32);
;                 if (fq == 0) ssp[(size_t)row * 32] = ss; }
.LBB0_1714:
	s_or_b64 exec, exec, s[36:37]
	v_pk_add_f32 v[76:77], v[76:77], v[108:109]
	s_waitcnt vmcnt(7)
	v_lshlrev_b32_e32 v82, 16, v132
	v_add_f32_e32 v76, v76, v82
	v_and_b32_e32 v82, 0xffff0000, v132
	v_pk_add_f32 v[78:79], v[78:79], v[110:111]
	v_add_f32_e32 v77, v77, v82
	v_lshlrev_b32_e32 v82, 16, v133
	v_add_f32_e32 v78, v78, v82
	v_and_b32_e32 v82, 0xffff0000, v133
	v_pk_add_f32 v[72:73], v[72:73], v[96:97]
	v_add_f32_e32 v79, v79, v82
	v_lshlrev_b32_e32 v82, 16, v134
	v_add_f32_e32 v82, v72, v82
	v_and_b32_e32 v72, 0xffff0000, v134
	v_pk_add_f32 v[74:75], v[74:75], v[98:99]
	v_add_f32_e32 v83, v73, v72
	v_lshlrev_b32_e32 v72, 16, v135
	v_add_f32_e32 v84, v74, v72
	v_and_b32_e32 v72, 0xffff0000, v135
	v_add_f32_e32 v75, v75, v72
	v_mul_f32_e32 v72, v77, v77
	v_mul_f32_e32 v73, v79, v79
	v_fmac_f32_e32 v72, v76, v76
	v_fmac_f32_e32 v73, v78, v78
	v_add_f32_e32 v72, v72, v73
	v_mul_f32_e32 v73, v83, v83
	v_fmac_f32_e32 v73, v82, v82
	v_add_f32_e32 v72, v73, v72
	v_mul_f32_e32 v73, v75, v75
	v_fmac_f32_e32 v73, v84, v84
	v_add_f32_e32 v85, v73, v72
	v_cvt_pk_bf16_f32 v72, v76, v77
	v_pk_add_f32 v[68:69], v[68:69], v[100:101]
	s_waitcnt vmcnt(6)
	v_lshlrev_b32_e32 v76, 16, v128
	v_add_f32_e32 v68, v68, v76
	v_and_b32_e32 v76, 0xffff0000, v128
	v_pk_add_f32 v[70:71], v[70:71], v[102:103]
	v_add_f32_e32 v69, v69, v76
	v_lshlrev_b32_e32 v76, 16, v129
	v_add_f32_e32 v76, v70, v76
	v_and_b32_e32 v70, 0xffff0000, v129
	v_pk_add_f32 v[64:65], v[64:65], v[92:93]
	v_add_f32_e32 v77, v71, v70
	v_lshlrev_b32_e32 v70, 16, v130
	v_cvt_pk_bf16_f32 v73, v78, v79
	v_add_f32_e32 v78, v64, v70
	v_and_b32_e32 v64, 0xffff0000, v130
	v_pk_add_f32 v[66:67], v[66:67], v[94:95]
	v_add_f32_e32 v79, v65, v64
	v_lshlrev_b32_e32 v64, 16, v131
	v_cvt_pk_bf16_f32 v74, v82, v83
	v_add_f32_e32 v82, v66, v64
	v_and_b32_e32 v64, 0xffff0000, v131
	v_add_f32_e32 v83, v67, v64
	v_mul_f32_e32 v64, v69, v69
	v_mul_f32_e32 v65, v77, v77
	v_fmac_f32_e32 v64, v68, v68
	v_fmac_f32_e32 v65, v76, v76
	v_add_f32_e32 v64, v64, v65
	v_mul_f32_e32 v65, v79, v79
	v_fmac_f32_e32 v65, v78, v78
	v_add_f32_e32 v64, v65, v64
	v_mul_f32_e32 v65, v83, v83
	v_fmac_f32_e32 v65, v82, v82
	v_add_f32_e32 v64, v65, v64
	v_add_f32_e32 v67, v85, v64
	v_cvt_pk_bf16_f32 v75, v84, v75
	ds_bpermute_b32 v84, v187, v67
	s_waitcnt lgkmcnt(1)
	v_lshlrev_b64 v[80:81], 11, v[174:175]
	v_lshl_add_u64 v[64:65], v[80:81], 1, s[18:19]
	v_lshl_add_u64 v[70:71], v[168:169], 1, v[64:65]
	global_store_dwordx4 v[70:71], v[72:75], off sc0 sc1
	s_waitcnt lgkmcnt(0)
	v_add_f32_e32 v64, v67, v84
	ds_bpermute_b32 v65, v188, v64
	v_cvt_pk_bf16_f32 v66, v68, v69
	v_cvt_pk_bf16_f32 v67, v76, v77
	v_cvt_pk_bf16_f32 v68, v78, v79
	v_cvt_pk_bf16_f32 v69, v82, v83
	global_store_dwordx4 v[70:71], v[66:69], off offset:256 sc0 sc1
	s_and_saveexec_b64 s[36:37], s[10:11]
	s_cbranch_execz .LBB0_1716
	v_lshlrev_b64 v[66:67], 7, v[174:175]
	v_lshl_add_u64 v[66:67], s[14:15], 0, v[66:67]
	s_waitcnt lgkmcnt(0)
	v_add_f32_e32 v64, v64, v65
	global_store_dword v[66:67], v64, off
.LBB0_1716:
	s_or_b64 exec, exec, s[36:37]
	v_add_u32_e32 v106, 0x80, v170
	v_ashrrev_i32_e32 v107, 31, v106
	v_lshlrev_b64 v[120:121], 12, v[106:107]
	s_waitcnt lgkmcnt(0)
	v_lshl_add_u64 v[64:65], v[172:173], 0, v[120:121]
	global_load_dwordx4 v[112:115], v[64:65], off
	global_load_dwordx4 v[116:119], v[64:65], off offset:256
	v_add_u32_e32 v104, 0x90, v170
	v_add_u32_e32 v90, 0xa0, v170
	v_add_u32_e32 v88, 0xb0, v170
	v_ashrrev_i32_e32 v105, 31, v104
	v_ashrrev_i32_e32 v91, 31, v90
	v_ashrrev_i32_e32 v89, 31, v88
	v_lshlrev_b64 v[64:65], 12, v[104:105]
	v_lshlrev_b64 v[66:67], 12, v[90:91]
	v_lshlrev_b64 v[68:69], 12, v[88:89]
	v_lshl_add_u64 v[64:65], v[172:173], 0, v[64:65]
	v_lshl_add_u64 v[66:67], v[172:173], 0, v[66:67]
	v_lshl_add_u64 v[122:123], v[172:173], 0, v[68:69]
	global_load_dwordx4 v[84:87], v[64:65], off
	global_load_dwordx4 v[80:83], v[64:65], off offset:256
	global_load_dwordx4 v[76:79], v[66:67], off
	global_load_dwordx4 v[72:75], v[66:67], off offset:256
	global_load_dwordx4 v[68:71], v[122:123], off
	s_nop 0
	global_load_dwordx4 v[64:67], v[122:123], off offset:256
	v_pk_add_f32 v[62:63], v[62:63], v[110:111]
	v_pk_add_f32 v[60:61], v[60:61], v[108:109]
	v_pk_add_f32 v[58:59], v[58:59], v[98:99]
	v_pk_add_f32 v[56:57], v[56:57], v[96:97]
	v_pk_add_f32 v[54:55], v[54:55], v[102:103]
	v_pk_add_f32 v[52:53], v[52:53], v[100:101]
	v_pk_add_f32 v[50:51], v[50:51], v[94:95]
	v_pk_add_f32 v[48:49], v[48:49], v[92:93]
	s_waitcnt vmcnt(7)
	v_lshlrev_b32_e32 v122, 16, v112
	v_and_b32_e32 v112, 0xffff0000, v112
	v_lshlrev_b32_e32 v123, 16, v113
	v_and_b32_e32 v113, 0xffff0000, v113
	v_lshlrev_b32_e32 v124, 16, v114
	v_and_b32_e32 v114, 0xffff0000, v114
	v_lshlrev_b32_e32 v125, 16, v115
	v_and_b32_e32 v115, 0xffff0000, v115
	s_waitcnt vmcnt(6)
	v_lshlrev_b32_e32 v126, 16, v116
	v_and_b32_e32 v116, 0xffff0000, v116
	v_lshlrev_b32_e32 v127, 16, v117
	v_and_b32_e32 v117, 0xffff0000, v117
	v_lshlrev_b32_e32 v128, 16, v118
	v_and_b32_e32 v118, 0xffff0000, v118
	v_lshlrev_b32_e32 v129, 16, v119
	v_and_b32_e32 v119, 0xffff0000, v119
	v_add_f32_e32 v61, v61, v112
	v_add_f32_e32 v63, v63, v113
	v_add_f32_e32 v57, v57, v114
	v_add_f32_e32 v59, v59, v115
	v_add_f32_e32 v113, v53, v116
	v_add_f32_e32 v115, v55, v117
	v_add_f32_e32 v60, v60, v122
	v_add_f32_e32 v62, v62, v123
	v_add_f32_e32 v56, v56, v124
	v_add_f32_e32 v58, v58, v125
	v_add_f32_e32 v112, v52, v126
	v_add_f32_e32 v114, v54, v127
	v_add_f32_e32 v116, v48, v128
	v_add_f32_e32 v117, v49, v118
	v_add_f32_e32 v118, v50, v129
	v_add_f32_e32 v119, v51, v119
	v_mul_f32_e32 v52, v61, v61
	v_mul_f32_e32 v53, v63, v63
	v_mul_f32_e32 v54, v57, v57
	v_mul_f32_e32 v55, v59, v59
	v_cvt_pk_bf16_f32 v48, v60, v61
	v_cvt_pk_bf16_f32 v49, v62, v63
	v_cvt_pk_bf16_f32 v50, v56, v57
	v_cvt_pk_bf16_f32 v51, v58, v59
	v_mul_f32_e32 v57, v113, v113
	v_mul_f32_e32 v59, v115, v115
	v_mul_f32_e32 v61, v117, v117
	v_fmac_f32_e32 v52, v60, v60
	v_fmac_f32_e32 v53, v62, v62
	v_fmac_f32_e32 v57, v112, v112
	v_fmac_f32_e32 v59, v114, v114
	v_mul_f32_e32 v63, v119, v119
	v_fmac_f32_e32 v54, v56, v56
	v_fmac_f32_e32 v61, v116, v116
	v_add_f32_e32 v52, v52, v53
	v_add_f32_e32 v53, v57, v59
	v_fmac_f32_e32 v55, v58, v58
	v_fmac_f32_e32 v63, v118, v118
	v_add_f32_e32 v52, v54, v52
	v_add_f32_e32 v53, v61, v53
	v_add_f32_e32 v52, v55, v52
	v_add_f32_e32 v53, v63, v53
	v_add_f32_e32 v56, v52, v53
	ds_bpermute_b32 v57, v187, v56
	v_lshl_add_u64 v[52:53], s[18:19], 0, v[120:121]
	v_lshl_add_u64 v[54:55], v[168:169], 1, v[52:53]
	global_store_dwordx4 v[54:55], v[48:51], off sc0 sc1
	s_waitcnt lgkmcnt(0)
	s_nop 0
	v_add_f32_e32 v48, v56, v57
	ds_bpermute_b32 v49, v188, v48
	v_cvt_pk_bf16_f32 v50, v112, v113
	v_cvt_pk_bf16_f32 v51, v114, v115
	v_cvt_pk_bf16_f32 v52, v116, v117
	v_cvt_pk_bf16_f32 v53, v118, v119
	global_store_dwordx4 v[54:55], v[50:53], off offset:256 sc0 sc1
	s_and_saveexec_b64 s[36:37], s[10:11]
	s_cbranch_execz .LBB0_1718
; __device__ __forceinline__ unsigned cvt_pk_bf16(float lo, float hi) { unsigned r; asm volatile("v_cvt_pk_bf16_f32 %0, %1, %2" : "=v"(r) : "v"(lo), "v"(hi)); return r; }
;     __device__ __forceinline__ void operator()(const f32x4 (&acc)[2][2][4][2], const Unit& u, int wr, int wc, int fr, int fq) const {
;     ...
;                 for (int bj = 0; bj < 2; ++bj) old[m][bj] = *(const u32x4*)(HB + (size_t)(row0 + ai * HALF + m * 16) * ldc + col0 + bj * HALF);
; #pragma unroll
;             for (int m = 0; m < 4; ++m) { const int row = row0 + ai * HALF + m * 16; float ss = 0.f;
; #pragma unroll
;                 for (int bj = 0; bj < 2; ++bj) { const u32x4 ow = old[m][bj];
;                     f32x4 v0 = (acc[ai][bj][m][0] + bv[bj][0]) * accs, v1 = (acc[ai][bj][m][1] + bv[bj][1]) * accs;
;                     v0[0] += __uint_as_float(ow.x << 16); v0[1] += __uint_as_float(ow.x & 0xffff0000u); v0[2] += __uint_as_float(ow.y << 16); v0[3] += __uint_as_float(ow.y & 0xffff0000u);
;                     v1[0] += __uint_as_float(ow.z << 16); v1[1] += __uint_as_float(ow.z & 0xffff0000u); v1[2] += __uint_as_float(ow.w << 16); v1[3] += __uint_as_float(ow.w & 0xffff0000u);
;                     ss += (v0[0] * v0[0] + v0[1] * v0[1]) + (v0[2] * v0[2] + v0[3] * v0[3]) + (v1[0] * v1[0] + v1[1] * v1[1]) + (v1[2] * v1[2] + v1[3] * v1[3]);
;                     u32x4 w; w.x = cvt_pk_bf16(v0[0], v0[1]); w.y = cvt_pk_bf16(v0[2], v0[3]); w.z = cvt_pk_bf16(v1[0], v1[1]); w.w = cvt_pk_bf16(v1[2], v1[3]);
;                     *(u32x4*)(HB + (size_t)row * ldc + col0 + bj * HALF) = w; }
;                 ss += __shfl_xor(ss, 16); ss += __shfl_xor(ss, 32);
;                 if (fq == 0) ssp[(size_t)row * 32] = ss; }
	v_lshlrev_b64 v[50:51], 7, v[106:107]
	v_lshl_add_u64 v[50:51], s[14:15], 0, v[50:51]
	s_waitcnt lgkmcnt(0)
	v_add_f32_e32 v48, v48, v49
	global_store_dword v[50:51], v48, off
.LBB0_1718:
	s_or_b64 exec, exec, s[36:37]
	v_pk_add_f32 v[44:45], v[44:45], v[108:109]
	s_waitcnt vmcnt(7)
	v_lshlrev_b32_e32 v50, 16, v84
	v_add_f32_e32 v44, v44, v50
	v_and_b32_e32 v50, 0xffff0000, v84
	v_pk_add_f32 v[46:47], v[46:47], v[110:111]
	v_add_f32_e32 v45, v45, v50
	v_lshlrev_b32_e32 v50, 16, v85
	v_add_f32_e32 v46, v46, v50
	v_and_b32_e32 v50, 0xffff0000, v85
	v_pk_add_f32 v[40:41], v[40:41], v[96:97]
	v_add_f32_e32 v47, v47, v50
	v_lshlrev_b32_e32 v50, 16, v86
	v_add_f32_e32 v50, v40, v50
	v_and_b32_e32 v40, 0xffff0000, v86
	v_pk_add_f32 v[42:43], v[42:43], v[98:99]
	v_add_f32_e32 v51, v41, v40
	v_lshlrev_b32_e32 v40, 16, v87
	v_add_f32_e32 v52, v42, v40
	v_and_b32_e32 v40, 0xffff0000, v87
	v_add_f32_e32 v43, v43, v40
	v_mul_f32_e32 v40, v45, v45
	v_mul_f32_e32 v41, v47, v47
	v_fmac_f32_e32 v40, v44, v44
	v_fmac_f32_e32 v41, v46, v46
	v_add_f32_e32 v40, v40, v41
	v_mul_f32_e32 v41, v51, v51
	v_fmac_f32_e32 v41, v50, v50
	v_add_f32_e32 v40, v41, v40
	v_mul_f32_e32 v41, v43, v43
	v_fmac_f32_e32 v41, v52, v52
	v_add_f32_e32 v53, v41, v40
	v_cvt_pk_bf16_f32 v40, v44, v45
	v_pk_add_f32 v[36:37], v[36:37], v[100:101]
	s_waitcnt vmcnt(6)
	v_lshlrev_b32_e32 v44, 16, v80
	v_add_f32_e32 v36, v36, v44
	v_and_b32_e32 v44, 0xffff0000, v80
	v_pk_add_f32 v[38:39], v[38:39], v[102:103]
	v_add_f32_e32 v37, v37, v44
	v_lshlrev_b32_e32 v44, 16, v81
	v_add_f32_e32 v44, v38, v44
	v_and_b32_e32 v38, 0xffff0000, v81
	v_pk_add_f32 v[32:33], v[32:33], v[92:93]
	v_add_f32_e32 v45, v39, v38
	v_lshlrev_b32_e32 v38, 16, v82
	v_cvt_pk_bf16_f32 v41, v46, v47
	v_add_f32_e32 v46, v32, v38
	v_and_b32_e32 v32, 0xffff0000, v82
	v_pk_add_f32 v[34:35], v[34:35], v[94:95]
	v_add_f32_e32 v47, v33, v32
	v_lshlrev_b32_e32 v32, 16, v83
	v_cvt_pk_bf16_f32 v42, v50, v51
	v_add_f32_e32 v50, v34, v32
	v_and_b32_e32 v32, 0xffff0000, v83
	v_add_f32_e32 v51, v35, v32
	v_mul_f32_e32 v32, v37, v37
	v_mul_f32_e32 v33, v45, v45
	v_fmac_f32_e32 v32, v36, v36
	v_fmac_f32_e32 v33, v44, v44
	v_add_f32_e32 v32, v32, v33
	v_mul_f32_e32 v33, v47, v47
	v_fmac_f32_e32 v33, v46, v46
	v_add_f32_e32 v32, v33, v32
	v_mul_f32_e32 v33, v51, v51
	v_fmac_f32_e32 v33, v50, v50
	v_add_f32_e32 v32, v33, v32
	v_add_f32_e32 v35, v53, v32
	v_cvt_pk_bf16_f32 v43, v52, v43
	ds_bpermute_b32 v52, v187, v35
	s_waitcnt lgkmcnt(1)
	v_lshlrev_b64 v[48:49], 11, v[104:105]
	v_lshl_add_u64 v[32:33], v[48:49], 1, s[18:19]
	v_lshl_add_u64 v[38:39], v[168:169], 1, v[32:33]
	global_store_dwordx4 v[38:39], v[40:43], off sc0 sc1
	s_waitcnt lgkmcnt(0)
	v_add_f32_e32 v32, v35, v52
	ds_bpermute_b32 v33, v188, v32
	v_cvt_pk_bf16_f32 v34, v36, v37
	v_cvt_pk_bf16_f32 v35, v44, v45
	v_cvt_pk_bf16_f32 v36, v46, v47
	v_cvt_pk_bf16_f32 v37, v50, v51
	global_store_dwordx4 v[38:39], v[34:37], off offset:256 sc0 sc1
	s_and_saveexec_b64 s[36:37], s[10:11]
	s_cbranch_execz .LBB0_1720
	v_lshlrev_b64 v[34:35], 7, v[104:105]
	v_lshl_add_u64 v[34:35], s[14:15], 0, v[34:35]
	s_waitcnt lgkmcnt(0)
	v_add_f32_e32 v32, v32, v33
	global_store_dword v[34:35], v32, off
; __device__ __forceinline__ unsigned cvt_pk_bf16(float lo, float hi) { unsigned r; asm volatile("v_cvt_pk_bf16_f32 %0, %1, %2" : "=v"(r) : "v"(lo), "v"(hi)); return r; }
;     __device__ __forceinline__ void operator()(const f32x4 (&acc)[2][2][4][2], const Unit& u, int wr, int wc, int fr, int fq) const {
;     ...
;                 for (int bj = 0; bj < 2; ++bj) old[m][bj] = *(const u32x4*)(HB + (size_t)(row0 + ai * HALF + m * 16) * ldc + col0 + bj * HALF);
; #pragma unroll
;             for (int m = 0; m < 4; ++m) { const int row = row0 + ai * HALF + m * 16; float ss = 0.f;
; #pragma unroll
;                 for (int bj = 0; bj < 2; ++bj) { const u32x4 ow = old[m][bj];
;                     f32x4 v0 = (acc[ai][bj][m][0] + bv[bj][0]) * accs, v1 = (acc[ai][bj][m][1] + bv[bj][1]) * accs;
;                     v0[0] += __uint_as_float(ow.x << 16); v0[1] += __uint_as_float(ow.x & 0xffff0000u); v0[2] += __uint_as_float(ow.y << 16); v0[3] += __uint_as_float(ow.y & 0xffff0000u);
;                     v1[0] += __uint_as_float(ow.z << 16); v1[1] += __uint_as_float(ow.z & 0xffff0000u); v1[2] += __uint_as_float(ow.w << 16); v1[3] += __uint_as_float(ow.w & 0xffff0000u);
;                     ss += (v0[0] * v0[0] + v0[1] * v0[1]) + (v0[2] * v0[2] + v0[3] * v0[3]) + (v1[0] * v1[0] + v1[1] * v1[1]) + (v1[2] * v1[2] + v1[3] * v1[3]);
;                     u32x4 w; w.x = cvt_pk_bf16(v0[0], v0[1]); w.y = cvt_pk_bf16(v0[2], v0[3]); w.z = cvt_pk_bf16(v1[0], v1[1]); w.w = cvt_pk_bf16(v1[2], v1[3]);
;                     *(u32x4*)(HB + (size_t)row * ldc + col0 + bj * HALF) = w; }
;                 ss += __shfl_xor(ss, 16); ss += __shfl_xor(ss, 32);
;                 if (fq == 0) ssp[(size_t)row * 32] = ss; }
.LBB0_1720:
	s_or_b64 exec, exec, s[36:37]
	v_pk_add_f32 v[28:29], v[28:29], v[108:109]
	s_waitcnt vmcnt(7)
	v_lshlrev_b32_e32 v34, 16, v76
	v_add_f32_e32 v28, v28, v34
	v_and_b32_e32 v34, 0xffff0000, v76
	v_pk_add_f32 v[30:31], v[30:31], v[110:111]
	v_add_f32_e32 v29, v29, v34
	v_lshlrev_b32_e32 v34, 16, v77
	v_add_f32_e32 v30, v30, v34
	v_and_b32_e32 v34, 0xffff0000, v77
	v_pk_add_f32 v[24:25], v[24:25], v[96:97]
	v_add_f32_e32 v31, v31, v34
	v_lshlrev_b32_e32 v34, 16, v78
	v_add_f32_e32 v34, v24, v34
	v_and_b32_e32 v24, 0xffff0000, v78
	v_pk_add_f32 v[26:27], v[26:27], v[98:99]
	v_add_f32_e32 v35, v25, v24
	v_lshlrev_b32_e32 v24, 16, v79
	v_add_f32_e32 v36, v26, v24
	v_and_b32_e32 v24, 0xffff0000, v79
	v_add_f32_e32 v27, v27, v24
	v_mul_f32_e32 v24, v29, v29
	v_mul_f32_e32 v25, v31, v31
	v_fmac_f32_e32 v24, v28, v28
	v_fmac_f32_e32 v25, v30, v30
	v_add_f32_e32 v24, v24, v25
	v_mul_f32_e32 v25, v35, v35
	v_fmac_f32_e32 v25, v34, v34
	v_add_f32_e32 v24, v25, v24
	v_mul_f32_e32 v25, v27, v27
	v_fmac_f32_e32 v25, v36, v36
	v_add_f32_e32 v37, v25, v24
	v_cvt_pk_bf16_f32 v24, v28, v29
	v_pk_add_f32 v[20:21], v[20:21], v[100:101]
	s_waitcnt vmcnt(6)
	v_lshlrev_b32_e32 v28, 16, v72
	v_add_f32_e32 v20, v20, v28
	v_and_b32_e32 v28, 0xffff0000, v72
	v_pk_add_f32 v[22:23], v[22:23], v[102:103]
	v_add_f32_e32 v21, v21, v28
	v_lshlrev_b32_e32 v28, 16, v73
	v_add_f32_e32 v28, v22, v28
	v_and_b32_e32 v22, 0xffff0000, v73
	v_pk_add_f32 v[16:17], v[16:17], v[92:93]
	v_add_f32_e32 v29, v23, v22
	v_lshlrev_b32_e32 v22, 16, v74
	v_cvt_pk_bf16_f32 v25, v30, v31
	v_add_f32_e32 v30, v16, v22
	v_and_b32_e32 v16, 0xffff0000, v74
	v_pk_add_f32 v[18:19], v[18:19], v[94:95]
	v_add_f32_e32 v31, v17, v16
	v_lshlrev_b32_e32 v16, 16, v75
	v_cvt_pk_bf16_f32 v26, v34, v35
	v_add_f32_e32 v34, v18, v16
	v_and_b32_e32 v16, 0xffff0000, v75
	v_add_f32_e32 v35, v19, v16
	v_mul_f32_e32 v16, v21, v21
	v_mul_f32_e32 v17, v29, v29
	v_fmac_f32_e32 v16, v20, v20
	v_fmac_f32_e32 v17, v28, v28
	v_add_f32_e32 v16, v16, v17
	v_mul_f32_e32 v17, v31, v31
	v_fmac_f32_e32 v17, v30, v30
	v_add_f32_e32 v16, v17, v16
	v_mul_f32_e32 v17, v35, v35
	v_fmac_f32_e32 v17, v34, v34
	v_add_f32_e32 v16, v17, v16
	v_add_f32_e32 v19, v37, v16
	v_cvt_pk_bf16_f32 v27, v36, v27
	ds_bpermute_b32 v36, v187, v19
	s_waitcnt lgkmcnt(1)
	v_lshlrev_b64 v[32:33], 11, v[90:91]
	v_lshl_add_u64 v[16:17], v[32:33], 1, s[18:19]
	v_lshl_add_u64 v[22:23], v[168:169], 1, v[16:17]
	global_store_dwordx4 v[22:23], v[24:27], off sc0 sc1
	s_waitcnt lgkmcnt(0)
	v_add_f32_e32 v16, v19, v36
	ds_bpermute_b32 v17, v188, v16
	v_cvt_pk_bf16_f32 v18, v20, v21
	v_cvt_pk_bf16_f32 v19, v28, v29
	v_cvt_pk_bf16_f32 v20, v30, v31
	v_cvt_pk_bf16_f32 v21, v34, v35
	global_store_dwordx4 v[22:23], v[18:21], off offset:256 sc0 sc1
	s_and_saveexec_b64 s[36:37], s[10:11]
	s_cbranch_execz .LBB0_1722
	v_lshlrev_b64 v[18:19], 7, v[90:91]
	v_lshl_add_u64 v[18:19], s[14:15], 0, v[18:19]
	s_waitcnt lgkmcnt(0)
	v_add_f32_e32 v16, v16, v17
	global_store_dword v[18:19], v16, off
.LBB0_1722:
	s_or_b64 exec, exec, s[36:37]
	v_pk_add_f32 v[12:13], v[12:13], v[108:109]
	s_waitcnt vmcnt(7)
	v_lshlrev_b32_e32 v18, 16, v68
	v_add_f32_e32 v12, v12, v18
	v_and_b32_e32 v18, 0xffff0000, v68
	v_pk_add_f32 v[14:15], v[14:15], v[110:111]
	v_add_f32_e32 v13, v13, v18
	v_lshlrev_b32_e32 v18, 16, v69
	v_add_f32_e32 v14, v14, v18
	v_and_b32_e32 v18, 0xffff0000, v69
	v_pk_add_f32 v[8:9], v[8:9], v[96:97]
	v_add_f32_e32 v15, v15, v18
	v_lshlrev_b32_e32 v18, 16, v70
	v_add_f32_e32 v18, v8, v18
	v_and_b32_e32 v8, 0xffff0000, v70
	v_pk_add_f32 v[10:11], v[10:11], v[98:99]
	v_add_f32_e32 v19, v9, v8
	v_lshlrev_b32_e32 v8, 16, v71
	v_add_f32_e32 v20, v10, v8
	v_and_b32_e32 v8, 0xffff0000, v71
	v_add_f32_e32 v11, v11, v8
	v_mul_f32_e32 v8, v13, v13
	v_mul_f32_e32 v9, v15, v15
	v_fmac_f32_e32 v8, v12, v12
	v_fmac_f32_e32 v9, v14, v14
	v_add_f32_e32 v8, v8, v9
	v_mul_f32_e32 v9, v19, v19
	v_fmac_f32_e32 v9, v18, v18
	v_add_f32_e32 v8, v9, v8
	v_mul_f32_e32 v9, v11, v11
	v_fmac_f32_e32 v9, v20, v20
	v_add_f32_e32 v21, v9, v8
	v_cvt_pk_bf16_f32 v8, v12, v13
	v_pk_add_f32 v[4:5], v[4:5], v[100:101]
	s_waitcnt vmcnt(6)
	v_lshlrev_b32_e32 v12, 16, v64
	v_add_f32_e32 v4, v4, v12
	v_and_b32_e32 v12, 0xffff0000, v64
	v_pk_add_f32 v[6:7], v[6:7], v[102:103]
	v_add_f32_e32 v5, v5, v12
	v_lshlrev_b32_e32 v12, 16, v65
	v_add_f32_e32 v12, v6, v12
	v_and_b32_e32 v6, 0xffff0000, v65
	v_pk_add_f32 v[0:1], v[0:1], v[92:93]
	v_add_f32_e32 v13, v7, v6
	v_lshlrev_b32_e32 v6, 16, v66
	v_cvt_pk_bf16_f32 v9, v14, v15
	v_add_f32_e32 v14, v0, v6
	v_and_b32_e32 v0, 0xffff0000, v66
	v_pk_add_f32 v[2:3], v[2:3], v[94:95]
	v_add_f32_e32 v15, v1, v0
	v_lshlrev_b32_e32 v0, 16, v67
	v_cvt_pk_bf16_f32 v10, v18, v19
	v_add_f32_e32 v18, v2, v0
	v_and_b32_e32 v0, 0xffff0000, v67
	v_add_f32_e32 v19, v3, v0
	v_mul_f32_e32 v0, v5, v5
	v_mul_f32_e32 v1, v13, v13
	v_fmac_f32_e32 v0, v4, v4
	v_fmac_f32_e32 v1, v12, v12
	v_add_f32_e32 v0, v0, v1
	v_mul_f32_e32 v1, v15, v15
	v_fmac_f32_e32 v1, v14, v14
	v_add_f32_e32 v0, v1, v0
	v_mul_f32_e32 v1, v19, v19
	v_fmac_f32_e32 v1, v18, v18
	v_add_f32_e32 v0, v1, v0
	v_add_f32_e32 v3, v21, v0
	v_cvt_pk_bf16_f32 v11, v20, v11
	ds_bpermute_b32 v20, v187, v3
	s_waitcnt lgkmcnt(1)
	v_lshlrev_b64 v[16:17], 11, v[88:89]
	v_lshl_add_u64 v[0:1], v[16:17], 1, s[18:19]
	v_lshl_add_u64 v[6:7], v[168:169], 1, v[0:1]
	global_store_dwordx4 v[6:7], v[8:11], off sc0 sc1
	s_waitcnt lgkmcnt(0)
	v_add_f32_e32 v0, v3, v20
	ds_bpermute_b32 v1, v188, v0
	v_cvt_pk_bf16_f32 v2, v4, v5
	v_cvt_pk_bf16_f32 v3, v12, v13
	v_cvt_pk_bf16_f32 v4, v14, v15
	v_cvt_pk_bf16_f32 v5, v18, v19
	global_store_dwordx4 v[6:7], v[2:5], off offset:256 sc0 sc1
	s_and_saveexec_b64 s[36:37], s[10:11]
	s_cbranch_execz .LBB0_1724
	v_lshlrev_b64 v[2:3], 7, v[88:89]
	v_lshl_add_u64 v[2:3], s[14:15], 0, v[2:3]
	s_waitcnt lgkmcnt(0)
	v_add_f32_e32 v0, v0, v1
	global_store_dword v[2:3], v0, off

; __device__ __forceinline__ unsigned cvt_pk_bf16(float lo, float hi) { unsigned r; asm volatile("v_cvt_pk_bf16_f32 %0, %1, %2" : "=v"(r) : "v"(lo), "v"(hi)); return r; }
; __device__ __forceinline__ float dpp_up1(float x) { return __builtin_bit_cast(float, __builtin_amdgcn_update_dpp(0, __builtin_bit_cast(int, x), 0x111, 0xf, 0xf, true)); }
;     __device__ __forceinline__ void operator()(const f32x4 (&acc)[2][2][4][2], const Unit& u, int wr, int wc, int fr, int fq) const {
;     ...
;                 f32x4 pg2, pg3, pv2, pv3;
; #pragma unroll
;                 for (int e = 0; e < 4; ++e) { pg2[e] = dpp_up1(xg[2][e]); pg3[e] = dpp_up1(xg[3][e]); pv2[e] = dpp_up1(xv[2][e]); pv3[e] = dpp_up1(xv[3][e]); }
; #pragma unroll
;                 for (int m = 0; m < 4; ++m) {
;                     u32x2_t w; float o[4];
; #pragma unroll
;                     for (int e = 0; e < 4; ++e) {
;                         const float g1 = m >= 1 ? xg[m - (m >= 1 ? 1 : 0)][e] : pg3[e], g2 = m >= 2 ? xg[m - (m >= 2 ? 2 : 0)][e] : (m == 1 ? pg3[e] : pg2[e]);
;                         const float v1 = m >= 1 ? xv[m - (m >= 1 ? 1 : 0)][e] : pv3[e], v2 = m >= 2 ? xv[m - (m >= 2 ? 2 : 0)][e] : (m == 1 ? pv3[e] : pv2[e]);
;                         const float cg_ = bg[e] + w0g[e] * g2 + w1g[e] * g1 + w2g[e] * xg[m][e];
;                         const float cv_ = bv[e] + w0v[e] * v2 + w1v[e] * v1 + w2v[e] * xv[m][e];
;                         o[e] = cg_ * __builtin_amdgcn_rcpf(1.0f + __expf(-cg_)) * cv_;
;                     }
;                     w.x = cvt_pk_bf16(o[0], o[1]); w.y = cvt_pk_bf16(o[2], o[3]);
;                     const int g = g0 + m;
;                     if (n == 0) stash[ai][m] = w;
;                     else if ((fr > 0 || m >= 2) && g < TT) { u32x4 ww; ww.x = stash[ai][m].x; ww.y = stash[ai][m].y; ww.z = w.x; ww.w = w.y; *(u32x4*)(G + (size_t)g * DFF_ + f0 - 4) = ww; }
.LBB0_1802:
	v_mov_b32_dpp v46, v58 row_shr:1 row_mask:0xf bank_mask:0xf bound_ctrl:1
	v_mov_b32_dpp v115, v44 row_shr:1 row_mask:0xf bank_mask:0xf bound_ctrl:1
	s_waitcnt vmcnt(4)
	v_fma_f32 v123, v102, v46, v70
	v_fmac_f32_e32 v123, v94, v115
	v_fmac_f32_e32 v123, v98, v76
	v_mul_f32_e32 v46, 0xbfb8aa3b, v123
	v_exp_f32_e32 v124, v46
	v_mov_b32_dpp v117, v59 row_shr:1 row_mask:0xf bank_mask:0xf bound_ctrl:1
	v_mov_b32_dpp v113, v45 row_shr:1 row_mask:0xf bank_mask:0xf bound_ctrl:1
	v_fma_f32 v117, v103, v117, v71
	v_fmac_f32_e32 v117, v95, v113
	v_add_f32_e32 v124, 1.0, v124
	v_fmac_f32_e32 v117, v99, v77
	v_rcp_f32_e32 v124, v124
	v_mul_f32_e32 v125, 0xbfb8aa3b, v117
	v_mov_b32_dpp v116, v52 row_shr:1 row_mask:0xf bank_mask:0xf bound_ctrl:1
	v_exp_f32_e32 v125, v125
	v_mov_b32_dpp v114, v38 row_shr:1 row_mask:0xf bank_mask:0xf bound_ctrl:1
	s_waitcnt vmcnt(0)
	v_fma_f32 v116, v78, v116, v90
	v_fmac_f32_e32 v116, v82, v114
	v_fmac_f32_e32 v116, v86, v68
	v_mul_f32_e32 v123, v123, v124
	v_mul_f32_e32 v116, v116, v123
	v_add_f32_e32 v123, 1.0, v125
	v_mov_b32_dpp v119, v42 row_shr:1 row_mask:0xf bank_mask:0xf bound_ctrl:1
	v_rcp_f32_e32 v123, v123
	v_mov_b32_dpp v55, v32 row_shr:1 row_mask:0xf bank_mask:0xf bound_ctrl:1
	v_fma_f32 v119, v104, v119, v72
	v_fmac_f32_e32 v119, v96, v55
	v_fmac_f32_e32 v119, v100, v62
	v_mul_f32_e32 v117, v117, v123
	v_mul_f32_e32 v123, 0xbfb8aa3b, v119
	v_mov_b32_dpp v118, v53 row_shr:1 row_mask:0xf bank_mask:0xf bound_ctrl:1
	v_exp_f32_e32 v123, v123
	v_mov_b32_dpp v112, v39 row_shr:1 row_mask:0xf bank_mask:0xf bound_ctrl:1
	v_mov_b32_dpp v121, v43 row_shr:1 row_mask:0xf bank_mask:0xf bound_ctrl:1
	v_fma_f32 v118, v79, v118, v91
	v_mov_b32_dpp v47, v33 row_shr:1 row_mask:0xf bank_mask:0xf bound_ctrl:1
	v_fmac_f32_e32 v118, v83, v112
	v_fma_f32 v121, v105, v121, v73
	v_mov_b32_dpp v120, v36 row_shr:1 row_mask:0xf bank_mask:0xf bound_ctrl:1
	v_fmac_f32_e32 v118, v87, v69
	v_fmac_f32_e32 v121, v97, v47
	v_mul_f32_e32 v117, v118, v117
	v_fma_f32 v118, v80, v120, v92
	v_add_f32_e32 v120, 1.0, v123
	v_fmac_f32_e32 v121, v101, v63
	v_rcp_f32_e32 v120, v120
	v_mul_f32_e32 v123, 0xbfb8aa3b, v121
	v_exp_f32_e32 v123, v123
	v_mov_b32_dpp v54, v34 row_shr:1 row_mask:0xf bank_mask:0xf bound_ctrl:1
	v_fmac_f32_e32 v118, v84, v54
	v_fmac_f32_e32 v118, v88, v60
	v_mul_f32_e32 v119, v119, v120
	v_mul_f32_e32 v118, v118, v119
	v_add_f32_e32 v119, 1.0, v123
	v_rcp_f32_e32 v119, v119
	v_mov_b32_dpp v122, v37 row_shr:1 row_mask:0xf bank_mask:0xf bound_ctrl:1
	v_mov_b32_dpp v46, v35 row_shr:1 row_mask:0xf bank_mask:0xf bound_ctrl:1
	v_fma_f32 v120, v81, v122, v93
	v_fmac_f32_e32 v120, v85, v46
	v_cmp_gt_i32_e32 vcc, s70, v216
	v_fmac_f32_e32 v120, v89, v61
	v_mul_f32_e32 v119, v121, v119
	s_and_b64 s[6:7], s[10:11], vcc
	v_mul_f32_e32 v119, v120, v119
	v_cvt_pk_bf16_f32 v144, v116, v117
	v_cvt_pk_bf16_f32 v145, v118, v119
	s_and_saveexec_b64 s[16:17], s[6:7]
	s_cbranch_execz .LBB0_1804
	v_mov_b64_e32 v[116:117], s[30:31]
	v_mad_i64_i32 v[116:117], s[6:7], v216, s86, v[116:117]
	v_lshl_add_u64 v[116:117], v[178:179], 1, v[116:117]
	global_store_dwordx4 v[116:117], v[142:145], off sc0 sc1
.LBB0_1804:
	s_or_b64 exec, exec, s[16:17]
	v_fma_f32 v115, v102, v115, v70
	v_fmac_f32_e32 v115, v94, v76
	v_fmac_f32_e32 v115, v98, v56
	v_mul_f32_e32 v116, 0xbfb8aa3b, v115
	v_exp_f32_e32 v116, v116
	v_fma_f32 v113, v103, v113, v71
	v_fmac_f32_e32 v113, v95, v77
	v_fmac_f32_e32 v113, v99, v57
	v_add_f32_e32 v116, 1.0, v116
	v_rcp_f32_e32 v116, v116
	v_mul_f32_e32 v117, 0xbfb8aa3b, v113
	v_exp_f32_e32 v117, v117
	v_fma_f32 v114, v78, v114, v90
	v_fmac_f32_e32 v114, v82, v68
	v_fmac_f32_e32 v114, v86, v50
	v_mul_f32_e32 v115, v115, v116
	v_mul_f32_e32 v114, v114, v115
	v_add_f32_e32 v115, 1.0, v117
	v_rcp_f32_e32 v115, v115
	v_fma_f32 v55, v104, v55, v72
	v_fmac_f32_e32 v55, v96, v62
	v_fmac_f32_e32 v55, v100, v48
	v_mul_f32_e32 v113, v113, v115
	v_mul_f32_e32 v115, 0xbfb8aa3b, v55
	v_exp_f32_e32 v115, v115
	v_fma_f32 v112, v79, v112, v91
	v_fmac_f32_e32 v112, v83, v69
	v_fma_f32 v47, v105, v47, v73
	v_fmac_f32_e32 v112, v87, v51
	v_fmac_f32_e32 v47, v97, v63
	v_mul_f32_e32 v112, v112, v113
	v_add_f32_e32 v113, 1.0, v115
	v_fmac_f32_e32 v47, v101, v49
	v_rcp_f32_e32 v113, v113
	v_mul_f32_e32 v115, 0xbfb8aa3b, v47
	v_exp_f32_e32 v115, v115
	v_fma_f32 v54, v80, v54, v92
	v_fmac_f32_e32 v54, v84, v60
	v_fmac_f32_e32 v54, v88, v40
	v_mul_f32_e32 v55, v55, v113
	v_mul_f32_e32 v54, v54, v55
	v_add_f32_e32 v55, 1.0, v115
	v_rcp_f32_e32 v55, v55
	v_fma_f32 v46, v81, v46, v93
	v_fmac_f32_e32 v46, v85, v61
	v_cmp_gt_i32_e32 vcc, s70, v219
	v_fmac_f32_e32 v46, v89, v41
	v_mul_f32_e32 v47, v47, v55
	s_and_b64 s[6:7], s[10:11], vcc
	v_mul_f32_e32 v46, v46, v47
	v_cvt_pk_bf16_f32 v142, v114, v112
	v_cvt_pk_bf16_f32 v143, v54, v46
	s_and_saveexec_b64 s[16:17], s[6:7]
	s_cbranch_execz .LBB0_1806
	v_mov_b64_e32 v[46:47], s[30:31]
	v_mad_i64_i32 v[46:47], s[6:7], v219, s86, v[46:47]
	v_lshl_add_u64 v[46:47], v[178:179], 1, v[46:47]
	global_store_dwordx4 v[46:47], v[140:143], off sc0 sc1
; __device__ __forceinline__ unsigned cvt_pk_bf16(float lo, float hi) { unsigned r; asm volatile("v_cvt_pk_bf16_f32 %0, %1, %2" : "=v"(r) : "v"(lo), "v"(hi)); return r; }
; __device__ __forceinline__ float dpp_up1(float x) { return __builtin_bit_cast(float, __builtin_amdgcn_update_dpp(0, __builtin_bit_cast(int, x), 0x111, 0xf, 0xf, true)); }
;     __device__ __forceinline__ void operator()(const f32x4 (&acc)[2][2][4][2], const Unit& u, int wr, int wc, int fr, int fq) const {
;     ...
;                 f32x4 pg2, pg3, pv2, pv3;
; #pragma unroll
;                 for (int e = 0; e < 4; ++e) { pg2[e] = dpp_up1(xg[2][e]); pg3[e] = dpp_up1(xg[3][e]); pv2[e] = dpp_up1(xv[2][e]); pv3[e] = dpp_up1(xv[3][e]); }
; #pragma unroll
;                 for (int m = 0; m < 4; ++m) {
;                     u32x2_t w; float o[4];
; #pragma unroll
;                     for (int e = 0; e < 4; ++e) {
;                         const float g1 = m >= 1 ? xg[m - (m >= 1 ? 1 : 0)][e] : pg3[e], g2 = m >= 2 ? xg[m - (m >= 2 ? 2 : 0)][e] : (m == 1 ? pg3[e] : pg2[e]);
;                         const float v1 = m >= 1 ? xv[m - (m >= 1 ? 1 : 0)][e] : pv3[e], v2 = m >= 2 ? xv[m - (m >= 2 ? 2 : 0)][e] : (m == 1 ? pv3[e] : pv2[e]);
;                         const float cg_ = bg[e] + w0g[e] * g2 + w1g[e] * g1 + w2g[e] * xg[m][e];
;                         const float cv_ = bv[e] + w0v[e] * v2 + w1v[e] * v1 + w2v[e] * xv[m][e];
;                         o[e] = cg_ * __builtin_amdgcn_rcpf(1.0f + __expf(-cg_)) * cv_;
;                     }
;                     w.x = cvt_pk_bf16(o[0], o[1]); w.y = cvt_pk_bf16(o[2], o[3]);
;                     const int g = g0 + m;
;                     if (n == 0) stash[ai][m] = w;
;                     else if ((fr > 0 || m >= 2) && g < TT) { u32x4 ww; ww.x = stash[ai][m].x; ww.y = stash[ai][m].y; ww.z = w.x; ww.w = w.y; *(u32x4*)(G + (size_t)g * DFF_ + f0 - 4) = ww; }
.LBB0_1806:
	s_or_b64 exec, exec, s[16:17]
	v_fma_f32 v46, v102, v76, v70
	v_fmac_f32_e32 v46, v94, v56
	v_fmac_f32_e32 v46, v98, v58
	v_mul_f32_e32 v47, 0xbfb8aa3b, v46
	v_exp_f32_e32 v47, v47
	v_fma_f32 v55, v103, v77, v71
	v_fmac_f32_e32 v55, v95, v57
	v_fmac_f32_e32 v55, v99, v59
	v_fma_f32 v54, v78, v68, v90
	v_add_f32_e32 v47, 1.0, v47
	v_mul_f32_e32 v68, 0xbfb8aa3b, v55
	v_rcp_f32_e32 v47, v47
	v_exp_f32_e32 v68, v68
	v_fmac_f32_e32 v54, v82, v50
	v_fmac_f32_e32 v54, v86, v52
	v_mul_f32_e32 v46, v46, v47
	v_add_f32_e32 v47, 1.0, v68
	v_rcp_f32_e32 v47, v47
	v_mul_f32_e32 v46, v54, v46
	v_fma_f32 v54, v79, v69, v91
	v_fmac_f32_e32 v54, v83, v51
	v_mul_f32_e32 v47, v55, v47
	v_fma_f32 v55, v104, v62, v72
	v_fmac_f32_e32 v55, v96, v48
	v_fmac_f32_e32 v55, v100, v42
	v_mul_f32_e32 v62, 0xbfb8aa3b, v55
	v_exp_f32_e32 v62, v62
	v_fmac_f32_e32 v54, v87, v53
	v_mul_f32_e32 v47, v54, v47
	v_fma_f32 v54, v80, v60, v92
	v_add_f32_e32 v60, 1.0, v62
	v_fma_f32 v62, v105, v63, v73
	v_fmac_f32_e32 v62, v97, v49
	v_fmac_f32_e32 v62, v101, v43
	v_rcp_f32_e32 v60, v60
	v_mul_f32_e32 v63, 0xbfb8aa3b, v62
	v_exp_f32_e32 v63, v63
	v_fmac_f32_e32 v54, v84, v40
	v_fmac_f32_e32 v54, v88, v36
	v_mul_f32_e32 v55, v55, v60
	v_mul_f32_e32 v54, v54, v55
	v_add_f32_e32 v55, 1.0, v63
	v_rcp_f32_e32 v55, v55
	v_fma_f32 v60, v81, v61, v93
	v_fmac_f32_e32 v60, v85, v41
	v_fmac_f32_e32 v60, v89, v37
	v_mul_f32_e32 v55, v62, v55
	v_cmp_gt_i32_e32 vcc, s87, v216
	v_mul_f32_e32 v55, v60, v55
	v_cvt_pk_bf16_f32 v112, v46, v47
	v_cvt_pk_bf16_f32 v113, v54, v55
	s_and_saveexec_b64 s[16:17], vcc
	s_cbranch_execz .LBB0_1808
	v_mov_b64_e32 v[46:47], s[30:31]
	v_mad_i64_i32 v[46:47], s[6:7], v218, s86, v[46:47]
	v_lshl_add_u64 v[46:47], v[178:179], 1, v[46:47]
	global_store_dwordx4 v[46:47], v[110:113], off sc0 sc1
.LBB0_1808:
	s_or_b64 exec, exec, s[16:17]
	v_fma_f32 v46, v102, v56, v70
	v_fmac_f32_e32 v46, v94, v58
	v_fmac_f32_e32 v46, v98, v44
	v_mul_f32_e32 v44, 0xbfb8aa3b, v46
	v_exp_f32_e32 v44, v44
	v_fma_f32 v47, v78, v50, v90
	v_fma_f32 v50, v103, v57, v71
	v_fmac_f32_e32 v50, v95, v59
	v_fmac_f32_e32 v50, v99, v45
	v_add_f32_e32 v44, 1.0, v44
	v_mul_f32_e32 v45, 0xbfb8aa3b, v50
	v_rcp_f32_e32 v44, v44
	v_exp_f32_e32 v45, v45
	v_fmac_f32_e32 v47, v82, v52
	v_fmac_f32_e32 v47, v86, v38
	v_mul_f32_e32 v38, v46, v44
	v_add_f32_e32 v44, 1.0, v45
	v_rcp_f32_e32 v44, v44
	v_fma_f32 v45, v79, v51, v91
	v_fmac_f32_e32 v45, v83, v53
	v_fma_f32 v40, v80, v40, v92
	v_fmac_f32_e32 v45, v87, v39
	v_mul_f32_e32 v39, v50, v44
	v_fma_f32 v44, v104, v48, v72
	v_fmac_f32_e32 v40, v84, v36
	v_fma_f32 v36, v105, v49, v73
	v_fmac_f32_e32 v44, v96, v42
	v_fmac_f32_e32 v36, v97, v43
	v_fmac_f32_e32 v44, v100, v32
	v_fmac_f32_e32 v36, v101, v33
	v_mul_f32_e32 v32, 0xbfb8aa3b, v44
	v_mul_f32_e32 v33, 0xbfb8aa3b, v36
	v_exp_f32_e32 v32, v32
	v_exp_f32_e32 v33, v33
	v_fmac_f32_e32 v40, v88, v34
	v_fma_f32 v34, v81, v41, v93
	v_add_f32_e32 v32, 1.0, v32
	v_add_f32_e32 v33, 1.0, v33
	v_rcp_f32_e32 v32, v32
	v_rcp_f32_e32 v33, v33
	v_fmac_f32_e32 v34, v85, v37
	v_fmac_f32_e32 v34, v89, v35
	v_mul_f32_e32 v32, v44, v32
	v_mul_f32_e32 v33, v36, v33
	v_cmp_gt_i32_e32 vcc, s88, v216
	v_mul_f32_e32 v38, v47, v38
	v_mul_f32_e32 v39, v45, v39
	v_mul_f32_e32 v32, v40, v32
	v_mul_f32_e32 v33, v34, v33
	v_cvt_pk_bf16_f32 v110, v38, v39
	v_cvt_pk_bf16_f32 v111, v32, v33
	s_and_saveexec_b64 s[16:17], vcc
	s_cbranch_execz .LBB0_1810
	v_mov_b64_e32 v[32:33], s[30:31]
	v_mad_i64_i32 v[32:33], s[6:7], v217, s86, v[32:33]
	v_lshl_add_u64 v[32:33], v[178:179], 1, v[32:33]
	global_store_dwordx4 v[32:33], v[108:111], off sc0 sc1

; __device__ __forceinline__ unsigned cvt_pk_bf16(float lo, float hi) { unsigned r; asm volatile("v_cvt_pk_bf16_f32 %0, %1, %2" : "=v"(r) : "v"(lo), "v"(hi)); return r; }
; __device__ __forceinline__ float dpp_up1(float x) { return __builtin_bit_cast(float, __builtin_amdgcn_update_dpp(0, __builtin_bit_cast(int, x), 0x111, 0xf, 0xf, true)); }
;     __device__ __forceinline__ void operator()(const f32x4 (&acc)[2][2][4][2], const Unit& u, int wr, int wc, int fr, int fq) const {
;     ...
;                 f32x4 pg2, pg3, pv2, pv3;
; #pragma unroll
;                 for (int e = 0; e < 4; ++e) { pg2[e] = dpp_up1(xg[2][e]); pg3[e] = dpp_up1(xg[3][e]); pv2[e] = dpp_up1(xv[2][e]); pv3[e] = dpp_up1(xv[3][e]); }
; #pragma unroll
;                 for (int m = 0; m < 4; ++m) {
;                     u32x2_t w; float o[4];
; #pragma unroll
;                     for (int e = 0; e < 4; ++e) {
;                         const float g1 = m >= 1 ? xg[m - (m >= 1 ? 1 : 0)][e] : pg3[e], g2 = m >= 2 ? xg[m - (m >= 2 ? 2 : 0)][e] : (m == 1 ? pg3[e] : pg2[e]);
;                         const float v1 = m >= 1 ? xv[m - (m >= 1 ? 1 : 0)][e] : pv3[e], v2 = m >= 2 ? xv[m - (m >= 2 ? 2 : 0)][e] : (m == 1 ? pv3[e] : pv2[e]);
;                         const float cg_ = bg[e] + w0g[e] * g2 + w1g[e] * g1 + w2g[e] * xg[m][e];
;                         const float cv_ = bv[e] + w0v[e] * v2 + w1v[e] * v1 + w2v[e] * xv[m][e];
;                         o[e] = cg_ * __builtin_amdgcn_rcpf(1.0f + __expf(-cg_)) * cv_;
;                     }
;                     w.x = cvt_pk_bf16(o[0], o[1]); w.y = cvt_pk_bf16(o[2], o[3]);
;                     const int g = g0 + m;
;                     if (n == 0) stash[ai][m] = w;
;                     else if ((fr > 0 || m >= 2) && g < TT) { u32x4 ww; ww.x = stash[ai][m].x; ww.y = stash[ai][m].y; ww.z = w.x; ww.w = w.y; *(u32x4*)(G + (size_t)g * DFF_ + f0 - 4) = ww; }
.LBB0_1812:
	v_mov_b32_dpp v14, v26 row_shr:1 row_mask:0xf bank_mask:0xf bound_ctrl:1
	v_mov_b32_dpp v39, v12 row_shr:1 row_mask:0xf bank_mask:0xf bound_ctrl:1
	v_fma_f32 v47, v102, v14, v70
	v_fmac_f32_e32 v47, v94, v39
	v_fmac_f32_e32 v47, v98, v34
	v_mul_f32_e32 v14, 0xbfb8aa3b, v47
	v_exp_f32_e32 v48, v14
	v_mov_b32_dpp v41, v27 row_shr:1 row_mask:0xf bank_mask:0xf bound_ctrl:1
	v_mov_b32_dpp v37, v13 row_shr:1 row_mask:0xf bank_mask:0xf bound_ctrl:1
	v_fma_f32 v41, v103, v41, v71
	v_fmac_f32_e32 v41, v95, v37
	v_add_f32_e32 v48, 1.0, v48
	v_fmac_f32_e32 v41, v99, v35
	v_rcp_f32_e32 v48, v48
	v_mul_f32_e32 v49, 0xbfb8aa3b, v41
	v_mov_b32_dpp v40, v20 row_shr:1 row_mask:0xf bank_mask:0xf bound_ctrl:1
	v_exp_f32_e32 v49, v49
	v_mov_b32_dpp v38, v6 row_shr:1 row_mask:0xf bank_mask:0xf bound_ctrl:1
	v_fma_f32 v40, v78, v40, v90
	v_fmac_f32_e32 v40, v82, v38
	v_fmac_f32_e32 v40, v86, v32
	v_mul_f32_e32 v47, v47, v48
	v_mul_f32_e32 v40, v40, v47
	v_add_f32_e32 v47, 1.0, v49
	v_mov_b32_dpp v43, v10 row_shr:1 row_mask:0xf bank_mask:0xf bound_ctrl:1
	v_rcp_f32_e32 v47, v47
	v_mov_b32_dpp v23, v0 row_shr:1 row_mask:0xf bank_mask:0xf bound_ctrl:1
	v_fma_f32 v43, v104, v43, v72
	v_fmac_f32_e32 v43, v96, v23
	v_fmac_f32_e32 v43, v100, v30
	v_mul_f32_e32 v41, v41, v47
	v_mul_f32_e32 v47, 0xbfb8aa3b, v43
	v_mov_b32_dpp v42, v21 row_shr:1 row_mask:0xf bank_mask:0xf bound_ctrl:1
	v_exp_f32_e32 v47, v47
	v_mov_b32_dpp v36, v7 row_shr:1 row_mask:0xf bank_mask:0xf bound_ctrl:1
	v_mov_b32_dpp v45, v11 row_shr:1 row_mask:0xf bank_mask:0xf bound_ctrl:1
	v_fma_f32 v42, v79, v42, v91
	v_mov_b32_dpp v15, v1 row_shr:1 row_mask:0xf bank_mask:0xf bound_ctrl:1
	v_fmac_f32_e32 v42, v83, v36
	v_fma_f32 v45, v105, v45, v73
	v_mov_b32_dpp v44, v4 row_shr:1 row_mask:0xf bank_mask:0xf bound_ctrl:1
	v_fmac_f32_e32 v42, v87, v33
	v_fmac_f32_e32 v45, v97, v15
	v_mul_f32_e32 v41, v42, v41
	v_fma_f32 v42, v80, v44, v92
	v_add_f32_e32 v44, 1.0, v47
	v_fmac_f32_e32 v45, v101, v31
	v_rcp_f32_e32 v44, v44
	v_mul_f32_e32 v47, 0xbfb8aa3b, v45
	v_exp_f32_e32 v47, v47
	v_mov_b32_dpp v22, v2 row_shr:1 row_mask:0xf bank_mask:0xf bound_ctrl:1
	v_fmac_f32_e32 v42, v84, v22
	v_fmac_f32_e32 v42, v88, v28
	v_mul_f32_e32 v43, v43, v44
	v_mul_f32_e32 v42, v42, v43
	v_add_f32_e32 v43, 1.0, v47
	v_rcp_f32_e32 v43, v43
	v_mov_b32_dpp v46, v5 row_shr:1 row_mask:0xf bank_mask:0xf bound_ctrl:1
	v_mov_b32_dpp v14, v3 row_shr:1 row_mask:0xf bank_mask:0xf bound_ctrl:1
	v_fma_f32 v44, v81, v46, v93
	v_fmac_f32_e32 v44, v85, v14
	v_cmp_gt_i32_e32 vcc, s70, v212
	v_fmac_f32_e32 v44, v89, v29
	v_mul_f32_e32 v43, v45, v43
	s_and_b64 s[6:7], s[10:11], vcc
	v_mul_f32_e32 v43, v44, v43
	v_cvt_pk_bf16_f32 v108, v40, v41
	v_cvt_pk_bf16_f32 v109, v42, v43
	s_and_saveexec_b64 s[14:15], s[6:7]
	s_cbranch_execz .LBB0_1814
	v_mov_b64_e32 v[40:41], s[30:31]
	v_mad_i64_i32 v[40:41], s[6:7], v212, s86, v[40:41]
	v_lshl_add_u64 v[40:41], v[178:179], 1, v[40:41]
	global_store_dwordx4 v[40:41], v[106:109], off sc0 sc1
.LBB0_1814:
	s_or_b64 exec, exec, s[14:15]
	v_fma_f32 v39, v102, v39, v70
	v_fmac_f32_e32 v39, v94, v34
	v_fmac_f32_e32 v39, v98, v24
	v_mul_f32_e32 v40, 0xbfb8aa3b, v39
	v_exp_f32_e32 v40, v40
	v_fma_f32 v37, v103, v37, v71
	v_fmac_f32_e32 v37, v95, v35
	v_fmac_f32_e32 v37, v99, v25
	v_add_f32_e32 v40, 1.0, v40
	v_rcp_f32_e32 v40, v40
	v_mul_f32_e32 v41, 0xbfb8aa3b, v37
	v_exp_f32_e32 v41, v41
	v_fma_f32 v38, v78, v38, v90
	v_fmac_f32_e32 v38, v82, v32
	v_fmac_f32_e32 v38, v86, v18
	v_mul_f32_e32 v39, v39, v40
	v_mul_f32_e32 v38, v38, v39
	v_add_f32_e32 v39, 1.0, v41
	v_rcp_f32_e32 v39, v39
	v_fma_f32 v23, v104, v23, v72
	v_fmac_f32_e32 v23, v96, v30
	v_fmac_f32_e32 v23, v100, v16
	v_mul_f32_e32 v37, v37, v39
	v_mul_f32_e32 v39, 0xbfb8aa3b, v23
	v_exp_f32_e32 v39, v39
	v_fma_f32 v36, v79, v36, v91
	v_fmac_f32_e32 v36, v83, v33
	v_fma_f32 v15, v105, v15, v73
	v_fmac_f32_e32 v36, v87, v19
	v_fmac_f32_e32 v15, v97, v31
	v_mul_f32_e32 v36, v36, v37
	v_add_f32_e32 v37, 1.0, v39
	v_fmac_f32_e32 v15, v101, v17
	v_rcp_f32_e32 v37, v37
	v_mul_f32_e32 v39, 0xbfb8aa3b, v15
	v_exp_f32_e32 v39, v39
	v_fma_f32 v22, v80, v22, v92
	v_fmac_f32_e32 v22, v84, v28
	v_fmac_f32_e32 v22, v88, v8
	v_mul_f32_e32 v23, v23, v37
	v_mul_f32_e32 v22, v22, v23
	v_add_f32_e32 v23, 1.0, v39
	v_rcp_f32_e32 v23, v23
	v_fma_f32 v14, v81, v14, v93
	v_fmac_f32_e32 v14, v85, v29
	v_cmp_gt_i32_e32 vcc, s70, v215
	v_fmac_f32_e32 v14, v89, v9
	v_mul_f32_e32 v15, v15, v23
	s_and_b64 s[6:7], s[10:11], vcc
	v_mul_f32_e32 v14, v14, v15
	v_cvt_pk_bf16_f32 v76, v38, v36
	v_cvt_pk_bf16_f32 v77, v22, v14
	s_and_saveexec_b64 s[14:15], s[6:7]
	s_cbranch_execz .LBB0_1816
	v_mov_b64_e32 v[14:15], s[30:31]
	v_mad_i64_i32 v[14:15], s[6:7], v215, s86, v[14:15]
	v_lshl_add_u64 v[14:15], v[178:179], 1, v[14:15]
	global_store_dwordx4 v[14:15], v[74:77], off sc0 sc1
; __device__ __forceinline__ unsigned cvt_pk_bf16(float lo, float hi) { unsigned r; asm volatile("v_cvt_pk_bf16_f32 %0, %1, %2" : "=v"(r) : "v"(lo), "v"(hi)); return r; }
; __device__ __forceinline__ float dpp_up1(float x) { return __builtin_bit_cast(float, __builtin_amdgcn_update_dpp(0, __builtin_bit_cast(int, x), 0x111, 0xf, 0xf, true)); }
;     __device__ __forceinline__ void operator()(const f32x4 (&acc)[2][2][4][2], const Unit& u, int wr, int wc, int fr, int fq) const {
;     ...
;                 f32x4 pg2, pg3, pv2, pv3;
; #pragma unroll
;                 for (int e = 0; e < 4; ++e) { pg2[e] = dpp_up1(xg[2][e]); pg3[e] = dpp_up1(xg[3][e]); pv2[e] = dpp_up1(xv[2][e]); pv3[e] = dpp_up1(xv[3][e]); }
; #pragma unroll
;                 for (int m = 0; m < 4; ++m) {
;                     u32x2_t w; float o[4];
; #pragma unroll
;                     for (int e = 0; e < 4; ++e) {
;                         const float g1 = m >= 1 ? xg[m - (m >= 1 ? 1 : 0)][e] : pg3[e], g2 = m >= 2 ? xg[m - (m >= 2 ? 2 : 0)][e] : (m == 1 ? pg3[e] : pg2[e]);
;                         const float v1 = m >= 1 ? xv[m - (m >= 1 ? 1 : 0)][e] : pv3[e], v2 = m >= 2 ? xv[m - (m >= 2 ? 2 : 0)][e] : (m == 1 ? pv3[e] : pv2[e]);
;                         const float cg_ = bg[e] + w0g[e] * g2 + w1g[e] * g1 + w2g[e] * xg[m][e];
;                         const float cv_ = bv[e] + w0v[e] * v2 + w1v[e] * v1 + w2v[e] * xv[m][e];
;                         o[e] = cg_ * __builtin_amdgcn_rcpf(1.0f + __expf(-cg_)) * cv_;
;                     }
;                     w.x = cvt_pk_bf16(o[0], o[1]); w.y = cvt_pk_bf16(o[2], o[3]);
;                     const int g = g0 + m;
;                     if (n == 0) stash[ai][m] = w;
;                     else if ((fr > 0 || m >= 2) && g < TT) { u32x4 ww; ww.x = stash[ai][m].x; ww.y = stash[ai][m].y; ww.z = w.x; ww.w = w.y; *(u32x4*)(G + (size_t)g * DFF_ + f0 - 4) = ww; }
.LBB0_1816:
	s_or_b64 exec, exec, s[14:15]
	v_fma_f32 v14, v102, v34, v70
	v_fmac_f32_e32 v14, v94, v24
	v_fmac_f32_e32 v14, v98, v26
	v_mul_f32_e32 v15, 0xbfb8aa3b, v14
	v_exp_f32_e32 v15, v15
	v_fma_f32 v23, v103, v35, v71
	v_fmac_f32_e32 v23, v95, v25
	v_fmac_f32_e32 v23, v99, v27
	v_fma_f32 v22, v78, v32, v90
	v_add_f32_e32 v15, 1.0, v15
	v_mul_f32_e32 v32, 0xbfb8aa3b, v23
	v_rcp_f32_e32 v15, v15
	v_exp_f32_e32 v32, v32
	v_fmac_f32_e32 v22, v82, v18
	v_fmac_f32_e32 v22, v86, v20
	v_mul_f32_e32 v14, v14, v15
	v_add_f32_e32 v15, 1.0, v32
	v_rcp_f32_e32 v15, v15
	v_mul_f32_e32 v14, v22, v14
	v_fma_f32 v22, v79, v33, v91
	v_fmac_f32_e32 v22, v83, v19
	v_mul_f32_e32 v15, v23, v15
	v_fma_f32 v23, v104, v30, v72
	v_fmac_f32_e32 v23, v96, v16
	v_fmac_f32_e32 v23, v100, v10
	v_mul_f32_e32 v30, 0xbfb8aa3b, v23
	v_exp_f32_e32 v30, v30
	v_fmac_f32_e32 v22, v87, v21
	v_mul_f32_e32 v15, v22, v15
	v_fma_f32 v22, v80, v28, v92
	v_add_f32_e32 v28, 1.0, v30
	v_fma_f32 v30, v105, v31, v73
	v_fmac_f32_e32 v30, v97, v17
	v_fmac_f32_e32 v30, v101, v11
	v_rcp_f32_e32 v28, v28
	v_mul_f32_e32 v31, 0xbfb8aa3b, v30
	v_exp_f32_e32 v31, v31
	v_fmac_f32_e32 v22, v84, v8
	v_fmac_f32_e32 v22, v88, v4
	v_mul_f32_e32 v23, v23, v28
	v_mul_f32_e32 v22, v22, v23
	v_add_f32_e32 v23, 1.0, v31
	v_rcp_f32_e32 v23, v23
	v_fma_f32 v28, v81, v29, v93
	v_fmac_f32_e32 v28, v85, v9
	v_fmac_f32_e32 v28, v89, v5
	v_mul_f32_e32 v23, v30, v23
	v_cmp_gt_i32_e32 vcc, s87, v212
	v_mul_f32_e32 v23, v28, v23
	v_cvt_pk_bf16_f32 v68, v14, v15
	v_cvt_pk_bf16_f32 v69, v22, v23
	s_and_saveexec_b64 s[14:15], vcc
	s_cbranch_execz .LBB0_1818
	v_mov_b64_e32 v[14:15], s[30:31]
	v_mad_i64_i32 v[14:15], s[6:7], v214, s86, v[14:15]
	v_lshl_add_u64 v[14:15], v[178:179], 1, v[14:15]
	global_store_dwordx4 v[14:15], v[66:69], off sc0 sc1
.LBB0_1818:
	s_or_b64 exec, exec, s[14:15]
	v_fma_f32 v14, v102, v24, v70
	v_fmac_f32_e32 v14, v94, v26
	v_fmac_f32_e32 v14, v98, v12
	v_mul_f32_e32 v12, 0xbfb8aa3b, v14
	v_exp_f32_e32 v12, v12
	v_fma_f32 v15, v78, v18, v90
	v_fma_f32 v18, v103, v25, v71
	v_fmac_f32_e32 v18, v95, v27
	v_fmac_f32_e32 v18, v99, v13
	v_add_f32_e32 v12, 1.0, v12
	v_mul_f32_e32 v13, 0xbfb8aa3b, v18
	v_rcp_f32_e32 v12, v12
	v_exp_f32_e32 v13, v13
	v_fmac_f32_e32 v15, v82, v20
	v_fmac_f32_e32 v15, v86, v6
	v_mul_f32_e32 v6, v14, v12
	v_add_f32_e32 v12, 1.0, v13
	v_rcp_f32_e32 v12, v12
	v_fma_f32 v13, v79, v19, v91
	v_fmac_f32_e32 v13, v83, v21
	v_fmac_f32_e32 v13, v87, v7
	v_mul_f32_e32 v7, v18, v12
	v_fma_f32 v12, v104, v16, v72
	v_fmac_f32_e32 v73, v105, v17
	v_fmac_f32_e32 v12, v96, v10
	v_fmac_f32_e32 v73, v97, v11
	v_fmac_f32_e32 v12, v100, v0
	v_fmac_f32_e32 v73, v101, v1
	v_mul_f32_e32 v0, 0xbfb8aa3b, v12
	v_mul_f32_e32 v1, 0xbfb8aa3b, v73
	v_exp_f32_e32 v0, v0
	v_exp_f32_e32 v1, v1
	v_fma_f32 v8, v80, v8, v92
	v_fmac_f32_e32 v93, v81, v9
	v_add_f32_e32 v0, 1.0, v0
	v_add_f32_e32 v1, 1.0, v1
	v_rcp_f32_e32 v0, v0
	v_rcp_f32_e32 v1, v1
	v_fmac_f32_e32 v8, v84, v4
	v_fmac_f32_e32 v93, v85, v5
	v_fmac_f32_e32 v8, v88, v2
	v_mul_f32_e32 v0, v12, v0
	v_fmac_f32_e32 v93, v89, v3
	v_mul_f32_e32 v1, v73, v1
	v_cmp_gt_i32_e32 vcc, s88, v212
	v_mul_f32_e32 v6, v15, v6
	v_mul_f32_e32 v7, v13, v7
	v_mul_f32_e32 v0, v8, v0
	v_mul_f32_e32 v1, v93, v1
	v_cvt_pk_bf16_f32 v66, v6, v7
	v_cvt_pk_bf16_f32 v67, v0, v1
	s_and_saveexec_b64 s[14:15], vcc
	s_cbranch_execz .LBB0_1820
	v_mov_b64_e32 v[0:1], s[30:31]
	v_mad_i64_i32 v[0:1], s[6:7], v213, s86, v[0:1]
	v_lshl_add_u64 v[0:1], v[178:179], 1, v[0:1]
	global_store_dwordx4 v[0:1], v[64:67], off sc0 sc1

; #define LAS __attribute__((address_space(3)))
; __device__ __forceinline__ unsigned cvtpk(float lo, float hi) { f32x2 v = {lo, hi}; bf16x2_t b = __builtin_convertvector(v, bf16x2_t); return __builtin_bit_cast(unsigned, b); }
; __device__ __forceinline__ void witem_store(const WItem& w, int K, bf16_t* WT, int kvperm, LAS float* scr, int item, int nblk, int lane) {
;     ...
;     for (int i = 0; i < 8; ++i) { LAS float* d = scr + (8 * i + rr) * 33 + col; const float g = w.g[i]; d[0] = w.v[i].x * g; d[1] = w.v[i].y * g; d[2] = w.v[i].z * g; d[3] = w.v[i].w * g; }
;     asm volatile("s_waitcnt lgkmcnt(0)" ::: "memory");
;     const int c = lane & 7;
; #pragma unroll
;     for (int j = 0; j < 4; ++j) { const int n = (lane >> 3) + 8 * j; const LAS float* s = scr + (8 * c) * 33 + n;
;         u32x4 o; o.x = cvtpk(s[0 * 33], s[1 * 33]); o.y = cvtpk(s[2 * 33], s[3 * 33]); o.z = cvtpk(s[4 * 33], s[5 * 33]); o.w = cvtpk(s[6 * 33], s[7 * 33]);
;         int nr = n0 + n; if (kvperm == 1) { const int hh = nr >> 8, ww = nr & 255; nr = (ww < 128) ? hh * 128 + ww : 2048 + hh * 128 + (ww - 128); }
;         else if (kvperm == 2) { const int isv = nr >= 5632, f = isv ? nr - 5632 : nr; nr = (f >> 7) * 256 + isv * 128 + (f & 127); }
;         *(u32x4*)(WT + (size_t)nr * K + k0 + 8 * c) = o; }
.LBB0_1844:
	v_pk_mul_f32 v[2:3], v[12:13], v[72:73] op_sel_hi:[1,0]
	ds_write2_b32 v79, v2, v3 offset1:1
	v_pk_mul_f32 v[2:3], v[14:15], v[72:73] op_sel_hi:[1,0]
	ds_write2_b32 v79, v2, v3 offset0:2 offset1:3
	v_pk_mul_f32 v[2:3], v[4:5], v[74:75] op_sel_hi:[1,0]
	v_add_u32_e32 v4, 0x420, v79
	ds_write2_b32 v4, v2, v3 offset1:1
	v_pk_mul_f32 v[2:3], v[6:7], v[74:75] op_sel_hi:[1,0]
	v_add_u32_e32 v4, 0x428, v79
	ds_write2_b32 v4, v2, v3 offset1:1
	v_pk_mul_f32 v[2:3], v[24:25], v[76:77] op_sel_hi:[1,0]
	v_add_u32_e32 v4, 0x840, v79
	ds_write2_b32 v4, v2, v3 offset1:1
	v_pk_mul_f32 v[2:3], v[26:27], v[76:77] op_sel_hi:[1,0]
	v_add_u32_e32 v4, 0x848, v79
	ds_write2_b32 v4, v2, v3 offset1:1
	v_pk_mul_f32 v[2:3], v[20:21], v[78:79] op_sel_hi:[1,0]
	v_add_u32_e32 v4, 0xc60, v79
	ds_write2_b32 v4, v2, v3 offset1:1
	v_pk_mul_f32 v[2:3], v[22:23], v[78:79] op_sel_hi:[1,0]
	v_add_u32_e32 v4, 0xc68, v79
	ds_write2_b32 v4, v2, v3 offset1:1
	v_pk_mul_f32 v[2:3], v[36:37], v[80:81] op_sel_hi:[1,0]
	v_add_u32_e32 v4, 0x1080, v79
	ds_write2_b32 v4, v2, v3 offset1:1
	v_pk_mul_f32 v[2:3], v[38:39], v[80:81] op_sel_hi:[1,0]
	v_add_u32_e32 v4, 0x1088, v79
	ds_write2_b32 v4, v2, v3 offset1:1
	v_pk_mul_f32 v[2:3], v[28:29], v[82:83] op_sel_hi:[1,0]
	v_add_u32_e32 v4, 0x14a0, v79
	ds_write2_b32 v4, v2, v3 offset1:1
	v_pk_mul_f32 v[2:3], v[30:31], v[82:83] op_sel_hi:[1,0]
	v_add_u32_e32 v4, 0x14a8, v79
	ds_write2_b32 v4, v2, v3 offset1:1
	s_waitcnt vmcnt(7)
	v_pk_mul_f32 v[2:3], v[48:49], v[84:85] op_sel_hi:[1,0]
	v_add_u32_e32 v4, 0x18c0, v79
	s_mul_hi_i32 s6, s6, 0x2e8ba2e9
	ds_write2_b32 v4, v2, v3 offset1:1
	v_pk_mul_f32 v[2:3], v[50:51], v[84:85] op_sel_hi:[1,0]
	v_add_u32_e32 v4, 0x18c8, v79
	s_lshr_b32 s12, s6, 31
	s_ashr_i32 s6, s6, 6
	ds_write2_b32 v4, v2, v3 offset1:1
	s_waitcnt vmcnt(6)
	v_pk_mul_f32 v[2:3], v[44:45], v[86:87] op_sel_hi:[1,0]
	v_add_u32_e32 v4, 0x1ce0, v79
	s_add_i32 s6, s6, s12
	ds_write2_b32 v4, v2, v3 offset1:1
	v_pk_mul_f32 v[2:3], v[46:47], v[86:87] op_sel_hi:[1,0]
	v_add_u32_e32 v4, 0x1ce8, v79
	s_lshl_b32 s12, s6, 6
	ds_write2_b32 v4, v2, v3 offset1:1
	s_mulk_i32 s6, 0xd400
	s_waitcnt lgkmcnt(0)
	s_add_i32 s6, s6, s7
	ds_read2_b32 v[6:7], v77 offset0:33 offset1:41
	ds_read2_b32 v[12:13], v77 offset1:8
	ds_read2_b32 v[14:15], v77 offset0:66 offset1:74
	ds_read2_b32 v[20:21], v77 offset0:99 offset1:107
	ds_read2_b32 v[22:23], v77 offset0:132 offset1:140
	ds_read2_b32 v[24:25], v77 offset0:165 offset1:173
	ds_read2_b32 v[26:27], v77 offset0:198 offset1:206
	ds_read2_b32 v[28:29], v77 offset0:231 offset1:239
	v_add_u32_e32 v38, s6, v83
	s_waitcnt lgkmcnt(6)
	v_cvt_pk_bf16_f32 v2, v12, v6
	v_add_u32_e32 v6, 0xffffea00, v38
	v_cmp_lt_i32_e32 vcc, s18, v38
	s_waitcnt lgkmcnt(4)
	v_cvt_pk_bf16_f32 v3, v14, v20
	s_ashr_i32 s13, s12, 31
	v_cndmask_b32_e32 v6, v38, v6, vcc
	v_lshlrev_b32_e32 v12, 1, v6
	v_and_b32_e32 v12, 0xffffff00, v12
	v_cndmask_b32_e32 v14, 0, v81, vcc
	v_and_b32_e32 v6, 0x67, v6
	v_or3_b32 v36, v6, v14, v12
	v_ashrrev_i32_e32 v37, 31, v36
	v_lshl_add_u64 v[30:31], s[12:13], 1, v[70:71]
	v_lshlrev_b64 v[36:37], 12, v[36:37]
	s_waitcnt lgkmcnt(2)
	v_cvt_pk_bf16_f32 v4, v22, v24
	s_waitcnt lgkmcnt(0)
	v_cvt_pk_bf16_f32 v5, v26, v28
	v_lshl_add_u64 v[36:37], v[30:31], 0, v[36:37]
	v_add_u32_e32 v6, 8, v38
	global_store_dwordx4 v[36:37], v[2:5], off sc0 sc1
	v_cmp_lt_i32_e32 vcc, s18, v6
	s_waitcnt vmcnt(3)
	v_mov_b64_e32 v[48:49], v[60:61]
	v_cvt_pk_bf16_f32 v2, v13, v7
	v_add_u32_e32 v7, 0xffffea08, v38
	v_cndmask_b32_e32 v6, v6, v7, vcc
	v_lshlrev_b32_e32 v7, 1, v6
	v_and_b32_e32 v7, 0xffffff00, v7
	v_cndmask_b32_e32 v12, 0, v81, vcc
	v_and_b32_e32 v6, 0x6f, v6
	v_or3_b32 v6, v6, v12, v7
	v_ashrrev_i32_e32 v7, 31, v6
	v_lshlrev_b64 v[6:7], 12, v[6:7]
	v_cvt_pk_bf16_f32 v3, v15, v21
	v_cvt_pk_bf16_f32 v4, v23, v25
	v_cvt_pk_bf16_f32 v5, v27, v29
	v_lshl_add_u64 v[6:7], v[30:31], 0, v[6:7]
	ds_read2_b32 v[12:13], v77 offset0:16 offset1:24
	ds_read2_b32 v[14:15], v77 offset0:49 offset1:57
	ds_read2_b32 v[20:21], v77 offset0:82 offset1:90
	ds_read2_b32 v[22:23], v77 offset0:115 offset1:123
	ds_read2_b32 v[24:25], v77 offset0:148 offset1:156
	ds_read2_b32 v[26:27], v77 offset0:181 offset1:189
	ds_read2_b32 v[28:29], v77 offset0:214 offset1:222
	ds_read2_b32 v[36:37], v77 offset0:247 offset1:255
	global_store_dwordx4 v[6:7], v[2:5], off sc0 sc1
	v_add_u32_e32 v6, 16, v38
	v_add_u32_e32 v7, 0xffffea10, v38
	v_cmp_lt_i32_e32 vcc, s18, v6
	s_waitcnt lgkmcnt(6)
	v_cvt_pk_bf16_f32 v2, v12, v14
	s_waitcnt lgkmcnt(4)
	v_cvt_pk_bf16_f32 v3, v20, v22
	v_cndmask_b32_e32 v6, v6, v7, vcc
	v_lshlrev_b32_e32 v7, 1, v6
	v_and_b32_e32 v7, 0xffffff00, v7
	v_cndmask_b32_e32 v12, 0, v81, vcc
	v_and_b32_e32 v6, 0x77, v6
	v_or3_b32 v6, v6, v12, v7
	v_ashrrev_i32_e32 v7, 31, v6
	v_lshlrev_b64 v[6:7], 12, v[6:7]
	s_waitcnt lgkmcnt(2)
	v_cvt_pk_bf16_f32 v4, v24, v26
	s_waitcnt lgkmcnt(0)
	v_cvt_pk_bf16_f32 v5, v28, v36
	v_lshl_add_u64 v[6:7], v[30:31], 0, v[6:7]
	global_store_dwordx4 v[6:7], v[2:5], off sc0 sc1
	s_waitcnt vmcnt(4)
	v_mov_b64_e32 v[44:45], v[64:65]
	v_add_u32_e32 v83, s14, v83
	v_add_u32_e32 v2, 24, v38
	v_add_u32_e32 v3, 0xffffea18, v38
	v_cmp_lt_i32_e32 vcc, s18, v2
	v_cvt_pk_bf16_f32 v5, v29, v37
	v_mov_b64_e32 v[36:37], v[52:53]
	v_cndmask_b32_e32 v2, v2, v3, vcc
	v_lshlrev_b32_e32 v3, 1, v2
	v_and_b32_e32 v3, 0xffffff00, v3
	v_cndmask_b32_e32 v4, 0, v81, vcc
	v_and_b32_e32 v2, 0x7f, v2
	v_or3_b32 v6, v2, v4, v3
	v_ashrrev_i32_e32 v7, 31, v6
	v_lshlrev_b64 v[6:7], 12, v[6:7]
	v_cvt_pk_bf16_f32 v2, v13, v15
	v_cvt_pk_bf16_f32 v3, v21, v23
	v_cvt_pk_bf16_f32 v4, v25, v27
	v_lshl_add_u64 v[6:7], v[30:31], 0, v[6:7]
	global_store_dwordx4 v[6:7], v[2:5], off sc0 sc1
	s_waitcnt lgkmcnt(0)
	v_mov_b64_e32 v[12:13], v[16:17]
	v_mov_b64_e32 v[24:25], v[32:33]
	v_mov_b64_e32 v[4:5], v[8:9]
	v_mov_b64_e32 v[20:21], v[40:41]
	v_mov_b64_e32 v[28:29], v[56:57]
	s_add_i32 s19, s19, s14
	v_add_u32_e32 v73, s14, v73
	s_andn2_b64 vcc, exec, s[10:11]
	s_mov_b32 s6, s20
	v_mov_b64_e32 v[14:15], v[18:19]
	v_mov_b64_e32 v[6:7], v[10:11]
	v_mov_b64_e32 v[26:27], v[34:35]
	v_mov_b64_e32 v[22:23], v[42:43]
	v_mov_b64_e32 v[38:39], v[54:55]
	v_mov_b64_e32 v[30:31], v[58:59]
	v_mov_b64_e32 v[50:51], v[62:63]
	v_mov_b64_e32 v[46:47], v[66:67]
	v_mov_b32_e32 v72, v85
	v_mov_b32_e32 v74, v87
	v_mov_b32_e32 v76, v89
	v_mov_b32_e32 v78, v94
	v_mov_b32_e32 v80, v95
	v_mov_b32_e32 v82, v96
	v_mov_b32_e32 v84, v97
	s_waitcnt vmcnt(4)
	v_mov_b32_e32 v86, v1
	s_cbranch_vccz .LBB0_1862

; __device__ __forceinline__ unsigned cvt_pk_bf16(float lo, float hi) { unsigned r; asm volatile("v_cvt_pk_bf16_f32 %0, %1, %2" : "=v"(r) : "v"(lo), "v"(hi)); return r; }
;     __device__ __forceinline__ void operator()(const f32x4 (&acc)[2][2][4][2], const Unit& u, int wr, int wc, int fr, int fq) const {
;         const int row0 = u.pm * BM + wr * 64 + fr, col0 = u.pn * BM + wc * 32 + 8 * fq;
;         f32x4 bv[2][2];
; #pragma unroll
;         for (int bj = 0; bj < 2; ++bj)
; #pragma unroll
;             for (int n = 0; n < 2; ++n) bv[bj][n] = bias ? *(const f32x4*)(bias + col0 + bj * HALF + 4 * n) : (f32x4){0.f, 0.f, 0.f, 0.f};
;         float* ssp = ssout + (size_t)(u.pn * 4 + wc);
; #pragma unroll
;         for (int ai = 0; ai < 2; ++ai) {
;             u32x4 old[4][2];
; #pragma unroll
;             for (int m = 0; m < 4; ++m)
; #pragma unroll
;                 for (int bj = 0; bj < 2; ++bj) old[m][bj] = *(const u32x4*)(HB + (size_t)(row0 + ai * HALF + m * 16) * ldc + col0 + bj * HALF);
; #pragma unroll
;             for (int m = 0; m < 4; ++m) { const int row = row0 + ai * HALF + m * 16; float ss = 0.f;
; #pragma unroll
;                 for (int bj = 0; bj < 2; ++bj) { const u32x4 ow = old[m][bj];
;                     f32x4 v0 = (acc[ai][bj][m][0] + bv[bj][0]) * accs, v1 = (acc[ai][bj][m][1] + bv[bj][1]) * accs;
;                     v0[0] += __uint_as_float(ow.x << 16); v0[1] += __uint_as_float(ow.x & 0xffff0000u); v0[2] += __uint_as_float(ow.y << 16); v0[3] += __uint_as_float(ow.y & 0xffff0000u);
;                     v1[0] += __uint_as_float(ow.z << 16); v1[1] += __uint_as_float(ow.z & 0xffff0000u); v1[2] += __uint_as_float(ow.w << 16); v1[3] += __uint_as_float(ow.w & 0xffff0000u);
;                     ss += (v0[0] * v0[0] + v0[1] * v0[1]) + (v0[2] * v0[2] + v0[3] * v0[3]) + (v1[0] * v1[0] + v1[1] * v1[1]) + (v1[2] * v1[2] + v1[3] * v1[3]);
;                     u32x4 w; w.x = cvt_pk_bf16(v0[0], v0[1]); w.y = cvt_pk_bf16(v0[2], v0[3]); w.z = cvt_pk_bf16(v1[0], v1[1]); w.w = cvt_pk_bf16(v1[2], v1[3]);
;                     *(u32x4*)(HB + (size_t)row * ldc + col0 + bj * HALF) = w; }
;                 ss += __shfl_xor(ss, 16); ss += __shfl_xor(ss, 32);
;                 if (fq == 0) ssp[(size_t)row * 32] = ss; }
.LBB0_1940:
	v_lshl_or_b32 v152, s6, 8, v166
	v_ashrrev_i32_e32 v153, 31, v152
	v_lshl_add_u32 v154, s7, 8, v164
	v_lshlrev_b64 v[180:181], 1, v[152:153]
	v_ashrrev_i32_e32 v155, 31, v154
	v_lshl_add_u64 v[156:157], s[16:17], 0, v[180:181]
	v_lshlrev_b64 v[182:183], 12, v[154:155]
	v_lshl_add_u64 v[128:129], v[156:157], 0, v[182:183]
	global_load_dwordx4 v[172:175], v[128:129], off
	global_load_dwordx4 v[176:179], v[128:129], off offset:256
	v_or_b32_e32 v162, 16, v154
	v_or_b32_e32 v160, 32, v154
	v_or_b32_e32 v158, 48, v154
	v_ashrrev_i32_e32 v163, 31, v162
	v_ashrrev_i32_e32 v161, 31, v160
	v_pk_add_f32 v[196:197], v[114:115], 0 op_sel_hi:[1,0]
	v_pk_add_f32 v[198:199], v[112:113], 0 op_sel_hi:[1,0]
	v_ashrrev_i32_e32 v159, 31, v158
	v_lshlrev_b64 v[112:113], 12, v[162:163]
	v_lshlrev_b64 v[114:115], 12, v[160:161]
	v_pk_add_f32 v[194:195], v[116:117], 0 op_sel_hi:[1,0]
	v_lshlrev_b64 v[116:117], 12, v[158:159]
	v_lshl_add_u64 v[112:113], v[156:157], 0, v[112:113]
	v_lshl_add_u64 v[114:115], v[156:157], 0, v[114:115]
	v_pk_add_f32 v[184:185], v[126:127], 0 op_sel_hi:[1,0]
	v_pk_add_f32 v[186:187], v[124:125], 0 op_sel_hi:[1,0]
	v_pk_add_f32 v[188:189], v[122:123], 0 op_sel_hi:[1,0]
	v_pk_add_f32 v[190:191], v[120:121], 0 op_sel_hi:[1,0]
	v_pk_add_f32 v[192:193], v[118:119], 0 op_sel_hi:[1,0]
	v_lshl_add_u64 v[200:201], v[156:157], 0, v[116:117]
	global_load_dwordx4 v[132:135], v[112:113], off
	global_load_dwordx4 v[128:131], v[112:113], off offset:256
	global_load_dwordx4 v[124:127], v[114:115], off
	global_load_dwordx4 v[120:123], v[114:115], off offset:256
	global_load_dwordx4 v[116:119], v[200:201], off
	s_nop 0
	global_load_dwordx4 v[112:115], v[200:201], off offset:256
	s_lshl_b32 s6, s6, 2
	s_or_b32 s6, s6, s44
	s_ashr_i32 s7, s6, 31
	s_lshl_b64 s[6:7], s[6:7], 2
	s_add_u32 s24, s42, s6
	s_addc_u32 s25, s43, s7
	s_waitcnt vmcnt(0)
	v_lshlrev_b32_e32 v171, 16, v172
	v_and_b32_e32 v172, 0xffff0000, v172
	v_lshlrev_b32_e32 v200, 16, v173
	v_and_b32_e32 v173, 0xffff0000, v173
	v_lshlrev_b32_e32 v201, 16, v174
	v_lshlrev_b32_e32 v202, 16, v175
	v_lshlrev_b32_e32 v203, 16, v176
	v_and_b32_e32 v176, 0xffff0000, v176
	v_lshlrev_b32_e32 v206, 16, v177
	v_and_b32_e32 v177, 0xffff0000, v177
	v_add_f32_e32 v172, v187, v172
	v_add_f32_e32 v173, v185, v173
	v_and_b32_e32 v175, 0xffff0000, v175
	v_lshlrev_b32_e32 v207, 16, v178
	v_and_b32_e32 v178, 0xffff0000, v178
	v_lshlrev_b32_e32 v208, 16, v179
	v_add_f32_e32 v171, v186, v171
	v_add_f32_e32 v184, v184, v200
	v_add_f32_e32 v185, v190, v201
	v_add_f32_e32 v186, v188, v202
	v_add_f32_e32 v188, v195, v176
	v_add_f32_e32 v190, v193, v177
	v_mul_f32_e32 v176, v172, v172
	v_mul_f32_e32 v177, v173, v173
	v_and_b32_e32 v174, 0xffff0000, v174
	v_add_f32_e32 v175, v189, v175
	v_add_f32_e32 v187, v194, v203
	v_add_f32_e32 v189, v192, v206
	v_add_f32_e32 v178, v199, v178
	v_add_f32_e32 v192, v196, v208
	v_mul_f32_e32 v195, v188, v188
	v_mul_f32_e32 v196, v190, v190
	v_fmac_f32_e32 v176, v171, v171
	v_fmac_f32_e32 v177, v184, v184
	v_and_b32_e32 v179, 0xffff0000, v179
	v_add_f32_e32 v174, v191, v174
	v_add_f32_e32 v191, v198, v207
	v_cvt_pk_bf16_f32 v172, v171, v172
	v_fmac_f32_e32 v195, v187, v187
	v_add_f32_e32 v171, v176, v177
	v_fmac_f32_e32 v196, v189, v189
	v_mul_f32_e32 v177, v178, v178
	v_add_f32_e32 v179, v197, v179
	v_mul_f32_e32 v193, v174, v174
	v_add_f32_e32 v176, v195, v196
	v_fmac_f32_e32 v177, v191, v191
	v_mul_f32_e32 v194, v175, v175
	v_fmac_f32_e32 v193, v185, v185
	v_add_f32_e32 v176, v177, v176
	v_mul_f32_e32 v177, v179, v179
	v_fmac_f32_e32 v194, v186, v186
	v_add_f32_e32 v171, v193, v171
	v_fmac_f32_e32 v177, v192, v192
	v_add_f32_e32 v171, v194, v171
	v_add_f32_e32 v176, v177, v176
	v_cvt_pk_bf16_f32 v173, v184, v173
	v_add_f32_e32 v184, v171, v176
	v_and_b32_e32 v176, 64, v170
	v_cvt_pk_bf16_f32 v174, v185, v174
	v_xor_b32_e32 v171, 16, v170
	v_add_u32_e32 v185, 64, v176
	v_cmp_lt_i32_e32 vcc, v171, v185
	v_cvt_pk_bf16_f32 v175, v186, v175
	v_lshl_add_u64 v[176:177], s[16:17], 0, v[182:183]
	v_lshl_add_u64 v[180:181], v[176:177], 0, v[180:181]
	v_cndmask_b32_e32 v171, v170, v171, vcc
	v_lshlrev_b32_e32 v171, 2, v171
	ds_bpermute_b32 v186, v171, v184
	global_store_dwordx4 v[180:181], v[172:175], off sc0 sc1
	v_cvt_pk_bf16_f32 v176, v187, v188
	v_cvt_pk_bf16_f32 v177, v189, v190
	v_cvt_pk_bf16_f32 v178, v191, v178
	v_cvt_pk_bf16_f32 v179, v192, v179
	global_store_dwordx4 v[180:181], v[176:179], off offset:256 sc0 sc1
	s_nop 0
	v_xor_b32_e32 v172, 32, v170
	v_cmp_lt_i32_e32 vcc, v172, v185
	s_waitcnt lgkmcnt(0)
	v_add_f32_e32 v173, v184, v186
	v_cndmask_b32_e32 v172, v170, v172, vcc
	v_lshlrev_b32_e32 v172, 2, v172
	ds_bpermute_b32 v174, v172, v173
	s_and_saveexec_b64 s[26:27], s[10:11]
	s_cbranch_execz .LBB0_1942
	v_lshlrev_b64 v[176:177], 7, v[154:155]
	v_lshl_add_u64 v[176:177], s[24:25], 0, v[176:177]
	s_waitcnt lgkmcnt(0)
	v_add_f32_e32 v155, v173, v174
	global_store_dword v[176:177], v155, off
; __device__ __forceinline__ unsigned cvt_pk_bf16(float lo, float hi) { unsigned r; asm volatile("v_cvt_pk_bf16_f32 %0, %1, %2" : "=v"(r) : "v"(lo), "v"(hi)); return r; }
;     __device__ __forceinline__ void operator()(const f32x4 (&acc)[2][2][4][2], const Unit& u, int wr, int wc, int fr, int fq) const {
;     ...
;                 for (int bj = 0; bj < 2; ++bj) old[m][bj] = *(const u32x4*)(HB + (size_t)(row0 + ai * HALF + m * 16) * ldc + col0 + bj * HALF);
; #pragma unroll
;             for (int m = 0; m < 4; ++m) { const int row = row0 + ai * HALF + m * 16; float ss = 0.f;
; #pragma unroll
;                 for (int bj = 0; bj < 2; ++bj) { const u32x4 ow = old[m][bj];
;                     f32x4 v0 = (acc[ai][bj][m][0] + bv[bj][0]) * accs, v1 = (acc[ai][bj][m][1] + bv[bj][1]) * accs;
;                     v0[0] += __uint_as_float(ow.x << 16); v0[1] += __uint_as_float(ow.x & 0xffff0000u); v0[2] += __uint_as_float(ow.y << 16); v0[3] += __uint_as_float(ow.y & 0xffff0000u);
;                     v1[0] += __uint_as_float(ow.z << 16); v1[1] += __uint_as_float(ow.z & 0xffff0000u); v1[2] += __uint_as_float(ow.w << 16); v1[3] += __uint_as_float(ow.w & 0xffff0000u);
;                     ss += (v0[0] * v0[0] + v0[1] * v0[1]) + (v0[2] * v0[2] + v0[3] * v0[3]) + (v1[0] * v1[0] + v1[1] * v1[1]) + (v1[2] * v1[2] + v1[3] * v1[3]);
;                     u32x4 w; w.x = cvt_pk_bf16(v0[0], v0[1]); w.y = cvt_pk_bf16(v0[2], v0[3]); w.z = cvt_pk_bf16(v1[0], v1[1]); w.w = cvt_pk_bf16(v1[2], v1[3]);
;                     *(u32x4*)(HB + (size_t)row * ldc + col0 + bj * HALF) = w; }
;                 ss += __shfl_xor(ss, 16); ss += __shfl_xor(ss, 32);
;                 if (fq == 0) ssp[(size_t)row * 32] = ss; }
.LBB0_1942:
	s_or_b64 exec, exec, s[26:27]
	v_pk_add_f32 v[108:109], v[108:109], 0 op_sel_hi:[1,0]
	v_lshlrev_b32_e32 v155, 16, v132
	v_and_b32_e32 v132, 0xffff0000, v132
	v_pk_add_f32 v[110:111], v[110:111], 0 op_sel_hi:[1,0]
	v_add_f32_e32 v109, v109, v132
	v_lshlrev_b32_e32 v132, 16, v133
	v_add_f32_e32 v110, v110, v132
	v_and_b32_e32 v132, 0xffff0000, v133
	v_pk_add_f32 v[104:105], v[104:105], 0 op_sel_hi:[1,0]
	v_add_f32_e32 v111, v111, v132
	v_lshlrev_b32_e32 v132, 16, v134
	v_add_f32_e32 v132, v104, v132
	v_and_b32_e32 v104, 0xffff0000, v134
	v_pk_add_f32 v[106:107], v[106:107], 0 op_sel_hi:[1,0]
	v_add_f32_e32 v133, v105, v104
	v_lshlrev_b32_e32 v104, 16, v135
	v_add_f32_e32 v134, v106, v104
	v_and_b32_e32 v104, 0xffff0000, v135
	v_add_f32_e32 v108, v108, v155
	v_add_f32_e32 v107, v107, v104
	v_mul_f32_e32 v104, v109, v109
	v_mul_f32_e32 v105, v111, v111
	v_fmac_f32_e32 v104, v108, v108
	v_fmac_f32_e32 v105, v110, v110
	v_add_f32_e32 v104, v104, v105
	v_mul_f32_e32 v105, v133, v133
	v_fmac_f32_e32 v105, v132, v132
	v_add_f32_e32 v104, v105, v104
	v_mul_f32_e32 v105, v107, v107
	v_fmac_f32_e32 v105, v134, v134
	v_add_f32_e32 v135, v105, v104
	v_cvt_pk_bf16_f32 v104, v108, v109
	v_pk_add_f32 v[100:101], v[100:101], 0 op_sel_hi:[1,0]
	v_lshlrev_b32_e32 v108, 16, v128
	v_add_f32_e32 v100, v100, v108
	v_and_b32_e32 v108, 0xffff0000, v128
	v_pk_add_f32 v[102:103], v[102:103], 0 op_sel_hi:[1,0]
	v_add_f32_e32 v101, v101, v108
	v_lshlrev_b32_e32 v108, 16, v129
	v_add_f32_e32 v108, v102, v108
	v_and_b32_e32 v102, 0xffff0000, v129
	v_pk_add_f32 v[96:97], v[96:97], 0 op_sel_hi:[1,0]
	v_add_f32_e32 v109, v103, v102
	v_lshlrev_b32_e32 v102, 16, v130
	v_cvt_pk_bf16_f32 v105, v110, v111
	v_add_f32_e32 v110, v96, v102
	v_and_b32_e32 v96, 0xffff0000, v130
	v_pk_add_f32 v[98:99], v[98:99], 0 op_sel_hi:[1,0]
	v_add_f32_e32 v111, v97, v96
	v_lshlrev_b32_e32 v96, 16, v131
	v_add_f32_e32 v128, v98, v96
	v_and_b32_e32 v96, 0xffff0000, v131
	v_add_f32_e32 v129, v99, v96
	v_mul_f32_e32 v96, v101, v101
	v_mul_f32_e32 v97, v109, v109
	v_fmac_f32_e32 v96, v100, v100
	v_fmac_f32_e32 v97, v108, v108
	v_add_f32_e32 v96, v96, v97
	v_mul_f32_e32 v97, v111, v111
	v_fmac_f32_e32 v97, v110, v110
	v_add_f32_e32 v96, v97, v96
	v_mul_f32_e32 v97, v129, v129
	v_fmac_f32_e32 v97, v128, v128
	v_add_f32_e32 v96, v97, v96
	v_add_f32_e32 v99, v135, v96
	ds_bpermute_b32 v130, v171, v99
	s_waitcnt lgkmcnt(1)
	v_lshlrev_b64 v[174:175], 11, v[162:163]
	v_lshl_add_u64 v[96:97], v[174:175], 1, s[16:17]
	v_lshl_add_u64 v[102:103], v[152:153], 1, v[96:97]
	v_cvt_pk_bf16_f32 v106, v132, v133
	s_waitcnt lgkmcnt(0)
	v_add_f32_e32 v96, v99, v130
	ds_bpermute_b32 v97, v172, v96
	v_cvt_pk_bf16_f32 v107, v134, v107
	global_store_dwordx4 v[102:103], v[104:107], off sc0 sc1
	v_cvt_pk_bf16_f32 v98, v100, v101
	v_cvt_pk_bf16_f32 v99, v108, v109
	v_cvt_pk_bf16_f32 v100, v110, v111
	v_cvt_pk_bf16_f32 v101, v128, v129
	global_store_dwordx4 v[102:103], v[98:101], off offset:256 sc0 sc1
	s_and_saveexec_b64 s[26:27], s[10:11]
	s_cbranch_execz .LBB0_1944
	v_lshlrev_b64 v[98:99], 7, v[162:163]
	v_lshl_add_u64 v[98:99], s[24:25], 0, v[98:99]
	s_waitcnt lgkmcnt(0)
	v_add_f32_e32 v96, v96, v97
	global_store_dword v[98:99], v96, off
.LBB0_1944:
	s_or_b64 exec, exec, s[26:27]
	v_pk_add_f32 v[92:93], v[92:93], 0 op_sel_hi:[1,0]
	v_lshlrev_b32_e32 v98, 16, v124
	v_add_f32_e32 v92, v92, v98
	v_and_b32_e32 v98, 0xffff0000, v124
	v_pk_add_f32 v[94:95], v[94:95], 0 op_sel_hi:[1,0]
	v_add_f32_e32 v93, v93, v98
	v_lshlrev_b32_e32 v98, 16, v125
	v_add_f32_e32 v94, v94, v98
	v_and_b32_e32 v98, 0xffff0000, v125
	v_pk_add_f32 v[88:89], v[88:89], 0 op_sel_hi:[1,0]
	v_add_f32_e32 v95, v95, v98
	v_lshlrev_b32_e32 v98, 16, v126
	v_add_f32_e32 v98, v88, v98
	v_and_b32_e32 v88, 0xffff0000, v126
	v_pk_add_f32 v[90:91], v[90:91], 0 op_sel_hi:[1,0]
	v_add_f32_e32 v99, v89, v88
	v_lshlrev_b32_e32 v88, 16, v127
	v_add_f32_e32 v100, v90, v88
	v_and_b32_e32 v88, 0xffff0000, v127
	v_add_f32_e32 v91, v91, v88
	v_mul_f32_e32 v88, v93, v93
	v_mul_f32_e32 v89, v95, v95
	v_fmac_f32_e32 v88, v92, v92
	v_fmac_f32_e32 v89, v94, v94
	v_add_f32_e32 v88, v88, v89
	v_mul_f32_e32 v89, v99, v99
	v_fmac_f32_e32 v89, v98, v98
	v_add_f32_e32 v88, v89, v88
	v_mul_f32_e32 v89, v91, v91
	v_fmac_f32_e32 v89, v100, v100
	v_add_f32_e32 v101, v89, v88
	v_cvt_pk_bf16_f32 v88, v92, v93
	v_pk_add_f32 v[84:85], v[84:85], 0 op_sel_hi:[1,0]
	v_lshlrev_b32_e32 v92, 16, v120
	v_add_f32_e32 v84, v84, v92
	v_and_b32_e32 v92, 0xffff0000, v120
	v_pk_add_f32 v[86:87], v[86:87], 0 op_sel_hi:[1,0]
	v_add_f32_e32 v85, v85, v92
	v_lshlrev_b32_e32 v92, 16, v121
	v_add_f32_e32 v92, v86, v92
	v_and_b32_e32 v86, 0xffff0000, v121
	v_pk_add_f32 v[80:81], v[80:81], 0 op_sel_hi:[1,0]
	v_add_f32_e32 v93, v87, v86
	v_lshlrev_b32_e32 v86, 16, v122
	v_cvt_pk_bf16_f32 v89, v94, v95
	v_add_f32_e32 v94, v80, v86
	v_and_b32_e32 v80, 0xffff0000, v122
	v_pk_add_f32 v[82:83], v[82:83], 0 op_sel_hi:[1,0]
	v_add_f32_e32 v95, v81, v80
	v_lshlrev_b32_e32 v80, 16, v123
	v_cvt_pk_bf16_f32 v90, v98, v99
	v_add_f32_e32 v98, v82, v80
	v_and_b32_e32 v80, 0xffff0000, v123
	v_add_f32_e32 v99, v83, v80
	v_mul_f32_e32 v80, v85, v85
	v_mul_f32_e32 v81, v93, v93
	v_fmac_f32_e32 v80, v84, v84
	v_fmac_f32_e32 v81, v92, v92
	v_add_f32_e32 v80, v80, v81
	v_mul_f32_e32 v81, v95, v95
	v_fmac_f32_e32 v81, v94, v94
	v_add_f32_e32 v80, v81, v80
	v_mul_f32_e32 v81, v99, v99
	v_fmac_f32_e32 v81, v98, v98
	v_add_f32_e32 v80, v81, v80
	v_add_f32_e32 v83, v101, v80
	v_cvt_pk_bf16_f32 v91, v100, v91
	ds_bpermute_b32 v100, v171, v83
	s_waitcnt lgkmcnt(1)
	v_lshlrev_b64 v[96:97], 11, v[160:161]
	v_lshl_add_u64 v[80:81], v[96:97], 1, s[16:17]
	v_lshl_add_u64 v[86:87], v[152:153], 1, v[80:81]
	global_store_dwordx4 v[86:87], v[88:91], off sc0 sc1
	s_waitcnt lgkmcnt(0)
	v_add_f32_e32 v80, v83, v100
	ds_bpermute_b32 v81, v172, v80
	v_cvt_pk_bf16_f32 v82, v84, v85
	v_cvt_pk_bf16_f32 v83, v92, v93
	v_cvt_pk_bf16_f32 v84, v94, v95
	v_cvt_pk_bf16_f32 v85, v98, v99
	global_store_dwordx4 v[86:87], v[82:85], off offset:256 sc0 sc1
	s_and_saveexec_b64 s[26:27], s[10:11]
	s_cbranch_execz .LBB0_1946
	v_lshlrev_b64 v[82:83], 7, v[160:161]
	v_lshl_add_u64 v[82:83], s[24:25], 0, v[82:83]
	s_waitcnt lgkmcnt(0)
	v_add_f32_e32 v80, v80, v81
	global_store_dword v[82:83], v80, off
; __device__ __forceinline__ unsigned cvt_pk_bf16(float lo, float hi) { unsigned r; asm volatile("v_cvt_pk_bf16_f32 %0, %1, %2" : "=v"(r) : "v"(lo), "v"(hi)); return r; }
;     __device__ __forceinline__ void operator()(const f32x4 (&acc)[2][2][4][2], const Unit& u, int wr, int wc, int fr, int fq) const {
;     ...
;         for (int ai = 0; ai < 2; ++ai) {
;             u32x4 old[4][2];
; #pragma unroll
;             for (int m = 0; m < 4; ++m)
; #pragma unroll
;                 for (int bj = 0; bj < 2; ++bj) old[m][bj] = *(const u32x4*)(HB + (size_t)(row0 + ai * HALF + m * 16) * ldc + col0 + bj * HALF);
; #pragma unroll
;             for (int m = 0; m < 4; ++m) { const int row = row0 + ai * HALF + m * 16; float ss = 0.f;
; #pragma unroll
;                 for (int bj = 0; bj < 2; ++bj) { const u32x4 ow = old[m][bj];
;                     f32x4 v0 = (acc[ai][bj][m][0] + bv[bj][0]) * accs, v1 = (acc[ai][bj][m][1] + bv[bj][1]) * accs;
;                     v0[0] += __uint_as_float(ow.x << 16); v0[1] += __uint_as_float(ow.x & 0xffff0000u); v0[2] += __uint_as_float(ow.y << 16); v0[3] += __uint_as_float(ow.y & 0xffff0000u);
;                     v1[0] += __uint_as_float(ow.z << 16); v1[1] += __uint_as_float(ow.z & 0xffff0000u); v1[2] += __uint_as_float(ow.w << 16); v1[3] += __uint_as_float(ow.w & 0xffff0000u);
;                     ss += (v0[0] * v0[0] + v0[1] * v0[1]) + (v0[2] * v0[2] + v0[3] * v0[3]) + (v1[0] * v1[0] + v1[1] * v1[1]) + (v1[2] * v1[2] + v1[3] * v1[3]);
;                     u32x4 w; w.x = cvt_pk_bf16(v0[0], v0[1]); w.y = cvt_pk_bf16(v0[2], v0[3]); w.z = cvt_pk_bf16(v1[0], v1[1]); w.w = cvt_pk_bf16(v1[2], v1[3]);
;                     *(u32x4*)(HB + (size_t)row * ldc + col0 + bj * HALF) = w; }
;                 ss += __shfl_xor(ss, 16); ss += __shfl_xor(ss, 32);
;                 if (fq == 0) ssp[(size_t)row * 32] = ss; }
.LBB0_1946:
	s_or_b64 exec, exec, s[26:27]
	v_pk_add_f32 v[76:77], v[76:77], 0 op_sel_hi:[1,0]
	v_lshlrev_b32_e32 v82, 16, v116
	v_add_f32_e32 v76, v76, v82
	v_and_b32_e32 v82, 0xffff0000, v116
	v_pk_add_f32 v[78:79], v[78:79], 0 op_sel_hi:[1,0]
	v_add_f32_e32 v77, v77, v82
	v_lshlrev_b32_e32 v82, 16, v117
	v_add_f32_e32 v78, v78, v82
	v_and_b32_e32 v82, 0xffff0000, v117
	v_pk_add_f32 v[72:73], v[72:73], 0 op_sel_hi:[1,0]
	v_add_f32_e32 v79, v79, v82
	v_lshlrev_b32_e32 v82, 16, v118
	v_add_f32_e32 v82, v72, v82
	v_and_b32_e32 v72, 0xffff0000, v118
	v_pk_add_f32 v[74:75], v[74:75], 0 op_sel_hi:[1,0]
	v_add_f32_e32 v83, v73, v72
	v_lshlrev_b32_e32 v72, 16, v119
	v_add_f32_e32 v84, v74, v72
	v_and_b32_e32 v72, 0xffff0000, v119
	v_add_f32_e32 v75, v75, v72
	v_mul_f32_e32 v72, v77, v77
	v_mul_f32_e32 v73, v79, v79
	v_fmac_f32_e32 v72, v76, v76
	v_fmac_f32_e32 v73, v78, v78
	v_add_f32_e32 v72, v72, v73
	v_mul_f32_e32 v73, v83, v83
	v_fmac_f32_e32 v73, v82, v82
	v_add_f32_e32 v72, v73, v72
	v_mul_f32_e32 v73, v75, v75
	v_fmac_f32_e32 v73, v84, v84
	v_add_f32_e32 v85, v73, v72
	v_cvt_pk_bf16_f32 v72, v76, v77
	v_pk_add_f32 v[68:69], v[68:69], 0 op_sel_hi:[1,0]
	v_lshlrev_b32_e32 v76, 16, v112
	v_add_f32_e32 v68, v68, v76
	v_and_b32_e32 v76, 0xffff0000, v112
	v_pk_add_f32 v[70:71], v[70:71], 0 op_sel_hi:[1,0]
	v_add_f32_e32 v69, v69, v76
	v_lshlrev_b32_e32 v76, 16, v113
	v_add_f32_e32 v76, v70, v76
	v_and_b32_e32 v70, 0xffff0000, v113
	v_pk_add_f32 v[64:65], v[64:65], 0 op_sel_hi:[1,0]
	v_add_f32_e32 v77, v71, v70
	v_lshlrev_b32_e32 v70, 16, v114
	v_cvt_pk_bf16_f32 v73, v78, v79
	v_add_f32_e32 v78, v64, v70
	v_and_b32_e32 v64, 0xffff0000, v114
	v_pk_add_f32 v[66:67], v[66:67], 0 op_sel_hi:[1,0]
	v_add_f32_e32 v79, v65, v64
	v_lshlrev_b32_e32 v64, 16, v115
	v_cvt_pk_bf16_f32 v74, v82, v83
	v_add_f32_e32 v82, v66, v64
	v_and_b32_e32 v64, 0xffff0000, v115
	v_add_f32_e32 v83, v67, v64
	v_mul_f32_e32 v64, v69, v69
	v_mul_f32_e32 v65, v77, v77
	v_fmac_f32_e32 v64, v68, v68
	v_fmac_f32_e32 v65, v76, v76
	v_add_f32_e32 v64, v64, v65
	v_mul_f32_e32 v65, v79, v79
	v_fmac_f32_e32 v65, v78, v78
	v_add_f32_e32 v64, v65, v64
	v_mul_f32_e32 v65, v83, v83
	v_fmac_f32_e32 v65, v82, v82
	v_add_f32_e32 v64, v65, v64
	v_add_f32_e32 v67, v85, v64
	v_cvt_pk_bf16_f32 v75, v84, v75
	ds_bpermute_b32 v84, v171, v67
	s_waitcnt lgkmcnt(1)
	v_lshlrev_b64 v[80:81], 11, v[158:159]
	v_lshl_add_u64 v[64:65], v[80:81], 1, s[16:17]
	v_lshl_add_u64 v[70:71], v[152:153], 1, v[64:65]
	global_store_dwordx4 v[70:71], v[72:75], off sc0 sc1
	s_waitcnt lgkmcnt(0)
	v_add_f32_e32 v64, v67, v84
	ds_bpermute_b32 v65, v172, v64
	v_cvt_pk_bf16_f32 v66, v68, v69
	v_cvt_pk_bf16_f32 v67, v76, v77
	v_cvt_pk_bf16_f32 v68, v78, v79
	v_cvt_pk_bf16_f32 v69, v82, v83
	global_store_dwordx4 v[70:71], v[66:69], off offset:256 sc0 sc1
	s_and_saveexec_b64 s[26:27], s[10:11]
	s_cbranch_execz .LBB0_1948
	v_lshlrev_b64 v[66:67], 7, v[158:159]
	v_lshl_add_u64 v[66:67], s[24:25], 0, v[66:67]
	s_waitcnt lgkmcnt(0)
	v_add_f32_e32 v64, v64, v65
	global_store_dword v[66:67], v64, off
.LBB0_1948:
	s_or_b64 exec, exec, s[26:27]
	v_add_u32_e32 v94, 0x80, v154
	v_ashrrev_i32_e32 v95, 31, v94
	v_lshlrev_b64 v[104:105], 12, v[94:95]
	s_waitcnt lgkmcnt(0)
	v_lshl_add_u64 v[64:65], v[156:157], 0, v[104:105]
	global_load_dwordx4 v[96:99], v[64:65], off
	global_load_dwordx4 v[100:103], v[64:65], off offset:256
	v_add_u32_e32 v92, 0x90, v154
	v_add_u32_e32 v90, 0xa0, v154
	v_add_u32_e32 v88, 0xb0, v154
	v_ashrrev_i32_e32 v93, 31, v92
	v_ashrrev_i32_e32 v91, 31, v90
	v_ashrrev_i32_e32 v89, 31, v88
	v_lshlrev_b64 v[64:65], 12, v[92:93]
	v_lshlrev_b64 v[66:67], 12, v[90:91]
	v_lshlrev_b64 v[68:69], 12, v[88:89]
	v_lshl_add_u64 v[64:65], v[156:157], 0, v[64:65]
	v_lshl_add_u64 v[66:67], v[156:157], 0, v[66:67]
	v_lshl_add_u64 v[106:107], v[156:157], 0, v[68:69]
	global_load_dwordx4 v[84:87], v[64:65], off
	global_load_dwordx4 v[80:83], v[64:65], off offset:256
	global_load_dwordx4 v[76:79], v[66:67], off
	global_load_dwordx4 v[72:75], v[66:67], off offset:256
	global_load_dwordx4 v[68:71], v[106:107], off
	s_nop 0
	global_load_dwordx4 v[64:67], v[106:107], off offset:256
	v_pk_add_f32 v[62:63], v[62:63], 0 op_sel_hi:[1,0]
	v_pk_add_f32 v[60:61], v[60:61], 0 op_sel_hi:[1,0]
	v_pk_add_f32 v[58:59], v[58:59], 0 op_sel_hi:[1,0]
	v_pk_add_f32 v[56:57], v[56:57], 0 op_sel_hi:[1,0]
	v_pk_add_f32 v[54:55], v[54:55], 0 op_sel_hi:[1,0]
	v_pk_add_f32 v[52:53], v[52:53], 0 op_sel_hi:[1,0]
	v_pk_add_f32 v[50:51], v[50:51], 0 op_sel_hi:[1,0]
	v_pk_add_f32 v[48:49], v[48:49], 0 op_sel_hi:[1,0]
	s_waitcnt vmcnt(7)
	v_lshlrev_b32_e32 v106, 16, v96
	v_and_b32_e32 v96, 0xffff0000, v96
	v_lshlrev_b32_e32 v107, 16, v97
	v_and_b32_e32 v97, 0xffff0000, v97
	v_lshlrev_b32_e32 v108, 16, v98
	v_and_b32_e32 v98, 0xffff0000, v98
	v_lshlrev_b32_e32 v109, 16, v99
	v_and_b32_e32 v99, 0xffff0000, v99
	s_waitcnt vmcnt(6)
	v_lshlrev_b32_e32 v110, 16, v100
	v_and_b32_e32 v100, 0xffff0000, v100
	v_lshlrev_b32_e32 v111, 16, v101
	v_and_b32_e32 v101, 0xffff0000, v101
	v_lshlrev_b32_e32 v112, 16, v102
	v_and_b32_e32 v102, 0xffff0000, v102
	v_lshlrev_b32_e32 v113, 16, v103
	v_and_b32_e32 v103, 0xffff0000, v103
	v_add_f32_e32 v61, v61, v96
	v_add_f32_e32 v63, v63, v97
	v_add_f32_e32 v57, v57, v98
	v_add_f32_e32 v59, v59, v99
	v_add_f32_e32 v97, v53, v100
	v_add_f32_e32 v99, v55, v101
	v_add_f32_e32 v60, v60, v106
	v_add_f32_e32 v62, v62, v107
	v_add_f32_e32 v56, v56, v108
	v_add_f32_e32 v58, v58, v109
	v_add_f32_e32 v96, v52, v110
	v_add_f32_e32 v98, v54, v111
	v_add_f32_e32 v100, v48, v112
	v_add_f32_e32 v101, v49, v102
	v_add_f32_e32 v102, v50, v113
	v_add_f32_e32 v103, v51, v103
	v_mul_f32_e32 v52, v61, v61
	v_mul_f32_e32 v53, v63, v63
	v_mul_f32_e32 v54, v57, v57
	v_mul_f32_e32 v55, v59, v59
	v_cvt_pk_bf16_f32 v48, v60, v61
	v_cvt_pk_bf16_f32 v49, v62, v63
	v_cvt_pk_bf16_f32 v50, v56, v57
	v_cvt_pk_bf16_f32 v51, v58, v59
	v_mul_f32_e32 v57, v97, v97
	v_mul_f32_e32 v59, v99, v99
	v_mul_f32_e32 v61, v101, v101
	v_fmac_f32_e32 v52, v60, v60
	v_fmac_f32_e32 v53, v62, v62
	v_fmac_f32_e32 v57, v96, v96
	v_fmac_f32_e32 v59, v98, v98
	v_mul_f32_e32 v63, v103, v103
	v_fmac_f32_e32 v54, v56, v56
	v_fmac_f32_e32 v61, v100, v100
	v_add_f32_e32 v52, v52, v53
	v_add_f32_e32 v53, v57, v59
	v_fmac_f32_e32 v55, v58, v58
	v_fmac_f32_e32 v63, v102, v102
	v_add_f32_e32 v52, v54, v52
	v_add_f32_e32 v53, v61, v53
	v_add_f32_e32 v52, v55, v52
	v_add_f32_e32 v53, v63, v53
	v_add_f32_e32 v56, v52, v53
	ds_bpermute_b32 v57, v171, v56
	v_lshl_add_u64 v[52:53], s[16:17], 0, v[104:105]
	v_lshl_add_u64 v[54:55], v[152:153], 1, v[52:53]
	global_store_dwordx4 v[54:55], v[48:51], off sc0 sc1
	s_waitcnt lgkmcnt(0)
	s_nop 0
	v_add_f32_e32 v48, v56, v57
	ds_bpermute_b32 v49, v172, v48
	v_cvt_pk_bf16_f32 v50, v96, v97
	v_cvt_pk_bf16_f32 v51, v98, v99
	v_cvt_pk_bf16_f32 v52, v100, v101
	v_cvt_pk_bf16_f32 v53, v102, v103
	global_store_dwordx4 v[54:55], v[50:53], off offset:256 sc0 sc1
	s_and_saveexec_b64 s[26:27], s[10:11]
	s_cbranch_execz .LBB0_1950
; __device__ __forceinline__ unsigned cvt_pk_bf16(float lo, float hi) { unsigned r; asm volatile("v_cvt_pk_bf16_f32 %0, %1, %2" : "=v"(r) : "v"(lo), "v"(hi)); return r; }
;     __device__ __forceinline__ void operator()(const f32x4 (&acc)[2][2][4][2], const Unit& u, int wr, int wc, int fr, int fq) const {
;     ...
;                 for (int bj = 0; bj < 2; ++bj) old[m][bj] = *(const u32x4*)(HB + (size_t)(row0 + ai * HALF + m * 16) * ldc + col0 + bj * HALF);
; #pragma unroll
;             for (int m = 0; m < 4; ++m) { const int row = row0 + ai * HALF + m * 16; float ss = 0.f;
; #pragma unroll
;                 for (int bj = 0; bj < 2; ++bj) { const u32x4 ow = old[m][bj];
;                     f32x4 v0 = (acc[ai][bj][m][0] + bv[bj][0]) * accs, v1 = (acc[ai][bj][m][1] + bv[bj][1]) * accs;
;                     v0[0] += __uint_as_float(ow.x << 16); v0[1] += __uint_as_float(ow.x & 0xffff0000u); v0[2] += __uint_as_float(ow.y << 16); v0[3] += __uint_as_float(ow.y & 0xffff0000u);
;                     v1[0] += __uint_as_float(ow.z << 16); v1[1] += __uint_as_float(ow.z & 0xffff0000u); v1[2] += __uint_as_float(ow.w << 16); v1[3] += __uint_as_float(ow.w & 0xffff0000u);
;                     ss += (v0[0] * v0[0] + v0[1] * v0[1]) + (v0[2] * v0[2] + v0[3] * v0[3]) + (v1[0] * v1[0] + v1[1] * v1[1]) + (v1[2] * v1[2] + v1[3] * v1[3]);
;                     u32x4 w; w.x = cvt_pk_bf16(v0[0], v0[1]); w.y = cvt_pk_bf16(v0[2], v0[3]); w.z = cvt_pk_bf16(v1[0], v1[1]); w.w = cvt_pk_bf16(v1[2], v1[3]);
;                     *(u32x4*)(HB + (size_t)row * ldc + col0 + bj * HALF) = w; }
;                 ss += __shfl_xor(ss, 16); ss += __shfl_xor(ss, 32);
;                 if (fq == 0) ssp[(size_t)row * 32] = ss; }
	v_lshlrev_b64 v[50:51], 7, v[94:95]
	v_lshl_add_u64 v[50:51], s[24:25], 0, v[50:51]
	s_waitcnt lgkmcnt(0)
	v_add_f32_e32 v48, v48, v49
	global_store_dword v[50:51], v48, off
.LBB0_1950:
	s_or_b64 exec, exec, s[26:27]
	v_pk_add_f32 v[44:45], v[44:45], 0 op_sel_hi:[1,0]
	s_waitcnt vmcnt(7)
	v_lshlrev_b32_e32 v50, 16, v84
	v_add_f32_e32 v44, v44, v50
	v_and_b32_e32 v50, 0xffff0000, v84
	v_pk_add_f32 v[46:47], v[46:47], 0 op_sel_hi:[1,0]
	v_add_f32_e32 v45, v45, v50
	v_lshlrev_b32_e32 v50, 16, v85
	v_add_f32_e32 v46, v46, v50
	v_and_b32_e32 v50, 0xffff0000, v85
	v_pk_add_f32 v[40:41], v[40:41], 0 op_sel_hi:[1,0]
	v_add_f32_e32 v47, v47, v50
	v_lshlrev_b32_e32 v50, 16, v86
	v_add_f32_e32 v50, v40, v50
	v_and_b32_e32 v40, 0xffff0000, v86
	v_pk_add_f32 v[42:43], v[42:43], 0 op_sel_hi:[1,0]
	v_add_f32_e32 v51, v41, v40
	v_lshlrev_b32_e32 v40, 16, v87
	v_add_f32_e32 v52, v42, v40
	v_and_b32_e32 v40, 0xffff0000, v87
	v_add_f32_e32 v43, v43, v40
	v_mul_f32_e32 v40, v45, v45
	v_mul_f32_e32 v41, v47, v47
	v_fmac_f32_e32 v40, v44, v44
	v_fmac_f32_e32 v41, v46, v46
	v_add_f32_e32 v40, v40, v41
	v_mul_f32_e32 v41, v51, v51
	v_fmac_f32_e32 v41, v50, v50
	v_add_f32_e32 v40, v41, v40
	v_mul_f32_e32 v41, v43, v43
	v_fmac_f32_e32 v41, v52, v52
	v_add_f32_e32 v53, v41, v40
	v_cvt_pk_bf16_f32 v40, v44, v45
	v_pk_add_f32 v[36:37], v[36:37], 0 op_sel_hi:[1,0]
	s_waitcnt vmcnt(6)
	v_lshlrev_b32_e32 v44, 16, v80
	v_add_f32_e32 v36, v36, v44
	v_and_b32_e32 v44, 0xffff0000, v80
	v_pk_add_f32 v[38:39], v[38:39], 0 op_sel_hi:[1,0]
	v_add_f32_e32 v37, v37, v44
	v_lshlrev_b32_e32 v44, 16, v81
	v_add_f32_e32 v44, v38, v44
	v_and_b32_e32 v38, 0xffff0000, v81
	v_pk_add_f32 v[32:33], v[32:33], 0 op_sel_hi:[1,0]
	v_add_f32_e32 v45, v39, v38
	v_lshlrev_b32_e32 v38, 16, v82
	v_cvt_pk_bf16_f32 v41, v46, v47
	v_add_f32_e32 v46, v32, v38
	v_and_b32_e32 v32, 0xffff0000, v82
	v_pk_add_f32 v[34:35], v[34:35], 0 op_sel_hi:[1,0]
	v_add_f32_e32 v47, v33, v32
	v_lshlrev_b32_e32 v32, 16, v83
	v_cvt_pk_bf16_f32 v42, v50, v51
	v_add_f32_e32 v50, v34, v32
	v_and_b32_e32 v32, 0xffff0000, v83
	v_add_f32_e32 v51, v35, v32
	v_mul_f32_e32 v32, v37, v37
	v_mul_f32_e32 v33, v45, v45
	v_fmac_f32_e32 v32, v36, v36
	v_fmac_f32_e32 v33, v44, v44
	v_add_f32_e32 v32, v32, v33
	v_mul_f32_e32 v33, v47, v47
	v_fmac_f32_e32 v33, v46, v46
	v_add_f32_e32 v32, v33, v32
	v_mul_f32_e32 v33, v51, v51
	v_fmac_f32_e32 v33, v50, v50
	v_add_f32_e32 v32, v33, v32
	v_add_f32_e32 v35, v53, v32
	v_cvt_pk_bf16_f32 v43, v52, v43
	ds_bpermute_b32 v52, v171, v35
	s_waitcnt lgkmcnt(1)
	v_lshlrev_b64 v[48:49], 11, v[92:93]
	v_lshl_add_u64 v[32:33], v[48:49], 1, s[16:17]
	v_lshl_add_u64 v[38:39], v[152:153], 1, v[32:33]
	global_store_dwordx4 v[38:39], v[40:43], off sc0 sc1
	s_waitcnt lgkmcnt(0)
	v_add_f32_e32 v32, v35, v52
	ds_bpermute_b32 v33, v172, v32
	v_cvt_pk_bf16_f32 v34, v36, v37
	v_cvt_pk_bf16_f32 v35, v44, v45
	v_cvt_pk_bf16_f32 v36, v46, v47
	v_cvt_pk_bf16_f32 v37, v50, v51
	global_store_dwordx4 v[38:39], v[34:37], off offset:256 sc0 sc1
	s_and_saveexec_b64 s[26:27], s[10:11]
	s_cbranch_execz .LBB0_1952
	v_lshlrev_b64 v[34:35], 7, v[92:93]
	v_lshl_add_u64 v[34:35], s[24:25], 0, v[34:35]
	s_waitcnt lgkmcnt(0)
	v_add_f32_e32 v32, v32, v33
	global_store_dword v[34:35], v32, off
; __device__ __forceinline__ unsigned cvt_pk_bf16(float lo, float hi) { unsigned r; asm volatile("v_cvt_pk_bf16_f32 %0, %1, %2" : "=v"(r) : "v"(lo), "v"(hi)); return r; }
;     __device__ __forceinline__ void operator()(const f32x4 (&acc)[2][2][4][2], const Unit& u, int wr, int wc, int fr, int fq) const {
;     ...
;                 for (int bj = 0; bj < 2; ++bj) old[m][bj] = *(const u32x4*)(HB + (size_t)(row0 + ai * HALF + m * 16) * ldc + col0 + bj * HALF);
; #pragma unroll
;             for (int m = 0; m < 4; ++m) { const int row = row0 + ai * HALF + m * 16; float ss = 0.f;
; #pragma unroll
;                 for (int bj = 0; bj < 2; ++bj) { const u32x4 ow = old[m][bj];
;                     f32x4 v0 = (acc[ai][bj][m][0] + bv[bj][0]) * accs, v1 = (acc[ai][bj][m][1] + bv[bj][1]) * accs;
;                     v0[0] += __uint_as_float(ow.x << 16); v0[1] += __uint_as_float(ow.x & 0xffff0000u); v0[2] += __uint_as_float(ow.y << 16); v0[3] += __uint_as_float(ow.y & 0xffff0000u);
;                     v1[0] += __uint_as_float(ow.z << 16); v1[1] += __uint_as_float(ow.z & 0xffff0000u); v1[2] += __uint_as_float(ow.w << 16); v1[3] += __uint_as_float(ow.w & 0xffff0000u);
;                     ss += (v0[0] * v0[0] + v0[1] * v0[1]) + (v0[2] * v0[2] + v0[3] * v0[3]) + (v1[0] * v1[0] + v1[1] * v1[1]) + (v1[2] * v1[2] + v1[3] * v1[3]);
;                     u32x4 w; w.x = cvt_pk_bf16(v0[0], v0[1]); w.y = cvt_pk_bf16(v0[2], v0[3]); w.z = cvt_pk_bf16(v1[0], v1[1]); w.w = cvt_pk_bf16(v1[2], v1[3]);
;                     *(u32x4*)(HB + (size_t)row * ldc + col0 + bj * HALF) = w; }
;                 ss += __shfl_xor(ss, 16); ss += __shfl_xor(ss, 32);
;                 if (fq == 0) ssp[(size_t)row * 32] = ss; }
.LBB0_1952:
	s_or_b64 exec, exec, s[26:27]
	v_pk_add_f32 v[28:29], v[28:29], 0 op_sel_hi:[1,0]
	s_waitcnt vmcnt(7)
	v_lshlrev_b32_e32 v34, 16, v76
	v_add_f32_e32 v28, v28, v34
	v_and_b32_e32 v34, 0xffff0000, v76
	v_pk_add_f32 v[30:31], v[30:31], 0 op_sel_hi:[1,0]
	v_add_f32_e32 v29, v29, v34
	v_lshlrev_b32_e32 v34, 16, v77
	v_add_f32_e32 v30, v30, v34
	v_and_b32_e32 v34, 0xffff0000, v77
	v_pk_add_f32 v[24:25], v[24:25], 0 op_sel_hi:[1,0]
	v_add_f32_e32 v31, v31, v34
	v_lshlrev_b32_e32 v34, 16, v78
	v_add_f32_e32 v34, v24, v34
	v_and_b32_e32 v24, 0xffff0000, v78
	v_pk_add_f32 v[26:27], v[26:27], 0 op_sel_hi:[1,0]
	v_add_f32_e32 v35, v25, v24
	v_lshlrev_b32_e32 v24, 16, v79
	v_add_f32_e32 v36, v26, v24
	v_and_b32_e32 v24, 0xffff0000, v79
	v_add_f32_e32 v27, v27, v24
	v_mul_f32_e32 v24, v29, v29
	v_mul_f32_e32 v25, v31, v31
	v_fmac_f32_e32 v24, v28, v28
	v_fmac_f32_e32 v25, v30, v30
	v_add_f32_e32 v24, v24, v25
	v_mul_f32_e32 v25, v35, v35
	v_fmac_f32_e32 v25, v34, v34
	v_add_f32_e32 v24, v25, v24
	v_mul_f32_e32 v25, v27, v27
	v_fmac_f32_e32 v25, v36, v36
	v_add_f32_e32 v37, v25, v24
	v_cvt_pk_bf16_f32 v24, v28, v29
	v_pk_add_f32 v[20:21], v[20:21], 0 op_sel_hi:[1,0]
	s_waitcnt vmcnt(6)
	v_lshlrev_b32_e32 v28, 16, v72
	v_add_f32_e32 v20, v20, v28
	v_and_b32_e32 v28, 0xffff0000, v72
	v_pk_add_f32 v[22:23], v[22:23], 0 op_sel_hi:[1,0]
	v_add_f32_e32 v21, v21, v28
	v_lshlrev_b32_e32 v28, 16, v73
	v_add_f32_e32 v28, v22, v28
	v_and_b32_e32 v22, 0xffff0000, v73
	v_pk_add_f32 v[16:17], v[16:17], 0 op_sel_hi:[1,0]
	v_add_f32_e32 v29, v23, v22
	v_lshlrev_b32_e32 v22, 16, v74
	v_cvt_pk_bf16_f32 v25, v30, v31
	v_add_f32_e32 v30, v16, v22
	v_and_b32_e32 v16, 0xffff0000, v74
	v_pk_add_f32 v[18:19], v[18:19], 0 op_sel_hi:[1,0]
	v_add_f32_e32 v31, v17, v16
	v_lshlrev_b32_e32 v16, 16, v75
	v_cvt_pk_bf16_f32 v26, v34, v35
	v_add_f32_e32 v34, v18, v16
	v_and_b32_e32 v16, 0xffff0000, v75
	v_add_f32_e32 v35, v19, v16
	v_mul_f32_e32 v16, v21, v21
	v_mul_f32_e32 v17, v29, v29
	v_fmac_f32_e32 v16, v20, v20
	v_fmac_f32_e32 v17, v28, v28
	v_add_f32_e32 v16, v16, v17
	v_mul_f32_e32 v17, v31, v31
	v_fmac_f32_e32 v17, v30, v30
	v_add_f32_e32 v16, v17, v16
	v_mul_f32_e32 v17, v35, v35
	v_fmac_f32_e32 v17, v34, v34
	v_add_f32_e32 v16, v17, v16
	v_add_f32_e32 v19, v37, v16
	v_cvt_pk_bf16_f32 v27, v36, v27
	ds_bpermute_b32 v36, v171, v19
	s_waitcnt lgkmcnt(1)
	v_lshlrev_b64 v[32:33], 11, v[90:91]
	v_lshl_add_u64 v[16:17], v[32:33], 1, s[16:17]
	v_lshl_add_u64 v[22:23], v[152:153], 1, v[16:17]
	global_store_dwordx4 v[22:23], v[24:27], off sc0 sc1
	s_waitcnt lgkmcnt(0)
	v_add_f32_e32 v16, v19, v36
	ds_bpermute_b32 v17, v172, v16
	v_cvt_pk_bf16_f32 v18, v20, v21
	v_cvt_pk_bf16_f32 v19, v28, v29
	v_cvt_pk_bf16_f32 v20, v30, v31
	v_cvt_pk_bf16_f32 v21, v34, v35
	global_store_dwordx4 v[22:23], v[18:21], off offset:256 sc0 sc1
	s_and_saveexec_b64 s[26:27], s[10:11]
	s_cbranch_execz .LBB0_1954
	v_lshlrev_b64 v[18:19], 7, v[90:91]
	v_lshl_add_u64 v[18:19], s[24:25], 0, v[18:19]
	s_waitcnt lgkmcnt(0)
	v_add_f32_e32 v16, v16, v17
	global_store_dword v[18:19], v16, off
.LBB0_1954:
	s_or_b64 exec, exec, s[26:27]
	v_pk_add_f32 v[12:13], v[12:13], 0 op_sel_hi:[1,0]
	s_waitcnt vmcnt(7)
	v_lshlrev_b32_e32 v18, 16, v68
	v_add_f32_e32 v12, v12, v18
	v_and_b32_e32 v18, 0xffff0000, v68
	v_pk_add_f32 v[14:15], v[14:15], 0 op_sel_hi:[1,0]
	v_add_f32_e32 v13, v13, v18
	v_lshlrev_b32_e32 v18, 16, v69
	v_add_f32_e32 v14, v14, v18
	v_and_b32_e32 v18, 0xffff0000, v69
	v_pk_add_f32 v[8:9], v[8:9], 0 op_sel_hi:[1,0]
	v_add_f32_e32 v15, v15, v18
	v_lshlrev_b32_e32 v18, 16, v70
	v_add_f32_e32 v18, v8, v18
	v_and_b32_e32 v8, 0xffff0000, v70
	v_pk_add_f32 v[10:11], v[10:11], 0 op_sel_hi:[1,0]
	v_add_f32_e32 v19, v9, v8
	v_lshlrev_b32_e32 v8, 16, v71
	v_add_f32_e32 v20, v10, v8
	v_and_b32_e32 v8, 0xffff0000, v71
	v_add_f32_e32 v11, v11, v8
	v_mul_f32_e32 v8, v13, v13
	v_mul_f32_e32 v9, v15, v15
	v_fmac_f32_e32 v8, v12, v12
	v_fmac_f32_e32 v9, v14, v14
	v_add_f32_e32 v8, v8, v9
	v_mul_f32_e32 v9, v19, v19
	v_fmac_f32_e32 v9, v18, v18
	v_add_f32_e32 v8, v9, v8
	v_mul_f32_e32 v9, v11, v11
	v_fmac_f32_e32 v9, v20, v20
	v_add_f32_e32 v21, v9, v8
	v_cvt_pk_bf16_f32 v8, v12, v13
	v_pk_add_f32 v[4:5], v[4:5], 0 op_sel_hi:[1,0]
	s_waitcnt vmcnt(6)
	v_lshlrev_b32_e32 v12, 16, v64
	v_add_f32_e32 v4, v4, v12
	v_and_b32_e32 v12, 0xffff0000, v64
	v_pk_add_f32 v[6:7], v[6:7], 0 op_sel_hi:[1,0]
	v_add_f32_e32 v5, v5, v12
	v_lshlrev_b32_e32 v12, 16, v65
	v_add_f32_e32 v12, v6, v12
	v_and_b32_e32 v6, 0xffff0000, v65
	v_pk_add_f32 v[0:1], v[0:1], 0 op_sel_hi:[1,0]
	v_add_f32_e32 v13, v7, v6
	v_lshlrev_b32_e32 v6, 16, v66
	v_cvt_pk_bf16_f32 v9, v14, v15
	v_add_f32_e32 v14, v0, v6
	v_and_b32_e32 v0, 0xffff0000, v66
	v_pk_add_f32 v[2:3], v[2:3], 0 op_sel_hi:[1,0]
	v_add_f32_e32 v15, v1, v0
	v_lshlrev_b32_e32 v0, 16, v67
	v_cvt_pk_bf16_f32 v10, v18, v19
	v_add_f32_e32 v18, v2, v0
	v_and_b32_e32 v0, 0xffff0000, v67
	v_add_f32_e32 v19, v3, v0
	v_mul_f32_e32 v0, v5, v5
	v_mul_f32_e32 v1, v13, v13
	v_fmac_f32_e32 v0, v4, v4
	v_fmac_f32_e32 v1, v12, v12
	v_add_f32_e32 v0, v0, v1
	v_mul_f32_e32 v1, v15, v15
	v_fmac_f32_e32 v1, v14, v14
	v_add_f32_e32 v0, v1, v0
	v_mul_f32_e32 v1, v19, v19
	v_fmac_f32_e32 v1, v18, v18
	v_add_f32_e32 v0, v1, v0
	v_add_f32_e32 v3, v21, v0
	v_cvt_pk_bf16_f32 v11, v20, v11
	ds_bpermute_b32 v20, v171, v3
	s_waitcnt lgkmcnt(1)
	v_lshlrev_b64 v[16:17], 11, v[88:89]
	v_lshl_add_u64 v[0:1], v[16:17], 1, s[16:17]
	v_lshl_add_u64 v[6:7], v[152:153], 1, v[0:1]
	global_store_dwordx4 v[6:7], v[8:11], off sc0 sc1
	s_waitcnt lgkmcnt(0)
	v_add_f32_e32 v0, v3, v20
	ds_bpermute_b32 v1, v172, v0
	v_cvt_pk_bf16_f32 v2, v4, v5
	v_cvt_pk_bf16_f32 v3, v12, v13
	v_cvt_pk_bf16_f32 v4, v14, v15
	v_cvt_pk_bf16_f32 v5, v18, v19
	global_store_dwordx4 v[6:7], v[2:5], off offset:256 sc0 sc1
	s_and_saveexec_b64 s[26:27], s[10:11]
	s_cbranch_execz .LBB0_1956
	v_lshlrev_b64 v[2:3], 7, v[88:89]
	v_lshl_add_u64 v[2:3], s[24:25], 0, v[2:3]
	s_waitcnt lgkmcnt(0)
	v_add_f32_e32 v0, v0, v1
	global_store_dword v[2:3], v0, off

; __device__ __forceinline__ unsigned cvt_pk_bf16(float lo, float hi) { unsigned r; asm volatile("v_cvt_pk_bf16_f32 %0, %1, %2" : "=v"(r) : "v"(lo), "v"(hi)); return r; }
; __device__ __forceinline__ float row_ss(const float* part, int row, int fq, int nf4) {
;     const f32x4* p = (const f32x4*)(part + (size_t)row * 32);
;     float s = 0.f;
; #pragma unroll
;     for (int j = 0; j < 2; ++j) { const int idx = fq + 4 * j; if (idx < nf4) { const f32x4 v = p[idx]; s += (v[0] + v[1]) + (v[2] + v[3]); } }
;     s += __shfl_xor(s, 16); s += __shfl_xor(s, 32);
;     return s;
;     __device__ __forceinline__ void operator()(const f32x4 (&acc)[2][2][4][2], const Unit& u, int wr, int wc, int fr, int fq) const {
;         const int row0 = u.pm * BM + wr * 64 + fr; int colt = u.pn * BM; bf16_t* base = O;
;         float sc = 1.f; if (split_cols) { const int t = colt / split_cols; base += (size_t)t * split_stride; colt -= t * split_cols; if (t == 0) sc = scale0; } else sc = scale0;
;         const int col0 = colt + wc * 32 + 8 * fq, bcol0 = u.pn * BM + wc * 32 + 8 * fq;
;         f32x4 bv[2][2];
; #pragma unroll
;         for (int bj = 0; bj < 2; ++bj)
; #pragma unroll
;             for (int n = 0; n < 2; ++n) bv[bj][n] = bias ? *(const f32x4*)(bias + bcol0 + bj * HALF + 4 * n) : (f32x4){0.f, 0.f, 0.f, 0.f};
; #pragma unroll
;         for (int ai = 0; ai < 2; ++ai)
; #pragma unroll
;             for (int m = 0; m < 4; ++m) { const int row = row0 + ai * HALF + m * 16; bf16_t* rowp = base + (size_t)row * ldc + col0;
;                 const float rs = rss ? __builtin_amdgcn_rsqf(row_ss(rss, row, fq, nf4) * rinv + 1e-6f) : 1.f;
; #pragma unroll
;                 for (int bj = 0; bj < 2; ++bj) { f32x4 v0 = acc[ai][bj][m][0] * rs + bv[bj][0], v1 = acc[ai][bj][m][1] * rs + bv[bj][1];
;                     v0 = v0 * sc; v1 = v1 * sc; u32x4 w; w.x = cvt_pk_bf16(v0[0], v0[1]); w.y = cvt_pk_bf16(v0[2], v0[3]); w.z = cvt_pk_bf16(v1[0], v1[1]); w.w = cvt_pk_bf16(v1[2], v1[3]);
;                     *(u32x4*)(rowp + bj * HALF) = w; } }
.LBB0_2024:
	v_lshl_add_u32 v146, s24, 8, v149
	v_ashrrev_i32_e32 v147, 31, v146
	v_lshlrev_b64 v[150:151], 7, v[146:147]
	v_lshl_add_u64 v[150:151], v[136:137], 0, v[150:151]
	global_load_dwordx4 v[162:165], v[150:151], off
	global_load_dwordx4 v[166:169], v[150:151], off offset:64
	v_and_b32_e32 v150, 64, v157
	v_xor_b32_e32 v148, 16, v157
	v_add_u32_e32 v150, 64, v150
	v_xor_b32_e32 v151, 32, v157
	v_or_b32_e32 v170, 16, v146
	v_cmp_lt_i32_e32 vcc, v148, v150
	v_lshlrev_b64 v[172:173], 12, v[146:147]
	v_ashrrev_i32_e32 v171, 31, v170
	v_cndmask_b32_e32 v147, v157, v148, vcc
	v_cmp_lt_i32_e32 vcc, v151, v150
	v_lshlrev_b32_e32 v160, 2, v147
	s_ashr_i32 s17, s6, 31
	v_cndmask_b32_e32 v148, v157, v151, vcc
	v_lshlrev_b64 v[150:151], 7, v[170:171]
	v_lshl_add_u64 v[174:175], v[136:137], 0, v[150:151]
	v_lshlrev_b32_e32 v147, 2, v148
	s_lshr_b32 s17, s17, 29
	s_add_i32 s17, s6, s17
	s_ashr_i32 s17, s17, 3
	s_lshl_b32 s7, s6, 8
	s_mul_i32 s24, s17, 0x3000000
	s_mul_hi_i32 s19, s17, 0x3000000
	s_add_u32 s26, s43, s24
	s_addc_u32 s27, s44, s19
	s_lshl_b32 s17, s17, 11
	s_add_i32 s6, s6, 7
	s_sub_i32 s7, s7, s17
	s_cmp_lt_u32 s6, 15
	s_cselect_b64 vcc, -1, 0
	s_waitcnt vmcnt(0)
	v_mov_b32_e32 v150, v162
	v_mov_b32_e32 v151, v166
	v_mov_b32_e32 v166, v163
	v_mov_b32_e32 v162, v164
	v_mov_b32_e32 v163, v168
	v_mov_b32_e32 v168, v165
	v_pk_add_f32 v[150:151], v[150:151], v[166:167]
	v_pk_add_f32 v[162:163], v[162:163], v[168:169]
	s_nop 0
	v_pk_add_f32 v[150:151], v[150:151], v[162:163]
	s_nop 0
	v_add_f32_e32 v148, 0, v150
	v_add_f32_e32 v148, v148, v151
	ds_bpermute_b32 v150, v160, v148
	s_waitcnt lgkmcnt(0)
	v_add_f32_e32 v151, v148, v150
	ds_bpermute_b32 v161, v147, v151
	v_or_b32_e32 v150, s7, v153
	v_cndmask_b32_e32 v148, 1.0, v159, vcc
	s_andn2_b64 vcc, exec, s[10:11]
	s_mov_b64 s[10:11], -1
	s_waitcnt lgkmcnt(0)
	v_add_f32_e32 v151, v151, v161
	v_fmamk_f32 v151, v151, 0x3a000000, v158
	v_rsq_f32_e32 v162, v151
	v_ashrrev_i32_e32 v151, 31, v150
	v_lshl_add_u64 v[150:151], v[150:151], 1, s[26:27]
	v_lshl_add_u64 v[164:165], v[150:151], 0, v[172:173]
	v_pk_fma_f32 v[124:125], v[124:125], v[162:163], 0 op_sel_hi:[1,0,0]
	v_pk_fma_f32 v[126:127], v[126:127], v[162:163], 0 op_sel_hi:[1,0,0]
	v_pk_fma_f32 v[120:121], v[120:121], v[162:163], 0 op_sel_hi:[1,0,0]
	v_pk_fma_f32 v[122:123], v[122:123], v[162:163], 0 op_sel_hi:[1,0,0]
	v_pk_fma_f32 v[112:113], v[112:113], v[162:163], 0 op_sel_hi:[1,0,0]
	v_pk_fma_f32 v[114:115], v[114:115], v[162:163], 0 op_sel_hi:[1,0,0]
	v_pk_fma_f32 v[116:117], v[116:117], v[162:163], 0 op_sel_hi:[1,0,0]
	v_pk_fma_f32 v[118:119], v[118:119], v[162:163], 0 op_sel_hi:[1,0,0]
	v_pk_mul_f32 v[126:127], v[148:149], v[126:127] op_sel_hi:[0,1]
	v_pk_mul_f32 v[124:125], v[148:149], v[124:125] op_sel_hi:[0,1]
	v_pk_mul_f32 v[122:123], v[148:149], v[122:123] op_sel_hi:[0,1]
	v_pk_mul_f32 v[120:121], v[148:149], v[120:121] op_sel_hi:[0,1]
	v_pk_mul_f32 v[162:163], v[148:149], v[114:115] op_sel_hi:[0,1]
	v_pk_mul_f32 v[166:167], v[148:149], v[112:113] op_sel_hi:[0,1]
	v_cvt_pk_bf16_f32 v112, v124, v125
	v_cvt_pk_bf16_f32 v113, v126, v127
	v_cvt_pk_bf16_f32 v114, v120, v121
	v_cvt_pk_bf16_f32 v115, v122, v123
	v_pk_mul_f32 v[118:119], v[148:149], v[118:119] op_sel_hi:[0,1]
	v_pk_mul_f32 v[116:117], v[148:149], v[116:117] op_sel_hi:[0,1]
	global_store_dwordx4 v[164:165], v[112:115], off sc0 sc1
	s_nop 1
	v_cvt_pk_bf16_f32 v112, v116, v117
	v_cvt_pk_bf16_f32 v113, v118, v119
	v_cvt_pk_bf16_f32 v114, v166, v167
	v_cvt_pk_bf16_f32 v115, v162, v163
	global_store_dwordx4 v[164:165], v[112:115], off offset:256 sc0 sc1
	global_load_dwordx4 v[112:115], v[174:175], off
	s_nop 0
	global_load_dwordx4 v[116:119], v[174:175], off offset:64
	s_waitcnt vmcnt(1)
	v_mov_b32_e32 v120, v112
	s_waitcnt vmcnt(0)
	v_mov_b32_e32 v121, v116
	v_mov_b32_e32 v116, v113
	v_mov_b32_e32 v112, v114
	v_mov_b32_e32 v113, v118
	v_mov_b32_e32 v118, v115
	v_pk_add_f32 v[114:115], v[120:121], v[116:117]
	v_pk_add_f32 v[112:113], v[112:113], v[118:119]
	s_nop 0
	v_pk_add_f32 v[112:113], v[114:115], v[112:113]
	v_lshlrev_b64 v[114:115], 12, v[170:171]
	v_add_f32_e32 v112, 0, v112
	v_add_f32_e32 v112, v112, v113
	ds_bpermute_b32 v113, v160, v112
	v_lshl_add_u64 v[114:115], v[150:151], 0, v[114:115]
	s_waitcnt lgkmcnt(0)
	v_add_f32_e32 v116, v112, v113
	ds_bpermute_b32 v117, v147, v116
	v_or_b32_e32 v112, 32, v146
	v_ashrrev_i32_e32 v113, 31, v112
	v_lshlrev_b64 v[118:119], 7, v[112:113]
	v_lshl_add_u64 v[118:119], v[136:137], 0, v[118:119]
	s_waitcnt lgkmcnt(0)
	v_add_f32_e32 v116, v116, v117
	v_fmamk_f32 v116, v116, 0x3a000000, v158
	v_rsq_f32_e32 v116, v116
	s_nop 0
	v_pk_fma_f32 v[108:109], v[108:109], v[116:117], 0 op_sel_hi:[1,0,0]
	v_pk_fma_f32 v[110:111], v[110:111], v[116:117], 0 op_sel_hi:[1,0,0]
	v_pk_fma_f32 v[104:105], v[104:105], v[116:117], 0 op_sel_hi:[1,0,0]
	v_pk_fma_f32 v[106:107], v[106:107], v[116:117], 0 op_sel_hi:[1,0,0]
	v_pk_fma_f32 v[96:97], v[96:97], v[116:117], 0 op_sel_hi:[1,0,0]
	v_pk_fma_f32 v[98:99], v[98:99], v[116:117], 0 op_sel_hi:[1,0,0]
	v_pk_fma_f32 v[100:101], v[100:101], v[116:117], 0 op_sel_hi:[1,0,0]
	v_pk_fma_f32 v[102:103], v[102:103], v[116:117], 0 op_sel_hi:[1,0,0]
	v_pk_mul_f32 v[110:111], v[148:149], v[110:111] op_sel_hi:[0,1]
	v_pk_mul_f32 v[108:109], v[148:149], v[108:109] op_sel_hi:[0,1]
	v_pk_mul_f32 v[106:107], v[148:149], v[106:107] op_sel_hi:[0,1]
	v_pk_mul_f32 v[104:105], v[148:149], v[104:105] op_sel_hi:[0,1]
	v_pk_mul_f32 v[116:117], v[148:149], v[98:99] op_sel_hi:[0,1]
	v_pk_mul_f32 v[120:121], v[148:149], v[96:97] op_sel_hi:[0,1]
	v_cvt_pk_bf16_f32 v96, v108, v109
	v_cvt_pk_bf16_f32 v97, v110, v111
	v_cvt_pk_bf16_f32 v98, v104, v105
	v_cvt_pk_bf16_f32 v99, v106, v107
	v_pk_mul_f32 v[102:103], v[148:149], v[102:103] op_sel_hi:[0,1]
	v_pk_mul_f32 v[100:101], v[148:149], v[100:101] op_sel_hi:[0,1]
	global_store_dwordx4 v[114:115], v[96:99], off sc0 sc1
	s_nop 1
	v_cvt_pk_bf16_f32 v96, v100, v101
	v_cvt_pk_bf16_f32 v97, v102, v103
	v_cvt_pk_bf16_f32 v98, v120, v121
	v_cvt_pk_bf16_f32 v99, v116, v117
	global_store_dwordx4 v[114:115], v[96:99], off offset:256 sc0 sc1
	global_load_dwordx4 v[96:99], v[118:119], off
	s_nop 0
	global_load_dwordx4 v[100:103], v[118:119], off offset:64
	s_waitcnt vmcnt(1)
; __device__ __forceinline__ unsigned cvt_pk_bf16(float lo, float hi) { unsigned r; asm volatile("v_cvt_pk_bf16_f32 %0, %1, %2" : "=v"(r) : "v"(lo), "v"(hi)); return r; }
; __device__ __forceinline__ float row_ss(const float* part, int row, int fq, int nf4) {
;     const f32x4* p = (const f32x4*)(part + (size_t)row * 32);
;     float s = 0.f;
; #pragma unroll
;     for (int j = 0; j < 2; ++j) { const int idx = fq + 4 * j; if (idx < nf4) { const f32x4 v = p[idx]; s += (v[0] + v[1]) + (v[2] + v[3]); } }
;     s += __shfl_xor(s, 16); s += __shfl_xor(s, 32);
;     return s;
;     __device__ __forceinline__ void operator()(const f32x4 (&acc)[2][2][4][2], const Unit& u, int wr, int wc, int fr, int fq) const {
;     ...
;             for (int m = 0; m < 4; ++m) { const int row = row0 + ai * HALF + m * 16; bf16_t* rowp = base + (size_t)row * ldc + col0;
;                 const float rs = rss ? __builtin_amdgcn_rsqf(row_ss(rss, row, fq, nf4) * rinv + 1e-6f) : 1.f;
; #pragma unroll
;                 for (int bj = 0; bj < 2; ++bj) { f32x4 v0 = acc[ai][bj][m][0] * rs + bv[bj][0], v1 = acc[ai][bj][m][1] * rs + bv[bj][1];
;                     v0 = v0 * sc; v1 = v1 * sc; u32x4 w; w.x = cvt_pk_bf16(v0[0], v0[1]); w.y = cvt_pk_bf16(v0[2], v0[3]); w.z = cvt_pk_bf16(v1[0], v1[1]); w.w = cvt_pk_bf16(v1[2], v1[3]);
;                     *(u32x4*)(rowp + bj * HALF) = w; } }
	v_mov_b32_e32 v104, v96
	s_waitcnt vmcnt(0)
	v_mov_b32_e32 v105, v100
	v_mov_b32_e32 v100, v97
	v_mov_b32_e32 v96, v98
	v_mov_b32_e32 v97, v102
	v_mov_b32_e32 v102, v99
	v_pk_add_f32 v[98:99], v[104:105], v[100:101]
	v_pk_add_f32 v[96:97], v[96:97], v[102:103]
	s_nop 0
	v_pk_add_f32 v[96:97], v[98:99], v[96:97]
	v_lshlrev_b64 v[98:99], 12, v[112:113]
	v_add_f32_e32 v96, 0, v96
	v_add_f32_e32 v96, v96, v97
	ds_bpermute_b32 v97, v160, v96
	v_lshl_add_u64 v[98:99], v[150:151], 0, v[98:99]
	s_waitcnt lgkmcnt(0)
	v_add_f32_e32 v100, v96, v97
	ds_bpermute_b32 v101, v147, v100
	v_or_b32_e32 v96, 48, v146
	v_ashrrev_i32_e32 v97, 31, v96
	v_lshlrev_b64 v[102:103], 7, v[96:97]
	v_lshl_add_u64 v[102:103], v[136:137], 0, v[102:103]
	s_waitcnt lgkmcnt(0)
	v_add_f32_e32 v100, v100, v101
	v_fmamk_f32 v100, v100, 0x3a000000, v158
	v_rsq_f32_e32 v100, v100
	s_nop 0
	v_pk_fma_f32 v[92:93], v[92:93], v[100:101], 0 op_sel_hi:[1,0,0]
	v_pk_fma_f32 v[94:95], v[94:95], v[100:101], 0 op_sel_hi:[1,0,0]
	v_pk_fma_f32 v[88:89], v[88:89], v[100:101], 0 op_sel_hi:[1,0,0]
	v_pk_fma_f32 v[90:91], v[90:91], v[100:101], 0 op_sel_hi:[1,0,0]
	v_pk_fma_f32 v[80:81], v[80:81], v[100:101], 0 op_sel_hi:[1,0,0]
	v_pk_fma_f32 v[82:83], v[82:83], v[100:101], 0 op_sel_hi:[1,0,0]
	v_pk_fma_f32 v[84:85], v[84:85], v[100:101], 0 op_sel_hi:[1,0,0]
	v_pk_fma_f32 v[86:87], v[86:87], v[100:101], 0 op_sel_hi:[1,0,0]
	v_pk_mul_f32 v[94:95], v[148:149], v[94:95] op_sel_hi:[0,1]
	v_pk_mul_f32 v[92:93], v[148:149], v[92:93] op_sel_hi:[0,1]
	v_pk_mul_f32 v[90:91], v[148:149], v[90:91] op_sel_hi:[0,1]
	v_pk_mul_f32 v[88:89], v[148:149], v[88:89] op_sel_hi:[0,1]
	v_pk_mul_f32 v[100:101], v[148:149], v[82:83] op_sel_hi:[0,1]
	v_pk_mul_f32 v[104:105], v[148:149], v[80:81] op_sel_hi:[0,1]
	v_cvt_pk_bf16_f32 v80, v92, v93
	v_cvt_pk_bf16_f32 v81, v94, v95
	v_cvt_pk_bf16_f32 v82, v88, v89
	v_cvt_pk_bf16_f32 v83, v90, v91
	v_pk_mul_f32 v[86:87], v[148:149], v[86:87] op_sel_hi:[0,1]
	v_pk_mul_f32 v[84:85], v[148:149], v[84:85] op_sel_hi:[0,1]
	global_store_dwordx4 v[98:99], v[80:83], off sc0 sc1
	s_nop 1
	v_cvt_pk_bf16_f32 v80, v84, v85
	v_cvt_pk_bf16_f32 v81, v86, v87
	v_cvt_pk_bf16_f32 v82, v104, v105
	v_cvt_pk_bf16_f32 v83, v100, v101
	global_store_dwordx4 v[98:99], v[80:83], off offset:256 sc0 sc1
	global_load_dwordx4 v[80:83], v[102:103], off
	s_nop 0
	global_load_dwordx4 v[84:87], v[102:103], off offset:64
	s_waitcnt vmcnt(1)
	v_mov_b32_e32 v88, v80
	s_waitcnt vmcnt(0)
	v_mov_b32_e32 v89, v84
	v_mov_b32_e32 v84, v81
	v_mov_b32_e32 v80, v82
	v_mov_b32_e32 v81, v86
	v_mov_b32_e32 v86, v83
	v_pk_add_f32 v[82:83], v[88:89], v[84:85]
	v_pk_add_f32 v[80:81], v[80:81], v[86:87]
	s_nop 0
	v_pk_add_f32 v[80:81], v[82:83], v[80:81]
	v_lshlrev_b64 v[82:83], 12, v[96:97]
	v_add_f32_e32 v80, 0, v80
	v_add_f32_e32 v80, v80, v81
	ds_bpermute_b32 v81, v160, v80
	v_lshl_add_u64 v[82:83], v[150:151], 0, v[82:83]
	s_waitcnt lgkmcnt(0)
	v_add_f32_e32 v84, v80, v81
	ds_bpermute_b32 v85, v147, v84
	v_add_u32_e32 v80, 0x80, v146
	v_ashrrev_i32_e32 v81, 31, v80
	v_lshlrev_b64 v[86:87], 7, v[80:81]
	v_lshl_add_u64 v[86:87], v[136:137], 0, v[86:87]
	s_waitcnt lgkmcnt(0)
	v_add_f32_e32 v84, v84, v85
	v_fmamk_f32 v84, v84, 0x3a000000, v158
	v_rsq_f32_e32 v84, v84
	s_nop 0
	v_pk_fma_f32 v[76:77], v[76:77], v[84:85], 0 op_sel_hi:[1,0,0]
	v_pk_fma_f32 v[78:79], v[78:79], v[84:85], 0 op_sel_hi:[1,0,0]
	v_pk_fma_f32 v[72:73], v[72:73], v[84:85], 0 op_sel_hi:[1,0,0]
	v_pk_fma_f32 v[74:75], v[74:75], v[84:85], 0 op_sel_hi:[1,0,0]
	v_pk_fma_f32 v[64:65], v[64:65], v[84:85], 0 op_sel_hi:[1,0,0]
	v_pk_fma_f32 v[66:67], v[66:67], v[84:85], 0 op_sel_hi:[1,0,0]
	v_pk_fma_f32 v[68:69], v[68:69], v[84:85], 0 op_sel_hi:[1,0,0]
	v_pk_fma_f32 v[70:71], v[70:71], v[84:85], 0 op_sel_hi:[1,0,0]
	v_pk_mul_f32 v[78:79], v[148:149], v[78:79] op_sel_hi:[0,1]
	v_pk_mul_f32 v[76:77], v[148:149], v[76:77] op_sel_hi:[0,1]
	v_pk_mul_f32 v[74:75], v[148:149], v[74:75] op_sel_hi:[0,1]
	v_pk_mul_f32 v[72:73], v[148:149], v[72:73] op_sel_hi:[0,1]
	v_pk_mul_f32 v[84:85], v[148:149], v[66:67] op_sel_hi:[0,1]
	v_pk_mul_f32 v[88:89], v[148:149], v[64:65] op_sel_hi:[0,1]
	v_cvt_pk_bf16_f32 v64, v76, v77
	v_cvt_pk_bf16_f32 v65, v78, v79
	v_cvt_pk_bf16_f32 v66, v72, v73
	v_cvt_pk_bf16_f32 v67, v74, v75
	v_pk_mul_f32 v[70:71], v[148:149], v[70:71] op_sel_hi:[0,1]
	v_pk_mul_f32 v[68:69], v[148:149], v[68:69] op_sel_hi:[0,1]
	global_store_dwordx4 v[82:83], v[64:67], off sc0 sc1
	s_nop 1
	v_cvt_pk_bf16_f32 v64, v68, v69
	v_cvt_pk_bf16_f32 v65, v70, v71
	v_cvt_pk_bf16_f32 v66, v88, v89
	v_cvt_pk_bf16_f32 v67, v84, v85
	global_store_dwordx4 v[82:83], v[64:67], off offset:256 sc0 sc1
	global_load_dwordx4 v[64:67], v[86:87], off
	s_nop 0
	global_load_dwordx4 v[68:71], v[86:87], off offset:64
	s_waitcnt vmcnt(1)
	v_mov_b32_e32 v72, v64
	s_waitcnt vmcnt(0)
	v_mov_b32_e32 v73, v68
	v_mov_b32_e32 v68, v65
	v_mov_b32_e32 v64, v66
	v_mov_b32_e32 v65, v70
	v_mov_b32_e32 v70, v67
	v_pk_add_f32 v[66:67], v[72:73], v[68:69]
	v_pk_add_f32 v[64:65], v[64:65], v[70:71]
	s_nop 0
	v_pk_add_f32 v[64:65], v[66:67], v[64:65]
	v_lshlrev_b64 v[66:67], 12, v[80:81]
	v_add_f32_e32 v64, 0, v64
	v_add_f32_e32 v64, v64, v65
	ds_bpermute_b32 v65, v160, v64
	v_lshl_add_u64 v[66:67], v[150:151], 0, v[66:67]
	s_waitcnt lgkmcnt(0)
	v_add_f32_e32 v68, v64, v65
	ds_bpermute_b32 v69, v147, v68
	v_add_u32_e32 v64, 0x90, v146
	v_ashrrev_i32_e32 v65, 31, v64
	v_lshlrev_b64 v[70:71], 7, v[64:65]
	v_lshl_add_u64 v[70:71], v[136:137], 0, v[70:71]
	s_waitcnt lgkmcnt(0)
; __device__ __forceinline__ unsigned cvt_pk_bf16(float lo, float hi) { unsigned r; asm volatile("v_cvt_pk_bf16_f32 %0, %1, %2" : "=v"(r) : "v"(lo), "v"(hi)); return r; }
; __device__ __forceinline__ float row_ss(const float* part, int row, int fq, int nf4) {
;     const f32x4* p = (const f32x4*)(part + (size_t)row * 32);
;     float s = 0.f;
; #pragma unroll
;     for (int j = 0; j < 2; ++j) { const int idx = fq + 4 * j; if (idx < nf4) { const f32x4 v = p[idx]; s += (v[0] + v[1]) + (v[2] + v[3]); } }
;     s += __shfl_xor(s, 16); s += __shfl_xor(s, 32);
;     return s;
;     __device__ __forceinline__ void operator()(const f32x4 (&acc)[2][2][4][2], const Unit& u, int wr, int wc, int fr, int fq) const {
;     ...
;             for (int m = 0; m < 4; ++m) { const int row = row0 + ai * HALF + m * 16; bf16_t* rowp = base + (size_t)row * ldc + col0;
;                 const float rs = rss ? __builtin_amdgcn_rsqf(row_ss(rss, row, fq, nf4) * rinv + 1e-6f) : 1.f;
; #pragma unroll
;                 for (int bj = 0; bj < 2; ++bj) { f32x4 v0 = acc[ai][bj][m][0] * rs + bv[bj][0], v1 = acc[ai][bj][m][1] * rs + bv[bj][1];
;                     v0 = v0 * sc; v1 = v1 * sc; u32x4 w; w.x = cvt_pk_bf16(v0[0], v0[1]); w.y = cvt_pk_bf16(v0[2], v0[3]); w.z = cvt_pk_bf16(v1[0], v1[1]); w.w = cvt_pk_bf16(v1[2], v1[3]);
;                     *(u32x4*)(rowp + bj * HALF) = w; } }
	v_add_f32_e32 v68, v68, v69
	v_fmamk_f32 v68, v68, 0x3a000000, v158
	v_rsq_f32_e32 v68, v68
	s_nop 0
	v_pk_fma_f32 v[60:61], v[60:61], v[68:69], 0 op_sel_hi:[1,0,0]
	v_pk_fma_f32 v[62:63], v[62:63], v[68:69], 0 op_sel_hi:[1,0,0]
	v_pk_fma_f32 v[56:57], v[56:57], v[68:69], 0 op_sel_hi:[1,0,0]
	v_pk_fma_f32 v[58:59], v[58:59], v[68:69], 0 op_sel_hi:[1,0,0]
	v_pk_fma_f32 v[48:49], v[48:49], v[68:69], 0 op_sel_hi:[1,0,0]
	v_pk_fma_f32 v[50:51], v[50:51], v[68:69], 0 op_sel_hi:[1,0,0]
	v_pk_fma_f32 v[52:53], v[52:53], v[68:69], 0 op_sel_hi:[1,0,0]
	v_pk_fma_f32 v[54:55], v[54:55], v[68:69], 0 op_sel_hi:[1,0,0]
	v_pk_mul_f32 v[62:63], v[148:149], v[62:63] op_sel_hi:[0,1]
	v_pk_mul_f32 v[60:61], v[148:149], v[60:61] op_sel_hi:[0,1]
	v_pk_mul_f32 v[58:59], v[148:149], v[58:59] op_sel_hi:[0,1]
	v_pk_mul_f32 v[56:57], v[148:149], v[56:57] op_sel_hi:[0,1]
	v_pk_mul_f32 v[68:69], v[148:149], v[50:51] op_sel_hi:[0,1]
	v_pk_mul_f32 v[72:73], v[148:149], v[48:49] op_sel_hi:[0,1]
	v_cvt_pk_bf16_f32 v48, v60, v61
	v_cvt_pk_bf16_f32 v49, v62, v63
	v_cvt_pk_bf16_f32 v50, v56, v57
	v_cvt_pk_bf16_f32 v51, v58, v59
	v_pk_mul_f32 v[54:55], v[148:149], v[54:55] op_sel_hi:[0,1]
	v_pk_mul_f32 v[52:53], v[148:149], v[52:53] op_sel_hi:[0,1]
	global_store_dwordx4 v[66:67], v[48:51], off sc0 sc1
	s_nop 1
	v_cvt_pk_bf16_f32 v48, v52, v53
	v_cvt_pk_bf16_f32 v49, v54, v55
	v_cvt_pk_bf16_f32 v50, v72, v73
	v_cvt_pk_bf16_f32 v51, v68, v69
	global_store_dwordx4 v[66:67], v[48:51], off offset:256 sc0 sc1
	global_load_dwordx4 v[48:51], v[70:71], off
	s_nop 0
	global_load_dwordx4 v[52:55], v[70:71], off offset:64
	s_waitcnt vmcnt(1)
	v_mov_b32_e32 v56, v48
	s_waitcnt vmcnt(0)
	v_mov_b32_e32 v57, v52
	v_mov_b32_e32 v52, v49
	v_mov_b32_e32 v48, v50
	v_mov_b32_e32 v49, v54
	v_mov_b32_e32 v54, v51
	v_pk_add_f32 v[50:51], v[56:57], v[52:53]
	v_pk_add_f32 v[48:49], v[48:49], v[54:55]
	s_nop 0
	v_pk_add_f32 v[48:49], v[50:51], v[48:49]
	v_lshlrev_b64 v[50:51], 12, v[64:65]
	v_add_f32_e32 v48, 0, v48
	v_add_f32_e32 v48, v48, v49
	ds_bpermute_b32 v49, v160, v48
	v_lshl_add_u64 v[50:51], v[150:151], 0, v[50:51]
	s_waitcnt lgkmcnt(0)
	v_add_f32_e32 v52, v48, v49
	ds_bpermute_b32 v53, v147, v52
	v_add_u32_e32 v48, 0xa0, v146
	v_ashrrev_i32_e32 v49, 31, v48
	v_lshlrev_b64 v[54:55], 7, v[48:49]
	v_lshl_add_u64 v[54:55], v[136:137], 0, v[54:55]
	s_waitcnt lgkmcnt(0)
	v_add_f32_e32 v52, v52, v53
	v_fmamk_f32 v52, v52, 0x3a000000, v158
	v_rsq_f32_e32 v52, v52
	s_nop 0
	v_pk_fma_f32 v[44:45], v[44:45], v[52:53], 0 op_sel_hi:[1,0,0]
	v_pk_fma_f32 v[46:47], v[46:47], v[52:53], 0 op_sel_hi:[1,0,0]
	v_pk_fma_f32 v[40:41], v[40:41], v[52:53], 0 op_sel_hi:[1,0,0]
	v_pk_fma_f32 v[42:43], v[42:43], v[52:53], 0 op_sel_hi:[1,0,0]
	v_pk_fma_f32 v[32:33], v[32:33], v[52:53], 0 op_sel_hi:[1,0,0]
	v_pk_fma_f32 v[34:35], v[34:35], v[52:53], 0 op_sel_hi:[1,0,0]
	v_pk_fma_f32 v[36:37], v[36:37], v[52:53], 0 op_sel_hi:[1,0,0]
	v_pk_fma_f32 v[38:39], v[38:39], v[52:53], 0 op_sel_hi:[1,0,0]
	v_pk_mul_f32 v[46:47], v[148:149], v[46:47] op_sel_hi:[0,1]
	v_pk_mul_f32 v[44:45], v[148:149], v[44:45] op_sel_hi:[0,1]
	v_pk_mul_f32 v[42:43], v[148:149], v[42:43] op_sel_hi:[0,1]
	v_pk_mul_f32 v[40:41], v[148:149], v[40:41] op_sel_hi:[0,1]
	v_pk_mul_f32 v[52:53], v[148:149], v[34:35] op_sel_hi:[0,1]
	v_pk_mul_f32 v[56:57], v[148:149], v[32:33] op_sel_hi:[0,1]
	v_cvt_pk_bf16_f32 v32, v44, v45
	v_cvt_pk_bf16_f32 v33, v46, v47
	v_cvt_pk_bf16_f32 v34, v40, v41
	v_cvt_pk_bf16_f32 v35, v42, v43
	v_pk_mul_f32 v[38:39], v[148:149], v[38:39] op_sel_hi:[0,1]
	v_pk_mul_f32 v[36:37], v[148:149], v[36:37] op_sel_hi:[0,1]
	global_store_dwordx4 v[50:51], v[32:35], off sc0 sc1
	s_nop 1
	v_cvt_pk_bf16_f32 v32, v36, v37
	v_cvt_pk_bf16_f32 v33, v38, v39
	v_cvt_pk_bf16_f32 v34, v56, v57
	v_cvt_pk_bf16_f32 v35, v52, v53
	global_store_dwordx4 v[50:51], v[32:35], off offset:256 sc0 sc1
	global_load_dwordx4 v[32:35], v[54:55], off
	s_nop 0
	global_load_dwordx4 v[36:39], v[54:55], off offset:64
	s_waitcnt vmcnt(1)
	v_mov_b32_e32 v40, v32
	s_waitcnt vmcnt(0)
; __device__ __forceinline__ unsigned cvt_pk_bf16(float lo, float hi) { unsigned r; asm volatile("v_cvt_pk_bf16_f32 %0, %1, %2" : "=v"(r) : "v"(lo), "v"(hi)); return r; }
; #define PG8_BAR __builtin_amdgcn_s_barrier()
;     __device__ __forceinline__ void operator()(const f32x4 (&acc)[2][2][4][2], const Unit& u, int wr, int wc, int fr, int fq) const {
;     ...
;             for (int m = 0; m < 4; ++m) { const int row = row0 + ai * HALF + m * 16; bf16_t* rowp = base + (size_t)row * ldc + col0;
;                 const float rs = rss ? __builtin_amdgcn_rsqf(row_ss(rss, row, fq, nf4) * rinv + 1e-6f) : 1.f;
; #pragma unroll
;                 for (int bj = 0; bj < 2; ++bj) { f32x4 v0 = acc[ai][bj][m][0] * rs + bv[bj][0], v1 = acc[ai][bj][m][1] * rs + bv[bj][1];
;                     v0 = v0 * sc; v1 = v1 * sc; u32x4 w; w.x = cvt_pk_bf16(v0[0], v0[1]); w.y = cvt_pk_bf16(v0[2], v0[3]); w.z = cvt_pk_bf16(v1[0], v1[1]); w.w = cvt_pk_bf16(v1[2], v1[3]);
;                     *(u32x4*)(rowp + bj * HALF) = w; } }
; template <class Epi, class Sched, bool ALIGN_EPI = false, bool SP2 = false>
; __device__ __forceinline__ void gemm_phase(PG8_LAS unsigned char* lds, const Gemm g, const Sched& S, const Epi& E) {
;     ...
;         if (!has_next) break;
; #pragma unroll
;         for (int a = 0; a < 2; ++a)
; #pragma unroll
;             for (int b = 0; b < 2; ++b)
; #pragma unroll
;                 for (int m = 0; m < 4; ++m)
; #pragma unroll
;                     for (int n = 0; n < 2; ++n) acc[a][b][m][n] = (f32x4){0.f, 0.f, 0.f, 0.f};
;         cur = nxt; cA = nA; cB = nB; ++ui;
;         if constexpr (ALIGN_EPI) { if (wr == 1) PG8_BAR; }
	v_mov_b32_e32 v41, v36
	v_mov_b32_e32 v36, v33
	v_mov_b32_e32 v32, v34
	v_mov_b32_e32 v33, v38
	v_mov_b32_e32 v38, v35
	v_pk_add_f32 v[34:35], v[40:41], v[36:37]
	v_pk_add_f32 v[32:33], v[32:33], v[38:39]
	s_nop 0
	v_pk_add_f32 v[32:33], v[34:35], v[32:33]
	v_lshlrev_b64 v[34:35], 12, v[48:49]
	v_add_f32_e32 v32, 0, v32
	v_add_f32_e32 v32, v32, v33
	ds_bpermute_b32 v33, v160, v32
	v_lshl_add_u64 v[34:35], v[150:151], 0, v[34:35]
	s_waitcnt lgkmcnt(0)
	v_add_f32_e32 v36, v32, v33
	ds_bpermute_b32 v37, v147, v36
	v_add_u32_e32 v32, 0xb0, v146
	v_ashrrev_i32_e32 v33, 31, v32
	v_lshlrev_b64 v[38:39], 7, v[32:33]
	v_lshl_add_u64 v[38:39], v[136:137], 0, v[38:39]
	s_waitcnt lgkmcnt(0)
	v_add_f32_e32 v36, v36, v37
	v_fmamk_f32 v36, v36, 0x3a000000, v158
	v_rsq_f32_e32 v36, v36
	s_nop 0
	v_pk_fma_f32 v[28:29], v[28:29], v[36:37], 0 op_sel_hi:[1,0,0]
	v_pk_fma_f32 v[30:31], v[30:31], v[36:37], 0 op_sel_hi:[1,0,0]
	v_pk_fma_f32 v[24:25], v[24:25], v[36:37], 0 op_sel_hi:[1,0,0]
	v_pk_fma_f32 v[26:27], v[26:27], v[36:37], 0 op_sel_hi:[1,0,0]
	v_pk_fma_f32 v[16:17], v[16:17], v[36:37], 0 op_sel_hi:[1,0,0]
	v_pk_fma_f32 v[18:19], v[18:19], v[36:37], 0 op_sel_hi:[1,0,0]
	v_pk_fma_f32 v[20:21], v[20:21], v[36:37], 0 op_sel_hi:[1,0,0]
	v_pk_fma_f32 v[22:23], v[22:23], v[36:37], 0 op_sel_hi:[1,0,0]
	v_pk_mul_f32 v[30:31], v[148:149], v[30:31] op_sel_hi:[0,1]
	v_pk_mul_f32 v[28:29], v[148:149], v[28:29] op_sel_hi:[0,1]
	v_pk_mul_f32 v[26:27], v[148:149], v[26:27] op_sel_hi:[0,1]
	v_pk_mul_f32 v[24:25], v[148:149], v[24:25] op_sel_hi:[0,1]
	v_pk_mul_f32 v[36:37], v[148:149], v[18:19] op_sel_hi:[0,1]
	v_pk_mul_f32 v[40:41], v[148:149], v[16:17] op_sel_hi:[0,1]
	v_cvt_pk_bf16_f32 v16, v28, v29
	v_cvt_pk_bf16_f32 v17, v30, v31
	v_cvt_pk_bf16_f32 v18, v24, v25
	v_cvt_pk_bf16_f32 v19, v26, v27
	v_pk_mul_f32 v[22:23], v[148:149], v[22:23] op_sel_hi:[0,1]
	v_pk_mul_f32 v[20:21], v[148:149], v[20:21] op_sel_hi:[0,1]
	global_store_dwordx4 v[34:35], v[16:19], off sc0 sc1
	s_nop 1
	v_cvt_pk_bf16_f32 v16, v20, v21
	v_cvt_pk_bf16_f32 v17, v22, v23
	v_cvt_pk_bf16_f32 v18, v40, v41
	v_cvt_pk_bf16_f32 v19, v36, v37
	global_store_dwordx4 v[34:35], v[16:19], off offset:256 sc0 sc1
	global_load_dwordx4 v[16:19], v[38:39], off
	s_nop 0
	global_load_dwordx4 v[20:23], v[38:39], off offset:64
	s_waitcnt vmcnt(1)
	v_mov_b32_e32 v24, v16
	s_waitcnt vmcnt(0)
	v_mov_b32_e32 v25, v20
	v_mov_b32_e32 v20, v17
	v_mov_b32_e32 v16, v18
	v_mov_b32_e32 v17, v22
	v_mov_b32_e32 v22, v19
	v_pk_add_f32 v[18:19], v[24:25], v[20:21]
	v_pk_add_f32 v[16:17], v[16:17], v[22:23]
	s_nop 0
	v_pk_add_f32 v[16:17], v[18:19], v[16:17]
	v_lshlrev_b64 v[18:19], 12, v[32:33]
	v_add_f32_e32 v16, 0, v16
	v_add_f32_e32 v16, v16, v17
	ds_bpermute_b32 v17, v160, v16
	v_lshl_add_u64 v[18:19], v[150:151], 0, v[18:19]
	s_waitcnt lgkmcnt(0)
	v_add_f32_e32 v16, v16, v17
	ds_bpermute_b32 v17, v147, v16
	s_waitcnt lgkmcnt(0)
	v_add_f32_e32 v16, v16, v17
	v_fmamk_f32 v16, v16, 0x3a000000, v158
	v_rsq_f32_e32 v16, v16
	s_nop 0
	v_pk_fma_f32 v[12:13], v[12:13], v[16:17], 0 op_sel_hi:[1,0,0]
	v_pk_fma_f32 v[14:15], v[14:15], v[16:17], 0 op_sel_hi:[1,0,0]
	v_pk_fma_f32 v[8:9], v[8:9], v[16:17], 0 op_sel_hi:[1,0,0]
	v_pk_fma_f32 v[10:11], v[10:11], v[16:17], 0 op_sel_hi:[1,0,0]
	v_pk_fma_f32 v[0:1], v[0:1], v[16:17], 0 op_sel_hi:[1,0,0]
	v_pk_fma_f32 v[2:3], v[2:3], v[16:17], 0 op_sel_hi:[1,0,0]
	v_pk_fma_f32 v[4:5], v[4:5], v[16:17], 0 op_sel_hi:[1,0,0]
	v_pk_fma_f32 v[6:7], v[6:7], v[16:17], 0 op_sel_hi:[1,0,0]
	v_pk_mul_f32 v[14:15], v[148:149], v[14:15] op_sel_hi:[0,1]
	v_pk_mul_f32 v[12:13], v[148:149], v[12:13] op_sel_hi:[0,1]
	v_pk_mul_f32 v[10:11], v[148:149], v[10:11] op_sel_hi:[0,1]
	v_pk_mul_f32 v[8:9], v[148:149], v[8:9] op_sel_hi:[0,1]
	v_pk_mul_f32 v[16:17], v[148:149], v[2:3] op_sel_hi:[0,1]
	v_pk_mul_f32 v[20:21], v[148:149], v[0:1] op_sel_hi:[0,1]
	v_cvt_pk_bf16_f32 v0, v12, v13
	v_cvt_pk_bf16_f32 v1, v14, v15
	v_cvt_pk_bf16_f32 v2, v8, v9
	v_cvt_pk_bf16_f32 v3, v10, v11
	v_pk_mul_f32 v[6:7], v[148:149], v[6:7] op_sel_hi:[0,1]
	v_pk_mul_f32 v[4:5], v[148:149], v[4:5] op_sel_hi:[0,1]
	global_store_dwordx4 v[18:19], v[0:3], off sc0 sc1
	s_nop 1
	v_cvt_pk_bf16_f32 v0, v4, v5
	v_cvt_pk_bf16_f32 v1, v6, v7
	v_cvt_pk_bf16_f32 v2, v20, v21
	v_cvt_pk_bf16_f32 v3, v16, v17
	global_store_dwordx4 v[18:19], v[0:3], off offset:256 sc0 sc1
	s_cbranch_vccnz .LBB0_2017
	s_andn2_b64 vcc, exec, s[0:1]
	s_cbranch_vccnz .LBB0_2016
	s_barrier
	s_branch .LBB0_2016

; __device__ __forceinline__ unsigned cvt_pk_bf16(float lo, float hi) { unsigned r; asm volatile("v_cvt_pk_bf16_f32 %0, %1, %2" : "=v"(r) : "v"(lo), "v"(hi)); return r; }
;     __device__ __forceinline__ void operator()(const f32x4 (&acc)[2][2][4][2], const Unit& u, int wr, int wc, int fr, int fq) const {
;         const int row0 = u.pm * BM + wr * 64 + fr, col0 = u.pn * BM + wc * 32 + 8 * fq;
;         f32x4 bv[2][2];
; #pragma unroll
;         for (int bj = 0; bj < 2; ++bj)
; #pragma unroll
;             for (int n = 0; n < 2; ++n) bv[bj][n] = bias ? *(const f32x4*)(bias + col0 + bj * HALF + 4 * n) : (f32x4){0.f, 0.f, 0.f, 0.f};
;         float* ssp = ssout + (size_t)(u.pn * 4 + wc);
; #pragma unroll
;         for (int ai = 0; ai < 2; ++ai) {
;             u32x4 old[4][2];
; #pragma unroll
;             for (int m = 0; m < 4; ++m)
; #pragma unroll
;                 for (int bj = 0; bj < 2; ++bj) old[m][bj] = *(const u32x4*)(HB + (size_t)(row0 + ai * HALF + m * 16) * ldc + col0 + bj * HALF);
; #pragma unroll
;             for (int m = 0; m < 4; ++m) { const int row = row0 + ai * HALF + m * 16; float ss = 0.f;
; #pragma unroll
;                 for (int bj = 0; bj < 2; ++bj) { const u32x4 ow = old[m][bj];
;                     f32x4 v0 = (acc[ai][bj][m][0] + bv[bj][0]) * accs, v1 = (acc[ai][bj][m][1] + bv[bj][1]) * accs;
;                     v0[0] += __uint_as_float(ow.x << 16); v0[1] += __uint_as_float(ow.x & 0xffff0000u); v0[2] += __uint_as_float(ow.y << 16); v0[3] += __uint_as_float(ow.y & 0xffff0000u);
;                     v1[0] += __uint_as_float(ow.z << 16); v1[1] += __uint_as_float(ow.z & 0xffff0000u); v1[2] += __uint_as_float(ow.w << 16); v1[3] += __uint_as_float(ow.w & 0xffff0000u);
;                     ss += (v0[0] * v0[0] + v0[1] * v0[1]) + (v0[2] * v0[2] + v0[3] * v0[3]) + (v1[0] * v1[0] + v1[1] * v1[1]) + (v1[2] * v1[2] + v1[3] * v1[3]);
;                     u32x4 w; w.x = cvt_pk_bf16(v0[0], v0[1]); w.y = cvt_pk_bf16(v0[2], v0[3]); w.z = cvt_pk_bf16(v1[0], v1[1]); w.w = cvt_pk_bf16(v1[2], v1[3]);
;                     *(u32x4*)(HB + (size_t)row * ldc + col0 + bj * HALF) = w; }
;                 ss += __shfl_xor(ss, 16); ss += __shfl_xor(ss, 32);
;                 if (fq == 0) ssp[(size_t)row * 32] = ss; }
.LBB0_2198:
	v_lshl_or_b32 v152, s22, 8, v166
	v_ashrrev_i32_e32 v153, 31, v152
	v_lshl_add_u32 v156, s24, 8, v164
	v_lshlrev_b64 v[178:179], 1, v[152:153]
	v_ashrrev_i32_e32 v157, 31, v156
	v_lshl_add_u64 v[154:155], s[10:11], 0, v[178:179]
	v_lshlrev_b64 v[180:181], 12, v[156:157]
	v_lshl_add_u64 v[128:129], v[154:155], 0, v[180:181]
	global_load_dwordx4 v[170:173], v[128:129], off
	global_load_dwordx4 v[174:177], v[128:129], off offset:256
	v_or_b32_e32 v162, 16, v156
	v_or_b32_e32 v160, 32, v156
	v_or_b32_e32 v158, 48, v156
	v_ashrrev_i32_e32 v163, 31, v162
	v_ashrrev_i32_e32 v161, 31, v160
	v_pk_add_f32 v[194:195], v[114:115], 0 op_sel_hi:[1,0]
	v_pk_add_f32 v[196:197], v[112:113], 0 op_sel_hi:[1,0]
	v_ashrrev_i32_e32 v159, 31, v158
	v_lshlrev_b64 v[112:113], 12, v[162:163]
	v_lshlrev_b64 v[114:115], 12, v[160:161]
	v_pk_add_f32 v[192:193], v[116:117], 0 op_sel_hi:[1,0]
	v_lshlrev_b64 v[116:117], 12, v[158:159]
	v_lshl_add_u64 v[112:113], v[154:155], 0, v[112:113]
	v_lshl_add_u64 v[114:115], v[154:155], 0, v[114:115]
	v_pk_add_f32 v[182:183], v[126:127], 0 op_sel_hi:[1,0]
	v_pk_add_f32 v[184:185], v[124:125], 0 op_sel_hi:[1,0]
	v_pk_add_f32 v[186:187], v[122:123], 0 op_sel_hi:[1,0]
	v_pk_add_f32 v[188:189], v[120:121], 0 op_sel_hi:[1,0]
	v_pk_add_f32 v[190:191], v[118:119], 0 op_sel_hi:[1,0]
	v_lshl_add_u64 v[198:199], v[154:155], 0, v[116:117]
	global_load_dwordx4 v[132:135], v[112:113], off
	global_load_dwordx4 v[128:131], v[112:113], off offset:256
	global_load_dwordx4 v[124:127], v[114:115], off
	global_load_dwordx4 v[120:123], v[114:115], off offset:256
	global_load_dwordx4 v[116:119], v[198:199], off
	s_nop 0
	global_load_dwordx4 v[112:115], v[198:199], off offset:256
	s_lshl_b32 s2, s22, 2
	s_or_b32 s6, s2, s38
	s_ashr_i32 s7, s6, 31
	s_lshl_b64 s[6:7], s[6:7], 2
	s_add_u32 s22, s3, s6
	s_addc_u32 s23, s33, s7
	s_waitcnt vmcnt(0)
	v_lshlrev_b32_e32 v198, 16, v170
	v_and_b32_e32 v170, 0xffff0000, v170
	v_lshlrev_b32_e32 v199, 16, v171
	v_and_b32_e32 v171, 0xffff0000, v171
	v_lshlrev_b32_e32 v200, 16, v172
	v_and_b32_e32 v172, 0xffff0000, v172
	v_lshlrev_b32_e32 v203, 16, v174
	v_and_b32_e32 v174, 0xffff0000, v174
	v_lshlrev_b32_e32 v205, 16, v175
	v_and_b32_e32 v175, 0xffff0000, v175
	v_lshlrev_b32_e32 v201, 16, v173
	v_and_b32_e32 v173, 0xffff0000, v173
	v_lshlrev_b32_e32 v206, 16, v176
	v_and_b32_e32 v176, 0xffff0000, v176
	v_lshlrev_b32_e32 v207, 16, v177
	v_and_b32_e32 v177, 0xffff0000, v177
	v_add_f32_e32 v170, v185, v170
	v_add_f32_e32 v171, v183, v171
	v_add_f32_e32 v185, v189, v172
	v_add_f32_e32 v189, v193, v174
	v_add_f32_e32 v191, v191, v175
	v_add_f32_e32 v184, v184, v198
	v_add_f32_e32 v182, v182, v199
	v_add_f32_e32 v183, v188, v200
	v_add_f32_e32 v187, v187, v173
	v_add_f32_e32 v188, v192, v203
	v_add_f32_e32 v190, v190, v205
	v_add_f32_e32 v193, v197, v176
	v_add_f32_e32 v195, v195, v177
	v_mul_f32_e32 v176, v170, v170
	v_mul_f32_e32 v177, v171, v171
	v_cvt_pk_bf16_f32 v172, v184, v170
	v_cvt_pk_bf16_f32 v173, v182, v171
	v_mul_f32_e32 v170, v189, v189
	v_mul_f32_e32 v171, v191, v191
	v_fmac_f32_e32 v170, v188, v188
	v_fmac_f32_e32 v171, v190, v190
	v_add_f32_e32 v192, v196, v206
	v_add_f32_e32 v170, v170, v171
	v_mul_f32_e32 v171, v193, v193
	v_mul_f32_e32 v196, v185, v185
	v_fmac_f32_e32 v176, v184, v184
	v_fmac_f32_e32 v177, v182, v182
	v_fmac_f32_e32 v171, v192, v192
	v_add_f32_e32 v186, v186, v201
	v_add_f32_e32 v194, v194, v207
	v_mul_f32_e32 v197, v187, v187
	v_fmac_f32_e32 v196, v183, v183
	v_add_f32_e32 v176, v176, v177
	v_add_f32_e32 v170, v171, v170
	v_mul_f32_e32 v171, v195, v195
	v_fmac_f32_e32 v197, v186, v186
	v_add_f32_e32 v176, v196, v176
	v_fmac_f32_e32 v171, v194, v194
	v_add_f32_e32 v176, v197, v176
	v_add_f32_e32 v170, v171, v170
	v_add_f32_e32 v171, v176, v170
	v_and_b32_e32 v176, 64, v202
	v_xor_b32_e32 v170, 16, v202
	v_add_u32_e32 v182, 64, v176
	v_cmp_lt_i32_e32 vcc, v170, v182
	v_cvt_pk_bf16_f32 v174, v183, v185
	v_lshl_add_u64 v[176:177], s[10:11], 0, v[180:181]
	v_lshl_add_u64 v[178:179], v[176:177], 0, v[178:179]
	v_cndmask_b32_e32 v170, v202, v170, vcc
	v_lshlrev_b32_e32 v170, 2, v170
	ds_bpermute_b32 v183, v170, v171
	v_cvt_pk_bf16_f32 v175, v186, v187
	global_store_dwordx4 v[178:179], v[172:175], off sc0 sc1
	s_waitcnt lgkmcnt(0)
	s_nop 0
	v_add_f32_e32 v172, v171, v183
	v_xor_b32_e32 v171, 32, v202
	v_cmp_lt_i32_e32 vcc, v171, v182
	v_cvt_pk_bf16_f32 v174, v188, v189
	v_cvt_pk_bf16_f32 v175, v190, v191
	v_cvt_pk_bf16_f32 v176, v192, v193
	v_cvt_pk_bf16_f32 v177, v194, v195
	global_store_dwordx4 v[178:179], v[174:177], off offset:256 sc0 sc1
	s_nop 0
	v_cndmask_b32_e32 v171, v202, v171, vcc
	v_lshlrev_b32_e32 v171, 2, v171
	ds_bpermute_b32 v173, v171, v172
	s_and_saveexec_b64 s[24:25], s[44:45]
	s_cbranch_execz .LBB0_2200
	v_lshlrev_b64 v[174:175], 7, v[156:157]
	v_lshl_add_u64 v[174:175], s[22:23], 0, v[174:175]
	s_waitcnt lgkmcnt(0)
	v_add_f32_e32 v157, v172, v173
	global_store_dword v[174:175], v157, off
; __device__ __forceinline__ unsigned cvt_pk_bf16(float lo, float hi) { unsigned r; asm volatile("v_cvt_pk_bf16_f32 %0, %1, %2" : "=v"(r) : "v"(lo), "v"(hi)); return r; }
;     __device__ __forceinline__ void operator()(const f32x4 (&acc)[2][2][4][2], const Unit& u, int wr, int wc, int fr, int fq) const {
;     ...
;                 for (int bj = 0; bj < 2; ++bj) old[m][bj] = *(const u32x4*)(HB + (size_t)(row0 + ai * HALF + m * 16) * ldc + col0 + bj * HALF);
; #pragma unroll
;             for (int m = 0; m < 4; ++m) { const int row = row0 + ai * HALF + m * 16; float ss = 0.f;
; #pragma unroll
;                 for (int bj = 0; bj < 2; ++bj) { const u32x4 ow = old[m][bj];
;                     f32x4 v0 = (acc[ai][bj][m][0] + bv[bj][0]) * accs, v1 = (acc[ai][bj][m][1] + bv[bj][1]) * accs;
;                     v0[0] += __uint_as_float(ow.x << 16); v0[1] += __uint_as_float(ow.x & 0xffff0000u); v0[2] += __uint_as_float(ow.y << 16); v0[3] += __uint_as_float(ow.y & 0xffff0000u);
;                     v1[0] += __uint_as_float(ow.z << 16); v1[1] += __uint_as_float(ow.z & 0xffff0000u); v1[2] += __uint_as_float(ow.w << 16); v1[3] += __uint_as_float(ow.w & 0xffff0000u);
;                     ss += (v0[0] * v0[0] + v0[1] * v0[1]) + (v0[2] * v0[2] + v0[3] * v0[3]) + (v1[0] * v1[0] + v1[1] * v1[1]) + (v1[2] * v1[2] + v1[3] * v1[3]);
;                     u32x4 w; w.x = cvt_pk_bf16(v0[0], v0[1]); w.y = cvt_pk_bf16(v0[2], v0[3]); w.z = cvt_pk_bf16(v1[0], v1[1]); w.w = cvt_pk_bf16(v1[2], v1[3]);
;                     *(u32x4*)(HB + (size_t)row * ldc + col0 + bj * HALF) = w; }
;                 ss += __shfl_xor(ss, 16); ss += __shfl_xor(ss, 32);
;                 if (fq == 0) ssp[(size_t)row * 32] = ss; }
.LBB0_2200:
	s_or_b64 exec, exec, s[24:25]
	v_pk_add_f32 v[108:109], v[108:109], 0 op_sel_hi:[1,0]
	v_lshlrev_b32_e32 v157, 16, v132
	v_and_b32_e32 v132, 0xffff0000, v132
	v_pk_add_f32 v[110:111], v[110:111], 0 op_sel_hi:[1,0]
	v_add_f32_e32 v109, v109, v132
	v_lshlrev_b32_e32 v132, 16, v133
	v_add_f32_e32 v110, v110, v132
	v_and_b32_e32 v132, 0xffff0000, v133
	v_pk_add_f32 v[104:105], v[104:105], 0 op_sel_hi:[1,0]
	v_add_f32_e32 v111, v111, v132
	v_lshlrev_b32_e32 v132, 16, v134
	v_add_f32_e32 v132, v104, v132
	v_and_b32_e32 v104, 0xffff0000, v134
	v_pk_add_f32 v[106:107], v[106:107], 0 op_sel_hi:[1,0]
	v_add_f32_e32 v133, v105, v104
	v_lshlrev_b32_e32 v104, 16, v135
	v_add_f32_e32 v134, v106, v104
	v_and_b32_e32 v104, 0xffff0000, v135
	v_add_f32_e32 v108, v108, v157
	v_add_f32_e32 v107, v107, v104
	v_mul_f32_e32 v104, v109, v109
	v_mul_f32_e32 v105, v111, v111
	v_fmac_f32_e32 v104, v108, v108
	v_fmac_f32_e32 v105, v110, v110
	v_add_f32_e32 v104, v104, v105
	v_mul_f32_e32 v105, v133, v133
	v_fmac_f32_e32 v105, v132, v132
	v_add_f32_e32 v104, v105, v104
	v_mul_f32_e32 v105, v107, v107
	v_fmac_f32_e32 v105, v134, v134
	v_add_f32_e32 v135, v105, v104
	v_cvt_pk_bf16_f32 v104, v108, v109
	v_pk_add_f32 v[100:101], v[100:101], 0 op_sel_hi:[1,0]
	v_lshlrev_b32_e32 v108, 16, v128
	v_add_f32_e32 v100, v100, v108
	v_and_b32_e32 v108, 0xffff0000, v128
	v_pk_add_f32 v[102:103], v[102:103], 0 op_sel_hi:[1,0]
	v_add_f32_e32 v101, v101, v108
	v_lshlrev_b32_e32 v108, 16, v129
	v_add_f32_e32 v108, v102, v108
	v_and_b32_e32 v102, 0xffff0000, v129
	v_pk_add_f32 v[96:97], v[96:97], 0 op_sel_hi:[1,0]
	v_add_f32_e32 v109, v103, v102
	v_lshlrev_b32_e32 v102, 16, v130
	v_cvt_pk_bf16_f32 v105, v110, v111
	v_add_f32_e32 v110, v96, v102
	v_and_b32_e32 v96, 0xffff0000, v130
	v_pk_add_f32 v[98:99], v[98:99], 0 op_sel_hi:[1,0]
	v_add_f32_e32 v111, v97, v96
	v_lshlrev_b32_e32 v96, 16, v131
	v_add_f32_e32 v128, v98, v96
	v_and_b32_e32 v96, 0xffff0000, v131
	v_add_f32_e32 v129, v99, v96
	v_mul_f32_e32 v96, v101, v101
	v_mul_f32_e32 v97, v109, v109
	v_fmac_f32_e32 v96, v100, v100
	v_fmac_f32_e32 v97, v108, v108
	v_add_f32_e32 v96, v96, v97
	v_mul_f32_e32 v97, v111, v111
	v_fmac_f32_e32 v97, v110, v110
	v_add_f32_e32 v96, v97, v96
	v_mul_f32_e32 v97, v129, v129
	v_fmac_f32_e32 v97, v128, v128
	v_add_f32_e32 v96, v97, v96
	v_add_f32_e32 v99, v135, v96
	ds_bpermute_b32 v130, v170, v99
	s_waitcnt lgkmcnt(1)
	v_lshlrev_b64 v[172:173], 11, v[162:163]
	v_lshl_add_u64 v[96:97], v[172:173], 1, s[10:11]
	v_lshl_add_u64 v[102:103], v[152:153], 1, v[96:97]
	v_cvt_pk_bf16_f32 v106, v132, v133
	s_waitcnt lgkmcnt(0)
	v_add_f32_e32 v96, v99, v130
	ds_bpermute_b32 v97, v171, v96
	v_cvt_pk_bf16_f32 v107, v134, v107
	global_store_dwordx4 v[102:103], v[104:107], off sc0 sc1
	v_cvt_pk_bf16_f32 v98, v100, v101
	v_cvt_pk_bf16_f32 v99, v108, v109
	v_cvt_pk_bf16_f32 v100, v110, v111
	v_cvt_pk_bf16_f32 v101, v128, v129
	global_store_dwordx4 v[102:103], v[98:101], off offset:256 sc0 sc1
	s_and_saveexec_b64 s[24:25], s[44:45]
	s_cbranch_execz .LBB0_2202
	v_lshlrev_b64 v[98:99], 7, v[162:163]
	v_lshl_add_u64 v[98:99], s[22:23], 0, v[98:99]
	s_waitcnt lgkmcnt(0)
	v_add_f32_e32 v96, v96, v97
	global_store_dword v[98:99], v96, off
.LBB0_2202:
	s_or_b64 exec, exec, s[24:25]
	v_pk_add_f32 v[92:93], v[92:93], 0 op_sel_hi:[1,0]
	v_lshlrev_b32_e32 v98, 16, v124
	v_add_f32_e32 v92, v92, v98
	v_and_b32_e32 v98, 0xffff0000, v124
	v_pk_add_f32 v[94:95], v[94:95], 0 op_sel_hi:[1,0]
	v_add_f32_e32 v93, v93, v98
	v_lshlrev_b32_e32 v98, 16, v125
	v_add_f32_e32 v94, v94, v98
	v_and_b32_e32 v98, 0xffff0000, v125
	v_pk_add_f32 v[88:89], v[88:89], 0 op_sel_hi:[1,0]
	v_add_f32_e32 v95, v95, v98
	v_lshlrev_b32_e32 v98, 16, v126
	v_add_f32_e32 v98, v88, v98
	v_and_b32_e32 v88, 0xffff0000, v126
	v_pk_add_f32 v[90:91], v[90:91], 0 op_sel_hi:[1,0]
	v_add_f32_e32 v99, v89, v88
	v_lshlrev_b32_e32 v88, 16, v127
	v_add_f32_e32 v100, v90, v88
	v_and_b32_e32 v88, 0xffff0000, v127
	v_add_f32_e32 v91, v91, v88
	v_mul_f32_e32 v88, v93, v93
	v_mul_f32_e32 v89, v95, v95
	v_fmac_f32_e32 v88, v92, v92
	v_fmac_f32_e32 v89, v94, v94
	v_add_f32_e32 v88, v88, v89
	v_mul_f32_e32 v89, v99, v99
	v_fmac_f32_e32 v89, v98, v98
	v_add_f32_e32 v88, v89, v88
	v_mul_f32_e32 v89, v91, v91
	v_fmac_f32_e32 v89, v100, v100
	v_add_f32_e32 v101, v89, v88
	v_cvt_pk_bf16_f32 v88, v92, v93
	v_pk_add_f32 v[84:85], v[84:85], 0 op_sel_hi:[1,0]
	v_lshlrev_b32_e32 v92, 16, v120
	v_add_f32_e32 v84, v84, v92
	v_and_b32_e32 v92, 0xffff0000, v120
	v_pk_add_f32 v[86:87], v[86:87], 0 op_sel_hi:[1,0]
	v_add_f32_e32 v85, v85, v92
	v_lshlrev_b32_e32 v92, 16, v121
	v_add_f32_e32 v92, v86, v92
	v_and_b32_e32 v86, 0xffff0000, v121
	v_pk_add_f32 v[80:81], v[80:81], 0 op_sel_hi:[1,0]
	v_add_f32_e32 v93, v87, v86
	v_lshlrev_b32_e32 v86, 16, v122
	v_cvt_pk_bf16_f32 v89, v94, v95
	v_add_f32_e32 v94, v80, v86
	v_and_b32_e32 v80, 0xffff0000, v122
	v_pk_add_f32 v[82:83], v[82:83], 0 op_sel_hi:[1,0]
	v_add_f32_e32 v95, v81, v80
	v_lshlrev_b32_e32 v80, 16, v123
	v_cvt_pk_bf16_f32 v90, v98, v99
	v_add_f32_e32 v98, v82, v80
	v_and_b32_e32 v80, 0xffff0000, v123
	v_add_f32_e32 v99, v83, v80
	v_mul_f32_e32 v80, v85, v85
	v_mul_f32_e32 v81, v93, v93
	v_fmac_f32_e32 v80, v84, v84
	v_fmac_f32_e32 v81, v92, v92
	v_add_f32_e32 v80, v80, v81
	v_mul_f32_e32 v81, v95, v95
	v_fmac_f32_e32 v81, v94, v94
	v_add_f32_e32 v80, v81, v80
	v_mul_f32_e32 v81, v99, v99
	v_fmac_f32_e32 v81, v98, v98
	v_add_f32_e32 v80, v81, v80
	v_add_f32_e32 v83, v101, v80
	v_cvt_pk_bf16_f32 v91, v100, v91
	ds_bpermute_b32 v100, v170, v83
	s_waitcnt lgkmcnt(1)
	v_lshlrev_b64 v[96:97], 11, v[160:161]
	v_lshl_add_u64 v[80:81], v[96:97], 1, s[10:11]
	v_lshl_add_u64 v[86:87], v[152:153], 1, v[80:81]
	global_store_dwordx4 v[86:87], v[88:91], off sc0 sc1
	s_waitcnt lgkmcnt(0)
	v_add_f32_e32 v80, v83, v100
	ds_bpermute_b32 v81, v171, v80
	v_cvt_pk_bf16_f32 v82, v84, v85
	v_cvt_pk_bf16_f32 v83, v92, v93
	v_cvt_pk_bf16_f32 v84, v94, v95
	v_cvt_pk_bf16_f32 v85, v98, v99
	global_store_dwordx4 v[86:87], v[82:85], off offset:256 sc0 sc1
	s_and_saveexec_b64 s[24:25], s[44:45]
	s_cbranch_execz .LBB0_2204
	v_lshlrev_b64 v[82:83], 7, v[160:161]
	v_lshl_add_u64 v[82:83], s[22:23], 0, v[82:83]
	s_waitcnt lgkmcnt(0)
	v_add_f32_e32 v80, v80, v81
	global_store_dword v[82:83], v80, off
; __device__ __forceinline__ unsigned cvt_pk_bf16(float lo, float hi) { unsigned r; asm volatile("v_cvt_pk_bf16_f32 %0, %1, %2" : "=v"(r) : "v"(lo), "v"(hi)); return r; }
;     __device__ __forceinline__ void operator()(const f32x4 (&acc)[2][2][4][2], const Unit& u, int wr, int wc, int fr, int fq) const {
;     ...
;         for (int ai = 0; ai < 2; ++ai) {
;             u32x4 old[4][2];
; #pragma unroll
;             for (int m = 0; m < 4; ++m)
; #pragma unroll
;                 for (int bj = 0; bj < 2; ++bj) old[m][bj] = *(const u32x4*)(HB + (size_t)(row0 + ai * HALF + m * 16) * ldc + col0 + bj * HALF);
; #pragma unroll
;             for (int m = 0; m < 4; ++m) { const int row = row0 + ai * HALF + m * 16; float ss = 0.f;
; #pragma unroll
;                 for (int bj = 0; bj < 2; ++bj) { const u32x4 ow = old[m][bj];
;                     f32x4 v0 = (acc[ai][bj][m][0] + bv[bj][0]) * accs, v1 = (acc[ai][bj][m][1] + bv[bj][1]) * accs;
;                     v0[0] += __uint_as_float(ow.x << 16); v0[1] += __uint_as_float(ow.x & 0xffff0000u); v0[2] += __uint_as_float(ow.y << 16); v0[3] += __uint_as_float(ow.y & 0xffff0000u);
;                     v1[0] += __uint_as_float(ow.z << 16); v1[1] += __uint_as_float(ow.z & 0xffff0000u); v1[2] += __uint_as_float(ow.w << 16); v1[3] += __uint_as_float(ow.w & 0xffff0000u);
;                     ss += (v0[0] * v0[0] + v0[1] * v0[1]) + (v0[2] * v0[2] + v0[3] * v0[3]) + (v1[0] * v1[0] + v1[1] * v1[1]) + (v1[2] * v1[2] + v1[3] * v1[3]);
;                     u32x4 w; w.x = cvt_pk_bf16(v0[0], v0[1]); w.y = cvt_pk_bf16(v0[2], v0[3]); w.z = cvt_pk_bf16(v1[0], v1[1]); w.w = cvt_pk_bf16(v1[2], v1[3]);
;                     *(u32x4*)(HB + (size_t)row * ldc + col0 + bj * HALF) = w; }
;                 ss += __shfl_xor(ss, 16); ss += __shfl_xor(ss, 32);
;                 if (fq == 0) ssp[(size_t)row * 32] = ss; }
.LBB0_2204:
	s_or_b64 exec, exec, s[24:25]
	v_pk_add_f32 v[76:77], v[76:77], 0 op_sel_hi:[1,0]
	v_lshlrev_b32_e32 v82, 16, v116
	v_add_f32_e32 v76, v76, v82
	v_and_b32_e32 v82, 0xffff0000, v116
	v_pk_add_f32 v[78:79], v[78:79], 0 op_sel_hi:[1,0]
	v_add_f32_e32 v77, v77, v82
	v_lshlrev_b32_e32 v82, 16, v117
	v_add_f32_e32 v78, v78, v82
	v_and_b32_e32 v82, 0xffff0000, v117
	v_pk_add_f32 v[72:73], v[72:73], 0 op_sel_hi:[1,0]
	v_add_f32_e32 v79, v79, v82
	v_lshlrev_b32_e32 v82, 16, v118
	v_add_f32_e32 v82, v72, v82
	v_and_b32_e32 v72, 0xffff0000, v118
	v_pk_add_f32 v[74:75], v[74:75], 0 op_sel_hi:[1,0]
	v_add_f32_e32 v83, v73, v72
	v_lshlrev_b32_e32 v72, 16, v119
	v_add_f32_e32 v84, v74, v72
	v_and_b32_e32 v72, 0xffff0000, v119
	v_add_f32_e32 v75, v75, v72
	v_mul_f32_e32 v72, v77, v77
	v_mul_f32_e32 v73, v79, v79
	v_fmac_f32_e32 v72, v76, v76
	v_fmac_f32_e32 v73, v78, v78
	v_add_f32_e32 v72, v72, v73
	v_mul_f32_e32 v73, v83, v83
	v_fmac_f32_e32 v73, v82, v82
	v_add_f32_e32 v72, v73, v72
	v_mul_f32_e32 v73, v75, v75
	v_fmac_f32_e32 v73, v84, v84
	v_add_f32_e32 v85, v73, v72
	v_cvt_pk_bf16_f32 v72, v76, v77
	v_pk_add_f32 v[68:69], v[68:69], 0 op_sel_hi:[1,0]
	v_lshlrev_b32_e32 v76, 16, v112
	v_add_f32_e32 v68, v68, v76
	v_and_b32_e32 v76, 0xffff0000, v112
	v_pk_add_f32 v[70:71], v[70:71], 0 op_sel_hi:[1,0]
	v_add_f32_e32 v69, v69, v76
	v_lshlrev_b32_e32 v76, 16, v113
	v_add_f32_e32 v76, v70, v76
	v_and_b32_e32 v70, 0xffff0000, v113
	v_pk_add_f32 v[64:65], v[64:65], 0 op_sel_hi:[1,0]
	v_add_f32_e32 v77, v71, v70
	v_lshlrev_b32_e32 v70, 16, v114
	v_cvt_pk_bf16_f32 v73, v78, v79
	v_add_f32_e32 v78, v64, v70
	v_and_b32_e32 v64, 0xffff0000, v114
	v_pk_add_f32 v[66:67], v[66:67], 0 op_sel_hi:[1,0]
	v_add_f32_e32 v79, v65, v64
	v_lshlrev_b32_e32 v64, 16, v115
	v_cvt_pk_bf16_f32 v74, v82, v83
	v_add_f32_e32 v82, v66, v64
	v_and_b32_e32 v64, 0xffff0000, v115
	v_add_f32_e32 v83, v67, v64
	v_mul_f32_e32 v64, v69, v69
	v_mul_f32_e32 v65, v77, v77
	v_fmac_f32_e32 v64, v68, v68
	v_fmac_f32_e32 v65, v76, v76
	v_add_f32_e32 v64, v64, v65
	v_mul_f32_e32 v65, v79, v79
	v_fmac_f32_e32 v65, v78, v78
	v_add_f32_e32 v64, v65, v64
	v_mul_f32_e32 v65, v83, v83
	v_fmac_f32_e32 v65, v82, v82
	v_add_f32_e32 v64, v65, v64
	v_add_f32_e32 v67, v85, v64
	v_cvt_pk_bf16_f32 v75, v84, v75
	ds_bpermute_b32 v84, v170, v67
	s_waitcnt lgkmcnt(1)
	v_lshlrev_b64 v[80:81], 11, v[158:159]
	v_lshl_add_u64 v[64:65], v[80:81], 1, s[10:11]
	v_lshl_add_u64 v[70:71], v[152:153], 1, v[64:65]
	global_store_dwordx4 v[70:71], v[72:75], off sc0 sc1
	s_waitcnt lgkmcnt(0)
	v_add_f32_e32 v64, v67, v84
	ds_bpermute_b32 v65, v171, v64
	v_cvt_pk_bf16_f32 v66, v68, v69
	v_cvt_pk_bf16_f32 v67, v76, v77
	v_cvt_pk_bf16_f32 v68, v78, v79
	v_cvt_pk_bf16_f32 v69, v82, v83
	global_store_dwordx4 v[70:71], v[66:69], off offset:256 sc0 sc1
	s_and_saveexec_b64 s[24:25], s[44:45]
	s_cbranch_execz .LBB0_2206
	v_lshlrev_b64 v[66:67], 7, v[158:159]
	v_lshl_add_u64 v[66:67], s[22:23], 0, v[66:67]
	s_waitcnt lgkmcnt(0)
	v_add_f32_e32 v64, v64, v65
	global_store_dword v[66:67], v64, off
.LBB0_2206:
	s_or_b64 exec, exec, s[24:25]
	v_add_u32_e32 v98, 0x80, v156
	v_ashrrev_i32_e32 v99, 31, v98
	v_lshlrev_b64 v[104:105], 12, v[98:99]
	s_waitcnt lgkmcnt(0)
	v_lshl_add_u64 v[64:65], v[154:155], 0, v[104:105]
	global_load_dwordx4 v[100:103], v[64:65], off
	global_load_dwordx4 v[88:91], v[64:65], off offset:256
	v_add_u32_e32 v96, 0x90, v156
	v_ashrrev_i32_e32 v97, 31, v96
	v_lshlrev_b64 v[64:65], 12, v[96:97]
	v_add_u32_e32 v94, 0xa0, v156
	v_lshl_add_u64 v[64:65], v[154:155], 0, v[64:65]
	v_ashrrev_i32_e32 v95, 31, v94
	global_load_dwordx4 v[84:87], v[64:65], off
	global_load_dwordx4 v[80:83], v[64:65], off offset:256
	v_lshlrev_b64 v[64:65], 12, v[94:95]
	v_add_u32_e32 v92, 0xb0, v156
	v_lshl_add_u64 v[64:65], v[154:155], 0, v[64:65]
	v_ashrrev_i32_e32 v93, 31, v92
	global_load_dwordx4 v[76:79], v[64:65], off
	global_load_dwordx4 v[72:75], v[64:65], off offset:256
	v_lshlrev_b64 v[64:65], 12, v[92:93]
	v_lshl_add_u64 v[64:65], v[154:155], 0, v[64:65]
	global_load_dwordx4 v[68:71], v[64:65], off
	s_nop 0
	global_load_dwordx4 v[64:67], v[64:65], off offset:256
	v_pk_add_f32 v[60:61], v[60:61], 0 op_sel_hi:[1,0]
	v_pk_add_f32 v[62:63], v[62:63], 0 op_sel_hi:[1,0]
	v_pk_add_f32 v[56:57], v[56:57], 0 op_sel_hi:[1,0]
	v_pk_add_f32 v[58:59], v[58:59], 0 op_sel_hi:[1,0]
	v_pk_add_f32 v[52:53], v[52:53], 0 op_sel_hi:[1,0]
	v_pk_add_f32 v[54:55], v[54:55], 0 op_sel_hi:[1,0]
	v_pk_add_f32 v[48:49], v[48:49], 0 op_sel_hi:[1,0]
	v_pk_add_f32 v[50:51], v[50:51], 0 op_sel_hi:[1,0]
	s_waitcnt vmcnt(7)
	v_lshlrev_b32_e32 v106, 16, v100
	v_and_b32_e32 v100, 0xffff0000, v100
	v_add_f32_e32 v61, v61, v100
	v_lshlrev_b32_e32 v100, 16, v101
	v_add_f32_e32 v62, v62, v100
	v_and_b32_e32 v100, 0xffff0000, v101
	v_add_f32_e32 v63, v63, v100
	v_lshlrev_b32_e32 v100, 16, v102
	v_add_f32_e32 v56, v56, v100
	v_and_b32_e32 v100, 0xffff0000, v102
	v_add_f32_e32 v57, v57, v100
	v_lshlrev_b32_e32 v100, 16, v103
	v_add_f32_e32 v100, v58, v100
	v_and_b32_e32 v58, 0xffff0000, v103
	v_add_f32_e32 v60, v60, v106
	v_add_f32_e32 v101, v59, v58
	v_mul_f32_e32 v58, v61, v61
	v_mul_f32_e32 v59, v63, v63
	v_fmac_f32_e32 v58, v60, v60
	v_fmac_f32_e32 v59, v62, v62
	v_add_f32_e32 v58, v58, v59
	v_mul_f32_e32 v59, v57, v57
	v_fmac_f32_e32 v59, v56, v56
	v_add_f32_e32 v58, v59, v58
	v_mul_f32_e32 v59, v101, v101
	v_fmac_f32_e32 v59, v100, v100
	v_add_f32_e32 v102, v59, v58
	v_cvt_pk_bf16_f32 v58, v60, v61
	v_cvt_pk_bf16_f32 v59, v62, v63
	v_cvt_pk_bf16_f32 v60, v56, v57
	v_lshl_add_u64 v[56:57], s[10:11], 0, v[104:105]
	v_lshl_add_u64 v[56:57], v[152:153], 1, v[56:57]
	v_cvt_pk_bf16_f32 v61, v100, v101
	global_store_dwordx4 v[56:57], v[58:61], off sc0 sc1
	s_waitcnt vmcnt(7)
	s_nop 0
	v_lshlrev_b32_e32 v58, 16, v88
	v_add_f32_e32 v52, v52, v58
	v_and_b32_e32 v58, 0xffff0000, v88
	v_add_f32_e32 v53, v53, v58
	v_lshlrev_b32_e32 v58, 16, v89
	v_add_f32_e32 v54, v54, v58
	v_and_b32_e32 v58, 0xffff0000, v89
	v_add_f32_e32 v55, v55, v58
	v_lshlrev_b32_e32 v58, 16, v90
	v_add_f32_e32 v58, v48, v58
	v_and_b32_e32 v48, 0xffff0000, v90
	v_add_f32_e32 v59, v49, v48
	v_lshlrev_b32_e32 v48, 16, v91
	v_add_f32_e32 v60, v50, v48
	v_and_b32_e32 v48, 0xffff0000, v91
	v_add_f32_e32 v51, v51, v48
	v_mul_f32_e32 v48, v53, v53
	v_mul_f32_e32 v49, v55, v55
	v_fmac_f32_e32 v48, v52, v52
	v_fmac_f32_e32 v49, v54, v54
	v_add_f32_e32 v48, v48, v49
	v_mul_f32_e32 v49, v59, v59
	v_fmac_f32_e32 v49, v58, v58
	v_add_f32_e32 v48, v49, v48
	v_mul_f32_e32 v49, v51, v51
	v_fmac_f32_e32 v49, v60, v60
	v_add_f32_e32 v48, v49, v48
	v_add_f32_e32 v61, v102, v48
	v_cvt_pk_bf16_f32 v48, v52, v53
	v_cvt_pk_bf16_f32 v49, v54, v55
	v_cvt_pk_bf16_f32 v50, v58, v59
	v_cvt_pk_bf16_f32 v51, v60, v51
	global_store_dwordx4 v[56:57], v[48:51], off offset:256 sc0 sc1
	ds_bpermute_b32 v48, v170, v61
	s_waitcnt lgkmcnt(0)
	v_add_f32_e32 v48, v61, v48
	ds_bpermute_b32 v49, v171, v48
	s_and_saveexec_b64 s[24:25], s[44:45]
	s_cbranch_execz .LBB0_2208
; __device__ __forceinline__ unsigned cvt_pk_bf16(float lo, float hi) { unsigned r; asm volatile("v_cvt_pk_bf16_f32 %0, %1, %2" : "=v"(r) : "v"(lo), "v"(hi)); return r; }
;     __device__ __forceinline__ void operator()(const f32x4 (&acc)[2][2][4][2], const Unit& u, int wr, int wc, int fr, int fq) const {
;     ...
;                 for (int bj = 0; bj < 2; ++bj) old[m][bj] = *(const u32x4*)(HB + (size_t)(row0 + ai * HALF + m * 16) * ldc + col0 + bj * HALF);
; #pragma unroll
;             for (int m = 0; m < 4; ++m) { const int row = row0 + ai * HALF + m * 16; float ss = 0.f;
; #pragma unroll
;                 for (int bj = 0; bj < 2; ++bj) { const u32x4 ow = old[m][bj];
;                     f32x4 v0 = (acc[ai][bj][m][0] + bv[bj][0]) * accs, v1 = (acc[ai][bj][m][1] + bv[bj][1]) * accs;
;                     v0[0] += __uint_as_float(ow.x << 16); v0[1] += __uint_as_float(ow.x & 0xffff0000u); v0[2] += __uint_as_float(ow.y << 16); v0[3] += __uint_as_float(ow.y & 0xffff0000u);
;                     v1[0] += __uint_as_float(ow.z << 16); v1[1] += __uint_as_float(ow.z & 0xffff0000u); v1[2] += __uint_as_float(ow.w << 16); v1[3] += __uint_as_float(ow.w & 0xffff0000u);
;                     ss += (v0[0] * v0[0] + v0[1] * v0[1]) + (v0[2] * v0[2] + v0[3] * v0[3]) + (v1[0] * v1[0] + v1[1] * v1[1]) + (v1[2] * v1[2] + v1[3] * v1[3]);
;                     u32x4 w; w.x = cvt_pk_bf16(v0[0], v0[1]); w.y = cvt_pk_bf16(v0[2], v0[3]); w.z = cvt_pk_bf16(v1[0], v1[1]); w.w = cvt_pk_bf16(v1[2], v1[3]);
;                     *(u32x4*)(HB + (size_t)row * ldc + col0 + bj * HALF) = w; }
;                 ss += __shfl_xor(ss, 16); ss += __shfl_xor(ss, 32);
;                 if (fq == 0) ssp[(size_t)row * 32] = ss; }
	v_lshlrev_b64 v[50:51], 7, v[98:99]
	v_lshl_add_u64 v[50:51], s[22:23], 0, v[50:51]
	s_waitcnt lgkmcnt(0)
	v_add_f32_e32 v48, v48, v49
	global_store_dword v[50:51], v48, off
.LBB0_2208:
	s_or_b64 exec, exec, s[24:25]
	v_pk_add_f32 v[44:45], v[44:45], 0 op_sel_hi:[1,0]
	s_waitcnt vmcnt(7)
	v_lshlrev_b32_e32 v50, 16, v84
	v_add_f32_e32 v44, v44, v50
	v_and_b32_e32 v50, 0xffff0000, v84
	v_pk_add_f32 v[46:47], v[46:47], 0 op_sel_hi:[1,0]
	v_add_f32_e32 v45, v45, v50
	v_lshlrev_b32_e32 v50, 16, v85
	v_add_f32_e32 v46, v46, v50
	v_and_b32_e32 v50, 0xffff0000, v85
	v_pk_add_f32 v[40:41], v[40:41], 0 op_sel_hi:[1,0]
	v_add_f32_e32 v47, v47, v50
	v_lshlrev_b32_e32 v50, 16, v86
	v_add_f32_e32 v50, v40, v50
	v_and_b32_e32 v40, 0xffff0000, v86
	v_pk_add_f32 v[42:43], v[42:43], 0 op_sel_hi:[1,0]
	v_add_f32_e32 v51, v41, v40
	v_lshlrev_b32_e32 v40, 16, v87
	v_add_f32_e32 v52, v42, v40
	v_and_b32_e32 v40, 0xffff0000, v87
	v_add_f32_e32 v43, v43, v40
	v_mul_f32_e32 v40, v45, v45
	v_mul_f32_e32 v41, v47, v47
	v_fmac_f32_e32 v40, v44, v44
	v_fmac_f32_e32 v41, v46, v46
	v_add_f32_e32 v40, v40, v41
	v_mul_f32_e32 v41, v51, v51
	v_fmac_f32_e32 v41, v50, v50
	v_add_f32_e32 v40, v41, v40
	v_mul_f32_e32 v41, v43, v43
	v_fmac_f32_e32 v41, v52, v52
	v_add_f32_e32 v53, v41, v40
	v_cvt_pk_bf16_f32 v40, v44, v45
	v_pk_add_f32 v[36:37], v[36:37], 0 op_sel_hi:[1,0]
	s_waitcnt vmcnt(6)
	v_lshlrev_b32_e32 v44, 16, v80
	v_add_f32_e32 v36, v36, v44
	v_and_b32_e32 v44, 0xffff0000, v80
	v_pk_add_f32 v[38:39], v[38:39], 0 op_sel_hi:[1,0]
	v_add_f32_e32 v37, v37, v44
	v_lshlrev_b32_e32 v44, 16, v81
	v_add_f32_e32 v44, v38, v44
	v_and_b32_e32 v38, 0xffff0000, v81
	v_pk_add_f32 v[32:33], v[32:33], 0 op_sel_hi:[1,0]
	v_add_f32_e32 v45, v39, v38
	v_lshlrev_b32_e32 v38, 16, v82
	v_cvt_pk_bf16_f32 v41, v46, v47
	v_add_f32_e32 v46, v32, v38
	v_and_b32_e32 v32, 0xffff0000, v82
	v_pk_add_f32 v[34:35], v[34:35], 0 op_sel_hi:[1,0]
	v_add_f32_e32 v47, v33, v32
	v_lshlrev_b32_e32 v32, 16, v83
	v_cvt_pk_bf16_f32 v42, v50, v51
	v_add_f32_e32 v50, v34, v32
	v_and_b32_e32 v32, 0xffff0000, v83
	v_add_f32_e32 v51, v35, v32
	v_mul_f32_e32 v32, v37, v37
	v_mul_f32_e32 v33, v45, v45
	v_fmac_f32_e32 v32, v36, v36
	v_fmac_f32_e32 v33, v44, v44
	v_add_f32_e32 v32, v32, v33
	v_mul_f32_e32 v33, v47, v47
	v_fmac_f32_e32 v33, v46, v46
	v_add_f32_e32 v32, v33, v32
	v_mul_f32_e32 v33, v51, v51
	v_fmac_f32_e32 v33, v50, v50
	v_add_f32_e32 v32, v33, v32
	v_add_f32_e32 v35, v53, v32
	v_cvt_pk_bf16_f32 v43, v52, v43
	ds_bpermute_b32 v52, v170, v35
	s_waitcnt lgkmcnt(1)
	v_lshlrev_b64 v[48:49], 11, v[96:97]
	v_lshl_add_u64 v[32:33], v[48:49], 1, s[10:11]
	v_lshl_add_u64 v[38:39], v[152:153], 1, v[32:33]
	global_store_dwordx4 v[38:39], v[40:43], off sc0 sc1
	s_waitcnt lgkmcnt(0)
	v_add_f32_e32 v32, v35, v52
	ds_bpermute_b32 v33, v171, v32
	v_cvt_pk_bf16_f32 v34, v36, v37
	v_cvt_pk_bf16_f32 v35, v44, v45
	v_cvt_pk_bf16_f32 v36, v46, v47
	v_cvt_pk_bf16_f32 v37, v50, v51
	global_store_dwordx4 v[38:39], v[34:37], off offset:256 sc0 sc1
	s_and_saveexec_b64 s[24:25], s[44:45]
	s_cbranch_execz .LBB0_2210
	v_lshlrev_b64 v[34:35], 7, v[96:97]
	v_lshl_add_u64 v[34:35], s[22:23], 0, v[34:35]
	s_waitcnt lgkmcnt(0)
	v_add_f32_e32 v32, v32, v33
	global_store_dword v[34:35], v32, off
; __device__ __forceinline__ unsigned cvt_pk_bf16(float lo, float hi) { unsigned r; asm volatile("v_cvt_pk_bf16_f32 %0, %1, %2" : "=v"(r) : "v"(lo), "v"(hi)); return r; }
;     __device__ __forceinline__ void operator()(const f32x4 (&acc)[2][2][4][2], const Unit& u, int wr, int wc, int fr, int fq) const {
;     ...
;                 for (int bj = 0; bj < 2; ++bj) old[m][bj] = *(const u32x4*)(HB + (size_t)(row0 + ai * HALF + m * 16) * ldc + col0 + bj * HALF);
; #pragma unroll
;             for (int m = 0; m < 4; ++m) { const int row = row0 + ai * HALF + m * 16; float ss = 0.f;
; #pragma unroll
;                 for (int bj = 0; bj < 2; ++bj) { const u32x4 ow = old[m][bj];
;                     f32x4 v0 = (acc[ai][bj][m][0] + bv[bj][0]) * accs, v1 = (acc[ai][bj][m][1] + bv[bj][1]) * accs;
;                     v0[0] += __uint_as_float(ow.x << 16); v0[1] += __uint_as_float(ow.x & 0xffff0000u); v0[2] += __uint_as_float(ow.y << 16); v0[3] += __uint_as_float(ow.y & 0xffff0000u);
;                     v1[0] += __uint_as_float(ow.z << 16); v1[1] += __uint_as_float(ow.z & 0xffff0000u); v1[2] += __uint_as_float(ow.w << 16); v1[3] += __uint_as_float(ow.w & 0xffff0000u);
;                     ss += (v0[0] * v0[0] + v0[1] * v0[1]) + (v0[2] * v0[2] + v0[3] * v0[3]) + (v1[0] * v1[0] + v1[1] * v1[1]) + (v1[2] * v1[2] + v1[3] * v1[3]);
;                     u32x4 w; w.x = cvt_pk_bf16(v0[0], v0[1]); w.y = cvt_pk_bf16(v0[2], v0[3]); w.z = cvt_pk_bf16(v1[0], v1[1]); w.w = cvt_pk_bf16(v1[2], v1[3]);
;                     *(u32x4*)(HB + (size_t)row * ldc + col0 + bj * HALF) = w; }
;                 ss += __shfl_xor(ss, 16); ss += __shfl_xor(ss, 32);
;                 if (fq == 0) ssp[(size_t)row * 32] = ss; }
.LBB0_2210:
	s_or_b64 exec, exec, s[24:25]
	v_pk_add_f32 v[28:29], v[28:29], 0 op_sel_hi:[1,0]
	s_waitcnt vmcnt(7)
	v_lshlrev_b32_e32 v34, 16, v76
	v_add_f32_e32 v28, v28, v34
	v_and_b32_e32 v34, 0xffff0000, v76
	v_pk_add_f32 v[30:31], v[30:31], 0 op_sel_hi:[1,0]
	v_add_f32_e32 v29, v29, v34
	v_lshlrev_b32_e32 v34, 16, v77
	v_add_f32_e32 v30, v30, v34
	v_and_b32_e32 v34, 0xffff0000, v77
	v_pk_add_f32 v[24:25], v[24:25], 0 op_sel_hi:[1,0]
	v_add_f32_e32 v31, v31, v34
	v_lshlrev_b32_e32 v34, 16, v78
	v_add_f32_e32 v34, v24, v34
	v_and_b32_e32 v24, 0xffff0000, v78
	v_pk_add_f32 v[26:27], v[26:27], 0 op_sel_hi:[1,0]
	v_add_f32_e32 v35, v25, v24
	v_lshlrev_b32_e32 v24, 16, v79
	v_add_f32_e32 v36, v26, v24
	v_and_b32_e32 v24, 0xffff0000, v79
	v_add_f32_e32 v27, v27, v24
	v_mul_f32_e32 v24, v29, v29
	v_mul_f32_e32 v25, v31, v31
	v_fmac_f32_e32 v24, v28, v28
	v_fmac_f32_e32 v25, v30, v30
	v_add_f32_e32 v24, v24, v25
	v_mul_f32_e32 v25, v35, v35
	v_fmac_f32_e32 v25, v34, v34
	v_add_f32_e32 v24, v25, v24
	v_mul_f32_e32 v25, v27, v27
	v_fmac_f32_e32 v25, v36, v36
	v_add_f32_e32 v37, v25, v24
	v_cvt_pk_bf16_f32 v24, v28, v29
	v_pk_add_f32 v[20:21], v[20:21], 0 op_sel_hi:[1,0]
	s_waitcnt vmcnt(6)
	v_lshlrev_b32_e32 v28, 16, v72
	v_add_f32_e32 v20, v20, v28
	v_and_b32_e32 v28, 0xffff0000, v72
	v_pk_add_f32 v[22:23], v[22:23], 0 op_sel_hi:[1,0]
	v_add_f32_e32 v21, v21, v28
	v_lshlrev_b32_e32 v28, 16, v73
	v_add_f32_e32 v28, v22, v28
	v_and_b32_e32 v22, 0xffff0000, v73
	v_pk_add_f32 v[16:17], v[16:17], 0 op_sel_hi:[1,0]
	v_add_f32_e32 v29, v23, v22
	v_lshlrev_b32_e32 v22, 16, v74
	v_cvt_pk_bf16_f32 v25, v30, v31
	v_add_f32_e32 v30, v16, v22
	v_and_b32_e32 v16, 0xffff0000, v74
	v_pk_add_f32 v[18:19], v[18:19], 0 op_sel_hi:[1,0]
	v_add_f32_e32 v31, v17, v16
	v_lshlrev_b32_e32 v16, 16, v75
	v_cvt_pk_bf16_f32 v26, v34, v35
	v_add_f32_e32 v34, v18, v16
	v_and_b32_e32 v16, 0xffff0000, v75
	v_add_f32_e32 v35, v19, v16
	v_mul_f32_e32 v16, v21, v21
	v_mul_f32_e32 v17, v29, v29
	v_fmac_f32_e32 v16, v20, v20
	v_fmac_f32_e32 v17, v28, v28
	v_add_f32_e32 v16, v16, v17
	v_mul_f32_e32 v17, v31, v31
	v_fmac_f32_e32 v17, v30, v30
	v_add_f32_e32 v16, v17, v16
	v_mul_f32_e32 v17, v35, v35
	v_fmac_f32_e32 v17, v34, v34
	v_add_f32_e32 v16, v17, v16
	v_add_f32_e32 v19, v37, v16
	v_cvt_pk_bf16_f32 v27, v36, v27
	ds_bpermute_b32 v36, v170, v19
	s_waitcnt lgkmcnt(1)
	v_lshlrev_b64 v[32:33], 11, v[94:95]
	v_lshl_add_u64 v[16:17], v[32:33], 1, s[10:11]
	v_lshl_add_u64 v[22:23], v[152:153], 1, v[16:17]
	global_store_dwordx4 v[22:23], v[24:27], off sc0 sc1
	s_waitcnt lgkmcnt(0)
	v_add_f32_e32 v16, v19, v36
	ds_bpermute_b32 v17, v171, v16
	v_cvt_pk_bf16_f32 v18, v20, v21
	v_cvt_pk_bf16_f32 v19, v28, v29
	v_cvt_pk_bf16_f32 v20, v30, v31
	v_cvt_pk_bf16_f32 v21, v34, v35
	global_store_dwordx4 v[22:23], v[18:21], off offset:256 sc0 sc1
	s_and_saveexec_b64 s[24:25], s[44:45]
	s_cbranch_execz .LBB0_2212
	v_lshlrev_b64 v[18:19], 7, v[94:95]
	v_lshl_add_u64 v[18:19], s[22:23], 0, v[18:19]
	s_waitcnt lgkmcnt(0)
	v_add_f32_e32 v16, v16, v17
	global_store_dword v[18:19], v16, off
.LBB0_2212:
	s_or_b64 exec, exec, s[24:25]
	v_pk_add_f32 v[12:13], v[12:13], 0 op_sel_hi:[1,0]
	s_waitcnt vmcnt(7)
	v_lshlrev_b32_e32 v18, 16, v68
	v_add_f32_e32 v12, v12, v18
	v_and_b32_e32 v18, 0xffff0000, v68
	v_pk_add_f32 v[14:15], v[14:15], 0 op_sel_hi:[1,0]
	v_add_f32_e32 v13, v13, v18
	v_lshlrev_b32_e32 v18, 16, v69
	v_add_f32_e32 v14, v14, v18
	v_and_b32_e32 v18, 0xffff0000, v69
	v_pk_add_f32 v[8:9], v[8:9], 0 op_sel_hi:[1,0]
	v_add_f32_e32 v15, v15, v18
	v_lshlrev_b32_e32 v18, 16, v70
	v_add_f32_e32 v18, v8, v18
	v_and_b32_e32 v8, 0xffff0000, v70
	v_pk_add_f32 v[10:11], v[10:11], 0 op_sel_hi:[1,0]
	v_add_f32_e32 v19, v9, v8
	v_lshlrev_b32_e32 v8, 16, v71
	v_add_f32_e32 v20, v10, v8
	v_and_b32_e32 v8, 0xffff0000, v71
	v_add_f32_e32 v11, v11, v8
	v_mul_f32_e32 v8, v13, v13
	v_mul_f32_e32 v9, v15, v15
	v_fmac_f32_e32 v8, v12, v12
	v_fmac_f32_e32 v9, v14, v14
	v_add_f32_e32 v8, v8, v9
	v_mul_f32_e32 v9, v19, v19
	v_fmac_f32_e32 v9, v18, v18
	v_add_f32_e32 v8, v9, v8
	v_mul_f32_e32 v9, v11, v11
	v_fmac_f32_e32 v9, v20, v20
	v_add_f32_e32 v21, v9, v8
	v_cvt_pk_bf16_f32 v8, v12, v13
	v_pk_add_f32 v[4:5], v[4:5], 0 op_sel_hi:[1,0]
	s_waitcnt vmcnt(6)
	v_lshlrev_b32_e32 v12, 16, v64
	v_add_f32_e32 v4, v4, v12
	v_and_b32_e32 v12, 0xffff0000, v64
	v_pk_add_f32 v[6:7], v[6:7], 0 op_sel_hi:[1,0]
	v_add_f32_e32 v5, v5, v12
	v_lshlrev_b32_e32 v12, 16, v65
	v_add_f32_e32 v12, v6, v12
	v_and_b32_e32 v6, 0xffff0000, v65
	v_pk_add_f32 v[0:1], v[0:1], 0 op_sel_hi:[1,0]
	v_add_f32_e32 v13, v7, v6
	v_lshlrev_b32_e32 v6, 16, v66
	v_cvt_pk_bf16_f32 v9, v14, v15
	v_add_f32_e32 v14, v0, v6
	v_and_b32_e32 v0, 0xffff0000, v66
	v_pk_add_f32 v[2:3], v[2:3], 0 op_sel_hi:[1,0]
	v_add_f32_e32 v15, v1, v0
	v_lshlrev_b32_e32 v0, 16, v67
	v_cvt_pk_bf16_f32 v10, v18, v19
	v_add_f32_e32 v18, v2, v0
	v_and_b32_e32 v0, 0xffff0000, v67
	v_add_f32_e32 v19, v3, v0
	v_mul_f32_e32 v0, v5, v5
	v_mul_f32_e32 v1, v13, v13
	v_fmac_f32_e32 v0, v4, v4
	v_fmac_f32_e32 v1, v12, v12
	v_add_f32_e32 v0, v0, v1
	v_mul_f32_e32 v1, v15, v15
	v_fmac_f32_e32 v1, v14, v14
	v_add_f32_e32 v0, v1, v0
	v_mul_f32_e32 v1, v19, v19
	v_fmac_f32_e32 v1, v18, v18
	v_add_f32_e32 v0, v1, v0
	v_add_f32_e32 v3, v21, v0
	v_cvt_pk_bf16_f32 v11, v20, v11
	ds_bpermute_b32 v20, v170, v3
	s_waitcnt lgkmcnt(1)
	v_lshlrev_b64 v[16:17], 11, v[92:93]
	v_lshl_add_u64 v[0:1], v[16:17], 1, s[10:11]
	v_lshl_add_u64 v[6:7], v[152:153], 1, v[0:1]
	global_store_dwordx4 v[6:7], v[8:11], off sc0 sc1
	s_waitcnt lgkmcnt(0)
	v_add_f32_e32 v0, v3, v20
	ds_bpermute_b32 v1, v171, v0
	v_cvt_pk_bf16_f32 v2, v4, v5
	v_cvt_pk_bf16_f32 v3, v12, v13
	v_cvt_pk_bf16_f32 v4, v14, v15
	v_cvt_pk_bf16_f32 v5, v18, v19
	global_store_dwordx4 v[6:7], v[2:5], off offset:256 sc0 sc1
	s_and_saveexec_b64 s[24:25], s[44:45]
	s_cbranch_execz .LBB0_2214
	v_lshlrev_b64 v[2:3], 7, v[92:93]
	v_lshl_add_u64 v[2:3], s[22:23], 0, v[2:3]
	s_waitcnt lgkmcnt(0)
	v_add_f32_e32 v0, v0, v1
	global_store_dword v[2:3], v0, off

; __device__ __forceinline__ unsigned cvt_pk_bf16(float lo, float hi) { unsigned r; asm volatile("v_cvt_pk_bf16_f32 %0, %1, %2" : "=v"(r) : "v"(lo), "v"(hi)); return r; }
; __device__ __forceinline__ float dpp_up1(float x) { return __builtin_bit_cast(float, __builtin_amdgcn_update_dpp(0, __builtin_bit_cast(int, x), 0x111, 0xf, 0xf, true)); }
;     __device__ __forceinline__ void operator()(const f32x4 (&acc)[2][2][4][2], const Unit& u, int wr, int wc, int fr, int fq) const {
;     ...
;                 f32x4 pg2, pg3, pv2, pv3;
; #pragma unroll
;                 for (int e = 0; e < 4; ++e) { pg2[e] = dpp_up1(xg[2][e]); pg3[e] = dpp_up1(xg[3][e]); pv2[e] = dpp_up1(xv[2][e]); pv3[e] = dpp_up1(xv[3][e]); }
; #pragma unroll
;                 for (int m = 0; m < 4; ++m) {
;                     u32x2_t w; float o[4];
; #pragma unroll
;                     for (int e = 0; e < 4; ++e) {
;                         const float g1 = m >= 1 ? xg[m - (m >= 1 ? 1 : 0)][e] : pg3[e], g2 = m >= 2 ? xg[m - (m >= 2 ? 2 : 0)][e] : (m == 1 ? pg3[e] : pg2[e]);
;                         const float v1 = m >= 1 ? xv[m - (m >= 1 ? 1 : 0)][e] : pv3[e], v2 = m >= 2 ? xv[m - (m >= 2 ? 2 : 0)][e] : (m == 1 ? pv3[e] : pv2[e]);
;                         const float cg_ = bg[e] + w0g[e] * g2 + w1g[e] * g1 + w2g[e] * xg[m][e];
;                         const float cv_ = bv[e] + w0v[e] * v2 + w1v[e] * v1 + w2v[e] * xv[m][e];
;                         o[e] = cg_ * __builtin_amdgcn_rcpf(1.0f + __expf(-cg_)) * cv_;
;                     }
;                     w.x = cvt_pk_bf16(o[0], o[1]); w.y = cvt_pk_bf16(o[2], o[3]);
;                     const int g = g0 + m;
;                     if (n == 0) stash[ai][m] = w;
;                     else if ((fr > 0 || m >= 2) && g < TT) { u32x4 ww; ww.x = stash[ai][m].x; ww.y = stash[ai][m].y; ww.z = w.x; ww.w = w.y; *(u32x4*)(G + (size_t)g * DFF_ + f0 - 4) = ww; }
.LBB0_2292:
	v_mov_b32_dpp v112, v58 row_shr:1 row_mask:0xf bank_mask:0xf bound_ctrl:1
	v_mov_b32_dpp v125, v44 row_shr:1 row_mask:0xf bank_mask:0xf bound_ctrl:1
	s_waitcnt vmcnt(4)
	v_fma_f32 v112, v98, v112, v70
	v_fmac_f32_e32 v112, v90, v125
	v_fmac_f32_e32 v112, v94, v116
	v_mul_f32_e32 v132, 0xbfb8aa3b, v112
	v_exp_f32_e32 v132, v132
	v_mov_b32_dpp v113, v52 row_shr:1 row_mask:0xf bank_mask:0xf bound_ctrl:1
	v_mov_b32_dpp v123, v38 row_shr:1 row_mask:0xf bank_mask:0xf bound_ctrl:1
	s_waitcnt vmcnt(0)
	v_fma_f32 v113, v74, v113, v86
	v_add_f32_e32 v132, 1.0, v132
	v_rcp_f32_e32 v132, v132
	v_fmac_f32_e32 v113, v78, v123
	v_mov_b32_dpp v126, v59 row_shr:1 row_mask:0xf bank_mask:0xf bound_ctrl:1
	v_fmac_f32_e32 v113, v82, v68
	v_mul_f32_e32 v112, v112, v132
	v_mov_b32_dpp v121, v45 row_shr:1 row_mask:0xf bank_mask:0xf bound_ctrl:1
	v_mul_f32_e32 v112, v113, v112
	v_fma_f32 v113, v99, v126, v71
	v_fmac_f32_e32 v113, v91, v121
	v_mov_b32_dpp v127, v53 row_shr:1 row_mask:0xf bank_mask:0xf bound_ctrl:1
	v_fmac_f32_e32 v113, v95, v117
	v_fma_f32 v126, v75, v127, v87
	v_mul_f32_e32 v127, 0xbfb8aa3b, v113
	v_exp_f32_e32 v127, v127
	v_mov_b32_dpp v119, v39 row_shr:1 row_mask:0xf bank_mask:0xf bound_ctrl:1
	v_fmac_f32_e32 v126, v79, v119
	v_mov_b32_dpp v128, v42 row_shr:1 row_mask:0xf bank_mask:0xf bound_ctrl:1
	v_add_f32_e32 v127, 1.0, v127
	v_rcp_f32_e32 v127, v127
	v_fmac_f32_e32 v126, v83, v69
	v_mov_b32_dpp v55, v32 row_shr:1 row_mask:0xf bank_mask:0xf bound_ctrl:1
	v_mov_b32_dpp v129, v36 row_shr:1 row_mask:0xf bank_mask:0xf bound_ctrl:1
	v_mul_f32_e32 v113, v113, v127
	v_mul_f32_e32 v113, v126, v113
	v_fma_f32 v126, v100, v128, v72
	v_fmac_f32_e32 v126, v92, v55
	v_fmac_f32_e32 v126, v96, v62
	v_mul_f32_e32 v128, 0xbfb8aa3b, v126
	v_exp_f32_e32 v128, v128
	v_mov_b32_dpp v54, v34 row_shr:1 row_mask:0xf bank_mask:0xf bound_ctrl:1
	v_fma_f32 v127, v76, v129, v88
	v_fmac_f32_e32 v127, v80, v54
	v_add_f32_e32 v128, 1.0, v128
	v_rcp_f32_e32 v128, v128
	v_mov_b32_dpp v130, v43 row_shr:1 row_mask:0xf bank_mask:0xf bound_ctrl:1
	v_fmac_f32_e32 v127, v84, v60
	v_mov_b32_dpp v47, v33 row_shr:1 row_mask:0xf bank_mask:0xf bound_ctrl:1
	v_mul_f32_e32 v126, v126, v128
	v_mul_f32_e32 v126, v127, v126
	v_fma_f32 v127, v101, v130, v73
	v_fmac_f32_e32 v127, v93, v47
	v_fmac_f32_e32 v127, v97, v63
	v_mul_f32_e32 v129, 0xbfb8aa3b, v127
	v_exp_f32_e32 v129, v129
	v_mov_b32_dpp v131, v37 row_shr:1 row_mask:0xf bank_mask:0xf bound_ctrl:1
	v_mov_b32_dpp v46, v35 row_shr:1 row_mask:0xf bank_mask:0xf bound_ctrl:1
	v_fma_f32 v128, v77, v131, v89
	v_add_f32_e32 v129, 1.0, v129
	v_rcp_f32_e32 v129, v129
	v_fmac_f32_e32 v128, v81, v46
	v_cmp_gt_i32_e32 vcc, s85, v215
	v_fmac_f32_e32 v128, v85, v61
	v_mul_f32_e32 v127, v127, v129
	s_and_b64 s[2:3], s[44:45], vcc
	v_mul_f32_e32 v127, v128, v127
	v_cvt_pk_bf16_f32 v112, v112, v113
	v_cvt_pk_bf16_f32 v113, v126, v127
	s_and_saveexec_b64 s[0:1], s[2:3]
	s_cbranch_execz .LBB0_2294
	v_mov_b64_e32 v[126:127], s[14:15]
	v_mad_i64_i32 v[126:127], s[2:3], v215, s92, v[126:127]
	v_lshl_add_u64 v[126:127], v[178:179], 1, v[126:127]
	global_store_dwordx4 v[126:127], v[110:113], off sc0 sc1
.LBB0_2294:
	s_or_b64 exec, exec, s[0:1]
	s_nop 0
	v_fma_f32 v110, v98, v125, v70
	v_fmac_f32_e32 v110, v90, v116
	v_fmac_f32_e32 v110, v94, v56
	v_mul_f32_e32 v112, 0xbfb8aa3b, v110
	v_exp_f32_e32 v112, v112
	v_fma_f32 v111, v74, v123, v86
	v_fmac_f32_e32 v111, v78, v68
	v_fmac_f32_e32 v111, v82, v50
	v_add_f32_e32 v112, 1.0, v112
	v_rcp_f32_e32 v112, v112
	v_fma_f32 v55, v100, v55, v72
	v_fmac_f32_e32 v55, v92, v62
	v_fmac_f32_e32 v55, v96, v48
	v_mul_f32_e32 v110, v110, v112
	v_mul_f32_e32 v110, v111, v110
	v_fma_f32 v111, v99, v121, v71
	v_fmac_f32_e32 v111, v91, v117
	v_fmac_f32_e32 v111, v95, v57
	v_mul_f32_e32 v113, 0xbfb8aa3b, v111
	v_exp_f32_e32 v113, v113
	v_fma_f32 v112, v75, v119, v87
	v_fmac_f32_e32 v112, v79, v69
	v_fmac_f32_e32 v112, v83, v51
	v_add_f32_e32 v113, 1.0, v113
	v_rcp_f32_e32 v113, v113
	v_fma_f32 v54, v76, v54, v88
	v_fma_f32 v47, v101, v47, v73
	v_fmac_f32_e32 v54, v80, v60
	v_mul_f32_e32 v111, v111, v113
	v_mul_f32_e32 v111, v112, v111
	v_mul_f32_e32 v112, 0xbfb8aa3b, v55
	v_exp_f32_e32 v112, v112
	v_fmac_f32_e32 v47, v93, v63
	v_fmac_f32_e32 v54, v84, v40
	v_fmac_f32_e32 v47, v97, v49
	v_add_f32_e32 v112, 1.0, v112
	v_rcp_f32_e32 v112, v112
	v_fma_f32 v46, v77, v46, v89
	v_fmac_f32_e32 v46, v81, v61
	v_cmp_gt_i32_e32 vcc, s85, v218
	v_mul_f32_e32 v55, v55, v112
	v_mul_f32_e32 v54, v54, v55
	v_mul_f32_e32 v55, 0xbfb8aa3b, v47
	v_exp_f32_e32 v55, v55
	v_fmac_f32_e32 v46, v85, v41
	s_and_b64 s[2:3], s[44:45], vcc
	v_cvt_pk_bf16_f32 v110, v110, v111
	v_add_f32_e32 v55, 1.0, v55
	v_rcp_f32_e32 v55, v55
	s_nop 0
	v_mul_f32_e32 v47, v47, v55
	v_mul_f32_e32 v46, v46, v47
	v_cvt_pk_bf16_f32 v111, v54, v46
	s_and_saveexec_b64 s[0:1], s[2:3]
	s_cbranch_execz .LBB0_2296
	v_mov_b64_e32 v[46:47], s[14:15]
	v_mad_i64_i32 v[46:47], s[2:3], v218, s92, v[46:47]
	v_lshl_add_u64 v[46:47], v[178:179], 1, v[46:47]
	global_store_dwordx4 v[46:47], v[108:111], off sc0 sc1
; __device__ __forceinline__ unsigned cvt_pk_bf16(float lo, float hi) { unsigned r; asm volatile("v_cvt_pk_bf16_f32 %0, %1, %2" : "=v"(r) : "v"(lo), "v"(hi)); return r; }
;     __device__ __forceinline__ void operator()(const f32x4 (&acc)[2][2][4][2], const Unit& u, int wr, int wc, int fr, int fq) const {
;     ...
;                 for (int m = 0; m < 4; ++m) {
;                     u32x2_t w; float o[4];
; #pragma unroll
;                     for (int e = 0; e < 4; ++e) {
;                         const float g1 = m >= 1 ? xg[m - (m >= 1 ? 1 : 0)][e] : pg3[e], g2 = m >= 2 ? xg[m - (m >= 2 ? 2 : 0)][e] : (m == 1 ? pg3[e] : pg2[e]);
;                         const float v1 = m >= 1 ? xv[m - (m >= 1 ? 1 : 0)][e] : pv3[e], v2 = m >= 2 ? xv[m - (m >= 2 ? 2 : 0)][e] : (m == 1 ? pv3[e] : pv2[e]);
;                         const float cg_ = bg[e] + w0g[e] * g2 + w1g[e] * g1 + w2g[e] * xg[m][e];
;                         const float cv_ = bv[e] + w0v[e] * v2 + w1v[e] * v1 + w2v[e] * xv[m][e];
;                         o[e] = cg_ * __builtin_amdgcn_rcpf(1.0f + __expf(-cg_)) * cv_;
;                     }
;                     w.x = cvt_pk_bf16(o[0], o[1]); w.y = cvt_pk_bf16(o[2], o[3]);
;                     const int g = g0 + m;
;                     if (n == 0) stash[ai][m] = w;
;                     else if ((fr > 0 || m >= 2) && g < TT) { u32x4 ww; ww.x = stash[ai][m].x; ww.y = stash[ai][m].y; ww.z = w.x; ww.w = w.y; *(u32x4*)(G + (size_t)g * DFF_ + f0 - 4) = ww; }
.LBB0_2296:
	s_or_b64 exec, exec, s[0:1]
	v_fma_f32 v46, v98, v116, v70
	v_fmac_f32_e32 v46, v90, v56
	v_fmac_f32_e32 v46, v94, v58
	v_mul_f32_e32 v54, 0xbfb8aa3b, v46
	v_exp_f32_e32 v54, v54
	v_fma_f32 v47, v74, v68, v86
	v_fmac_f32_e32 v47, v78, v50
	v_fmac_f32_e32 v47, v82, v52
	v_add_f32_e32 v54, 1.0, v54
	v_rcp_f32_e32 v54, v54
	v_cmp_gt_i32_e32 vcc, s93, v215
	v_mul_f32_e32 v46, v46, v54
	v_mul_f32_e32 v46, v47, v46
	v_fma_f32 v47, v99, v117, v71
	v_fmac_f32_e32 v47, v91, v57
	v_fmac_f32_e32 v47, v95, v59
	v_mul_f32_e32 v55, 0xbfb8aa3b, v47
	v_exp_f32_e32 v55, v55
	v_fma_f32 v54, v75, v69, v87
	v_fmac_f32_e32 v54, v79, v51
	v_fmac_f32_e32 v54, v83, v53
	v_add_f32_e32 v55, 1.0, v55
	v_rcp_f32_e32 v55, v55
	s_nop 0
	v_mul_f32_e32 v47, v47, v55
	v_mul_f32_e32 v47, v54, v47
	v_fma_f32 v54, v100, v62, v72
	v_fmac_f32_e32 v54, v92, v48
	v_fmac_f32_e32 v54, v96, v42
	v_fma_f32 v55, v76, v60, v88
	v_mul_f32_e32 v60, 0xbfb8aa3b, v54
	v_exp_f32_e32 v60, v60
	v_fmac_f32_e32 v55, v80, v40
	v_fmac_f32_e32 v55, v84, v36
	v_cvt_pk_bf16_f32 v108, v46, v47
	v_add_f32_e32 v60, 1.0, v60
	v_rcp_f32_e32 v60, v60
	s_nop 0
	v_mul_f32_e32 v54, v54, v60
	v_mul_f32_e32 v54, v55, v54
	v_fma_f32 v55, v101, v63, v73
	v_fmac_f32_e32 v55, v93, v49
	v_fmac_f32_e32 v55, v97, v43
	v_fma_f32 v60, v77, v61, v89
	v_mul_f32_e32 v61, 0xbfb8aa3b, v55
	v_exp_f32_e32 v61, v61
	v_fmac_f32_e32 v60, v81, v41
	v_fmac_f32_e32 v60, v85, v37
	v_add_f32_e32 v61, 1.0, v61
	v_rcp_f32_e32 v61, v61
	s_nop 0
	v_mul_f32_e32 v55, v55, v61
	v_mul_f32_e32 v55, v60, v55
	v_cvt_pk_bf16_f32 v109, v54, v55
	s_and_saveexec_b64 s[0:1], vcc
	s_cbranch_execz .LBB0_2298
	v_mov_b64_e32 v[46:47], s[14:15]
	v_mad_i64_i32 v[46:47], s[2:3], v216, s92, v[46:47]
	v_lshl_add_u64 v[46:47], v[178:179], 1, v[46:47]
	global_store_dwordx4 v[46:47], v[106:109], off sc0 sc1
.LBB0_2298:
	s_or_b64 exec, exec, s[0:1]
	v_fma_f32 v46, v98, v56, v70
	v_fmac_f32_e32 v46, v90, v58
	v_fmac_f32_e32 v46, v94, v44
	v_mul_f32_e32 v44, 0xbfb8aa3b, v46
	v_exp_f32_e32 v44, v44
	v_fma_f32 v47, v74, v50, v86
	v_fma_f32 v50, v99, v57, v71
	v_fmac_f32_e32 v50, v91, v59
	v_fmac_f32_e32 v50, v95, v45
	v_add_f32_e32 v44, 1.0, v44
	v_mul_f32_e32 v45, 0xbfb8aa3b, v50
	v_rcp_f32_e32 v44, v44
	v_exp_f32_e32 v45, v45
	v_fmac_f32_e32 v47, v78, v52
	v_fmac_f32_e32 v47, v82, v38
	v_mul_f32_e32 v38, v46, v44
	v_add_f32_e32 v44, 1.0, v45
	v_rcp_f32_e32 v44, v44
	v_fma_f32 v45, v75, v51, v87
	v_fmac_f32_e32 v45, v79, v53
	v_fma_f32 v40, v76, v40, v88
	v_fmac_f32_e32 v45, v83, v39
	v_mul_f32_e32 v39, v50, v44
	v_fma_f32 v44, v100, v48, v72
	v_fmac_f32_e32 v40, v80, v36
	v_fma_f32 v36, v101, v49, v73
	v_fmac_f32_e32 v44, v92, v42
	v_fmac_f32_e32 v36, v93, v43
	v_fmac_f32_e32 v44, v96, v32
	v_fmac_f32_e32 v36, v97, v33
	v_mul_f32_e32 v32, 0xbfb8aa3b, v44
	v_mul_f32_e32 v33, 0xbfb8aa3b, v36
	v_exp_f32_e32 v32, v32
	v_exp_f32_e32 v33, v33
	v_fmac_f32_e32 v40, v84, v34
	v_fma_f32 v34, v77, v41, v89
	v_add_f32_e32 v32, 1.0, v32
	v_add_f32_e32 v33, 1.0, v33
	v_rcp_f32_e32 v32, v32
	v_rcp_f32_e32 v33, v33
	v_fmac_f32_e32 v34, v81, v37
	v_fmac_f32_e32 v34, v85, v35
	v_mul_f32_e32 v32, v44, v32
	v_mul_f32_e32 v33, v36, v33
	v_cmp_gt_i32_e32 vcc, s94, v215
	v_mul_f32_e32 v38, v47, v38
	v_mul_f32_e32 v39, v45, v39
	v_mul_f32_e32 v32, v40, v32
	v_mul_f32_e32 v33, v34, v33
	v_cvt_pk_bf16_f32 v116, v38, v39
	v_cvt_pk_bf16_f32 v117, v32, v33
	s_and_saveexec_b64 s[0:1], vcc
	s_cbranch_execz .LBB0_2300
	v_mov_b64_e32 v[32:33], s[14:15]
	v_mad_i64_i32 v[32:33], s[2:3], v217, s92, v[32:33]
	v_lshl_add_u64 v[32:33], v[178:179], 1, v[32:33]
	global_store_dwordx4 v[32:33], v[114:117], off sc0 sc1

; __device__ __forceinline__ unsigned cvt_pk_bf16(float lo, float hi) { unsigned r; asm volatile("v_cvt_pk_bf16_f32 %0, %1, %2" : "=v"(r) : "v"(lo), "v"(hi)); return r; }
; __device__ __forceinline__ float dpp_up1(float x) { return __builtin_bit_cast(float, __builtin_amdgcn_update_dpp(0, __builtin_bit_cast(int, x), 0x111, 0xf, 0xf, true)); }
;     __device__ __forceinline__ void operator()(const f32x4 (&acc)[2][2][4][2], const Unit& u, int wr, int wc, int fr, int fq) const {
;     ...
;                 f32x4 pg2, pg3, pv2, pv3;
; #pragma unroll
;                 for (int e = 0; e < 4; ++e) { pg2[e] = dpp_up1(xg[2][e]); pg3[e] = dpp_up1(xg[3][e]); pv2[e] = dpp_up1(xv[2][e]); pv3[e] = dpp_up1(xv[3][e]); }
; #pragma unroll
;                 for (int m = 0; m < 4; ++m) {
;                     u32x2_t w; float o[4];
; #pragma unroll
;                     for (int e = 0; e < 4; ++e) {
;                         const float g1 = m >= 1 ? xg[m - (m >= 1 ? 1 : 0)][e] : pg3[e], g2 = m >= 2 ? xg[m - (m >= 2 ? 2 : 0)][e] : (m == 1 ? pg3[e] : pg2[e]);
;                         const float v1 = m >= 1 ? xv[m - (m >= 1 ? 1 : 0)][e] : pv3[e], v2 = m >= 2 ? xv[m - (m >= 2 ? 2 : 0)][e] : (m == 1 ? pv3[e] : pv2[e]);
;                         const float cg_ = bg[e] + w0g[e] * g2 + w1g[e] * g1 + w2g[e] * xg[m][e];
;                         const float cv_ = bv[e] + w0v[e] * v2 + w1v[e] * v1 + w2v[e] * xv[m][e];
;                         o[e] = cg_ * __builtin_amdgcn_rcpf(1.0f + __expf(-cg_)) * cv_;
;                     }
;                     w.x = cvt_pk_bf16(o[0], o[1]); w.y = cvt_pk_bf16(o[2], o[3]);
;                     const int g = g0 + m;
;                     if (n == 0) stash[ai][m] = w;
;                     else if ((fr > 0 || m >= 2) && g < TT) { u32x4 ww; ww.x = stash[ai][m].x; ww.y = stash[ai][m].y; ww.z = w.x; ww.w = w.y; *(u32x4*)(G + (size_t)g * DFF_ + f0 - 4) = ww; }
.LBB0_2302:
	v_mov_b32_dpp v40, v26 row_shr:1 row_mask:0xf bank_mask:0xf bound_ctrl:1
	v_mov_b32_dpp v39, v12 row_shr:1 row_mask:0xf bank_mask:0xf bound_ctrl:1
	v_fma_f32 v40, v98, v40, v70
	v_fmac_f32_e32 v40, v90, v39
	v_fmac_f32_e32 v40, v94, v34
	v_mul_f32_e32 v48, 0xbfb8aa3b, v40
	v_exp_f32_e32 v48, v48
	v_mov_b32_dpp v41, v20 row_shr:1 row_mask:0xf bank_mask:0xf bound_ctrl:1
	v_mov_b32_dpp v38, v6 row_shr:1 row_mask:0xf bank_mask:0xf bound_ctrl:1
	v_fma_f32 v41, v74, v41, v86
	v_add_f32_e32 v48, 1.0, v48
	v_rcp_f32_e32 v48, v48
	v_fmac_f32_e32 v41, v78, v38
	v_mov_b32_dpp v42, v27 row_shr:1 row_mask:0xf bank_mask:0xf bound_ctrl:1
	v_fmac_f32_e32 v41, v82, v32
	v_mul_f32_e32 v40, v40, v48
	v_mov_b32_dpp v37, v13 row_shr:1 row_mask:0xf bank_mask:0xf bound_ctrl:1
	v_mul_f32_e32 v40, v41, v40
	v_fma_f32 v41, v99, v42, v71
	v_fmac_f32_e32 v41, v91, v37
	v_mov_b32_dpp v43, v21 row_shr:1 row_mask:0xf bank_mask:0xf bound_ctrl:1
	v_fmac_f32_e32 v41, v95, v35
	v_fma_f32 v42, v75, v43, v87
	v_mul_f32_e32 v43, 0xbfb8aa3b, v41
	v_exp_f32_e32 v43, v43
	v_mov_b32_dpp v36, v7 row_shr:1 row_mask:0xf bank_mask:0xf bound_ctrl:1
	v_fmac_f32_e32 v42, v79, v36
	v_mov_b32_dpp v44, v10 row_shr:1 row_mask:0xf bank_mask:0xf bound_ctrl:1
	v_add_f32_e32 v43, 1.0, v43
	v_rcp_f32_e32 v43, v43
	v_fmac_f32_e32 v42, v83, v33
	v_mov_b32_dpp v23, v0 row_shr:1 row_mask:0xf bank_mask:0xf bound_ctrl:1
	v_mov_b32_dpp v45, v4 row_shr:1 row_mask:0xf bank_mask:0xf bound_ctrl:1
	v_mul_f32_e32 v41, v41, v43
	v_mul_f32_e32 v41, v42, v41
	v_fma_f32 v42, v100, v44, v72
	v_fmac_f32_e32 v42, v92, v23
	v_fmac_f32_e32 v42, v96, v30
	v_mul_f32_e32 v44, 0xbfb8aa3b, v42
	v_exp_f32_e32 v44, v44
	v_mov_b32_dpp v22, v2 row_shr:1 row_mask:0xf bank_mask:0xf bound_ctrl:1
	v_fma_f32 v43, v76, v45, v88
	v_fmac_f32_e32 v43, v80, v22
	v_add_f32_e32 v44, 1.0, v44
	v_rcp_f32_e32 v44, v44
	v_mov_b32_dpp v46, v11 row_shr:1 row_mask:0xf bank_mask:0xf bound_ctrl:1
	v_fmac_f32_e32 v43, v84, v28
	v_mov_b32_dpp v15, v1 row_shr:1 row_mask:0xf bank_mask:0xf bound_ctrl:1
	v_mul_f32_e32 v42, v42, v44
	v_mul_f32_e32 v42, v43, v42
	v_fma_f32 v43, v101, v46, v73
	v_fmac_f32_e32 v43, v93, v15
	v_fmac_f32_e32 v43, v97, v31
	v_mul_f32_e32 v45, 0xbfb8aa3b, v43
	v_exp_f32_e32 v45, v45
	v_mov_b32_dpp v47, v5 row_shr:1 row_mask:0xf bank_mask:0xf bound_ctrl:1
	v_mov_b32_dpp v14, v3 row_shr:1 row_mask:0xf bank_mask:0xf bound_ctrl:1
	v_fma_f32 v44, v77, v47, v89
	v_add_f32_e32 v45, 1.0, v45
	v_rcp_f32_e32 v45, v45
	v_fmac_f32_e32 v44, v81, v14
	v_cmp_gt_i32_e32 vcc, s85, v211
	v_fmac_f32_e32 v44, v85, v29
	v_mul_f32_e32 v43, v43, v45
	s_and_b64 s[2:3], s[44:45], vcc
	v_mul_f32_e32 v43, v44, v43
	v_cvt_pk_bf16_f32 v106, v40, v41
	v_cvt_pk_bf16_f32 v107, v42, v43
	s_and_saveexec_b64 s[0:1], s[2:3]
	s_cbranch_execz .LBB0_2304
	v_mov_b64_e32 v[40:41], s[14:15]
	v_mad_i64_i32 v[40:41], s[2:3], v211, s92, v[40:41]
	v_lshl_add_u64 v[40:41], v[178:179], 1, v[40:41]
	global_store_dwordx4 v[40:41], v[104:107], off sc0 sc1
.LBB0_2304:
	s_or_b64 exec, exec, s[0:1]
	v_fma_f32 v39, v98, v39, v70
	v_fmac_f32_e32 v39, v90, v34
	v_fmac_f32_e32 v39, v94, v24
	v_mul_f32_e32 v40, 0xbfb8aa3b, v39
	v_exp_f32_e32 v40, v40
	v_fma_f32 v38, v74, v38, v86
	v_fma_f32 v37, v99, v37, v71
	v_fmac_f32_e32 v38, v78, v32
	v_add_f32_e32 v40, 1.0, v40
	v_rcp_f32_e32 v40, v40
	v_fmac_f32_e32 v37, v91, v35
	v_fmac_f32_e32 v38, v82, v18
	v_fmac_f32_e32 v37, v95, v25
	v_mul_f32_e32 v39, v39, v40
	v_mul_f32_e32 v38, v38, v39
	v_mul_f32_e32 v39, 0xbfb8aa3b, v37
	v_exp_f32_e32 v39, v39
	v_fma_f32 v36, v75, v36, v87
	v_fma_f32 v23, v100, v23, v72
	v_fmac_f32_e32 v36, v79, v33
	v_add_f32_e32 v39, 1.0, v39
	v_rcp_f32_e32 v39, v39
	v_fmac_f32_e32 v23, v92, v30
	v_fmac_f32_e32 v36, v83, v19
	v_fmac_f32_e32 v23, v96, v16
	v_mul_f32_e32 v37, v37, v39
	v_mul_f32_e32 v36, v36, v37
	v_mul_f32_e32 v37, 0xbfb8aa3b, v23
	v_exp_f32_e32 v37, v37
	v_fma_f32 v22, v76, v22, v88
	v_fma_f32 v15, v101, v15, v73
	v_fmac_f32_e32 v22, v80, v28
	v_add_f32_e32 v37, 1.0, v37
	v_rcp_f32_e32 v37, v37
	v_fmac_f32_e32 v15, v93, v31
	v_fmac_f32_e32 v22, v84, v8
	v_fmac_f32_e32 v15, v97, v17
	v_mul_f32_e32 v23, v23, v37
	v_mul_f32_e32 v22, v22, v23
	v_mul_f32_e32 v23, 0xbfb8aa3b, v15
	v_exp_f32_e32 v23, v23
	v_fma_f32 v14, v77, v14, v89
	v_fmac_f32_e32 v14, v81, v29
	v_cmp_gt_i32_e32 vcc, s85, v213
	v_add_f32_e32 v23, 1.0, v23
	v_rcp_f32_e32 v23, v23
	v_fmac_f32_e32 v14, v85, v9
	s_and_b64 s[2:3], s[44:45], vcc
	v_cvt_pk_bf16_f32 v104, v38, v36
	v_mul_f32_e32 v15, v15, v23
	v_mul_f32_e32 v14, v14, v15
	v_cvt_pk_bf16_f32 v105, v22, v14
	s_and_saveexec_b64 s[0:1], s[2:3]
	s_cbranch_execz .LBB0_2306
	v_mov_b64_e32 v[14:15], s[14:15]
	v_mad_i64_i32 v[14:15], s[2:3], v213, s92, v[14:15]
	v_lshl_add_u64 v[14:15], v[178:179], 1, v[14:15]
	global_store_dwordx4 v[14:15], v[102:105], off sc0 sc1
; __device__ __forceinline__ unsigned cvt_pk_bf16(float lo, float hi) { unsigned r; asm volatile("v_cvt_pk_bf16_f32 %0, %1, %2" : "=v"(r) : "v"(lo), "v"(hi)); return r; }
;     __device__ __forceinline__ void operator()(const f32x4 (&acc)[2][2][4][2], const Unit& u, int wr, int wc, int fr, int fq) const {
;     ...
;                 for (int m = 0; m < 4; ++m) {
;                     u32x2_t w; float o[4];
; #pragma unroll
;                     for (int e = 0; e < 4; ++e) {
;                         const float g1 = m >= 1 ? xg[m - (m >= 1 ? 1 : 0)][e] : pg3[e], g2 = m >= 2 ? xg[m - (m >= 2 ? 2 : 0)][e] : (m == 1 ? pg3[e] : pg2[e]);
;                         const float v1 = m >= 1 ? xv[m - (m >= 1 ? 1 : 0)][e] : pv3[e], v2 = m >= 2 ? xv[m - (m >= 2 ? 2 : 0)][e] : (m == 1 ? pv3[e] : pv2[e]);
;                         const float cg_ = bg[e] + w0g[e] * g2 + w1g[e] * g1 + w2g[e] * xg[m][e];
;                         const float cv_ = bv[e] + w0v[e] * v2 + w1v[e] * v1 + w2v[e] * xv[m][e];
;                         o[e] = cg_ * __builtin_amdgcn_rcpf(1.0f + __expf(-cg_)) * cv_;
;                     }
;                     w.x = cvt_pk_bf16(o[0], o[1]); w.y = cvt_pk_bf16(o[2], o[3]);
;                     const int g = g0 + m;
;                     if (n == 0) stash[ai][m] = w;
;                     else if ((fr > 0 || m >= 2) && g < TT) { u32x4 ww; ww.x = stash[ai][m].x; ww.y = stash[ai][m].y; ww.z = w.x; ww.w = w.y; *(u32x4*)(G + (size_t)g * DFF_ + f0 - 4) = ww; }
.LBB0_2306:
	s_or_b64 exec, exec, s[0:1]
	v_fma_f32 v14, v98, v34, v70
	v_fmac_f32_e32 v14, v90, v24
	v_fmac_f32_e32 v14, v94, v26
	v_mul_f32_e32 v22, 0xbfb8aa3b, v14
	v_exp_f32_e32 v22, v22
	v_fma_f32 v15, v74, v32, v86
	v_fmac_f32_e32 v15, v78, v18
	v_fmac_f32_e32 v15, v82, v20
	v_add_f32_e32 v22, 1.0, v22
	v_rcp_f32_e32 v22, v22
	v_cmp_gt_i32_e32 vcc, s93, v211
	v_mul_f32_e32 v14, v14, v22
	v_mul_f32_e32 v14, v15, v14
	v_fma_f32 v15, v99, v35, v71
	v_fmac_f32_e32 v15, v91, v25
	v_fmac_f32_e32 v15, v95, v27
	v_mul_f32_e32 v23, 0xbfb8aa3b, v15
	v_exp_f32_e32 v23, v23
	v_fma_f32 v22, v75, v33, v87
	v_fmac_f32_e32 v22, v79, v19
	v_fmac_f32_e32 v22, v83, v21
	v_add_f32_e32 v23, 1.0, v23
	v_rcp_f32_e32 v23, v23
	s_nop 0
	v_mul_f32_e32 v15, v15, v23
	v_mul_f32_e32 v15, v22, v15
	v_fma_f32 v22, v100, v30, v72
	v_fmac_f32_e32 v22, v92, v16
	v_fmac_f32_e32 v22, v96, v10
	v_fma_f32 v23, v76, v28, v88
	v_mul_f32_e32 v28, 0xbfb8aa3b, v22
	v_exp_f32_e32 v28, v28
	v_fmac_f32_e32 v23, v80, v8
	v_fmac_f32_e32 v23, v84, v4
	v_cvt_pk_bf16_f32 v68, v14, v15
	v_add_f32_e32 v28, 1.0, v28
	v_rcp_f32_e32 v28, v28
	s_nop 0
	v_mul_f32_e32 v22, v22, v28
	v_mul_f32_e32 v22, v23, v22
	v_fma_f32 v23, v101, v31, v73
	v_fmac_f32_e32 v23, v93, v17
	v_fmac_f32_e32 v23, v97, v11
	v_fma_f32 v28, v77, v29, v89
	v_mul_f32_e32 v29, 0xbfb8aa3b, v23
	v_exp_f32_e32 v29, v29
	v_fmac_f32_e32 v28, v81, v9
	v_fmac_f32_e32 v28, v85, v5
	v_add_f32_e32 v29, 1.0, v29
	v_rcp_f32_e32 v29, v29
	s_nop 0
	v_mul_f32_e32 v23, v23, v29
	v_mul_f32_e32 v23, v28, v23
	v_cvt_pk_bf16_f32 v69, v22, v23
	s_and_saveexec_b64 s[0:1], vcc
	s_cbranch_execz .LBB0_2308
	v_mov_b64_e32 v[14:15], s[14:15]
	v_mad_i64_i32 v[14:15], s[2:3], v212, s92, v[14:15]
	v_lshl_add_u64 v[14:15], v[178:179], 1, v[14:15]
	global_store_dwordx4 v[14:15], v[66:69], off sc0 sc1
.LBB0_2308:
	s_or_b64 exec, exec, s[0:1]
	v_fma_f32 v14, v98, v24, v70
	v_fmac_f32_e32 v14, v90, v26
	v_fmac_f32_e32 v14, v94, v12
	v_mul_f32_e32 v12, 0xbfb8aa3b, v14
	v_exp_f32_e32 v12, v12
	v_fma_f32 v15, v74, v18, v86
	v_fma_f32 v18, v99, v25, v71
	v_fmac_f32_e32 v18, v91, v27
	v_fmac_f32_e32 v18, v95, v13
	v_add_f32_e32 v12, 1.0, v12
	v_mul_f32_e32 v13, 0xbfb8aa3b, v18
	v_rcp_f32_e32 v12, v12
	v_exp_f32_e32 v13, v13
	v_fmac_f32_e32 v15, v78, v20
	v_fmac_f32_e32 v15, v82, v6
	v_mul_f32_e32 v6, v14, v12
	v_add_f32_e32 v12, 1.0, v13
	v_rcp_f32_e32 v12, v12
	v_fma_f32 v13, v75, v19, v87
	v_fmac_f32_e32 v13, v79, v21
	v_fmac_f32_e32 v13, v83, v7
	v_mul_f32_e32 v7, v18, v12
	v_fma_f32 v12, v100, v16, v72
	v_fmac_f32_e32 v73, v101, v17
	v_fmac_f32_e32 v12, v92, v10
	v_fmac_f32_e32 v73, v93, v11
	v_fmac_f32_e32 v12, v96, v0
	v_fmac_f32_e32 v73, v97, v1
	v_mul_f32_e32 v0, 0xbfb8aa3b, v12
	v_mul_f32_e32 v1, 0xbfb8aa3b, v73
	v_exp_f32_e32 v0, v0
	v_exp_f32_e32 v1, v1
	v_fma_f32 v8, v76, v8, v88
	v_fmac_f32_e32 v89, v77, v9
	v_add_f32_e32 v0, 1.0, v0
	v_add_f32_e32 v1, 1.0, v1
	v_rcp_f32_e32 v0, v0
	v_rcp_f32_e32 v1, v1
	v_fmac_f32_e32 v8, v80, v4
	v_fmac_f32_e32 v89, v81, v5
	v_fmac_f32_e32 v8, v84, v2
	v_mul_f32_e32 v0, v12, v0
	v_fmac_f32_e32 v89, v85, v3
	v_mul_f32_e32 v1, v73, v1
	v_cmp_gt_i32_e32 vcc, s94, v211
	v_mul_f32_e32 v6, v15, v6
	v_mul_f32_e32 v7, v13, v7
	v_mul_f32_e32 v0, v8, v0
	v_mul_f32_e32 v1, v89, v1
	v_cvt_pk_bf16_f32 v66, v6, v7
	v_cvt_pk_bf16_f32 v67, v0, v1
	s_and_saveexec_b64 s[0:1], vcc
	s_cbranch_execz .LBB0_2310
	v_mov_b64_e32 v[0:1], s[14:15]
	v_mad_i64_i32 v[0:1], s[2:3], v214, s92, v[0:1]
	v_lshl_add_u64 v[0:1], v[178:179], 1, v[0:1]
	global_store_dwordx4 v[0:1], v[64:67], off sc0 sc1

; #define LAS __attribute__((address_space(3)))
; __device__ __forceinline__ unsigned cvtpk(float lo, float hi) { f32x2 v = {lo, hi}; bf16x2_t b = __builtin_convertvector(v, bf16x2_t); return __builtin_bit_cast(unsigned, b); }
; __device__ __forceinline__ void witem_store(const WItem& w, int K, bf16_t* WT, int kvperm, LAS float* scr, int item, int nblk, int lane) {
;     ...
; #pragma unroll
;     for (int i = 0; i < 8; ++i) { LAS float* d = scr + (8 * i + rr) * 33 + col; const float g = w.g[i]; d[0] = w.v[i].x * g; d[1] = w.v[i].y * g; d[2] = w.v[i].z * g; d[3] = w.v[i].w * g; }
;     asm volatile("s_waitcnt lgkmcnt(0)" ::: "memory");
;     const int c = lane & 7;
; #pragma unroll
;     for (int j = 0; j < 4; ++j) { const int n = (lane >> 3) + 8 * j; const LAS float* s = scr + (8 * c) * 33 + n;
;         u32x4 o; o.x = cvtpk(s[0 * 33], s[1 * 33]); o.y = cvtpk(s[2 * 33], s[3 * 33]); o.z = cvtpk(s[4 * 33], s[5 * 33]); o.w = cvtpk(s[6 * 33], s[7 * 33]);
;         int nr = n0 + n; if (kvperm == 1) { const int hh = nr >> 8, ww = nr & 255; nr = (ww < 128) ? hh * 128 + ww : 2048 + hh * 128 + (ww - 128); }
;         else if (kvperm == 2) { const int isv = nr >= 5632, f = isv ? nr - 5632 : nr; nr = (f >> 7) * 256 + isv * 128 + (f & 127); }
;         *(u32x4*)(WT + (size_t)nr * K + k0 + 8 * c) = o; }
;     asm volatile("s_waitcnt lgkmcnt(0)" ::: "memory");
; }
;     ...
;     while (it < i1) {
;         cur = nxt;
;         const int nit = it + NGW;
;         if (nit < i1) witem_load(nxt, W, N, gk, nit, nblk, lane);
;         witem_store(cur, K, WT, kvperm, scr, it, nblk, lane);
;         it = nit;
.LBB0_2334:
	v_pk_mul_f32 v[2:3], v[8:9], v[72:73] op_sel_hi:[1,0]
	ds_write2_b32 v79, v2, v3 offset1:1
	v_pk_mul_f32 v[2:3], v[10:11], v[72:73] op_sel_hi:[1,0]
	ds_write2_b32 v79, v2, v3 offset0:2 offset1:3
	v_pk_mul_f32 v[2:3], v[4:5], v[74:75] op_sel_hi:[1,0]
	v_add_u32_e32 v4, 0x420, v79
	ds_write2_b32 v4, v2, v3 offset1:1
	v_pk_mul_f32 v[2:3], v[6:7], v[74:75] op_sel_hi:[1,0]
	v_add_u32_e32 v4, 0x428, v79
	ds_write2_b32 v4, v2, v3 offset1:1
	v_pk_mul_f32 v[2:3], v[24:25], v[76:77] op_sel_hi:[1,0]
	v_add_u32_e32 v4, 0x840, v79
	ds_write2_b32 v4, v2, v3 offset1:1
	v_pk_mul_f32 v[2:3], v[26:27], v[76:77] op_sel_hi:[1,0]
	v_add_u32_e32 v4, 0x848, v79
	ds_write2_b32 v4, v2, v3 offset1:1
	v_pk_mul_f32 v[2:3], v[20:21], v[78:79] op_sel_hi:[1,0]
	v_add_u32_e32 v4, 0xc60, v79
	ds_write2_b32 v4, v2, v3 offset1:1
	v_pk_mul_f32 v[2:3], v[22:23], v[78:79] op_sel_hi:[1,0]
	v_add_u32_e32 v4, 0xc68, v79
	ds_write2_b32 v4, v2, v3 offset1:1
	v_pk_mul_f32 v[2:3], v[36:37], v[80:81] op_sel_hi:[1,0]
	v_add_u32_e32 v4, 0x1080, v79
	ds_write2_b32 v4, v2, v3 offset1:1
	v_pk_mul_f32 v[2:3], v[38:39], v[80:81] op_sel_hi:[1,0]
	v_add_u32_e32 v4, 0x1088, v79
	ds_write2_b32 v4, v2, v3 offset1:1
	v_pk_mul_f32 v[2:3], v[28:29], v[82:83] op_sel_hi:[1,0]
	v_add_u32_e32 v4, 0x14a0, v79
	ds_write2_b32 v4, v2, v3 offset1:1
	v_pk_mul_f32 v[2:3], v[30:31], v[82:83] op_sel_hi:[1,0]
	v_add_u32_e32 v4, 0x14a8, v79
	ds_write2_b32 v4, v2, v3 offset1:1
	s_waitcnt vmcnt(7)
	v_pk_mul_f32 v[2:3], v[48:49], v[84:85] op_sel_hi:[1,0]
	v_add_u32_e32 v4, 0x18c0, v79
	s_mul_hi_i32 s3, s3, 0x2e8ba2e9
	ds_write2_b32 v4, v2, v3 offset1:1
	v_pk_mul_f32 v[2:3], v[50:51], v[84:85] op_sel_hi:[1,0]
	v_add_u32_e32 v4, 0x18c8, v79
	s_lshr_b32 s8, s3, 31
	s_ashr_i32 s3, s3, 6
	ds_write2_b32 v4, v2, v3 offset1:1
	s_waitcnt vmcnt(6)
	v_pk_mul_f32 v[2:3], v[44:45], v[86:87] op_sel_hi:[1,0]
	v_add_u32_e32 v4, 0x1ce0, v79
	s_add_i32 s3, s3, s8
	ds_write2_b32 v4, v2, v3 offset1:1
	v_pk_mul_f32 v[2:3], v[46:47], v[86:87] op_sel_hi:[1,0]
	v_add_u32_e32 v4, 0x1ce8, v79
	s_lshl_b32 s8, s3, 6
	ds_write2_b32 v4, v2, v3 offset1:1
	s_mulk_i32 s3, 0xd400
	s_waitcnt lgkmcnt(0)
	s_add_i32 s3, s3, s6
	ds_read2_b32 v[6:7], v77 offset0:33 offset1:41
	ds_read2_b32 v[8:9], v77 offset1:8
	ds_read2_b32 v[10:11], v77 offset0:66 offset1:74
	ds_read2_b32 v[20:21], v77 offset0:99 offset1:107
	ds_read2_b32 v[22:23], v77 offset0:132 offset1:140
	ds_read2_b32 v[24:25], v77 offset0:165 offset1:173
	ds_read2_b32 v[26:27], v77 offset0:198 offset1:206
	ds_read2_b32 v[28:29], v77 offset0:231 offset1:239
	v_add_u32_e32 v38, s3, v83
	s_waitcnt lgkmcnt(6)
	v_cvt_pk_bf16_f32 v2, v8, v6
	v_add_u32_e32 v6, 0xffffea00, v38
	v_cmp_lt_i32_e32 vcc, s12, v38
	s_waitcnt lgkmcnt(4)
	v_cvt_pk_bf16_f32 v3, v10, v20
	s_ashr_i32 s9, s8, 31
	v_cndmask_b32_e32 v6, v38, v6, vcc
	v_lshlrev_b32_e32 v8, 1, v6
	v_and_b32_e32 v8, 0xffffff00, v8
	v_cndmask_b32_e32 v10, 0, v81, vcc
	v_and_b32_e32 v6, 0x67, v6
	v_or3_b32 v36, v6, v10, v8
	v_ashrrev_i32_e32 v37, 31, v36
	v_lshl_add_u64 v[30:31], s[8:9], 1, v[70:71]
	v_lshlrev_b64 v[36:37], 12, v[36:37]
	s_waitcnt lgkmcnt(2)
	v_cvt_pk_bf16_f32 v4, v22, v24
	s_waitcnt lgkmcnt(0)
	v_cvt_pk_bf16_f32 v5, v26, v28
	v_lshl_add_u64 v[36:37], v[30:31], 0, v[36:37]
	v_add_u32_e32 v6, 8, v38
	global_store_dwordx4 v[36:37], v[2:5], off sc0 sc1
	v_cmp_lt_i32_e32 vcc, s12, v6
	s_waitcnt vmcnt(3)
	v_mov_b64_e32 v[48:49], v[60:61]
	v_cvt_pk_bf16_f32 v2, v9, v7
	v_add_u32_e32 v7, 0xffffea08, v38
	v_cndmask_b32_e32 v6, v6, v7, vcc
	v_lshlrev_b32_e32 v7, 1, v6
	v_and_b32_e32 v7, 0xffffff00, v7
	v_cndmask_b32_e32 v8, 0, v81, vcc
	v_and_b32_e32 v6, 0x6f, v6
	v_or3_b32 v6, v6, v8, v7
	v_ashrrev_i32_e32 v7, 31, v6
	v_lshlrev_b64 v[6:7], 12, v[6:7]
	v_cvt_pk_bf16_f32 v3, v11, v21
	v_cvt_pk_bf16_f32 v4, v23, v25
	v_cvt_pk_bf16_f32 v5, v27, v29
	v_lshl_add_u64 v[6:7], v[30:31], 0, v[6:7]
	ds_read2_b32 v[8:9], v77 offset0:16 offset1:24
	ds_read2_b32 v[10:11], v77 offset0:49 offset1:57
	ds_read2_b32 v[20:21], v77 offset0:82 offset1:90
	ds_read2_b32 v[22:23], v77 offset0:115 offset1:123
	ds_read2_b32 v[24:25], v77 offset0:148 offset1:156
	ds_read2_b32 v[26:27], v77 offset0:181 offset1:189
	ds_read2_b32 v[28:29], v77 offset0:214 offset1:222
	ds_read2_b32 v[36:37], v77 offset0:247 offset1:255
	global_store_dwordx4 v[6:7], v[2:5], off sc0 sc1
	v_add_u32_e32 v6, 16, v38
	v_add_u32_e32 v7, 0xffffea10, v38
	v_cmp_lt_i32_e32 vcc, s12, v6
	s_waitcnt lgkmcnt(6)
	v_cvt_pk_bf16_f32 v2, v8, v10
	s_waitcnt lgkmcnt(4)
	v_cvt_pk_bf16_f32 v3, v20, v22
	v_cndmask_b32_e32 v6, v6, v7, vcc
	v_lshlrev_b32_e32 v7, 1, v6
	v_and_b32_e32 v7, 0xffffff00, v7
	v_cndmask_b32_e32 v8, 0, v81, vcc
	v_and_b32_e32 v6, 0x77, v6
	v_or3_b32 v6, v6, v8, v7
	v_ashrrev_i32_e32 v7, 31, v6
	v_lshlrev_b64 v[6:7], 12, v[6:7]
	s_waitcnt lgkmcnt(2)
	v_cvt_pk_bf16_f32 v4, v24, v26
	s_waitcnt lgkmcnt(0)
	v_cvt_pk_bf16_f32 v5, v28, v36
	v_lshl_add_u64 v[6:7], v[30:31], 0, v[6:7]
	global_store_dwordx4 v[6:7], v[2:5], off sc0 sc1
	s_waitcnt vmcnt(4)
	v_mov_b64_e32 v[44:45], v[64:65]
	v_add_u32_e32 v83, s7, v83
	v_add_u32_e32 v2, 24, v38
	v_add_u32_e32 v3, 0xffffea18, v38
	v_cmp_lt_i32_e32 vcc, s12, v2
	v_cvt_pk_bf16_f32 v5, v29, v37
	v_mov_b64_e32 v[36:37], v[52:53]
	v_cndmask_b32_e32 v2, v2, v3, vcc
	v_lshlrev_b32_e32 v3, 1, v2
	v_and_b32_e32 v3, 0xffffff00, v3
	v_cndmask_b32_e32 v4, 0, v81, vcc
	v_and_b32_e32 v2, 0x7f, v2
	v_or3_b32 v6, v2, v4, v3
	v_ashrrev_i32_e32 v7, 31, v6
	v_lshlrev_b64 v[6:7], 12, v[6:7]
	v_cvt_pk_bf16_f32 v2, v9, v11
	v_cvt_pk_bf16_f32 v3, v21, v23
	v_cvt_pk_bf16_f32 v4, v25, v27
	v_lshl_add_u64 v[6:7], v[30:31], 0, v[6:7]
	global_store_dwordx4 v[6:7], v[2:5], off sc0 sc1
	s_waitcnt lgkmcnt(0)
	v_mov_b64_e32 v[8:9], v[16:17]
	v_mov_b64_e32 v[24:25], v[32:33]
	v_mov_b64_e32 v[4:5], v[12:13]
	v_mov_b64_e32 v[20:21], v[40:41]
	v_mov_b64_e32 v[28:29], v[56:57]
	s_add_i32 s13, s13, s7
	v_add_u32_e32 v73, s7, v73
	s_andn2_b64 vcc, exec, s[4:5]
	s_mov_b32 s3, s14
	v_mov_b64_e32 v[10:11], v[18:19]
	v_mov_b64_e32 v[6:7], v[14:15]
	v_mov_b64_e32 v[26:27], v[34:35]
	v_mov_b64_e32 v[22:23], v[42:43]
	v_mov_b64_e32 v[38:39], v[54:55]
	v_mov_b64_e32 v[30:31], v[58:59]
	v_mov_b64_e32 v[50:51], v[62:63]
	v_mov_b64_e32 v[46:47], v[66:67]
	v_mov_b32_e32 v72, v85
	v_mov_b32_e32 v74, v87
	v_mov_b32_e32 v76, v89
	v_mov_b32_e32 v78, v94
	v_mov_b32_e32 v80, v95
	v_mov_b32_e32 v82, v96
	v_mov_b32_e32 v84, v97
	s_waitcnt vmcnt(4)
	v_mov_b32_e32 v86, v1
	s_cbranch_vccz .LBB0_2352

; __device__ __forceinline__ unsigned cvt_pk_bf16(float lo, float hi) { unsigned r; asm volatile("v_cvt_pk_bf16_f32 %0, %1, %2" : "=v"(r) : "v"(lo), "v"(hi)); return r; }
;     __device__ __forceinline__ void operator()(const f32x4 (&acc)[2][2][4][2], const Unit& u, int wr, int wc, int fr, int fq) const {
;         const int row0 = u.pm * BM + wr * 64 + fr, col0 = u.pn * BM + wc * 32 + 8 * fq;
;         f32x4 bv[2][2];
; #pragma unroll
;         for (int bj = 0; bj < 2; ++bj)
; #pragma unroll
;             for (int n = 0; n < 2; ++n) bv[bj][n] = bias ? *(const f32x4*)(bias + col0 + bj * HALF + 4 * n) : (f32x4){0.f, 0.f, 0.f, 0.f};
;         float* ssp = ssout + (size_t)(u.pn * 4 + wc);
; #pragma unroll
;         for (int ai = 0; ai < 2; ++ai) {
;             u32x4 old[4][2];
; #pragma unroll
;             for (int m = 0; m < 4; ++m)
; #pragma unroll
;                 for (int bj = 0; bj < 2; ++bj) old[m][bj] = *(const u32x4*)(HB + (size_t)(row0 + ai * HALF + m * 16) * ldc + col0 + bj * HALF);
; #pragma unroll
;             for (int m = 0; m < 4; ++m) { const int row = row0 + ai * HALF + m * 16; float ss = 0.f;
; #pragma unroll
;                 for (int bj = 0; bj < 2; ++bj) { const u32x4 ow = old[m][bj];
;                     f32x4 v0 = (acc[ai][bj][m][0] + bv[bj][0]) * accs, v1 = (acc[ai][bj][m][1] + bv[bj][1]) * accs;
;                     v0[0] += __uint_as_float(ow.x << 16); v0[1] += __uint_as_float(ow.x & 0xffff0000u); v0[2] += __uint_as_float(ow.y << 16); v0[3] += __uint_as_float(ow.y & 0xffff0000u);
;                     v1[0] += __uint_as_float(ow.z << 16); v1[1] += __uint_as_float(ow.z & 0xffff0000u); v1[2] += __uint_as_float(ow.w << 16); v1[3] += __uint_as_float(ow.w & 0xffff0000u);
;                     ss += (v0[0] * v0[0] + v0[1] * v0[1]) + (v0[2] * v0[2] + v0[3] * v0[3]) + (v1[0] * v1[0] + v1[1] * v1[1]) + (v1[2] * v1[2] + v1[3] * v1[3]);
;                     u32x4 w; w.x = cvt_pk_bf16(v0[0], v0[1]); w.y = cvt_pk_bf16(v0[2], v0[3]); w.z = cvt_pk_bf16(v1[0], v1[1]); w.w = cvt_pk_bf16(v1[2], v1[3]);
;                     *(u32x4*)(HB + (size_t)row * ldc + col0 + bj * HALF) = w; }
;                 ss += __shfl_xor(ss, 16); ss += __shfl_xor(ss, 32);
;                 if (fq == 0) ssp[(size_t)row * 32] = ss; }
.LBB0_2430:
	v_lshl_or_b32 v152, s6, 8, v166
	v_ashrrev_i32_e32 v153, 31, v152
	v_lshl_add_u32 v156, s7, 8, v164
	v_lshlrev_b64 v[178:179], 1, v[152:153]
	v_ashrrev_i32_e32 v157, 31, v156
	v_lshl_add_u64 v[154:155], s[8:9], 0, v[178:179]
	v_lshlrev_b64 v[180:181], 12, v[156:157]
	v_lshl_add_u64 v[128:129], v[154:155], 0, v[180:181]
	global_load_dwordx4 v[170:173], v[128:129], off
	global_load_dwordx4 v[174:177], v[128:129], off offset:256
	v_or_b32_e32 v162, 16, v156
	v_or_b32_e32 v160, 32, v156
	v_or_b32_e32 v158, 48, v156
	v_ashrrev_i32_e32 v163, 31, v162
	v_ashrrev_i32_e32 v161, 31, v160
	v_pk_add_f32 v[194:195], v[114:115], 0 op_sel_hi:[1,0]
	v_pk_add_f32 v[196:197], v[112:113], 0 op_sel_hi:[1,0]
	v_ashrrev_i32_e32 v159, 31, v158
	v_lshlrev_b64 v[112:113], 12, v[162:163]
	v_lshlrev_b64 v[114:115], 12, v[160:161]
	v_pk_add_f32 v[192:193], v[116:117], 0 op_sel_hi:[1,0]
	v_lshlrev_b64 v[116:117], 12, v[158:159]
	v_lshl_add_u64 v[112:113], v[154:155], 0, v[112:113]
	v_lshl_add_u64 v[114:115], v[154:155], 0, v[114:115]
	v_pk_add_f32 v[182:183], v[126:127], 0 op_sel_hi:[1,0]
	v_pk_add_f32 v[184:185], v[124:125], 0 op_sel_hi:[1,0]
	v_pk_add_f32 v[186:187], v[122:123], 0 op_sel_hi:[1,0]
	v_pk_add_f32 v[188:189], v[120:121], 0 op_sel_hi:[1,0]
	v_pk_add_f32 v[190:191], v[118:119], 0 op_sel_hi:[1,0]
	v_lshl_add_u64 v[198:199], v[154:155], 0, v[116:117]
	global_load_dwordx4 v[132:135], v[112:113], off
	global_load_dwordx4 v[128:131], v[112:113], off offset:256
	global_load_dwordx4 v[124:127], v[114:115], off
	global_load_dwordx4 v[120:123], v[114:115], off offset:256
	global_load_dwordx4 v[116:119], v[198:199], off
	s_nop 0
	global_load_dwordx4 v[112:115], v[198:199], off offset:256
	s_lshl_b32 s6, s6, 2
	s_or_b32 s6, s6, s50
	s_ashr_i32 s7, s6, 31
	s_lshl_b64 s[6:7], s[6:7], 2
	s_add_u32 s16, s36, s6
	s_addc_u32 s17, s37, s7
	s_waitcnt vmcnt(0)
	v_lshlrev_b32_e32 v198, 16, v170
	v_and_b32_e32 v170, 0xffff0000, v170
	v_lshlrev_b32_e32 v199, 16, v171
	v_and_b32_e32 v171, 0xffff0000, v171
	v_lshlrev_b32_e32 v200, 16, v172
	v_and_b32_e32 v172, 0xffff0000, v172
	v_lshlrev_b32_e32 v203, 16, v174
	v_and_b32_e32 v174, 0xffff0000, v174
	v_lshlrev_b32_e32 v205, 16, v175
	v_and_b32_e32 v175, 0xffff0000, v175
	v_lshlrev_b32_e32 v201, 16, v173
	v_and_b32_e32 v173, 0xffff0000, v173
	v_lshlrev_b32_e32 v206, 16, v176
	v_and_b32_e32 v176, 0xffff0000, v176
	v_lshlrev_b32_e32 v207, 16, v177
	v_and_b32_e32 v177, 0xffff0000, v177
	v_add_f32_e32 v170, v185, v170
	v_add_f32_e32 v171, v183, v171
	v_add_f32_e32 v185, v189, v172
	v_add_f32_e32 v189, v193, v174
	v_add_f32_e32 v191, v191, v175
	v_add_f32_e32 v184, v184, v198
	v_add_f32_e32 v182, v182, v199
	v_add_f32_e32 v183, v188, v200
	v_add_f32_e32 v187, v187, v173
	v_add_f32_e32 v188, v192, v203
	v_add_f32_e32 v190, v190, v205
	v_add_f32_e32 v193, v197, v176
	v_add_f32_e32 v195, v195, v177
	v_mul_f32_e32 v176, v170, v170
	v_mul_f32_e32 v177, v171, v171
	v_cvt_pk_bf16_f32 v172, v184, v170
	v_cvt_pk_bf16_f32 v173, v182, v171
	v_mul_f32_e32 v170, v189, v189
	v_mul_f32_e32 v171, v191, v191
	v_fmac_f32_e32 v170, v188, v188
	v_fmac_f32_e32 v171, v190, v190
	v_add_f32_e32 v192, v196, v206
	v_add_f32_e32 v170, v170, v171
	v_mul_f32_e32 v171, v193, v193
	v_mul_f32_e32 v196, v185, v185
	v_fmac_f32_e32 v176, v184, v184
	v_fmac_f32_e32 v177, v182, v182
	v_fmac_f32_e32 v171, v192, v192
	v_add_f32_e32 v186, v186, v201
	v_add_f32_e32 v194, v194, v207
	v_mul_f32_e32 v197, v187, v187
	v_fmac_f32_e32 v196, v183, v183
	v_add_f32_e32 v176, v176, v177
	v_add_f32_e32 v170, v171, v170
	v_mul_f32_e32 v171, v195, v195
	v_fmac_f32_e32 v197, v186, v186
	v_add_f32_e32 v176, v196, v176
	v_fmac_f32_e32 v171, v194, v194
	v_add_f32_e32 v176, v197, v176
	v_add_f32_e32 v170, v171, v170
	v_add_f32_e32 v171, v176, v170
	v_and_b32_e32 v176, 64, v202
	v_xor_b32_e32 v170, 16, v202
	v_add_u32_e32 v182, 64, v176
	v_cmp_lt_i32_e32 vcc, v170, v182
	v_cvt_pk_bf16_f32 v174, v183, v185
	v_lshl_add_u64 v[176:177], s[8:9], 0, v[180:181]
	v_lshl_add_u64 v[178:179], v[176:177], 0, v[178:179]
	v_cndmask_b32_e32 v170, v202, v170, vcc
	v_lshlrev_b32_e32 v170, 2, v170
	ds_bpermute_b32 v183, v170, v171
	v_cvt_pk_bf16_f32 v175, v186, v187
	global_store_dwordx4 v[178:179], v[172:175], off sc0 sc1
	s_waitcnt lgkmcnt(0)
	s_nop 0
	v_add_f32_e32 v172, v171, v183
	v_xor_b32_e32 v171, 32, v202
	v_cmp_lt_i32_e32 vcc, v171, v182
	v_cvt_pk_bf16_f32 v174, v188, v189
	v_cvt_pk_bf16_f32 v175, v190, v191
	v_cvt_pk_bf16_f32 v176, v192, v193
	v_cvt_pk_bf16_f32 v177, v194, v195
	global_store_dwordx4 v[178:179], v[174:177], off offset:256 sc0 sc1
	s_nop 0
	v_cndmask_b32_e32 v171, v202, v171, vcc
	v_lshlrev_b32_e32 v171, 2, v171
	ds_bpermute_b32 v173, v171, v172
	s_and_saveexec_b64 s[18:19], s[44:45]
	s_cbranch_execz .LBB0_2432
	v_lshlrev_b64 v[174:175], 7, v[156:157]
	v_lshl_add_u64 v[174:175], s[16:17], 0, v[174:175]
	s_waitcnt lgkmcnt(0)
	v_add_f32_e32 v157, v172, v173
	global_store_dword v[174:175], v157, off
; __device__ __forceinline__ unsigned cvt_pk_bf16(float lo, float hi) { unsigned r; asm volatile("v_cvt_pk_bf16_f32 %0, %1, %2" : "=v"(r) : "v"(lo), "v"(hi)); return r; }
;     __device__ __forceinline__ void operator()(const f32x4 (&acc)[2][2][4][2], const Unit& u, int wr, int wc, int fr, int fq) const {
;     ...
;             for (int m = 0; m < 4; ++m) { const int row = row0 + ai * HALF + m * 16; float ss = 0.f;
; #pragma unroll
;                 for (int bj = 0; bj < 2; ++bj) { const u32x4 ow = old[m][bj];
;                     f32x4 v0 = (acc[ai][bj][m][0] + bv[bj][0]) * accs, v1 = (acc[ai][bj][m][1] + bv[bj][1]) * accs;
;                     v0[0] += __uint_as_float(ow.x << 16); v0[1] += __uint_as_float(ow.x & 0xffff0000u); v0[2] += __uint_as_float(ow.y << 16); v0[3] += __uint_as_float(ow.y & 0xffff0000u);
;                     v1[0] += __uint_as_float(ow.z << 16); v1[1] += __uint_as_float(ow.z & 0xffff0000u); v1[2] += __uint_as_float(ow.w << 16); v1[3] += __uint_as_float(ow.w & 0xffff0000u);
;                     ss += (v0[0] * v0[0] + v0[1] * v0[1]) + (v0[2] * v0[2] + v0[3] * v0[3]) + (v1[0] * v1[0] + v1[1] * v1[1]) + (v1[2] * v1[2] + v1[3] * v1[3]);
;                     u32x4 w; w.x = cvt_pk_bf16(v0[0], v0[1]); w.y = cvt_pk_bf16(v0[2], v0[3]); w.z = cvt_pk_bf16(v1[0], v1[1]); w.w = cvt_pk_bf16(v1[2], v1[3]);
;                     *(u32x4*)(HB + (size_t)row * ldc + col0 + bj * HALF) = w; }
;                 ss += __shfl_xor(ss, 16); ss += __shfl_xor(ss, 32);
;                 if (fq == 0) ssp[(size_t)row * 32] = ss; }
.LBB0_2432:
	s_or_b64 exec, exec, s[18:19]
	v_pk_add_f32 v[108:109], v[108:109], 0 op_sel_hi:[1,0]
	v_lshlrev_b32_e32 v157, 16, v132
	v_and_b32_e32 v132, 0xffff0000, v132
	v_pk_add_f32 v[110:111], v[110:111], 0 op_sel_hi:[1,0]
	v_add_f32_e32 v109, v109, v132
	v_lshlrev_b32_e32 v132, 16, v133
	v_add_f32_e32 v110, v110, v132
	v_and_b32_e32 v132, 0xffff0000, v133
	v_pk_add_f32 v[104:105], v[104:105], 0 op_sel_hi:[1,0]
	v_add_f32_e32 v111, v111, v132
	v_lshlrev_b32_e32 v132, 16, v134
	v_add_f32_e32 v132, v104, v132
	v_and_b32_e32 v104, 0xffff0000, v134
	v_pk_add_f32 v[106:107], v[106:107], 0 op_sel_hi:[1,0]
	v_add_f32_e32 v133, v105, v104
	v_lshlrev_b32_e32 v104, 16, v135
	v_add_f32_e32 v134, v106, v104
	v_and_b32_e32 v104, 0xffff0000, v135
	v_add_f32_e32 v108, v108, v157
	v_add_f32_e32 v107, v107, v104
	v_mul_f32_e32 v104, v109, v109
	v_mul_f32_e32 v105, v111, v111
	v_fmac_f32_e32 v104, v108, v108
	v_fmac_f32_e32 v105, v110, v110
	v_add_f32_e32 v104, v104, v105
	v_mul_f32_e32 v105, v133, v133
	v_fmac_f32_e32 v105, v132, v132
	v_add_f32_e32 v104, v105, v104
	v_mul_f32_e32 v105, v107, v107
	v_fmac_f32_e32 v105, v134, v134
	v_add_f32_e32 v135, v105, v104
	v_cvt_pk_bf16_f32 v104, v108, v109
	v_pk_add_f32 v[100:101], v[100:101], 0 op_sel_hi:[1,0]
	v_lshlrev_b32_e32 v108, 16, v128
	v_add_f32_e32 v100, v100, v108
	v_and_b32_e32 v108, 0xffff0000, v128
	v_pk_add_f32 v[102:103], v[102:103], 0 op_sel_hi:[1,0]
	v_add_f32_e32 v101, v101, v108
	v_lshlrev_b32_e32 v108, 16, v129
	v_add_f32_e32 v108, v102, v108
	v_and_b32_e32 v102, 0xffff0000, v129
	v_pk_add_f32 v[96:97], v[96:97], 0 op_sel_hi:[1,0]
	v_add_f32_e32 v109, v103, v102
	v_lshlrev_b32_e32 v102, 16, v130
	v_cvt_pk_bf16_f32 v105, v110, v111
	v_add_f32_e32 v110, v96, v102
	v_and_b32_e32 v96, 0xffff0000, v130
	v_pk_add_f32 v[98:99], v[98:99], 0 op_sel_hi:[1,0]
	v_add_f32_e32 v111, v97, v96
	v_lshlrev_b32_e32 v96, 16, v131
	v_add_f32_e32 v128, v98, v96
	v_and_b32_e32 v96, 0xffff0000, v131
	v_add_f32_e32 v129, v99, v96
	v_mul_f32_e32 v96, v101, v101
	v_mul_f32_e32 v97, v109, v109
	v_fmac_f32_e32 v96, v100, v100
	v_fmac_f32_e32 v97, v108, v108
	v_add_f32_e32 v96, v96, v97
	v_mul_f32_e32 v97, v111, v111
	v_fmac_f32_e32 v97, v110, v110
	v_add_f32_e32 v96, v97, v96
	v_mul_f32_e32 v97, v129, v129
	v_fmac_f32_e32 v97, v128, v128
	v_add_f32_e32 v96, v97, v96
	v_add_f32_e32 v99, v135, v96
	ds_bpermute_b32 v130, v170, v99
	s_waitcnt lgkmcnt(1)
	v_lshlrev_b64 v[172:173], 11, v[162:163]
	v_lshl_add_u64 v[96:97], v[172:173], 1, s[8:9]
	v_lshl_add_u64 v[102:103], v[152:153], 1, v[96:97]
	v_cvt_pk_bf16_f32 v106, v132, v133
	s_waitcnt lgkmcnt(0)
	v_add_f32_e32 v96, v99, v130
	ds_bpermute_b32 v97, v171, v96
	v_cvt_pk_bf16_f32 v107, v134, v107
	global_store_dwordx4 v[102:103], v[104:107], off sc0 sc1
	v_cvt_pk_bf16_f32 v98, v100, v101
	v_cvt_pk_bf16_f32 v99, v108, v109
	v_cvt_pk_bf16_f32 v100, v110, v111
	v_cvt_pk_bf16_f32 v101, v128, v129
	global_store_dwordx4 v[102:103], v[98:101], off offset:256 sc0 sc1
	s_and_saveexec_b64 s[18:19], s[44:45]
	s_cbranch_execz .LBB0_2434
	v_lshlrev_b64 v[98:99], 7, v[162:163]
	v_lshl_add_u64 v[98:99], s[16:17], 0, v[98:99]
	s_waitcnt lgkmcnt(0)
	v_add_f32_e32 v96, v96, v97
	global_store_dword v[98:99], v96, off
.LBB0_2434:
	s_or_b64 exec, exec, s[18:19]
	v_pk_add_f32 v[92:93], v[92:93], 0 op_sel_hi:[1,0]
	v_lshlrev_b32_e32 v98, 16, v124
	v_add_f32_e32 v92, v92, v98
	v_and_b32_e32 v98, 0xffff0000, v124
	v_pk_add_f32 v[94:95], v[94:95], 0 op_sel_hi:[1,0]
	v_add_f32_e32 v93, v93, v98
	v_lshlrev_b32_e32 v98, 16, v125
	v_add_f32_e32 v94, v94, v98
	v_and_b32_e32 v98, 0xffff0000, v125
	v_pk_add_f32 v[88:89], v[88:89], 0 op_sel_hi:[1,0]
	v_add_f32_e32 v95, v95, v98
	v_lshlrev_b32_e32 v98, 16, v126
	v_add_f32_e32 v98, v88, v98
	v_and_b32_e32 v88, 0xffff0000, v126
	v_pk_add_f32 v[90:91], v[90:91], 0 op_sel_hi:[1,0]
	v_add_f32_e32 v99, v89, v88
	v_lshlrev_b32_e32 v88, 16, v127
	v_add_f32_e32 v100, v90, v88
	v_and_b32_e32 v88, 0xffff0000, v127
	v_add_f32_e32 v91, v91, v88
	v_mul_f32_e32 v88, v93, v93
	v_mul_f32_e32 v89, v95, v95
	v_fmac_f32_e32 v88, v92, v92
	v_fmac_f32_e32 v89, v94, v94
	v_add_f32_e32 v88, v88, v89
	v_mul_f32_e32 v89, v99, v99
	v_fmac_f32_e32 v89, v98, v98
	v_add_f32_e32 v88, v89, v88
	v_mul_f32_e32 v89, v91, v91
	v_fmac_f32_e32 v89, v100, v100
	v_add_f32_e32 v101, v89, v88
	v_cvt_pk_bf16_f32 v88, v92, v93
	v_pk_add_f32 v[84:85], v[84:85], 0 op_sel_hi:[1,0]
	v_lshlrev_b32_e32 v92, 16, v120
	v_add_f32_e32 v84, v84, v92
	v_and_b32_e32 v92, 0xffff0000, v120
	v_pk_add_f32 v[86:87], v[86:87], 0 op_sel_hi:[1,0]
	v_add_f32_e32 v85, v85, v92
	v_lshlrev_b32_e32 v92, 16, v121
	v_add_f32_e32 v92, v86, v92
	v_and_b32_e32 v86, 0xffff0000, v121
	v_pk_add_f32 v[80:81], v[80:81], 0 op_sel_hi:[1,0]
	v_add_f32_e32 v93, v87, v86
	v_lshlrev_b32_e32 v86, 16, v122
	v_cvt_pk_bf16_f32 v89, v94, v95
	v_add_f32_e32 v94, v80, v86
	v_and_b32_e32 v80, 0xffff0000, v122
	v_pk_add_f32 v[82:83], v[82:83], 0 op_sel_hi:[1,0]
	v_add_f32_e32 v95, v81, v80
	v_lshlrev_b32_e32 v80, 16, v123
	v_cvt_pk_bf16_f32 v90, v98, v99
	v_add_f32_e32 v98, v82, v80
	v_and_b32_e32 v80, 0xffff0000, v123
	v_add_f32_e32 v99, v83, v80
	v_mul_f32_e32 v80, v85, v85
	v_mul_f32_e32 v81, v93, v93
	v_fmac_f32_e32 v80, v84, v84
	v_fmac_f32_e32 v81, v92, v92
	v_add_f32_e32 v80, v80, v81
	v_mul_f32_e32 v81, v95, v95
	v_fmac_f32_e32 v81, v94, v94
	v_add_f32_e32 v80, v81, v80
	v_mul_f32_e32 v81, v99, v99
	v_fmac_f32_e32 v81, v98, v98
	v_add_f32_e32 v80, v81, v80
	v_add_f32_e32 v83, v101, v80
	v_cvt_pk_bf16_f32 v91, v100, v91
	ds_bpermute_b32 v100, v170, v83
	s_waitcnt lgkmcnt(1)
	v_lshlrev_b64 v[96:97], 11, v[160:161]
	v_lshl_add_u64 v[80:81], v[96:97], 1, s[8:9]
	v_lshl_add_u64 v[86:87], v[152:153], 1, v[80:81]
	global_store_dwordx4 v[86:87], v[88:91], off sc0 sc1
	s_waitcnt lgkmcnt(0)
	v_add_f32_e32 v80, v83, v100
	ds_bpermute_b32 v81, v171, v80
	v_cvt_pk_bf16_f32 v82, v84, v85
	v_cvt_pk_bf16_f32 v83, v92, v93
	v_cvt_pk_bf16_f32 v84, v94, v95
	v_cvt_pk_bf16_f32 v85, v98, v99
	global_store_dwordx4 v[86:87], v[82:85], off offset:256 sc0 sc1
	s_and_saveexec_b64 s[18:19], s[44:45]
	s_cbranch_execz .LBB0_2436
	v_lshlrev_b64 v[82:83], 7, v[160:161]
	v_lshl_add_u64 v[82:83], s[16:17], 0, v[82:83]
	s_waitcnt lgkmcnt(0)
	v_add_f32_e32 v80, v80, v81
	global_store_dword v[82:83], v80, off
; __device__ __forceinline__ unsigned cvt_pk_bf16(float lo, float hi) { unsigned r; asm volatile("v_cvt_pk_bf16_f32 %0, %1, %2" : "=v"(r) : "v"(lo), "v"(hi)); return r; }
;     __device__ __forceinline__ void operator()(const f32x4 (&acc)[2][2][4][2], const Unit& u, int wr, int wc, int fr, int fq) const {
;     ...
;         for (int ai = 0; ai < 2; ++ai) {
;             u32x4 old[4][2];
; #pragma unroll
;             for (int m = 0; m < 4; ++m)
; #pragma unroll
;                 for (int bj = 0; bj < 2; ++bj) old[m][bj] = *(const u32x4*)(HB + (size_t)(row0 + ai * HALF + m * 16) * ldc + col0 + bj * HALF);
; #pragma unroll
;             for (int m = 0; m < 4; ++m) { const int row = row0 + ai * HALF + m * 16; float ss = 0.f;
; #pragma unroll
;                 for (int bj = 0; bj < 2; ++bj) { const u32x4 ow = old[m][bj];
;                     f32x4 v0 = (acc[ai][bj][m][0] + bv[bj][0]) * accs, v1 = (acc[ai][bj][m][1] + bv[bj][1]) * accs;
;                     v0[0] += __uint_as_float(ow.x << 16); v0[1] += __uint_as_float(ow.x & 0xffff0000u); v0[2] += __uint_as_float(ow.y << 16); v0[3] += __uint_as_float(ow.y & 0xffff0000u);
;                     v1[0] += __uint_as_float(ow.z << 16); v1[1] += __uint_as_float(ow.z & 0xffff0000u); v1[2] += __uint_as_float(ow.w << 16); v1[3] += __uint_as_float(ow.w & 0xffff0000u);
;                     ss += (v0[0] * v0[0] + v0[1] * v0[1]) + (v0[2] * v0[2] + v0[3] * v0[3]) + (v1[0] * v1[0] + v1[1] * v1[1]) + (v1[2] * v1[2] + v1[3] * v1[3]);
;                     u32x4 w; w.x = cvt_pk_bf16(v0[0], v0[1]); w.y = cvt_pk_bf16(v0[2], v0[3]); w.z = cvt_pk_bf16(v1[0], v1[1]); w.w = cvt_pk_bf16(v1[2], v1[3]);
;                     *(u32x4*)(HB + (size_t)row * ldc + col0 + bj * HALF) = w; }
;                 ss += __shfl_xor(ss, 16); ss += __shfl_xor(ss, 32);
;                 if (fq == 0) ssp[(size_t)row * 32] = ss; }
.LBB0_2436:
	s_or_b64 exec, exec, s[18:19]
	v_pk_add_f32 v[76:77], v[76:77], 0 op_sel_hi:[1,0]
	v_lshlrev_b32_e32 v82, 16, v116
	v_add_f32_e32 v76, v76, v82
	v_and_b32_e32 v82, 0xffff0000, v116
	v_pk_add_f32 v[78:79], v[78:79], 0 op_sel_hi:[1,0]
	v_add_f32_e32 v77, v77, v82
	v_lshlrev_b32_e32 v82, 16, v117
	v_add_f32_e32 v78, v78, v82
	v_and_b32_e32 v82, 0xffff0000, v117
	v_pk_add_f32 v[72:73], v[72:73], 0 op_sel_hi:[1,0]
	v_add_f32_e32 v79, v79, v82
	v_lshlrev_b32_e32 v82, 16, v118
	v_add_f32_e32 v82, v72, v82
	v_and_b32_e32 v72, 0xffff0000, v118
	v_pk_add_f32 v[74:75], v[74:75], 0 op_sel_hi:[1,0]
	v_add_f32_e32 v83, v73, v72
	v_lshlrev_b32_e32 v72, 16, v119
	v_add_f32_e32 v84, v74, v72
	v_and_b32_e32 v72, 0xffff0000, v119
	v_add_f32_e32 v75, v75, v72
	v_mul_f32_e32 v72, v77, v77
	v_mul_f32_e32 v73, v79, v79
	v_fmac_f32_e32 v72, v76, v76
	v_fmac_f32_e32 v73, v78, v78
	v_add_f32_e32 v72, v72, v73
	v_mul_f32_e32 v73, v83, v83
	v_fmac_f32_e32 v73, v82, v82
	v_add_f32_e32 v72, v73, v72
	v_mul_f32_e32 v73, v75, v75
	v_fmac_f32_e32 v73, v84, v84
	v_add_f32_e32 v85, v73, v72
	v_cvt_pk_bf16_f32 v72, v76, v77
	v_pk_add_f32 v[68:69], v[68:69], 0 op_sel_hi:[1,0]
	v_lshlrev_b32_e32 v76, 16, v112
	v_add_f32_e32 v68, v68, v76
	v_and_b32_e32 v76, 0xffff0000, v112
	v_pk_add_f32 v[70:71], v[70:71], 0 op_sel_hi:[1,0]
	v_add_f32_e32 v69, v69, v76
	v_lshlrev_b32_e32 v76, 16, v113
	v_add_f32_e32 v76, v70, v76
	v_and_b32_e32 v70, 0xffff0000, v113
	v_pk_add_f32 v[64:65], v[64:65], 0 op_sel_hi:[1,0]
	v_add_f32_e32 v77, v71, v70
	v_lshlrev_b32_e32 v70, 16, v114
	v_cvt_pk_bf16_f32 v73, v78, v79
	v_add_f32_e32 v78, v64, v70
	v_and_b32_e32 v64, 0xffff0000, v114
	v_pk_add_f32 v[66:67], v[66:67], 0 op_sel_hi:[1,0]
	v_add_f32_e32 v79, v65, v64
	v_lshlrev_b32_e32 v64, 16, v115
	v_cvt_pk_bf16_f32 v74, v82, v83
	v_add_f32_e32 v82, v66, v64
	v_and_b32_e32 v64, 0xffff0000, v115
	v_add_f32_e32 v83, v67, v64
	v_mul_f32_e32 v64, v69, v69
	v_mul_f32_e32 v65, v77, v77
	v_fmac_f32_e32 v64, v68, v68
	v_fmac_f32_e32 v65, v76, v76
	v_add_f32_e32 v64, v64, v65
	v_mul_f32_e32 v65, v79, v79
	v_fmac_f32_e32 v65, v78, v78
	v_add_f32_e32 v64, v65, v64
	v_mul_f32_e32 v65, v83, v83
	v_fmac_f32_e32 v65, v82, v82
	v_add_f32_e32 v64, v65, v64
	v_add_f32_e32 v67, v85, v64
	v_cvt_pk_bf16_f32 v75, v84, v75
	ds_bpermute_b32 v84, v170, v67
	s_waitcnt lgkmcnt(1)
	v_lshlrev_b64 v[80:81], 11, v[158:159]
	v_lshl_add_u64 v[64:65], v[80:81], 1, s[8:9]
	v_lshl_add_u64 v[70:71], v[152:153], 1, v[64:65]
	global_store_dwordx4 v[70:71], v[72:75], off sc0 sc1
	s_waitcnt lgkmcnt(0)
	v_add_f32_e32 v64, v67, v84
	ds_bpermute_b32 v65, v171, v64
	v_cvt_pk_bf16_f32 v66, v68, v69
	v_cvt_pk_bf16_f32 v67, v76, v77
	v_cvt_pk_bf16_f32 v68, v78, v79
	v_cvt_pk_bf16_f32 v69, v82, v83
	global_store_dwordx4 v[70:71], v[66:69], off offset:256 sc0 sc1
	s_and_saveexec_b64 s[18:19], s[44:45]
	s_cbranch_execz .LBB0_2438
	v_lshlrev_b64 v[66:67], 7, v[158:159]
	v_lshl_add_u64 v[66:67], s[16:17], 0, v[66:67]
	s_waitcnt lgkmcnt(0)
	v_add_f32_e32 v64, v64, v65
	global_store_dword v[66:67], v64, off
.LBB0_2438:
	s_or_b64 exec, exec, s[18:19]
	v_add_u32_e32 v98, 0x80, v156
	v_ashrrev_i32_e32 v99, 31, v98
	v_lshlrev_b64 v[104:105], 12, v[98:99]
	s_waitcnt lgkmcnt(0)
	v_lshl_add_u64 v[64:65], v[154:155], 0, v[104:105]
	global_load_dwordx4 v[100:103], v[64:65], off
	global_load_dwordx4 v[88:91], v[64:65], off offset:256
	v_add_u32_e32 v96, 0x90, v156
	v_ashrrev_i32_e32 v97, 31, v96
	v_lshlrev_b64 v[64:65], 12, v[96:97]
	v_add_u32_e32 v94, 0xa0, v156
	v_lshl_add_u64 v[64:65], v[154:155], 0, v[64:65]
	v_ashrrev_i32_e32 v95, 31, v94
	global_load_dwordx4 v[84:87], v[64:65], off
	global_load_dwordx4 v[80:83], v[64:65], off offset:256
	v_lshlrev_b64 v[64:65], 12, v[94:95]
	v_add_u32_e32 v92, 0xb0, v156
	v_lshl_add_u64 v[64:65], v[154:155], 0, v[64:65]
	v_ashrrev_i32_e32 v93, 31, v92
	global_load_dwordx4 v[76:79], v[64:65], off
	global_load_dwordx4 v[72:75], v[64:65], off offset:256
	v_lshlrev_b64 v[64:65], 12, v[92:93]
	v_lshl_add_u64 v[64:65], v[154:155], 0, v[64:65]
	global_load_dwordx4 v[68:71], v[64:65], off
	s_nop 0
	global_load_dwordx4 v[64:67], v[64:65], off offset:256
	v_pk_add_f32 v[60:61], v[60:61], 0 op_sel_hi:[1,0]
	v_pk_add_f32 v[62:63], v[62:63], 0 op_sel_hi:[1,0]
	v_pk_add_f32 v[56:57], v[56:57], 0 op_sel_hi:[1,0]
	v_pk_add_f32 v[58:59], v[58:59], 0 op_sel_hi:[1,0]
	v_pk_add_f32 v[52:53], v[52:53], 0 op_sel_hi:[1,0]
	v_pk_add_f32 v[54:55], v[54:55], 0 op_sel_hi:[1,0]
	v_pk_add_f32 v[48:49], v[48:49], 0 op_sel_hi:[1,0]
	v_pk_add_f32 v[50:51], v[50:51], 0 op_sel_hi:[1,0]
	s_waitcnt vmcnt(7)
	v_lshlrev_b32_e32 v106, 16, v100
	v_and_b32_e32 v100, 0xffff0000, v100
	v_add_f32_e32 v61, v61, v100
	v_lshlrev_b32_e32 v100, 16, v101
	v_add_f32_e32 v62, v62, v100
	v_and_b32_e32 v100, 0xffff0000, v101
	v_add_f32_e32 v63, v63, v100
	v_lshlrev_b32_e32 v100, 16, v102
	v_add_f32_e32 v56, v56, v100
	v_and_b32_e32 v100, 0xffff0000, v102
	v_add_f32_e32 v57, v57, v100
	v_lshlrev_b32_e32 v100, 16, v103
	v_add_f32_e32 v100, v58, v100
	v_and_b32_e32 v58, 0xffff0000, v103
	v_add_f32_e32 v60, v60, v106
	v_add_f32_e32 v101, v59, v58
	v_mul_f32_e32 v58, v61, v61
	v_mul_f32_e32 v59, v63, v63
	v_fmac_f32_e32 v58, v60, v60
	v_fmac_f32_e32 v59, v62, v62
	v_add_f32_e32 v58, v58, v59
	v_mul_f32_e32 v59, v57, v57
	v_fmac_f32_e32 v59, v56, v56
	v_add_f32_e32 v58, v59, v58
	v_mul_f32_e32 v59, v101, v101
	v_fmac_f32_e32 v59, v100, v100
	v_add_f32_e32 v102, v59, v58
	v_cvt_pk_bf16_f32 v58, v60, v61
	v_cvt_pk_bf16_f32 v59, v62, v63
	v_cvt_pk_bf16_f32 v60, v56, v57
	v_lshl_add_u64 v[56:57], s[8:9], 0, v[104:105]
	v_lshl_add_u64 v[56:57], v[152:153], 1, v[56:57]
	v_cvt_pk_bf16_f32 v61, v100, v101
	global_store_dwordx4 v[56:57], v[58:61], off sc0 sc1
	s_waitcnt vmcnt(7)
	s_nop 0
	v_lshlrev_b32_e32 v58, 16, v88
	v_add_f32_e32 v52, v52, v58
	v_and_b32_e32 v58, 0xffff0000, v88
	v_add_f32_e32 v53, v53, v58
	v_lshlrev_b32_e32 v58, 16, v89
	v_add_f32_e32 v54, v54, v58
	v_and_b32_e32 v58, 0xffff0000, v89
	v_add_f32_e32 v55, v55, v58
	v_lshlrev_b32_e32 v58, 16, v90
	v_add_f32_e32 v58, v48, v58
	v_and_b32_e32 v48, 0xffff0000, v90
	v_add_f32_e32 v59, v49, v48
	v_lshlrev_b32_e32 v48, 16, v91
	v_add_f32_e32 v60, v50, v48
	v_and_b32_e32 v48, 0xffff0000, v91
	v_add_f32_e32 v51, v51, v48
	v_mul_f32_e32 v48, v53, v53
	v_mul_f32_e32 v49, v55, v55
	v_fmac_f32_e32 v48, v52, v52
	v_fmac_f32_e32 v49, v54, v54
	v_add_f32_e32 v48, v48, v49
	v_mul_f32_e32 v49, v59, v59
	v_fmac_f32_e32 v49, v58, v58
	v_add_f32_e32 v48, v49, v48
	v_mul_f32_e32 v49, v51, v51
	v_fmac_f32_e32 v49, v60, v60
	v_add_f32_e32 v48, v49, v48
	v_add_f32_e32 v61, v102, v48
	v_cvt_pk_bf16_f32 v48, v52, v53
	v_cvt_pk_bf16_f32 v49, v54, v55
	v_cvt_pk_bf16_f32 v50, v58, v59
	v_cvt_pk_bf16_f32 v51, v60, v51
	global_store_dwordx4 v[56:57], v[48:51], off offset:256 sc0 sc1
	ds_bpermute_b32 v48, v170, v61
	s_waitcnt lgkmcnt(0)
	v_add_f32_e32 v48, v61, v48
	ds_bpermute_b32 v49, v171, v48
	s_and_saveexec_b64 s[18:19], s[44:45]
	s_cbranch_execz .LBB0_2440
; __device__ __forceinline__ unsigned cvt_pk_bf16(float lo, float hi) { unsigned r; asm volatile("v_cvt_pk_bf16_f32 %0, %1, %2" : "=v"(r) : "v"(lo), "v"(hi)); return r; }
;     __device__ __forceinline__ void operator()(const f32x4 (&acc)[2][2][4][2], const Unit& u, int wr, int wc, int fr, int fq) const {
;     ...
;             for (int m = 0; m < 4; ++m) { const int row = row0 + ai * HALF + m * 16; float ss = 0.f;
; #pragma unroll
;                 for (int bj = 0; bj < 2; ++bj) { const u32x4 ow = old[m][bj];
;                     f32x4 v0 = (acc[ai][bj][m][0] + bv[bj][0]) * accs, v1 = (acc[ai][bj][m][1] + bv[bj][1]) * accs;
;                     v0[0] += __uint_as_float(ow.x << 16); v0[1] += __uint_as_float(ow.x & 0xffff0000u); v0[2] += __uint_as_float(ow.y << 16); v0[3] += __uint_as_float(ow.y & 0xffff0000u);
;                     v1[0] += __uint_as_float(ow.z << 16); v1[1] += __uint_as_float(ow.z & 0xffff0000u); v1[2] += __uint_as_float(ow.w << 16); v1[3] += __uint_as_float(ow.w & 0xffff0000u);
;                     ss += (v0[0] * v0[0] + v0[1] * v0[1]) + (v0[2] * v0[2] + v0[3] * v0[3]) + (v1[0] * v1[0] + v1[1] * v1[1]) + (v1[2] * v1[2] + v1[3] * v1[3]);
;                     u32x4 w; w.x = cvt_pk_bf16(v0[0], v0[1]); w.y = cvt_pk_bf16(v0[2], v0[3]); w.z = cvt_pk_bf16(v1[0], v1[1]); w.w = cvt_pk_bf16(v1[2], v1[3]);
;                     *(u32x4*)(HB + (size_t)row * ldc + col0 + bj * HALF) = w; }
;                 ss += __shfl_xor(ss, 16); ss += __shfl_xor(ss, 32);
;                 if (fq == 0) ssp[(size_t)row * 32] = ss; }
	v_lshlrev_b64 v[50:51], 7, v[98:99]
	v_lshl_add_u64 v[50:51], s[16:17], 0, v[50:51]
	s_waitcnt lgkmcnt(0)
	v_add_f32_e32 v48, v48, v49
	global_store_dword v[50:51], v48, off
.LBB0_2440:
	s_or_b64 exec, exec, s[18:19]
	v_pk_add_f32 v[44:45], v[44:45], 0 op_sel_hi:[1,0]
	s_waitcnt vmcnt(7)
	v_lshlrev_b32_e32 v50, 16, v84
	v_add_f32_e32 v44, v44, v50
	v_and_b32_e32 v50, 0xffff0000, v84
	v_pk_add_f32 v[46:47], v[46:47], 0 op_sel_hi:[1,0]
	v_add_f32_e32 v45, v45, v50
	v_lshlrev_b32_e32 v50, 16, v85
	v_add_f32_e32 v46, v46, v50
	v_and_b32_e32 v50, 0xffff0000, v85
	v_pk_add_f32 v[40:41], v[40:41], 0 op_sel_hi:[1,0]
	v_add_f32_e32 v47, v47, v50
	v_lshlrev_b32_e32 v50, 16, v86
	v_add_f32_e32 v50, v40, v50
	v_and_b32_e32 v40, 0xffff0000, v86
	v_pk_add_f32 v[42:43], v[42:43], 0 op_sel_hi:[1,0]
	v_add_f32_e32 v51, v41, v40
	v_lshlrev_b32_e32 v40, 16, v87
	v_add_f32_e32 v52, v42, v40
	v_and_b32_e32 v40, 0xffff0000, v87
	v_add_f32_e32 v43, v43, v40
	v_mul_f32_e32 v40, v45, v45
	v_mul_f32_e32 v41, v47, v47
	v_fmac_f32_e32 v40, v44, v44
	v_fmac_f32_e32 v41, v46, v46
	v_add_f32_e32 v40, v40, v41
	v_mul_f32_e32 v41, v51, v51
	v_fmac_f32_e32 v41, v50, v50
	v_add_f32_e32 v40, v41, v40
	v_mul_f32_e32 v41, v43, v43
	v_fmac_f32_e32 v41, v52, v52
	v_add_f32_e32 v53, v41, v40
	v_cvt_pk_bf16_f32 v40, v44, v45
	v_pk_add_f32 v[36:37], v[36:37], 0 op_sel_hi:[1,0]
	s_waitcnt vmcnt(6)
	v_lshlrev_b32_e32 v44, 16, v80
	v_add_f32_e32 v36, v36, v44
	v_and_b32_e32 v44, 0xffff0000, v80
	v_pk_add_f32 v[38:39], v[38:39], 0 op_sel_hi:[1,0]
	v_add_f32_e32 v37, v37, v44
	v_lshlrev_b32_e32 v44, 16, v81
	v_add_f32_e32 v44, v38, v44
	v_and_b32_e32 v38, 0xffff0000, v81
	v_pk_add_f32 v[32:33], v[32:33], 0 op_sel_hi:[1,0]
	v_add_f32_e32 v45, v39, v38
	v_lshlrev_b32_e32 v38, 16, v82
	v_cvt_pk_bf16_f32 v41, v46, v47
	v_add_f32_e32 v46, v32, v38
	v_and_b32_e32 v32, 0xffff0000, v82
	v_pk_add_f32 v[34:35], v[34:35], 0 op_sel_hi:[1,0]
	v_add_f32_e32 v47, v33, v32
	v_lshlrev_b32_e32 v32, 16, v83
	v_cvt_pk_bf16_f32 v42, v50, v51
	v_add_f32_e32 v50, v34, v32
	v_and_b32_e32 v32, 0xffff0000, v83
	v_add_f32_e32 v51, v35, v32
	v_mul_f32_e32 v32, v37, v37
	v_mul_f32_e32 v33, v45, v45
	v_fmac_f32_e32 v32, v36, v36
	v_fmac_f32_e32 v33, v44, v44
	v_add_f32_e32 v32, v32, v33
	v_mul_f32_e32 v33, v47, v47
	v_fmac_f32_e32 v33, v46, v46
	v_add_f32_e32 v32, v33, v32
	v_mul_f32_e32 v33, v51, v51
	v_fmac_f32_e32 v33, v50, v50
	v_add_f32_e32 v32, v33, v32
	v_add_f32_e32 v35, v53, v32
	v_cvt_pk_bf16_f32 v43, v52, v43
	ds_bpermute_b32 v52, v170, v35
	s_waitcnt lgkmcnt(1)
	v_lshlrev_b64 v[48:49], 11, v[96:97]
	v_lshl_add_u64 v[32:33], v[48:49], 1, s[8:9]
	v_lshl_add_u64 v[38:39], v[152:153], 1, v[32:33]
	global_store_dwordx4 v[38:39], v[40:43], off sc0 sc1
	s_waitcnt lgkmcnt(0)
	v_add_f32_e32 v32, v35, v52
	ds_bpermute_b32 v33, v171, v32
	v_cvt_pk_bf16_f32 v34, v36, v37
	v_cvt_pk_bf16_f32 v35, v44, v45
	v_cvt_pk_bf16_f32 v36, v46, v47
	v_cvt_pk_bf16_f32 v37, v50, v51
	global_store_dwordx4 v[38:39], v[34:37], off offset:256 sc0 sc1
	s_and_saveexec_b64 s[18:19], s[44:45]
	s_cbranch_execz .LBB0_2442
	v_lshlrev_b64 v[34:35], 7, v[96:97]
	v_lshl_add_u64 v[34:35], s[16:17], 0, v[34:35]
	s_waitcnt lgkmcnt(0)
	v_add_f32_e32 v32, v32, v33
	global_store_dword v[34:35], v32, off
; __device__ __forceinline__ unsigned cvt_pk_bf16(float lo, float hi) { unsigned r; asm volatile("v_cvt_pk_bf16_f32 %0, %1, %2" : "=v"(r) : "v"(lo), "v"(hi)); return r; }
;     __device__ __forceinline__ void operator()(const f32x4 (&acc)[2][2][4][2], const Unit& u, int wr, int wc, int fr, int fq) const {
;     ...
;             for (int m = 0; m < 4; ++m) { const int row = row0 + ai * HALF + m * 16; float ss = 0.f;
; #pragma unroll
;                 for (int bj = 0; bj < 2; ++bj) { const u32x4 ow = old[m][bj];
;                     f32x4 v0 = (acc[ai][bj][m][0] + bv[bj][0]) * accs, v1 = (acc[ai][bj][m][1] + bv[bj][1]) * accs;
;                     v0[0] += __uint_as_float(ow.x << 16); v0[1] += __uint_as_float(ow.x & 0xffff0000u); v0[2] += __uint_as_float(ow.y << 16); v0[3] += __uint_as_float(ow.y & 0xffff0000u);
;                     v1[0] += __uint_as_float(ow.z << 16); v1[1] += __uint_as_float(ow.z & 0xffff0000u); v1[2] += __uint_as_float(ow.w << 16); v1[3] += __uint_as_float(ow.w & 0xffff0000u);
;                     ss += (v0[0] * v0[0] + v0[1] * v0[1]) + (v0[2] * v0[2] + v0[3] * v0[3]) + (v1[0] * v1[0] + v1[1] * v1[1]) + (v1[2] * v1[2] + v1[3] * v1[3]);
;                     u32x4 w; w.x = cvt_pk_bf16(v0[0], v0[1]); w.y = cvt_pk_bf16(v0[2], v0[3]); w.z = cvt_pk_bf16(v1[0], v1[1]); w.w = cvt_pk_bf16(v1[2], v1[3]);
;                     *(u32x4*)(HB + (size_t)row * ldc + col0 + bj * HALF) = w; }
;                 ss += __shfl_xor(ss, 16); ss += __shfl_xor(ss, 32);
;                 if (fq == 0) ssp[(size_t)row * 32] = ss; }
.LBB0_2442:
	s_or_b64 exec, exec, s[18:19]
	v_pk_add_f32 v[28:29], v[28:29], 0 op_sel_hi:[1,0]
	s_waitcnt vmcnt(7)
	v_lshlrev_b32_e32 v34, 16, v76
	v_add_f32_e32 v28, v28, v34
	v_and_b32_e32 v34, 0xffff0000, v76
	v_pk_add_f32 v[30:31], v[30:31], 0 op_sel_hi:[1,0]
	v_add_f32_e32 v29, v29, v34
	v_lshlrev_b32_e32 v34, 16, v77
	v_add_f32_e32 v30, v30, v34
	v_and_b32_e32 v34, 0xffff0000, v77
	v_pk_add_f32 v[24:25], v[24:25], 0 op_sel_hi:[1,0]
	v_add_f32_e32 v31, v31, v34
	v_lshlrev_b32_e32 v34, 16, v78
	v_add_f32_e32 v34, v24, v34
	v_and_b32_e32 v24, 0xffff0000, v78
	v_pk_add_f32 v[26:27], v[26:27], 0 op_sel_hi:[1,0]
	v_add_f32_e32 v35, v25, v24
	v_lshlrev_b32_e32 v24, 16, v79
	v_add_f32_e32 v36, v26, v24
	v_and_b32_e32 v24, 0xffff0000, v79
	v_add_f32_e32 v27, v27, v24
	v_mul_f32_e32 v24, v29, v29
	v_mul_f32_e32 v25, v31, v31
	v_fmac_f32_e32 v24, v28, v28
	v_fmac_f32_e32 v25, v30, v30
	v_add_f32_e32 v24, v24, v25
	v_mul_f32_e32 v25, v35, v35
	v_fmac_f32_e32 v25, v34, v34
	v_add_f32_e32 v24, v25, v24
	v_mul_f32_e32 v25, v27, v27
	v_fmac_f32_e32 v25, v36, v36
	v_add_f32_e32 v37, v25, v24
	v_cvt_pk_bf16_f32 v24, v28, v29
	v_pk_add_f32 v[20:21], v[20:21], 0 op_sel_hi:[1,0]
	s_waitcnt vmcnt(6)
	v_lshlrev_b32_e32 v28, 16, v72
	v_add_f32_e32 v20, v20, v28
	v_and_b32_e32 v28, 0xffff0000, v72
	v_pk_add_f32 v[22:23], v[22:23], 0 op_sel_hi:[1,0]
	v_add_f32_e32 v21, v21, v28
	v_lshlrev_b32_e32 v28, 16, v73
	v_add_f32_e32 v28, v22, v28
	v_and_b32_e32 v22, 0xffff0000, v73
	v_pk_add_f32 v[16:17], v[16:17], 0 op_sel_hi:[1,0]
	v_add_f32_e32 v29, v23, v22
	v_lshlrev_b32_e32 v22, 16, v74
	v_cvt_pk_bf16_f32 v25, v30, v31
	v_add_f32_e32 v30, v16, v22
	v_and_b32_e32 v16, 0xffff0000, v74
	v_pk_add_f32 v[18:19], v[18:19], 0 op_sel_hi:[1,0]
	v_add_f32_e32 v31, v17, v16
	v_lshlrev_b32_e32 v16, 16, v75
	v_cvt_pk_bf16_f32 v26, v34, v35
	v_add_f32_e32 v34, v18, v16
	v_and_b32_e32 v16, 0xffff0000, v75
	v_add_f32_e32 v35, v19, v16
	v_mul_f32_e32 v16, v21, v21
	v_mul_f32_e32 v17, v29, v29
	v_fmac_f32_e32 v16, v20, v20
	v_fmac_f32_e32 v17, v28, v28
	v_add_f32_e32 v16, v16, v17
	v_mul_f32_e32 v17, v31, v31
	v_fmac_f32_e32 v17, v30, v30
	v_add_f32_e32 v16, v17, v16
	v_mul_f32_e32 v17, v35, v35
	v_fmac_f32_e32 v17, v34, v34
	v_add_f32_e32 v16, v17, v16
	v_add_f32_e32 v19, v37, v16
	v_cvt_pk_bf16_f32 v27, v36, v27
	ds_bpermute_b32 v36, v170, v19
	s_waitcnt lgkmcnt(1)
	v_lshlrev_b64 v[32:33], 11, v[94:95]
	v_lshl_add_u64 v[16:17], v[32:33], 1, s[8:9]
	v_lshl_add_u64 v[22:23], v[152:153], 1, v[16:17]
	global_store_dwordx4 v[22:23], v[24:27], off sc0 sc1
	s_waitcnt lgkmcnt(0)
	v_add_f32_e32 v16, v19, v36
	ds_bpermute_b32 v17, v171, v16
	v_cvt_pk_bf16_f32 v18, v20, v21
	v_cvt_pk_bf16_f32 v19, v28, v29
	v_cvt_pk_bf16_f32 v20, v30, v31
	v_cvt_pk_bf16_f32 v21, v34, v35
	global_store_dwordx4 v[22:23], v[18:21], off offset:256 sc0 sc1
	s_and_saveexec_b64 s[18:19], s[44:45]
	s_cbranch_execz .LBB0_2444
	v_lshlrev_b64 v[18:19], 7, v[94:95]
	v_lshl_add_u64 v[18:19], s[16:17], 0, v[18:19]
	s_waitcnt lgkmcnt(0)
	v_add_f32_e32 v16, v16, v17
	global_store_dword v[18:19], v16, off
.LBB0_2444:
	s_or_b64 exec, exec, s[18:19]
	v_pk_add_f32 v[12:13], v[12:13], 0 op_sel_hi:[1,0]
	s_waitcnt vmcnt(7)
	v_lshlrev_b32_e32 v18, 16, v68
	v_add_f32_e32 v12, v12, v18
	v_and_b32_e32 v18, 0xffff0000, v68
	v_pk_add_f32 v[14:15], v[14:15], 0 op_sel_hi:[1,0]
	v_add_f32_e32 v13, v13, v18
	v_lshlrev_b32_e32 v18, 16, v69
	v_add_f32_e32 v14, v14, v18
	v_and_b32_e32 v18, 0xffff0000, v69
	v_pk_add_f32 v[8:9], v[8:9], 0 op_sel_hi:[1,0]
	v_add_f32_e32 v15, v15, v18
	v_lshlrev_b32_e32 v18, 16, v70
	v_add_f32_e32 v18, v8, v18
	v_and_b32_e32 v8, 0xffff0000, v70
	v_pk_add_f32 v[10:11], v[10:11], 0 op_sel_hi:[1,0]
	v_add_f32_e32 v19, v9, v8
	v_lshlrev_b32_e32 v8, 16, v71
	v_add_f32_e32 v20, v10, v8
	v_and_b32_e32 v8, 0xffff0000, v71
	v_add_f32_e32 v11, v11, v8
	v_mul_f32_e32 v8, v13, v13
	v_mul_f32_e32 v9, v15, v15
	v_fmac_f32_e32 v8, v12, v12
	v_fmac_f32_e32 v9, v14, v14
	v_add_f32_e32 v8, v8, v9
	v_mul_f32_e32 v9, v19, v19
	v_fmac_f32_e32 v9, v18, v18
	v_add_f32_e32 v8, v9, v8
	v_mul_f32_e32 v9, v11, v11
	v_fmac_f32_e32 v9, v20, v20
	v_add_f32_e32 v21, v9, v8
	v_cvt_pk_bf16_f32 v8, v12, v13
	v_pk_add_f32 v[4:5], v[4:5], 0 op_sel_hi:[1,0]
	s_waitcnt vmcnt(6)
	v_lshlrev_b32_e32 v12, 16, v64
	v_add_f32_e32 v4, v4, v12
	v_and_b32_e32 v12, 0xffff0000, v64
	v_pk_add_f32 v[6:7], v[6:7], 0 op_sel_hi:[1,0]
	v_add_f32_e32 v5, v5, v12
	v_lshlrev_b32_e32 v12, 16, v65
	v_add_f32_e32 v12, v6, v12
	v_and_b32_e32 v6, 0xffff0000, v65
	v_pk_add_f32 v[0:1], v[0:1], 0 op_sel_hi:[1,0]
	v_add_f32_e32 v13, v7, v6
	v_lshlrev_b32_e32 v6, 16, v66
	v_cvt_pk_bf16_f32 v9, v14, v15
	v_add_f32_e32 v14, v0, v6
	v_and_b32_e32 v0, 0xffff0000, v66
	v_pk_add_f32 v[2:3], v[2:3], 0 op_sel_hi:[1,0]
	v_add_f32_e32 v15, v1, v0
	v_lshlrev_b32_e32 v0, 16, v67
	v_cvt_pk_bf16_f32 v10, v18, v19
	v_add_f32_e32 v18, v2, v0
	v_and_b32_e32 v0, 0xffff0000, v67
	v_add_f32_e32 v19, v3, v0
	v_mul_f32_e32 v0, v5, v5
	v_mul_f32_e32 v1, v13, v13
	v_fmac_f32_e32 v0, v4, v4
	v_fmac_f32_e32 v1, v12, v12
	v_add_f32_e32 v0, v0, v1
	v_mul_f32_e32 v1, v15, v15
	v_fmac_f32_e32 v1, v14, v14
	v_add_f32_e32 v0, v1, v0
	v_mul_f32_e32 v1, v19, v19
	v_fmac_f32_e32 v1, v18, v18
	v_add_f32_e32 v0, v1, v0
	v_add_f32_e32 v3, v21, v0
	v_cvt_pk_bf16_f32 v11, v20, v11
	ds_bpermute_b32 v20, v170, v3
	s_waitcnt lgkmcnt(1)
	v_lshlrev_b64 v[16:17], 11, v[92:93]
	v_lshl_add_u64 v[0:1], v[16:17], 1, s[8:9]
	v_lshl_add_u64 v[6:7], v[152:153], 1, v[0:1]
	global_store_dwordx4 v[6:7], v[8:11], off sc0 sc1
	s_waitcnt lgkmcnt(0)
	v_add_f32_e32 v0, v3, v20
	ds_bpermute_b32 v1, v171, v0
	v_cvt_pk_bf16_f32 v2, v4, v5
	v_cvt_pk_bf16_f32 v3, v12, v13
	v_cvt_pk_bf16_f32 v4, v14, v15
	v_cvt_pk_bf16_f32 v5, v18, v19
	global_store_dwordx4 v[6:7], v[2:5], off offset:256 sc0 sc1
	s_and_saveexec_b64 s[18:19], s[44:45]
	s_cbranch_execz .LBB0_2446
	v_lshlrev_b64 v[2:3], 7, v[92:93]
	v_lshl_add_u64 v[2:3], s[16:17], 0, v[2:3]
	s_waitcnt lgkmcnt(0)
	v_add_f32_e32 v0, v0, v1
	global_store_dword v[2:3], v0, off

; __device__ __forceinline__ unsigned cvt_pk_bf16(float lo, float hi) { unsigned r; asm volatile("v_cvt_pk_bf16_f32 %0, %1, %2" : "=v"(r) : "v"(lo), "v"(hi)); return r; }
; __device__ __forceinline__ float row_ss(const float* part, int row, int fq, int nf4) {
;     const f32x4* p = (const f32x4*)(part + (size_t)row * 32);
;     float s = 0.f;
; #pragma unroll
;     for (int j = 0; j < 2; ++j) { const int idx = fq + 4 * j; if (idx < nf4) { const f32x4 v = p[idx]; s += (v[0] + v[1]) + (v[2] + v[3]); } }
;     s += __shfl_xor(s, 16); s += __shfl_xor(s, 32);
;     return s;
; }
;     __device__ __forceinline__ void operator()(const f32x4 (&acc)[2][2][4][2], const Unit& u, int wr, int wc, int fr, int fq) const {
;     ...
;             for (int m = 0; m < 4; ++m) { const int row = row0 + ai * HALF + m * 16; bf16_t* rowp = base + (size_t)row * ldc + col0;
;                 const float rs = rss ? __builtin_amdgcn_rsqf(row_ss(rss, row, fq, nf4) * rinv + 1e-6f) : 1.f;
; #pragma unroll
;                 for (int bj = 0; bj < 2; ++bj) { f32x4 v0 = acc[ai][bj][m][0] * rs + bv[bj][0], v1 = acc[ai][bj][m][1] * rs + bv[bj][1];
;                     v0 = v0 * sc; v1 = v1 * sc; u32x4 w; w.x = cvt_pk_bf16(v0[0], v0[1]); w.y = cvt_pk_bf16(v0[2], v0[3]); w.z = cvt_pk_bf16(v1[0], v1[1]); w.w = cvt_pk_bf16(v1[2], v1[3]);
;                     *(u32x4*)(rowp + bj * HALF) = w; } }
.LBB0_2514:
	s_ashr_i32 s2, s1, 31
	s_lshr_b32 s2, s2, 29
	s_add_i32 s2, s1, s2
	s_ashr_i32 s6, s2, 3
	v_lshl_add_u32 v150, s0, 8, v147
	s_lshl_b32 s0, s1, 8
	s_mul_i32 s2, s6, 0x3000000
	s_mul_hi_i32 s3, s6, 0x3000000
	s_add_u32 s2, s47, s2
	s_addc_u32 s3, s48, s3
	s_lshl_b32 s6, s6, 11
	s_sub_i32 s0, s0, s6
	v_or_b32_e32 v148, s0, v153
	v_ashrrev_i32_e32 v149, 31, v148
	v_ashrrev_i32_e32 v151, 31, v150
	v_lshl_add_u64 v[148:149], v[148:149], 1, s[2:3]
	v_lshlrev_b64 v[160:161], 12, v[150:151]
	v_lshl_add_u64 v[168:169], v[148:149], 0, v[160:161]
	v_lshlrev_b64 v[160:161], 7, v[150:151]
	v_lshl_add_u64 v[164:165], v[136:137], 0, v[160:161]
	global_load_dwordx4 v[160:163], v[164:165], off
	s_nop 0
	global_load_dwordx4 v[164:167], v[164:165], off offset:64
	s_add_i32 s1, s1, 7
	s_cmp_lt_u32 s1, 15
	s_cselect_b64 vcc, -1, 0
	v_cndmask_b32_e32 v146, 1.0, v158, vcc
	v_readlane_b32 s38, v245, 6
	v_readlane_b32 s40, v245, 8
	s_mov_b64 s[0:1], -1
	v_readlane_b32 s39, v245, 7
	v_readlane_b32 s41, v245, 9
	s_waitcnt vmcnt(0)
	v_mov_b32_e32 v170, v160
	v_mov_b32_e32 v171, v164
	v_mov_b32_e32 v164, v161
	v_pk_add_f32 v[160:161], v[170:171], v[164:165]
	v_mov_b32_e32 v164, v162
	v_mov_b32_e32 v165, v166
	v_mov_b32_e32 v166, v163
	v_pk_add_f32 v[162:163], v[164:165], v[166:167]
	s_nop 0
	v_pk_add_f32 v[160:161], v[160:161], v[162:163]
	s_nop 0
	v_add_f32_e32 v151, 0, v160
	v_and_b32_e32 v160, 64, v202
	v_add_f32_e32 v159, v151, v161
	v_xor_b32_e32 v151, 16, v202
	v_add_u32_e32 v160, 64, v160
	v_cmp_lt_i32_e32 vcc, v151, v160
	s_nop 1
	v_cndmask_b32_e32 v151, v202, v151, vcc
	v_lshlrev_b32_e32 v151, 2, v151
	ds_bpermute_b32 v161, v151, v159
	s_waitcnt lgkmcnt(0)
	v_add_f32_e32 v161, v159, v161
	v_xor_b32_e32 v159, 32, v202
	v_cmp_lt_i32_e32 vcc, v159, v160
	s_nop 1
	v_cndmask_b32_e32 v159, v202, v159, vcc
	v_lshlrev_b32_e32 v159, 2, v159
	ds_bpermute_b32 v160, v159, v161
	s_andn2_b64 vcc, exec, s[44:45]
	s_waitcnt lgkmcnt(0)
	v_add_f32_e32 v160, v161, v160
	v_fmamk_f32 v160, v160, 0x3a000000, v157
	v_rsq_f32_e32 v160, v160
	s_nop 0
	v_pk_fma_f32 v[124:125], v[124:125], v[160:161], 0 op_sel_hi:[1,0,0]
	v_pk_fma_f32 v[126:127], v[126:127], v[160:161], 0 op_sel_hi:[1,0,0]
	v_pk_fma_f32 v[120:121], v[120:121], v[160:161], 0 op_sel_hi:[1,0,0]
	v_pk_fma_f32 v[122:123], v[122:123], v[160:161], 0 op_sel_hi:[1,0,0]
	v_pk_mul_f32 v[126:127], v[146:147], v[126:127] op_sel_hi:[0,1]
	v_pk_mul_f32 v[124:125], v[146:147], v[124:125] op_sel_hi:[0,1]
	v_pk_mul_f32 v[162:163], v[146:147], v[122:123] op_sel_hi:[0,1]
	v_pk_mul_f32 v[122:123], v[146:147], v[120:121] op_sel_hi:[0,1]
	v_cvt_pk_bf16_f32 v120, v124, v125
	v_cvt_pk_bf16_f32 v121, v126, v127
	v_pk_fma_f32 v[116:117], v[116:117], v[160:161], 0 op_sel_hi:[1,0,0]
	v_pk_fma_f32 v[112:113], v[112:113], v[160:161], 0 op_sel_hi:[1,0,0]
	v_pk_fma_f32 v[114:115], v[114:115], v[160:161], 0 op_sel_hi:[1,0,0]
	v_cvt_pk_bf16_f32 v122, v122, v123
	v_cvt_pk_bf16_f32 v123, v162, v163
	global_store_dwordx4 v[168:169], v[120:123], off sc0 sc1
	v_pk_fma_f32 v[118:119], v[118:119], v[160:161], 0 op_sel_hi:[1,0,0]
	v_pk_mul_f32 v[116:117], v[146:147], v[116:117] op_sel_hi:[0,1]
	v_pk_mul_f32 v[120:121], v[146:147], v[114:115] op_sel_hi:[0,1]
	v_pk_mul_f32 v[114:115], v[146:147], v[112:113] op_sel_hi:[0,1]
	v_cvt_pk_bf16_f32 v112, v116, v117
	v_pk_mul_f32 v[118:119], v[146:147], v[118:119] op_sel_hi:[0,1]
	v_cvt_pk_bf16_f32 v113, v118, v119
	v_cvt_pk_bf16_f32 v114, v114, v115
	v_cvt_pk_bf16_f32 v115, v120, v121
	global_store_dwordx4 v[168:169], v[112:115], off offset:256 sc0 sc1
	s_nop 1
	v_or_b32_e32 v112, 16, v150
	v_ashrrev_i32_e32 v113, 31, v112
	v_lshlrev_b64 v[114:115], 12, v[112:113]
	v_lshlrev_b64 v[112:113], 7, v[112:113]
	v_lshl_add_u64 v[116:117], v[136:137], 0, v[112:113]
	v_lshl_add_u64 v[120:121], v[148:149], 0, v[114:115]
	global_load_dwordx4 v[112:115], v[116:117], off
	s_nop 0
	global_load_dwordx4 v[116:119], v[116:117], off offset:64
	s_waitcnt vmcnt(1)
	v_mov_b32_e32 v122, v112
	s_waitcnt vmcnt(0)
	v_mov_b32_e32 v123, v116
	v_mov_b32_e32 v116, v113
	v_pk_add_f32 v[112:113], v[122:123], v[116:117]
	v_mov_b32_e32 v116, v114
	v_mov_b32_e32 v117, v118
	v_mov_b32_e32 v118, v115
	v_pk_add_f32 v[114:115], v[116:117], v[118:119]
	s_nop 0
	v_pk_add_f32 v[112:113], v[112:113], v[114:115]
	s_nop 0
	v_add_f32_e32 v112, 0, v112
	v_add_f32_e32 v112, v112, v113
	ds_bpermute_b32 v113, v151, v112
	s_waitcnt lgkmcnt(0)
	v_add_f32_e32 v112, v112, v113
	ds_bpermute_b32 v113, v159, v112
	s_waitcnt lgkmcnt(0)
	v_add_f32_e32 v112, v112, v113
	v_fmamk_f32 v112, v112, 0x3a000000, v157
	v_rsq_f32_e32 v112, v112
	s_nop 0
	v_pk_fma_f32 v[108:109], v[108:109], v[112:113], 0 op_sel_hi:[1,0,0]
	v_pk_fma_f32 v[110:111], v[110:111], v[112:113], 0 op_sel_hi:[1,0,0]
	v_pk_fma_f32 v[104:105], v[104:105], v[112:113], 0 op_sel_hi:[1,0,0]
	v_pk_fma_f32 v[106:107], v[106:107], v[112:113], 0 op_sel_hi:[1,0,0]
	v_pk_mul_f32 v[110:111], v[146:147], v[110:111] op_sel_hi:[0,1]
	v_pk_mul_f32 v[108:109], v[146:147], v[108:109] op_sel_hi:[0,1]
	v_pk_mul_f32 v[114:115], v[146:147], v[106:107] op_sel_hi:[0,1]
	v_pk_mul_f32 v[106:107], v[146:147], v[104:105] op_sel_hi:[0,1]
	v_cvt_pk_bf16_f32 v104, v108, v109
	v_cvt_pk_bf16_f32 v105, v110, v111
	v_pk_fma_f32 v[100:101], v[100:101], v[112:113], 0 op_sel_hi:[1,0,0]
	v_pk_fma_f32 v[96:97], v[96:97], v[112:113], 0 op_sel_hi:[1,0,0]
	v_pk_fma_f32 v[98:99], v[98:99], v[112:113], 0 op_sel_hi:[1,0,0]
	v_cvt_pk_bf16_f32 v106, v106, v107
	v_cvt_pk_bf16_f32 v107, v114, v115
	global_store_dwordx4 v[120:121], v[104:107], off sc0 sc1
	v_pk_fma_f32 v[102:103], v[102:103], v[112:113], 0 op_sel_hi:[1,0,0]
	v_pk_mul_f32 v[100:101], v[146:147], v[100:101] op_sel_hi:[0,1]
	v_pk_mul_f32 v[104:105], v[146:147], v[98:99] op_sel_hi:[0,1]
	v_pk_mul_f32 v[98:99], v[146:147], v[96:97] op_sel_hi:[0,1]
	v_cvt_pk_bf16_f32 v96, v100, v101
	v_pk_mul_f32 v[102:103], v[146:147], v[102:103] op_sel_hi:[0,1]
	v_cvt_pk_bf16_f32 v97, v102, v103
	v_cvt_pk_bf16_f32 v98, v98, v99
	v_cvt_pk_bf16_f32 v99, v104, v105
	global_store_dwordx4 v[120:121], v[96:99], off offset:256 sc0 sc1
	s_nop 1
	v_or_b32_e32 v96, 32, v150
	v_ashrrev_i32_e32 v97, 31, v96
	v_lshlrev_b64 v[98:99], 12, v[96:97]
	v_lshlrev_b64 v[96:97], 7, v[96:97]
	v_lshl_add_u64 v[100:101], v[136:137], 0, v[96:97]
	v_lshl_add_u64 v[104:105], v[148:149], 0, v[98:99]
	global_load_dwordx4 v[96:99], v[100:101], off
	s_nop 0
	global_load_dwordx4 v[100:103], v[100:101], off offset:64
	s_waitcnt vmcnt(1)
; __device__ __forceinline__ unsigned cvt_pk_bf16(float lo, float hi) { unsigned r; asm volatile("v_cvt_pk_bf16_f32 %0, %1, %2" : "=v"(r) : "v"(lo), "v"(hi)); return r; }
; __device__ __forceinline__ float row_ss(const float* part, int row, int fq, int nf4) {
;     const f32x4* p = (const f32x4*)(part + (size_t)row * 32);
;     float s = 0.f;
; #pragma unroll
;     for (int j = 0; j < 2; ++j) { const int idx = fq + 4 * j; if (idx < nf4) { const f32x4 v = p[idx]; s += (v[0] + v[1]) + (v[2] + v[3]); } }
;     s += __shfl_xor(s, 16); s += __shfl_xor(s, 32);
;     return s;
; }
;     __device__ __forceinline__ void operator()(const f32x4 (&acc)[2][2][4][2], const Unit& u, int wr, int wc, int fr, int fq) const {
;     ...
;             for (int m = 0; m < 4; ++m) { const int row = row0 + ai * HALF + m * 16; bf16_t* rowp = base + (size_t)row * ldc + col0;
;                 const float rs = rss ? __builtin_amdgcn_rsqf(row_ss(rss, row, fq, nf4) * rinv + 1e-6f) : 1.f;
; #pragma unroll
;                 for (int bj = 0; bj < 2; ++bj) { f32x4 v0 = acc[ai][bj][m][0] * rs + bv[bj][0], v1 = acc[ai][bj][m][1] * rs + bv[bj][1];
;                     v0 = v0 * sc; v1 = v1 * sc; u32x4 w; w.x = cvt_pk_bf16(v0[0], v0[1]); w.y = cvt_pk_bf16(v0[2], v0[3]); w.z = cvt_pk_bf16(v1[0], v1[1]); w.w = cvt_pk_bf16(v1[2], v1[3]);
;                     *(u32x4*)(rowp + bj * HALF) = w; } }
	v_mov_b32_e32 v106, v96
	s_waitcnt vmcnt(0)
	v_mov_b32_e32 v107, v100
	v_mov_b32_e32 v100, v97
	v_pk_add_f32 v[96:97], v[106:107], v[100:101]
	v_mov_b32_e32 v100, v98
	v_mov_b32_e32 v101, v102
	v_mov_b32_e32 v102, v99
	v_pk_add_f32 v[98:99], v[100:101], v[102:103]
	s_nop 0
	v_pk_add_f32 v[96:97], v[96:97], v[98:99]
	s_nop 0
	v_add_f32_e32 v96, 0, v96
	v_add_f32_e32 v96, v96, v97
	ds_bpermute_b32 v97, v151, v96
	s_waitcnt lgkmcnt(0)
	v_add_f32_e32 v96, v96, v97
	ds_bpermute_b32 v97, v159, v96
	s_waitcnt lgkmcnt(0)
	v_add_f32_e32 v96, v96, v97
	v_fmamk_f32 v96, v96, 0x3a000000, v157
	v_rsq_f32_e32 v96, v96
	s_nop 0
	v_pk_fma_f32 v[92:93], v[92:93], v[96:97], 0 op_sel_hi:[1,0,0]
	v_pk_fma_f32 v[94:95], v[94:95], v[96:97], 0 op_sel_hi:[1,0,0]
	v_pk_fma_f32 v[88:89], v[88:89], v[96:97], 0 op_sel_hi:[1,0,0]
	v_pk_fma_f32 v[90:91], v[90:91], v[96:97], 0 op_sel_hi:[1,0,0]
	v_pk_mul_f32 v[94:95], v[146:147], v[94:95] op_sel_hi:[0,1]
	v_pk_mul_f32 v[92:93], v[146:147], v[92:93] op_sel_hi:[0,1]
	v_pk_mul_f32 v[98:99], v[146:147], v[90:91] op_sel_hi:[0,1]
	v_pk_mul_f32 v[90:91], v[146:147], v[88:89] op_sel_hi:[0,1]
	v_cvt_pk_bf16_f32 v88, v92, v93
	v_cvt_pk_bf16_f32 v89, v94, v95
	v_pk_fma_f32 v[84:85], v[84:85], v[96:97], 0 op_sel_hi:[1,0,0]
	v_pk_fma_f32 v[80:81], v[80:81], v[96:97], 0 op_sel_hi:[1,0,0]
	v_pk_fma_f32 v[82:83], v[82:83], v[96:97], 0 op_sel_hi:[1,0,0]
	v_cvt_pk_bf16_f32 v90, v90, v91
	v_cvt_pk_bf16_f32 v91, v98, v99
	global_store_dwordx4 v[104:105], v[88:91], off sc0 sc1
	v_pk_fma_f32 v[86:87], v[86:87], v[96:97], 0 op_sel_hi:[1,0,0]
	v_pk_mul_f32 v[84:85], v[146:147], v[84:85] op_sel_hi:[0,1]
	v_pk_mul_f32 v[88:89], v[146:147], v[82:83] op_sel_hi:[0,1]
	v_pk_mul_f32 v[82:83], v[146:147], v[80:81] op_sel_hi:[0,1]
	v_cvt_pk_bf16_f32 v80, v84, v85
	v_pk_mul_f32 v[86:87], v[146:147], v[86:87] op_sel_hi:[0,1]
	v_cvt_pk_bf16_f32 v81, v86, v87
	v_cvt_pk_bf16_f32 v82, v82, v83
	v_cvt_pk_bf16_f32 v83, v88, v89
	global_store_dwordx4 v[104:105], v[80:83], off offset:256 sc0 sc1
	s_nop 1
	v_or_b32_e32 v80, 48, v150
	v_ashrrev_i32_e32 v81, 31, v80
	v_lshlrev_b64 v[82:83], 12, v[80:81]
	v_lshlrev_b64 v[80:81], 7, v[80:81]
	v_lshl_add_u64 v[84:85], v[136:137], 0, v[80:81]
	v_lshl_add_u64 v[88:89], v[148:149], 0, v[82:83]
	global_load_dwordx4 v[80:83], v[84:85], off
	s_nop 0
	global_load_dwordx4 v[84:87], v[84:85], off offset:64
	s_waitcnt vmcnt(1)
	v_mov_b32_e32 v90, v80
	s_waitcnt vmcnt(0)
	v_mov_b32_e32 v91, v84
	v_mov_b32_e32 v84, v81
	v_pk_add_f32 v[80:81], v[90:91], v[84:85]
	v_mov_b32_e32 v84, v82
	v_mov_b32_e32 v85, v86
	v_mov_b32_e32 v86, v83
	v_pk_add_f32 v[82:83], v[84:85], v[86:87]
	s_nop 0
	v_pk_add_f32 v[80:81], v[80:81], v[82:83]
	s_nop 0
	v_add_f32_e32 v80, 0, v80
	v_add_f32_e32 v80, v80, v81
	ds_bpermute_b32 v81, v151, v80
	s_waitcnt lgkmcnt(0)
	v_add_f32_e32 v80, v80, v81
	ds_bpermute_b32 v81, v159, v80
	s_waitcnt lgkmcnt(0)
	v_add_f32_e32 v80, v80, v81
	v_fmamk_f32 v80, v80, 0x3a000000, v157
	v_rsq_f32_e32 v80, v80
	s_nop 0
	v_pk_fma_f32 v[76:77], v[76:77], v[80:81], 0 op_sel_hi:[1,0,0]
	v_pk_fma_f32 v[78:79], v[78:79], v[80:81], 0 op_sel_hi:[1,0,0]
	v_pk_fma_f32 v[72:73], v[72:73], v[80:81], 0 op_sel_hi:[1,0,0]
	v_pk_fma_f32 v[74:75], v[74:75], v[80:81], 0 op_sel_hi:[1,0,0]
	v_pk_mul_f32 v[78:79], v[146:147], v[78:79] op_sel_hi:[0,1]
	v_pk_mul_f32 v[76:77], v[146:147], v[76:77] op_sel_hi:[0,1]
	v_pk_mul_f32 v[82:83], v[146:147], v[74:75] op_sel_hi:[0,1]
	v_pk_mul_f32 v[74:75], v[146:147], v[72:73] op_sel_hi:[0,1]
	v_cvt_pk_bf16_f32 v72, v76, v77
	v_cvt_pk_bf16_f32 v73, v78, v79
	v_pk_fma_f32 v[68:69], v[68:69], v[80:81], 0 op_sel_hi:[1,0,0]
	v_pk_fma_f32 v[64:65], v[64:65], v[80:81], 0 op_sel_hi:[1,0,0]
	v_pk_fma_f32 v[66:67], v[66:67], v[80:81], 0 op_sel_hi:[1,0,0]
	v_cvt_pk_bf16_f32 v74, v74, v75
	v_cvt_pk_bf16_f32 v75, v82, v83
	global_store_dwordx4 v[88:89], v[72:75], off sc0 sc1
	v_pk_fma_f32 v[70:71], v[70:71], v[80:81], 0 op_sel_hi:[1,0,0]
	v_pk_mul_f32 v[68:69], v[146:147], v[68:69] op_sel_hi:[0,1]
	v_pk_mul_f32 v[72:73], v[146:147], v[66:67] op_sel_hi:[0,1]
	v_pk_mul_f32 v[66:67], v[146:147], v[64:65] op_sel_hi:[0,1]
	v_cvt_pk_bf16_f32 v64, v68, v69
	v_pk_mul_f32 v[70:71], v[146:147], v[70:71] op_sel_hi:[0,1]
	v_cvt_pk_bf16_f32 v65, v70, v71
	v_cvt_pk_bf16_f32 v66, v66, v67
	v_cvt_pk_bf16_f32 v67, v72, v73
	global_store_dwordx4 v[88:89], v[64:67], off offset:256 sc0 sc1
	s_nop 1
	v_add_u32_e32 v64, 0x80, v150
	v_ashrrev_i32_e32 v65, 31, v64
	v_lshlrev_b64 v[66:67], 12, v[64:65]
	v_lshlrev_b64 v[64:65], 7, v[64:65]
	v_lshl_add_u64 v[68:69], v[136:137], 0, v[64:65]
	v_lshl_add_u64 v[72:73], v[148:149], 0, v[66:67]
	global_load_dwordx4 v[64:67], v[68:69], off
	s_nop 0
	global_load_dwordx4 v[68:71], v[68:69], off offset:64
	s_waitcnt vmcnt(1)
	v_mov_b32_e32 v74, v64
	s_waitcnt vmcnt(0)
	v_mov_b32_e32 v75, v68
	v_mov_b32_e32 v68, v65
	v_pk_add_f32 v[64:65], v[74:75], v[68:69]
	v_mov_b32_e32 v68, v66
	v_mov_b32_e32 v69, v70
	v_mov_b32_e32 v70, v67
	v_pk_add_f32 v[66:67], v[68:69], v[70:71]
	s_nop 0
	v_pk_add_f32 v[64:65], v[64:65], v[66:67]
	s_nop 0
	v_add_f32_e32 v64, 0, v64
	v_add_f32_e32 v64, v64, v65
	ds_bpermute_b32 v65, v151, v64
	s_waitcnt lgkmcnt(0)
	v_add_f32_e32 v64, v64, v65
	ds_bpermute_b32 v65, v159, v64
	s_waitcnt lgkmcnt(0)
; __device__ __forceinline__ unsigned cvt_pk_bf16(float lo, float hi) { unsigned r; asm volatile("v_cvt_pk_bf16_f32 %0, %1, %2" : "=v"(r) : "v"(lo), "v"(hi)); return r; }
; __device__ __forceinline__ float row_ss(const float* part, int row, int fq, int nf4) {
;     const f32x4* p = (const f32x4*)(part + (size_t)row * 32);
;     float s = 0.f;
; #pragma unroll
;     for (int j = 0; j < 2; ++j) { const int idx = fq + 4 * j; if (idx < nf4) { const f32x4 v = p[idx]; s += (v[0] + v[1]) + (v[2] + v[3]); } }
;     s += __shfl_xor(s, 16); s += __shfl_xor(s, 32);
;     return s;
; }
;     __device__ __forceinline__ void operator()(const f32x4 (&acc)[2][2][4][2], const Unit& u, int wr, int wc, int fr, int fq) const {
;     ...
;             for (int m = 0; m < 4; ++m) { const int row = row0 + ai * HALF + m * 16; bf16_t* rowp = base + (size_t)row * ldc + col0;
;                 const float rs = rss ? __builtin_amdgcn_rsqf(row_ss(rss, row, fq, nf4) * rinv + 1e-6f) : 1.f;
; #pragma unroll
;                 for (int bj = 0; bj < 2; ++bj) { f32x4 v0 = acc[ai][bj][m][0] * rs + bv[bj][0], v1 = acc[ai][bj][m][1] * rs + bv[bj][1];
;                     v0 = v0 * sc; v1 = v1 * sc; u32x4 w; w.x = cvt_pk_bf16(v0[0], v0[1]); w.y = cvt_pk_bf16(v0[2], v0[3]); w.z = cvt_pk_bf16(v1[0], v1[1]); w.w = cvt_pk_bf16(v1[2], v1[3]);
;                     *(u32x4*)(rowp + bj * HALF) = w; } }
	v_add_f32_e32 v64, v64, v65
	v_fmamk_f32 v64, v64, 0x3a000000, v157
	v_rsq_f32_e32 v64, v64
	s_nop 0
	v_pk_fma_f32 v[60:61], v[60:61], v[64:65], 0 op_sel_hi:[1,0,0]
	v_pk_fma_f32 v[62:63], v[62:63], v[64:65], 0 op_sel_hi:[1,0,0]
	v_pk_fma_f32 v[56:57], v[56:57], v[64:65], 0 op_sel_hi:[1,0,0]
	v_pk_fma_f32 v[58:59], v[58:59], v[64:65], 0 op_sel_hi:[1,0,0]
	v_pk_mul_f32 v[62:63], v[146:147], v[62:63] op_sel_hi:[0,1]
	v_pk_mul_f32 v[60:61], v[146:147], v[60:61] op_sel_hi:[0,1]
	v_pk_mul_f32 v[66:67], v[146:147], v[58:59] op_sel_hi:[0,1]
	v_pk_mul_f32 v[58:59], v[146:147], v[56:57] op_sel_hi:[0,1]
	v_cvt_pk_bf16_f32 v56, v60, v61
	v_cvt_pk_bf16_f32 v57, v62, v63
	v_pk_fma_f32 v[52:53], v[52:53], v[64:65], 0 op_sel_hi:[1,0,0]
	v_pk_fma_f32 v[48:49], v[48:49], v[64:65], 0 op_sel_hi:[1,0,0]
	v_pk_fma_f32 v[50:51], v[50:51], v[64:65], 0 op_sel_hi:[1,0,0]
	v_cvt_pk_bf16_f32 v58, v58, v59
	v_cvt_pk_bf16_f32 v59, v66, v67
	global_store_dwordx4 v[72:73], v[56:59], off sc0 sc1
	v_pk_fma_f32 v[54:55], v[54:55], v[64:65], 0 op_sel_hi:[1,0,0]
	v_pk_mul_f32 v[52:53], v[146:147], v[52:53] op_sel_hi:[0,1]
	v_pk_mul_f32 v[56:57], v[146:147], v[50:51] op_sel_hi:[0,1]
	v_pk_mul_f32 v[50:51], v[146:147], v[48:49] op_sel_hi:[0,1]
	v_cvt_pk_bf16_f32 v48, v52, v53
	v_pk_mul_f32 v[54:55], v[146:147], v[54:55] op_sel_hi:[0,1]
	v_cvt_pk_bf16_f32 v49, v54, v55
	v_cvt_pk_bf16_f32 v50, v50, v51
	v_cvt_pk_bf16_f32 v51, v56, v57
	global_store_dwordx4 v[72:73], v[48:51], off offset:256 sc0 sc1
	s_nop 1
	v_add_u32_e32 v48, 0x90, v150
	v_ashrrev_i32_e32 v49, 31, v48
	v_lshlrev_b64 v[50:51], 12, v[48:49]
	v_lshlrev_b64 v[48:49], 7, v[48:49]
	v_lshl_add_u64 v[52:53], v[136:137], 0, v[48:49]
	v_lshl_add_u64 v[56:57], v[148:149], 0, v[50:51]
	global_load_dwordx4 v[48:51], v[52:53], off
	s_nop 0
	global_load_dwordx4 v[52:55], v[52:53], off offset:64
	s_waitcnt vmcnt(1)
	v_mov_b32_e32 v58, v48
	s_waitcnt vmcnt(0)
	v_mov_b32_e32 v59, v52
	v_mov_b32_e32 v52, v49
	v_pk_add_f32 v[48:49], v[58:59], v[52:53]
	v_mov_b32_e32 v52, v50
	v_mov_b32_e32 v53, v54
	v_mov_b32_e32 v54, v51
	v_pk_add_f32 v[50:51], v[52:53], v[54:55]
	s_nop 0
	v_pk_add_f32 v[48:49], v[48:49], v[50:51]
	s_nop 0
	v_add_f32_e32 v48, 0, v48
	v_add_f32_e32 v48, v48, v49
	ds_bpermute_b32 v49, v151, v48
	s_waitcnt lgkmcnt(0)
	v_add_f32_e32 v48, v48, v49
	ds_bpermute_b32 v49, v159, v48
	s_waitcnt lgkmcnt(0)
	v_add_f32_e32 v48, v48, v49
	v_fmamk_f32 v48, v48, 0x3a000000, v157
	v_rsq_f32_e32 v48, v48
	s_nop 0
	v_pk_fma_f32 v[44:45], v[44:45], v[48:49], 0 op_sel_hi:[1,0,0]
	v_pk_fma_f32 v[46:47], v[46:47], v[48:49], 0 op_sel_hi:[1,0,0]
	v_pk_fma_f32 v[40:41], v[40:41], v[48:49], 0 op_sel_hi:[1,0,0]
	v_pk_fma_f32 v[42:43], v[42:43], v[48:49], 0 op_sel_hi:[1,0,0]
	v_pk_mul_f32 v[46:47], v[146:147], v[46:47] op_sel_hi:[0,1]
	v_pk_mul_f32 v[44:45], v[146:147], v[44:45] op_sel_hi:[0,1]
	v_pk_mul_f32 v[50:51], v[146:147], v[42:43] op_sel_hi:[0,1]
	v_pk_mul_f32 v[42:43], v[146:147], v[40:41] op_sel_hi:[0,1]
	v_cvt_pk_bf16_f32 v40, v44, v45
	v_cvt_pk_bf16_f32 v41, v46, v47
	v_pk_fma_f32 v[36:37], v[36:37], v[48:49], 0 op_sel_hi:[1,0,0]
	v_pk_fma_f32 v[32:33], v[32:33], v[48:49], 0 op_sel_hi:[1,0,0]
	v_pk_fma_f32 v[34:35], v[34:35], v[48:49], 0 op_sel_hi:[1,0,0]
	v_cvt_pk_bf16_f32 v42, v42, v43
	v_cvt_pk_bf16_f32 v43, v50, v51
	global_store_dwordx4 v[56:57], v[40:43], off sc0 sc1
	v_pk_fma_f32 v[38:39], v[38:39], v[48:49], 0 op_sel_hi:[1,0,0]
	v_pk_mul_f32 v[36:37], v[146:147], v[36:37] op_sel_hi:[0,1]
	v_pk_mul_f32 v[40:41], v[146:147], v[34:35] op_sel_hi:[0,1]
	v_pk_mul_f32 v[34:35], v[146:147], v[32:33] op_sel_hi:[0,1]
	v_cvt_pk_bf16_f32 v32, v36, v37
	v_pk_mul_f32 v[38:39], v[146:147], v[38:39] op_sel_hi:[0,1]
	v_cvt_pk_bf16_f32 v33, v38, v39
	v_cvt_pk_bf16_f32 v34, v34, v35
	v_cvt_pk_bf16_f32 v35, v40, v41
	global_store_dwordx4 v[56:57], v[32:35], off offset:256 sc0 sc1
	s_nop 1
	v_add_u32_e32 v32, 0xa0, v150
	v_ashrrev_i32_e32 v33, 31, v32
	v_lshlrev_b64 v[34:35], 12, v[32:33]
	v_lshlrev_b64 v[32:33], 7, v[32:33]
	v_lshl_add_u64 v[36:37], v[136:137], 0, v[32:33]
	v_lshl_add_u64 v[40:41], v[148:149], 0, v[34:35]
	global_load_dwordx4 v[32:35], v[36:37], off
	s_nop 0
	global_load_dwordx4 v[36:39], v[36:37], off offset:64
	s_waitcnt vmcnt(1)
	v_mov_b32_e32 v42, v32
	s_waitcnt vmcnt(0)
; __device__ __forceinline__ unsigned cvt_pk_bf16(float lo, float hi) { unsigned r; asm volatile("v_cvt_pk_bf16_f32 %0, %1, %2" : "=v"(r) : "v"(lo), "v"(hi)); return r; }
; __device__ __forceinline__ float row_ss(const float* part, int row, int fq, int nf4) {
;     const f32x4* p = (const f32x4*)(part + (size_t)row * 32);
;     float s = 0.f;
; #pragma unroll
;     for (int j = 0; j < 2; ++j) { const int idx = fq + 4 * j; if (idx < nf4) { const f32x4 v = p[idx]; s += (v[0] + v[1]) + (v[2] + v[3]); } }
;     s += __shfl_xor(s, 16); s += __shfl_xor(s, 32);
;     return s;
; }
;     __device__ __forceinline__ void operator()(const f32x4 (&acc)[2][2][4][2], const Unit& u, int wr, int wc, int fr, int fq) const {
;     ...
;             for (int m = 0; m < 4; ++m) { const int row = row0 + ai * HALF + m * 16; bf16_t* rowp = base + (size_t)row * ldc + col0;
;                 const float rs = rss ? __builtin_amdgcn_rsqf(row_ss(rss, row, fq, nf4) * rinv + 1e-6f) : 1.f;
; #pragma unroll
;                 for (int bj = 0; bj < 2; ++bj) { f32x4 v0 = acc[ai][bj][m][0] * rs + bv[bj][0], v1 = acc[ai][bj][m][1] * rs + bv[bj][1];
;                     v0 = v0 * sc; v1 = v1 * sc; u32x4 w; w.x = cvt_pk_bf16(v0[0], v0[1]); w.y = cvt_pk_bf16(v0[2], v0[3]); w.z = cvt_pk_bf16(v1[0], v1[1]); w.w = cvt_pk_bf16(v1[2], v1[3]);
;                     *(u32x4*)(rowp + bj * HALF) = w; } }
	v_mov_b32_e32 v43, v36
	v_mov_b32_e32 v36, v33
	v_pk_add_f32 v[32:33], v[42:43], v[36:37]
	v_mov_b32_e32 v36, v34
	v_mov_b32_e32 v37, v38
	v_mov_b32_e32 v38, v35
	v_pk_add_f32 v[34:35], v[36:37], v[38:39]
	s_nop 0
	v_pk_add_f32 v[32:33], v[32:33], v[34:35]
	s_nop 0
	v_add_f32_e32 v32, 0, v32
	v_add_f32_e32 v32, v32, v33
	ds_bpermute_b32 v33, v151, v32
	s_waitcnt lgkmcnt(0)
	v_add_f32_e32 v32, v32, v33
	ds_bpermute_b32 v33, v159, v32
	s_waitcnt lgkmcnt(0)
	v_add_f32_e32 v32, v32, v33
	v_fmamk_f32 v32, v32, 0x3a000000, v157
	v_rsq_f32_e32 v32, v32
	s_nop 0
	v_pk_fma_f32 v[28:29], v[28:29], v[32:33], 0 op_sel_hi:[1,0,0]
	v_pk_fma_f32 v[30:31], v[30:31], v[32:33], 0 op_sel_hi:[1,0,0]
	v_pk_fma_f32 v[24:25], v[24:25], v[32:33], 0 op_sel_hi:[1,0,0]
	v_pk_fma_f32 v[26:27], v[26:27], v[32:33], 0 op_sel_hi:[1,0,0]
	v_pk_mul_f32 v[30:31], v[146:147], v[30:31] op_sel_hi:[0,1]
	v_pk_mul_f32 v[28:29], v[146:147], v[28:29] op_sel_hi:[0,1]
	v_pk_mul_f32 v[34:35], v[146:147], v[26:27] op_sel_hi:[0,1]
	v_pk_mul_f32 v[26:27], v[146:147], v[24:25] op_sel_hi:[0,1]
	v_cvt_pk_bf16_f32 v24, v28, v29
	v_cvt_pk_bf16_f32 v25, v30, v31
	v_pk_fma_f32 v[16:17], v[16:17], v[32:33], 0 op_sel_hi:[1,0,0]
	v_pk_fma_f32 v[18:19], v[18:19], v[32:33], 0 op_sel_hi:[1,0,0]
	v_cvt_pk_bf16_f32 v26, v26, v27
	v_cvt_pk_bf16_f32 v27, v34, v35
	global_store_dwordx4 v[40:41], v[24:27], off sc0 sc1
	v_pk_fma_f32 v[20:21], v[20:21], v[32:33], 0 op_sel_hi:[1,0,0]
	v_pk_fma_f32 v[22:23], v[22:23], v[32:33], 0 op_sel_hi:[1,0,0]
	v_pk_mul_f32 v[24:25], v[146:147], v[18:19] op_sel_hi:[0,1]
	v_pk_mul_f32 v[18:19], v[146:147], v[16:17] op_sel_hi:[0,1]
	v_pk_mul_f32 v[22:23], v[146:147], v[22:23] op_sel_hi:[0,1]
	v_pk_mul_f32 v[20:21], v[146:147], v[20:21] op_sel_hi:[0,1]
	v_cvt_pk_bf16_f32 v16, v20, v21
	v_cvt_pk_bf16_f32 v17, v22, v23
	v_cvt_pk_bf16_f32 v18, v18, v19
	v_cvt_pk_bf16_f32 v19, v24, v25
	v_add_u32_e32 v24, 0xb0, v150
	v_ashrrev_i32_e32 v25, 31, v24
	global_store_dwordx4 v[40:41], v[16:19], off offset:256 sc0 sc1
	s_nop 1
	v_lshlrev_b64 v[16:17], 7, v[24:25]
	v_lshl_add_u64 v[20:21], v[136:137], 0, v[16:17]
	global_load_dwordx4 v[16:19], v[20:21], off
	s_nop 0
	global_load_dwordx4 v[20:23], v[20:21], off offset:64
	s_waitcnt vmcnt(1)
	v_mov_b32_e32 v26, v16
	s_waitcnt vmcnt(0)
	v_mov_b32_e32 v27, v20
	v_mov_b32_e32 v20, v17
	v_pk_add_f32 v[16:17], v[26:27], v[20:21]
	v_mov_b32_e32 v20, v18
	v_mov_b32_e32 v21, v22
	v_mov_b32_e32 v22, v19
	v_pk_add_f32 v[18:19], v[20:21], v[22:23]
	s_nop 0
	v_pk_add_f32 v[16:17], v[16:17], v[18:19]
	v_lshlrev_b64 v[18:19], 12, v[24:25]
	v_add_f32_e32 v16, 0, v16
	v_add_f32_e32 v16, v16, v17
	ds_bpermute_b32 v17, v151, v16
	v_lshl_add_u64 v[18:19], v[148:149], 0, v[18:19]
	s_waitcnt lgkmcnt(0)
	v_add_f32_e32 v16, v16, v17
	ds_bpermute_b32 v17, v159, v16
	s_waitcnt lgkmcnt(0)
	v_add_f32_e32 v16, v16, v17
	v_fmamk_f32 v16, v16, 0x3a000000, v157
	v_rsq_f32_e32 v16, v16
	s_nop 0
	v_pk_fma_f32 v[12:13], v[12:13], v[16:17], 0 op_sel_hi:[1,0,0]
	v_pk_fma_f32 v[14:15], v[14:15], v[16:17], 0 op_sel_hi:[1,0,0]
	v_pk_fma_f32 v[8:9], v[8:9], v[16:17], 0 op_sel_hi:[1,0,0]
	v_pk_fma_f32 v[10:11], v[10:11], v[16:17], 0 op_sel_hi:[1,0,0]
	v_pk_mul_f32 v[14:15], v[146:147], v[14:15] op_sel_hi:[0,1]
	v_pk_mul_f32 v[12:13], v[146:147], v[12:13] op_sel_hi:[0,1]
	v_pk_mul_f32 v[20:21], v[146:147], v[10:11] op_sel_hi:[0,1]
	v_pk_mul_f32 v[10:11], v[146:147], v[8:9] op_sel_hi:[0,1]
	v_cvt_pk_bf16_f32 v8, v12, v13
	v_cvt_pk_bf16_f32 v9, v14, v15
	v_pk_fma_f32 v[0:1], v[0:1], v[16:17], 0 op_sel_hi:[1,0,0]
	v_pk_fma_f32 v[2:3], v[2:3], v[16:17], 0 op_sel_hi:[1,0,0]
	v_cvt_pk_bf16_f32 v10, v10, v11
	v_cvt_pk_bf16_f32 v11, v20, v21
	global_store_dwordx4 v[18:19], v[8:11], off sc0 sc1
	v_pk_fma_f32 v[4:5], v[4:5], v[16:17], 0 op_sel_hi:[1,0,0]
	v_pk_fma_f32 v[6:7], v[6:7], v[16:17], 0 op_sel_hi:[1,0,0]
	v_pk_mul_f32 v[8:9], v[146:147], v[2:3] op_sel_hi:[0,1]
	v_pk_mul_f32 v[2:3], v[146:147], v[0:1] op_sel_hi:[0,1]
	v_pk_mul_f32 v[6:7], v[146:147], v[6:7] op_sel_hi:[0,1]
	v_pk_mul_f32 v[4:5], v[146:147], v[4:5] op_sel_hi:[0,1]
	v_cvt_pk_bf16_f32 v0, v4, v5
	v_cvt_pk_bf16_f32 v1, v6, v7
	v_cvt_pk_bf16_f32 v2, v2, v3
	v_cvt_pk_bf16_f32 v3, v8, v9
	global_store_dwordx4 v[18:19], v[0:3], off offset:256 sc0 sc1
	s_cbranch_vccnz .LBB0_2507
	s_andn2_b64 vcc, exec, s[4:5]
	s_cbranch_vccnz .LBB0_2506
	s_barrier
	s_branch .LBB0_2506

; #define LAS __attribute__((address_space(3)))
; __device__ __forceinline__ unsigned cvtpk(float lo, float hi) { f32x2 v = {lo, hi}; bf16x2_t b = __builtin_convertvector(v, bf16x2_t); return __builtin_bit_cast(unsigned, b); }
; __device__ __forceinline__ void witem_store(const WItem& w, int K, bf16_t* WT, int kvperm, LAS float* scr, int item, int nblk, int lane) {
;     ...
; #pragma unroll
;     for (int i = 0; i < 8; ++i) { LAS float* d = scr + (8 * i + rr) * 33 + col; const float g = w.g[i]; d[0] = w.v[i].x * g; d[1] = w.v[i].y * g; d[2] = w.v[i].z * g; d[3] = w.v[i].w * g; }
;     asm volatile("s_waitcnt lgkmcnt(0)" ::: "memory");
;     const int c = lane & 7;
; #pragma unroll
;     for (int j = 0; j < 4; ++j) { const int n = (lane >> 3) + 8 * j; const LAS float* s = scr + (8 * c) * 33 + n;
;         u32x4 o; o.x = cvtpk(s[0 * 33], s[1 * 33]); o.y = cvtpk(s[2 * 33], s[3 * 33]); o.z = cvtpk(s[4 * 33], s[5 * 33]); o.w = cvtpk(s[6 * 33], s[7 * 33]);
;         int nr = n0 + n; if (kvperm == 1) { const int hh = nr >> 8, ww = nr & 255; nr = (ww < 128) ? hh * 128 + ww : 2048 + hh * 128 + (ww - 128); }
;         else if (kvperm == 2) { const int isv = nr >= 5632, f = isv ? nr - 5632 : nr; nr = (f >> 7) * 256 + isv * 128 + (f & 127); }
;         *(u32x4*)(WT + (size_t)nr * K + k0 + 8 * c) = o; }
;     asm volatile("s_waitcnt lgkmcnt(0)" ::: "memory");
; }
.LBB0_2538:
	ds_write2_b32 v84, v4, v5 offset1:1
	ds_write2_b32 v84, v6, v7 offset0:2 offset1:3
	v_add_u32_e32 v4, 0x420, v84
	ds_write2_b32 v4, v0, v1 offset1:1
	v_add_u32_e32 v0, 0x428, v84
	ds_write2_b32 v0, v2, v3 offset1:1
	v_add_u32_e32 v0, 0x840, v84
	ds_write2_b32 v0, v12, v13 offset1:1
	v_add_u32_e32 v0, 0x848, v84
	ds_write2_b32 v0, v14, v15 offset1:1
	v_add_u32_e32 v0, 0xc60, v84
	ds_write2_b32 v0, v8, v9 offset1:1
	v_add_u32_e32 v0, 0xc68, v84
	ds_write2_b32 v0, v10, v11 offset1:1
	v_add_u32_e32 v0, 0x1080, v84
	ds_write2_b32 v0, v24, v25 offset1:1
	v_add_u32_e32 v0, 0x1088, v84
	ds_write2_b32 v0, v26, v27 offset1:1
	v_add_u32_e32 v0, 0x14a0, v84
	ds_write2_b32 v0, v16, v17 offset1:1
	v_add_u32_e32 v0, 0x14a8, v84
	ds_write2_b32 v0, v18, v19 offset1:1
	v_add_u32_e32 v0, 0x18c0, v84
	ds_write2_b32 v0, v36, v37 offset1:1
	v_add_u32_e32 v0, 0x18c8, v84
	ds_write2_b32 v0, v38, v39 offset1:1
	v_add_u32_e32 v0, 0x1ce0, v84
	ds_write2_b32 v0, v40, v41 offset1:1
	v_add_u32_e32 v0, 0x1ce8, v84
	s_ashr_i32 s10, s13, 31
	ds_write2_b32 v0, v42, v43 offset1:1
	s_lshr_b32 s10, s10, 26
	s_waitcnt lgkmcnt(0)
	s_add_i32 s10, s13, s10
	ds_read2_b32 v[4:5], v82 offset0:33 offset1:41
	ds_read2_b32 v[6:7], v82 offset1:8
	ds_read2_b32 v[8:9], v82 offset0:66 offset1:74
	ds_read2_b32 v[10:11], v82 offset0:99 offset1:107
	ds_read2_b32 v[12:13], v82 offset0:132 offset1:140
	ds_read2_b32 v[14:15], v82 offset0:165 offset1:173
	ds_read2_b32 v[16:17], v82 offset0:198 offset1:206
	ds_read2_b32 v[18:19], v82 offset0:231 offset1:239
	s_lshr_b32 s13, s10, 6
	s_andn2_b32 s10, s10, 63
	s_mul_i32 s13, s13, 0xff500000
	s_ashr_i32 s11, s10, 31
	v_add_u32_e32 v24, s13, v83
	v_lshl_add_u64 v[22:23], s[10:11], 1, v[70:71]
	v_ashrrev_i32_e32 v25, 31, v24
	s_waitcnt lgkmcnt(6)
	v_cvt_pk_bf16_f32 v0, v6, v4
	s_waitcnt lgkmcnt(4)
	v_cvt_pk_bf16_f32 v1, v8, v10
	s_waitcnt lgkmcnt(2)
	v_cvt_pk_bf16_f32 v2, v12, v14
	s_waitcnt lgkmcnt(0)
	v_cvt_pk_bf16_f32 v3, v16, v18
	v_lshl_add_u64 v[26:27], v[24:25], 1, v[22:23]
	global_store_dwordx4 v[26:27], v[0:3], off sc0 sc1
	v_add_u32_e32 v4, 0xb000, v24
	s_mul_i32 s10, s2, 0x2c000
	v_cvt_pk_bf16_f32 v0, v7, v5
	v_cvt_pk_bf16_f32 v1, v9, v11
	v_cvt_pk_bf16_f32 v2, v13, v15
	v_cvt_pk_bf16_f32 v3, v17, v19
	ds_read2_b32 v[6:7], v82 offset0:49 offset1:57
	ds_read2_b32 v[8:9], v82 offset0:16 offset1:24
	ds_read2_b32 v[10:11], v82 offset0:82 offset1:90
	ds_read2_b32 v[12:13], v82 offset0:115 offset1:123
	ds_read2_b32 v[14:15], v82 offset0:148 offset1:156
	ds_read2_b32 v[16:17], v82 offset0:181 offset1:189
	ds_read2_b32 v[18:19], v82 offset0:214 offset1:222
	ds_read2_b32 v[26:27], v82 offset0:247 offset1:255
	v_ashrrev_i32_e32 v5, 31, v4
	v_lshl_add_u64 v[4:5], v[4:5], 1, v[22:23]
	global_store_dwordx4 v[4:5], v[0:3], off sc0 sc1
	v_add_u32_e32 v4, 0x16000, v24
	v_ashrrev_i32_e32 v5, 31, v4
	s_waitcnt lgkmcnt(6)
	v_cvt_pk_bf16_f32 v0, v8, v6
	s_waitcnt lgkmcnt(4)
	v_cvt_pk_bf16_f32 v1, v10, v12
	s_waitcnt lgkmcnt(2)
	v_cvt_pk_bf16_f32 v2, v14, v16
	s_waitcnt lgkmcnt(0)
	v_cvt_pk_bf16_f32 v3, v18, v26
	v_lshl_add_u64 v[4:5], v[4:5], 1, v[22:23]
	global_store_dwordx4 v[4:5], v[0:3], off sc0 sc1
	v_add_u32_e32 v4, 0x21000, v24
	v_ashrrev_i32_e32 v5, 31, v4
	v_cvt_pk_bf16_f32 v0, v9, v7
	v_cvt_pk_bf16_f32 v1, v11, v13
	v_cvt_pk_bf16_f32 v2, v15, v17
	v_cvt_pk_bf16_f32 v3, v19, v27
	v_lshl_add_u64 v[4:5], v[4:5], 1, v[22:23]
	global_store_dwordx4 v[4:5], v[0:3], off sc0 sc1
	s_waitcnt lgkmcnt(0)
	s_waitcnt vmcnt(4)
	v_mov_b64_e32 v[4:5], v[32:33]
	v_mov_b64_e32 v[12:13], v[44:45]
	v_mov_b64_e32 v[0:1], v[28:29]
	v_mov_b64_e32 v[8:9], v[48:49]
	v_mov_b64_e32 v[24:25], v[52:53]
	v_mov_b64_e32 v[16:17], v[56:57]
	v_mov_b64_e32 v[36:37], v[60:61]
	v_add_u32_e32 v83, s10, v83
	s_add_i32 s14, s14, s15
	s_andn2_b64 vcc, exec, s[8:9]
	s_mov_b32 s13, s16
	v_mov_b64_e32 v[6:7], v[34:35]
	v_mov_b64_e32 v[2:3], v[30:31]
	v_mov_b64_e32 v[14:15], v[46:47]
	v_mov_b64_e32 v[10:11], v[50:51]
	v_mov_b64_e32 v[26:27], v[54:55]
	v_mov_b64_e32 v[18:19], v[58:59]
	v_mov_b64_e32 v[38:39], v[62:63]
	v_mov_b32_e32 v40, v64
	v_mov_b32_e32 v41, v65
	v_mov_b32_e32 v42, v66
	v_mov_b32_e32 v43, v67
	s_cbranch_vccz .LBB0_2556

; #define LAS __attribute__((address_space(3)))
; __device__ __forceinline__ unsigned cvtpk(float lo, float hi) { f32x2 v = {lo, hi}; bf16x2_t b = __builtin_convertvector(v, bf16x2_t); return __builtin_bit_cast(unsigned, b); }
; __device__ __forceinline__ void witem_store(const WItem& w, int K, bf16_t* WT, int kvperm, LAS float* scr, int item, int nblk, int lane) {
;     ...
; #pragma unroll
;     for (int i = 0; i < 8; ++i) { LAS float* d = scr + (8 * i + rr) * 33 + col; const float g = w.g[i]; d[0] = w.v[i].x * g; d[1] = w.v[i].y * g; d[2] = w.v[i].z * g; d[3] = w.v[i].w * g; }
;     asm volatile("s_waitcnt lgkmcnt(0)" ::: "memory");
;     const int c = lane & 7;
; #pragma unroll
;     for (int j = 0; j < 4; ++j) { const int n = (lane >> 3) + 8 * j; const LAS float* s = scr + (8 * c) * 33 + n;
;         u32x4 o; o.x = cvtpk(s[0 * 33], s[1 * 33]); o.y = cvtpk(s[2 * 33], s[3 * 33]); o.z = cvtpk(s[4 * 33], s[5 * 33]); o.w = cvtpk(s[6 * 33], s[7 * 33]);
;         int nr = n0 + n; if (kvperm == 1) { const int hh = nr >> 8, ww = nr & 255; nr = (ww < 128) ? hh * 128 + ww : 2048 + hh * 128 + (ww - 128); }
;         else if (kvperm == 2) { const int isv = nr >= 5632, f = isv ? nr - 5632 : nr; nr = (f >> 7) * 256 + isv * 128 + (f & 127); }
;         *(u32x4*)(WT + (size_t)nr * K + k0 + 8 * c) = o; }
;     asm volatile("s_waitcnt lgkmcnt(0)" ::: "memory");
; }
.LBB0_2575:
	ds_write2_b32 v82, v4, v5 offset1:1
	ds_write2_b32 v82, v6, v7 offset0:2 offset1:3
	v_add_u32_e32 v4, 0x420, v82
	ds_write2_b32 v4, v0, v1 offset1:1
	v_add_u32_e32 v0, 0x428, v82
	ds_write2_b32 v0, v2, v3 offset1:1
	v_add_u32_e32 v0, 0x840, v82
	ds_write2_b32 v0, v12, v13 offset1:1
	v_add_u32_e32 v0, 0x848, v82
	ds_write2_b32 v0, v14, v15 offset1:1
	v_add_u32_e32 v0, 0xc60, v82
	ds_write2_b32 v0, v8, v9 offset1:1
	v_add_u32_e32 v0, 0xc68, v82
	ds_write2_b32 v0, v10, v11 offset1:1
	v_add_u32_e32 v0, 0x1080, v82
	ds_write2_b32 v0, v24, v25 offset1:1
	v_add_u32_e32 v0, 0x1088, v82
	ds_write2_b32 v0, v26, v27 offset1:1
	v_add_u32_e32 v0, 0x14a0, v82
	ds_write2_b32 v0, v20, v21 offset1:1
	v_add_u32_e32 v0, 0x14a8, v82
	ds_write2_b32 v0, v22, v23 offset1:1
	v_add_u32_e32 v0, 0x18c0, v82
	s_ashr_i32 s10, s15, 31
	ds_write2_b32 v0, v36, v37 offset1:1
	v_add_u32_e32 v0, 0x18c8, v82
	s_lshr_b32 s10, s10, 26
	ds_write2_b32 v0, v38, v39 offset1:1
	v_add_u32_e32 v0, 0x1ce0, v82
	s_add_i32 s15, s15, s10
	ds_write2_b32 v0, v40, v41 offset1:1
	v_add_u32_e32 v0, 0x1ce8, v82
	s_and_b32 s10, s15, 0xffffffc0
	ds_write2_b32 v0, v42, v43 offset1:1
	s_waitcnt lgkmcnt(0)
	s_ashr_i32 s11, s10, 31
	ds_read2_b32 v[4:5], v81 offset0:33 offset1:41
	ds_read2_b32 v[6:7], v81 offset1:8
	ds_read2_b32 v[8:9], v81 offset0:66 offset1:74
	ds_read2_b32 v[10:11], v81 offset0:99 offset1:107
	ds_read2_b32 v[12:13], v81 offset0:132 offset1:140
	ds_read2_b32 v[14:15], v81 offset0:165 offset1:173
	ds_read2_b32 v[18:19], v81 offset0:198 offset1:206
	ds_read2_b32 v[20:21], v81 offset0:231 offset1:239
	v_lshl_add_u64 v[22:23], s[10:11], 1, v[70:71]
	s_lshl_b32 s10, s15, 5
	s_waitcnt lgkmcnt(6)
	v_cvt_pk_bf16_f32 v0, v6, v4
	v_add_u32_e32 v4, s16, v83
	s_and_b32 s10, s10, 0xfffff800
	v_subrev_u32_e32 v24, s10, v4
	v_ashrrev_i32_e32 v25, 31, v24
	v_lshlrev_b64 v[26:27], 12, v[24:25]
	s_waitcnt lgkmcnt(4)
	v_cvt_pk_bf16_f32 v1, v8, v10
	s_waitcnt lgkmcnt(2)
	v_cvt_pk_bf16_f32 v2, v12, v14
	s_waitcnt lgkmcnt(0)
	v_cvt_pk_bf16_f32 v3, v18, v20
	v_lshl_add_u64 v[26:27], v[22:23], 0, v[26:27]
	v_add_u32_e32 v4, 8, v24
	global_store_dwordx4 v[26:27], v[0:3], off sc0 sc1
	s_waitcnt vmcnt(1)
	v_mov_b64_e32 v[36:37], v[60:61]
	v_add_u32_e32 v83, s17, v83
	v_cvt_pk_bf16_f32 v0, v7, v5
	v_ashrrev_i32_e32 v5, 31, v4
	v_cvt_pk_bf16_f32 v1, v9, v11
	v_cvt_pk_bf16_f32 v2, v13, v15
	v_cvt_pk_bf16_f32 v3, v19, v21
	v_lshlrev_b64 v[4:5], 12, v[4:5]
	ds_read2_b32 v[6:7], v81 offset0:49 offset1:57
	ds_read2_b32 v[8:9], v81 offset0:16 offset1:24
	ds_read2_b32 v[10:11], v81 offset0:82 offset1:90
	ds_read2_b32 v[12:13], v81 offset0:115 offset1:123
	ds_read2_b32 v[14:15], v81 offset0:148 offset1:156
	ds_read2_b32 v[18:19], v81 offset0:181 offset1:189
	ds_read2_b32 v[20:21], v81 offset0:214 offset1:222
	ds_read2_b32 v[26:27], v81 offset0:247 offset1:255
	v_lshl_add_u64 v[4:5], v[22:23], 0, v[4:5]
	global_store_dwordx4 v[4:5], v[0:3], off sc0 sc1
	v_add_u32_e32 v4, 16, v24
	v_ashrrev_i32_e32 v5, 31, v4
	v_lshlrev_b64 v[4:5], 12, v[4:5]
	s_waitcnt lgkmcnt(6)
	v_cvt_pk_bf16_f32 v0, v8, v6
	s_waitcnt lgkmcnt(4)
	v_cvt_pk_bf16_f32 v1, v10, v12
	s_waitcnt lgkmcnt(2)
	v_cvt_pk_bf16_f32 v2, v14, v18
	s_waitcnt lgkmcnt(0)
	v_cvt_pk_bf16_f32 v3, v20, v26
	v_lshl_add_u64 v[4:5], v[22:23], 0, v[4:5]
	global_store_dwordx4 v[4:5], v[0:3], off sc0 sc1
	v_add_u32_e32 v4, 24, v24
	v_ashrrev_i32_e32 v5, 31, v4
	v_lshlrev_b64 v[4:5], 12, v[4:5]
	v_cvt_pk_bf16_f32 v0, v9, v7
	v_cvt_pk_bf16_f32 v1, v11, v13
	v_cvt_pk_bf16_f32 v2, v15, v19
	v_cvt_pk_bf16_f32 v3, v21, v27
	v_lshl_add_u64 v[4:5], v[22:23], 0, v[4:5]
	global_store_dwordx4 v[4:5], v[0:3], off sc0 sc1
	s_waitcnt lgkmcnt(0)
	v_mov_b64_e32 v[4:5], v[32:33]
	v_mov_b64_e32 v[12:13], v[44:45]
	v_mov_b64_e32 v[0:1], v[28:29]
	v_mov_b64_e32 v[8:9], v[48:49]
	v_mov_b64_e32 v[24:25], v[52:53]
	v_mov_b64_e32 v[20:21], v[56:57]
	s_add_i32 s19, s19, s17
	v_add_u32_e32 v80, s17, v80
	s_andn2_b64 vcc, exec, s[8:9]
	s_mov_b32 s15, s20
	v_mov_b64_e32 v[6:7], v[34:35]
	v_mov_b64_e32 v[2:3], v[30:31]
	v_mov_b64_e32 v[14:15], v[46:47]
	v_mov_b64_e32 v[10:11], v[50:51]
	v_mov_b64_e32 v[26:27], v[54:55]
	v_mov_b64_e32 v[22:23], v[58:59]
	v_mov_b64_e32 v[38:39], v[62:63]
	v_mov_b32_e32 v40, v64
	v_mov_b32_e32 v41, v65
	v_mov_b32_e32 v42, v66
	v_mov_b32_e32 v43, v67
	s_cbranch_vccz .LBB0_2593

; #define LAS __attribute__((address_space(3)))
; __device__ __forceinline__ unsigned cvtpk(float lo, float hi) { f32x2 v = {lo, hi}; bf16x2_t b = __builtin_convertvector(v, bf16x2_t); return __builtin_bit_cast(unsigned, b); }
; __device__ __forceinline__ void witem_store(const WItem& w, int K, bf16_t* WT, int kvperm, LAS float* scr, int item, int nblk, int lane) {
;     ...
; #pragma unroll
;     for (int i = 0; i < 8; ++i) { LAS float* d = scr + (8 * i + rr) * 33 + col; const float g = w.g[i]; d[0] = w.v[i].x * g; d[1] = w.v[i].y * g; d[2] = w.v[i].z * g; d[3] = w.v[i].w * g; }
;     asm volatile("s_waitcnt lgkmcnt(0)" ::: "memory");
;     const int c = lane & 7;
; #pragma unroll
;     for (int j = 0; j < 4; ++j) { const int n = (lane >> 3) + 8 * j; const LAS float* s = scr + (8 * c) * 33 + n;
;         u32x4 o; o.x = cvtpk(s[0 * 33], s[1 * 33]); o.y = cvtpk(s[2 * 33], s[3 * 33]); o.z = cvtpk(s[4 * 33], s[5 * 33]); o.w = cvtpk(s[6 * 33], s[7 * 33]);
;         int nr = n0 + n; if (kvperm == 1) { const int hh = nr >> 8, ww = nr & 255; nr = (ww < 128) ? hh * 128 + ww : 2048 + hh * 128 + (ww - 128); }
;         else if (kvperm == 2) { const int isv = nr >= 5632, f = isv ? nr - 5632 : nr; nr = (f >> 7) * 256 + isv * 128 + (f & 127); }
;         *(u32x4*)(WT + (size_t)nr * K + k0 + 8 * c) = o; }
;     asm volatile("s_waitcnt lgkmcnt(0)" ::: "memory");
; }
.LBB0_2612:
	v_pk_mul_f32 v[2:3], v[16:17], v[72:73] op_sel_hi:[1,0]
	ds_write2_b32 v79, v2, v3 offset1:1
	v_pk_mul_f32 v[2:3], v[18:19], v[72:73] op_sel_hi:[1,0]
	ds_write2_b32 v79, v2, v3 offset0:2 offset1:3
	v_pk_mul_f32 v[2:3], v[4:5], v[74:75] op_sel_hi:[1,0]
	v_add_u32_e32 v4, 0x420, v79
	ds_write2_b32 v4, v2, v3 offset1:1
	v_pk_mul_f32 v[2:3], v[6:7], v[74:75] op_sel_hi:[1,0]
	v_add_u32_e32 v4, 0x428, v79
	ds_write2_b32 v4, v2, v3 offset1:1
	v_pk_mul_f32 v[2:3], v[24:25], v[76:77] op_sel_hi:[1,0]
	v_add_u32_e32 v4, 0x840, v79
	ds_write2_b32 v4, v2, v3 offset1:1
	v_pk_mul_f32 v[2:3], v[26:27], v[76:77] op_sel_hi:[1,0]
	v_add_u32_e32 v4, 0x848, v79
	ds_write2_b32 v4, v2, v3 offset1:1
	v_pk_mul_f32 v[2:3], v[20:21], v[78:79] op_sel_hi:[1,0]
	v_add_u32_e32 v4, 0xc60, v79
	ds_write2_b32 v4, v2, v3 offset1:1
	v_pk_mul_f32 v[2:3], v[22:23], v[78:79] op_sel_hi:[1,0]
	v_add_u32_e32 v4, 0xc68, v79
	ds_write2_b32 v4, v2, v3 offset1:1
	v_pk_mul_f32 v[2:3], v[36:37], v[80:81] op_sel_hi:[1,0]
	v_add_u32_e32 v4, 0x1080, v79
	ds_write2_b32 v4, v2, v3 offset1:1
	v_pk_mul_f32 v[2:3], v[38:39], v[80:81] op_sel_hi:[1,0]
	v_add_u32_e32 v4, 0x1088, v79
	ds_write2_b32 v4, v2, v3 offset1:1
	v_pk_mul_f32 v[2:3], v[32:33], v[82:83] op_sel_hi:[1,0]
	v_add_u32_e32 v4, 0x14a0, v79
	s_mul_hi_i32 s8, s12, 0x2e8ba2e9
	ds_write2_b32 v4, v2, v3 offset1:1
	v_pk_mul_f32 v[2:3], v[34:35], v[82:83] op_sel_hi:[1,0]
	v_add_u32_e32 v4, 0x14a8, v79
	s_lshr_b32 s9, s8, 31
	s_ashr_i32 s8, s8, 6
	ds_write2_b32 v4, v2, v3 offset1:1
	s_waitcnt vmcnt(7)
	v_pk_mul_f32 v[2:3], v[48:49], v[84:85] op_sel_hi:[1,0]
	v_add_u32_e32 v4, 0x18c0, v79
	s_add_i32 s12, s8, s9
	ds_write2_b32 v4, v2, v3 offset1:1
	v_pk_mul_f32 v[2:3], v[50:51], v[84:85] op_sel_hi:[1,0]
	v_add_u32_e32 v4, 0x18c8, v79
	s_lshl_b32 s8, s12, 6
	ds_write2_b32 v4, v2, v3 offset1:1
	s_waitcnt vmcnt(6)
	v_pk_mul_f32 v[2:3], v[44:45], v[86:87] op_sel_hi:[1,0]
	v_add_u32_e32 v4, 0x1ce0, v79
	ds_write2_b32 v4, v2, v3 offset1:1
	v_pk_mul_f32 v[2:3], v[46:47], v[86:87] op_sel_hi:[1,0]
	v_add_u32_e32 v4, 0x1ce8, v79
	s_ashr_i32 s9, s8, 31
	ds_write2_b32 v4, v2, v3 offset1:1
	v_lshl_add_u64 v[34:35], s[8:9], 1, v[70:71]
	s_mul_i32 s8, s12, 0xffffd400
	s_waitcnt lgkmcnt(0)
	s_add_i32 s8, s8, s3
	ds_read2_b32 v[6:7], v75 offset0:33 offset1:41
	ds_read2_b32 v[16:17], v75 offset1:8
	ds_read2_b32 v[18:19], v75 offset0:66 offset1:74
	ds_read2_b32 v[20:21], v75 offset0:99 offset1:107
	ds_read2_b32 v[22:23], v75 offset0:132 offset1:140
	ds_read2_b32 v[24:25], v75 offset0:165 offset1:173
	ds_read2_b32 v[26:27], v75 offset0:198 offset1:206
	ds_read2_b32 v[32:33], v75 offset0:231 offset1:239
	v_add_u32_e32 v38, s8, v83
	s_waitcnt lgkmcnt(6)
	v_cvt_pk_bf16_f32 v2, v16, v6
	v_add_u32_e32 v6, 0xffffea00, v38
	v_cmp_lt_i32_e32 vcc, s11, v38
	s_waitcnt lgkmcnt(4)
	v_cvt_pk_bf16_f32 v3, v18, v20
	s_waitcnt lgkmcnt(2)
	v_cvt_pk_bf16_f32 v4, v22, v24
	v_cndmask_b32_e32 v6, v38, v6, vcc
	v_lshlrev_b32_e32 v16, 1, v6
	v_and_b32_e32 v16, 0xffffff00, v16
	v_cndmask_b32_e32 v18, 0, v81, vcc
	v_and_b32_e32 v6, 0x67, v6
	v_or3_b32 v36, v6, v18, v16
	v_ashrrev_i32_e32 v37, 31, v36
	v_lshlrev_b64 v[36:37], 12, v[36:37]
	s_waitcnt lgkmcnt(0)
	v_cvt_pk_bf16_f32 v5, v26, v32
	v_lshl_add_u64 v[36:37], v[34:35], 0, v[36:37]
	v_add_u32_e32 v6, 8, v38
	global_store_dwordx4 v[36:37], v[2:5], off sc0 sc1
	v_cmp_lt_i32_e32 vcc, s11, v6
	s_waitcnt vmcnt(3)
	v_mov_b64_e32 v[48:49], v[60:61]
	v_cvt_pk_bf16_f32 v2, v17, v7
	v_add_u32_e32 v7, 0xffffea08, v38
	v_cndmask_b32_e32 v6, v6, v7, vcc
	v_lshlrev_b32_e32 v7, 1, v6
	v_and_b32_e32 v7, 0xffffff00, v7
	v_cndmask_b32_e32 v16, 0, v81, vcc
	v_and_b32_e32 v6, 0x6f, v6
	v_or3_b32 v6, v6, v16, v7
	v_ashrrev_i32_e32 v7, 31, v6
	v_lshlrev_b64 v[6:7], 12, v[6:7]
	v_cvt_pk_bf16_f32 v3, v19, v21
	v_cvt_pk_bf16_f32 v4, v23, v25
	v_cvt_pk_bf16_f32 v5, v27, v33
	v_lshl_add_u64 v[6:7], v[34:35], 0, v[6:7]
	ds_read2_b32 v[16:17], v75 offset0:16 offset1:24
	ds_read2_b32 v[18:19], v75 offset0:49 offset1:57
	ds_read2_b32 v[20:21], v75 offset0:82 offset1:90
	ds_read2_b32 v[22:23], v75 offset0:115 offset1:123
	ds_read2_b32 v[24:25], v75 offset0:148 offset1:156
	ds_read2_b32 v[26:27], v75 offset0:181 offset1:189
	ds_read2_b32 v[32:33], v75 offset0:214 offset1:222
	ds_read2_b32 v[36:37], v75 offset0:247 offset1:255
	global_store_dwordx4 v[6:7], v[2:5], off sc0 sc1
	v_add_u32_e32 v6, 16, v38
	v_add_u32_e32 v7, 0xffffea10, v38
	v_cmp_lt_i32_e32 vcc, s11, v6
	s_waitcnt lgkmcnt(6)
	v_cvt_pk_bf16_f32 v2, v16, v18
	s_waitcnt lgkmcnt(4)
	v_cvt_pk_bf16_f32 v3, v20, v22
	v_cndmask_b32_e32 v6, v6, v7, vcc
	v_lshlrev_b32_e32 v7, 1, v6
	v_and_b32_e32 v7, 0xffffff00, v7
	v_cndmask_b32_e32 v16, 0, v81, vcc
	v_and_b32_e32 v6, 0x77, v6
	v_or3_b32 v6, v6, v16, v7
	v_ashrrev_i32_e32 v7, 31, v6
	v_lshlrev_b64 v[6:7], 12, v[6:7]
	s_waitcnt lgkmcnt(2)
	v_cvt_pk_bf16_f32 v4, v24, v26
	s_waitcnt lgkmcnt(0)
	v_cvt_pk_bf16_f32 v5, v32, v36
	v_lshl_add_u64 v[6:7], v[34:35], 0, v[6:7]
	global_store_dwordx4 v[6:7], v[2:5], off sc0 sc1
	s_waitcnt vmcnt(4)
	v_mov_b64_e32 v[44:45], v[64:65]
	v_add_u32_e32 v83, s6, v83
	v_add_u32_e32 v2, 24, v38
	v_add_u32_e32 v3, 0xffffea18, v38
	v_cmp_lt_i32_e32 vcc, s11, v2
	v_cvt_pk_bf16_f32 v5, v33, v37
	v_mov_b64_e32 v[36:37], v[52:53]
	v_cndmask_b32_e32 v2, v2, v3, vcc
	v_lshlrev_b32_e32 v3, 1, v2
	v_and_b32_e32 v3, 0xffffff00, v3
	v_cndmask_b32_e32 v4, 0, v81, vcc
	v_and_b32_e32 v2, 0x7f, v2
	v_or3_b32 v6, v2, v4, v3
	v_ashrrev_i32_e32 v7, 31, v6
	v_lshlrev_b64 v[6:7], 12, v[6:7]
	v_cvt_pk_bf16_f32 v2, v17, v19
	v_cvt_pk_bf16_f32 v3, v21, v23
	v_cvt_pk_bf16_f32 v4, v25, v27
	v_lshl_add_u64 v[6:7], v[34:35], 0, v[6:7]
	global_store_dwordx4 v[6:7], v[2:5], off sc0 sc1
	s_waitcnt lgkmcnt(0)
	v_mov_b64_e32 v[18:19], v[14:15]
	v_mov_b64_e32 v[24:25], v[28:29]
	v_mov_b64_e32 v[4:5], v[8:9]
	v_mov_b64_e32 v[20:21], v[40:41]
	v_mov_b64_e32 v[32:33], v[56:57]
	s_add_i32 s13, s13, s6
	v_add_u32_e32 v73, s6, v73
	s_andn2_b64 vcc, exec, s[0:1]
	s_mov_b32 s12, s14
	v_mov_b64_e32 v[16:17], v[12:13]
	v_mov_b64_e32 v[6:7], v[10:11]
	v_mov_b64_e32 v[26:27], v[30:31]
	v_mov_b64_e32 v[22:23], v[42:43]
	v_mov_b64_e32 v[38:39], v[54:55]
	v_mov_b64_e32 v[34:35], v[58:59]
	v_mov_b64_e32 v[50:51], v[62:63]
	v_mov_b64_e32 v[46:47], v[66:67]
	v_mov_b32_e32 v72, v85
	v_mov_b32_e32 v74, v87
	v_mov_b32_e32 v76, v89
	v_mov_b32_e32 v78, v94
	v_mov_b32_e32 v80, v95
	v_mov_b32_e32 v82, v96
	v_mov_b32_e32 v84, v97
	s_waitcnt vmcnt(4)
	v_mov_b32_e32 v86, v1
	s_cbranch_vccz .LBB0_2630

; __device__ __forceinline__ unsigned cvt_pk_bf16(float lo, float hi) { unsigned r; asm volatile("v_cvt_pk_bf16_f32 %0, %1, %2" : "=v"(r) : "v"(lo), "v"(hi)); return r; }
;     __device__ __forceinline__ void operator()(const f32x4 (&acc)[2][2][4][2], const Unit& u, int wr, int wc, int fr, int fq) const {
;         const int row0 = u.pm * BM + wr * 64 + fr, col0 = u.pn * BM + wc * 32 + 8 * fq;
;         f32x4 bv[2][2];
; #pragma unroll
;         for (int bj = 0; bj < 2; ++bj)
; #pragma unroll
;             for (int n = 0; n < 2; ++n) bv[bj][n] = bias ? *(const f32x4*)(bias + col0 + bj * HALF + 4 * n) : (f32x4){0.f, 0.f, 0.f, 0.f};
;         float* ssp = ssout + (size_t)(u.pn * 4 + wc);
; #pragma unroll
;         for (int ai = 0; ai < 2; ++ai) {
;             u32x4 old[4][2];
; #pragma unroll
;             for (int m = 0; m < 4; ++m)
; #pragma unroll
;                 for (int bj = 0; bj < 2; ++bj) old[m][bj] = *(const u32x4*)(HB + (size_t)(row0 + ai * HALF + m * 16) * ldc + col0 + bj * HALF);
; #pragma unroll
;             for (int m = 0; m < 4; ++m) { const int row = row0 + ai * HALF + m * 16; float ss = 0.f;
; #pragma unroll
;                 for (int bj = 0; bj < 2; ++bj) { const u32x4 ow = old[m][bj];
;                     f32x4 v0 = (acc[ai][bj][m][0] + bv[bj][0]) * accs, v1 = (acc[ai][bj][m][1] + bv[bj][1]) * accs;
;                     v0[0] += __uint_as_float(ow.x << 16); v0[1] += __uint_as_float(ow.x & 0xffff0000u); v0[2] += __uint_as_float(ow.y << 16); v0[3] += __uint_as_float(ow.y & 0xffff0000u);
;                     v1[0] += __uint_as_float(ow.z << 16); v1[1] += __uint_as_float(ow.z & 0xffff0000u); v1[2] += __uint_as_float(ow.w << 16); v1[3] += __uint_as_float(ow.w & 0xffff0000u);
;                     ss += (v0[0] * v0[0] + v0[1] * v0[1]) + (v0[2] * v0[2] + v0[3] * v0[3]) + (v1[0] * v1[0] + v1[1] * v1[1]) + (v1[2] * v1[2] + v1[3] * v1[3]);
;                     u32x4 w; w.x = cvt_pk_bf16(v0[0], v0[1]); w.y = cvt_pk_bf16(v0[2], v0[3]); w.z = cvt_pk_bf16(v1[0], v1[1]); w.w = cvt_pk_bf16(v1[2], v1[3]);
;                     *(u32x4*)(HB + (size_t)row * ldc + col0 + bj * HALF) = w; }
;                 ss += __shfl_xor(ss, 16); ss += __shfl_xor(ss, 32);
;                 if (fq == 0) ssp[(size_t)row * 32] = ss; }
.LBB0_2849:
	v_lshl_or_b32 v152, s20, 8, v166
	v_ashrrev_i32_e32 v153, 31, v152
	v_lshl_add_u32 v156, s22, 8, v164
	v_lshlrev_b64 v[178:179], 1, v[152:153]
	v_ashrrev_i32_e32 v157, 31, v156
	v_lshl_add_u64 v[154:155], s[8:9], 0, v[178:179]
	v_lshlrev_b64 v[180:181], 12, v[156:157]
	v_lshl_add_u64 v[128:129], v[154:155], 0, v[180:181]
	global_load_dwordx4 v[170:173], v[128:129], off
	global_load_dwordx4 v[174:177], v[128:129], off offset:256
	v_or_b32_e32 v162, 16, v156
	v_or_b32_e32 v160, 32, v156
	v_or_b32_e32 v158, 48, v156
	v_ashrrev_i32_e32 v163, 31, v162
	v_ashrrev_i32_e32 v161, 31, v160
	v_pk_add_f32 v[194:195], v[114:115], 0 op_sel_hi:[1,0]
	v_pk_add_f32 v[196:197], v[112:113], 0 op_sel_hi:[1,0]
	v_ashrrev_i32_e32 v159, 31, v158
	v_lshlrev_b64 v[112:113], 12, v[162:163]
	v_lshlrev_b64 v[114:115], 12, v[160:161]
	v_pk_add_f32 v[192:193], v[116:117], 0 op_sel_hi:[1,0]
	v_lshlrev_b64 v[116:117], 12, v[158:159]
	v_lshl_add_u64 v[112:113], v[154:155], 0, v[112:113]
	v_lshl_add_u64 v[114:115], v[154:155], 0, v[114:115]
	v_pk_add_f32 v[182:183], v[126:127], 0 op_sel_hi:[1,0]
	v_pk_add_f32 v[184:185], v[124:125], 0 op_sel_hi:[1,0]
	v_pk_add_f32 v[186:187], v[122:123], 0 op_sel_hi:[1,0]
	v_pk_add_f32 v[188:189], v[120:121], 0 op_sel_hi:[1,0]
	v_pk_add_f32 v[190:191], v[118:119], 0 op_sel_hi:[1,0]
	v_lshl_add_u64 v[198:199], v[154:155], 0, v[116:117]
	global_load_dwordx4 v[132:135], v[112:113], off
	global_load_dwordx4 v[128:131], v[112:113], off offset:256
	global_load_dwordx4 v[124:127], v[114:115], off
	global_load_dwordx4 v[120:123], v[114:115], off offset:256
	global_load_dwordx4 v[116:119], v[198:199], off
	s_nop 0
	global_load_dwordx4 v[112:115], v[198:199], off offset:256
	s_lshl_b32 s2, s20, 2
	s_or_b32 s20, s2, s38
	s_ashr_i32 s21, s20, 31
	s_lshl_b64 s[20:21], s[20:21], 2
	s_add_u32 s20, s3, s20
	s_addc_u32 s21, s33, s21
	s_waitcnt vmcnt(0)
	v_lshlrev_b32_e32 v198, 16, v170
	v_and_b32_e32 v170, 0xffff0000, v170
	v_lshlrev_b32_e32 v199, 16, v171
	v_and_b32_e32 v171, 0xffff0000, v171
	v_lshlrev_b32_e32 v200, 16, v172
	v_and_b32_e32 v172, 0xffff0000, v172
	v_lshlrev_b32_e32 v203, 16, v174
	v_and_b32_e32 v174, 0xffff0000, v174
	v_lshlrev_b32_e32 v205, 16, v175
	v_and_b32_e32 v175, 0xffff0000, v175
	v_lshlrev_b32_e32 v201, 16, v173
	v_and_b32_e32 v173, 0xffff0000, v173
	v_lshlrev_b32_e32 v206, 16, v176
	v_and_b32_e32 v176, 0xffff0000, v176
	v_lshlrev_b32_e32 v207, 16, v177
	v_and_b32_e32 v177, 0xffff0000, v177
	v_add_f32_e32 v170, v185, v170
	v_add_f32_e32 v171, v183, v171
	v_add_f32_e32 v185, v189, v172
	v_add_f32_e32 v189, v193, v174
	v_add_f32_e32 v191, v191, v175
	v_add_f32_e32 v184, v184, v198
	v_add_f32_e32 v182, v182, v199
	v_add_f32_e32 v183, v188, v200
	v_add_f32_e32 v187, v187, v173
	v_add_f32_e32 v188, v192, v203
	v_add_f32_e32 v190, v190, v205
	v_add_f32_e32 v193, v197, v176
	v_add_f32_e32 v195, v195, v177
	v_mul_f32_e32 v176, v170, v170
	v_mul_f32_e32 v177, v171, v171
	v_cvt_pk_bf16_f32 v172, v184, v170
	v_cvt_pk_bf16_f32 v173, v182, v171
	v_mul_f32_e32 v170, v189, v189
	v_mul_f32_e32 v171, v191, v191
	v_fmac_f32_e32 v170, v188, v188
	v_fmac_f32_e32 v171, v190, v190
	v_add_f32_e32 v192, v196, v206
	v_add_f32_e32 v170, v170, v171
	v_mul_f32_e32 v171, v193, v193
	v_mul_f32_e32 v196, v185, v185
	v_fmac_f32_e32 v176, v184, v184
	v_fmac_f32_e32 v177, v182, v182
	v_fmac_f32_e32 v171, v192, v192
	v_add_f32_e32 v186, v186, v201
	v_add_f32_e32 v194, v194, v207
	v_mul_f32_e32 v197, v187, v187
	v_fmac_f32_e32 v196, v183, v183
	v_add_f32_e32 v176, v176, v177
	v_add_f32_e32 v170, v171, v170
	v_mul_f32_e32 v171, v195, v195
	v_fmac_f32_e32 v197, v186, v186
	v_add_f32_e32 v176, v196, v176
	v_fmac_f32_e32 v171, v194, v194
	v_add_f32_e32 v176, v197, v176
	v_add_f32_e32 v170, v171, v170
	v_add_f32_e32 v171, v176, v170
	v_and_b32_e32 v176, 64, v202
	v_xor_b32_e32 v170, 16, v202
	v_add_u32_e32 v182, 64, v176
	v_cmp_lt_i32_e32 vcc, v170, v182
	v_cvt_pk_bf16_f32 v174, v183, v185
	v_lshl_add_u64 v[176:177], s[8:9], 0, v[180:181]
	v_lshl_add_u64 v[178:179], v[176:177], 0, v[178:179]
	v_cndmask_b32_e32 v170, v202, v170, vcc
	v_lshlrev_b32_e32 v170, 2, v170
	ds_bpermute_b32 v183, v170, v171
	v_cvt_pk_bf16_f32 v175, v186, v187
	global_store_dwordx4 v[178:179], v[172:175], off sc0 sc1
	s_waitcnt lgkmcnt(0)
	s_nop 0
	v_add_f32_e32 v172, v171, v183
	v_xor_b32_e32 v171, 32, v202
	v_cmp_lt_i32_e32 vcc, v171, v182
	v_cvt_pk_bf16_f32 v174, v188, v189
	v_cvt_pk_bf16_f32 v175, v190, v191
	v_cvt_pk_bf16_f32 v176, v192, v193
	v_cvt_pk_bf16_f32 v177, v194, v195
	global_store_dwordx4 v[178:179], v[174:177], off offset:256 sc0 sc1
	s_nop 0
	v_cndmask_b32_e32 v171, v202, v171, vcc
	v_lshlrev_b32_e32 v171, 2, v171
	ds_bpermute_b32 v173, v171, v172
	s_and_saveexec_b64 s[22:23], s[6:7]
	s_cbranch_execz .LBB0_2851
	v_lshlrev_b64 v[174:175], 7, v[156:157]
	v_lshl_add_u64 v[174:175], s[20:21], 0, v[174:175]
	s_waitcnt lgkmcnt(0)
	v_add_f32_e32 v157, v172, v173
	global_store_dword v[174:175], v157, off
; __device__ __forceinline__ unsigned cvt_pk_bf16(float lo, float hi) { unsigned r; asm volatile("v_cvt_pk_bf16_f32 %0, %1, %2" : "=v"(r) : "v"(lo), "v"(hi)); return r; }
;     __device__ __forceinline__ void operator()(const f32x4 (&acc)[2][2][4][2], const Unit& u, int wr, int wc, int fr, int fq) const {
;     ...
;             for (int m = 0; m < 4; ++m) { const int row = row0 + ai * HALF + m * 16; float ss = 0.f;
; #pragma unroll
;                 for (int bj = 0; bj < 2; ++bj) { const u32x4 ow = old[m][bj];
;                     f32x4 v0 = (acc[ai][bj][m][0] + bv[bj][0]) * accs, v1 = (acc[ai][bj][m][1] + bv[bj][1]) * accs;
;                     v0[0] += __uint_as_float(ow.x << 16); v0[1] += __uint_as_float(ow.x & 0xffff0000u); v0[2] += __uint_as_float(ow.y << 16); v0[3] += __uint_as_float(ow.y & 0xffff0000u);
;                     v1[0] += __uint_as_float(ow.z << 16); v1[1] += __uint_as_float(ow.z & 0xffff0000u); v1[2] += __uint_as_float(ow.w << 16); v1[3] += __uint_as_float(ow.w & 0xffff0000u);
;                     ss += (v0[0] * v0[0] + v0[1] * v0[1]) + (v0[2] * v0[2] + v0[3] * v0[3]) + (v1[0] * v1[0] + v1[1] * v1[1]) + (v1[2] * v1[2] + v1[3] * v1[3]);
;                     u32x4 w; w.x = cvt_pk_bf16(v0[0], v0[1]); w.y = cvt_pk_bf16(v0[2], v0[3]); w.z = cvt_pk_bf16(v1[0], v1[1]); w.w = cvt_pk_bf16(v1[2], v1[3]);
;                     *(u32x4*)(HB + (size_t)row * ldc + col0 + bj * HALF) = w; }
;                 ss += __shfl_xor(ss, 16); ss += __shfl_xor(ss, 32);
;                 if (fq == 0) ssp[(size_t)row * 32] = ss; }
.LBB0_2851:
	s_or_b64 exec, exec, s[22:23]
	v_pk_add_f32 v[108:109], v[108:109], 0 op_sel_hi:[1,0]
	v_lshlrev_b32_e32 v157, 16, v132
	v_and_b32_e32 v132, 0xffff0000, v132
	v_pk_add_f32 v[110:111], v[110:111], 0 op_sel_hi:[1,0]
	v_add_f32_e32 v109, v109, v132
	v_lshlrev_b32_e32 v132, 16, v133
	v_add_f32_e32 v110, v110, v132
	v_and_b32_e32 v132, 0xffff0000, v133
	v_pk_add_f32 v[104:105], v[104:105], 0 op_sel_hi:[1,0]
	v_add_f32_e32 v111, v111, v132
	v_lshlrev_b32_e32 v132, 16, v134
	v_add_f32_e32 v132, v104, v132
	v_and_b32_e32 v104, 0xffff0000, v134
	v_pk_add_f32 v[106:107], v[106:107], 0 op_sel_hi:[1,0]
	v_add_f32_e32 v133, v105, v104
	v_lshlrev_b32_e32 v104, 16, v135
	v_add_f32_e32 v134, v106, v104
	v_and_b32_e32 v104, 0xffff0000, v135
	v_add_f32_e32 v108, v108, v157
	v_add_f32_e32 v107, v107, v104
	v_mul_f32_e32 v104, v109, v109
	v_mul_f32_e32 v105, v111, v111
	v_fmac_f32_e32 v104, v108, v108
	v_fmac_f32_e32 v105, v110, v110
	v_add_f32_e32 v104, v104, v105
	v_mul_f32_e32 v105, v133, v133
	v_fmac_f32_e32 v105, v132, v132
	v_add_f32_e32 v104, v105, v104
	v_mul_f32_e32 v105, v107, v107
	v_fmac_f32_e32 v105, v134, v134
	v_add_f32_e32 v135, v105, v104
	v_cvt_pk_bf16_f32 v104, v108, v109
	v_pk_add_f32 v[100:101], v[100:101], 0 op_sel_hi:[1,0]
	v_lshlrev_b32_e32 v108, 16, v128
	v_add_f32_e32 v100, v100, v108
	v_and_b32_e32 v108, 0xffff0000, v128
	v_pk_add_f32 v[102:103], v[102:103], 0 op_sel_hi:[1,0]
	v_add_f32_e32 v101, v101, v108
	v_lshlrev_b32_e32 v108, 16, v129
	v_add_f32_e32 v108, v102, v108
	v_and_b32_e32 v102, 0xffff0000, v129
	v_pk_add_f32 v[96:97], v[96:97], 0 op_sel_hi:[1,0]
	v_add_f32_e32 v109, v103, v102
	v_lshlrev_b32_e32 v102, 16, v130
	v_cvt_pk_bf16_f32 v105, v110, v111
	v_add_f32_e32 v110, v96, v102
	v_and_b32_e32 v96, 0xffff0000, v130
	v_pk_add_f32 v[98:99], v[98:99], 0 op_sel_hi:[1,0]
	v_add_f32_e32 v111, v97, v96
	v_lshlrev_b32_e32 v96, 16, v131
	v_add_f32_e32 v128, v98, v96
	v_and_b32_e32 v96, 0xffff0000, v131
	v_add_f32_e32 v129, v99, v96
	v_mul_f32_e32 v96, v101, v101
	v_mul_f32_e32 v97, v109, v109
	v_fmac_f32_e32 v96, v100, v100
	v_fmac_f32_e32 v97, v108, v108
	v_add_f32_e32 v96, v96, v97
	v_mul_f32_e32 v97, v111, v111
	v_fmac_f32_e32 v97, v110, v110
	v_add_f32_e32 v96, v97, v96
	v_mul_f32_e32 v97, v129, v129
	v_fmac_f32_e32 v97, v128, v128
	v_add_f32_e32 v96, v97, v96
	v_add_f32_e32 v99, v135, v96
	ds_bpermute_b32 v130, v170, v99
	s_waitcnt lgkmcnt(1)
	v_lshlrev_b64 v[172:173], 11, v[162:163]
	v_lshl_add_u64 v[96:97], v[172:173], 1, s[8:9]
	v_lshl_add_u64 v[102:103], v[152:153], 1, v[96:97]
	v_cvt_pk_bf16_f32 v106, v132, v133
	s_waitcnt lgkmcnt(0)
	v_add_f32_e32 v96, v99, v130
	ds_bpermute_b32 v97, v171, v96
	v_cvt_pk_bf16_f32 v107, v134, v107
	global_store_dwordx4 v[102:103], v[104:107], off sc0 sc1
	v_cvt_pk_bf16_f32 v98, v100, v101
	v_cvt_pk_bf16_f32 v99, v108, v109
	v_cvt_pk_bf16_f32 v100, v110, v111
	v_cvt_pk_bf16_f32 v101, v128, v129
	global_store_dwordx4 v[102:103], v[98:101], off offset:256 sc0 sc1
	s_and_saveexec_b64 s[22:23], s[6:7]
	s_cbranch_execz .LBB0_2853
	v_lshlrev_b64 v[98:99], 7, v[162:163]
	v_lshl_add_u64 v[98:99], s[20:21], 0, v[98:99]
	s_waitcnt lgkmcnt(0)
	v_add_f32_e32 v96, v96, v97
	global_store_dword v[98:99], v96, off
.LBB0_2853:
	s_or_b64 exec, exec, s[22:23]
	v_pk_add_f32 v[92:93], v[92:93], 0 op_sel_hi:[1,0]
	v_lshlrev_b32_e32 v98, 16, v124
	v_add_f32_e32 v92, v92, v98
	v_and_b32_e32 v98, 0xffff0000, v124
	v_pk_add_f32 v[94:95], v[94:95], 0 op_sel_hi:[1,0]
	v_add_f32_e32 v93, v93, v98
	v_lshlrev_b32_e32 v98, 16, v125
	v_add_f32_e32 v94, v94, v98
	v_and_b32_e32 v98, 0xffff0000, v125
	v_pk_add_f32 v[88:89], v[88:89], 0 op_sel_hi:[1,0]
	v_add_f32_e32 v95, v95, v98
	v_lshlrev_b32_e32 v98, 16, v126
	v_add_f32_e32 v98, v88, v98
	v_and_b32_e32 v88, 0xffff0000, v126
	v_pk_add_f32 v[90:91], v[90:91], 0 op_sel_hi:[1,0]
	v_add_f32_e32 v99, v89, v88
	v_lshlrev_b32_e32 v88, 16, v127
	v_add_f32_e32 v100, v90, v88
	v_and_b32_e32 v88, 0xffff0000, v127
	v_add_f32_e32 v91, v91, v88
	v_mul_f32_e32 v88, v93, v93
	v_mul_f32_e32 v89, v95, v95
	v_fmac_f32_e32 v88, v92, v92
	v_fmac_f32_e32 v89, v94, v94
	v_add_f32_e32 v88, v88, v89
	v_mul_f32_e32 v89, v99, v99
	v_fmac_f32_e32 v89, v98, v98
	v_add_f32_e32 v88, v89, v88
	v_mul_f32_e32 v89, v91, v91
	v_fmac_f32_e32 v89, v100, v100
	v_add_f32_e32 v101, v89, v88
	v_cvt_pk_bf16_f32 v88, v92, v93
	v_pk_add_f32 v[84:85], v[84:85], 0 op_sel_hi:[1,0]
	v_lshlrev_b32_e32 v92, 16, v120
	v_add_f32_e32 v84, v84, v92
	v_and_b32_e32 v92, 0xffff0000, v120
	v_pk_add_f32 v[86:87], v[86:87], 0 op_sel_hi:[1,0]
	v_add_f32_e32 v85, v85, v92
	v_lshlrev_b32_e32 v92, 16, v121
	v_add_f32_e32 v92, v86, v92
	v_and_b32_e32 v86, 0xffff0000, v121
	v_pk_add_f32 v[80:81], v[80:81], 0 op_sel_hi:[1,0]
	v_add_f32_e32 v93, v87, v86
	v_lshlrev_b32_e32 v86, 16, v122
	v_cvt_pk_bf16_f32 v89, v94, v95
	v_add_f32_e32 v94, v80, v86
	v_and_b32_e32 v80, 0xffff0000, v122
	v_pk_add_f32 v[82:83], v[82:83], 0 op_sel_hi:[1,0]
	v_add_f32_e32 v95, v81, v80
	v_lshlrev_b32_e32 v80, 16, v123
	v_cvt_pk_bf16_f32 v90, v98, v99
	v_add_f32_e32 v98, v82, v80
	v_and_b32_e32 v80, 0xffff0000, v123
	v_add_f32_e32 v99, v83, v80
	v_mul_f32_e32 v80, v85, v85
	v_mul_f32_e32 v81, v93, v93
	v_fmac_f32_e32 v80, v84, v84
	v_fmac_f32_e32 v81, v92, v92
	v_add_f32_e32 v80, v80, v81
	v_mul_f32_e32 v81, v95, v95
	v_fmac_f32_e32 v81, v94, v94
	v_add_f32_e32 v80, v81, v80
	v_mul_f32_e32 v81, v99, v99
	v_fmac_f32_e32 v81, v98, v98
	v_add_f32_e32 v80, v81, v80
	v_add_f32_e32 v83, v101, v80
	v_cvt_pk_bf16_f32 v91, v100, v91
	ds_bpermute_b32 v100, v170, v83
	s_waitcnt lgkmcnt(1)
	v_lshlrev_b64 v[96:97], 11, v[160:161]
	v_lshl_add_u64 v[80:81], v[96:97], 1, s[8:9]
	v_lshl_add_u64 v[86:87], v[152:153], 1, v[80:81]
	global_store_dwordx4 v[86:87], v[88:91], off sc0 sc1
	s_waitcnt lgkmcnt(0)
	v_add_f32_e32 v80, v83, v100
	ds_bpermute_b32 v81, v171, v80
	v_cvt_pk_bf16_f32 v82, v84, v85
	v_cvt_pk_bf16_f32 v83, v92, v93
	v_cvt_pk_bf16_f32 v84, v94, v95
	v_cvt_pk_bf16_f32 v85, v98, v99
	global_store_dwordx4 v[86:87], v[82:85], off offset:256 sc0 sc1
	s_and_saveexec_b64 s[22:23], s[6:7]
	s_cbranch_execz .LBB0_2855
	v_lshlrev_b64 v[82:83], 7, v[160:161]
	v_lshl_add_u64 v[82:83], s[20:21], 0, v[82:83]
	s_waitcnt lgkmcnt(0)
	v_add_f32_e32 v80, v80, v81
	global_store_dword v[82:83], v80, off
; __device__ __forceinline__ unsigned cvt_pk_bf16(float lo, float hi) { unsigned r; asm volatile("v_cvt_pk_bf16_f32 %0, %1, %2" : "=v"(r) : "v"(lo), "v"(hi)); return r; }
;     __device__ __forceinline__ void operator()(const f32x4 (&acc)[2][2][4][2], const Unit& u, int wr, int wc, int fr, int fq) const {
;     ...
;         for (int ai = 0; ai < 2; ++ai) {
;             u32x4 old[4][2];
; #pragma unroll
;             for (int m = 0; m < 4; ++m)
; #pragma unroll
;                 for (int bj = 0; bj < 2; ++bj) old[m][bj] = *(const u32x4*)(HB + (size_t)(row0 + ai * HALF + m * 16) * ldc + col0 + bj * HALF);
; #pragma unroll
;             for (int m = 0; m < 4; ++m) { const int row = row0 + ai * HALF + m * 16; float ss = 0.f;
; #pragma unroll
;                 for (int bj = 0; bj < 2; ++bj) { const u32x4 ow = old[m][bj];
;                     f32x4 v0 = (acc[ai][bj][m][0] + bv[bj][0]) * accs, v1 = (acc[ai][bj][m][1] + bv[bj][1]) * accs;
;                     v0[0] += __uint_as_float(ow.x << 16); v0[1] += __uint_as_float(ow.x & 0xffff0000u); v0[2] += __uint_as_float(ow.y << 16); v0[3] += __uint_as_float(ow.y & 0xffff0000u);
;                     v1[0] += __uint_as_float(ow.z << 16); v1[1] += __uint_as_float(ow.z & 0xffff0000u); v1[2] += __uint_as_float(ow.w << 16); v1[3] += __uint_as_float(ow.w & 0xffff0000u);
;                     ss += (v0[0] * v0[0] + v0[1] * v0[1]) + (v0[2] * v0[2] + v0[3] * v0[3]) + (v1[0] * v1[0] + v1[1] * v1[1]) + (v1[2] * v1[2] + v1[3] * v1[3]);
;                     u32x4 w; w.x = cvt_pk_bf16(v0[0], v0[1]); w.y = cvt_pk_bf16(v0[2], v0[3]); w.z = cvt_pk_bf16(v1[0], v1[1]); w.w = cvt_pk_bf16(v1[2], v1[3]);
;                     *(u32x4*)(HB + (size_t)row * ldc + col0 + bj * HALF) = w; }
;                 ss += __shfl_xor(ss, 16); ss += __shfl_xor(ss, 32);
;                 if (fq == 0) ssp[(size_t)row * 32] = ss; }
.LBB0_2855:
	s_or_b64 exec, exec, s[22:23]
	v_pk_add_f32 v[76:77], v[76:77], 0 op_sel_hi:[1,0]
	v_lshlrev_b32_e32 v82, 16, v116
	v_add_f32_e32 v76, v76, v82
	v_and_b32_e32 v82, 0xffff0000, v116
	v_pk_add_f32 v[78:79], v[78:79], 0 op_sel_hi:[1,0]
	v_add_f32_e32 v77, v77, v82
	v_lshlrev_b32_e32 v82, 16, v117
	v_add_f32_e32 v78, v78, v82
	v_and_b32_e32 v82, 0xffff0000, v117
	v_pk_add_f32 v[72:73], v[72:73], 0 op_sel_hi:[1,0]
	v_add_f32_e32 v79, v79, v82
	v_lshlrev_b32_e32 v82, 16, v118
	v_add_f32_e32 v82, v72, v82
	v_and_b32_e32 v72, 0xffff0000, v118
	v_pk_add_f32 v[74:75], v[74:75], 0 op_sel_hi:[1,0]
	v_add_f32_e32 v83, v73, v72
	v_lshlrev_b32_e32 v72, 16, v119
	v_add_f32_e32 v84, v74, v72
	v_and_b32_e32 v72, 0xffff0000, v119
	v_add_f32_e32 v75, v75, v72
	v_mul_f32_e32 v72, v77, v77
	v_mul_f32_e32 v73, v79, v79
	v_fmac_f32_e32 v72, v76, v76
	v_fmac_f32_e32 v73, v78, v78
	v_add_f32_e32 v72, v72, v73
	v_mul_f32_e32 v73, v83, v83
	v_fmac_f32_e32 v73, v82, v82
	v_add_f32_e32 v72, v73, v72
	v_mul_f32_e32 v73, v75, v75
	v_fmac_f32_e32 v73, v84, v84
	v_add_f32_e32 v85, v73, v72
	v_cvt_pk_bf16_f32 v72, v76, v77
	v_pk_add_f32 v[68:69], v[68:69], 0 op_sel_hi:[1,0]
	v_lshlrev_b32_e32 v76, 16, v112
	v_add_f32_e32 v68, v68, v76
	v_and_b32_e32 v76, 0xffff0000, v112
	v_pk_add_f32 v[70:71], v[70:71], 0 op_sel_hi:[1,0]
	v_add_f32_e32 v69, v69, v76
	v_lshlrev_b32_e32 v76, 16, v113
	v_add_f32_e32 v76, v70, v76
	v_and_b32_e32 v70, 0xffff0000, v113
	v_pk_add_f32 v[64:65], v[64:65], 0 op_sel_hi:[1,0]
	v_add_f32_e32 v77, v71, v70
	v_lshlrev_b32_e32 v70, 16, v114
	v_cvt_pk_bf16_f32 v73, v78, v79
	v_add_f32_e32 v78, v64, v70
	v_and_b32_e32 v64, 0xffff0000, v114
	v_pk_add_f32 v[66:67], v[66:67], 0 op_sel_hi:[1,0]
	v_add_f32_e32 v79, v65, v64
	v_lshlrev_b32_e32 v64, 16, v115
	v_cvt_pk_bf16_f32 v74, v82, v83
	v_add_f32_e32 v82, v66, v64
	v_and_b32_e32 v64, 0xffff0000, v115
	v_add_f32_e32 v83, v67, v64
	v_mul_f32_e32 v64, v69, v69
	v_mul_f32_e32 v65, v77, v77
	v_fmac_f32_e32 v64, v68, v68
	v_fmac_f32_e32 v65, v76, v76
	v_add_f32_e32 v64, v64, v65
	v_mul_f32_e32 v65, v79, v79
	v_fmac_f32_e32 v65, v78, v78
	v_add_f32_e32 v64, v65, v64
	v_mul_f32_e32 v65, v83, v83
	v_fmac_f32_e32 v65, v82, v82
	v_add_f32_e32 v64, v65, v64
	v_add_f32_e32 v67, v85, v64
	v_cvt_pk_bf16_f32 v75, v84, v75
	ds_bpermute_b32 v84, v170, v67
	s_waitcnt lgkmcnt(1)
	v_lshlrev_b64 v[80:81], 11, v[158:159]
	v_lshl_add_u64 v[64:65], v[80:81], 1, s[8:9]
	v_lshl_add_u64 v[70:71], v[152:153], 1, v[64:65]
	global_store_dwordx4 v[70:71], v[72:75], off sc0 sc1
	s_waitcnt lgkmcnt(0)
	v_add_f32_e32 v64, v67, v84
	ds_bpermute_b32 v65, v171, v64
	v_cvt_pk_bf16_f32 v66, v68, v69
	v_cvt_pk_bf16_f32 v67, v76, v77
	v_cvt_pk_bf16_f32 v68, v78, v79
	v_cvt_pk_bf16_f32 v69, v82, v83
	global_store_dwordx4 v[70:71], v[66:69], off offset:256 sc0 sc1
	s_and_saveexec_b64 s[22:23], s[6:7]
	s_cbranch_execz .LBB0_2857
	v_lshlrev_b64 v[66:67], 7, v[158:159]
	v_lshl_add_u64 v[66:67], s[20:21], 0, v[66:67]
	s_waitcnt lgkmcnt(0)
	v_add_f32_e32 v64, v64, v65
	global_store_dword v[66:67], v64, off
.LBB0_2857:
	s_or_b64 exec, exec, s[22:23]
	v_add_u32_e32 v98, 0x80, v156
	v_ashrrev_i32_e32 v99, 31, v98
	v_lshlrev_b64 v[104:105], 12, v[98:99]
	s_waitcnt lgkmcnt(0)
	v_lshl_add_u64 v[64:65], v[154:155], 0, v[104:105]
	global_load_dwordx4 v[100:103], v[64:65], off
	global_load_dwordx4 v[88:91], v[64:65], off offset:256
	v_add_u32_e32 v96, 0x90, v156
	v_ashrrev_i32_e32 v97, 31, v96
	v_lshlrev_b64 v[64:65], 12, v[96:97]
	v_add_u32_e32 v94, 0xa0, v156
	v_lshl_add_u64 v[64:65], v[154:155], 0, v[64:65]
	v_ashrrev_i32_e32 v95, 31, v94
	global_load_dwordx4 v[84:87], v[64:65], off
	global_load_dwordx4 v[80:83], v[64:65], off offset:256
	v_lshlrev_b64 v[64:65], 12, v[94:95]
	v_add_u32_e32 v92, 0xb0, v156
	v_lshl_add_u64 v[64:65], v[154:155], 0, v[64:65]
	v_ashrrev_i32_e32 v93, 31, v92
	global_load_dwordx4 v[76:79], v[64:65], off
	global_load_dwordx4 v[72:75], v[64:65], off offset:256
	v_lshlrev_b64 v[64:65], 12, v[92:93]
	v_lshl_add_u64 v[64:65], v[154:155], 0, v[64:65]
	global_load_dwordx4 v[68:71], v[64:65], off
	s_nop 0
	global_load_dwordx4 v[64:67], v[64:65], off offset:256
	v_pk_add_f32 v[60:61], v[60:61], 0 op_sel_hi:[1,0]
	v_pk_add_f32 v[62:63], v[62:63], 0 op_sel_hi:[1,0]
	v_pk_add_f32 v[56:57], v[56:57], 0 op_sel_hi:[1,0]
	v_pk_add_f32 v[58:59], v[58:59], 0 op_sel_hi:[1,0]
	v_pk_add_f32 v[52:53], v[52:53], 0 op_sel_hi:[1,0]
	v_pk_add_f32 v[54:55], v[54:55], 0 op_sel_hi:[1,0]
	v_pk_add_f32 v[48:49], v[48:49], 0 op_sel_hi:[1,0]
	v_pk_add_f32 v[50:51], v[50:51], 0 op_sel_hi:[1,0]
	s_waitcnt vmcnt(7)
	v_lshlrev_b32_e32 v106, 16, v100
	v_and_b32_e32 v100, 0xffff0000, v100
	v_add_f32_e32 v61, v61, v100
	v_lshlrev_b32_e32 v100, 16, v101
	v_add_f32_e32 v62, v62, v100
	v_and_b32_e32 v100, 0xffff0000, v101
	v_add_f32_e32 v63, v63, v100
	v_lshlrev_b32_e32 v100, 16, v102
	v_add_f32_e32 v56, v56, v100
	v_and_b32_e32 v100, 0xffff0000, v102
	v_add_f32_e32 v57, v57, v100
	v_lshlrev_b32_e32 v100, 16, v103
	v_add_f32_e32 v100, v58, v100
	v_and_b32_e32 v58, 0xffff0000, v103
	v_add_f32_e32 v60, v60, v106
	v_add_f32_e32 v101, v59, v58
	v_mul_f32_e32 v58, v61, v61
	v_mul_f32_e32 v59, v63, v63
	v_fmac_f32_e32 v58, v60, v60
	v_fmac_f32_e32 v59, v62, v62
	v_add_f32_e32 v58, v58, v59
	v_mul_f32_e32 v59, v57, v57
	v_fmac_f32_e32 v59, v56, v56
	v_add_f32_e32 v58, v59, v58
	v_mul_f32_e32 v59, v101, v101
	v_fmac_f32_e32 v59, v100, v100
	v_add_f32_e32 v102, v59, v58
	v_cvt_pk_bf16_f32 v58, v60, v61
	v_cvt_pk_bf16_f32 v59, v62, v63
	v_cvt_pk_bf16_f32 v60, v56, v57
	v_lshl_add_u64 v[56:57], s[8:9], 0, v[104:105]
	v_lshl_add_u64 v[56:57], v[152:153], 1, v[56:57]
	v_cvt_pk_bf16_f32 v61, v100, v101
	global_store_dwordx4 v[56:57], v[58:61], off sc0 sc1
	s_waitcnt vmcnt(7)
	s_nop 0
	v_lshlrev_b32_e32 v58, 16, v88
	v_add_f32_e32 v52, v52, v58
	v_and_b32_e32 v58, 0xffff0000, v88
	v_add_f32_e32 v53, v53, v58
	v_lshlrev_b32_e32 v58, 16, v89
	v_add_f32_e32 v54, v54, v58
	v_and_b32_e32 v58, 0xffff0000, v89
	v_add_f32_e32 v55, v55, v58
	v_lshlrev_b32_e32 v58, 16, v90
	v_add_f32_e32 v58, v48, v58
	v_and_b32_e32 v48, 0xffff0000, v90
	v_add_f32_e32 v59, v49, v48
	v_lshlrev_b32_e32 v48, 16, v91
	v_add_f32_e32 v60, v50, v48
	v_and_b32_e32 v48, 0xffff0000, v91
	v_add_f32_e32 v51, v51, v48
	v_mul_f32_e32 v48, v53, v53
	v_mul_f32_e32 v49, v55, v55
	v_fmac_f32_e32 v48, v52, v52
	v_fmac_f32_e32 v49, v54, v54
	v_add_f32_e32 v48, v48, v49
	v_mul_f32_e32 v49, v59, v59
	v_fmac_f32_e32 v49, v58, v58
	v_add_f32_e32 v48, v49, v48
	v_mul_f32_e32 v49, v51, v51
	v_fmac_f32_e32 v49, v60, v60
	v_add_f32_e32 v48, v49, v48
	v_add_f32_e32 v61, v102, v48
	v_cvt_pk_bf16_f32 v48, v52, v53
	v_cvt_pk_bf16_f32 v49, v54, v55
	v_cvt_pk_bf16_f32 v50, v58, v59
	v_cvt_pk_bf16_f32 v51, v60, v51
	global_store_dwordx4 v[56:57], v[48:51], off offset:256 sc0 sc1
	ds_bpermute_b32 v48, v170, v61
	s_waitcnt lgkmcnt(0)
	v_add_f32_e32 v48, v61, v48
	ds_bpermute_b32 v49, v171, v48
	s_and_saveexec_b64 s[22:23], s[6:7]
	s_cbranch_execz .LBB0_2859
; __device__ __forceinline__ unsigned cvt_pk_bf16(float lo, float hi) { unsigned r; asm volatile("v_cvt_pk_bf16_f32 %0, %1, %2" : "=v"(r) : "v"(lo), "v"(hi)); return r; }
;     __device__ __forceinline__ void operator()(const f32x4 (&acc)[2][2][4][2], const Unit& u, int wr, int wc, int fr, int fq) const {
;     ...
;             for (int m = 0; m < 4; ++m) { const int row = row0 + ai * HALF + m * 16; float ss = 0.f;
; #pragma unroll
;                 for (int bj = 0; bj < 2; ++bj) { const u32x4 ow = old[m][bj];
;                     f32x4 v0 = (acc[ai][bj][m][0] + bv[bj][0]) * accs, v1 = (acc[ai][bj][m][1] + bv[bj][1]) * accs;
;                     v0[0] += __uint_as_float(ow.x << 16); v0[1] += __uint_as_float(ow.x & 0xffff0000u); v0[2] += __uint_as_float(ow.y << 16); v0[3] += __uint_as_float(ow.y & 0xffff0000u);
;                     v1[0] += __uint_as_float(ow.z << 16); v1[1] += __uint_as_float(ow.z & 0xffff0000u); v1[2] += __uint_as_float(ow.w << 16); v1[3] += __uint_as_float(ow.w & 0xffff0000u);
;                     ss += (v0[0] * v0[0] + v0[1] * v0[1]) + (v0[2] * v0[2] + v0[3] * v0[3]) + (v1[0] * v1[0] + v1[1] * v1[1]) + (v1[2] * v1[2] + v1[3] * v1[3]);
;                     u32x4 w; w.x = cvt_pk_bf16(v0[0], v0[1]); w.y = cvt_pk_bf16(v0[2], v0[3]); w.z = cvt_pk_bf16(v1[0], v1[1]); w.w = cvt_pk_bf16(v1[2], v1[3]);
;                     *(u32x4*)(HB + (size_t)row * ldc + col0 + bj * HALF) = w; }
;                 ss += __shfl_xor(ss, 16); ss += __shfl_xor(ss, 32);
;                 if (fq == 0) ssp[(size_t)row * 32] = ss; }
	v_lshlrev_b64 v[50:51], 7, v[98:99]
	v_lshl_add_u64 v[50:51], s[20:21], 0, v[50:51]
	s_waitcnt lgkmcnt(0)
	v_add_f32_e32 v48, v48, v49
	global_store_dword v[50:51], v48, off
.LBB0_2859:
	s_or_b64 exec, exec, s[22:23]
	v_pk_add_f32 v[44:45], v[44:45], 0 op_sel_hi:[1,0]
	s_waitcnt vmcnt(7)
	v_lshlrev_b32_e32 v50, 16, v84
	v_add_f32_e32 v44, v44, v50
	v_and_b32_e32 v50, 0xffff0000, v84
	v_pk_add_f32 v[46:47], v[46:47], 0 op_sel_hi:[1,0]
	v_add_f32_e32 v45, v45, v50
	v_lshlrev_b32_e32 v50, 16, v85
	v_add_f32_e32 v46, v46, v50
	v_and_b32_e32 v50, 0xffff0000, v85
	v_pk_add_f32 v[40:41], v[40:41], 0 op_sel_hi:[1,0]
	v_add_f32_e32 v47, v47, v50
	v_lshlrev_b32_e32 v50, 16, v86
	v_add_f32_e32 v50, v40, v50
	v_and_b32_e32 v40, 0xffff0000, v86
	v_pk_add_f32 v[42:43], v[42:43], 0 op_sel_hi:[1,0]
	v_add_f32_e32 v51, v41, v40
	v_lshlrev_b32_e32 v40, 16, v87
	v_add_f32_e32 v52, v42, v40
	v_and_b32_e32 v40, 0xffff0000, v87
	v_add_f32_e32 v43, v43, v40
	v_mul_f32_e32 v40, v45, v45
	v_mul_f32_e32 v41, v47, v47
	v_fmac_f32_e32 v40, v44, v44
	v_fmac_f32_e32 v41, v46, v46
	v_add_f32_e32 v40, v40, v41
	v_mul_f32_e32 v41, v51, v51
	v_fmac_f32_e32 v41, v50, v50
	v_add_f32_e32 v40, v41, v40
	v_mul_f32_e32 v41, v43, v43
	v_fmac_f32_e32 v41, v52, v52
	v_add_f32_e32 v53, v41, v40
	v_cvt_pk_bf16_f32 v40, v44, v45
	v_pk_add_f32 v[36:37], v[36:37], 0 op_sel_hi:[1,0]
	s_waitcnt vmcnt(6)
	v_lshlrev_b32_e32 v44, 16, v80
	v_add_f32_e32 v36, v36, v44
	v_and_b32_e32 v44, 0xffff0000, v80
	v_pk_add_f32 v[38:39], v[38:39], 0 op_sel_hi:[1,0]
	v_add_f32_e32 v37, v37, v44
	v_lshlrev_b32_e32 v44, 16, v81
	v_add_f32_e32 v44, v38, v44
	v_and_b32_e32 v38, 0xffff0000, v81
	v_pk_add_f32 v[32:33], v[32:33], 0 op_sel_hi:[1,0]
	v_add_f32_e32 v45, v39, v38
	v_lshlrev_b32_e32 v38, 16, v82
	v_cvt_pk_bf16_f32 v41, v46, v47
	v_add_f32_e32 v46, v32, v38
	v_and_b32_e32 v32, 0xffff0000, v82
	v_pk_add_f32 v[34:35], v[34:35], 0 op_sel_hi:[1,0]
	v_add_f32_e32 v47, v33, v32
	v_lshlrev_b32_e32 v32, 16, v83
	v_cvt_pk_bf16_f32 v42, v50, v51
	v_add_f32_e32 v50, v34, v32
	v_and_b32_e32 v32, 0xffff0000, v83
	v_add_f32_e32 v51, v35, v32
	v_mul_f32_e32 v32, v37, v37
	v_mul_f32_e32 v33, v45, v45
	v_fmac_f32_e32 v32, v36, v36
	v_fmac_f32_e32 v33, v44, v44
	v_add_f32_e32 v32, v32, v33
	v_mul_f32_e32 v33, v47, v47
	v_fmac_f32_e32 v33, v46, v46
	v_add_f32_e32 v32, v33, v32
	v_mul_f32_e32 v33, v51, v51
	v_fmac_f32_e32 v33, v50, v50
	v_add_f32_e32 v32, v33, v32
	v_add_f32_e32 v35, v53, v32
	v_cvt_pk_bf16_f32 v43, v52, v43
	ds_bpermute_b32 v52, v170, v35
	s_waitcnt lgkmcnt(1)
	v_lshlrev_b64 v[48:49], 11, v[96:97]
	v_lshl_add_u64 v[32:33], v[48:49], 1, s[8:9]
	v_lshl_add_u64 v[38:39], v[152:153], 1, v[32:33]
	global_store_dwordx4 v[38:39], v[40:43], off sc0 sc1
	s_waitcnt lgkmcnt(0)
	v_add_f32_e32 v32, v35, v52
	ds_bpermute_b32 v33, v171, v32
	v_cvt_pk_bf16_f32 v34, v36, v37
	v_cvt_pk_bf16_f32 v35, v44, v45
	v_cvt_pk_bf16_f32 v36, v46, v47
	v_cvt_pk_bf16_f32 v37, v50, v51
	global_store_dwordx4 v[38:39], v[34:37], off offset:256 sc0 sc1
	s_and_saveexec_b64 s[22:23], s[6:7]
	s_cbranch_execz .LBB0_2861
	v_lshlrev_b64 v[34:35], 7, v[96:97]
	v_lshl_add_u64 v[34:35], s[20:21], 0, v[34:35]
	s_waitcnt lgkmcnt(0)
	v_add_f32_e32 v32, v32, v33
	global_store_dword v[34:35], v32, off
; __device__ __forceinline__ unsigned cvt_pk_bf16(float lo, float hi) { unsigned r; asm volatile("v_cvt_pk_bf16_f32 %0, %1, %2" : "=v"(r) : "v"(lo), "v"(hi)); return r; }
;     __device__ __forceinline__ void operator()(const f32x4 (&acc)[2][2][4][2], const Unit& u, int wr, int wc, int fr, int fq) const {
;     ...
;             for (int m = 0; m < 4; ++m) { const int row = row0 + ai * HALF + m * 16; float ss = 0.f;
; #pragma unroll
;                 for (int bj = 0; bj < 2; ++bj) { const u32x4 ow = old[m][bj];
;                     f32x4 v0 = (acc[ai][bj][m][0] + bv[bj][0]) * accs, v1 = (acc[ai][bj][m][1] + bv[bj][1]) * accs;
;                     v0[0] += __uint_as_float(ow.x << 16); v0[1] += __uint_as_float(ow.x & 0xffff0000u); v0[2] += __uint_as_float(ow.y << 16); v0[3] += __uint_as_float(ow.y & 0xffff0000u);
;                     v1[0] += __uint_as_float(ow.z << 16); v1[1] += __uint_as_float(ow.z & 0xffff0000u); v1[2] += __uint_as_float(ow.w << 16); v1[3] += __uint_as_float(ow.w & 0xffff0000u);
;                     ss += (v0[0] * v0[0] + v0[1] * v0[1]) + (v0[2] * v0[2] + v0[3] * v0[3]) + (v1[0] * v1[0] + v1[1] * v1[1]) + (v1[2] * v1[2] + v1[3] * v1[3]);
;                     u32x4 w; w.x = cvt_pk_bf16(v0[0], v0[1]); w.y = cvt_pk_bf16(v0[2], v0[3]); w.z = cvt_pk_bf16(v1[0], v1[1]); w.w = cvt_pk_bf16(v1[2], v1[3]);
;                     *(u32x4*)(HB + (size_t)row * ldc + col0 + bj * HALF) = w; }
;                 ss += __shfl_xor(ss, 16); ss += __shfl_xor(ss, 32);
;                 if (fq == 0) ssp[(size_t)row * 32] = ss; }
.LBB0_2861:
	s_or_b64 exec, exec, s[22:23]
	v_pk_add_f32 v[28:29], v[28:29], 0 op_sel_hi:[1,0]
	s_waitcnt vmcnt(7)
	v_lshlrev_b32_e32 v34, 16, v76
	v_add_f32_e32 v28, v28, v34
	v_and_b32_e32 v34, 0xffff0000, v76
	v_pk_add_f32 v[30:31], v[30:31], 0 op_sel_hi:[1,0]
	v_add_f32_e32 v29, v29, v34
	v_lshlrev_b32_e32 v34, 16, v77
	v_add_f32_e32 v30, v30, v34
	v_and_b32_e32 v34, 0xffff0000, v77
	v_pk_add_f32 v[24:25], v[24:25], 0 op_sel_hi:[1,0]
	v_add_f32_e32 v31, v31, v34
	v_lshlrev_b32_e32 v34, 16, v78
	v_add_f32_e32 v34, v24, v34
	v_and_b32_e32 v24, 0xffff0000, v78
	v_pk_add_f32 v[26:27], v[26:27], 0 op_sel_hi:[1,0]
	v_add_f32_e32 v35, v25, v24
	v_lshlrev_b32_e32 v24, 16, v79
	v_add_f32_e32 v36, v26, v24
	v_and_b32_e32 v24, 0xffff0000, v79
	v_add_f32_e32 v27, v27, v24
	v_mul_f32_e32 v24, v29, v29
	v_mul_f32_e32 v25, v31, v31
	v_fmac_f32_e32 v24, v28, v28
	v_fmac_f32_e32 v25, v30, v30
	v_add_f32_e32 v24, v24, v25
	v_mul_f32_e32 v25, v35, v35
	v_fmac_f32_e32 v25, v34, v34
	v_add_f32_e32 v24, v25, v24
	v_mul_f32_e32 v25, v27, v27
	v_fmac_f32_e32 v25, v36, v36
	v_add_f32_e32 v37, v25, v24
	v_cvt_pk_bf16_f32 v24, v28, v29
	v_pk_add_f32 v[20:21], v[20:21], 0 op_sel_hi:[1,0]
	s_waitcnt vmcnt(6)
	v_lshlrev_b32_e32 v28, 16, v72
	v_add_f32_e32 v20, v20, v28
	v_and_b32_e32 v28, 0xffff0000, v72
	v_pk_add_f32 v[22:23], v[22:23], 0 op_sel_hi:[1,0]
	v_add_f32_e32 v21, v21, v28
	v_lshlrev_b32_e32 v28, 16, v73
	v_add_f32_e32 v28, v22, v28
	v_and_b32_e32 v22, 0xffff0000, v73
	v_pk_add_f32 v[16:17], v[16:17], 0 op_sel_hi:[1,0]
	v_add_f32_e32 v29, v23, v22
	v_lshlrev_b32_e32 v22, 16, v74
	v_cvt_pk_bf16_f32 v25, v30, v31
	v_add_f32_e32 v30, v16, v22
	v_and_b32_e32 v16, 0xffff0000, v74
	v_pk_add_f32 v[18:19], v[18:19], 0 op_sel_hi:[1,0]
	v_add_f32_e32 v31, v17, v16
	v_lshlrev_b32_e32 v16, 16, v75
	v_cvt_pk_bf16_f32 v26, v34, v35
	v_add_f32_e32 v34, v18, v16
	v_and_b32_e32 v16, 0xffff0000, v75
	v_add_f32_e32 v35, v19, v16
	v_mul_f32_e32 v16, v21, v21
	v_mul_f32_e32 v17, v29, v29
	v_fmac_f32_e32 v16, v20, v20
	v_fmac_f32_e32 v17, v28, v28
	v_add_f32_e32 v16, v16, v17
	v_mul_f32_e32 v17, v31, v31
	v_fmac_f32_e32 v17, v30, v30
	v_add_f32_e32 v16, v17, v16
	v_mul_f32_e32 v17, v35, v35
	v_fmac_f32_e32 v17, v34, v34
	v_add_f32_e32 v16, v17, v16
	v_add_f32_e32 v19, v37, v16
	v_cvt_pk_bf16_f32 v27, v36, v27
	ds_bpermute_b32 v36, v170, v19
	s_waitcnt lgkmcnt(1)
	v_lshlrev_b64 v[32:33], 11, v[94:95]
	v_lshl_add_u64 v[16:17], v[32:33], 1, s[8:9]
	v_lshl_add_u64 v[22:23], v[152:153], 1, v[16:17]
	global_store_dwordx4 v[22:23], v[24:27], off sc0 sc1
	s_waitcnt lgkmcnt(0)
	v_add_f32_e32 v16, v19, v36
	ds_bpermute_b32 v17, v171, v16
	v_cvt_pk_bf16_f32 v18, v20, v21
	v_cvt_pk_bf16_f32 v19, v28, v29
	v_cvt_pk_bf16_f32 v20, v30, v31
	v_cvt_pk_bf16_f32 v21, v34, v35
	global_store_dwordx4 v[22:23], v[18:21], off offset:256 sc0 sc1
	s_and_saveexec_b64 s[22:23], s[6:7]
	s_cbranch_execz .LBB0_2863
	v_lshlrev_b64 v[18:19], 7, v[94:95]
	v_lshl_add_u64 v[18:19], s[20:21], 0, v[18:19]
	s_waitcnt lgkmcnt(0)
	v_add_f32_e32 v16, v16, v17
	global_store_dword v[18:19], v16, off
.LBB0_2863:
	s_or_b64 exec, exec, s[22:23]
	v_pk_add_f32 v[12:13], v[12:13], 0 op_sel_hi:[1,0]
	s_waitcnt vmcnt(7)
	v_lshlrev_b32_e32 v18, 16, v68
	v_add_f32_e32 v12, v12, v18
	v_and_b32_e32 v18, 0xffff0000, v68
	v_pk_add_f32 v[14:15], v[14:15], 0 op_sel_hi:[1,0]
	v_add_f32_e32 v13, v13, v18
	v_lshlrev_b32_e32 v18, 16, v69
	v_add_f32_e32 v14, v14, v18
	v_and_b32_e32 v18, 0xffff0000, v69
	v_pk_add_f32 v[8:9], v[8:9], 0 op_sel_hi:[1,0]
	v_add_f32_e32 v15, v15, v18
	v_lshlrev_b32_e32 v18, 16, v70
	v_add_f32_e32 v18, v8, v18
	v_and_b32_e32 v8, 0xffff0000, v70
	v_pk_add_f32 v[10:11], v[10:11], 0 op_sel_hi:[1,0]
	v_add_f32_e32 v19, v9, v8
	v_lshlrev_b32_e32 v8, 16, v71
	v_add_f32_e32 v20, v10, v8
	v_and_b32_e32 v8, 0xffff0000, v71
	v_add_f32_e32 v11, v11, v8
	v_mul_f32_e32 v8, v13, v13
	v_mul_f32_e32 v9, v15, v15
	v_fmac_f32_e32 v8, v12, v12
	v_fmac_f32_e32 v9, v14, v14
	v_add_f32_e32 v8, v8, v9
	v_mul_f32_e32 v9, v19, v19
	v_fmac_f32_e32 v9, v18, v18
	v_add_f32_e32 v8, v9, v8
	v_mul_f32_e32 v9, v11, v11
	v_fmac_f32_e32 v9, v20, v20
	v_add_f32_e32 v21, v9, v8
	v_cvt_pk_bf16_f32 v8, v12, v13
	v_pk_add_f32 v[4:5], v[4:5], 0 op_sel_hi:[1,0]
	s_waitcnt vmcnt(6)
	v_lshlrev_b32_e32 v12, 16, v64
	v_add_f32_e32 v4, v4, v12
	v_and_b32_e32 v12, 0xffff0000, v64
	v_pk_add_f32 v[6:7], v[6:7], 0 op_sel_hi:[1,0]
	v_add_f32_e32 v5, v5, v12
	v_lshlrev_b32_e32 v12, 16, v65
	v_add_f32_e32 v12, v6, v12
	v_and_b32_e32 v6, 0xffff0000, v65
	v_pk_add_f32 v[0:1], v[0:1], 0 op_sel_hi:[1,0]
	v_add_f32_e32 v13, v7, v6
	v_lshlrev_b32_e32 v6, 16, v66
	v_cvt_pk_bf16_f32 v9, v14, v15
	v_add_f32_e32 v14, v0, v6
	v_and_b32_e32 v0, 0xffff0000, v66
	v_pk_add_f32 v[2:3], v[2:3], 0 op_sel_hi:[1,0]
	v_add_f32_e32 v15, v1, v0
	v_lshlrev_b32_e32 v0, 16, v67
	v_cvt_pk_bf16_f32 v10, v18, v19
	v_add_f32_e32 v18, v2, v0
	v_and_b32_e32 v0, 0xffff0000, v67
	v_add_f32_e32 v19, v3, v0
	v_mul_f32_e32 v0, v5, v5
	v_mul_f32_e32 v1, v13, v13
	v_fmac_f32_e32 v0, v4, v4
	v_fmac_f32_e32 v1, v12, v12
	v_add_f32_e32 v0, v0, v1
	v_mul_f32_e32 v1, v15, v15
	v_fmac_f32_e32 v1, v14, v14
	v_add_f32_e32 v0, v1, v0
	v_mul_f32_e32 v1, v19, v19
	v_fmac_f32_e32 v1, v18, v18
	v_add_f32_e32 v0, v1, v0
	v_add_f32_e32 v3, v21, v0
	v_cvt_pk_bf16_f32 v11, v20, v11
	ds_bpermute_b32 v20, v170, v3
	s_waitcnt lgkmcnt(1)
	v_lshlrev_b64 v[16:17], 11, v[92:93]
	v_lshl_add_u64 v[0:1], v[16:17], 1, s[8:9]
	v_lshl_add_u64 v[6:7], v[152:153], 1, v[0:1]
	global_store_dwordx4 v[6:7], v[8:11], off sc0 sc1
	s_waitcnt lgkmcnt(0)
	v_add_f32_e32 v0, v3, v20
	ds_bpermute_b32 v1, v171, v0
	v_cvt_pk_bf16_f32 v2, v4, v5
	v_cvt_pk_bf16_f32 v3, v12, v13
	v_cvt_pk_bf16_f32 v4, v14, v15
	v_cvt_pk_bf16_f32 v5, v18, v19
	global_store_dwordx4 v[6:7], v[2:5], off offset:256 sc0 sc1
	s_and_saveexec_b64 s[22:23], s[6:7]
	s_cbranch_execz .LBB0_2865
	v_lshlrev_b64 v[2:3], 7, v[92:93]
	v_lshl_add_u64 v[2:3], s[20:21], 0, v[2:3]
	s_waitcnt lgkmcnt(0)
	v_add_f32_e32 v0, v0, v1
	global_store_dword v[2:3], v0, off

; __device__ __forceinline__ unsigned cvt_pk_bf16(float lo, float hi) { unsigned r; asm volatile("v_cvt_pk_bf16_f32 %0, %1, %2" : "=v"(r) : "v"(lo), "v"(hi)); return r; }
; __device__ __forceinline__ float dpp_up1(float x) { return __builtin_bit_cast(float, __builtin_amdgcn_update_dpp(0, __builtin_bit_cast(int, x), 0x111, 0xf, 0xf, true)); }
;     __device__ __forceinline__ void operator()(const f32x4 (&acc)[2][2][4][2], const Unit& u, int wr, int wc, int fr, int fq) const {
;     ...
;                 f32x4 pg2, pg3, pv2, pv3;
; #pragma unroll
;                 for (int e = 0; e < 4; ++e) { pg2[e] = dpp_up1(xg[2][e]); pg3[e] = dpp_up1(xg[3][e]); pv2[e] = dpp_up1(xv[2][e]); pv3[e] = dpp_up1(xv[3][e]); }
; #pragma unroll
;                 for (int m = 0; m < 4; ++m) {
;                     u32x2_t w; float o[4];
; #pragma unroll
;                     for (int e = 0; e < 4; ++e) {
;                         const float g1 = m >= 1 ? xg[m - (m >= 1 ? 1 : 0)][e] : pg3[e], g2 = m >= 2 ? xg[m - (m >= 2 ? 2 : 0)][e] : (m == 1 ? pg3[e] : pg2[e]);
;                         const float v1 = m >= 1 ? xv[m - (m >= 1 ? 1 : 0)][e] : pv3[e], v2 = m >= 2 ? xv[m - (m >= 2 ? 2 : 0)][e] : (m == 1 ? pv3[e] : pv2[e]);
;                         const float cg_ = bg[e] + w0g[e] * g2 + w1g[e] * g1 + w2g[e] * xg[m][e];
;                         const float cv_ = bv[e] + w0v[e] * v2 + w1v[e] * v1 + w2v[e] * xv[m][e];
;                         o[e] = cg_ * __builtin_amdgcn_rcpf(1.0f + __expf(-cg_)) * cv_;
;                     }
;                     w.x = cvt_pk_bf16(o[0], o[1]); w.y = cvt_pk_bf16(o[2], o[3]);
;                     const int g = g0 + m;
;                     if (n == 0) stash[ai][m] = w;
;                     else if ((fr > 0 || m >= 2) && g < TT) { u32x4 ww; ww.x = stash[ai][m].x; ww.y = stash[ai][m].y; ww.z = w.x; ww.w = w.y; *(u32x4*)(G + (size_t)g * DFF_ + f0 - 4) = ww; }
.LBB0_2943:
	v_mov_b32_dpp v112, v58 row_shr:1 row_mask:0xf bank_mask:0xf bound_ctrl:1
	v_mov_b32_dpp v125, v44 row_shr:1 row_mask:0xf bank_mask:0xf bound_ctrl:1
	s_waitcnt vmcnt(4)
	v_fma_f32 v112, v98, v112, v70
	v_fmac_f32_e32 v112, v90, v125
	v_fmac_f32_e32 v112, v94, v116
	v_mul_f32_e32 v132, 0xbfb8aa3b, v112
	v_exp_f32_e32 v132, v132
	v_mov_b32_dpp v113, v52 row_shr:1 row_mask:0xf bank_mask:0xf bound_ctrl:1
	v_mov_b32_dpp v123, v38 row_shr:1 row_mask:0xf bank_mask:0xf bound_ctrl:1
	s_waitcnt vmcnt(0)
	v_fma_f32 v113, v74, v113, v86
	v_add_f32_e32 v132, 1.0, v132
	v_rcp_f32_e32 v132, v132
	v_fmac_f32_e32 v113, v78, v123
	v_mov_b32_dpp v126, v59 row_shr:1 row_mask:0xf bank_mask:0xf bound_ctrl:1
	v_fmac_f32_e32 v113, v82, v68
	v_mul_f32_e32 v112, v112, v132
	v_mov_b32_dpp v121, v45 row_shr:1 row_mask:0xf bank_mask:0xf bound_ctrl:1
	v_mul_f32_e32 v112, v113, v112
	v_fma_f32 v113, v99, v126, v71
	v_fmac_f32_e32 v113, v91, v121
	v_mov_b32_dpp v127, v53 row_shr:1 row_mask:0xf bank_mask:0xf bound_ctrl:1
	v_fmac_f32_e32 v113, v95, v117
	v_fma_f32 v126, v75, v127, v87
	v_mul_f32_e32 v127, 0xbfb8aa3b, v113
	v_exp_f32_e32 v127, v127
	v_mov_b32_dpp v119, v39 row_shr:1 row_mask:0xf bank_mask:0xf bound_ctrl:1
	v_fmac_f32_e32 v126, v79, v119
	v_mov_b32_dpp v128, v42 row_shr:1 row_mask:0xf bank_mask:0xf bound_ctrl:1
	v_add_f32_e32 v127, 1.0, v127
	v_rcp_f32_e32 v127, v127
	v_fmac_f32_e32 v126, v83, v69
	v_mov_b32_dpp v55, v32 row_shr:1 row_mask:0xf bank_mask:0xf bound_ctrl:1
	v_mov_b32_dpp v129, v36 row_shr:1 row_mask:0xf bank_mask:0xf bound_ctrl:1
	v_mul_f32_e32 v113, v113, v127
	v_mul_f32_e32 v113, v126, v113
	v_fma_f32 v126, v100, v128, v72
	v_fmac_f32_e32 v126, v92, v55
	v_fmac_f32_e32 v126, v96, v62
	v_mul_f32_e32 v128, 0xbfb8aa3b, v126
	v_exp_f32_e32 v128, v128
	v_mov_b32_dpp v54, v34 row_shr:1 row_mask:0xf bank_mask:0xf bound_ctrl:1
	v_fma_f32 v127, v76, v129, v88
	v_fmac_f32_e32 v127, v80, v54
	v_add_f32_e32 v128, 1.0, v128
	v_rcp_f32_e32 v128, v128
	v_mov_b32_dpp v130, v43 row_shr:1 row_mask:0xf bank_mask:0xf bound_ctrl:1
	v_fmac_f32_e32 v127, v84, v60
	v_mov_b32_dpp v47, v33 row_shr:1 row_mask:0xf bank_mask:0xf bound_ctrl:1
	v_mul_f32_e32 v126, v126, v128
	v_mul_f32_e32 v126, v127, v126
	v_fma_f32 v127, v101, v130, v73
	v_fmac_f32_e32 v127, v93, v47
	v_fmac_f32_e32 v127, v97, v63
	v_mul_f32_e32 v129, 0xbfb8aa3b, v127
	v_exp_f32_e32 v129, v129
	v_mov_b32_dpp v131, v37 row_shr:1 row_mask:0xf bank_mask:0xf bound_ctrl:1
	v_mov_b32_dpp v46, v35 row_shr:1 row_mask:0xf bank_mask:0xf bound_ctrl:1
	v_fma_f32 v128, v77, v131, v89
	v_add_f32_e32 v129, 1.0, v129
	v_rcp_f32_e32 v129, v129
	v_fmac_f32_e32 v128, v81, v46
	v_cmp_gt_i32_e32 vcc, s79, v215
	v_fmac_f32_e32 v128, v85, v61
	v_mul_f32_e32 v127, v127, v129
	s_and_b64 s[2:3], s[6:7], vcc
	v_mul_f32_e32 v127, v128, v127
	v_cvt_pk_bf16_f32 v112, v112, v113
	v_cvt_pk_bf16_f32 v113, v126, v127
	s_and_saveexec_b64 s[0:1], s[2:3]
	s_cbranch_execz .LBB0_2945
	v_mov_b64_e32 v[126:127], s[12:13]
	v_mad_i64_i32 v[126:127], s[2:3], v215, s86, v[126:127]
	v_lshl_add_u64 v[126:127], v[178:179], 1, v[126:127]
	global_store_dwordx4 v[126:127], v[110:113], off sc0 sc1
.LBB0_2945:
	s_or_b64 exec, exec, s[0:1]
	s_nop 0
	v_fma_f32 v110, v98, v125, v70
	v_fmac_f32_e32 v110, v90, v116
	v_fmac_f32_e32 v110, v94, v56
	v_mul_f32_e32 v112, 0xbfb8aa3b, v110
	v_exp_f32_e32 v112, v112
	v_fma_f32 v111, v74, v123, v86
	v_fmac_f32_e32 v111, v78, v68
	v_fmac_f32_e32 v111, v82, v50
	v_add_f32_e32 v112, 1.0, v112
	v_rcp_f32_e32 v112, v112
	v_fma_f32 v55, v100, v55, v72
	v_fmac_f32_e32 v55, v92, v62
	v_fmac_f32_e32 v55, v96, v48
	v_mul_f32_e32 v110, v110, v112
	v_mul_f32_e32 v110, v111, v110
	v_fma_f32 v111, v99, v121, v71
	v_fmac_f32_e32 v111, v91, v117
	v_fmac_f32_e32 v111, v95, v57
	v_mul_f32_e32 v113, 0xbfb8aa3b, v111
	v_exp_f32_e32 v113, v113
	v_fma_f32 v112, v75, v119, v87
	v_fmac_f32_e32 v112, v79, v69
	v_fmac_f32_e32 v112, v83, v51
	v_add_f32_e32 v113, 1.0, v113
	v_rcp_f32_e32 v113, v113
	v_fma_f32 v54, v76, v54, v88
	v_fma_f32 v47, v101, v47, v73
	v_fmac_f32_e32 v54, v80, v60
	v_mul_f32_e32 v111, v111, v113
	v_mul_f32_e32 v111, v112, v111
	v_mul_f32_e32 v112, 0xbfb8aa3b, v55
	v_exp_f32_e32 v112, v112
	v_fmac_f32_e32 v47, v93, v63
	v_fmac_f32_e32 v54, v84, v40
	v_fmac_f32_e32 v47, v97, v49
	v_add_f32_e32 v112, 1.0, v112
	v_rcp_f32_e32 v112, v112
	v_fma_f32 v46, v77, v46, v89
	v_fmac_f32_e32 v46, v81, v61
	v_cmp_gt_i32_e32 vcc, s79, v218
	v_mul_f32_e32 v55, v55, v112
	v_mul_f32_e32 v54, v54, v55
	v_mul_f32_e32 v55, 0xbfb8aa3b, v47
	v_exp_f32_e32 v55, v55
	v_fmac_f32_e32 v46, v85, v41
	s_and_b64 s[2:3], s[6:7], vcc
	v_cvt_pk_bf16_f32 v110, v110, v111
	v_add_f32_e32 v55, 1.0, v55
	v_rcp_f32_e32 v55, v55
	s_nop 0
	v_mul_f32_e32 v47, v47, v55
	v_mul_f32_e32 v46, v46, v47
	v_cvt_pk_bf16_f32 v111, v54, v46
	s_and_saveexec_b64 s[0:1], s[2:3]
	s_cbranch_execz .LBB0_2947
	v_mov_b64_e32 v[46:47], s[12:13]
	v_mad_i64_i32 v[46:47], s[2:3], v218, s86, v[46:47]
	v_lshl_add_u64 v[46:47], v[178:179], 1, v[46:47]
	global_store_dwordx4 v[46:47], v[108:111], off sc0 sc1
; __device__ __forceinline__ unsigned cvt_pk_bf16(float lo, float hi) { unsigned r; asm volatile("v_cvt_pk_bf16_f32 %0, %1, %2" : "=v"(r) : "v"(lo), "v"(hi)); return r; }
;     __device__ __forceinline__ void operator()(const f32x4 (&acc)[2][2][4][2], const Unit& u, int wr, int wc, int fr, int fq) const {
;     ...
;                 for (int m = 0; m < 4; ++m) {
;                     u32x2_t w; float o[4];
; #pragma unroll
;                     for (int e = 0; e < 4; ++e) {
;                         const float g1 = m >= 1 ? xg[m - (m >= 1 ? 1 : 0)][e] : pg3[e], g2 = m >= 2 ? xg[m - (m >= 2 ? 2 : 0)][e] : (m == 1 ? pg3[e] : pg2[e]);
;                         const float v1 = m >= 1 ? xv[m - (m >= 1 ? 1 : 0)][e] : pv3[e], v2 = m >= 2 ? xv[m - (m >= 2 ? 2 : 0)][e] : (m == 1 ? pv3[e] : pv2[e]);
;                         const float cg_ = bg[e] + w0g[e] * g2 + w1g[e] * g1 + w2g[e] * xg[m][e];
;                         const float cv_ = bv[e] + w0v[e] * v2 + w1v[e] * v1 + w2v[e] * xv[m][e];
;                         o[e] = cg_ * __builtin_amdgcn_rcpf(1.0f + __expf(-cg_)) * cv_;
;                     }
;                     w.x = cvt_pk_bf16(o[0], o[1]); w.y = cvt_pk_bf16(o[2], o[3]);
;                     const int g = g0 + m;
;                     if (n == 0) stash[ai][m] = w;
;                     else if ((fr > 0 || m >= 2) && g < TT) { u32x4 ww; ww.x = stash[ai][m].x; ww.y = stash[ai][m].y; ww.z = w.x; ww.w = w.y; *(u32x4*)(G + (size_t)g * DFF_ + f0 - 4) = ww; }
;                 }
.LBB0_2947:
	s_or_b64 exec, exec, s[0:1]
	v_fma_f32 v46, v98, v116, v70
	v_fmac_f32_e32 v46, v90, v56
	v_fmac_f32_e32 v46, v94, v58
	v_mul_f32_e32 v54, 0xbfb8aa3b, v46
	v_exp_f32_e32 v54, v54
	v_fma_f32 v47, v74, v68, v86
	v_fmac_f32_e32 v47, v78, v50
	v_fmac_f32_e32 v47, v82, v52
	v_add_f32_e32 v54, 1.0, v54
	v_rcp_f32_e32 v54, v54
	v_cmp_gt_i32_e32 vcc, s87, v215
	v_mul_f32_e32 v46, v46, v54
	v_mul_f32_e32 v46, v47, v46
	v_fma_f32 v47, v99, v117, v71
	v_fmac_f32_e32 v47, v91, v57
	v_fmac_f32_e32 v47, v95, v59
	v_mul_f32_e32 v55, 0xbfb8aa3b, v47
	v_exp_f32_e32 v55, v55
	v_fma_f32 v54, v75, v69, v87
	v_fmac_f32_e32 v54, v79, v51
	v_fmac_f32_e32 v54, v83, v53
	v_add_f32_e32 v55, 1.0, v55
	v_rcp_f32_e32 v55, v55
	s_nop 0
	v_mul_f32_e32 v47, v47, v55
	v_mul_f32_e32 v47, v54, v47
	v_fma_f32 v54, v100, v62, v72
	v_fmac_f32_e32 v54, v92, v48
	v_fmac_f32_e32 v54, v96, v42
	v_fma_f32 v55, v76, v60, v88
	v_mul_f32_e32 v60, 0xbfb8aa3b, v54
	v_exp_f32_e32 v60, v60
	v_fmac_f32_e32 v55, v80, v40
	v_fmac_f32_e32 v55, v84, v36
	v_cvt_pk_bf16_f32 v108, v46, v47
	v_add_f32_e32 v60, 1.0, v60
	v_rcp_f32_e32 v60, v60
	s_nop 0
	v_mul_f32_e32 v54, v54, v60
	v_mul_f32_e32 v54, v55, v54
	v_fma_f32 v55, v101, v63, v73
	v_fmac_f32_e32 v55, v93, v49
	v_fmac_f32_e32 v55, v97, v43
	v_fma_f32 v60, v77, v61, v89
	v_mul_f32_e32 v61, 0xbfb8aa3b, v55
	v_exp_f32_e32 v61, v61
	v_fmac_f32_e32 v60, v81, v41
	v_fmac_f32_e32 v60, v85, v37
	v_add_f32_e32 v61, 1.0, v61
	v_rcp_f32_e32 v61, v61
	s_nop 0
	v_mul_f32_e32 v55, v55, v61
	v_mul_f32_e32 v55, v60, v55
	v_cvt_pk_bf16_f32 v109, v54, v55
	s_and_saveexec_b64 s[0:1], vcc
	s_cbranch_execz .LBB0_2949
	v_mov_b64_e32 v[46:47], s[12:13]
	v_mad_i64_i32 v[46:47], s[2:3], v216, s86, v[46:47]
	v_lshl_add_u64 v[46:47], v[178:179], 1, v[46:47]
	global_store_dwordx4 v[46:47], v[106:109], off sc0 sc1
.LBB0_2949:
	s_or_b64 exec, exec, s[0:1]
	v_fma_f32 v46, v98, v56, v70
	v_fmac_f32_e32 v46, v90, v58
	v_fmac_f32_e32 v46, v94, v44
	v_mul_f32_e32 v44, 0xbfb8aa3b, v46
	v_exp_f32_e32 v44, v44
	v_fma_f32 v47, v74, v50, v86
	v_fma_f32 v50, v99, v57, v71
	v_fmac_f32_e32 v50, v91, v59
	v_fmac_f32_e32 v50, v95, v45
	v_add_f32_e32 v44, 1.0, v44
	v_mul_f32_e32 v45, 0xbfb8aa3b, v50
	v_rcp_f32_e32 v44, v44
	v_exp_f32_e32 v45, v45
	v_fmac_f32_e32 v47, v78, v52
	v_fmac_f32_e32 v47, v82, v38
	v_mul_f32_e32 v38, v46, v44
	v_add_f32_e32 v44, 1.0, v45
	v_rcp_f32_e32 v44, v44
	v_fma_f32 v45, v75, v51, v87
	v_fmac_f32_e32 v45, v79, v53
	v_fma_f32 v40, v76, v40, v88
	v_fmac_f32_e32 v45, v83, v39
	v_mul_f32_e32 v39, v50, v44
	v_fma_f32 v44, v100, v48, v72
	v_fmac_f32_e32 v40, v80, v36
	v_fma_f32 v36, v101, v49, v73
	v_fmac_f32_e32 v44, v92, v42
	v_fmac_f32_e32 v36, v93, v43
	v_fmac_f32_e32 v44, v96, v32
	v_fmac_f32_e32 v36, v97, v33
	v_mul_f32_e32 v32, 0xbfb8aa3b, v44
	v_mul_f32_e32 v33, 0xbfb8aa3b, v36
	v_exp_f32_e32 v32, v32
	v_exp_f32_e32 v33, v33
	v_fmac_f32_e32 v40, v84, v34
	v_fma_f32 v34, v77, v41, v89
	v_add_f32_e32 v32, 1.0, v32
	v_add_f32_e32 v33, 1.0, v33
	v_rcp_f32_e32 v32, v32
	v_rcp_f32_e32 v33, v33
	v_fmac_f32_e32 v34, v81, v37
	v_fmac_f32_e32 v34, v85, v35
	v_mul_f32_e32 v32, v44, v32
	v_mul_f32_e32 v33, v36, v33
	v_cmp_gt_i32_e32 vcc, s88, v215
	v_mul_f32_e32 v38, v47, v38
	v_mul_f32_e32 v39, v45, v39
	v_mul_f32_e32 v32, v40, v32
	v_mul_f32_e32 v33, v34, v33
	v_cvt_pk_bf16_f32 v116, v38, v39
	v_cvt_pk_bf16_f32 v117, v32, v33
	s_and_saveexec_b64 s[0:1], vcc
	s_cbranch_execz .LBB0_2951
	v_mov_b64_e32 v[32:33], s[12:13]
	v_mad_i64_i32 v[32:33], s[2:3], v217, s86, v[32:33]
	v_lshl_add_u64 v[32:33], v[178:179], 1, v[32:33]
	global_store_dwordx4 v[32:33], v[114:117], off sc0 sc1

; __device__ __forceinline__ unsigned cvt_pk_bf16(float lo, float hi) { unsigned r; asm volatile("v_cvt_pk_bf16_f32 %0, %1, %2" : "=v"(r) : "v"(lo), "v"(hi)); return r; }
; __device__ __forceinline__ float dpp_up1(float x) { return __builtin_bit_cast(float, __builtin_amdgcn_update_dpp(0, __builtin_bit_cast(int, x), 0x111, 0xf, 0xf, true)); }
;     __device__ __forceinline__ void operator()(const f32x4 (&acc)[2][2][4][2], const Unit& u, int wr, int wc, int fr, int fq) const {
;     ...
;                 f32x4 pg2, pg3, pv2, pv3;
; #pragma unroll
;                 for (int e = 0; e < 4; ++e) { pg2[e] = dpp_up1(xg[2][e]); pg3[e] = dpp_up1(xg[3][e]); pv2[e] = dpp_up1(xv[2][e]); pv3[e] = dpp_up1(xv[3][e]); }
; #pragma unroll
;                 for (int m = 0; m < 4; ++m) {
;                     u32x2_t w; float o[4];
; #pragma unroll
;                     for (int e = 0; e < 4; ++e) {
;                         const float g1 = m >= 1 ? xg[m - (m >= 1 ? 1 : 0)][e] : pg3[e], g2 = m >= 2 ? xg[m - (m >= 2 ? 2 : 0)][e] : (m == 1 ? pg3[e] : pg2[e]);
;                         const float v1 = m >= 1 ? xv[m - (m >= 1 ? 1 : 0)][e] : pv3[e], v2 = m >= 2 ? xv[m - (m >= 2 ? 2 : 0)][e] : (m == 1 ? pv3[e] : pv2[e]);
;                         const float cg_ = bg[e] + w0g[e] * g2 + w1g[e] * g1 + w2g[e] * xg[m][e];
;                         const float cv_ = bv[e] + w0v[e] * v2 + w1v[e] * v1 + w2v[e] * xv[m][e];
;                         o[e] = cg_ * __builtin_amdgcn_rcpf(1.0f + __expf(-cg_)) * cv_;
;                     }
;                     w.x = cvt_pk_bf16(o[0], o[1]); w.y = cvt_pk_bf16(o[2], o[3]);
;                     const int g = g0 + m;
;                     if (n == 0) stash[ai][m] = w;
;                     else if ((fr > 0 || m >= 2) && g < TT) { u32x4 ww; ww.x = stash[ai][m].x; ww.y = stash[ai][m].y; ww.z = w.x; ww.w = w.y; *(u32x4*)(G + (size_t)g * DFF_ + f0 - 4) = ww; }
;                 }
.LBB0_2953:
	v_mov_b32_dpp v40, v26 row_shr:1 row_mask:0xf bank_mask:0xf bound_ctrl:1
	v_mov_b32_dpp v39, v12 row_shr:1 row_mask:0xf bank_mask:0xf bound_ctrl:1
	v_fma_f32 v40, v98, v40, v70
	v_fmac_f32_e32 v40, v90, v39
	v_fmac_f32_e32 v40, v94, v34
	v_mul_f32_e32 v48, 0xbfb8aa3b, v40
	v_exp_f32_e32 v48, v48
	v_mov_b32_dpp v41, v20 row_shr:1 row_mask:0xf bank_mask:0xf bound_ctrl:1
	v_mov_b32_dpp v38, v6 row_shr:1 row_mask:0xf bank_mask:0xf bound_ctrl:1
	v_fma_f32 v41, v74, v41, v86
	v_add_f32_e32 v48, 1.0, v48
	v_rcp_f32_e32 v48, v48
	v_fmac_f32_e32 v41, v78, v38
	v_mov_b32_dpp v42, v27 row_shr:1 row_mask:0xf bank_mask:0xf bound_ctrl:1
	v_fmac_f32_e32 v41, v82, v32
	v_mul_f32_e32 v40, v40, v48
	v_mov_b32_dpp v37, v13 row_shr:1 row_mask:0xf bank_mask:0xf bound_ctrl:1
	v_mul_f32_e32 v40, v41, v40
	v_fma_f32 v41, v99, v42, v71
	v_fmac_f32_e32 v41, v91, v37
	v_mov_b32_dpp v43, v21 row_shr:1 row_mask:0xf bank_mask:0xf bound_ctrl:1
	v_fmac_f32_e32 v41, v95, v35
	v_fma_f32 v42, v75, v43, v87
	v_mul_f32_e32 v43, 0xbfb8aa3b, v41
	v_exp_f32_e32 v43, v43
	v_mov_b32_dpp v36, v7 row_shr:1 row_mask:0xf bank_mask:0xf bound_ctrl:1
	v_fmac_f32_e32 v42, v79, v36
	v_mov_b32_dpp v44, v10 row_shr:1 row_mask:0xf bank_mask:0xf bound_ctrl:1
	v_add_f32_e32 v43, 1.0, v43
	v_rcp_f32_e32 v43, v43
	v_fmac_f32_e32 v42, v83, v33
	v_mov_b32_dpp v23, v0 row_shr:1 row_mask:0xf bank_mask:0xf bound_ctrl:1
	v_mov_b32_dpp v45, v4 row_shr:1 row_mask:0xf bank_mask:0xf bound_ctrl:1
	v_mul_f32_e32 v41, v41, v43
	v_mul_f32_e32 v41, v42, v41
	v_fma_f32 v42, v100, v44, v72
	v_fmac_f32_e32 v42, v92, v23
	v_fmac_f32_e32 v42, v96, v30
	v_mul_f32_e32 v44, 0xbfb8aa3b, v42
	v_exp_f32_e32 v44, v44
	v_mov_b32_dpp v22, v2 row_shr:1 row_mask:0xf bank_mask:0xf bound_ctrl:1
	v_fma_f32 v43, v76, v45, v88
	v_fmac_f32_e32 v43, v80, v22
	v_add_f32_e32 v44, 1.0, v44
	v_rcp_f32_e32 v44, v44
	v_mov_b32_dpp v46, v11 row_shr:1 row_mask:0xf bank_mask:0xf bound_ctrl:1
	v_fmac_f32_e32 v43, v84, v28
	v_mov_b32_dpp v15, v1 row_shr:1 row_mask:0xf bank_mask:0xf bound_ctrl:1
	v_mul_f32_e32 v42, v42, v44
	v_mul_f32_e32 v42, v43, v42
	v_fma_f32 v43, v101, v46, v73
	v_fmac_f32_e32 v43, v93, v15
	v_fmac_f32_e32 v43, v97, v31
	v_mul_f32_e32 v45, 0xbfb8aa3b, v43
	v_exp_f32_e32 v45, v45
	v_mov_b32_dpp v47, v5 row_shr:1 row_mask:0xf bank_mask:0xf bound_ctrl:1
	v_mov_b32_dpp v14, v3 row_shr:1 row_mask:0xf bank_mask:0xf bound_ctrl:1
	v_fma_f32 v44, v77, v47, v89
	v_add_f32_e32 v45, 1.0, v45
	v_rcp_f32_e32 v45, v45
	v_fmac_f32_e32 v44, v81, v14
	v_cmp_gt_i32_e32 vcc, s79, v211
	v_fmac_f32_e32 v44, v85, v29
	v_mul_f32_e32 v43, v43, v45
	s_and_b64 s[2:3], s[6:7], vcc
	v_mul_f32_e32 v43, v44, v43
	v_cvt_pk_bf16_f32 v106, v40, v41
	v_cvt_pk_bf16_f32 v107, v42, v43
	s_and_saveexec_b64 s[0:1], s[2:3]
	s_cbranch_execz .LBB0_2955
	v_mov_b64_e32 v[40:41], s[12:13]
	v_mad_i64_i32 v[40:41], s[2:3], v211, s86, v[40:41]
	v_lshl_add_u64 v[40:41], v[178:179], 1, v[40:41]
	global_store_dwordx4 v[40:41], v[104:107], off sc0 sc1
.LBB0_2955:
	s_or_b64 exec, exec, s[0:1]
	v_fma_f32 v39, v98, v39, v70
	v_fmac_f32_e32 v39, v90, v34
	v_fmac_f32_e32 v39, v94, v24
	v_mul_f32_e32 v40, 0xbfb8aa3b, v39
	v_exp_f32_e32 v40, v40
	v_fma_f32 v38, v74, v38, v86
	v_fma_f32 v37, v99, v37, v71
	v_fmac_f32_e32 v38, v78, v32
	v_add_f32_e32 v40, 1.0, v40
	v_rcp_f32_e32 v40, v40
	v_fmac_f32_e32 v37, v91, v35
	v_fmac_f32_e32 v38, v82, v18
	v_fmac_f32_e32 v37, v95, v25
	v_mul_f32_e32 v39, v39, v40
	v_mul_f32_e32 v38, v38, v39
	v_mul_f32_e32 v39, 0xbfb8aa3b, v37
	v_exp_f32_e32 v39, v39
	v_fma_f32 v36, v75, v36, v87
	v_fma_f32 v23, v100, v23, v72
	v_fmac_f32_e32 v36, v79, v33
	v_add_f32_e32 v39, 1.0, v39
	v_rcp_f32_e32 v39, v39
	v_fmac_f32_e32 v23, v92, v30
	v_fmac_f32_e32 v36, v83, v19
	v_fmac_f32_e32 v23, v96, v16
	v_mul_f32_e32 v37, v37, v39
	v_mul_f32_e32 v36, v36, v37
	v_mul_f32_e32 v37, 0xbfb8aa3b, v23
	v_exp_f32_e32 v37, v37
	v_fma_f32 v22, v76, v22, v88
	v_fma_f32 v15, v101, v15, v73
	v_fmac_f32_e32 v22, v80, v28
	v_add_f32_e32 v37, 1.0, v37
	v_rcp_f32_e32 v37, v37
	v_fmac_f32_e32 v15, v93, v31
	v_fmac_f32_e32 v22, v84, v8
	v_fmac_f32_e32 v15, v97, v17
	v_mul_f32_e32 v23, v23, v37
	v_mul_f32_e32 v22, v22, v23
	v_mul_f32_e32 v23, 0xbfb8aa3b, v15
	v_exp_f32_e32 v23, v23
	v_fma_f32 v14, v77, v14, v89
	v_fmac_f32_e32 v14, v81, v29
	v_cmp_gt_i32_e32 vcc, s79, v213
	v_add_f32_e32 v23, 1.0, v23
	v_rcp_f32_e32 v23, v23
	v_fmac_f32_e32 v14, v85, v9
	s_and_b64 s[2:3], s[6:7], vcc
	v_cvt_pk_bf16_f32 v104, v38, v36
	v_mul_f32_e32 v15, v15, v23
	v_mul_f32_e32 v14, v14, v15
	v_cvt_pk_bf16_f32 v105, v22, v14
	s_and_saveexec_b64 s[0:1], s[2:3]
	s_cbranch_execz .LBB0_2957
	v_mov_b64_e32 v[14:15], s[12:13]
	v_mad_i64_i32 v[14:15], s[2:3], v213, s86, v[14:15]
	v_lshl_add_u64 v[14:15], v[178:179], 1, v[14:15]
	global_store_dwordx4 v[14:15], v[102:105], off sc0 sc1
; __device__ __forceinline__ unsigned cvt_pk_bf16(float lo, float hi) { unsigned r; asm volatile("v_cvt_pk_bf16_f32 %0, %1, %2" : "=v"(r) : "v"(lo), "v"(hi)); return r; }
;     __device__ __forceinline__ void operator()(const f32x4 (&acc)[2][2][4][2], const Unit& u, int wr, int wc, int fr, int fq) const {
;     ...
;                 for (int m = 0; m < 4; ++m) {
;                     u32x2_t w; float o[4];
; #pragma unroll
;                     for (int e = 0; e < 4; ++e) {
;                         const float g1 = m >= 1 ? xg[m - (m >= 1 ? 1 : 0)][e] : pg3[e], g2 = m >= 2 ? xg[m - (m >= 2 ? 2 : 0)][e] : (m == 1 ? pg3[e] : pg2[e]);
;                         const float v1 = m >= 1 ? xv[m - (m >= 1 ? 1 : 0)][e] : pv3[e], v2 = m >= 2 ? xv[m - (m >= 2 ? 2 : 0)][e] : (m == 1 ? pv3[e] : pv2[e]);
;                         const float cg_ = bg[e] + w0g[e] * g2 + w1g[e] * g1 + w2g[e] * xg[m][e];
;                         const float cv_ = bv[e] + w0v[e] * v2 + w1v[e] * v1 + w2v[e] * xv[m][e];
;                         o[e] = cg_ * __builtin_amdgcn_rcpf(1.0f + __expf(-cg_)) * cv_;
;                     }
;                     w.x = cvt_pk_bf16(o[0], o[1]); w.y = cvt_pk_bf16(o[2], o[3]);
;                     const int g = g0 + m;
;                     if (n == 0) stash[ai][m] = w;
;                     else if ((fr > 0 || m >= 2) && g < TT) { u32x4 ww; ww.x = stash[ai][m].x; ww.y = stash[ai][m].y; ww.z = w.x; ww.w = w.y; *(u32x4*)(G + (size_t)g * DFF_ + f0 - 4) = ww; }
;                 }
.LBB0_2957:
	s_or_b64 exec, exec, s[0:1]
	v_fma_f32 v14, v98, v34, v70
	v_fmac_f32_e32 v14, v90, v24
	v_fmac_f32_e32 v14, v94, v26
	v_mul_f32_e32 v22, 0xbfb8aa3b, v14
	v_exp_f32_e32 v22, v22
	v_fma_f32 v15, v74, v32, v86
	v_fmac_f32_e32 v15, v78, v18
	v_fmac_f32_e32 v15, v82, v20
	v_add_f32_e32 v22, 1.0, v22
	v_rcp_f32_e32 v22, v22
	v_cmp_gt_i32_e32 vcc, s87, v211
	v_mul_f32_e32 v14, v14, v22
	v_mul_f32_e32 v14, v15, v14
	v_fma_f32 v15, v99, v35, v71
	v_fmac_f32_e32 v15, v91, v25
	v_fmac_f32_e32 v15, v95, v27
	v_mul_f32_e32 v23, 0xbfb8aa3b, v15
	v_exp_f32_e32 v23, v23
	v_fma_f32 v22, v75, v33, v87
	v_fmac_f32_e32 v22, v79, v19
	v_fmac_f32_e32 v22, v83, v21
	v_add_f32_e32 v23, 1.0, v23
	v_rcp_f32_e32 v23, v23
	s_nop 0
	v_mul_f32_e32 v15, v15, v23
	v_mul_f32_e32 v15, v22, v15
	v_fma_f32 v22, v100, v30, v72
	v_fmac_f32_e32 v22, v92, v16
	v_fmac_f32_e32 v22, v96, v10
	v_fma_f32 v23, v76, v28, v88
	v_mul_f32_e32 v28, 0xbfb8aa3b, v22
	v_exp_f32_e32 v28, v28
	v_fmac_f32_e32 v23, v80, v8
	v_fmac_f32_e32 v23, v84, v4
	v_cvt_pk_bf16_f32 v68, v14, v15
	v_add_f32_e32 v28, 1.0, v28
	v_rcp_f32_e32 v28, v28
	s_nop 0
	v_mul_f32_e32 v22, v22, v28
	v_mul_f32_e32 v22, v23, v22
	v_fma_f32 v23, v101, v31, v73
	v_fmac_f32_e32 v23, v93, v17
	v_fmac_f32_e32 v23, v97, v11
	v_fma_f32 v28, v77, v29, v89
	v_mul_f32_e32 v29, 0xbfb8aa3b, v23
	v_exp_f32_e32 v29, v29
	v_fmac_f32_e32 v28, v81, v9
	v_fmac_f32_e32 v28, v85, v5
	v_add_f32_e32 v29, 1.0, v29
	v_rcp_f32_e32 v29, v29
	s_nop 0
	v_mul_f32_e32 v23, v23, v29
	v_mul_f32_e32 v23, v28, v23
	v_cvt_pk_bf16_f32 v69, v22, v23
	s_and_saveexec_b64 s[0:1], vcc
	s_cbranch_execz .LBB0_2959
	v_mov_b64_e32 v[14:15], s[12:13]
	v_mad_i64_i32 v[14:15], s[2:3], v212, s86, v[14:15]
	v_lshl_add_u64 v[14:15], v[178:179], 1, v[14:15]
	global_store_dwordx4 v[14:15], v[66:69], off sc0 sc1
.LBB0_2959:
	s_or_b64 exec, exec, s[0:1]
	v_fma_f32 v14, v98, v24, v70
	v_fmac_f32_e32 v14, v90, v26
	v_fmac_f32_e32 v14, v94, v12
	v_mul_f32_e32 v12, 0xbfb8aa3b, v14
	v_exp_f32_e32 v12, v12
	v_fma_f32 v15, v74, v18, v86
	v_fma_f32 v18, v99, v25, v71
	v_fmac_f32_e32 v18, v91, v27
	v_fmac_f32_e32 v18, v95, v13
	v_add_f32_e32 v12, 1.0, v12
	v_mul_f32_e32 v13, 0xbfb8aa3b, v18
	v_rcp_f32_e32 v12, v12
	v_exp_f32_e32 v13, v13
	v_fmac_f32_e32 v15, v78, v20
	v_fmac_f32_e32 v15, v82, v6
	v_mul_f32_e32 v6, v14, v12
	v_add_f32_e32 v12, 1.0, v13
	v_rcp_f32_e32 v12, v12
	v_fma_f32 v13, v75, v19, v87
	v_fmac_f32_e32 v13, v79, v21
	v_fmac_f32_e32 v13, v83, v7
	v_mul_f32_e32 v7, v18, v12
	v_fma_f32 v12, v100, v16, v72
	v_fmac_f32_e32 v73, v101, v17
	v_fmac_f32_e32 v12, v92, v10
	v_fmac_f32_e32 v73, v93, v11
	v_fmac_f32_e32 v12, v96, v0
	v_fmac_f32_e32 v73, v97, v1
	v_mul_f32_e32 v0, 0xbfb8aa3b, v12
	v_mul_f32_e32 v1, 0xbfb8aa3b, v73
	v_exp_f32_e32 v0, v0
	v_exp_f32_e32 v1, v1
	v_fma_f32 v8, v76, v8, v88
	v_fmac_f32_e32 v89, v77, v9
	v_add_f32_e32 v0, 1.0, v0
	v_add_f32_e32 v1, 1.0, v1
	v_rcp_f32_e32 v0, v0
	v_rcp_f32_e32 v1, v1
	v_fmac_f32_e32 v8, v80, v4
	v_fmac_f32_e32 v89, v81, v5
	v_fmac_f32_e32 v8, v84, v2
	v_mul_f32_e32 v0, v12, v0
	v_fmac_f32_e32 v89, v85, v3
	v_mul_f32_e32 v1, v73, v1
	v_cmp_gt_i32_e32 vcc, s88, v211
	v_mul_f32_e32 v6, v15, v6
	v_mul_f32_e32 v7, v13, v7
	v_mul_f32_e32 v0, v8, v0
	v_mul_f32_e32 v1, v89, v1
	v_cvt_pk_bf16_f32 v66, v6, v7
	v_cvt_pk_bf16_f32 v67, v0, v1
	s_and_saveexec_b64 s[0:1], vcc
	s_cbranch_execz .LBB0_2961
	v_mov_b64_e32 v[0:1], s[12:13]
	v_mad_i64_i32 v[0:1], s[2:3], v214, s86, v[0:1]
	v_lshl_add_u64 v[0:1], v[178:179], 1, v[0:1]
	global_store_dwordx4 v[0:1], v[64:67], off sc0 sc1

; __device__ __forceinline__ unsigned cvt_pk_bf16(float lo, float hi) { unsigned r; asm volatile("v_cvt_pk_bf16_f32 %0, %1, %2" : "=v"(r) : "v"(lo), "v"(hi)); return r; }
;     __device__ __forceinline__ void operator()(const f32x4 (&acc)[2][2][4][2], const Unit& u, int wr, int wc, int fr, int fq) const {
;     ...
;         for (int ai = 0; ai < 2; ++ai) {
;             u32x4 old[4][2];
; #pragma unroll
;             for (int m = 0; m < 4; ++m)
; #pragma unroll
;                 for (int bj = 0; bj < 2; ++bj) old[m][bj] = *(const u32x4*)(HB + (size_t)(row0 + ai * HALF + m * 16) * ldc + col0 + bj * HALF);
; #pragma unroll
;             for (int m = 0; m < 4; ++m) { const int row = row0 + ai * HALF + m * 16; float ss = 0.f;
; #pragma unroll
;                 for (int bj = 0; bj < 2; ++bj) { const u32x4 ow = old[m][bj];
;                     f32x4 v0 = (acc[ai][bj][m][0] + bv[bj][0]) * accs, v1 = (acc[ai][bj][m][1] + bv[bj][1]) * accs;
;                     v0[0] += __uint_as_float(ow.x << 16); v0[1] += __uint_as_float(ow.x & 0xffff0000u); v0[2] += __uint_as_float(ow.y << 16); v0[3] += __uint_as_float(ow.y & 0xffff0000u);
;                     v1[0] += __uint_as_float(ow.z << 16); v1[1] += __uint_as_float(ow.z & 0xffff0000u); v1[2] += __uint_as_float(ow.w << 16); v1[3] += __uint_as_float(ow.w & 0xffff0000u);
;                     ss += (v0[0] * v0[0] + v0[1] * v0[1]) + (v0[2] * v0[2] + v0[3] * v0[3]) + (v1[0] * v1[0] + v1[1] * v1[1]) + (v1[2] * v1[2] + v1[3] * v1[3]);
;                     u32x4 w; w.x = cvt_pk_bf16(v0[0], v0[1]); w.y = cvt_pk_bf16(v0[2], v0[3]); w.z = cvt_pk_bf16(v1[0], v1[1]); w.w = cvt_pk_bf16(v1[2], v1[3]);
;                     *(u32x4*)(HB + (size_t)row * ldc + col0 + bj * HALF) = w; }
;                 ss += __shfl_xor(ss, 16); ss += __shfl_xor(ss, 32);
;                 if (fq == 0) ssp[(size_t)row * 32] = ss; }
.LBB0_3043:
	v_lshl_or_b32 v152, s42, 8, v166
	v_ashrrev_i32_e32 v153, 31, v152
	v_lshl_add_u32 v156, s43, 8, v164
	v_lshlrev_b64 v[178:179], 1, v[152:153]
	v_ashrrev_i32_e32 v157, 31, v156
	v_lshl_add_u64 v[154:155], s[12:13], 0, v[178:179]
	v_lshlrev_b64 v[180:181], 12, v[156:157]
	v_lshl_add_u64 v[128:129], v[154:155], 0, v[180:181]
	global_load_dwordx4 v[170:173], v[128:129], off
	global_load_dwordx4 v[174:177], v[128:129], off offset:256
	v_or_b32_e32 v162, 16, v156
	v_or_b32_e32 v160, 32, v156
	v_or_b32_e32 v158, 48, v156
	v_ashrrev_i32_e32 v163, 31, v162
	v_ashrrev_i32_e32 v161, 31, v160
	v_pk_add_f32 v[194:195], v[114:115], 0 op_sel_hi:[1,0]
	v_pk_add_f32 v[196:197], v[112:113], 0 op_sel_hi:[1,0]
	v_ashrrev_i32_e32 v159, 31, v158
	v_lshlrev_b64 v[112:113], 12, v[162:163]
	v_lshlrev_b64 v[114:115], 12, v[160:161]
	v_pk_add_f32 v[192:193], v[116:117], 0 op_sel_hi:[1,0]
	v_lshlrev_b64 v[116:117], 12, v[158:159]
	v_lshl_add_u64 v[112:113], v[154:155], 0, v[112:113]
	v_lshl_add_u64 v[114:115], v[154:155], 0, v[114:115]
	v_pk_add_f32 v[182:183], v[126:127], 0 op_sel_hi:[1,0]
	v_pk_add_f32 v[184:185], v[124:125], 0 op_sel_hi:[1,0]
	v_pk_add_f32 v[186:187], v[122:123], 0 op_sel_hi:[1,0]
	v_pk_add_f32 v[188:189], v[120:121], 0 op_sel_hi:[1,0]
	v_pk_add_f32 v[190:191], v[118:119], 0 op_sel_hi:[1,0]
	v_lshl_add_u64 v[198:199], v[154:155], 0, v[116:117]
	global_load_dwordx4 v[132:135], v[112:113], off
	global_load_dwordx4 v[128:131], v[112:113], off offset:256
	global_load_dwordx4 v[124:127], v[114:115], off
	global_load_dwordx4 v[120:123], v[114:115], off offset:256
	global_load_dwordx4 v[116:119], v[198:199], off
	s_nop 0
	global_load_dwordx4 v[112:115], v[198:199], off offset:256
	s_lshl_b32 s18, s42, 2
	s_or_b32 s18, s18, s46
	s_ashr_i32 s19, s18, 31
	s_lshl_b64 s[18:19], s[18:19], 2
	s_add_u32 s18, s44, s18
	s_addc_u32 s19, s45, s19
	s_waitcnt vmcnt(0)
	v_lshlrev_b32_e32 v198, 16, v170
	v_and_b32_e32 v170, 0xffff0000, v170
	v_lshlrev_b32_e32 v199, 16, v171
	v_and_b32_e32 v171, 0xffff0000, v171
	v_lshlrev_b32_e32 v200, 16, v172
	v_and_b32_e32 v172, 0xffff0000, v172
	v_lshlrev_b32_e32 v203, 16, v174
	v_and_b32_e32 v174, 0xffff0000, v174
	v_lshlrev_b32_e32 v205, 16, v175
	v_and_b32_e32 v175, 0xffff0000, v175
	v_lshlrev_b32_e32 v201, 16, v173
	v_and_b32_e32 v173, 0xffff0000, v173
	v_lshlrev_b32_e32 v206, 16, v176
	v_and_b32_e32 v176, 0xffff0000, v176
	v_lshlrev_b32_e32 v207, 16, v177
	v_and_b32_e32 v177, 0xffff0000, v177
	v_add_f32_e32 v170, v185, v170
	v_add_f32_e32 v171, v183, v171
	v_add_f32_e32 v185, v189, v172
	v_add_f32_e32 v189, v193, v174
	v_add_f32_e32 v191, v191, v175
	v_add_f32_e32 v184, v184, v198
	v_add_f32_e32 v182, v182, v199
	v_add_f32_e32 v183, v188, v200
	v_add_f32_e32 v187, v187, v173
	v_add_f32_e32 v188, v192, v203
	v_add_f32_e32 v190, v190, v205
	v_add_f32_e32 v193, v197, v176
	v_add_f32_e32 v195, v195, v177
	v_mul_f32_e32 v176, v170, v170
	v_mul_f32_e32 v177, v171, v171
	v_cvt_pk_bf16_f32 v172, v184, v170
	v_cvt_pk_bf16_f32 v173, v182, v171
	v_mul_f32_e32 v170, v189, v189
	v_mul_f32_e32 v171, v191, v191
	v_fmac_f32_e32 v170, v188, v188
	v_fmac_f32_e32 v171, v190, v190
	v_add_f32_e32 v192, v196, v206
	v_add_f32_e32 v170, v170, v171
	v_mul_f32_e32 v171, v193, v193
	v_mul_f32_e32 v196, v185, v185
	v_fmac_f32_e32 v176, v184, v184
	v_fmac_f32_e32 v177, v182, v182
	v_fmac_f32_e32 v171, v192, v192
	v_add_f32_e32 v186, v186, v201
	v_add_f32_e32 v194, v194, v207
	v_mul_f32_e32 v197, v187, v187
	v_fmac_f32_e32 v196, v183, v183
	v_add_f32_e32 v176, v176, v177
	v_add_f32_e32 v170, v171, v170
	v_mul_f32_e32 v171, v195, v195
	v_fmac_f32_e32 v197, v186, v186
	v_add_f32_e32 v176, v196, v176
	v_fmac_f32_e32 v171, v194, v194
	v_add_f32_e32 v176, v197, v176
	v_add_f32_e32 v170, v171, v170
	v_add_f32_e32 v171, v176, v170
	v_and_b32_e32 v176, 64, v202
	v_xor_b32_e32 v170, 16, v202
	v_add_u32_e32 v182, 64, v176
	v_cmp_lt_i32_e32 vcc, v170, v182
	v_cvt_pk_bf16_f32 v174, v183, v185
	v_lshl_add_u64 v[176:177], s[12:13], 0, v[180:181]
	v_lshl_add_u64 v[178:179], v[176:177], 0, v[178:179]
	v_cndmask_b32_e32 v170, v202, v170, vcc
	v_lshlrev_b32_e32 v170, 2, v170
	ds_bpermute_b32 v183, v170, v171
	v_cvt_pk_bf16_f32 v175, v186, v187
	global_store_dwordx4 v[178:179], v[172:175], off sc0 sc1
	s_waitcnt lgkmcnt(0)
	s_nop 0
	v_add_f32_e32 v172, v171, v183
	v_xor_b32_e32 v171, 32, v202
	v_cmp_lt_i32_e32 vcc, v171, v182
	v_cvt_pk_bf16_f32 v174, v188, v189
	v_cvt_pk_bf16_f32 v175, v190, v191
	v_cvt_pk_bf16_f32 v176, v192, v193
	v_cvt_pk_bf16_f32 v177, v194, v195
	global_store_dwordx4 v[178:179], v[174:177], off offset:256 sc0 sc1
	s_nop 0
	v_cndmask_b32_e32 v171, v202, v171, vcc
	v_lshlrev_b32_e32 v171, 2, v171
	ds_bpermute_b32 v173, v171, v172
	s_and_saveexec_b64 s[20:21], s[4:5]
	s_cbranch_execz .LBB0_3045
	v_lshlrev_b64 v[174:175], 7, v[156:157]
	v_lshl_add_u64 v[174:175], s[18:19], 0, v[174:175]
	s_waitcnt lgkmcnt(0)
	v_add_f32_e32 v157, v172, v173
	global_store_dword v[174:175], v157, off
; __device__ __forceinline__ unsigned cvt_pk_bf16(float lo, float hi) { unsigned r; asm volatile("v_cvt_pk_bf16_f32 %0, %1, %2" : "=v"(r) : "v"(lo), "v"(hi)); return r; }
;     __device__ __forceinline__ void operator()(const f32x4 (&acc)[2][2][4][2], const Unit& u, int wr, int wc, int fr, int fq) const {
;     ...
;             for (int m = 0; m < 4; ++m) { const int row = row0 + ai * HALF + m * 16; float ss = 0.f;
; #pragma unroll
;                 for (int bj = 0; bj < 2; ++bj) { const u32x4 ow = old[m][bj];
;                     f32x4 v0 = (acc[ai][bj][m][0] + bv[bj][0]) * accs, v1 = (acc[ai][bj][m][1] + bv[bj][1]) * accs;
;                     v0[0] += __uint_as_float(ow.x << 16); v0[1] += __uint_as_float(ow.x & 0xffff0000u); v0[2] += __uint_as_float(ow.y << 16); v0[3] += __uint_as_float(ow.y & 0xffff0000u);
;                     v1[0] += __uint_as_float(ow.z << 16); v1[1] += __uint_as_float(ow.z & 0xffff0000u); v1[2] += __uint_as_float(ow.w << 16); v1[3] += __uint_as_float(ow.w & 0xffff0000u);
;                     ss += (v0[0] * v0[0] + v0[1] * v0[1]) + (v0[2] * v0[2] + v0[3] * v0[3]) + (v1[0] * v1[0] + v1[1] * v1[1]) + (v1[2] * v1[2] + v1[3] * v1[3]);
;                     u32x4 w; w.x = cvt_pk_bf16(v0[0], v0[1]); w.y = cvt_pk_bf16(v0[2], v0[3]); w.z = cvt_pk_bf16(v1[0], v1[1]); w.w = cvt_pk_bf16(v1[2], v1[3]);
;                     *(u32x4*)(HB + (size_t)row * ldc + col0 + bj * HALF) = w; }
;                 ss += __shfl_xor(ss, 16); ss += __shfl_xor(ss, 32);
;                 if (fq == 0) ssp[(size_t)row * 32] = ss; }
.LBB0_3045:
	s_or_b64 exec, exec, s[20:21]
	v_pk_add_f32 v[108:109], v[108:109], 0 op_sel_hi:[1,0]
	v_lshlrev_b32_e32 v157, 16, v132
	v_and_b32_e32 v132, 0xffff0000, v132
	v_pk_add_f32 v[110:111], v[110:111], 0 op_sel_hi:[1,0]
	v_add_f32_e32 v109, v109, v132
	v_lshlrev_b32_e32 v132, 16, v133
	v_add_f32_e32 v110, v110, v132
	v_and_b32_e32 v132, 0xffff0000, v133
	v_pk_add_f32 v[104:105], v[104:105], 0 op_sel_hi:[1,0]
	v_add_f32_e32 v111, v111, v132
	v_lshlrev_b32_e32 v132, 16, v134
	v_add_f32_e32 v132, v104, v132
	v_and_b32_e32 v104, 0xffff0000, v134
	v_pk_add_f32 v[106:107], v[106:107], 0 op_sel_hi:[1,0]
	v_add_f32_e32 v133, v105, v104
	v_lshlrev_b32_e32 v104, 16, v135
	v_add_f32_e32 v134, v106, v104
	v_and_b32_e32 v104, 0xffff0000, v135
	v_add_f32_e32 v108, v108, v157
	v_add_f32_e32 v107, v107, v104
	v_mul_f32_e32 v104, v109, v109
	v_mul_f32_e32 v105, v111, v111
	v_fmac_f32_e32 v104, v108, v108
	v_fmac_f32_e32 v105, v110, v110
	v_add_f32_e32 v104, v104, v105
	v_mul_f32_e32 v105, v133, v133
	v_fmac_f32_e32 v105, v132, v132
	v_add_f32_e32 v104, v105, v104
	v_mul_f32_e32 v105, v107, v107
	v_fmac_f32_e32 v105, v134, v134
	v_add_f32_e32 v135, v105, v104
	v_cvt_pk_bf16_f32 v104, v108, v109
	v_pk_add_f32 v[100:101], v[100:101], 0 op_sel_hi:[1,0]
	v_lshlrev_b32_e32 v108, 16, v128
	v_add_f32_e32 v100, v100, v108
	v_and_b32_e32 v108, 0xffff0000, v128
	v_pk_add_f32 v[102:103], v[102:103], 0 op_sel_hi:[1,0]
	v_add_f32_e32 v101, v101, v108
	v_lshlrev_b32_e32 v108, 16, v129
	v_add_f32_e32 v108, v102, v108
	v_and_b32_e32 v102, 0xffff0000, v129
	v_pk_add_f32 v[96:97], v[96:97], 0 op_sel_hi:[1,0]
	v_add_f32_e32 v109, v103, v102
	v_lshlrev_b32_e32 v102, 16, v130
	v_cvt_pk_bf16_f32 v105, v110, v111
	v_add_f32_e32 v110, v96, v102
	v_and_b32_e32 v96, 0xffff0000, v130
	v_pk_add_f32 v[98:99], v[98:99], 0 op_sel_hi:[1,0]
	v_add_f32_e32 v111, v97, v96
	v_lshlrev_b32_e32 v96, 16, v131
	v_add_f32_e32 v128, v98, v96
	v_and_b32_e32 v96, 0xffff0000, v131
	v_add_f32_e32 v129, v99, v96
	v_mul_f32_e32 v96, v101, v101
	v_mul_f32_e32 v97, v109, v109
	v_fmac_f32_e32 v96, v100, v100
	v_fmac_f32_e32 v97, v108, v108
	v_add_f32_e32 v96, v96, v97
	v_mul_f32_e32 v97, v111, v111
	v_fmac_f32_e32 v97, v110, v110
	v_add_f32_e32 v96, v97, v96
	v_mul_f32_e32 v97, v129, v129
	v_fmac_f32_e32 v97, v128, v128
	v_add_f32_e32 v96, v97, v96
	v_add_f32_e32 v99, v135, v96
	ds_bpermute_b32 v130, v170, v99
	s_waitcnt lgkmcnt(1)
	v_lshlrev_b64 v[172:173], 11, v[162:163]
	v_lshl_add_u64 v[96:97], v[172:173], 1, s[12:13]
	v_lshl_add_u64 v[102:103], v[152:153], 1, v[96:97]
	v_cvt_pk_bf16_f32 v106, v132, v133
	s_waitcnt lgkmcnt(0)
	v_add_f32_e32 v96, v99, v130
	ds_bpermute_b32 v97, v171, v96
	v_cvt_pk_bf16_f32 v107, v134, v107
	global_store_dwordx4 v[102:103], v[104:107], off sc0 sc1
	v_cvt_pk_bf16_f32 v98, v100, v101
	v_cvt_pk_bf16_f32 v99, v108, v109
	v_cvt_pk_bf16_f32 v100, v110, v111
	v_cvt_pk_bf16_f32 v101, v128, v129
	global_store_dwordx4 v[102:103], v[98:101], off offset:256 sc0 sc1
	s_and_saveexec_b64 s[20:21], s[4:5]
	s_cbranch_execz .LBB0_3047
	v_lshlrev_b64 v[98:99], 7, v[162:163]
	v_lshl_add_u64 v[98:99], s[18:19], 0, v[98:99]
	s_waitcnt lgkmcnt(0)
	v_add_f32_e32 v96, v96, v97
	global_store_dword v[98:99], v96, off
.LBB0_3047:
	s_or_b64 exec, exec, s[20:21]
	v_pk_add_f32 v[92:93], v[92:93], 0 op_sel_hi:[1,0]
	v_lshlrev_b32_e32 v98, 16, v124
	v_add_f32_e32 v92, v92, v98
	v_and_b32_e32 v98, 0xffff0000, v124
	v_pk_add_f32 v[94:95], v[94:95], 0 op_sel_hi:[1,0]
	v_add_f32_e32 v93, v93, v98
	v_lshlrev_b32_e32 v98, 16, v125
	v_add_f32_e32 v94, v94, v98
	v_and_b32_e32 v98, 0xffff0000, v125
	v_pk_add_f32 v[88:89], v[88:89], 0 op_sel_hi:[1,0]
	v_add_f32_e32 v95, v95, v98
	v_lshlrev_b32_e32 v98, 16, v126
	v_add_f32_e32 v98, v88, v98
	v_and_b32_e32 v88, 0xffff0000, v126
	v_pk_add_f32 v[90:91], v[90:91], 0 op_sel_hi:[1,0]
	v_add_f32_e32 v99, v89, v88
	v_lshlrev_b32_e32 v88, 16, v127
	v_add_f32_e32 v100, v90, v88
	v_and_b32_e32 v88, 0xffff0000, v127
	v_add_f32_e32 v91, v91, v88
	v_mul_f32_e32 v88, v93, v93
	v_mul_f32_e32 v89, v95, v95
	v_fmac_f32_e32 v88, v92, v92
	v_fmac_f32_e32 v89, v94, v94
	v_add_f32_e32 v88, v88, v89
	v_mul_f32_e32 v89, v99, v99
	v_fmac_f32_e32 v89, v98, v98
	v_add_f32_e32 v88, v89, v88
	v_mul_f32_e32 v89, v91, v91
	v_fmac_f32_e32 v89, v100, v100
	v_add_f32_e32 v101, v89, v88
	v_cvt_pk_bf16_f32 v88, v92, v93
	v_pk_add_f32 v[84:85], v[84:85], 0 op_sel_hi:[1,0]
	v_lshlrev_b32_e32 v92, 16, v120
	v_add_f32_e32 v84, v84, v92
	v_and_b32_e32 v92, 0xffff0000, v120
	v_pk_add_f32 v[86:87], v[86:87], 0 op_sel_hi:[1,0]
	v_add_f32_e32 v85, v85, v92
	v_lshlrev_b32_e32 v92, 16, v121
	v_add_f32_e32 v92, v86, v92
	v_and_b32_e32 v86, 0xffff0000, v121
	v_pk_add_f32 v[80:81], v[80:81], 0 op_sel_hi:[1,0]
	v_add_f32_e32 v93, v87, v86
	v_lshlrev_b32_e32 v86, 16, v122
	v_cvt_pk_bf16_f32 v89, v94, v95
	v_add_f32_e32 v94, v80, v86
	v_and_b32_e32 v80, 0xffff0000, v122
	v_pk_add_f32 v[82:83], v[82:83], 0 op_sel_hi:[1,0]
	v_add_f32_e32 v95, v81, v80
	v_lshlrev_b32_e32 v80, 16, v123
	v_cvt_pk_bf16_f32 v90, v98, v99
	v_add_f32_e32 v98, v82, v80
	v_and_b32_e32 v80, 0xffff0000, v123
	v_add_f32_e32 v99, v83, v80
	v_mul_f32_e32 v80, v85, v85
	v_mul_f32_e32 v81, v93, v93
	v_fmac_f32_e32 v80, v84, v84
	v_fmac_f32_e32 v81, v92, v92
	v_add_f32_e32 v80, v80, v81
	v_mul_f32_e32 v81, v95, v95
	v_fmac_f32_e32 v81, v94, v94
	v_add_f32_e32 v80, v81, v80
	v_mul_f32_e32 v81, v99, v99
	v_fmac_f32_e32 v81, v98, v98
	v_add_f32_e32 v80, v81, v80
	v_add_f32_e32 v83, v101, v80
	v_cvt_pk_bf16_f32 v91, v100, v91
	ds_bpermute_b32 v100, v170, v83
	s_waitcnt lgkmcnt(1)
	v_lshlrev_b64 v[96:97], 11, v[160:161]
	v_lshl_add_u64 v[80:81], v[96:97], 1, s[12:13]
	v_lshl_add_u64 v[86:87], v[152:153], 1, v[80:81]
	global_store_dwordx4 v[86:87], v[88:91], off sc0 sc1
	s_waitcnt lgkmcnt(0)
	v_add_f32_e32 v80, v83, v100
	ds_bpermute_b32 v81, v171, v80
	v_cvt_pk_bf16_f32 v82, v84, v85
	v_cvt_pk_bf16_f32 v83, v92, v93
	v_cvt_pk_bf16_f32 v84, v94, v95
	v_cvt_pk_bf16_f32 v85, v98, v99
	global_store_dwordx4 v[86:87], v[82:85], off offset:256 sc0 sc1
	s_and_saveexec_b64 s[20:21], s[4:5]
	s_cbranch_execz .LBB0_3049
	v_lshlrev_b64 v[82:83], 7, v[160:161]
	v_lshl_add_u64 v[82:83], s[18:19], 0, v[82:83]
	s_waitcnt lgkmcnt(0)
	v_add_f32_e32 v80, v80, v81
	global_store_dword v[82:83], v80, off
; __device__ __forceinline__ unsigned cvt_pk_bf16(float lo, float hi) { unsigned r; asm volatile("v_cvt_pk_bf16_f32 %0, %1, %2" : "=v"(r) : "v"(lo), "v"(hi)); return r; }
;     __device__ __forceinline__ void operator()(const f32x4 (&acc)[2][2][4][2], const Unit& u, int wr, int wc, int fr, int fq) const {
;     ...
;             for (int m = 0; m < 4; ++m)
; #pragma unroll
;                 for (int bj = 0; bj < 2; ++bj) old[m][bj] = *(const u32x4*)(HB + (size_t)(row0 + ai * HALF + m * 16) * ldc + col0 + bj * HALF);
; #pragma unroll
;             for (int m = 0; m < 4; ++m) { const int row = row0 + ai * HALF + m * 16; float ss = 0.f;
; #pragma unroll
;                 for (int bj = 0; bj < 2; ++bj) { const u32x4 ow = old[m][bj];
;                     f32x4 v0 = (acc[ai][bj][m][0] + bv[bj][0]) * accs, v1 = (acc[ai][bj][m][1] + bv[bj][1]) * accs;
;                     v0[0] += __uint_as_float(ow.x << 16); v0[1] += __uint_as_float(ow.x & 0xffff0000u); v0[2] += __uint_as_float(ow.y << 16); v0[3] += __uint_as_float(ow.y & 0xffff0000u);
;                     v1[0] += __uint_as_float(ow.z << 16); v1[1] += __uint_as_float(ow.z & 0xffff0000u); v1[2] += __uint_as_float(ow.w << 16); v1[3] += __uint_as_float(ow.w & 0xffff0000u);
;                     ss += (v0[0] * v0[0] + v0[1] * v0[1]) + (v0[2] * v0[2] + v0[3] * v0[3]) + (v1[0] * v1[0] + v1[1] * v1[1]) + (v1[2] * v1[2] + v1[3] * v1[3]);
;                     u32x4 w; w.x = cvt_pk_bf16(v0[0], v0[1]); w.y = cvt_pk_bf16(v0[2], v0[3]); w.z = cvt_pk_bf16(v1[0], v1[1]); w.w = cvt_pk_bf16(v1[2], v1[3]);
;                     *(u32x4*)(HB + (size_t)row * ldc + col0 + bj * HALF) = w; }
;                 ss += __shfl_xor(ss, 16); ss += __shfl_xor(ss, 32);
;                 if (fq == 0) ssp[(size_t)row * 32] = ss; }
.LBB0_3049:
	s_or_b64 exec, exec, s[20:21]
	v_pk_add_f32 v[76:77], v[76:77], 0 op_sel_hi:[1,0]
	v_lshlrev_b32_e32 v82, 16, v116
	v_add_f32_e32 v76, v76, v82
	v_and_b32_e32 v82, 0xffff0000, v116
	v_pk_add_f32 v[78:79], v[78:79], 0 op_sel_hi:[1,0]
	v_add_f32_e32 v77, v77, v82
	v_lshlrev_b32_e32 v82, 16, v117
	v_add_f32_e32 v78, v78, v82
	v_and_b32_e32 v82, 0xffff0000, v117
	v_pk_add_f32 v[72:73], v[72:73], 0 op_sel_hi:[1,0]
	v_add_f32_e32 v79, v79, v82
	v_lshlrev_b32_e32 v82, 16, v118
	v_add_f32_e32 v82, v72, v82
	v_and_b32_e32 v72, 0xffff0000, v118
	v_pk_add_f32 v[74:75], v[74:75], 0 op_sel_hi:[1,0]
	v_add_f32_e32 v83, v73, v72
	v_lshlrev_b32_e32 v72, 16, v119
	v_add_f32_e32 v84, v74, v72
	v_and_b32_e32 v72, 0xffff0000, v119
	v_add_f32_e32 v75, v75, v72
	v_mul_f32_e32 v72, v77, v77
	v_mul_f32_e32 v73, v79, v79
	v_fmac_f32_e32 v72, v76, v76
	v_fmac_f32_e32 v73, v78, v78
	v_add_f32_e32 v72, v72, v73
	v_mul_f32_e32 v73, v83, v83
	v_fmac_f32_e32 v73, v82, v82
	v_add_f32_e32 v72, v73, v72
	v_mul_f32_e32 v73, v75, v75
	v_fmac_f32_e32 v73, v84, v84
	v_add_f32_e32 v85, v73, v72
	v_cvt_pk_bf16_f32 v72, v76, v77
	v_pk_add_f32 v[68:69], v[68:69], 0 op_sel_hi:[1,0]
	v_lshlrev_b32_e32 v76, 16, v112
	v_add_f32_e32 v68, v68, v76
	v_and_b32_e32 v76, 0xffff0000, v112
	v_pk_add_f32 v[70:71], v[70:71], 0 op_sel_hi:[1,0]
	v_add_f32_e32 v69, v69, v76
	v_lshlrev_b32_e32 v76, 16, v113
	v_add_f32_e32 v76, v70, v76
	v_and_b32_e32 v70, 0xffff0000, v113
	v_pk_add_f32 v[64:65], v[64:65], 0 op_sel_hi:[1,0]
	v_add_f32_e32 v77, v71, v70
	v_lshlrev_b32_e32 v70, 16, v114
	v_cvt_pk_bf16_f32 v73, v78, v79
	v_add_f32_e32 v78, v64, v70
	v_and_b32_e32 v64, 0xffff0000, v114
	v_pk_add_f32 v[66:67], v[66:67], 0 op_sel_hi:[1,0]
	v_add_f32_e32 v79, v65, v64
	v_lshlrev_b32_e32 v64, 16, v115
	v_cvt_pk_bf16_f32 v74, v82, v83
	v_add_f32_e32 v82, v66, v64
	v_and_b32_e32 v64, 0xffff0000, v115
	v_add_f32_e32 v83, v67, v64
	v_mul_f32_e32 v64, v69, v69
	v_mul_f32_e32 v65, v77, v77
	v_fmac_f32_e32 v64, v68, v68
	v_fmac_f32_e32 v65, v76, v76
	v_add_f32_e32 v64, v64, v65
	v_mul_f32_e32 v65, v79, v79
	v_fmac_f32_e32 v65, v78, v78
	v_add_f32_e32 v64, v65, v64
	v_mul_f32_e32 v65, v83, v83
	v_fmac_f32_e32 v65, v82, v82
	v_add_f32_e32 v64, v65, v64
	v_add_f32_e32 v67, v85, v64
	v_cvt_pk_bf16_f32 v75, v84, v75
	ds_bpermute_b32 v84, v170, v67
	s_waitcnt lgkmcnt(1)
	v_lshlrev_b64 v[80:81], 11, v[158:159]
	v_lshl_add_u64 v[64:65], v[80:81], 1, s[12:13]
	v_lshl_add_u64 v[70:71], v[152:153], 1, v[64:65]
	global_store_dwordx4 v[70:71], v[72:75], off sc0 sc1
	s_waitcnt lgkmcnt(0)
	v_add_f32_e32 v64, v67, v84
	ds_bpermute_b32 v65, v171, v64
	v_cvt_pk_bf16_f32 v66, v68, v69
	v_cvt_pk_bf16_f32 v67, v76, v77
	v_cvt_pk_bf16_f32 v68, v78, v79
	v_cvt_pk_bf16_f32 v69, v82, v83
	global_store_dwordx4 v[70:71], v[66:69], off offset:256 sc0 sc1
	s_and_saveexec_b64 s[20:21], s[4:5]
	s_cbranch_execz .LBB0_3051
	v_lshlrev_b64 v[66:67], 7, v[158:159]
	v_lshl_add_u64 v[66:67], s[18:19], 0, v[66:67]
	s_waitcnt lgkmcnt(0)
	v_add_f32_e32 v64, v64, v65
	global_store_dword v[66:67], v64, off
.LBB0_3051:
	s_or_b64 exec, exec, s[20:21]
	v_add_u32_e32 v98, 0x80, v156
	v_ashrrev_i32_e32 v99, 31, v98
	v_lshlrev_b64 v[104:105], 12, v[98:99]
	s_waitcnt lgkmcnt(0)
	v_lshl_add_u64 v[64:65], v[154:155], 0, v[104:105]
	global_load_dwordx4 v[100:103], v[64:65], off
	global_load_dwordx4 v[88:91], v[64:65], off offset:256
	v_add_u32_e32 v96, 0x90, v156
	v_ashrrev_i32_e32 v97, 31, v96
	v_lshlrev_b64 v[64:65], 12, v[96:97]
	v_add_u32_e32 v94, 0xa0, v156
	v_lshl_add_u64 v[64:65], v[154:155], 0, v[64:65]
	v_ashrrev_i32_e32 v95, 31, v94
	global_load_dwordx4 v[84:87], v[64:65], off
	global_load_dwordx4 v[80:83], v[64:65], off offset:256
	v_lshlrev_b64 v[64:65], 12, v[94:95]
	v_add_u32_e32 v92, 0xb0, v156
	v_lshl_add_u64 v[64:65], v[154:155], 0, v[64:65]
	v_ashrrev_i32_e32 v93, 31, v92
	global_load_dwordx4 v[76:79], v[64:65], off
	global_load_dwordx4 v[72:75], v[64:65], off offset:256
	v_lshlrev_b64 v[64:65], 12, v[92:93]
	v_lshl_add_u64 v[64:65], v[154:155], 0, v[64:65]
	global_load_dwordx4 v[68:71], v[64:65], off
	s_nop 0
	global_load_dwordx4 v[64:67], v[64:65], off offset:256
	v_pk_add_f32 v[60:61], v[60:61], 0 op_sel_hi:[1,0]
	v_pk_add_f32 v[62:63], v[62:63], 0 op_sel_hi:[1,0]
	v_pk_add_f32 v[56:57], v[56:57], 0 op_sel_hi:[1,0]
	v_pk_add_f32 v[58:59], v[58:59], 0 op_sel_hi:[1,0]
	v_pk_add_f32 v[52:53], v[52:53], 0 op_sel_hi:[1,0]
	v_pk_add_f32 v[54:55], v[54:55], 0 op_sel_hi:[1,0]
	v_pk_add_f32 v[48:49], v[48:49], 0 op_sel_hi:[1,0]
	v_pk_add_f32 v[50:51], v[50:51], 0 op_sel_hi:[1,0]
	s_waitcnt vmcnt(7)
	v_lshlrev_b32_e32 v106, 16, v100
	v_and_b32_e32 v100, 0xffff0000, v100
	v_add_f32_e32 v61, v61, v100
	v_lshlrev_b32_e32 v100, 16, v101
	v_add_f32_e32 v62, v62, v100
	v_and_b32_e32 v100, 0xffff0000, v101
	v_add_f32_e32 v63, v63, v100
	v_lshlrev_b32_e32 v100, 16, v102
	v_add_f32_e32 v56, v56, v100
	v_and_b32_e32 v100, 0xffff0000, v102
	v_add_f32_e32 v57, v57, v100
	v_lshlrev_b32_e32 v100, 16, v103
	v_add_f32_e32 v100, v58, v100
	v_and_b32_e32 v58, 0xffff0000, v103
	v_add_f32_e32 v60, v60, v106
	v_add_f32_e32 v101, v59, v58
	v_mul_f32_e32 v58, v61, v61
	v_mul_f32_e32 v59, v63, v63
	v_fmac_f32_e32 v58, v60, v60
	v_fmac_f32_e32 v59, v62, v62
	v_add_f32_e32 v58, v58, v59
	v_mul_f32_e32 v59, v57, v57
	v_fmac_f32_e32 v59, v56, v56
	v_add_f32_e32 v58, v59, v58
	v_mul_f32_e32 v59, v101, v101
	v_fmac_f32_e32 v59, v100, v100
	v_add_f32_e32 v102, v59, v58
	v_cvt_pk_bf16_f32 v58, v60, v61
	v_cvt_pk_bf16_f32 v59, v62, v63
	v_cvt_pk_bf16_f32 v60, v56, v57
	v_lshl_add_u64 v[56:57], s[12:13], 0, v[104:105]
	v_lshl_add_u64 v[56:57], v[152:153], 1, v[56:57]
	v_cvt_pk_bf16_f32 v61, v100, v101
	global_store_dwordx4 v[56:57], v[58:61], off sc0 sc1
	s_waitcnt vmcnt(7)
	s_nop 0
	v_lshlrev_b32_e32 v58, 16, v88
	v_add_f32_e32 v52, v52, v58
	v_and_b32_e32 v58, 0xffff0000, v88
	v_add_f32_e32 v53, v53, v58
	v_lshlrev_b32_e32 v58, 16, v89
	v_add_f32_e32 v54, v54, v58
	v_and_b32_e32 v58, 0xffff0000, v89
	v_add_f32_e32 v55, v55, v58
	v_lshlrev_b32_e32 v58, 16, v90
	v_add_f32_e32 v58, v48, v58
	v_and_b32_e32 v48, 0xffff0000, v90
	v_add_f32_e32 v59, v49, v48
	v_lshlrev_b32_e32 v48, 16, v91
	v_add_f32_e32 v60, v50, v48
	v_and_b32_e32 v48, 0xffff0000, v91
	v_add_f32_e32 v51, v51, v48
	v_mul_f32_e32 v48, v53, v53
	v_mul_f32_e32 v49, v55, v55
	v_fmac_f32_e32 v48, v52, v52
	v_fmac_f32_e32 v49, v54, v54
	v_add_f32_e32 v48, v48, v49
	v_mul_f32_e32 v49, v59, v59
	v_fmac_f32_e32 v49, v58, v58
	v_add_f32_e32 v48, v49, v48
	v_mul_f32_e32 v49, v51, v51
	v_fmac_f32_e32 v49, v60, v60
	v_add_f32_e32 v48, v49, v48
	v_add_f32_e32 v61, v102, v48
	v_cvt_pk_bf16_f32 v48, v52, v53
	v_cvt_pk_bf16_f32 v49, v54, v55
	v_cvt_pk_bf16_f32 v50, v58, v59
	v_cvt_pk_bf16_f32 v51, v60, v51
	global_store_dwordx4 v[56:57], v[48:51], off offset:256 sc0 sc1
	ds_bpermute_b32 v48, v170, v61
	s_waitcnt lgkmcnt(0)
	v_add_f32_e32 v48, v61, v48
	ds_bpermute_b32 v49, v171, v48
	s_and_saveexec_b64 s[20:21], s[4:5]
	s_cbranch_execz .LBB0_3053
; __device__ __forceinline__ unsigned cvt_pk_bf16(float lo, float hi) { unsigned r; asm volatile("v_cvt_pk_bf16_f32 %0, %1, %2" : "=v"(r) : "v"(lo), "v"(hi)); return r; }
;     __device__ __forceinline__ void operator()(const f32x4 (&acc)[2][2][4][2], const Unit& u, int wr, int wc, int fr, int fq) const {
;     ...
;             for (int m = 0; m < 4; ++m) { const int row = row0 + ai * HALF + m * 16; float ss = 0.f;
; #pragma unroll
;                 for (int bj = 0; bj < 2; ++bj) { const u32x4 ow = old[m][bj];
;                     f32x4 v0 = (acc[ai][bj][m][0] + bv[bj][0]) * accs, v1 = (acc[ai][bj][m][1] + bv[bj][1]) * accs;
;                     v0[0] += __uint_as_float(ow.x << 16); v0[1] += __uint_as_float(ow.x & 0xffff0000u); v0[2] += __uint_as_float(ow.y << 16); v0[3] += __uint_as_float(ow.y & 0xffff0000u);
;                     v1[0] += __uint_as_float(ow.z << 16); v1[1] += __uint_as_float(ow.z & 0xffff0000u); v1[2] += __uint_as_float(ow.w << 16); v1[3] += __uint_as_float(ow.w & 0xffff0000u);
;                     ss += (v0[0] * v0[0] + v0[1] * v0[1]) + (v0[2] * v0[2] + v0[3] * v0[3]) + (v1[0] * v1[0] + v1[1] * v1[1]) + (v1[2] * v1[2] + v1[3] * v1[3]);
;                     u32x4 w; w.x = cvt_pk_bf16(v0[0], v0[1]); w.y = cvt_pk_bf16(v0[2], v0[3]); w.z = cvt_pk_bf16(v1[0], v1[1]); w.w = cvt_pk_bf16(v1[2], v1[3]);
;                     *(u32x4*)(HB + (size_t)row * ldc + col0 + bj * HALF) = w; }
;                 ss += __shfl_xor(ss, 16); ss += __shfl_xor(ss, 32);
;                 if (fq == 0) ssp[(size_t)row * 32] = ss; }
	v_lshlrev_b64 v[50:51], 7, v[98:99]
	v_lshl_add_u64 v[50:51], s[18:19], 0, v[50:51]
	s_waitcnt lgkmcnt(0)
	v_add_f32_e32 v48, v48, v49
	global_store_dword v[50:51], v48, off
.LBB0_3053:
	s_or_b64 exec, exec, s[20:21]
	v_pk_add_f32 v[44:45], v[44:45], 0 op_sel_hi:[1,0]
	s_waitcnt vmcnt(7)
	v_lshlrev_b32_e32 v50, 16, v84
	v_add_f32_e32 v44, v44, v50
	v_and_b32_e32 v50, 0xffff0000, v84
	v_pk_add_f32 v[46:47], v[46:47], 0 op_sel_hi:[1,0]
	v_add_f32_e32 v45, v45, v50
	v_lshlrev_b32_e32 v50, 16, v85
	v_add_f32_e32 v46, v46, v50
	v_and_b32_e32 v50, 0xffff0000, v85
	v_pk_add_f32 v[40:41], v[40:41], 0 op_sel_hi:[1,0]
	v_add_f32_e32 v47, v47, v50
	v_lshlrev_b32_e32 v50, 16, v86
	v_add_f32_e32 v50, v40, v50
	v_and_b32_e32 v40, 0xffff0000, v86
	v_pk_add_f32 v[42:43], v[42:43], 0 op_sel_hi:[1,0]
	v_add_f32_e32 v51, v41, v40
	v_lshlrev_b32_e32 v40, 16, v87
	v_add_f32_e32 v52, v42, v40
	v_and_b32_e32 v40, 0xffff0000, v87
	v_add_f32_e32 v43, v43, v40
	v_mul_f32_e32 v40, v45, v45
	v_mul_f32_e32 v41, v47, v47
	v_fmac_f32_e32 v40, v44, v44
	v_fmac_f32_e32 v41, v46, v46
	v_add_f32_e32 v40, v40, v41
	v_mul_f32_e32 v41, v51, v51
	v_fmac_f32_e32 v41, v50, v50
	v_add_f32_e32 v40, v41, v40
	v_mul_f32_e32 v41, v43, v43
	v_fmac_f32_e32 v41, v52, v52
	v_add_f32_e32 v53, v41, v40
	v_cvt_pk_bf16_f32 v40, v44, v45
	v_pk_add_f32 v[36:37], v[36:37], 0 op_sel_hi:[1,0]
	s_waitcnt vmcnt(6)
	v_lshlrev_b32_e32 v44, 16, v80
	v_add_f32_e32 v36, v36, v44
	v_and_b32_e32 v44, 0xffff0000, v80
	v_pk_add_f32 v[38:39], v[38:39], 0 op_sel_hi:[1,0]
	v_add_f32_e32 v37, v37, v44
	v_lshlrev_b32_e32 v44, 16, v81
	v_add_f32_e32 v44, v38, v44
	v_and_b32_e32 v38, 0xffff0000, v81
	v_pk_add_f32 v[32:33], v[32:33], 0 op_sel_hi:[1,0]
	v_add_f32_e32 v45, v39, v38
	v_lshlrev_b32_e32 v38, 16, v82
	v_cvt_pk_bf16_f32 v41, v46, v47
	v_add_f32_e32 v46, v32, v38
	v_and_b32_e32 v32, 0xffff0000, v82
	v_pk_add_f32 v[34:35], v[34:35], 0 op_sel_hi:[1,0]
	v_add_f32_e32 v47, v33, v32
	v_lshlrev_b32_e32 v32, 16, v83
	v_cvt_pk_bf16_f32 v42, v50, v51
	v_add_f32_e32 v50, v34, v32
	v_and_b32_e32 v32, 0xffff0000, v83
	v_add_f32_e32 v51, v35, v32
	v_mul_f32_e32 v32, v37, v37
	v_mul_f32_e32 v33, v45, v45
	v_fmac_f32_e32 v32, v36, v36
	v_fmac_f32_e32 v33, v44, v44
	v_add_f32_e32 v32, v32, v33
	v_mul_f32_e32 v33, v47, v47
	v_fmac_f32_e32 v33, v46, v46
	v_add_f32_e32 v32, v33, v32
	v_mul_f32_e32 v33, v51, v51
	v_fmac_f32_e32 v33, v50, v50
	v_add_f32_e32 v32, v33, v32
	v_add_f32_e32 v35, v53, v32
	v_cvt_pk_bf16_f32 v43, v52, v43
	ds_bpermute_b32 v52, v170, v35
	s_waitcnt lgkmcnt(1)
	v_lshlrev_b64 v[48:49], 11, v[96:97]
	v_lshl_add_u64 v[32:33], v[48:49], 1, s[12:13]
	v_lshl_add_u64 v[38:39], v[152:153], 1, v[32:33]
	global_store_dwordx4 v[38:39], v[40:43], off sc0 sc1
	s_waitcnt lgkmcnt(0)
	v_add_f32_e32 v32, v35, v52
	ds_bpermute_b32 v33, v171, v32
	v_cvt_pk_bf16_f32 v34, v36, v37
	v_cvt_pk_bf16_f32 v35, v44, v45
	v_cvt_pk_bf16_f32 v36, v46, v47
	v_cvt_pk_bf16_f32 v37, v50, v51
	global_store_dwordx4 v[38:39], v[34:37], off offset:256 sc0 sc1
	s_and_saveexec_b64 s[20:21], s[4:5]
	s_cbranch_execz .LBB0_3055
	v_lshlrev_b64 v[34:35], 7, v[96:97]
	v_lshl_add_u64 v[34:35], s[18:19], 0, v[34:35]
	s_waitcnt lgkmcnt(0)
	v_add_f32_e32 v32, v32, v33
	global_store_dword v[34:35], v32, off
; __device__ __forceinline__ unsigned cvt_pk_bf16(float lo, float hi) { unsigned r; asm volatile("v_cvt_pk_bf16_f32 %0, %1, %2" : "=v"(r) : "v"(lo), "v"(hi)); return r; }
;     __device__ __forceinline__ void operator()(const f32x4 (&acc)[2][2][4][2], const Unit& u, int wr, int wc, int fr, int fq) const {
;     ...
;             for (int m = 0; m < 4; ++m) { const int row = row0 + ai * HALF + m * 16; float ss = 0.f;
; #pragma unroll
;                 for (int bj = 0; bj < 2; ++bj) { const u32x4 ow = old[m][bj];
;                     f32x4 v0 = (acc[ai][bj][m][0] + bv[bj][0]) * accs, v1 = (acc[ai][bj][m][1] + bv[bj][1]) * accs;
;                     v0[0] += __uint_as_float(ow.x << 16); v0[1] += __uint_as_float(ow.x & 0xffff0000u); v0[2] += __uint_as_float(ow.y << 16); v0[3] += __uint_as_float(ow.y & 0xffff0000u);
;                     v1[0] += __uint_as_float(ow.z << 16); v1[1] += __uint_as_float(ow.z & 0xffff0000u); v1[2] += __uint_as_float(ow.w << 16); v1[3] += __uint_as_float(ow.w & 0xffff0000u);
;                     ss += (v0[0] * v0[0] + v0[1] * v0[1]) + (v0[2] * v0[2] + v0[3] * v0[3]) + (v1[0] * v1[0] + v1[1] * v1[1]) + (v1[2] * v1[2] + v1[3] * v1[3]);
;                     u32x4 w; w.x = cvt_pk_bf16(v0[0], v0[1]); w.y = cvt_pk_bf16(v0[2], v0[3]); w.z = cvt_pk_bf16(v1[0], v1[1]); w.w = cvt_pk_bf16(v1[2], v1[3]);
;                     *(u32x4*)(HB + (size_t)row * ldc + col0 + bj * HALF) = w; }
;                 ss += __shfl_xor(ss, 16); ss += __shfl_xor(ss, 32);
;                 if (fq == 0) ssp[(size_t)row * 32] = ss; }
.LBB0_3055:
	s_or_b64 exec, exec, s[20:21]
	v_pk_add_f32 v[28:29], v[28:29], 0 op_sel_hi:[1,0]
	s_waitcnt vmcnt(7)
	v_lshlrev_b32_e32 v34, 16, v76
	v_add_f32_e32 v28, v28, v34
	v_and_b32_e32 v34, 0xffff0000, v76
	v_pk_add_f32 v[30:31], v[30:31], 0 op_sel_hi:[1,0]
	v_add_f32_e32 v29, v29, v34
	v_lshlrev_b32_e32 v34, 16, v77
	v_add_f32_e32 v30, v30, v34
	v_and_b32_e32 v34, 0xffff0000, v77
	v_pk_add_f32 v[24:25], v[24:25], 0 op_sel_hi:[1,0]
	v_add_f32_e32 v31, v31, v34
	v_lshlrev_b32_e32 v34, 16, v78
	v_add_f32_e32 v34, v24, v34
	v_and_b32_e32 v24, 0xffff0000, v78
	v_pk_add_f32 v[26:27], v[26:27], 0 op_sel_hi:[1,0]
	v_add_f32_e32 v35, v25, v24
	v_lshlrev_b32_e32 v24, 16, v79
	v_add_f32_e32 v36, v26, v24
	v_and_b32_e32 v24, 0xffff0000, v79
	v_add_f32_e32 v27, v27, v24
	v_mul_f32_e32 v24, v29, v29
	v_mul_f32_e32 v25, v31, v31
	v_fmac_f32_e32 v24, v28, v28
	v_fmac_f32_e32 v25, v30, v30
	v_add_f32_e32 v24, v24, v25
	v_mul_f32_e32 v25, v35, v35
	v_fmac_f32_e32 v25, v34, v34
	v_add_f32_e32 v24, v25, v24
	v_mul_f32_e32 v25, v27, v27
	v_fmac_f32_e32 v25, v36, v36
	v_add_f32_e32 v37, v25, v24
	v_cvt_pk_bf16_f32 v24, v28, v29
	v_pk_add_f32 v[20:21], v[20:21], 0 op_sel_hi:[1,0]
	s_waitcnt vmcnt(6)
	v_lshlrev_b32_e32 v28, 16, v72
	v_add_f32_e32 v20, v20, v28
	v_and_b32_e32 v28, 0xffff0000, v72
	v_pk_add_f32 v[22:23], v[22:23], 0 op_sel_hi:[1,0]
	v_add_f32_e32 v21, v21, v28
	v_lshlrev_b32_e32 v28, 16, v73
	v_add_f32_e32 v28, v22, v28
	v_and_b32_e32 v22, 0xffff0000, v73
	v_pk_add_f32 v[16:17], v[16:17], 0 op_sel_hi:[1,0]
	v_add_f32_e32 v29, v23, v22
	v_lshlrev_b32_e32 v22, 16, v74
	v_cvt_pk_bf16_f32 v25, v30, v31
	v_add_f32_e32 v30, v16, v22
	v_and_b32_e32 v16, 0xffff0000, v74
	v_pk_add_f32 v[18:19], v[18:19], 0 op_sel_hi:[1,0]
	v_add_f32_e32 v31, v17, v16
	v_lshlrev_b32_e32 v16, 16, v75
	v_cvt_pk_bf16_f32 v26, v34, v35
	v_add_f32_e32 v34, v18, v16
	v_and_b32_e32 v16, 0xffff0000, v75
	v_add_f32_e32 v35, v19, v16
	v_mul_f32_e32 v16, v21, v21
	v_mul_f32_e32 v17, v29, v29
	v_fmac_f32_e32 v16, v20, v20
	v_fmac_f32_e32 v17, v28, v28
	v_add_f32_e32 v16, v16, v17
	v_mul_f32_e32 v17, v31, v31
	v_fmac_f32_e32 v17, v30, v30
	v_add_f32_e32 v16, v17, v16
	v_mul_f32_e32 v17, v35, v35
	v_fmac_f32_e32 v17, v34, v34
	v_add_f32_e32 v16, v17, v16
	v_add_f32_e32 v19, v37, v16
	v_cvt_pk_bf16_f32 v27, v36, v27
	ds_bpermute_b32 v36, v170, v19
	s_waitcnt lgkmcnt(1)
	v_lshlrev_b64 v[32:33], 11, v[94:95]
	v_lshl_add_u64 v[16:17], v[32:33], 1, s[12:13]
	v_lshl_add_u64 v[22:23], v[152:153], 1, v[16:17]
	global_store_dwordx4 v[22:23], v[24:27], off sc0 sc1
	s_waitcnt lgkmcnt(0)
	v_add_f32_e32 v16, v19, v36
	ds_bpermute_b32 v17, v171, v16
	v_cvt_pk_bf16_f32 v18, v20, v21
	v_cvt_pk_bf16_f32 v19, v28, v29
	v_cvt_pk_bf16_f32 v20, v30, v31
	v_cvt_pk_bf16_f32 v21, v34, v35
	global_store_dwordx4 v[22:23], v[18:21], off offset:256 sc0 sc1
	s_and_saveexec_b64 s[20:21], s[4:5]
	s_cbranch_execz .LBB0_3057
	v_lshlrev_b64 v[18:19], 7, v[94:95]
	v_lshl_add_u64 v[18:19], s[18:19], 0, v[18:19]
	s_waitcnt lgkmcnt(0)
	v_add_f32_e32 v16, v16, v17
	global_store_dword v[18:19], v16, off
.LBB0_3057:
	s_or_b64 exec, exec, s[20:21]
	v_pk_add_f32 v[12:13], v[12:13], 0 op_sel_hi:[1,0]
	s_waitcnt vmcnt(7)
	v_lshlrev_b32_e32 v18, 16, v68
	v_add_f32_e32 v12, v12, v18
	v_and_b32_e32 v18, 0xffff0000, v68
	v_pk_add_f32 v[14:15], v[14:15], 0 op_sel_hi:[1,0]
	v_add_f32_e32 v13, v13, v18
	v_lshlrev_b32_e32 v18, 16, v69
	v_add_f32_e32 v14, v14, v18
	v_and_b32_e32 v18, 0xffff0000, v69
	v_pk_add_f32 v[8:9], v[8:9], 0 op_sel_hi:[1,0]
	v_add_f32_e32 v15, v15, v18
	v_lshlrev_b32_e32 v18, 16, v70
	v_add_f32_e32 v18, v8, v18
	v_and_b32_e32 v8, 0xffff0000, v70
	v_pk_add_f32 v[10:11], v[10:11], 0 op_sel_hi:[1,0]
	v_add_f32_e32 v19, v9, v8
	v_lshlrev_b32_e32 v8, 16, v71
	v_add_f32_e32 v20, v10, v8
	v_and_b32_e32 v8, 0xffff0000, v71
	v_add_f32_e32 v11, v11, v8
	v_mul_f32_e32 v8, v13, v13
	v_mul_f32_e32 v9, v15, v15
	v_fmac_f32_e32 v8, v12, v12
	v_fmac_f32_e32 v9, v14, v14
	v_add_f32_e32 v8, v8, v9
	v_mul_f32_e32 v9, v19, v19
	v_fmac_f32_e32 v9, v18, v18
	v_add_f32_e32 v8, v9, v8
	v_mul_f32_e32 v9, v11, v11
	v_fmac_f32_e32 v9, v20, v20
	v_add_f32_e32 v21, v9, v8
	v_cvt_pk_bf16_f32 v8, v12, v13
	v_pk_add_f32 v[4:5], v[4:5], 0 op_sel_hi:[1,0]
	s_waitcnt vmcnt(6)
	v_lshlrev_b32_e32 v12, 16, v64
	v_add_f32_e32 v4, v4, v12
	v_and_b32_e32 v12, 0xffff0000, v64
	v_pk_add_f32 v[6:7], v[6:7], 0 op_sel_hi:[1,0]
	v_add_f32_e32 v5, v5, v12
	v_lshlrev_b32_e32 v12, 16, v65
	v_add_f32_e32 v12, v6, v12
	v_and_b32_e32 v6, 0xffff0000, v65
	v_pk_add_f32 v[0:1], v[0:1], 0 op_sel_hi:[1,0]
	v_add_f32_e32 v13, v7, v6
	v_lshlrev_b32_e32 v6, 16, v66
	v_cvt_pk_bf16_f32 v9, v14, v15
	v_add_f32_e32 v14, v0, v6
	v_and_b32_e32 v0, 0xffff0000, v66
	v_pk_add_f32 v[2:3], v[2:3], 0 op_sel_hi:[1,0]
	v_add_f32_e32 v15, v1, v0
	v_lshlrev_b32_e32 v0, 16, v67
	v_cvt_pk_bf16_f32 v10, v18, v19
	v_add_f32_e32 v18, v2, v0
	v_and_b32_e32 v0, 0xffff0000, v67
	v_add_f32_e32 v19, v3, v0
	v_mul_f32_e32 v0, v5, v5
	v_mul_f32_e32 v1, v13, v13
	v_fmac_f32_e32 v0, v4, v4
	v_fmac_f32_e32 v1, v12, v12
	v_add_f32_e32 v0, v0, v1
	v_mul_f32_e32 v1, v15, v15
	v_fmac_f32_e32 v1, v14, v14
	v_add_f32_e32 v0, v1, v0
	v_mul_f32_e32 v1, v19, v19
	v_fmac_f32_e32 v1, v18, v18
	v_add_f32_e32 v0, v1, v0
	v_add_f32_e32 v3, v21, v0
	v_cvt_pk_bf16_f32 v11, v20, v11
	ds_bpermute_b32 v20, v170, v3
	s_waitcnt lgkmcnt(1)
	v_lshlrev_b64 v[16:17], 11, v[92:93]
	v_lshl_add_u64 v[0:1], v[16:17], 1, s[12:13]
	v_lshl_add_u64 v[6:7], v[152:153], 1, v[0:1]
	global_store_dwordx4 v[6:7], v[8:11], off sc0 sc1
	s_waitcnt lgkmcnt(0)
	v_add_f32_e32 v0, v3, v20
	ds_bpermute_b32 v1, v171, v0
	v_cvt_pk_bf16_f32 v2, v4, v5
	v_cvt_pk_bf16_f32 v3, v12, v13
	v_cvt_pk_bf16_f32 v4, v14, v15
	v_cvt_pk_bf16_f32 v5, v18, v19
	global_store_dwordx4 v[6:7], v[2:5], off offset:256 sc0 sc1
	s_and_saveexec_b64 s[20:21], s[4:5]
	s_cbranch_execz .LBB0_3059
	v_lshlrev_b64 v[2:3], 7, v[92:93]
	v_lshl_add_u64 v[2:3], s[18:19], 0, v[2:3]
	s_waitcnt lgkmcnt(0)
	v_add_f32_e32 v0, v0, v1
	global_store_dword v[2:3], v0, off

; __device__ __forceinline__ void final_row(const bf16_t* hrow, const float* gain, const float* ssrow, float* orow, int lane) {
;     const float ss = wave_sum(lane < 32 ? ssrow[lane] : 0.f);
;     const float r = 1.0f / sqrtf(ss * (1.f / D) + EPS);
; #pragma unroll
;     for (int j = 0; j < 8; ++j) { const u32x2 hw = *(const u32x2*)(hrow + 4 * lane + 256 * j); const f32x4 g = *(const f32x4*)(gain + 4 * lane + 256 * j);
;         f32x4 o; o.x = __uint_as_float(hw.x << 16) * r * g.x; o.y = __uint_as_float(hw.x & 0xffff0000u) * r * g.y; o.z = __uint_as_float(hw.y << 16) * r * g.z; o.w = __uint_as_float(hw.y & 0xffff0000u) * r * g.w;
;         *(f32x4*)(orow + 4 * lane + 256 * j) = o; }
.LBB0_3117:
	s_or_b64 exec, exec, s[2:3]
	v_lshl_add_u64 v[26:27], s[10:11], 0, v[14:15]
	v_add_co_u32_e32 v30, vcc, s14, v26
	s_waitcnt vmcnt(0)
	ds_bpermute_b32 v25, v16, v24
	v_addc_co_u32_e32 v31, vcc, 0, v27, vcc
	global_load_dwordx2 v[32:33], v[30:31], off
	global_load_dwordx4 v[26:29], v[0:1], off
	s_waitcnt lgkmcnt(0)
	v_add_f32_e32 v24, v24, v25
	ds_bpermute_b32 v25, v17, v24
	s_add_i32 s8, s8, s72
	v_lshl_add_u64 v[10:11], v[10:11], 0, s[4:5]
	s_cmpk_gt_i32 s8, 0x1fff
	v_lshl_add_u64 v[14:15], v[14:15], 0, s[12:13]
	s_waitcnt lgkmcnt(0)
	v_add_f32_e32 v24, v24, v25
	ds_bpermute_b32 v25, v18, v24
	s_waitcnt lgkmcnt(0)
	v_add_f32_e32 v24, v24, v25
	ds_bpermute_b32 v25, v19, v24
	s_waitcnt lgkmcnt(0)
	v_add_f32_e32 v24, v24, v25
	ds_bpermute_b32 v25, v20, v24
	s_waitcnt lgkmcnt(0)
	v_add_f32_e32 v24, v24, v25
	ds_bpermute_b32 v25, v21, v24
	s_waitcnt lgkmcnt(0)
	v_add_f32_e32 v24, v24, v25
	v_fmamk_f32 v24, v24, 0x3a000000, v22
	v_mul_f32_e32 v25, 0x4f800000, v24
	v_cmp_gt_f32_e32 vcc, s9, v24
	s_nop 1
	v_cndmask_b32_e32 v24, v24, v25, vcc
	v_sqrt_f32_e32 v25, v24
	s_nop 0
	v_add_u32_e32 v34, -1, v25
	v_add_u32_e32 v35, 1, v25
	v_fma_f32 v36, -v34, v25, v24
	v_fma_f32 v37, -v35, v25, v24
	v_cmp_ge_f32_e64 s[2:3], 0, v36
	s_nop 1
	v_cndmask_b32_e64 v25, v25, v34, s[2:3]
	v_cmp_lt_f32_e64 s[2:3], 0, v37
	s_nop 1
	v_cndmask_b32_e64 v25, v25, v35, s[2:3]
	v_mul_f32_e32 v34, 0x37800000, v25
	v_cndmask_b32_e32 v25, v25, v34, vcc
	v_cmp_class_f32_e32 vcc, v24, v23
	s_nop 1
	v_cndmask_b32_e32 v24, v25, v24, vcc
	v_div_scale_f32 v25, s[2:3], v24, v24, 1.0
	v_rcp_f32_e32 v36, v25
	v_add_co_u32_e32 v34, vcc, s15, v12
	v_fma_f32 v38, -v25, v36, 1.0
	s_nop 0
	v_addc_co_u32_e32 v35, vcc, -1, v13, vcc
	v_div_scale_f32 v37, vcc, 1.0, v24, 1.0
	v_fmac_f32_e32 v36, v38, v36
	v_mul_f32_e32 v38, v37, v36
	v_fma_f32 v39, -v25, v38, v37
	v_fmac_f32_e32 v38, v39, v36
	v_fma_f32 v25, -v25, v38, v37
	v_div_fmas_f32 v25, v25, v36, v38
	v_div_fixup_f32 v36, v25, v24, 1.0
	s_waitcnt vmcnt(1)
	v_lshlrev_b32_e32 v24, 16, v32
	v_and_b32_e32 v25, 0xffff0000, v32
	v_lshlrev_b32_e32 v32, 16, v33
	v_and_b32_e32 v33, 0xffff0000, v33
	v_pk_mul_f32 v[24:25], v[36:37], v[24:25] op_sel_hi:[0,1]
	v_pk_mul_f32 v[32:33], v[36:37], v[32:33] op_sel_hi:[0,1]
	s_waitcnt vmcnt(0)
	v_pk_mul_f32 v[24:25], v[26:27], v[24:25]
	v_pk_mul_f32 v[26:27], v[28:29], v[32:33]
	global_store_dwordx4 v[34:35], v[24:27], off offset:-3072 sc0 sc1
	global_load_dwordx2 v[28:29], v[30:31], off offset:512
	s_nop 0
	global_load_dwordx4 v[24:27], v[0:1], off offset:1024
	s_waitcnt vmcnt(1)
	v_lshlrev_b32_e32 v32, 16, v28
	v_and_b32_e32 v33, 0xffff0000, v28
	v_lshlrev_b32_e32 v28, 16, v29
	v_and_b32_e32 v29, 0xffff0000, v29
	v_pk_mul_f32 v[32:33], v[36:37], v[32:33] op_sel_hi:[0,1]
	v_pk_mul_f32 v[28:29], v[36:37], v[28:29] op_sel_hi:[0,1]
	s_waitcnt vmcnt(0)
	v_pk_mul_f32 v[24:25], v[24:25], v[32:33]
	v_pk_mul_f32 v[26:27], v[26:27], v[28:29]
	global_store_dwordx4 v[34:35], v[24:27], off offset:-2048 sc0 sc1
	global_load_dwordx2 v[28:29], v[30:31], off offset:1024
	s_nop 0
	global_load_dwordx4 v[24:27], v[0:1], off offset:2048
	s_waitcnt vmcnt(1)
	v_lshlrev_b32_e32 v32, 16, v28
	v_and_b32_e32 v33, 0xffff0000, v28
	v_lshlrev_b32_e32 v28, 16, v29
	v_and_b32_e32 v29, 0xffff0000, v29
	v_pk_mul_f32 v[32:33], v[36:37], v[32:33] op_sel_hi:[0,1]
	v_pk_mul_f32 v[28:29], v[36:37], v[28:29] op_sel_hi:[0,1]
	s_waitcnt vmcnt(0)
	v_pk_mul_f32 v[24:25], v[24:25], v[32:33]
	v_pk_mul_f32 v[26:27], v[26:27], v[28:29]
	global_store_dwordx4 v[34:35], v[24:27], off offset:-1024 sc0 sc1
	global_load_dwordx2 v[28:29], v[30:31], off offset:1536
	s_nop 0
	global_load_dwordx4 v[24:27], v[0:1], off offset:3072
	s_waitcnt vmcnt(1)
	v_lshlrev_b32_e32 v32, 16, v28
	v_and_b32_e32 v33, 0xffff0000, v28
	v_lshlrev_b32_e32 v28, 16, v29
	v_and_b32_e32 v29, 0xffff0000, v29
	v_pk_mul_f32 v[32:33], v[36:37], v[32:33] op_sel_hi:[0,1]
	v_pk_mul_f32 v[28:29], v[36:37], v[28:29] op_sel_hi:[0,1]
	s_waitcnt vmcnt(0)
	v_pk_mul_f32 v[24:25], v[24:25], v[32:33]
	v_pk_mul_f32 v[26:27], v[26:27], v[28:29]
	global_store_dwordx4 v[12:13], v[24:27], off offset:-4096 sc0 sc1
	global_load_dwordx2 v[28:29], v[30:31], off offset:2048
	s_nop 0
	global_load_dwordx4 v[24:27], v[2:3], off
	s_waitcnt vmcnt(1)
	v_lshlrev_b32_e32 v32, 16, v28
	v_and_b32_e32 v33, 0xffff0000, v28
	v_lshlrev_b32_e32 v28, 16, v29
	v_and_b32_e32 v29, 0xffff0000, v29
	v_pk_mul_f32 v[32:33], v[36:37], v[32:33] op_sel_hi:[0,1]
	v_pk_mul_f32 v[28:29], v[36:37], v[28:29] op_sel_hi:[0,1]
	s_waitcnt vmcnt(0)
	v_pk_mul_f32 v[24:25], v[24:25], v[32:33]
	v_pk_mul_f32 v[26:27], v[26:27], v[28:29]
	global_store_dwordx4 v[12:13], v[24:27], off offset:-3072 sc0 sc1
	global_load_dwordx2 v[28:29], v[30:31], off offset:2560
	s_nop 0
	global_load_dwordx4 v[24:27], v[4:5], off
	s_waitcnt vmcnt(1)
	v_lshlrev_b32_e32 v32, 16, v28
	v_and_b32_e32 v33, 0xffff0000, v28
	v_lshlrev_b32_e32 v28, 16, v29
	v_and_b32_e32 v29, 0xffff0000, v29
	v_pk_mul_f32 v[32:33], v[36:37], v[32:33] op_sel_hi:[0,1]
	v_pk_mul_f32 v[28:29], v[36:37], v[28:29] op_sel_hi:[0,1]
	s_waitcnt vmcnt(0)
	v_pk_mul_f32 v[24:25], v[24:25], v[32:33]
	v_pk_mul_f32 v[26:27], v[26:27], v[28:29]
	global_store_dwordx4 v[12:13], v[24:27], off offset:-2048 sc0 sc1
	global_load_dwordx2 v[28:29], v[30:31], off offset:3072
	s_nop 0
	global_load_dwordx4 v[24:27], v[6:7], off
	s_waitcnt vmcnt(1)
	v_lshlrev_b32_e32 v32, 16, v28
	v_and_b32_e32 v33, 0xffff0000, v28
	v_lshlrev_b32_e32 v28, 16, v29
	v_and_b32_e32 v29, 0xffff0000, v29
	v_pk_mul_f32 v[32:33], v[36:37], v[32:33] op_sel_hi:[0,1]
	v_pk_mul_f32 v[28:29], v[36:37], v[28:29] op_sel_hi:[0,1]
	s_waitcnt vmcnt(0)
	v_pk_mul_f32 v[24:25], v[24:25], v[32:33]
	v_pk_mul_f32 v[26:27], v[26:27], v[28:29]
	global_store_dwordx4 v[12:13], v[24:27], off offset:-1024 sc0 sc1
	global_load_dwordx2 v[28:29], v[30:31], off offset:3584
	s_nop 0
	global_load_dwordx4 v[24:27], v[8:9], off
	s_waitcnt vmcnt(1)
	v_lshlrev_b32_e32 v30, 16, v28
	v_and_b32_e32 v31, 0xffff0000, v28
	v_lshlrev_b32_e32 v28, 16, v29
	v_and_b32_e32 v29, 0xffff0000, v29
	v_pk_mul_f32 v[30:31], v[36:37], v[30:31] op_sel_hi:[0,1]
	v_pk_mul_f32 v[28:29], v[36:37], v[28:29] op_sel_hi:[0,1]
	s_waitcnt vmcnt(0)
	v_pk_mul_f32 v[24:25], v[24:25], v[30:31]
	v_pk_mul_f32 v[26:27], v[26:27], v[28:29]
	global_store_dwordx4 v[12:13], v[24:27], off sc0 sc1
	v_lshl_add_u64 v[12:13], v[12:13], 0, s[6:7]
	s_cbranch_scc1 .LBB0_3120
